# FFT code: multiply-by-+-i register shuffles (v_xor + v_mov) folded into op_sel/neg modifiers of packed-f32 consumers (220 sites, exact same arithmetic)
# speedup vs baseline: 1.0073x; 1.0073x over previous
.LBB0_134:
	global_load_dword v6, v[22:23], off
	v_lshrrev_b32_e32 v26, 2, v11
	v_add_u32_e32 v25, 0x200, v25
	v_and_b32_e32 v26, 0x3ffffff8, v26
	v_cmp_lt_u32_e32 vcc, s34, v25
	v_add_u32_e32 v11, 8, v11
	v_lshl_add_u64 v[22:23], v[22:23], 0, s[26:27]
	v_add_u32_e32 v26, v24, v26
	v_add_u32_e32 v24, 64, v24
	s_or_b64 s[62:63], vcc, s[62:63]
	s_waitcnt vmcnt(0)
	ds_write_b64 v26, v[6:7]
	s_andn2_b64 exec, exec, s[62:63]
	s_cbranch_execnz .LBB0_134
	s_or_b64 exec, exec, s[62:63]
	v_mov_b32_e32 v6, v62
	s_waitcnt lgkmcnt(0)
	s_barrier
	s_mov_b32 s43, s40
	v_and_b32_e32 v11, 15, v6
	v_cvt_f32_ubyte0_e32 v22, v11
	v_mul_f32_e32 v23, 0x3b800000, v22
	v_sin_f32_e32 v22, v23
	v_cos_f32_e32 v24, v23
	v_lshlrev_b32_e32 v6, 4, v6
	v_and_b32_e32 v6, 0xffffff00, v6
	v_xor_b32_e32 v25, 0x80000000, v22
	v_mov_b32_e32 v23, v25
	v_pk_mul_f32 v[26:27], v[24:25], v[22:23] op_sel:[1,0] op_sel_hi:[0,1]
	v_pk_fma_f32 v[26:27], v[24:25], v[24:25], v[26:27] op_sel_hi:[1,0,1]
	v_lshlrev_b32_e32 v11, 3, v11
	v_xor_b32_e32 v32, 0x80000000, v27
	v_mov_b32_e32 v33, v27
	v_pk_mul_f32 v[30:31], v[26:27], v[32:33] op_sel:[1,0] op_sel_hi:[0,1]
	v_pk_fma_f32 v[30:31], v[26:27], v[26:27], v[30:31] op_sel_hi:[1,0,1]
	v_pk_mul_f32 v[28:29], v[22:23], v[26:27] op_sel:[0,1] op_sel_hi:[1,0]
	v_xor_b32_e32 v34, 0x80000000, v31
	v_mov_b32_e32 v35, v31
	v_pk_mul_f32 v[50:51], v[30:31], v[34:35] op_sel:[1,0] op_sel_hi:[0,1]
	v_pk_fma_f32 v[50:51], v[30:31], v[30:31], v[50:51] op_sel_hi:[1,0,1]
	v_pk_mul_f32 v[36:37], v[22:23], v[30:31] op_sel:[0,1] op_sel_hi:[1,0]
	v_pk_mul_f32 v[70:71], v[34:35], v[50:51] op_sel:[0,1] op_sel_hi:[1,0]
	v_pk_mul_f32 v[54:55], v[22:23], v[50:51] op_sel:[0,1] op_sel_hi:[1,0]
	v_pk_fma_f32 v[70:71], v[30:31], v[50:51], v[70:71] op_sel_hi:[0,1,1]
	v_pk_mul_f32 v[74:75], v[22:23], v[70:71] op_sel:[0,1] op_sel_hi:[1,0]
	v_pk_fma_f32 v[28:29], v[24:25], v[26:27], v[28:29] op_sel_hi:[0,1,1]
	v_pk_fma_f32 v[36:37], v[24:25], v[30:31], v[36:37] op_sel_hi:[0,1,1]
	v_pk_fma_f32 v[54:55], v[24:25], v[50:51], v[54:55] op_sel_hi:[0,1,1]
	v_pk_fma_f32 v[74:75], v[24:25], v[70:71], v[74:75] op_sel_hi:[0,1,1]
	v_lshlrev_b32_e32 v25, 3, v6
	v_add3_u32 v11, 0, v11, v25
	v_ashrrev_i32_e32 v25, 2, v6
	v_add_u32_e32 v25, v11, v25
	ds_read2_b64 v[92:95], v25 offset1:16
	ds_read2_b64 v[96:99], v25 offset0:33 offset1:49
	ds_read2_b64 v[100:103], v25 offset0:66 offset1:82
	ds_read2_b64 v[104:107], v25 offset0:132 offset1:148
	ds_read2_b64 v[108:111], v25 offset0:99 offset1:115
	ds_read2_b64 v[112:115], v25 offset0:165 offset1:181
	ds_read2_b64 v[116:119], v25 offset0:198 offset1:214
	ds_read2_b64 v[120:123], v25 offset0:231 offset1:247
	s_waitcnt lgkmcnt(4)
	v_pk_add_f32 v[124:125], v[92:93], v[104:105]
	v_pk_add_f32 v[92:93], v[92:93], v[104:105] neg_lo:[0,1] neg_hi:[0,1]
	v_pk_add_f32 v[104:105], v[94:95], v[106:107]
	v_pk_add_f32 v[94:95], v[94:95], v[106:107] neg_lo:[0,1] neg_hi:[0,1]
	s_mov_b32 s45, s36
	v_pk_mul_f32 v[106:107], v[94:95], s[38:39]
	s_waitcnt lgkmcnt(1)
	v_pk_add_f32 v[126:127], v[102:103], v[118:119]
	v_pk_fma_f32 v[94:95], v[94:95], s[36:37], v[106:107] op_sel:[0,0,1] op_sel_hi:[1,0,0]
	v_pk_add_f32 v[106:107], v[96:97], v[112:113]
	v_pk_add_f32 v[96:97], v[96:97], v[112:113] neg_lo:[0,1] neg_hi:[0,1]
	v_pk_add_f32 v[102:103], v[102:103], v[118:119] neg_lo:[0,1] neg_hi:[0,1]
	v_pk_mul_f32 v[112:113], v[96:97], s[42:43]
	s_mov_b32 s62, s39
	v_pk_mul_f32 v[118:119], v[102:103], s[44:45]
	v_pk_fma_f32 v[96:97], v[96:97], s[40:41], v[112:113] op_sel:[0,0,1] op_sel_hi:[1,0,0]
	v_pk_add_f32 v[112:113], v[98:99], v[114:115]
	v_pk_add_f32 v[98:99], v[98:99], v[114:115] neg_lo:[0,1] neg_hi:[0,1]
	v_pk_fma_f32 v[102:103], v[102:103], s[62:63], v[118:119] op_sel:[0,0,1] op_sel_hi:[1,0,0] neg_lo:[1,0,0] neg_hi:[1,0,0]
	s_waitcnt lgkmcnt(0)
	v_pk_add_f32 v[118:119], v[108:109], v[120:121]
	v_pk_add_f32 v[108:109], v[108:109], v[120:121] neg_lo:[0,1] neg_hi:[0,1]
	v_pk_mul_f32 v[114:115], v[98:99], s[44:45]
	v_pk_mul_f32 v[120:121], v[108:109], s[42:43]
	v_pk_fma_f32 v[98:99], v[98:99], s[62:63], v[114:115] op_sel:[0,0,1] op_sel_hi:[1,0,0]
	v_pk_add_f32 v[114:115], v[100:101], v[116:117]
	v_pk_add_f32 v[116:117], v[100:101], v[116:117] neg_lo:[0,1] neg_hi:[0,1]
	v_pk_fma_f32 v[108:109], v[108:109], s[40:41], v[120:121] op_sel:[0,0,1] op_sel_hi:[1,0,0] neg_lo:[1,0,0] neg_hi:[1,0,0]
	v_pk_add_f32 v[120:121], v[110:111], v[122:123]
	v_pk_add_f32 v[110:111], v[110:111], v[122:123] neg_lo:[0,1] neg_hi:[0,1]
	v_pk_mul_f32 v[122:123], v[110:111], s[38:39]
	v_pk_fma_f32 v[110:111], v[110:111], s[36:37], v[122:123] op_sel:[0,0,1] op_sel_hi:[1,0,0] neg_lo:[1,0,0] neg_hi:[1,0,0]
	v_pk_add_f32 v[122:123], v[124:125], v[114:115]
	v_pk_add_f32 v[114:115], v[124:125], v[114:115] neg_lo:[0,1] neg_hi:[0,1]
	v_pk_add_f32 v[124:125], v[104:105], v[126:127]
	v_pk_add_f32 v[104:105], v[104:105], v[126:127] neg_lo:[0,1] neg_hi:[0,1]
	v_pk_add_f32 v[128:129], v[112:113], v[120:121]
	v_pk_add_f32 v[112:113], v[112:113], v[120:121] neg_lo:[0,1] neg_hi:[0,1]
	v_pk_add_f32 v[100:101], v[92:93], v[116:117] op_sel:[0,1] op_sel_hi:[1,0] neg_hi:[0,1]
	v_pk_add_f32 v[92:93], v[92:93], v[116:117] op_sel:[0,1] op_sel_hi:[1,0] neg_lo:[0,1]
	v_pk_add_f32 v[116:117], v[94:95], v[102:103]
	v_pk_add_f32 v[94:95], v[94:95], v[102:103] neg_lo:[0,1] neg_hi:[0,1]
	v_pk_mul_f32 v[126:127], v[104:105], s[42:43]
	v_pk_mul_f32 v[120:121], v[112:113], s[42:43]
	v_pk_mul_f32 v[102:103], v[94:95], s[42:43]
	v_pk_fma_f32 v[104:105], v[104:105], s[40:41], v[126:127] op_sel:[0,0,1] op_sel_hi:[1,0,0]
	v_pk_add_f32 v[126:127], v[106:107], v[118:119]
	v_pk_add_f32 v[118:119], v[106:107], v[118:119] neg_lo:[0,1] neg_hi:[0,1]
	v_pk_fma_f32 v[112:113], v[112:113], s[40:41], v[120:121] op_sel:[0,0,1] op_sel_hi:[1,0,0] neg_lo:[1,0,0] neg_hi:[1,0,0]
	v_pk_fma_f32 v[94:95], v[94:95], s[40:41], v[102:103] op_sel:[0,0,1] op_sel_hi:[1,0,0]
	v_pk_add_f32 v[102:103], v[96:97], v[108:109]
	v_pk_add_f32 v[120:121], v[98:99], v[110:111]
	v_pk_add_f32 v[98:99], v[98:99], v[110:111] neg_lo:[0,1] neg_hi:[0,1]
	v_pk_add_f32 v[96:97], v[96:97], v[108:109] neg_lo:[0,1] neg_hi:[0,1]
	v_pk_mul_f32 v[110:111], v[98:99], s[42:43]
	v_pk_add_f32 v[130:131], v[100:101], v[102:103]
	v_pk_add_f32 v[100:101], v[100:101], v[102:103] neg_lo:[0,1] neg_hi:[0,1]
	v_pk_add_f32 v[102:103], v[116:117], v[120:121]
	v_pk_add_f32 v[120:121], v[116:117], v[120:121] neg_lo:[0,1] neg_hi:[0,1]
	v_xor_b32_e32 v38, 0x80000000, v29
	v_mov_b32_e32 v39, v29
	v_pk_mul_f32 v[42:43], v[32:33], v[30:31] op_sel:[0,1] op_sel_hi:[1,0]
	v_xor_b32_e32 v109, 0x80000000, v96
	v_pk_fma_f32 v[98:99], v[98:99], s[40:41], v[110:111] op_sel:[0,0,1] op_sel_hi:[1,0,0] neg_lo:[1,0,0] neg_hi:[1,0,0]
	v_pk_add_f32 v[106:107], v[114:115], v[118:119] op_sel:[0,1] op_sel_hi:[1,0] neg_hi:[0,1]
	v_pk_add_f32 v[114:115], v[114:115], v[118:119] op_sel:[0,1] op_sel_hi:[1,0] neg_lo:[0,1]
	v_pk_add_f32 v[118:119], v[104:105], v[112:113]
	v_pk_add_f32 v[112:113], v[104:105], v[112:113] neg_lo:[0,1] neg_hi:[0,1]
	v_mov_b32_e32 v108, v97
	v_xor_b32_e32 v40, 0x80000000, v37
	v_mov_b32_e32 v41, v37
	v_pk_fma_f32 v[42:43], v[26:27], v[30:31], v[42:43] op_sel_hi:[0,1,1]
	v_pk_mul_f32 v[46:47], v[30:31], v[38:39] op_sel:[1,0] op_sel_hi:[0,1]
	v_pk_add_f32 v[96:97], v[92:93], v[108:109]
	v_pk_add_f32 v[92:93], v[92:93], v[108:109] neg_lo:[0,1] neg_hi:[0,1]
	v_pk_add_f32 v[108:109], v[94:95], v[98:99]
	v_pk_add_f32 v[98:99], v[94:95], v[98:99] neg_lo:[0,1] neg_hi:[0,1]
	v_pk_add_f32 v[116:117], v[100:101], v[120:121] op_sel:[0,1] op_sel_hi:[1,0] neg_hi:[0,1]
	v_xor_b32_e32 v44, 0x80000000, v43
	v_mov_b32_e32 v45, v43
	v_pk_fma_f32 v[46:47], v[30:31], v[28:29], v[46:47] op_sel_hi:[1,0,1]
	v_pk_add_f32 v[104:105], v[114:115], v[112:113] op_sel:[0,1] op_sel_hi:[1,0] neg_hi:[0,1]
	v_pk_add_f32 v[100:101], v[100:101], v[120:121] op_sel:[0,1] op_sel_hi:[1,0] neg_lo:[0,1]
	v_pk_mul_f32 v[120:121], v[40:41], v[116:117] op_sel:[0,1] op_sel_hi:[1,0]
	v_xor_b32_e32 v48, 0x80000000, v47
	v_mov_b32_e32 v49, v47
	v_pk_add_f32 v[110:111], v[122:123], v[126:127]
	v_pk_add_f32 v[122:123], v[122:123], v[126:127] neg_lo:[0,1] neg_hi:[0,1]
	v_pk_add_f32 v[126:127], v[124:125], v[128:129]
	v_pk_add_f32 v[94:95], v[92:93], v[98:99] op_sel:[0,1] op_sel_hi:[1,0] neg_hi:[0,1]
	v_pk_fma_f32 v[116:117], v[36:37], v[116:117], v[120:121] op_sel_hi:[0,1,1]
	v_pk_mul_f32 v[120:121], v[44:45], v[104:105] op_sel:[0,1] op_sel_hi:[1,0]
	v_xor_b32_e32 v52, 0x80000000, v51
	v_mov_b32_e32 v53, v51
	v_pk_mul_f32 v[58:59], v[32:33], v[50:51] op_sel:[0,1] op_sel_hi:[1,0]
	v_pk_add_f32 v[132:133], v[110:111], v[126:127]
	v_pk_add_f32 v[110:111], v[110:111], v[126:127] neg_lo:[0,1] neg_hi:[0,1]
	v_pk_fma_f32 v[104:105], v[42:43], v[104:105], v[120:121] op_sel_hi:[0,1,1]
	v_pk_mul_f32 v[120:121], v[48:49], v[94:95] op_sel:[0,1] op_sel_hi:[1,0]
	v_xor_b32_e32 v56, 0x80000000, v55
	v_mov_b32_e32 v57, v55
	v_pk_fma_f32 v[58:59], v[26:27], v[50:51], v[58:59] op_sel_hi:[0,1,1]
	v_pk_mul_f32 v[66:67], v[38:39], v[50:51] op_sel:[0,1] op_sel_hi:[1,0]
	v_pk_add_f32 v[112:113], v[114:115], v[112:113] op_sel:[0,1] op_sel_hi:[1,0] neg_lo:[0,1]
	v_pk_add_f32 v[114:115], v[130:131], v[102:103]
	v_pk_add_f32 v[102:103], v[130:131], v[102:103] neg_lo:[0,1] neg_hi:[0,1]
	v_pk_fma_f32 v[94:95], v[46:47], v[94:95], v[120:121] op_sel_hi:[0,1,1]
	v_pk_mul_f32 v[120:121], v[52:53], v[110:111] op_sel:[0,1] op_sel_hi:[1,0]
	v_xor_b32_e32 v60, 0x80000000, v59
	v_mov_b32_e32 v61, v59
	v_pk_fma_f32 v[66:67], v[28:29], v[50:51], v[66:67] op_sel_hi:[0,1,1]
	v_pk_add_f32 v[128:129], v[124:125], v[128:129] neg_lo:[0,1] neg_hi:[0,1]
	v_pk_add_f32 v[126:127], v[106:107], v[118:119]
	v_pk_add_f32 v[106:107], v[106:107], v[118:119] neg_lo:[0,1] neg_hi:[0,1]
	v_pk_fma_f32 v[110:111], v[50:51], v[110:111], v[120:121] op_sel_hi:[0,1,1]
	v_pk_mul_f32 v[120:121], v[56:57], v[102:103] op_sel:[0,1] op_sel_hi:[1,0]
	v_xor_b32_e32 v68, 0x80000000, v67
	v_mov_b32_e32 v69, v67
	v_pk_add_f32 v[118:119], v[96:97], v[108:109]
	v_pk_add_f32 v[96:97], v[96:97], v[108:109] neg_lo:[0,1] neg_hi:[0,1]
	v_pk_fma_f32 v[102:103], v[54:55], v[102:103], v[120:121] op_sel_hi:[0,1,1]
	v_pk_mul_f32 v[120:121], v[60:61], v[106:107] op_sel:[0,1] op_sel_hi:[1,0]
	v_xor_b32_e32 v72, 0x80000000, v71
	v_mov_b32_e32 v73, v71
	v_pk_mul_f32 v[78:79], v[32:33], v[70:71] op_sel:[0,1] op_sel_hi:[1,0]
	v_pk_add_f32 v[124:125], v[122:123], v[128:129] op_sel:[0,1] op_sel_hi:[1,0] neg_hi:[0,1]
	v_pk_add_f32 v[122:123], v[122:123], v[128:129] op_sel:[0,1] op_sel_hi:[1,0] neg_lo:[0,1]
	v_pk_fma_f32 v[106:107], v[58:59], v[106:107], v[120:121] op_sel_hi:[0,1,1]
	v_pk_mul_f32 v[120:121], v[68:69], v[96:97] op_sel:[0,1] op_sel_hi:[1,0]
	v_xor_b32_e32 v76, 0x80000000, v75
	v_mov_b32_e32 v77, v75
	v_pk_fma_f32 v[78:79], v[26:27], v[70:71], v[78:79] op_sel_hi:[0,1,1]
	v_pk_mul_f32 v[82:83], v[38:39], v[70:71] op_sel:[0,1] op_sel_hi:[1,0]
	v_pk_fma_f32 v[96:97], v[66:67], v[96:97], v[120:121] op_sel_hi:[0,1,1]
	v_pk_mul_f32 v[120:121], v[72:73], v[122:123] op_sel:[0,1] op_sel_hi:[1,0]
	v_xor_b32_e32 v80, 0x80000000, v79
	v_mov_b32_e32 v81, v79
	v_pk_fma_f32 v[82:83], v[28:29], v[70:71], v[82:83] op_sel_hi:[0,1,1]
	v_pk_add_f32 v[92:93], v[92:93], v[98:99] op_sel:[0,1] op_sel_hi:[1,0] neg_lo:[0,1]
	v_pk_mul_f32 v[98:99], v[22:23], v[114:115] op_sel:[0,1] op_sel_hi:[1,0]
	v_pk_fma_f32 v[120:121], v[70:71], v[122:123], v[120:121] op_sel_hi:[0,1,1]
	v_pk_mul_f32 v[122:123], v[76:77], v[100:101] op_sel:[0,1] op_sel_hi:[1,0]
	v_xor_b32_e32 v84, 0x80000000, v83
	v_mov_b32_e32 v85, v83
	v_pk_fma_f32 v[98:99], v[24:25], v[114:115], v[98:99] op_sel_hi:[0,1,1]
	v_pk_mul_f32 v[114:115], v[38:39], v[118:119] op_sel:[0,1] op_sel_hi:[1,0]
	v_pk_fma_f32 v[100:101], v[74:75], v[100:101], v[122:123] op_sel_hi:[0,1,1]
	v_pk_mul_f32 v[122:123], v[80:81], v[112:113] op_sel:[0,1] op_sel_hi:[1,0]
	v_add_u32_e32 v6, 0x2000, v6
	v_pk_mul_f32 v[108:109], v[32:33], v[126:127] op_sel:[0,1] op_sel_hi:[1,0]
	v_pk_fma_f32 v[114:115], v[28:29], v[118:119], v[114:115] op_sel_hi:[0,1,1]
	v_pk_mul_f32 v[118:119], v[34:35], v[124:125] op_sel:[0,1] op_sel_hi:[1,0]
	v_pk_fma_f32 v[112:113], v[78:79], v[112:113], v[122:123] op_sel_hi:[0,1,1]
	v_pk_mul_f32 v[122:123], v[84:85], v[92:93] op_sel:[0,1] op_sel_hi:[1,0]
	v_ashrrev_i32_e32 v6, 2, v6
	v_pk_fma_f32 v[108:109], v[26:27], v[126:127], v[108:109] op_sel_hi:[0,1,1]
	v_pk_fma_f32 v[118:119], v[30:31], v[124:125], v[118:119] op_sel_hi:[0,1,1]
	v_pk_fma_f32 v[92:93], v[82:83], v[92:93], v[122:123] op_sel_hi:[0,1,1]
	ds_write2_b64 v25, v[132:133], v[110:111] offset1:16
	ds_write2_b64 v25, v[118:119], v[120:121] offset0:33 offset1:49
	ds_write2_b64 v25, v[108:109], v[106:107] offset0:66 offset1:82
	ds_write2_b64 v25, v[104:105], v[112:113] offset0:99 offset1:115
	ds_write2_b64 v25, v[98:99], v[102:103] offset0:132 offset1:148
	ds_write2_b64 v25, v[116:117], v[100:101] offset0:165 offset1:181
	ds_write2_b64 v25, v[114:115], v[96:97] offset0:198 offset1:214
	ds_write2_b64 v25, v[94:95], v[92:93] offset0:231 offset1:247
	v_add3_u32 v6, v11, v6, s35
	ds_read2_b64 v[92:95], v6 offset1:16
	ds_read2_b64 v[96:99], v6 offset0:33 offset1:49
	ds_read2_b64 v[100:103], v6 offset0:66 offset1:82
	ds_read2_b64 v[104:107], v6 offset0:132 offset1:148
	ds_read2_b64 v[108:111], v6 offset0:99 offset1:115
	ds_read2_b64 v[112:115], v6 offset0:165 offset1:181
	ds_read2_b64 v[116:119], v6 offset0:198 offset1:214
	ds_read2_b64 v[120:123], v6 offset0:231 offset1:247
	s_waitcnt lgkmcnt(4)
	v_pk_add_f32 v[124:125], v[92:93], v[104:105]
	v_pk_add_f32 v[92:93], v[92:93], v[104:105] neg_lo:[0,1] neg_hi:[0,1]
	v_pk_add_f32 v[104:105], v[94:95], v[106:107]
	v_pk_add_f32 v[94:95], v[94:95], v[106:107] neg_lo:[0,1] neg_hi:[0,1]
	s_waitcnt lgkmcnt(1)
	v_pk_add_f32 v[126:127], v[102:103], v[118:119]
	v_pk_mul_f32 v[106:107], v[94:95], s[38:39]
	v_pk_add_f32 v[102:103], v[102:103], v[118:119] neg_lo:[0,1] neg_hi:[0,1]
	v_pk_fma_f32 v[94:95], v[94:95], s[36:37], v[106:107] op_sel:[0,0,1] op_sel_hi:[1,0,0]
	v_pk_add_f32 v[106:107], v[96:97], v[112:113]
	v_pk_add_f32 v[96:97], v[96:97], v[112:113] neg_lo:[0,1] neg_hi:[0,1]
	v_pk_mul_f32 v[118:119], v[102:103], s[44:45]
	v_pk_mul_f32 v[112:113], v[96:97], s[42:43]
	v_pk_fma_f32 v[102:103], v[102:103], s[62:63], v[118:119] op_sel:[0,0,1] op_sel_hi:[1,0,0] neg_lo:[1,0,0] neg_hi:[1,0,0]
	s_waitcnt lgkmcnt(0)
	v_pk_add_f32 v[118:119], v[108:109], v[120:121]
	v_pk_add_f32 v[108:109], v[108:109], v[120:121] neg_lo:[0,1] neg_hi:[0,1]
	v_pk_fma_f32 v[96:97], v[96:97], s[40:41], v[112:113] op_sel:[0,0,1] op_sel_hi:[1,0,0]
	v_pk_add_f32 v[112:113], v[98:99], v[114:115]
	v_pk_add_f32 v[98:99], v[98:99], v[114:115] neg_lo:[0,1] neg_hi:[0,1]
	v_pk_mul_f32 v[120:121], v[108:109], s[42:43]
	v_pk_mul_f32 v[114:115], v[98:99], s[44:45]
	v_pk_fma_f32 v[108:109], v[108:109], s[40:41], v[120:121] op_sel:[0,0,1] op_sel_hi:[1,0,0] neg_lo:[1,0,0] neg_hi:[1,0,0]
	v_pk_add_f32 v[120:121], v[110:111], v[122:123]
	v_pk_add_f32 v[110:111], v[110:111], v[122:123] neg_lo:[0,1] neg_hi:[0,1]
	v_pk_fma_f32 v[98:99], v[98:99], s[62:63], v[114:115] op_sel:[0,0,1] op_sel_hi:[1,0,0]
	v_pk_add_f32 v[114:115], v[100:101], v[116:117]
	v_pk_mul_f32 v[122:123], v[110:111], s[38:39]
	v_pk_add_f32 v[116:117], v[100:101], v[116:117] neg_lo:[0,1] neg_hi:[0,1]
	v_pk_fma_f32 v[110:111], v[110:111], s[36:37], v[122:123] op_sel:[0,0,1] op_sel_hi:[1,0,0] neg_lo:[1,0,0] neg_hi:[1,0,0]
	v_pk_add_f32 v[122:123], v[124:125], v[114:115]
	v_pk_add_f32 v[114:115], v[124:125], v[114:115] neg_lo:[0,1] neg_hi:[0,1]
	v_pk_add_f32 v[124:125], v[104:105], v[126:127]
	v_pk_add_f32 v[104:105], v[104:105], v[126:127] neg_lo:[0,1] neg_hi:[0,1]
	v_pk_mul_f32 v[126:127], v[104:105], s[42:43]
	v_pk_add_f32 v[128:129], v[112:113], v[120:121]
	v_pk_add_f32 v[112:113], v[112:113], v[120:121] neg_lo:[0,1] neg_hi:[0,1]
	v_pk_fma_f32 v[104:105], v[104:105], s[40:41], v[126:127] op_sel:[0,0,1] op_sel_hi:[1,0,0]
	v_pk_add_f32 v[126:127], v[106:107], v[118:119]
	v_pk_add_f32 v[118:119], v[106:107], v[118:119] neg_lo:[0,1] neg_hi:[0,1]
	v_pk_mul_f32 v[120:121], v[112:113], s[42:43]
	v_pk_add_f32 v[100:101], v[92:93], v[116:117] op_sel:[0,1] op_sel_hi:[1,0] neg_hi:[0,1]
	v_pk_add_f32 v[92:93], v[92:93], v[116:117] op_sel:[0,1] op_sel_hi:[1,0] neg_lo:[0,1]
	v_pk_add_f32 v[116:117], v[94:95], v[102:103]
	v_pk_add_f32 v[94:95], v[94:95], v[102:103] neg_lo:[0,1] neg_hi:[0,1]
	v_pk_fma_f32 v[112:113], v[112:113], s[40:41], v[120:121] op_sel:[0,0,1] op_sel_hi:[1,0,0] neg_lo:[1,0,0] neg_hi:[1,0,0]
	v_pk_mul_f32 v[102:103], v[94:95], s[42:43]
	v_pk_fma_f32 v[94:95], v[94:95], s[40:41], v[102:103] op_sel:[0,0,1] op_sel_hi:[1,0,0]
	v_pk_add_f32 v[102:103], v[96:97], v[108:109]
	v_pk_add_f32 v[120:121], v[98:99], v[110:111]
	v_pk_add_f32 v[98:99], v[98:99], v[110:111] neg_lo:[0,1] neg_hi:[0,1]
	v_pk_add_f32 v[106:107], v[114:115], v[118:119] op_sel:[0,1] op_sel_hi:[1,0] neg_hi:[0,1]
	v_pk_add_f32 v[114:115], v[114:115], v[118:119] op_sel:[0,1] op_sel_hi:[1,0] neg_lo:[0,1]
	v_pk_add_f32 v[118:119], v[104:105], v[112:113]
	v_pk_add_f32 v[112:113], v[104:105], v[112:113] neg_lo:[0,1] neg_hi:[0,1]
	v_pk_add_f32 v[108:109], v[96:97], v[108:109] neg_lo:[0,1] neg_hi:[0,1]
	v_pk_mul_f32 v[110:111], v[98:99], s[42:43]
	v_pk_add_f32 v[130:131], v[100:101], v[102:103]
	v_pk_add_f32 v[100:101], v[100:101], v[102:103] neg_lo:[0,1] neg_hi:[0,1]
	v_pk_add_f32 v[102:103], v[116:117], v[120:121]
	v_pk_fma_f32 v[98:99], v[98:99], s[40:41], v[110:111] op_sel:[0,0,1] op_sel_hi:[1,0,0] neg_lo:[1,0,0] neg_hi:[1,0,0]
	v_pk_add_f32 v[110:111], v[122:123], v[126:127]
	v_pk_add_f32 v[122:123], v[122:123], v[126:127] neg_lo:[0,1] neg_hi:[0,1]
	v_pk_add_f32 v[126:127], v[124:125], v[128:129]
	v_pk_add_f32 v[104:105], v[114:115], v[112:113] op_sel:[0,1] op_sel_hi:[1,0] neg_hi:[0,1]
	v_pk_add_f32 v[112:113], v[114:115], v[112:113] op_sel:[0,1] op_sel_hi:[1,0] neg_lo:[0,1]
	v_pk_add_f32 v[114:115], v[130:131], v[102:103]
	v_pk_add_f32 v[124:125], v[124:125], v[128:129] neg_lo:[0,1] neg_hi:[0,1]
	v_pk_add_f32 v[96:97], v[92:93], v[108:109] op_sel:[0,1] op_sel_hi:[1,0] neg_hi:[0,1]
	v_pk_add_f32 v[92:93], v[92:93], v[108:109] op_sel:[0,1] op_sel_hi:[1,0] neg_lo:[0,1]
	v_pk_add_f32 v[108:109], v[94:95], v[98:99]
	v_pk_add_f32 v[132:133], v[110:111], v[126:127]
	v_pk_add_f32 v[110:111], v[110:111], v[126:127] neg_lo:[0,1] neg_hi:[0,1]
	v_pk_add_f32 v[126:127], v[106:107], v[118:119]
	v_pk_mul_f32 v[22:23], v[22:23], v[114:115] op_sel:[0,1] op_sel_hi:[1,0]
	v_xor_b32_e32 v129, 0x80000000, v124
	v_pk_add_f32 v[116:117], v[116:117], v[120:121] neg_lo:[0,1] neg_hi:[0,1]
	v_mov_b32_e32 v128, v125
	v_pk_add_f32 v[106:107], v[106:107], v[118:119] neg_lo:[0,1] neg_hi:[0,1]
	v_pk_add_f32 v[118:119], v[96:97], v[108:109]
	v_pk_fma_f32 v[22:23], v[24:25], v[114:115], v[22:23] op_sel_hi:[0,1,1]
	v_pk_mul_f32 v[24:25], v[32:33], v[126:127] op_sel:[0,1] op_sel_hi:[1,0]
	v_xor_b32_e32 v121, 0x80000000, v116
	v_pk_add_f32 v[94:95], v[94:95], v[98:99] neg_lo:[0,1] neg_hi:[0,1]
	v_pk_add_f32 v[124:125], v[122:123], v[128:129]
	v_mov_b32_e32 v120, v117
	v_pk_fma_f32 v[24:25], v[26:27], v[126:127], v[24:25] op_sel_hi:[0,1,1]
	v_pk_mul_f32 v[26:27], v[38:39], v[118:119] op_sel:[0,1] op_sel_hi:[1,0]
	v_xor_b32_e32 v99, 0x80000000, v94
	v_pk_add_f32 v[116:117], v[100:101], v[120:121]
	v_mov_b32_e32 v98, v95
	v_pk_fma_f32 v[26:27], v[28:29], v[118:119], v[26:27] op_sel_hi:[0,1,1]
	v_pk_mul_f32 v[28:29], v[34:35], v[124:125] op_sel:[0,1] op_sel_hi:[1,0]
	v_pk_add_f32 v[94:95], v[92:93], v[98:99]
	v_pk_fma_f32 v[28:29], v[30:31], v[124:125], v[28:29] op_sel_hi:[0,1,1]
	v_pk_mul_f32 v[30:31], v[40:41], v[116:117] op_sel:[0,1] op_sel_hi:[1,0]
	v_pk_add_f32 v[122:123], v[122:123], v[128:129] neg_lo:[0,1] neg_hi:[0,1]
	v_pk_add_f32 v[102:103], v[130:131], v[102:103] neg_lo:[0,1] neg_hi:[0,1]
	v_pk_add_f32 v[100:101], v[100:101], v[120:121] neg_lo:[0,1] neg_hi:[0,1]
	v_pk_add_f32 v[96:97], v[96:97], v[108:109] neg_lo:[0,1] neg_hi:[0,1]
	v_pk_add_f32 v[92:93], v[92:93], v[98:99] neg_lo:[0,1] neg_hi:[0,1]
	v_pk_fma_f32 v[30:31], v[36:37], v[116:117], v[30:31] op_sel_hi:[0,1,1]
	v_pk_mul_f32 v[32:33], v[44:45], v[104:105] op_sel:[0,1] op_sel_hi:[1,0]
	v_pk_mul_f32 v[34:35], v[48:49], v[94:95] op_sel:[0,1] op_sel_hi:[1,0]
	v_pk_mul_f32 v[36:37], v[52:53], v[110:111] op_sel:[0,1] op_sel_hi:[1,0]
	v_pk_fma_f32 v[32:33], v[42:43], v[104:105], v[32:33] op_sel_hi:[0,1,1]
	v_pk_fma_f32 v[34:35], v[46:47], v[94:95], v[34:35] op_sel_hi:[0,1,1]
	v_pk_fma_f32 v[36:37], v[50:51], v[110:111], v[36:37] op_sel_hi:[0,1,1]
	v_pk_mul_f32 v[38:39], v[56:57], v[102:103] op_sel:[0,1] op_sel_hi:[1,0]
	v_pk_mul_f32 v[40:41], v[60:61], v[106:107] op_sel:[0,1] op_sel_hi:[1,0]
	v_pk_mul_f32 v[42:43], v[68:69], v[96:97] op_sel:[0,1] op_sel_hi:[1,0]
	v_pk_mul_f32 v[44:45], v[72:73], v[122:123] op_sel:[0,1] op_sel_hi:[1,0]
	v_pk_mul_f32 v[46:47], v[76:77], v[100:101] op_sel:[0,1] op_sel_hi:[1,0]
	v_pk_mul_f32 v[48:49], v[80:81], v[112:113] op_sel:[0,1] op_sel_hi:[1,0]
	v_pk_mul_f32 v[50:51], v[84:85], v[92:93] op_sel:[0,1] op_sel_hi:[1,0]
	v_pk_fma_f32 v[38:39], v[54:55], v[102:103], v[38:39] op_sel_hi:[0,1,1]
	v_pk_fma_f32 v[40:41], v[58:59], v[106:107], v[40:41] op_sel_hi:[0,1,1]
	v_pk_fma_f32 v[42:43], v[66:67], v[96:97], v[42:43] op_sel_hi:[0,1,1]
	v_pk_fma_f32 v[44:45], v[70:71], v[122:123], v[44:45] op_sel_hi:[0,1,1]
	v_pk_fma_f32 v[46:47], v[74:75], v[100:101], v[46:47] op_sel_hi:[0,1,1]
	v_pk_fma_f32 v[48:49], v[78:79], v[112:113], v[48:49] op_sel_hi:[0,1,1]
	v_pk_fma_f32 v[50:51], v[82:83], v[92:93], v[50:51] op_sel_hi:[0,1,1]
	ds_write2_b64 v6, v[132:133], v[36:37] offset1:16
	ds_write2_b64 v6, v[28:29], v[44:45] offset0:33 offset1:49
	ds_write2_b64 v6, v[24:25], v[40:41] offset0:66 offset1:82
	ds_write2_b64 v6, v[32:33], v[48:49] offset0:99 offset1:115
	ds_write2_b64 v6, v[22:23], v[38:39] offset0:132 offset1:148
	ds_write2_b64 v6, v[30:31], v[46:47] offset0:165 offset1:181
	ds_write2_b64 v6, v[26:27], v[42:43] offset0:198 offset1:214
	ds_write2_b64 v6, v[34:35], v[50:51] offset0:231 offset1:247
	v_mov_b32_e32 v6, v62
	s_waitcnt lgkmcnt(0)
	s_barrier
	s_lshl_b32 s24, s71, 6
	v_bfe_i32 v11, v6, 1, 27
	v_lshl_add_u32 v68, v6, 7, 0
	v_lshl_add_u32 v11, v11, 3, v68
	ds_read2_b64 v[22:25], v11 offset1:1
	ds_read2_b64 v[26:29], v11 offset0:2 offset1:3
	ds_read2_b64 v[30:33], v11 offset0:8 offset1:9
	ds_read2_b64 v[34:37], v11 offset0:4 offset1:5
	ds_read2_b64 v[38:41], v11 offset0:6 offset1:7
	ds_read2_b64 v[42:45], v11 offset0:10 offset1:11
	ds_read2_b64 v[46:49], v11 offset0:12 offset1:13
	ds_read2_b64 v[50:53], v11 offset0:14 offset1:15
	s_waitcnt lgkmcnt(5)
	v_pk_add_f32 v[54:55], v[22:23], v[30:31]
	v_pk_add_f32 v[22:23], v[22:23], v[30:31] neg_lo:[0,1] neg_hi:[0,1]
	v_pk_add_f32 v[30:31], v[24:25], v[32:33]
	v_pk_add_f32 v[24:25], v[24:25], v[32:33] neg_lo:[0,1] neg_hi:[0,1]
	s_waitcnt lgkmcnt(1)
	v_pk_add_f32 v[56:57], v[36:37], v[48:49]
	v_pk_mul_f32 v[32:33], v[24:25], s[38:39]
	v_pk_add_f32 v[36:37], v[36:37], v[48:49] neg_lo:[0,1] neg_hi:[0,1]
	v_pk_fma_f32 v[24:25], v[24:25], s[36:37], v[32:33] op_sel:[0,0,1] op_sel_hi:[1,0,0]
	v_pk_add_f32 v[32:33], v[26:27], v[42:43]
	v_pk_add_f32 v[26:27], v[26:27], v[42:43] neg_lo:[0,1] neg_hi:[0,1]
	v_pk_mul_f32 v[48:49], v[36:37], s[44:45]
	v_pk_mul_f32 v[42:43], v[26:27], s[42:43]
	v_pk_fma_f32 v[36:37], v[36:37], s[62:63], v[48:49] op_sel:[0,0,1] op_sel_hi:[1,0,0] neg_lo:[1,0,0] neg_hi:[1,0,0]
	v_pk_fma_f32 v[26:27], v[26:27], s[40:41], v[42:43] op_sel:[0,0,1] op_sel_hi:[1,0,0]
	v_pk_add_f32 v[42:43], v[28:29], v[44:45]
	v_pk_add_f32 v[28:29], v[28:29], v[44:45] neg_lo:[0,1] neg_hi:[0,1]
	s_waitcnt lgkmcnt(0)
	v_pk_add_f32 v[48:49], v[38:39], v[50:51]
	v_pk_add_f32 v[38:39], v[38:39], v[50:51] neg_lo:[0,1] neg_hi:[0,1]
	v_pk_mul_f32 v[44:45], v[28:29], s[44:45]
	v_pk_mul_f32 v[50:51], v[38:39], s[42:43]
	v_pk_fma_f32 v[28:29], v[28:29], s[62:63], v[44:45] op_sel:[0,0,1] op_sel_hi:[1,0,0]
	v_pk_add_f32 v[44:45], v[34:35], v[46:47]
	v_pk_add_f32 v[46:47], v[34:35], v[46:47] neg_lo:[0,1] neg_hi:[0,1]
	v_pk_fma_f32 v[38:39], v[38:39], s[40:41], v[50:51] op_sel:[0,0,1] op_sel_hi:[1,0,0] neg_lo:[1,0,0] neg_hi:[1,0,0]
	v_pk_add_f32 v[50:51], v[40:41], v[52:53]
	v_pk_add_f32 v[40:41], v[40:41], v[52:53] neg_lo:[0,1] neg_hi:[0,1]
	v_pk_mul_f32 v[52:53], v[40:41], s[38:39]
	v_pk_add_f32 v[58:59], v[42:43], v[50:51]
	v_pk_add_f32 v[42:43], v[42:43], v[50:51] neg_lo:[0,1] neg_hi:[0,1]
	v_pk_fma_f32 v[40:41], v[40:41], s[36:37], v[52:53] op_sel:[0,0,1] op_sel_hi:[1,0,0] neg_lo:[1,0,0] neg_hi:[1,0,0]
	v_pk_add_f32 v[52:53], v[54:55], v[44:45]
	v_pk_add_f32 v[44:45], v[54:55], v[44:45] neg_lo:[0,1] neg_hi:[0,1]
	v_pk_add_f32 v[54:55], v[30:31], v[56:57]
	v_pk_add_f32 v[30:31], v[30:31], v[56:57] neg_lo:[0,1] neg_hi:[0,1]
	v_pk_mul_f32 v[50:51], v[42:43], s[42:43]
	v_pk_add_f32 v[34:35], v[22:23], v[46:47] op_sel:[0,1] op_sel_hi:[1,0] neg_hi:[0,1]
	v_pk_add_f32 v[22:23], v[22:23], v[46:47] op_sel:[0,1] op_sel_hi:[1,0] neg_lo:[0,1]
	v_pk_add_f32 v[46:47], v[24:25], v[36:37]
	v_pk_add_f32 v[24:25], v[24:25], v[36:37] neg_lo:[0,1] neg_hi:[0,1]
	v_pk_mul_f32 v[56:57], v[30:31], s[42:43]
	v_pk_fma_f32 v[42:43], v[42:43], s[40:41], v[50:51] op_sel:[0,0,1] op_sel_hi:[1,0,0] neg_lo:[1,0,0] neg_hi:[1,0,0]
	v_pk_mul_f32 v[36:37], v[24:25], s[42:43]
	v_pk_add_f32 v[50:51], v[28:29], v[40:41]
	v_pk_add_f32 v[28:29], v[28:29], v[40:41] neg_lo:[0,1] neg_hi:[0,1]
	v_pk_fma_f32 v[30:31], v[30:31], s[40:41], v[56:57] op_sel:[0,0,1] op_sel_hi:[1,0,0]
	v_pk_add_f32 v[56:57], v[32:33], v[48:49]
	v_pk_add_f32 v[48:49], v[32:33], v[48:49] neg_lo:[0,1] neg_hi:[0,1]
	v_pk_fma_f32 v[24:25], v[24:25], s[40:41], v[36:37] op_sel:[0,0,1] op_sel_hi:[1,0,0]
	v_pk_add_f32 v[36:37], v[26:27], v[38:39]
	v_pk_add_f32 v[38:39], v[26:27], v[38:39] neg_lo:[0,1] neg_hi:[0,1]
	v_pk_mul_f32 v[40:41], v[28:29], s[42:43]
	v_pk_fma_f32 v[28:29], v[28:29], s[40:41], v[40:41] op_sel:[0,0,1] op_sel_hi:[1,0,0] neg_lo:[1,0,0] neg_hi:[1,0,0]
	v_lshl_add_u32 v6, v6, 4, v90
	v_pk_add_f32 v[40:41], v[52:53], v[56:57]
	v_pk_add_f32 v[52:53], v[52:53], v[56:57] neg_lo:[0,1] neg_hi:[0,1]
	v_pk_add_f32 v[56:57], v[54:55], v[58:59]
	v_pk_add_f32 v[58:59], v[54:55], v[58:59] neg_lo:[0,1] neg_hi:[0,1]
	v_pk_add_f32 v[32:33], v[44:45], v[48:49] op_sel:[0,1] op_sel_hi:[1,0] neg_hi:[0,1]
	v_pk_add_f32 v[44:45], v[44:45], v[48:49] op_sel:[0,1] op_sel_hi:[1,0] neg_lo:[0,1]
	v_pk_add_f32 v[48:49], v[30:31], v[42:43]
	v_pk_add_f32 v[42:43], v[30:31], v[42:43] neg_lo:[0,1] neg_hi:[0,1]
	v_pk_add_f32 v[60:61], v[34:35], v[36:37]
	v_pk_add_f32 v[34:35], v[34:35], v[36:37] neg_lo:[0,1] neg_hi:[0,1]
	v_pk_add_f32 v[36:37], v[46:47], v[50:51]
	v_pk_add_f32 v[50:51], v[46:47], v[50:51] neg_lo:[0,1] neg_hi:[0,1]
	v_pk_add_f32 v[26:27], v[22:23], v[38:39] op_sel:[0,1] op_sel_hi:[1,0] neg_hi:[0,1]
	v_pk_add_f32 v[22:23], v[22:23], v[38:39] op_sel:[0,1] op_sel_hi:[1,0] neg_lo:[0,1]
	v_pk_add_f32 v[38:39], v[24:25], v[28:29]
	v_pk_add_f32 v[28:29], v[24:25], v[28:29] neg_lo:[0,1] neg_hi:[0,1]
	v_ashrrev_i32_e32 v6, 5, v6
	v_pk_add_f32 v[66:67], v[40:41], v[56:57]
	v_pk_add_f32 v[40:41], v[40:41], v[56:57] neg_lo:[0,1] neg_hi:[0,1]
	v_lshlrev_b32_e32 v6, 3, v6
	v_pk_add_f32 v[54:55], v[52:53], v[58:59] op_sel:[0,1] op_sel_hi:[1,0] neg_hi:[0,1]
	v_pk_add_f32 v[52:53], v[52:53], v[58:59] op_sel:[0,1] op_sel_hi:[1,0] neg_lo:[0,1]
	v_pk_add_f32 v[56:57], v[32:33], v[48:49]
	v_pk_add_f32 v[32:33], v[32:33], v[48:49] neg_lo:[0,1] neg_hi:[0,1]
	v_pk_add_f32 v[30:31], v[44:45], v[42:43] op_sel:[0,1] op_sel_hi:[1,0] neg_hi:[0,1]
	v_pk_add_f32 v[42:43], v[44:45], v[42:43] op_sel:[0,1] op_sel_hi:[1,0] neg_lo:[0,1]
	v_pk_add_f32 v[44:45], v[60:61], v[36:37]
	v_pk_add_f32 v[36:37], v[60:61], v[36:37] neg_lo:[0,1] neg_hi:[0,1]
	v_pk_add_f32 v[46:47], v[34:35], v[50:51] op_sel:[0,1] op_sel_hi:[1,0] neg_hi:[0,1]
	v_pk_add_f32 v[34:35], v[34:35], v[50:51] op_sel:[0,1] op_sel_hi:[1,0] neg_lo:[0,1]
	v_pk_add_f32 v[48:49], v[26:27], v[38:39]
	v_pk_add_f32 v[26:27], v[26:27], v[38:39] neg_lo:[0,1] neg_hi:[0,1]
	v_pk_add_f32 v[24:25], v[22:23], v[28:29] op_sel:[0,1] op_sel_hi:[1,0] neg_hi:[0,1]
	v_pk_add_f32 v[22:23], v[22:23], v[28:29] op_sel:[0,1] op_sel_hi:[1,0] neg_lo:[0,1]
	ds_write2_b64 v11, v[66:67], v[40:41] offset1:1
	ds_write2_b64 v11, v[54:55], v[52:53] offset0:2 offset1:3
	ds_write2_b64 v11, v[56:57], v[32:33] offset0:4 offset1:5
	ds_write2_b64 v11, v[30:31], v[42:43] offset0:6 offset1:7
	ds_write2_b64 v11, v[44:45], v[36:37] offset0:8 offset1:9
	ds_write2_b64 v11, v[46:47], v[34:35] offset0:10 offset1:11
	ds_write2_b64 v11, v[48:49], v[26:27] offset0:12 offset1:13
	ds_write2_b64 v11, v[24:25], v[22:23] offset0:14 offset1:15
	v_add3_u32 v6, v68, v6, s35
	ds_read2_b64 v[22:25], v6 offset1:1
	ds_read2_b64 v[26:29], v6 offset0:2 offset1:3
	ds_read2_b64 v[30:33], v6 offset0:8 offset1:9
	ds_read2_b64 v[34:37], v6 offset0:4 offset1:5
	ds_read2_b64 v[38:41], v6 offset0:6 offset1:7
	ds_read2_b64 v[42:45], v6 offset0:10 offset1:11
	ds_read2_b64 v[46:49], v6 offset0:12 offset1:13
	ds_read2_b64 v[50:53], v6 offset0:14 offset1:15
	s_waitcnt lgkmcnt(5)
	v_pk_add_f32 v[54:55], v[22:23], v[30:31]
	v_pk_add_f32 v[22:23], v[22:23], v[30:31] neg_lo:[0,1] neg_hi:[0,1]
	v_pk_add_f32 v[30:31], v[24:25], v[32:33]
	v_pk_add_f32 v[24:25], v[24:25], v[32:33] neg_lo:[0,1] neg_hi:[0,1]
	s_waitcnt lgkmcnt(1)
	v_pk_add_f32 v[56:57], v[36:37], v[48:49]
	v_pk_mul_f32 v[32:33], v[24:25], s[38:39]
	v_pk_add_f32 v[36:37], v[36:37], v[48:49] neg_lo:[0,1] neg_hi:[0,1]
	v_pk_fma_f32 v[24:25], v[24:25], s[36:37], v[32:33] op_sel:[0,0,1] op_sel_hi:[1,0,0]
	v_pk_add_f32 v[32:33], v[26:27], v[42:43]
	v_pk_add_f32 v[26:27], v[26:27], v[42:43] neg_lo:[0,1] neg_hi:[0,1]
	v_pk_mul_f32 v[48:49], v[36:37], s[44:45]
	v_pk_mul_f32 v[42:43], v[26:27], s[42:43]
	v_pk_fma_f32 v[36:37], v[36:37], s[62:63], v[48:49] op_sel:[0,0,1] op_sel_hi:[1,0,0] neg_lo:[1,0,0] neg_hi:[1,0,0]
	v_pk_fma_f32 v[26:27], v[26:27], s[40:41], v[42:43] op_sel:[0,0,1] op_sel_hi:[1,0,0]
	v_pk_add_f32 v[42:43], v[28:29], v[44:45]
	v_pk_add_f32 v[28:29], v[28:29], v[44:45] neg_lo:[0,1] neg_hi:[0,1]
	s_waitcnt lgkmcnt(0)
	v_pk_add_f32 v[48:49], v[38:39], v[50:51]
	v_pk_add_f32 v[38:39], v[38:39], v[50:51] neg_lo:[0,1] neg_hi:[0,1]
	v_pk_mul_f32 v[44:45], v[28:29], s[44:45]
	v_pk_mul_f32 v[50:51], v[38:39], s[42:43]
	v_pk_fma_f32 v[28:29], v[28:29], s[62:63], v[44:45] op_sel:[0,0,1] op_sel_hi:[1,0,0]
	v_pk_add_f32 v[44:45], v[34:35], v[46:47]
	v_pk_add_f32 v[46:47], v[34:35], v[46:47] neg_lo:[0,1] neg_hi:[0,1]
	v_pk_fma_f32 v[38:39], v[38:39], s[40:41], v[50:51] op_sel:[0,0,1] op_sel_hi:[1,0,0] neg_lo:[1,0,0] neg_hi:[1,0,0]
	v_pk_add_f32 v[50:51], v[40:41], v[52:53]
	v_pk_add_f32 v[40:41], v[40:41], v[52:53] neg_lo:[0,1] neg_hi:[0,1]
	v_pk_mul_f32 v[52:53], v[40:41], s[38:39]
	v_pk_add_f32 v[58:59], v[42:43], v[50:51]
	v_pk_add_f32 v[42:43], v[42:43], v[50:51] neg_lo:[0,1] neg_hi:[0,1]
	v_pk_fma_f32 v[40:41], v[40:41], s[36:37], v[52:53] op_sel:[0,0,1] op_sel_hi:[1,0,0] neg_lo:[1,0,0] neg_hi:[1,0,0]
	v_pk_mul_f32 v[50:51], v[42:43], s[42:43]
	v_pk_add_f32 v[34:35], v[22:23], v[46:47] op_sel:[0,1] op_sel_hi:[1,0] neg_hi:[0,1]
	v_pk_add_f32 v[22:23], v[22:23], v[46:47] op_sel:[0,1] op_sel_hi:[1,0] neg_lo:[0,1]
	v_pk_add_f32 v[46:47], v[24:25], v[36:37]
	v_pk_add_f32 v[24:25], v[24:25], v[36:37] neg_lo:[0,1] neg_hi:[0,1]
	v_pk_add_f32 v[52:53], v[54:55], v[44:45]
	v_pk_add_f32 v[44:45], v[54:55], v[44:45] neg_lo:[0,1] neg_hi:[0,1]
	v_pk_add_f32 v[54:55], v[30:31], v[56:57]
	v_pk_add_f32 v[30:31], v[30:31], v[56:57] neg_lo:[0,1] neg_hi:[0,1]
	v_pk_fma_f32 v[42:43], v[42:43], s[40:41], v[50:51] op_sel:[0,0,1] op_sel_hi:[1,0,0] neg_lo:[1,0,0] neg_hi:[1,0,0]
	v_pk_mul_f32 v[36:37], v[24:25], s[42:43]
	v_pk_add_f32 v[50:51], v[28:29], v[40:41]
	v_pk_add_f32 v[28:29], v[28:29], v[40:41] neg_lo:[0,1] neg_hi:[0,1]
	s_and_b32 s24, s24, 0xc0
	v_pk_mul_f32 v[56:57], v[30:31], s[42:43]
	v_pk_fma_f32 v[24:25], v[24:25], s[40:41], v[36:37] op_sel:[0,0,1] op_sel_hi:[1,0,0]
	v_pk_add_f32 v[36:37], v[26:27], v[38:39]
	v_pk_add_f32 v[38:39], v[26:27], v[38:39] neg_lo:[0,1] neg_hi:[0,1]
	v_pk_mul_f32 v[40:41], v[28:29], s[42:43]
	s_lshl_b64 s[62:63], s[50:51], 19
	v_pk_fma_f32 v[30:31], v[30:31], s[40:41], v[56:57] op_sel:[0,0,1] op_sel_hi:[1,0,0]
	v_pk_add_f32 v[56:57], v[32:33], v[48:49]
	v_pk_add_f32 v[48:49], v[32:33], v[48:49] neg_lo:[0,1] neg_hi:[0,1]
	s_nop 0
	v_pk_fma_f32 v[28:29], v[28:29], s[40:41], v[40:41] op_sel:[0,0,1] op_sel_hi:[1,0,0] neg_lo:[1,0,0] neg_hi:[1,0,0]
	s_add_u32 s43, s3, s62
	s_nop 0
	s_nop 0
	v_pk_add_f32 v[26:27], v[22:23], v[38:39] op_sel:[0,1] op_sel_hi:[1,0] neg_hi:[0,1]
	v_pk_add_f32 v[22:23], v[22:23], v[38:39] op_sel:[0,1] op_sel_hi:[1,0] neg_lo:[0,1]
	v_pk_add_f32 v[38:39], v[24:25], v[28:29]
	v_pk_add_f32 v[24:25], v[24:25], v[28:29] neg_lo:[0,1] neg_hi:[0,1]
	s_addc_u32 s45, s29, s63
	s_lshl_b32 s64, s24, 2
	v_pk_add_f32 v[40:41], v[52:53], v[56:57]
	v_pk_add_f32 v[52:53], v[52:53], v[56:57] neg_lo:[0,1] neg_hi:[0,1]
	v_pk_add_f32 v[56:57], v[54:55], v[58:59]
	v_pk_add_f32 v[54:55], v[54:55], v[58:59] neg_lo:[0,1] neg_hi:[0,1]
	v_pk_add_f32 v[32:33], v[44:45], v[48:49] op_sel:[0,1] op_sel_hi:[1,0] neg_hi:[0,1]
	v_pk_add_f32 v[44:45], v[44:45], v[48:49] op_sel:[0,1] op_sel_hi:[1,0] neg_lo:[0,1]
	v_pk_add_f32 v[48:49], v[30:31], v[42:43]
	v_pk_add_f32 v[42:43], v[30:31], v[42:43] neg_lo:[0,1] neg_hi:[0,1]
	v_pk_add_f32 v[60:61], v[34:35], v[36:37]
	v_pk_add_f32 v[34:35], v[34:35], v[36:37] neg_lo:[0,1] neg_hi:[0,1]
	v_pk_add_f32 v[36:37], v[46:47], v[50:51]
	v_pk_add_f32 v[46:47], v[46:47], v[50:51] neg_lo:[0,1] neg_hi:[0,1]
	v_xor_b32_e32 v29, 0x80000000, v24
	v_mov_b32_e32 v28, v25
	s_add_u32 s64, s43, s64
	v_xor_b32_e32 v59, 0x80000000, v54
	s_nop 0
	v_xor_b32_e32 v51, 0x80000000, v46
	v_pk_add_f32 v[66:67], v[40:41], v[56:57]
	v_pk_add_f32 v[40:41], v[40:41], v[56:57] neg_lo:[0,1] neg_hi:[0,1]
	v_mov_b32_e32 v58, v55
	v_mov_b32_e32 v50, v47
	v_pk_add_f32 v[24:25], v[22:23], v[28:29]
	v_pk_add_f32 v[22:23], v[22:23], v[28:29] neg_lo:[0,1] neg_hi:[0,1]
	s_addc_u32 s65, s45, 0
	v_pk_add_f32 v[54:55], v[52:53], v[58:59]
	v_pk_add_f32 v[52:53], v[52:53], v[58:59] neg_lo:[0,1] neg_hi:[0,1]
	v_pk_add_f32 v[56:57], v[32:33], v[48:49]
	v_pk_add_f32 v[32:33], v[32:33], v[48:49] neg_lo:[0,1] neg_hi:[0,1]
	v_pk_add_f32 v[30:31], v[44:45], v[42:43] op_sel:[0,1] op_sel_hi:[1,0] neg_hi:[0,1]
	v_pk_add_f32 v[42:43], v[44:45], v[42:43] op_sel:[0,1] op_sel_hi:[1,0] neg_lo:[0,1]
	v_pk_add_f32 v[44:45], v[60:61], v[36:37]
	v_pk_add_f32 v[36:37], v[60:61], v[36:37] neg_lo:[0,1] neg_hi:[0,1]
	v_pk_add_f32 v[46:47], v[34:35], v[50:51]
	v_pk_add_f32 v[34:35], v[34:35], v[50:51] neg_lo:[0,1] neg_hi:[0,1]
	v_pk_add_f32 v[48:49], v[26:27], v[38:39]
	v_pk_add_f32 v[26:27], v[26:27], v[38:39] neg_lo:[0,1] neg_hi:[0,1]
	ds_write2_b64 v6, v[66:67], v[40:41] offset1:1
	ds_write2_b64 v6, v[54:55], v[52:53] offset0:2 offset1:3
	ds_write2_b64 v6, v[56:57], v[32:33] offset0:4 offset1:5
	ds_write2_b64 v6, v[30:31], v[42:43] offset0:6 offset1:7
	ds_write2_b64 v6, v[44:45], v[36:37] offset0:8 offset1:9
	ds_write2_b64 v6, v[46:47], v[34:35] offset0:10 offset1:11
	ds_write2_b64 v6, v[48:49], v[26:27] offset0:12 offset1:13
	ds_write2_b64 v6, v[24:25], v[22:23] offset0:14 offset1:15
	v_lshl_add_u64 v[22:23], s[64:65], 0, v[20:21]
	s_mov_b64 s[64:65], 0
	v_mov_b32_e32 v11, v9
	v_mov_b64_e32 v[24:25], v[62:63]
	s_waitcnt lgkmcnt(0)
	s_barrier

.LBB0_271:
	global_load_dword v40, v35, s[18:19]
	v_lshl_add_u64 v[44:45], s[18:19], 0, v[34:35]
	global_load_dword v42, v[44:45], off
	s_waitcnt vmcnt(9)
	v_cvt_f32_f16_e32 v62, v6
	v_cvt_f32_f16_sdwa v44, v6 dst_sel:DWORD dst_unused:UNUSED_PAD src0_sel:WORD_1
	v_cvt_f32_f16_e32 v45, v7
	v_cvt_f32_f16_e32 v47, v8
	v_cvt_f32_f16_sdwa v48, v8 dst_sel:DWORD dst_unused:UNUSED_PAD src0_sel:WORD_1
	v_cvt_f32_f16_e32 v49, v9
	v_cvt_f32_f16_sdwa v8, v9 dst_sel:DWORD dst_unused:UNUSED_PAD src0_sel:WORD_1
	s_waitcnt vmcnt(8)
	v_cvt_f32_f16_e32 v9, v30
	s_waitcnt vmcnt(7)
	v_cvt_f32_f16_sdwa v52, v26 dst_sel:DWORD dst_unused:UNUSED_PAD src0_sel:WORD_1
	v_cvt_f32_f16_e32 v53, v27
	v_cvt_f32_f16_sdwa v46, v7 dst_sel:DWORD dst_unused:UNUSED_PAD src0_sel:WORD_1
	v_cvt_f32_f16_sdwa v50, v30 dst_sel:DWORD dst_unused:UNUSED_PAD src0_sel:WORD_1
	v_cvt_f32_f16_e32 v51, v31
	v_cvt_f32_f16_sdwa v30, v31 dst_sel:DWORD dst_unused:UNUSED_PAD src0_sel:WORD_1
	v_cvt_f32_f16_e32 v31, v32
	v_cvt_f32_f16_sdwa v7, v33 dst_sel:DWORD dst_unused:UNUSED_PAD src0_sel:WORD_1
	v_cvt_f32_f16_sdwa v32, v32 dst_sel:DWORD dst_unused:UNUSED_PAD src0_sel:WORD_1
	v_cvt_f32_f16_e32 v33, v33
	v_cvt_f32_f16_sdwa v26, v27 dst_sel:DWORD dst_unused:UNUSED_PAD src0_sel:WORD_1
	v_cvt_f32_f16_e32 v27, v28
	v_cvt_f32_f16_sdwa v54, v28 dst_sel:DWORD dst_unused:UNUSED_PAD src0_sel:WORD_1
	v_cvt_f32_f16_e32 v55, v29
	s_waitcnt vmcnt(6)
	v_cvt_f32_f16_e32 v28, v18
	v_cvt_f32_f16_sdwa v56, v18 dst_sel:DWORD dst_unused:UNUSED_PAD src0_sel:WORD_1
	v_cvt_f32_f16_e32 v57, v19
	v_cvt_f32_f16_sdwa v18, v19 dst_sel:DWORD dst_unused:UNUSED_PAD src0_sel:WORD_1
	v_cvt_f32_f16_e32 v19, v20
	v_cvt_f32_f16_sdwa v58, v20 dst_sel:DWORD dst_unused:UNUSED_PAD src0_sel:WORD_1
	v_cvt_f32_f16_e32 v59, v21
	v_cvt_f32_f16_sdwa v29, v29 dst_sel:DWORD dst_unused:UNUSED_PAD src0_sel:WORD_1
	v_cvt_f32_f16_sdwa v21, v21 dst_sel:DWORD dst_unused:UNUSED_PAD src0_sel:WORD_1
	v_cvt_f32_f16_e32 v20, v120
	s_waitcnt vmcnt(5)
	v_cvt_f32_f16_e32 v63, v22
	v_mul_f32_e32 v62, 0x3b800000, v62
	v_pk_mul_f32 v[44:45], v[44:45], s[38:39] op_sel_hi:[1,0]
	v_pk_mul_f32 v[8:9], v[8:9], s[38:39] op_sel_hi:[1,0]
	v_pk_mul_f32 v[52:53], v[52:53], s[38:39] op_sel_hi:[1,0]
	v_pk_mul_f32 v[46:47], v[46:47], s[38:39] op_sel_hi:[1,0]
	v_pk_mul_f32 v[48:49], v[48:49], s[38:39] op_sel_hi:[1,0]
	v_pk_mul_f32 v[50:51], v[50:51], s[38:39] op_sel_hi:[1,0]
	v_pk_mul_f32 v[30:31], v[30:31], s[38:39] op_sel_hi:[1,0]
	v_mul_f32_e32 v7, 0x3b800000, v7
	v_pk_mul_f32 v[32:33], v[32:33], s[38:39] op_sel_hi:[1,0]
	v_pk_mul_f32 v[26:27], v[26:27], s[38:39] op_sel_hi:[1,0]
	v_pk_mul_f32 v[54:55], v[54:55], s[38:39] op_sel_hi:[1,0]
	v_pk_mul_f32 v[56:57], v[56:57], s[38:39] op_sel_hi:[1,0]
	v_pk_mul_f32 v[18:19], v[18:19], s[38:39] op_sel_hi:[1,0]
	v_pk_mul_f32 v[58:59], v[58:59], s[38:39] op_sel_hi:[1,0]
	ds_write2_b32 v135, v44, v45 offset0:1 offset1:2
	ds_write2_b32 v135, v46, v47 offset0:3 offset1:4
	ds_write2_b32 v135, v48, v49 offset0:5 offset1:6
	ds_write2_b32 v135, v8, v9 offset0:7 offset1:8
	ds_write2_b32 v135, v50, v51 offset0:9 offset1:10
	ds_write2_b32 v135, v30, v31 offset0:11 offset1:12
	ds_write2_b32 v135, v32, v33 offset0:13 offset1:14
	v_pk_mov_b32 v[8:9], v[52:53], v[52:53] op_sel:[1,0]
	v_pk_mul_f32 v[28:29], v[28:29], s[38:39] op_sel_hi:[1,0]
	v_pk_mul_f32 v[20:21], v[20:21], s[38:39] op_sel_hi:[1,0]
	v_mul_f32_e32 v63, 0x3b800000, v63
	v_pk_mov_b32 v[26:27], v[26:27], v[26:27] op_sel:[1,0]
	v_pk_mov_b32 v[30:31], v[54:55], v[54:55] op_sel:[1,0]
	v_pk_mov_b32 v[32:33], v[56:57], v[56:57] op_sel:[1,0]
	v_pk_mov_b32 v[18:19], v[18:19], v[18:19] op_sel:[1,0]
	v_pk_mov_b32 v[44:45], v[58:59], v[58:59] op_sel:[1,0]
	ds_write_b64 v136, v[8:9]
	ds_write_b64 v137, v[26:27]
	ds_write_b64 v138, v[30:31]
	ds_write_b64 v139, v[28:29]
	ds_write_b64 v140, v[32:33]
	ds_write_b64 v141, v[18:19]
	ds_write_b64 v142, v[44:45]
	ds_write_b64 v143, v[20:21]
	v_cvt_f32_f16_e32 v9, v25
	s_waitcnt vmcnt(4)
	v_cvt_f32_f16_sdwa v18, v14 dst_sel:DWORD dst_unused:UNUSED_PAD src0_sel:WORD_1
	v_cvt_f32_f16_e32 v19, v15
	v_cvt_f32_f16_sdwa v60, v22 dst_sel:DWORD dst_unused:UNUSED_PAD src0_sel:WORD_1
	v_cvt_f32_f16_e32 v61, v23
	s_mov_b32 s10, s69
	s_mov_b32 s71, s64
	s_mov_b32 s78, s67
	v_pk_mul_f32 v[60:61], v[60:61], s[38:39] op_sel_hi:[1,0]
	s_mov_b32 s73, s50
	s_mov_b32 s76, s63
	s_waitcnt vmcnt(1)
	v_fma_mix_f32 v6, v6, s38, v40 op_sel_hi:[1,0,0]
	s_nop 0
	v_cndmask_b32_e64 v6, v62, v6, s[6:7]
	s_waitcnt vmcnt(0)
	v_fma_mix_f32 v8, v22, s38, v42 op_sel_hi:[1,0,0]
	ds_write2_b32 v135, v6, v7 offset1:15
	v_cvt_f32_f16_sdwa v6, v23 dst_sel:DWORD dst_unused:UNUSED_PAD src0_sel:WORD_1
	v_cvt_f32_f16_e32 v7, v24
	v_cndmask_b32_e64 v20, v63, v8, s[8:9]
	v_cvt_f32_f16_sdwa v8, v24 dst_sel:DWORD dst_unused:UNUSED_PAD src0_sel:WORD_1
	ds_write2_b32 v144, v60, v61 offset0:1 offset1:2
	v_pk_mul_f32 v[6:7], v[6:7], s[38:39] op_sel_hi:[1,0]
	ds_write2_b32 v144, v6, v7 offset0:3 offset1:4
	v_pk_mul_f32 v[6:7], v[8:9], s[38:39] op_sel_hi:[1,0]
	v_cvt_f32_f16_sdwa v8, v25 dst_sel:DWORD dst_unused:UNUSED_PAD src0_sel:WORD_1
	v_cvt_f32_f16_e32 v9, v14
	ds_write2_b32 v144, v6, v7 offset0:5 offset1:6
	v_cvt_f32_f16_sdwa v14, v17 dst_sel:DWORD dst_unused:UNUSED_PAD src0_sel:WORD_1
	v_pk_mul_f32 v[6:7], v[8:9], s[38:39] op_sel_hi:[1,0]
	ds_write2_b32 v144, v6, v7 offset0:7 offset1:8
	v_pk_mul_f32 v[6:7], v[18:19], s[38:39] op_sel_hi:[1,0]
	ds_write2_b32 v144, v6, v7 offset0:9 offset1:10
	v_cvt_f32_f16_sdwa v6, v15 dst_sel:DWORD dst_unused:UNUSED_PAD src0_sel:WORD_1
	v_cvt_f32_f16_e32 v7, v16
	v_cvt_f32_f16_sdwa v8, v16 dst_sel:DWORD dst_unused:UNUSED_PAD src0_sel:WORD_1
	v_cvt_f32_f16_e32 v9, v17
	v_mul_f32_e32 v14, 0x3b800000, v14
	v_pk_mul_f32 v[6:7], v[6:7], s[38:39] op_sel_hi:[1,0]
	ds_write2_b32 v144, v6, v7 offset0:11 offset1:12
	v_pk_mul_f32 v[6:7], v[8:9], s[38:39] op_sel_hi:[1,0]
	ds_write2_b32 v144, v6, v7 offset0:13 offset1:14
	v_cvt_f32_f16_sdwa v6, v10 dst_sel:DWORD dst_unused:UNUSED_PAD src0_sel:WORD_1
	v_cvt_f32_f16_e32 v7, v11
	v_cvt_f32_f16_sdwa v8, v11 dst_sel:DWORD dst_unused:UNUSED_PAD src0_sel:WORD_1
	v_cvt_f32_f16_e32 v9, v12
	ds_write2_b32 v144, v20, v14 offset1:15
	v_pk_mul_f32 v[6:7], v[6:7], s[38:39] op_sel_hi:[1,0]
	s_nop 0
	v_pk_mov_b32 v[6:7], v[6:7], v[6:7] op_sel:[1,0]
	ds_write_b64 v145, v[6:7]
	v_pk_mul_f32 v[6:7], v[8:9], s[38:39] op_sel_hi:[1,0]
	v_cvt_f32_f16_sdwa v8, v12 dst_sel:DWORD dst_unused:UNUSED_PAD src0_sel:WORD_1
	v_cvt_f32_f16_e32 v9, v13
	v_pk_mov_b32 v[6:7], v[6:7], v[6:7] op_sel:[1,0]
	ds_write_b64 v147, v[6:7]
	v_cvt_f32_f16_sdwa v7, v13 dst_sel:DWORD dst_unused:UNUSED_PAD src0_sel:WORD_1
	v_pk_mul_f32 v[8:9], v[8:9], s[38:39] op_sel_hi:[1,0]
	v_cvt_f32_f16_e32 v6, v2
	v_pk_mov_b32 v[8:9], v[8:9], v[8:9] op_sel:[1,0]
	ds_write_b64 v148, v[8:9]
	v_cvt_f32_f16_sdwa v8, v2 dst_sel:DWORD dst_unused:UNUSED_PAD src0_sel:WORD_1
	v_cvt_f32_f16_e32 v9, v3
	v_cvt_f32_f16_sdwa v2, v3 dst_sel:DWORD dst_unused:UNUSED_PAD src0_sel:WORD_1
	v_cvt_f32_f16_e32 v3, v4
	v_pk_mul_f32 v[6:7], v[6:7], s[38:39] op_sel_hi:[1,0]
	ds_write_b64 v149, v[6:7]
	v_pk_mul_f32 v[6:7], v[8:9], s[38:39] op_sel_hi:[1,0]
	v_pk_mul_f32 v[2:3], v[2:3], s[38:39] op_sel_hi:[1,0]
	v_pk_mov_b32 v[6:7], v[6:7], v[6:7] op_sel:[1,0]
	ds_write_b64 v150, v[6:7]
	v_pk_mov_b32 v[2:3], v[2:3], v[2:3] op_sel:[1,0]
	v_cvt_f32_f16_sdwa v6, v4 dst_sel:DWORD dst_unused:UNUSED_PAD src0_sel:WORD_1
	v_cvt_f32_f16_e32 v7, v5
	ds_write_b64 v151, v[2:3]
	v_cvt_f32_f16_sdwa v3, v5 dst_sel:DWORD dst_unused:UNUSED_PAD src0_sel:WORD_1
	v_cvt_f32_f16_e32 v2, v43
	v_pk_mul_f32 v[4:5], v[6:7], s[38:39] op_sel_hi:[1,0]
	v_pk_mul_f32 v[2:3], v[2:3], s[38:39] op_sel_hi:[1,0]
	v_pk_mov_b32 v[4:5], v[4:5], v[4:5] op_sel:[1,0]
	ds_write_b64 v152, v[4:5]
	ds_write_b64 v153, v[2:3]
	v_mov_b32_e32 v2, v1
	s_waitcnt lgkmcnt(0)
	s_barrier
	s_nop 0
	v_and_b32_e32 v3, 0x1ff, v2
	v_lshlrev_b32_e32 v2, 5, v2
	v_and_or_b32 v2, v2, s3, v3
	v_cvt_f32_u32_e32 v4, v3
	v_ashrrev_i32_e32 v3, 5, v2
	v_lshlrev_b32_e32 v5, 3, v2
	v_lshlrev_b32_e32 v3, 3, v3
	v_add3_u32 v40, 0, v5, v3
	v_add_u32_e32 v155, 0x10800, v40
	ds_read_b64 v[156:157], v40
	ds_read_b64 v[158:159], v40 offset:4224
	ds_read_b64 v[160:161], v40 offset:8448
	ds_read_b64 v[162:163], v40 offset:12672
	ds_read_b64 v[164:165], v40 offset:16896
	ds_read_b64 v[166:167], v40 offset:21120
	ds_read_b64 v[168:169], v40 offset:25344
	ds_read_b64 v[170:171], v40 offset:29568
	ds_read_b64 v[172:173], v40 offset:33792
	ds_read_b64 v[174:175], v40 offset:38016
	ds_read_b64 v[176:177], v40 offset:42240
	ds_read_b64 v[178:179], v40 offset:46464
	ds_read_b64 v[180:181], v40 offset:50688
	ds_read_b64 v[182:183], v40 offset:54912
	ds_read_b64 v[184:185], v40 offset:59136
	ds_read_b64 v[186:187], v40 offset:63360
	v_add_u32_e32 v201, 0x11880, v40
	v_add_u32_e32 v224, 0x12900, v40
	v_add_u32_e32 v225, 0x13980, v40
	ds_read_b64 v[188:189], v155
	ds_read_b64 v[190:191], v201
	ds_read_b64 v[192:193], v224
	ds_read_b64 v[194:195], v225
	v_add_u32_e32 v226, 0x14a00, v40
	s_waitcnt lgkmcnt(3)
	v_pk_add_f32 v[222:223], v[156:157], v[188:189]
	v_pk_add_f32 v[156:157], v[156:157], v[188:189] neg_lo:[0,1] neg_hi:[0,1]
	s_waitcnt lgkmcnt(2)
	v_pk_add_f32 v[188:189], v[158:159], v[190:191]
	v_pk_add_f32 v[158:159], v[158:159], v[190:191] neg_lo:[0,1] neg_hi:[0,1]
	v_add_u32_e32 v227, 0x15a80, v40
	v_pk_mul_f32 v[190:191], v[158:159], s[46:47]
	v_add_u32_e32 v228, 0x16b00, v40
	v_pk_fma_f32 v[158:159], v[158:159], s[42:43], v[190:191] op_sel:[0,0,1] op_sel_hi:[1,0,0]
	s_waitcnt lgkmcnt(1)
	v_pk_add_f32 v[190:191], v[160:161], v[192:193]
	v_pk_add_f32 v[160:161], v[160:161], v[192:193] neg_lo:[0,1] neg_hi:[0,1]
	v_add_u32_e32 v229, 0x17b80, v40
	v_pk_mul_f32 v[192:193], v[160:161], s[62:63]
	ds_read_b64 v[196:197], v226
	ds_read_b64 v[198:199], v227
	ds_read_b64 v[202:203], v228
	ds_read_b64 v[204:205], v229
	v_pk_fma_f32 v[160:161], v[160:161], s[50:51], v[192:193] op_sel:[0,0,1] op_sel_hi:[1,0,0]
	s_waitcnt lgkmcnt(4)
	v_pk_add_f32 v[192:193], v[162:163], v[194:195]
	v_pk_add_f32 v[162:163], v[162:163], v[194:195] neg_lo:[0,1] neg_hi:[0,1]
	v_add_u32_e32 v230, 0x18c00, v40
	v_pk_mul_f32 v[194:195], v[162:163], s[66:67]
	v_add_u32_e32 v231, 0x19c80, v40
	v_pk_fma_f32 v[162:163], v[162:163], s[64:65], v[194:195] op_sel:[0,0,1] op_sel_hi:[1,0,0]
	s_waitcnt lgkmcnt(3)
	v_pk_add_f32 v[194:195], v[164:165], v[196:197]
	v_pk_add_f32 v[164:165], v[164:165], v[196:197] neg_lo:[0,1] neg_hi:[0,1]
	v_add_u32_e32 v232, 0x1ad00, v40
	v_pk_mul_f32 v[196:197], v[164:165], s[68:69]
	v_add_u32_e32 v233, 0x1bd80, v40
	v_pk_fma_f32 v[164:165], v[164:165], s[10:11], v[196:197] op_sel:[0,0,1] op_sel_hi:[1,0,0]
	s_waitcnt lgkmcnt(2)
	v_pk_add_f32 v[196:197], v[166:167], v[198:199]
	v_pk_add_f32 v[166:167], v[166:167], v[198:199] neg_lo:[0,1] neg_hi:[0,1]
	ds_read_b64 v[206:207], v230
	ds_read_b64 v[208:209], v231
	ds_read_b64 v[210:211], v232
	ds_read_b64 v[212:213], v233
	v_pk_mul_f32 v[198:199], v[166:167], s[70:71]
	v_add_u32_e32 v234, 0x1ce00, v40
	v_pk_fma_f32 v[166:167], v[166:167], s[78:79], v[198:199] op_sel:[0,0,1] op_sel_hi:[1,0,0]
	s_waitcnt lgkmcnt(5)
	v_pk_add_f32 v[198:199], v[168:169], v[202:203]
	v_pk_add_f32 v[168:169], v[168:169], v[202:203] neg_lo:[0,1] neg_hi:[0,1]
	v_add_u32_e32 v235, 0x1de80, v40
	v_pk_mul_f32 v[202:203], v[168:169], s[72:73]
	v_add_u32_e32 v236, 0x1ef00, v40
	v_pk_fma_f32 v[168:169], v[168:169], s[76:77], v[202:203] op_sel:[0,0,1] op_sel_hi:[1,0,0]
	s_waitcnt lgkmcnt(4)
	v_pk_add_f32 v[202:203], v[170:171], v[204:205]
	v_pk_add_f32 v[170:171], v[170:171], v[204:205] neg_lo:[0,1] neg_hi:[0,1]
	v_add_u32_e32 v237, 0x1ff80, v40
	v_pk_mul_f32 v[204:205], v[170:171], s[40:41]
	ds_read_b64 v[214:215], v234
	ds_read_b64 v[216:217], v235
	ds_read_b64 v[218:219], v236
	ds_read_b64 v[220:221], v237
	v_pk_fma_f32 v[170:171], v[170:171], s[44:45], v[204:205] op_sel:[0,0,1] op_sel_hi:[1,0,0]
	s_waitcnt lgkmcnt(7)
	v_pk_add_f32 v[204:205], v[172:173], v[206:207]
	v_pk_add_f32 v[206:207], v[172:173], v[206:207] neg_lo:[0,1] neg_hi:[0,1]
	v_mul_f32_e32 v4, 0x38800000, v4
	s_waitcnt lgkmcnt(6)
	v_pk_add_f32 v[172:173], v[174:175], v[208:209]
	v_pk_add_f32 v[174:175], v[174:175], v[208:209] neg_lo:[0,1] neg_hi:[0,1]
	v_sin_f32_e32 v2, v4
	v_pk_mul_f32 v[208:209], v[174:175], s[40:41]
	v_cos_f32_e32 v4, v4
	v_pk_fma_f32 v[174:175], v[174:175], s[44:45], v[208:209] op_sel:[0,0,1] op_sel_hi:[1,0,0] neg_lo:[1,0,0] neg_hi:[1,0,0]
	s_waitcnt lgkmcnt(5)
	v_pk_add_f32 v[208:209], v[176:177], v[210:211]
	v_pk_add_f32 v[176:177], v[176:177], v[210:211] neg_lo:[0,1] neg_hi:[0,1]
	v_xor_b32_e32 v5, 0x80000000, v2
	v_pk_mul_f32 v[210:211], v[176:177], s[72:73]
	v_mov_b32_e32 v3, v5
	v_pk_fma_f32 v[176:177], v[176:177], s[76:77], v[210:211] op_sel:[0,0,1] op_sel_hi:[1,0,0] neg_lo:[1,0,0] neg_hi:[1,0,0]
	s_waitcnt lgkmcnt(4)
	v_pk_add_f32 v[210:211], v[178:179], v[212:213]
	v_pk_add_f32 v[178:179], v[178:179], v[212:213] neg_lo:[0,1] neg_hi:[0,1]
	v_pk_mul_f32 v[6:7], v[4:5], v[2:3] op_sel:[1,0] op_sel_hi:[0,1]
	v_pk_mul_f32 v[212:213], v[178:179], s[70:71]
	v_pk_fma_f32 v[6:7], v[4:5], v[4:5], v[6:7] op_sel_hi:[1,0,1]
	v_pk_fma_f32 v[178:179], v[178:179], s[78:79], v[212:213] op_sel:[0,0,1] op_sel_hi:[1,0,0] neg_lo:[1,0,0] neg_hi:[1,0,0]
	s_waitcnt lgkmcnt(3)
	v_pk_add_f32 v[212:213], v[180:181], v[214:215]
	v_pk_add_f32 v[180:181], v[180:181], v[214:215] neg_lo:[0,1] neg_hi:[0,1]
	v_xor_b32_e32 v12, 0x80000000, v7
	v_pk_mul_f32 v[214:215], v[180:181], s[68:69]
	v_mov_b32_e32 v13, v7
	v_pk_fma_f32 v[180:181], v[180:181], s[10:11], v[214:215] op_sel:[0,0,1] op_sel_hi:[1,0,0] neg_lo:[1,0,0] neg_hi:[1,0,0]
	s_waitcnt lgkmcnt(2)
	v_pk_add_f32 v[214:215], v[182:183], v[216:217]
	v_pk_add_f32 v[182:183], v[182:183], v[216:217] neg_lo:[0,1] neg_hi:[0,1]
	v_pk_mul_f32 v[10:11], v[6:7], v[12:13] op_sel:[1,0] op_sel_hi:[0,1]
	v_pk_mul_f32 v[216:217], v[182:183], s[66:67]
	v_pk_fma_f32 v[10:11], v[6:7], v[6:7], v[10:11] op_sel_hi:[1,0,1]
	v_pk_fma_f32 v[182:183], v[182:183], s[64:65], v[216:217] op_sel:[0,0,1] op_sel_hi:[1,0,0] neg_lo:[1,0,0] neg_hi:[1,0,0]
	s_waitcnt lgkmcnt(1)
	v_pk_add_f32 v[216:217], v[184:185], v[218:219]
	v_pk_add_f32 v[184:185], v[184:185], v[218:219] neg_lo:[0,1] neg_hi:[0,1]
	v_xor_b32_e32 v14, 0x80000000, v11
	v_pk_mul_f32 v[218:219], v[184:185], s[62:63]
	v_mov_b32_e32 v15, v11
	v_pk_fma_f32 v[184:185], v[184:185], s[50:51], v[218:219] op_sel:[0,0,1] op_sel_hi:[1,0,0] neg_lo:[1,0,0] neg_hi:[1,0,0]
	s_waitcnt lgkmcnt(0)
	v_pk_add_f32 v[218:219], v[186:187], v[220:221]
	v_pk_add_f32 v[186:187], v[186:187], v[220:221] neg_lo:[0,1] neg_hi:[0,1]
	v_pk_mul_f32 v[26:27], v[10:11], v[14:15] op_sel:[1,0] op_sel_hi:[0,1]
	v_pk_mul_f32 v[220:221], v[186:187], s[46:47]
	v_pk_fma_f32 v[26:27], v[10:11], v[10:11], v[26:27] op_sel_hi:[1,0,1]
	v_pk_fma_f32 v[186:187], v[186:187], s[42:43], v[220:221] op_sel:[0,0,1] op_sel_hi:[1,0,0] neg_lo:[1,0,0] neg_hi:[1,0,0]
	v_pk_add_f32 v[220:221], v[222:223], v[204:205]
	v_pk_add_f32 v[204:205], v[222:223], v[204:205] neg_lo:[0,1] neg_hi:[0,1]
	v_pk_add_f32 v[222:223], v[188:189], v[172:173]
	v_pk_add_f32 v[172:173], v[188:189], v[172:173] neg_lo:[0,1] neg_hi:[0,1]
	v_pk_mul_f32 v[50:51], v[14:15], v[26:27] op_sel:[0,1] op_sel_hi:[1,0]
	v_pk_mul_f32 v[188:189], v[172:173], s[62:63]
	v_pk_fma_f32 v[50:51], v[10:11], v[26:27], v[50:51] op_sel_hi:[0,1,1]
	v_pk_fma_f32 v[172:173], v[172:173], s[50:51], v[188:189] op_sel:[0,0,1] op_sel_hi:[1,0,0]
	v_pk_add_f32 v[188:189], v[190:191], v[208:209]
	v_pk_add_f32 v[190:191], v[190:191], v[208:209] neg_lo:[0,1] neg_hi:[0,1]
	v_pk_mul_f32 v[66:67], v[14:15], v[50:51] op_sel:[0,1] op_sel_hi:[1,0]
	v_pk_mul_f32 v[208:209], v[190:191], s[68:69]
	v_pk_fma_f32 v[66:67], v[10:11], v[50:51], v[66:67] op_sel_hi:[0,1,1]
	v_pk_fma_f32 v[190:191], v[190:191], s[10:11], v[208:209] op_sel:[0,0,1] op_sel_hi:[1,0,0]
	v_pk_add_f32 v[208:209], v[192:193], v[210:211]
	v_pk_add_f32 v[192:193], v[192:193], v[210:211] neg_lo:[0,1] neg_hi:[0,1]
	v_pk_mul_f32 v[82:83], v[14:15], v[66:67] op_sel:[0,1] op_sel_hi:[1,0]
	v_pk_mul_f32 v[210:211], v[192:193], s[72:73]
	v_pk_fma_f32 v[82:83], v[10:11], v[66:67], v[82:83] op_sel_hi:[0,1,1]
	v_pk_fma_f32 v[192:193], v[192:193], s[76:77], v[210:211] op_sel:[0,0,1] op_sel_hi:[1,0,0]
	v_pk_add_f32 v[210:211], v[194:195], v[212:213]
	v_pk_add_f32 v[212:213], v[194:195], v[212:213] neg_lo:[0,1] neg_hi:[0,1]
	v_pk_mul_f32 v[98:99], v[14:15], v[82:83] op_sel:[0,1] op_sel_hi:[1,0]
	v_pk_add_f32 v[194:195], v[196:197], v[214:215]
	v_pk_add_f32 v[196:197], v[196:197], v[214:215] neg_lo:[0,1] neg_hi:[0,1]
	v_pk_fma_f32 v[98:99], v[10:11], v[82:83], v[98:99] op_sel_hi:[0,1,1]
	v_pk_mul_f32 v[214:215], v[196:197], s[72:73]
	v_pk_mul_f32 v[114:115], v[14:15], v[98:99] op_sel:[0,1] op_sel_hi:[1,0]
	v_pk_fma_f32 v[196:197], v[196:197], s[76:77], v[214:215] op_sel:[0,0,1] op_sel_hi:[1,0,0] neg_lo:[1,0,0] neg_hi:[1,0,0]
	v_pk_add_f32 v[214:215], v[198:199], v[216:217]
	v_pk_add_f32 v[198:199], v[198:199], v[216:217] neg_lo:[0,1] neg_hi:[0,1]
	v_pk_mul_f32 v[8:9], v[2:3], v[6:7] op_sel:[0,1] op_sel_hi:[1,0]
	v_pk_mul_f32 v[216:217], v[198:199], s[68:69]
	v_pk_fma_f32 v[114:115], v[10:11], v[98:99], v[114:115] op_sel_hi:[0,1,1]
	v_pk_fma_f32 v[198:199], v[198:199], s[10:11], v[216:217] op_sel:[0,0,1] op_sel_hi:[1,0,0] neg_lo:[1,0,0] neg_hi:[1,0,0]
	v_pk_add_f32 v[216:217], v[202:203], v[218:219]
	v_pk_add_f32 v[202:203], v[202:203], v[218:219] neg_lo:[0,1] neg_hi:[0,1]
	v_pk_fma_f32 v[8:9], v[4:5], v[6:7], v[8:9] op_sel_hi:[0,1,1]
	v_pk_mul_f32 v[218:219], v[202:203], s[62:63]
	v_pk_mul_f32 v[16:17], v[2:3], v[10:11] op_sel:[0,1] op_sel_hi:[1,0]
	v_pk_fma_f32 v[202:203], v[202:203], s[50:51], v[218:219] op_sel:[0,0,1] op_sel_hi:[1,0,0] neg_lo:[1,0,0] neg_hi:[1,0,0]
	v_pk_add_f32 v[218:219], v[156:157], v[206:207] op_sel:[0,1] op_sel_hi:[1,0] neg_hi:[0,1]
	v_pk_add_f32 v[156:157], v[156:157], v[206:207] op_sel:[0,1] op_sel_hi:[1,0] neg_lo:[0,1]
	v_pk_add_f32 v[206:207], v[158:159], v[174:175]
	v_pk_add_f32 v[158:159], v[158:159], v[174:175] neg_lo:[0,1] neg_hi:[0,1]
	v_pk_mul_f32 v[30:31], v[2:3], v[26:27] op_sel:[0,1] op_sel_hi:[1,0]
	v_pk_mul_f32 v[174:175], v[158:159], s[62:63]
	v_pk_mul_f32 v[54:55], v[2:3], v[50:51] op_sel:[0,1] op_sel_hi:[1,0]
	v_pk_fma_f32 v[158:159], v[158:159], s[50:51], v[174:175] op_sel:[0,0,1] op_sel_hi:[1,0,0]
	v_pk_add_f32 v[174:175], v[160:161], v[176:177]
	v_pk_add_f32 v[160:161], v[160:161], v[176:177] neg_lo:[0,1] neg_hi:[0,1]
	v_pk_mul_f32 v[70:71], v[2:3], v[66:67] op_sel:[0,1] op_sel_hi:[1,0]
	v_pk_mul_f32 v[176:177], v[160:161], s[68:69]
	v_pk_mul_f32 v[86:87], v[2:3], v[82:83] op_sel:[0,1] op_sel_hi:[1,0]
	v_pk_fma_f32 v[160:161], v[160:161], s[10:11], v[176:177] op_sel:[0,0,1] op_sel_hi:[1,0,0]
	v_pk_add_f32 v[176:177], v[162:163], v[178:179]
	v_pk_add_f32 v[162:163], v[162:163], v[178:179] neg_lo:[0,1] neg_hi:[0,1]
	v_pk_mul_f32 v[102:103], v[2:3], v[98:99] op_sel:[0,1] op_sel_hi:[1,0]
	v_pk_mul_f32 v[178:179], v[162:163], s[72:73]
	v_pk_mul_f32 v[118:119], v[2:3], v[114:115] op_sel:[0,1] op_sel_hi:[1,0]
	v_pk_fma_f32 v[162:163], v[162:163], s[76:77], v[178:179] op_sel:[0,0,1] op_sel_hi:[1,0,0]
	v_pk_add_f32 v[178:179], v[164:165], v[180:181]
	v_pk_add_f32 v[180:181], v[164:165], v[180:181] neg_lo:[0,1] neg_hi:[0,1]
	v_xor_b32_e32 v20, 0x80000000, v9
	v_pk_add_f32 v[164:165], v[166:167], v[182:183]
	v_pk_add_f32 v[166:167], v[166:167], v[182:183] neg_lo:[0,1] neg_hi:[0,1]
	v_mov_b32_e32 v21, v9
	v_pk_mul_f32 v[182:183], v[166:167], s[72:73]
	v_pk_fma_f32 v[16:17], v[4:5], v[10:11], v[16:17] op_sel_hi:[0,1,1]
	v_pk_fma_f32 v[166:167], v[166:167], s[76:77], v[182:183] op_sel:[0,0,1] op_sel_hi:[1,0,0] neg_lo:[1,0,0] neg_hi:[1,0,0]
	v_pk_add_f32 v[182:183], v[168:169], v[184:185]
	v_pk_add_f32 v[168:169], v[168:169], v[184:185] neg_lo:[0,1] neg_hi:[0,1]
	v_pk_mul_f32 v[18:19], v[12:13], v[10:11] op_sel:[0,1] op_sel_hi:[1,0]
	v_pk_mul_f32 v[184:185], v[168:169], s[68:69]
	v_pk_fma_f32 v[30:31], v[4:5], v[26:27], v[30:31] op_sel_hi:[0,1,1]
	v_pk_fma_f32 v[168:169], v[168:169], s[10:11], v[184:185] op_sel:[0,0,1] op_sel_hi:[1,0,0] neg_lo:[1,0,0] neg_hi:[1,0,0]
	v_pk_add_f32 v[184:185], v[170:171], v[186:187]
	v_pk_add_f32 v[170:171], v[170:171], v[186:187] neg_lo:[0,1] neg_hi:[0,1]
	v_pk_mul_f32 v[42:43], v[12:13], v[26:27] op_sel:[0,1] op_sel_hi:[1,0]
	v_pk_mul_f32 v[186:187], v[170:171], s[62:63]
	v_pk_fma_f32 v[54:55], v[4:5], v[50:51], v[54:55] op_sel_hi:[0,1,1]
	v_pk_fma_f32 v[170:171], v[170:171], s[50:51], v[186:187] op_sel:[0,0,1] op_sel_hi:[1,0,0] neg_lo:[1,0,0] neg_hi:[1,0,0]
	v_pk_add_f32 v[186:187], v[220:221], v[210:211]
	v_pk_add_f32 v[210:211], v[220:221], v[210:211] neg_lo:[0,1] neg_hi:[0,1]
	v_pk_add_f32 v[220:221], v[222:223], v[194:195]
	v_pk_add_f32 v[194:195], v[222:223], v[194:195] neg_lo:[0,1] neg_hi:[0,1]
	v_pk_mul_f32 v[58:59], v[12:13], v[50:51] op_sel:[0,1] op_sel_hi:[1,0]
	v_pk_mul_f32 v[222:223], v[194:195], s[68:69]
	v_pk_fma_f32 v[70:71], v[4:5], v[66:67], v[70:71] op_sel_hi:[0,1,1]
	v_pk_fma_f32 v[194:195], v[194:195], s[10:11], v[222:223] op_sel:[0,0,1] op_sel_hi:[1,0,0]
	v_pk_add_f32 v[222:223], v[188:189], v[214:215]
	v_pk_add_f32 v[214:215], v[188:189], v[214:215] neg_lo:[0,1] neg_hi:[0,1]
	v_pk_mul_f32 v[74:75], v[12:13], v[66:67] op_sel:[0,1] op_sel_hi:[1,0]
	v_pk_add_f32 v[188:189], v[208:209], v[216:217]
	v_pk_add_f32 v[208:209], v[208:209], v[216:217] neg_lo:[0,1] neg_hi:[0,1]
	v_pk_fma_f32 v[86:87], v[4:5], v[82:83], v[86:87] op_sel_hi:[0,1,1]
	v_pk_mul_f32 v[216:217], v[208:209], s[68:69]
	v_pk_mul_f32 v[90:91], v[12:13], v[82:83] op_sel:[0,1] op_sel_hi:[1,0]
	v_pk_fma_f32 v[208:209], v[208:209], s[10:11], v[216:217] op_sel:[0,0,1] op_sel_hi:[1,0,0] neg_lo:[1,0,0] neg_hi:[1,0,0]
	v_pk_add_f32 v[216:217], v[204:205], v[212:213] op_sel:[0,1] op_sel_hi:[1,0] neg_hi:[0,1]
	v_pk_add_f32 v[204:205], v[204:205], v[212:213] op_sel:[0,1] op_sel_hi:[1,0] neg_lo:[0,1]
	v_pk_add_f32 v[212:213], v[172:173], v[196:197]
	v_pk_add_f32 v[172:173], v[172:173], v[196:197] neg_lo:[0,1] neg_hi:[0,1]
	v_pk_fma_f32 v[102:103], v[4:5], v[98:99], v[102:103] op_sel_hi:[0,1,1]
	v_pk_mul_f32 v[196:197], v[172:173], s[68:69]
	v_pk_mul_f32 v[106:107], v[12:13], v[98:99] op_sel:[0,1] op_sel_hi:[1,0]
	v_pk_fma_f32 v[172:173], v[172:173], s[10:11], v[196:197] op_sel:[0,0,1] op_sel_hi:[1,0,0]
	v_pk_add_f32 v[196:197], v[190:191], v[198:199]
	v_pk_add_f32 v[198:199], v[190:191], v[198:199] neg_lo:[0,1] neg_hi:[0,1]
	v_pk_fma_f32 v[118:119], v[4:5], v[114:115], v[118:119] op_sel_hi:[0,1,1]
	v_pk_add_f32 v[190:191], v[192:193], v[202:203]
	v_pk_add_f32 v[192:193], v[192:193], v[202:203] neg_lo:[0,1] neg_hi:[0,1]
	v_pk_mul_f32 v[122:123], v[12:13], v[114:115] op_sel:[0,1] op_sel_hi:[1,0]
	v_pk_mul_f32 v[202:203], v[192:193], s[68:69]
	v_pk_fma_f32 v[18:19], v[6:7], v[10:11], v[18:19] op_sel_hi:[0,1,1]
	v_pk_fma_f32 v[192:193], v[192:193], s[10:11], v[202:203] op_sel:[0,0,1] op_sel_hi:[1,0,0] neg_lo:[1,0,0] neg_hi:[1,0,0]
	v_pk_add_f32 v[202:203], v[218:219], v[178:179]
	v_pk_add_f32 v[178:179], v[218:219], v[178:179] neg_lo:[0,1] neg_hi:[0,1]
	v_pk_add_f32 v[218:219], v[206:207], v[164:165]
	v_pk_add_f32 v[164:165], v[206:207], v[164:165] neg_lo:[0,1] neg_hi:[0,1]
	v_pk_mul_f32 v[22:23], v[10:11], v[20:21] op_sel:[1,0] op_sel_hi:[0,1]
	v_pk_mul_f32 v[206:207], v[164:165], s[68:69]
	v_pk_fma_f32 v[42:43], v[6:7], v[26:27], v[42:43] op_sel_hi:[0,1,1]
	v_pk_fma_f32 v[164:165], v[164:165], s[10:11], v[206:207] op_sel:[0,0,1] op_sel_hi:[1,0,0]
	v_pk_add_f32 v[206:207], v[174:175], v[182:183]
	v_pk_add_f32 v[182:183], v[174:175], v[182:183] neg_lo:[0,1] neg_hi:[0,1]
	v_pk_mul_f32 v[46:47], v[20:21], v[26:27] op_sel:[0,1] op_sel_hi:[1,0]
	v_pk_add_f32 v[174:175], v[176:177], v[184:185]
	v_pk_add_f32 v[176:177], v[176:177], v[184:185] neg_lo:[0,1] neg_hi:[0,1]
	v_pk_fma_f32 v[58:59], v[6:7], v[50:51], v[58:59] op_sel_hi:[0,1,1]
	v_pk_mul_f32 v[184:185], v[176:177], s[68:69]
	v_pk_mul_f32 v[62:63], v[20:21], v[50:51] op_sel:[0,1] op_sel_hi:[1,0]
	v_pk_fma_f32 v[176:177], v[176:177], s[10:11], v[184:185] op_sel:[0,0,1] op_sel_hi:[1,0,0] neg_lo:[1,0,0] neg_hi:[1,0,0]
	v_pk_add_f32 v[184:185], v[156:157], v[180:181] op_sel:[0,1] op_sel_hi:[1,0] neg_hi:[0,1]
	v_pk_add_f32 v[156:157], v[156:157], v[180:181] op_sel:[0,1] op_sel_hi:[1,0] neg_lo:[0,1]
	v_pk_add_f32 v[180:181], v[158:159], v[166:167]
	v_pk_add_f32 v[158:159], v[158:159], v[166:167] neg_lo:[0,1] neg_hi:[0,1]
	v_pk_fma_f32 v[74:75], v[6:7], v[66:67], v[74:75] op_sel_hi:[0,1,1]
	v_pk_mul_f32 v[166:167], v[158:159], s[68:69]
	v_pk_mul_f32 v[78:79], v[20:21], v[66:67] op_sel:[0,1] op_sel_hi:[1,0]
	v_pk_fma_f32 v[158:159], v[158:159], s[10:11], v[166:167] op_sel:[0,0,1] op_sel_hi:[1,0,0]
	v_pk_add_f32 v[166:167], v[160:161], v[168:169]
	v_pk_add_f32 v[168:169], v[160:161], v[168:169] neg_lo:[0,1] neg_hi:[0,1]
	v_pk_fma_f32 v[90:91], v[6:7], v[82:83], v[90:91] op_sel_hi:[0,1,1]
	v_pk_add_f32 v[160:161], v[162:163], v[170:171]
	v_pk_add_f32 v[162:163], v[162:163], v[170:171] neg_lo:[0,1] neg_hi:[0,1]
	v_pk_mul_f32 v[94:95], v[20:21], v[82:83] op_sel:[0,1] op_sel_hi:[1,0]
	v_pk_mul_f32 v[170:171], v[162:163], s[68:69]
	v_pk_fma_f32 v[106:107], v[6:7], v[98:99], v[106:107] op_sel_hi:[0,1,1]
	v_pk_fma_f32 v[162:163], v[162:163], s[10:11], v[170:171] op_sel:[0,0,1] op_sel_hi:[1,0,0] neg_lo:[1,0,0] neg_hi:[1,0,0]
	v_pk_add_f32 v[170:171], v[186:187], v[222:223]
	v_pk_add_f32 v[186:187], v[186:187], v[222:223] neg_lo:[0,1] neg_hi:[0,1]
	v_pk_add_f32 v[222:223], v[220:221], v[188:189]
	v_pk_add_f32 v[220:221], v[220:221], v[188:189] neg_lo:[0,1] neg_hi:[0,1]
	v_pk_mul_f32 v[110:111], v[20:21], v[98:99] op_sel:[0,1] op_sel_hi:[1,0]
	v_pk_add_f32 v[188:189], v[210:211], v[214:215] op_sel:[0,1] op_sel_hi:[1,0] neg_hi:[0,1]
	v_pk_add_f32 v[210:211], v[210:211], v[214:215] op_sel:[0,1] op_sel_hi:[1,0] neg_lo:[0,1]
	v_pk_add_f32 v[214:215], v[194:195], v[208:209]
	v_pk_add_f32 v[208:209], v[194:195], v[208:209] neg_lo:[0,1] neg_hi:[0,1]
	v_pk_fma_f32 v[122:123], v[6:7], v[114:115], v[122:123] op_sel_hi:[0,1,1]
	v_pk_add_f32 v[194:195], v[216:217], v[196:197]
	v_pk_add_f32 v[196:197], v[216:217], v[196:197] neg_lo:[0,1] neg_hi:[0,1]
	v_pk_add_f32 v[216:217], v[212:213], v[190:191]
	v_pk_add_f32 v[212:213], v[212:213], v[190:191] neg_lo:[0,1] neg_hi:[0,1]
	v_pk_mul_f32 v[126:127], v[20:21], v[114:115] op_sel:[0,1] op_sel_hi:[1,0]
	v_pk_add_f32 v[190:191], v[204:205], v[198:199] op_sel:[0,1] op_sel_hi:[1,0] neg_hi:[0,1]
	v_pk_add_f32 v[198:199], v[204:205], v[198:199] op_sel:[0,1] op_sel_hi:[1,0] neg_lo:[0,1]
	v_pk_add_f32 v[204:205], v[172:173], v[192:193]
	v_pk_add_f32 v[192:193], v[172:173], v[192:193] neg_lo:[0,1] neg_hi:[0,1]
	v_xor_b32_e32 v24, 0x80000000, v17
	v_pk_add_f32 v[172:173], v[202:203], v[206:207]
	v_pk_add_f32 v[202:203], v[202:203], v[206:207] neg_lo:[0,1] neg_hi:[0,1]
	v_pk_add_f32 v[206:207], v[218:219], v[174:175]
	v_pk_add_f32 v[218:219], v[218:219], v[174:175] neg_lo:[0,1] neg_hi:[0,1]
	v_xor_b32_e32 v28, 0x80000000, v19
	v_pk_add_f32 v[174:175], v[178:179], v[182:183] op_sel:[0,1] op_sel_hi:[1,0] neg_hi:[0,1]
	v_pk_add_f32 v[178:179], v[178:179], v[182:183] op_sel:[0,1] op_sel_hi:[1,0] neg_lo:[0,1]
	v_pk_add_f32 v[182:183], v[164:165], v[176:177]
	v_pk_add_f32 v[176:177], v[164:165], v[176:177] neg_lo:[0,1] neg_hi:[0,1]
	v_pk_fma_f32 v[22:23], v[10:11], v[8:9], v[22:23] op_sel_hi:[1,0,1]
	v_pk_add_f32 v[164:165], v[184:185], v[166:167]
	v_pk_add_f32 v[166:167], v[184:185], v[166:167] neg_lo:[0,1] neg_hi:[0,1]
	v_pk_add_f32 v[184:185], v[180:181], v[160:161]
	v_pk_add_f32 v[180:181], v[180:181], v[160:161] neg_lo:[0,1] neg_hi:[0,1]
	v_pk_fma_f32 v[46:47], v[8:9], v[26:27], v[46:47] op_sel_hi:[0,1,1]
	v_pk_add_f32 v[160:161], v[156:157], v[168:169] op_sel:[0,1] op_sel_hi:[1,0] neg_hi:[0,1]
	v_pk_add_f32 v[156:157], v[156:157], v[168:169] op_sel:[0,1] op_sel_hi:[1,0] neg_lo:[0,1]
	v_pk_add_f32 v[168:169], v[158:159], v[162:163]
	v_pk_add_f32 v[158:159], v[158:159], v[162:163] neg_lo:[0,1] neg_hi:[0,1]
	v_pk_fma_f32 v[62:63], v[8:9], v[50:51], v[62:63] op_sel_hi:[0,1,1]
	v_xor_b32_e32 v163, 0x80000000, v158
	v_mov_b32_e32 v162, v159
	v_pk_add_f32 v[158:159], v[170:171], v[222:223]
	v_pk_add_f32 v[170:171], v[170:171], v[222:223] neg_lo:[0,1] neg_hi:[0,1]
	v_pk_add_f32 v[222:223], v[186:187], v[220:221] op_sel:[0,1] op_sel_hi:[1,0] neg_hi:[0,1]
	v_pk_add_f32 v[186:187], v[186:187], v[220:221] op_sel:[0,1] op_sel_hi:[1,0] neg_lo:[0,1]
	v_pk_add_f32 v[220:221], v[188:189], v[214:215]
	v_pk_add_f32 v[188:189], v[188:189], v[214:215] neg_lo:[0,1] neg_hi:[0,1]
	v_pk_add_f32 v[214:215], v[210:211], v[208:209] op_sel:[0,1] op_sel_hi:[1,0] neg_hi:[0,1]
	v_pk_add_f32 v[208:209], v[210:211], v[208:209] op_sel:[0,1] op_sel_hi:[1,0] neg_lo:[0,1]
	v_pk_add_f32 v[210:211], v[194:195], v[216:217]
	v_pk_add_f32 v[194:195], v[194:195], v[216:217] neg_lo:[0,1] neg_hi:[0,1]
	v_pk_add_f32 v[216:217], v[196:197], v[212:213] op_sel:[0,1] op_sel_hi:[1,0] neg_hi:[0,1]
	v_pk_add_f32 v[196:197], v[196:197], v[212:213] op_sel:[0,1] op_sel_hi:[1,0] neg_lo:[0,1]
	v_pk_add_f32 v[212:213], v[190:191], v[204:205]
	v_pk_add_f32 v[190:191], v[190:191], v[204:205] neg_lo:[0,1] neg_hi:[0,1]
	v_pk_add_f32 v[204:205], v[198:199], v[192:193] op_sel:[0,1] op_sel_hi:[1,0] neg_hi:[0,1]
	v_pk_add_f32 v[192:193], v[198:199], v[192:193] op_sel:[0,1] op_sel_hi:[1,0] neg_lo:[0,1]
	v_pk_add_f32 v[198:199], v[172:173], v[206:207]
	v_pk_add_f32 v[172:173], v[172:173], v[206:207] neg_lo:[0,1] neg_hi:[0,1]
	v_pk_mul_f32 v[2:3], v[2:3], v[198:199] op_sel:[0,1] op_sel_hi:[1,0]
	v_pk_add_f32 v[206:207], v[202:203], v[218:219] op_sel:[0,1] op_sel_hi:[1,0] neg_hi:[0,1]
	v_pk_add_f32 v[202:203], v[202:203], v[218:219] op_sel:[0,1] op_sel_hi:[1,0] neg_lo:[0,1]
	v_pk_add_f32 v[218:219], v[174:175], v[182:183]
	v_pk_add_f32 v[174:175], v[174:175], v[182:183] neg_lo:[0,1] neg_hi:[0,1]
	v_pk_add_f32 v[182:183], v[178:179], v[176:177] op_sel:[0,1] op_sel_hi:[1,0] neg_hi:[0,1]
	v_pk_add_f32 v[176:177], v[178:179], v[176:177] op_sel:[0,1] op_sel_hi:[1,0] neg_lo:[0,1]
	v_pk_add_f32 v[178:179], v[164:165], v[184:185]
	v_pk_fma_f32 v[2:3], v[4:5], v[198:199], v[2:3] op_sel_hi:[0,1,1]
	v_pk_mul_f32 v[4:5], v[12:13], v[210:211] op_sel:[0,1] op_sel_hi:[1,0]
	v_pk_fma_f32 v[78:79], v[8:9], v[66:67], v[78:79] op_sel_hi:[0,1,1]
	v_pk_fma_f32 v[4:5], v[6:7], v[210:211], v[4:5] op_sel_hi:[0,1,1]
	v_pk_mul_f32 v[6:7], v[20:21], v[178:179] op_sel:[0,1] op_sel_hi:[1,0]
	v_pk_fma_f32 v[94:95], v[8:9], v[82:83], v[94:95] op_sel_hi:[0,1,1]
	v_pk_fma_f32 v[110:111], v[8:9], v[98:99], v[110:111] op_sel_hi:[0,1,1]
	v_pk_fma_f32 v[126:127], v[8:9], v[114:115], v[126:127] op_sel_hi:[0,1,1]
	v_mov_b32_e32 v25, v17
	v_mov_b32_e32 v29, v19
	v_pk_fma_f32 v[6:7], v[8:9], v[178:179], v[6:7] op_sel_hi:[0,1,1]
	v_pk_mul_f32 v[8:9], v[14:15], v[220:221] op_sel:[0,1] op_sel_hi:[1,0]
	v_xor_b32_e32 v32, 0x80000000, v23
	v_xor_b32_e32 v44, 0x80000000, v27
	v_xor_b32_e32 v48, 0x80000000, v31
	v_xor_b32_e32 v52, 0x80000000, v43
	v_mov_b32_e32 v33, v23
	v_mov_b32_e32 v45, v27
	v_mov_b32_e32 v49, v31
	v_mov_b32_e32 v53, v43
	v_pk_add_f32 v[164:165], v[164:165], v[184:185] neg_lo:[0,1] neg_hi:[0,1]
	v_pk_add_f32 v[184:185], v[166:167], v[180:181] op_sel:[0,1] op_sel_hi:[1,0] neg_hi:[0,1]
	v_pk_add_f32 v[166:167], v[166:167], v[180:181] op_sel:[0,1] op_sel_hi:[1,0] neg_lo:[0,1]
	v_pk_add_f32 v[180:181], v[160:161], v[168:169]
	v_pk_fma_f32 v[8:9], v[10:11], v[220:221], v[8:9] op_sel_hi:[0,1,1]
	v_pk_mul_f32 v[10:11], v[24:25], v[218:219] op_sel:[0,1] op_sel_hi:[1,0]
	v_pk_mul_f32 v[12:13], v[28:29], v[212:213] op_sel:[0,1] op_sel_hi:[1,0]
	v_xor_b32_e32 v56, 0x80000000, v47
	v_xor_b32_e32 v60, 0x80000000, v51
	v_xor_b32_e32 v64, 0x80000000, v55
	v_xor_b32_e32 v68, 0x80000000, v59
	v_xor_b32_e32 v72, 0x80000000, v63
	v_xor_b32_e32 v76, 0x80000000, v67
	v_xor_b32_e32 v80, 0x80000000, v71
	v_mov_b32_e32 v57, v47
	v_mov_b32_e32 v61, v51
	v_mov_b32_e32 v65, v55
	v_mov_b32_e32 v69, v59
	v_mov_b32_e32 v73, v63
	v_mov_b32_e32 v77, v67
	v_mov_b32_e32 v81, v71
	v_pk_add_f32 v[160:161], v[160:161], v[168:169] neg_lo:[0,1] neg_hi:[0,1]
	v_pk_add_f32 v[168:169], v[156:157], v[162:163]
	v_pk_fma_f32 v[10:11], v[16:17], v[218:219], v[10:11] op_sel_hi:[0,1,1]
	v_pk_fma_f32 v[12:13], v[18:19], v[212:213], v[12:13] op_sel_hi:[0,1,1]
	v_pk_mul_f32 v[14:15], v[32:33], v[180:181] op_sel:[0,1] op_sel_hi:[1,0]
	v_pk_mul_f32 v[16:17], v[44:45], v[222:223] op_sel:[0,1] op_sel_hi:[1,0]
	v_pk_mul_f32 v[18:19], v[48:49], v[206:207] op_sel:[0,1] op_sel_hi:[1,0]
	v_pk_mul_f32 v[20:21], v[52:53], v[216:217] op_sel:[0,1] op_sel_hi:[1,0]
	v_xor_b32_e32 v84, 0x80000000, v75
	v_xor_b32_e32 v88, 0x80000000, v79
	v_xor_b32_e32 v92, 0x80000000, v83
	v_xor_b32_e32 v96, 0x80000000, v87
	v_xor_b32_e32 v100, 0x80000000, v91
	v_xor_b32_e32 v104, 0x80000000, v95
	v_xor_b32_e32 v108, 0x80000000, v99
	v_xor_b32_e32 v112, 0x80000000, v103
	v_xor_b32_e32 v116, 0x80000000, v107
	v_xor_b32_e32 v120, 0x80000000, v111
	v_xor_b32_e32 v124, 0x80000000, v115
	v_xor_b32_e32 v128, 0x80000000, v119
	v_xor_b32_e32 v130, 0x80000000, v123
	v_xor_b32_e32 v132, 0x80000000, v127
	v_mov_b32_e32 v85, v75
	v_mov_b32_e32 v89, v79
	v_mov_b32_e32 v93, v83
	v_mov_b32_e32 v97, v87
	v_mov_b32_e32 v101, v91
	v_mov_b32_e32 v105, v95
	v_mov_b32_e32 v109, v99
	v_mov_b32_e32 v113, v103
	v_mov_b32_e32 v117, v107
	v_mov_b32_e32 v121, v111
	v_mov_b32_e32 v125, v115
	v_mov_b32_e32 v129, v119
	v_mov_b32_e32 v131, v123
	v_mov_b32_e32 v133, v127
	v_pk_add_f32 v[156:157], v[156:157], v[162:163] neg_lo:[0,1] neg_hi:[0,1]
	v_pk_fma_f32 v[14:15], v[22:23], v[180:181], v[14:15] op_sel_hi:[0,1,1]
	v_pk_fma_f32 v[16:17], v[26:27], v[222:223], v[16:17] op_sel_hi:[0,1,1]
	v_pk_fma_f32 v[18:19], v[30:31], v[206:207], v[18:19] op_sel_hi:[0,1,1]
	v_pk_fma_f32 v[20:21], v[42:43], v[216:217], v[20:21] op_sel_hi:[0,1,1]
	v_pk_mul_f32 v[22:23], v[56:57], v[184:185] op_sel:[0,1] op_sel_hi:[1,0]
	v_pk_mul_f32 v[24:25], v[60:61], v[214:215] op_sel:[0,1] op_sel_hi:[1,0]
	v_pk_mul_f32 v[26:27], v[64:65], v[182:183] op_sel:[0,1] op_sel_hi:[1,0]
	v_pk_mul_f32 v[28:29], v[68:69], v[204:205] op_sel:[0,1] op_sel_hi:[1,0]
	v_pk_mul_f32 v[30:31], v[72:73], v[168:169] op_sel:[0,1] op_sel_hi:[1,0]
	v_pk_mul_f32 v[32:33], v[76:77], v[170:171] op_sel:[0,1] op_sel_hi:[1,0]
	v_pk_mul_f32 v[42:43], v[80:81], v[172:173] op_sel:[0,1] op_sel_hi:[1,0]
	v_pk_fma_f32 v[22:23], v[46:47], v[184:185], v[22:23] op_sel_hi:[0,1,1]
	v_pk_fma_f32 v[24:25], v[50:51], v[214:215], v[24:25] op_sel_hi:[0,1,1]
	v_pk_fma_f32 v[26:27], v[54:55], v[182:183], v[26:27] op_sel_hi:[0,1,1]
	v_pk_fma_f32 v[28:29], v[58:59], v[204:205], v[28:29] op_sel_hi:[0,1,1]
	v_pk_fma_f32 v[30:31], v[62:63], v[168:169], v[30:31] op_sel_hi:[0,1,1]
	v_pk_fma_f32 v[32:33], v[66:67], v[170:171], v[32:33] op_sel_hi:[0,1,1]
	v_pk_fma_f32 v[42:43], v[70:71], v[172:173], v[42:43] op_sel_hi:[0,1,1]
	v_pk_mul_f32 v[44:45], v[84:85], v[194:195] op_sel:[0,1] op_sel_hi:[1,0]
	v_pk_mul_f32 v[46:47], v[88:89], v[164:165] op_sel:[0,1] op_sel_hi:[1,0]
	v_pk_mul_f32 v[48:49], v[92:93], v[188:189] op_sel:[0,1] op_sel_hi:[1,0]
	v_pk_mul_f32 v[50:51], v[96:97], v[174:175] op_sel:[0,1] op_sel_hi:[1,0]
	v_pk_mul_f32 v[52:53], v[100:101], v[190:191] op_sel:[0,1] op_sel_hi:[1,0]
	v_pk_mul_f32 v[54:55], v[104:105], v[160:161] op_sel:[0,1] op_sel_hi:[1,0]
	v_pk_mul_f32 v[56:57], v[108:109], v[186:187] op_sel:[0,1] op_sel_hi:[1,0]
	v_pk_mul_f32 v[58:59], v[112:113], v[202:203] op_sel:[0,1] op_sel_hi:[1,0]
	v_pk_mul_f32 v[60:61], v[116:117], v[196:197] op_sel:[0,1] op_sel_hi:[1,0]
	v_pk_mul_f32 v[62:63], v[120:121], v[166:167] op_sel:[0,1] op_sel_hi:[1,0]
	v_pk_mul_f32 v[64:65], v[124:125], v[208:209] op_sel:[0,1] op_sel_hi:[1,0]
	v_pk_mul_f32 v[66:67], v[128:129], v[176:177] op_sel:[0,1] op_sel_hi:[1,0]
	v_pk_mul_f32 v[68:69], v[130:131], v[192:193] op_sel:[0,1] op_sel_hi:[1,0]
	v_pk_mul_f32 v[70:71], v[132:133], v[156:157] op_sel:[0,1] op_sel_hi:[1,0]
	v_pk_fma_f32 v[44:45], v[74:75], v[194:195], v[44:45] op_sel_hi:[0,1,1]
	v_pk_fma_f32 v[46:47], v[78:79], v[164:165], v[46:47] op_sel_hi:[0,1,1]
	v_pk_fma_f32 v[48:49], v[82:83], v[188:189], v[48:49] op_sel_hi:[0,1,1]
	v_pk_fma_f32 v[50:51], v[86:87], v[174:175], v[50:51] op_sel_hi:[0,1,1]
	v_pk_fma_f32 v[52:53], v[90:91], v[190:191], v[52:53] op_sel_hi:[0,1,1]
	v_pk_fma_f32 v[54:55], v[94:95], v[160:161], v[54:55] op_sel_hi:[0,1,1]
	v_pk_fma_f32 v[56:57], v[98:99], v[186:187], v[56:57] op_sel_hi:[0,1,1]
	v_pk_fma_f32 v[58:59], v[102:103], v[202:203], v[58:59] op_sel_hi:[0,1,1]
	v_pk_fma_f32 v[60:61], v[106:107], v[196:197], v[60:61] op_sel_hi:[0,1,1]
	v_pk_fma_f32 v[62:63], v[110:111], v[166:167], v[62:63] op_sel_hi:[0,1,1]
	v_pk_fma_f32 v[64:65], v[114:115], v[208:209], v[64:65] op_sel_hi:[0,1,1]
	v_pk_fma_f32 v[66:67], v[118:119], v[176:177], v[66:67] op_sel_hi:[0,1,1]
	v_pk_fma_f32 v[68:69], v[122:123], v[192:193], v[68:69] op_sel_hi:[0,1,1]
	v_pk_fma_f32 v[70:71], v[126:127], v[156:157], v[70:71] op_sel_hi:[0,1,1]
	ds_write_b64 v40, v[158:159]
	ds_write_b64 v40, v[32:33] offset:4224
	ds_write_b64 v40, v[16:17] offset:8448
	ds_write_b64 v40, v[56:57] offset:12672
	ds_write_b64 v40, v[8:9] offset:16896
	ds_write_b64 v40, v[48:49] offset:21120
	ds_write_b64 v40, v[24:25] offset:25344
	ds_write_b64 v40, v[64:65] offset:29568
	ds_write_b64 v40, v[4:5] offset:33792
	ds_write_b64 v40, v[44:45] offset:38016
	ds_write_b64 v40, v[20:21] offset:42240
	ds_write_b64 v40, v[60:61] offset:46464
	ds_write_b64 v40, v[12:13] offset:50688
	ds_write_b64 v40, v[52:53] offset:54912
	ds_write_b64 v40, v[28:29] offset:59136
	ds_write_b64 v40, v[68:69] offset:63360
	ds_write_b64 v155, v[2:3]
	ds_write_b64 v201, v[42:43]
	ds_write_b64 v224, v[18:19]
	ds_write_b64 v225, v[58:59]
	ds_write_b64 v226, v[10:11]
	ds_write_b64 v227, v[50:51]
	ds_write_b64 v228, v[26:27]
	ds_write_b64 v229, v[66:67]
	ds_write_b64 v230, v[6:7]
	ds_write_b64 v231, v[46:47]
	ds_write_b64 v232, v[22:23]
	ds_write_b64 v233, v[62:63]
	ds_write_b64 v234, v[14:15]
	ds_write_b64 v235, v[54:55]
	ds_write_b64 v236, v[30:31]
	ds_write_b64 v237, v[70:71]
	v_mov_b32_e32 v2, v1
	s_waitcnt lgkmcnt(0)
	s_barrier
	s_nop 0
	v_and_b32_e32 v3, 15, v2
	v_lshlrev_b32_e32 v2, 5, v2
	v_and_b32_e32 v4, 0xfffffe00, v2
	v_lshl_add_u32 v5, v4, 3, 0
	v_lshlrev_b32_e32 v6, 3, v3
	v_ashrrev_i32_e32 v7, 2, v4
	v_add3_u32 v40, v5, v6, v7
	v_add_u32_e32 v155, 0x800, v40
	ds_read2_b64 v[156:159], v40 offset1:16
	ds_read2_b64 v[160:163], v40 offset0:33 offset1:49
	ds_read2_b64 v[164:167], v40 offset0:66 offset1:82
	ds_read2_b64 v[168:171], v40 offset0:99 offset1:115
	ds_read2_b64 v[172:175], v40 offset0:132 offset1:148
	ds_read2_b64 v[176:179], v40 offset0:165 offset1:181
	ds_read2_b64 v[180:183], v40 offset0:198 offset1:214
	ds_read2_b64 v[184:187], v40 offset0:231 offset1:247
	ds_read2_b64 v[188:191], v155 offset0:8 offset1:24
	ds_read2_b64 v[192:195], v155 offset0:41 offset1:57
	ds_read2_b64 v[196:199], v155 offset0:74 offset1:90
	ds_read2_b64 v[202:205], v155 offset0:107 offset1:123
	ds_read2_b64 v[206:209], v155 offset0:140 offset1:156
	ds_read2_b64 v[210:213], v155 offset0:173 offset1:189
	ds_read2_b64 v[214:217], v155 offset0:206 offset1:222
	ds_read2_b64 v[218:221], v155 offset0:239 offset1:255
	s_waitcnt lgkmcnt(7)
	v_pk_add_f32 v[222:223], v[156:157], v[188:189]
	v_pk_add_f32 v[156:157], v[156:157], v[188:189] neg_lo:[0,1] neg_hi:[0,1]
	v_pk_add_f32 v[188:189], v[158:159], v[190:191]
	v_pk_add_f32 v[158:159], v[158:159], v[190:191] neg_lo:[0,1] neg_hi:[0,1]
	v_cvt_f32_ubyte0_e32 v2, v3
	v_pk_mul_f32 v[190:191], v[158:159], s[46:47]
	v_mul_f32_e32 v3, 0x3b000000, v2
	v_pk_fma_f32 v[158:159], v[158:159], s[42:43], v[190:191] op_sel:[0,0,1] op_sel_hi:[1,0,0]
	s_waitcnt lgkmcnt(6)
	v_pk_add_f32 v[190:191], v[160:161], v[192:193]
	v_pk_add_f32 v[160:161], v[160:161], v[192:193] neg_lo:[0,1] neg_hi:[0,1]
	v_sin_f32_e32 v2, v3
	v_pk_mul_f32 v[192:193], v[160:161], s[62:63]
	v_cos_f32_e32 v4, v3
	v_pk_fma_f32 v[160:161], v[160:161], s[50:51], v[192:193] op_sel:[0,0,1] op_sel_hi:[1,0,0]
	v_pk_add_f32 v[192:193], v[162:163], v[194:195]
	v_pk_add_f32 v[162:163], v[162:163], v[194:195] neg_lo:[0,1] neg_hi:[0,1]
	v_xor_b32_e32 v5, 0x80000000, v2
	v_pk_mul_f32 v[194:195], v[162:163], s[66:67]
	v_mov_b32_e32 v3, v5
	v_pk_fma_f32 v[162:163], v[162:163], s[64:65], v[194:195] op_sel:[0,0,1] op_sel_hi:[1,0,0]
	s_waitcnt lgkmcnt(5)
	v_pk_add_f32 v[194:195], v[164:165], v[196:197]
	v_pk_add_f32 v[164:165], v[164:165], v[196:197] neg_lo:[0,1] neg_hi:[0,1]
	v_pk_mul_f32 v[6:7], v[4:5], v[2:3] op_sel:[1,0] op_sel_hi:[0,1]
	v_pk_mul_f32 v[196:197], v[164:165], s[68:69]
	v_pk_fma_f32 v[6:7], v[4:5], v[4:5], v[6:7] op_sel_hi:[1,0,1]
	v_pk_fma_f32 v[164:165], v[164:165], s[10:11], v[196:197] op_sel:[0,0,1] op_sel_hi:[1,0,0]
	v_pk_add_f32 v[196:197], v[166:167], v[198:199]
	v_pk_add_f32 v[166:167], v[166:167], v[198:199] neg_lo:[0,1] neg_hi:[0,1]
	v_xor_b32_e32 v12, 0x80000000, v7
	v_pk_mul_f32 v[198:199], v[166:167], s[70:71]
	v_mov_b32_e32 v13, v7
	v_pk_fma_f32 v[166:167], v[166:167], s[78:79], v[198:199] op_sel:[0,0,1] op_sel_hi:[1,0,0]
	s_waitcnt lgkmcnt(4)
	v_pk_add_f32 v[198:199], v[168:169], v[202:203]
	v_pk_add_f32 v[168:169], v[168:169], v[202:203] neg_lo:[0,1] neg_hi:[0,1]
	v_pk_mul_f32 v[10:11], v[6:7], v[12:13] op_sel:[1,0] op_sel_hi:[0,1]
	v_pk_mul_f32 v[202:203], v[168:169], s[72:73]
	v_pk_fma_f32 v[10:11], v[6:7], v[6:7], v[10:11] op_sel_hi:[1,0,1]
	v_pk_fma_f32 v[168:169], v[168:169], s[76:77], v[202:203] op_sel:[0,0,1] op_sel_hi:[1,0,0]
	v_pk_add_f32 v[202:203], v[170:171], v[204:205]
	v_pk_add_f32 v[170:171], v[170:171], v[204:205] neg_lo:[0,1] neg_hi:[0,1]
	v_xor_b32_e32 v14, 0x80000000, v11
	v_pk_mul_f32 v[204:205], v[170:171], s[40:41]
	v_mov_b32_e32 v15, v11
	v_pk_fma_f32 v[170:171], v[170:171], s[44:45], v[204:205] op_sel:[0,0,1] op_sel_hi:[1,0,0]
	s_waitcnt lgkmcnt(3)
	v_pk_add_f32 v[204:205], v[172:173], v[206:207]
	v_pk_add_f32 v[206:207], v[172:173], v[206:207] neg_lo:[0,1] neg_hi:[0,1]
	v_pk_mul_f32 v[26:27], v[10:11], v[14:15] op_sel:[1,0] op_sel_hi:[0,1]
	v_pk_add_f32 v[172:173], v[174:175], v[208:209]
	v_pk_add_f32 v[174:175], v[174:175], v[208:209] neg_lo:[0,1] neg_hi:[0,1]
	v_pk_fma_f32 v[26:27], v[10:11], v[10:11], v[26:27] op_sel_hi:[1,0,1]
	v_pk_mul_f32 v[208:209], v[174:175], s[40:41]
	v_pk_mul_f32 v[50:51], v[14:15], v[26:27] op_sel:[0,1] op_sel_hi:[1,0]
	v_pk_fma_f32 v[174:175], v[174:175], s[44:45], v[208:209] op_sel:[0,0,1] op_sel_hi:[1,0,0] neg_lo:[1,0,0] neg_hi:[1,0,0]
	s_waitcnt lgkmcnt(2)
	v_pk_add_f32 v[208:209], v[176:177], v[210:211]
	v_pk_add_f32 v[176:177], v[176:177], v[210:211] neg_lo:[0,1] neg_hi:[0,1]
	v_pk_fma_f32 v[50:51], v[10:11], v[26:27], v[50:51] op_sel_hi:[0,1,1]
	v_pk_mul_f32 v[210:211], v[176:177], s[72:73]
	v_pk_mul_f32 v[66:67], v[14:15], v[50:51] op_sel:[0,1] op_sel_hi:[1,0]
	v_pk_fma_f32 v[176:177], v[176:177], s[76:77], v[210:211] op_sel:[0,0,1] op_sel_hi:[1,0,0] neg_lo:[1,0,0] neg_hi:[1,0,0]
	v_pk_add_f32 v[210:211], v[178:179], v[212:213]
	v_pk_add_f32 v[178:179], v[178:179], v[212:213] neg_lo:[0,1] neg_hi:[0,1]
	v_pk_fma_f32 v[66:67], v[10:11], v[50:51], v[66:67] op_sel_hi:[0,1,1]
	v_pk_mul_f32 v[212:213], v[178:179], s[70:71]
	v_pk_mul_f32 v[82:83], v[14:15], v[66:67] op_sel:[0,1] op_sel_hi:[1,0]
	v_pk_fma_f32 v[178:179], v[178:179], s[78:79], v[212:213] op_sel:[0,0,1] op_sel_hi:[1,0,0] neg_lo:[1,0,0] neg_hi:[1,0,0]
	s_waitcnt lgkmcnt(1)
	v_pk_add_f32 v[212:213], v[180:181], v[214:215]
	v_pk_add_f32 v[180:181], v[180:181], v[214:215] neg_lo:[0,1] neg_hi:[0,1]
	v_pk_fma_f32 v[82:83], v[10:11], v[66:67], v[82:83] op_sel_hi:[0,1,1]
	v_pk_mul_f32 v[214:215], v[180:181], s[68:69]
	v_pk_mul_f32 v[98:99], v[14:15], v[82:83] op_sel:[0,1] op_sel_hi:[1,0]
	v_pk_fma_f32 v[180:181], v[180:181], s[10:11], v[214:215] op_sel:[0,0,1] op_sel_hi:[1,0,0] neg_lo:[1,0,0] neg_hi:[1,0,0]
	v_pk_add_f32 v[214:215], v[182:183], v[216:217]
	v_pk_add_f32 v[182:183], v[182:183], v[216:217] neg_lo:[0,1] neg_hi:[0,1]
	v_pk_fma_f32 v[98:99], v[10:11], v[82:83], v[98:99] op_sel_hi:[0,1,1]
	v_pk_mul_f32 v[216:217], v[182:183], s[66:67]
	v_pk_mul_f32 v[114:115], v[14:15], v[98:99] op_sel:[0,1] op_sel_hi:[1,0]
	v_pk_fma_f32 v[182:183], v[182:183], s[64:65], v[216:217] op_sel:[0,0,1] op_sel_hi:[1,0,0] neg_lo:[1,0,0] neg_hi:[1,0,0]
	s_waitcnt lgkmcnt(0)
	v_pk_add_f32 v[216:217], v[184:185], v[218:219]
	v_pk_add_f32 v[184:185], v[184:185], v[218:219] neg_lo:[0,1] neg_hi:[0,1]
	v_pk_mul_f32 v[8:9], v[2:3], v[6:7] op_sel:[0,1] op_sel_hi:[1,0]
	v_pk_mul_f32 v[218:219], v[184:185], s[62:63]
	v_pk_fma_f32 v[114:115], v[10:11], v[98:99], v[114:115] op_sel_hi:[0,1,1]
	v_pk_fma_f32 v[184:185], v[184:185], s[50:51], v[218:219] op_sel:[0,0,1] op_sel_hi:[1,0,0] neg_lo:[1,0,0] neg_hi:[1,0,0]
	v_pk_add_f32 v[218:219], v[186:187], v[220:221]
	v_pk_add_f32 v[186:187], v[186:187], v[220:221] neg_lo:[0,1] neg_hi:[0,1]
	v_pk_fma_f32 v[8:9], v[4:5], v[6:7], v[8:9] op_sel_hi:[0,1,1]
	v_pk_mul_f32 v[220:221], v[186:187], s[46:47]
	v_pk_mul_f32 v[16:17], v[2:3], v[10:11] op_sel:[0,1] op_sel_hi:[1,0]
	v_pk_fma_f32 v[186:187], v[186:187], s[42:43], v[220:221] op_sel:[0,0,1] op_sel_hi:[1,0,0] neg_lo:[1,0,0] neg_hi:[1,0,0]
	v_pk_add_f32 v[220:221], v[222:223], v[204:205]
	v_pk_add_f32 v[204:205], v[222:223], v[204:205] neg_lo:[0,1] neg_hi:[0,1]
	v_pk_add_f32 v[222:223], v[188:189], v[172:173]
	v_pk_add_f32 v[172:173], v[188:189], v[172:173] neg_lo:[0,1] neg_hi:[0,1]
	v_pk_mul_f32 v[30:31], v[2:3], v[26:27] op_sel:[0,1] op_sel_hi:[1,0]
	v_pk_mul_f32 v[188:189], v[172:173], s[62:63]
	v_pk_mul_f32 v[54:55], v[2:3], v[50:51] op_sel:[0,1] op_sel_hi:[1,0]
	v_pk_fma_f32 v[172:173], v[172:173], s[50:51], v[188:189] op_sel:[0,0,1] op_sel_hi:[1,0,0]
	v_pk_add_f32 v[188:189], v[190:191], v[208:209]
	v_pk_add_f32 v[190:191], v[190:191], v[208:209] neg_lo:[0,1] neg_hi:[0,1]
	v_pk_mul_f32 v[70:71], v[2:3], v[66:67] op_sel:[0,1] op_sel_hi:[1,0]
	v_pk_mul_f32 v[208:209], v[190:191], s[68:69]
	v_pk_mul_f32 v[86:87], v[2:3], v[82:83] op_sel:[0,1] op_sel_hi:[1,0]
	v_pk_fma_f32 v[190:191], v[190:191], s[10:11], v[208:209] op_sel:[0,0,1] op_sel_hi:[1,0,0]
	v_pk_add_f32 v[208:209], v[192:193], v[210:211]
	v_pk_add_f32 v[192:193], v[192:193], v[210:211] neg_lo:[0,1] neg_hi:[0,1]
	v_pk_mul_f32 v[102:103], v[2:3], v[98:99] op_sel:[0,1] op_sel_hi:[1,0]
	v_pk_mul_f32 v[210:211], v[192:193], s[72:73]
	v_pk_mul_f32 v[118:119], v[2:3], v[114:115] op_sel:[0,1] op_sel_hi:[1,0]
	v_pk_fma_f32 v[192:193], v[192:193], s[76:77], v[210:211] op_sel:[0,0,1] op_sel_hi:[1,0,0]
	v_pk_add_f32 v[210:211], v[194:195], v[212:213]
	v_pk_add_f32 v[212:213], v[194:195], v[212:213] neg_lo:[0,1] neg_hi:[0,1]
	v_xor_b32_e32 v20, 0x80000000, v9
	v_pk_add_f32 v[194:195], v[196:197], v[214:215]
	v_pk_add_f32 v[196:197], v[196:197], v[214:215] neg_lo:[0,1] neg_hi:[0,1]
	v_mov_b32_e32 v21, v9
	v_pk_mul_f32 v[214:215], v[196:197], s[72:73]
	v_pk_fma_f32 v[16:17], v[4:5], v[10:11], v[16:17] op_sel_hi:[0,1,1]
	v_pk_fma_f32 v[196:197], v[196:197], s[76:77], v[214:215] op_sel:[0,0,1] op_sel_hi:[1,0,0] neg_lo:[1,0,0] neg_hi:[1,0,0]
	v_pk_add_f32 v[214:215], v[198:199], v[216:217]
	v_pk_add_f32 v[198:199], v[198:199], v[216:217] neg_lo:[0,1] neg_hi:[0,1]
	v_pk_mul_f32 v[18:19], v[12:13], v[10:11] op_sel:[0,1] op_sel_hi:[1,0]
	v_pk_mul_f32 v[216:217], v[198:199], s[68:69]
	v_pk_fma_f32 v[30:31], v[4:5], v[26:27], v[30:31] op_sel_hi:[0,1,1]
	v_pk_fma_f32 v[198:199], v[198:199], s[10:11], v[216:217] op_sel:[0,0,1] op_sel_hi:[1,0,0] neg_lo:[1,0,0] neg_hi:[1,0,0]
	v_pk_add_f32 v[216:217], v[202:203], v[218:219]
	v_pk_add_f32 v[202:203], v[202:203], v[218:219] neg_lo:[0,1] neg_hi:[0,1]
	v_pk_mul_f32 v[42:43], v[12:13], v[26:27] op_sel:[0,1] op_sel_hi:[1,0]
	v_pk_mul_f32 v[218:219], v[202:203], s[62:63]
	v_pk_fma_f32 v[54:55], v[4:5], v[50:51], v[54:55] op_sel_hi:[0,1,1]
	v_pk_fma_f32 v[202:203], v[202:203], s[50:51], v[218:219] op_sel:[0,0,1] op_sel_hi:[1,0,0] neg_lo:[1,0,0] neg_hi:[1,0,0]
	v_pk_add_f32 v[218:219], v[156:157], v[206:207] op_sel:[0,1] op_sel_hi:[1,0] neg_hi:[0,1]
	v_pk_add_f32 v[156:157], v[156:157], v[206:207] op_sel:[0,1] op_sel_hi:[1,0] neg_lo:[0,1]
	v_pk_add_f32 v[206:207], v[158:159], v[174:175]
	v_pk_add_f32 v[158:159], v[158:159], v[174:175] neg_lo:[0,1] neg_hi:[0,1]
	v_pk_mul_f32 v[58:59], v[12:13], v[50:51] op_sel:[0,1] op_sel_hi:[1,0]
	v_pk_mul_f32 v[174:175], v[158:159], s[62:63]
	v_pk_fma_f32 v[70:71], v[4:5], v[66:67], v[70:71] op_sel_hi:[0,1,1]
	v_pk_fma_f32 v[158:159], v[158:159], s[50:51], v[174:175] op_sel:[0,0,1] op_sel_hi:[1,0,0]
	v_pk_add_f32 v[174:175], v[160:161], v[176:177]
	v_pk_add_f32 v[160:161], v[160:161], v[176:177] neg_lo:[0,1] neg_hi:[0,1]
	v_pk_mul_f32 v[74:75], v[12:13], v[66:67] op_sel:[0,1] op_sel_hi:[1,0]
	v_pk_mul_f32 v[176:177], v[160:161], s[68:69]
	v_pk_fma_f32 v[86:87], v[4:5], v[82:83], v[86:87] op_sel_hi:[0,1,1]
	v_pk_fma_f32 v[160:161], v[160:161], s[10:11], v[176:177] op_sel:[0,0,1] op_sel_hi:[1,0,0]
	v_pk_add_f32 v[176:177], v[162:163], v[178:179]
	v_pk_add_f32 v[162:163], v[162:163], v[178:179] neg_lo:[0,1] neg_hi:[0,1]
	v_pk_mul_f32 v[90:91], v[12:13], v[82:83] op_sel:[0,1] op_sel_hi:[1,0]
	v_pk_mul_f32 v[178:179], v[162:163], s[72:73]
	v_pk_fma_f32 v[102:103], v[4:5], v[98:99], v[102:103] op_sel_hi:[0,1,1]
	v_pk_fma_f32 v[162:163], v[162:163], s[76:77], v[178:179] op_sel:[0,0,1] op_sel_hi:[1,0,0]
	v_pk_add_f32 v[178:179], v[164:165], v[180:181]
	v_pk_add_f32 v[180:181], v[164:165], v[180:181] neg_lo:[0,1] neg_hi:[0,1]
	v_pk_mul_f32 v[106:107], v[12:13], v[98:99] op_sel:[0,1] op_sel_hi:[1,0]
	v_pk_add_f32 v[164:165], v[166:167], v[182:183]
	v_pk_add_f32 v[166:167], v[166:167], v[182:183] neg_lo:[0,1] neg_hi:[0,1]
	v_pk_fma_f32 v[118:119], v[4:5], v[114:115], v[118:119] op_sel_hi:[0,1,1]
	v_pk_mul_f32 v[182:183], v[166:167], s[72:73]
	v_pk_mul_f32 v[122:123], v[12:13], v[114:115] op_sel:[0,1] op_sel_hi:[1,0]
	v_pk_fma_f32 v[166:167], v[166:167], s[76:77], v[182:183] op_sel:[0,0,1] op_sel_hi:[1,0,0] neg_lo:[1,0,0] neg_hi:[1,0,0]
	v_pk_add_f32 v[182:183], v[168:169], v[184:185]
	v_pk_add_f32 v[168:169], v[168:169], v[184:185] neg_lo:[0,1] neg_hi:[0,1]
	v_pk_fma_f32 v[18:19], v[6:7], v[10:11], v[18:19] op_sel_hi:[0,1,1]
	v_pk_mul_f32 v[184:185], v[168:169], s[68:69]
	v_pk_mul_f32 v[22:23], v[10:11], v[20:21] op_sel:[1,0] op_sel_hi:[0,1]
	v_pk_fma_f32 v[168:169], v[168:169], s[10:11], v[184:185] op_sel:[0,0,1] op_sel_hi:[1,0,0] neg_lo:[1,0,0] neg_hi:[1,0,0]
	v_pk_add_f32 v[184:185], v[170:171], v[186:187]
	v_pk_add_f32 v[170:171], v[170:171], v[186:187] neg_lo:[0,1] neg_hi:[0,1]
	v_pk_fma_f32 v[42:43], v[6:7], v[26:27], v[42:43] op_sel_hi:[0,1,1]
	v_pk_mul_f32 v[186:187], v[170:171], s[62:63]
	v_pk_mul_f32 v[46:47], v[20:21], v[26:27] op_sel:[0,1] op_sel_hi:[1,0]
	v_pk_fma_f32 v[170:171], v[170:171], s[50:51], v[186:187] op_sel:[0,0,1] op_sel_hi:[1,0,0] neg_lo:[1,0,0] neg_hi:[1,0,0]
	v_pk_add_f32 v[186:187], v[220:221], v[210:211]
	v_pk_add_f32 v[210:211], v[220:221], v[210:211] neg_lo:[0,1] neg_hi:[0,1]
	v_pk_add_f32 v[220:221], v[222:223], v[194:195]
	v_pk_add_f32 v[194:195], v[222:223], v[194:195] neg_lo:[0,1] neg_hi:[0,1]
	v_pk_fma_f32 v[58:59], v[6:7], v[50:51], v[58:59] op_sel_hi:[0,1,1]
	v_pk_mul_f32 v[222:223], v[194:195], s[68:69]
	v_pk_mul_f32 v[62:63], v[20:21], v[50:51] op_sel:[0,1] op_sel_hi:[1,0]
	v_pk_fma_f32 v[194:195], v[194:195], s[10:11], v[222:223] op_sel:[0,0,1] op_sel_hi:[1,0,0]
	v_pk_add_f32 v[222:223], v[188:189], v[214:215]
	v_pk_add_f32 v[214:215], v[188:189], v[214:215] neg_lo:[0,1] neg_hi:[0,1]
	v_pk_fma_f32 v[74:75], v[6:7], v[66:67], v[74:75] op_sel_hi:[0,1,1]
	v_pk_add_f32 v[188:189], v[208:209], v[216:217]
	v_pk_add_f32 v[208:209], v[208:209], v[216:217] neg_lo:[0,1] neg_hi:[0,1]
	v_pk_mul_f32 v[78:79], v[20:21], v[66:67] op_sel:[0,1] op_sel_hi:[1,0]
	v_pk_mul_f32 v[216:217], v[208:209], s[68:69]
	v_pk_fma_f32 v[90:91], v[6:7], v[82:83], v[90:91] op_sel_hi:[0,1,1]
	v_pk_fma_f32 v[208:209], v[208:209], s[10:11], v[216:217] op_sel:[0,0,1] op_sel_hi:[1,0,0] neg_lo:[1,0,0] neg_hi:[1,0,0]
	v_pk_add_f32 v[216:217], v[204:205], v[212:213] op_sel:[0,1] op_sel_hi:[1,0] neg_hi:[0,1]
	v_pk_add_f32 v[204:205], v[204:205], v[212:213] op_sel:[0,1] op_sel_hi:[1,0] neg_lo:[0,1]
	v_pk_add_f32 v[212:213], v[172:173], v[196:197]
	v_pk_add_f32 v[172:173], v[172:173], v[196:197] neg_lo:[0,1] neg_hi:[0,1]
	v_pk_mul_f32 v[94:95], v[20:21], v[82:83] op_sel:[0,1] op_sel_hi:[1,0]
	v_pk_mul_f32 v[196:197], v[172:173], s[68:69]
	v_pk_fma_f32 v[106:107], v[6:7], v[98:99], v[106:107] op_sel_hi:[0,1,1]
	v_pk_fma_f32 v[172:173], v[172:173], s[10:11], v[196:197] op_sel:[0,0,1] op_sel_hi:[1,0,0]
	v_pk_add_f32 v[196:197], v[190:191], v[198:199]
	v_pk_add_f32 v[198:199], v[190:191], v[198:199] neg_lo:[0,1] neg_hi:[0,1]
	v_pk_mul_f32 v[110:111], v[20:21], v[98:99] op_sel:[0,1] op_sel_hi:[1,0]
	v_pk_add_f32 v[190:191], v[192:193], v[202:203]
	v_pk_add_f32 v[192:193], v[192:193], v[202:203] neg_lo:[0,1] neg_hi:[0,1]
	v_pk_fma_f32 v[122:123], v[6:7], v[114:115], v[122:123] op_sel_hi:[0,1,1]
	v_pk_mul_f32 v[202:203], v[192:193], s[68:69]
	v_pk_mul_f32 v[126:127], v[20:21], v[114:115] op_sel:[0,1] op_sel_hi:[1,0]
	v_pk_fma_f32 v[192:193], v[192:193], s[10:11], v[202:203] op_sel:[0,0,1] op_sel_hi:[1,0,0] neg_lo:[1,0,0] neg_hi:[1,0,0]
	v_pk_add_f32 v[202:203], v[218:219], v[178:179]
	v_pk_add_f32 v[178:179], v[218:219], v[178:179] neg_lo:[0,1] neg_hi:[0,1]
	v_pk_add_f32 v[218:219], v[206:207], v[164:165]
	v_pk_add_f32 v[164:165], v[206:207], v[164:165] neg_lo:[0,1] neg_hi:[0,1]
	v_xor_b32_e32 v24, 0x80000000, v17
	v_pk_mul_f32 v[206:207], v[164:165], s[68:69]
	v_xor_b32_e32 v28, 0x80000000, v19
	v_pk_fma_f32 v[164:165], v[164:165], s[10:11], v[206:207] op_sel:[0,0,1] op_sel_hi:[1,0,0]
	v_pk_add_f32 v[206:207], v[174:175], v[182:183]
	v_pk_add_f32 v[182:183], v[174:175], v[182:183] neg_lo:[0,1] neg_hi:[0,1]
	v_pk_fma_f32 v[22:23], v[10:11], v[8:9], v[22:23] op_sel_hi:[1,0,1]
	v_pk_add_f32 v[174:175], v[176:177], v[184:185]
	v_pk_add_f32 v[176:177], v[176:177], v[184:185] neg_lo:[0,1] neg_hi:[0,1]
	v_pk_fma_f32 v[46:47], v[8:9], v[26:27], v[46:47] op_sel_hi:[0,1,1]
	v_pk_mul_f32 v[184:185], v[176:177], s[68:69]
	v_pk_fma_f32 v[62:63], v[8:9], v[50:51], v[62:63] op_sel_hi:[0,1,1]
	v_pk_fma_f32 v[176:177], v[176:177], s[10:11], v[184:185] op_sel:[0,0,1] op_sel_hi:[1,0,0] neg_lo:[1,0,0] neg_hi:[1,0,0]
	v_pk_add_f32 v[184:185], v[156:157], v[180:181] op_sel:[0,1] op_sel_hi:[1,0] neg_hi:[0,1]
	v_pk_add_f32 v[156:157], v[156:157], v[180:181] op_sel:[0,1] op_sel_hi:[1,0] neg_lo:[0,1]
	v_pk_add_f32 v[180:181], v[158:159], v[166:167]
	v_pk_add_f32 v[158:159], v[158:159], v[166:167] neg_lo:[0,1] neg_hi:[0,1]
	v_pk_fma_f32 v[78:79], v[8:9], v[66:67], v[78:79] op_sel_hi:[0,1,1]
	v_pk_mul_f32 v[166:167], v[158:159], s[68:69]
	v_pk_fma_f32 v[94:95], v[8:9], v[82:83], v[94:95] op_sel_hi:[0,1,1]
	v_pk_fma_f32 v[158:159], v[158:159], s[10:11], v[166:167] op_sel:[0,0,1] op_sel_hi:[1,0,0]
	v_pk_add_f32 v[166:167], v[160:161], v[168:169]
	v_pk_add_f32 v[168:169], v[160:161], v[168:169] neg_lo:[0,1] neg_hi:[0,1]
	v_pk_fma_f32 v[110:111], v[8:9], v[98:99], v[110:111] op_sel_hi:[0,1,1]
	v_pk_add_f32 v[160:161], v[162:163], v[170:171]
	v_pk_add_f32 v[162:163], v[162:163], v[170:171] neg_lo:[0,1] neg_hi:[0,1]
	v_pk_fma_f32 v[126:127], v[8:9], v[114:115], v[126:127] op_sel_hi:[0,1,1]
	v_pk_mul_f32 v[170:171], v[162:163], s[68:69]
	v_mov_b32_e32 v25, v17
	v_pk_fma_f32 v[162:163], v[162:163], s[10:11], v[170:171] op_sel:[0,0,1] op_sel_hi:[1,0,0] neg_lo:[1,0,0] neg_hi:[1,0,0]
	v_pk_add_f32 v[170:171], v[186:187], v[222:223]
	v_pk_add_f32 v[186:187], v[186:187], v[222:223] neg_lo:[0,1] neg_hi:[0,1]
	v_pk_add_f32 v[222:223], v[220:221], v[188:189]
	v_pk_add_f32 v[220:221], v[220:221], v[188:189] neg_lo:[0,1] neg_hi:[0,1]
	s_mov_b32 s10, s60
	s_nop 0
	s_nop 0
	v_pk_add_f32 v[188:189], v[210:211], v[214:215] op_sel:[0,1] op_sel_hi:[1,0] neg_hi:[0,1]
	v_pk_add_f32 v[210:211], v[210:211], v[214:215] op_sel:[0,1] op_sel_hi:[1,0] neg_lo:[0,1]
	v_pk_add_f32 v[214:215], v[194:195], v[208:209]
	v_pk_add_f32 v[208:209], v[194:195], v[208:209] neg_lo:[0,1] neg_hi:[0,1]
	s_add_i32 s60, s60, s28
	s_nop 0
	s_nop 0
	v_pk_add_f32 v[194:195], v[216:217], v[196:197]
	v_pk_add_f32 v[196:197], v[216:217], v[196:197] neg_lo:[0,1] neg_hi:[0,1]
	v_pk_add_f32 v[216:217], v[212:213], v[190:191]
	v_pk_add_f32 v[212:213], v[212:213], v[190:191] neg_lo:[0,1] neg_hi:[0,1]
	s_cmpk_gt_i32 s60, 0x7ff
	s_nop 0
	s_nop 0
	v_pk_add_f32 v[190:191], v[204:205], v[198:199] op_sel:[0,1] op_sel_hi:[1,0] neg_hi:[0,1]
	v_pk_add_f32 v[198:199], v[204:205], v[198:199] op_sel:[0,1] op_sel_hi:[1,0] neg_lo:[0,1]
	v_pk_add_f32 v[204:205], v[172:173], v[192:193]
	v_pk_add_f32 v[192:193], v[172:173], v[192:193] neg_lo:[0,1] neg_hi:[0,1]
	s_cselect_b64 s[76:77], -1, 0
	s_nop 0
	s_nop 0
	v_pk_add_f32 v[172:173], v[202:203], v[206:207]
	v_pk_add_f32 v[202:203], v[202:203], v[206:207] neg_lo:[0,1] neg_hi:[0,1]
	v_pk_add_f32 v[206:207], v[218:219], v[174:175]
	v_pk_add_f32 v[218:219], v[218:219], v[174:175] neg_lo:[0,1] neg_hi:[0,1]
	s_cmpk_lt_i32 s60, 0x800
	s_nop 0
	s_nop 0
	v_pk_add_f32 v[174:175], v[178:179], v[182:183] op_sel:[0,1] op_sel_hi:[1,0] neg_hi:[0,1]
	v_pk_add_f32 v[178:179], v[178:179], v[182:183] op_sel:[0,1] op_sel_hi:[1,0] neg_lo:[0,1]
	v_pk_add_f32 v[182:183], v[164:165], v[176:177]
	v_pk_add_f32 v[176:177], v[164:165], v[176:177] neg_lo:[0,1] neg_hi:[0,1]
	s_cselect_b32 s45, s60, s10
	s_nop 0
	s_nop 0
	v_pk_add_f32 v[164:165], v[184:185], v[166:167]
	v_pk_add_f32 v[166:167], v[184:185], v[166:167] neg_lo:[0,1] neg_hi:[0,1]
	v_pk_add_f32 v[184:185], v[180:181], v[160:161]
	v_pk_add_f32 v[180:181], v[180:181], v[160:161] neg_lo:[0,1] neg_hi:[0,1]
	s_lshl_b32 s11, s45, 1
	s_nop 0
	s_nop 0
	v_pk_add_f32 v[160:161], v[156:157], v[168:169] op_sel:[0,1] op_sel_hi:[1,0] neg_hi:[0,1]
	v_pk_add_f32 v[156:157], v[156:157], v[168:169] op_sel:[0,1] op_sel_hi:[1,0] neg_lo:[0,1]
	v_pk_add_f32 v[168:169], v[158:159], v[162:163]
	v_pk_add_f32 v[158:159], v[158:159], v[162:163] neg_lo:[0,1] neg_hi:[0,1]
	v_mov_b32_e32 v29, v19
	v_xor_b32_e32 v163, 0x80000000, v158
	v_mov_b32_e32 v162, v159
	v_pk_add_f32 v[158:159], v[170:171], v[222:223]
	v_pk_add_f32 v[170:171], v[170:171], v[222:223] neg_lo:[0,1] neg_hi:[0,1]
	v_pk_add_f32 v[222:223], v[186:187], v[220:221] op_sel:[0,1] op_sel_hi:[1,0] neg_hi:[0,1]
	v_pk_add_f32 v[186:187], v[186:187], v[220:221] op_sel:[0,1] op_sel_hi:[1,0] neg_lo:[0,1]
	v_pk_add_f32 v[220:221], v[188:189], v[214:215]
	v_pk_add_f32 v[188:189], v[188:189], v[214:215] neg_lo:[0,1] neg_hi:[0,1]
	v_pk_add_f32 v[214:215], v[210:211], v[208:209] op_sel:[0,1] op_sel_hi:[1,0] neg_hi:[0,1]
	v_pk_add_f32 v[208:209], v[210:211], v[208:209] op_sel:[0,1] op_sel_hi:[1,0] neg_lo:[0,1]
	v_pk_add_f32 v[210:211], v[194:195], v[216:217]
	v_pk_add_f32 v[194:195], v[194:195], v[216:217] neg_lo:[0,1] neg_hi:[0,1]
	v_pk_add_f32 v[216:217], v[196:197], v[212:213] op_sel:[0,1] op_sel_hi:[1,0] neg_hi:[0,1]
	v_pk_add_f32 v[196:197], v[196:197], v[212:213] op_sel:[0,1] op_sel_hi:[1,0] neg_lo:[0,1]
	v_pk_add_f32 v[212:213], v[190:191], v[204:205]
	v_pk_add_f32 v[190:191], v[190:191], v[204:205] neg_lo:[0,1] neg_hi:[0,1]
	v_pk_add_f32 v[204:205], v[198:199], v[192:193] op_sel:[0,1] op_sel_hi:[1,0] neg_hi:[0,1]
	v_pk_add_f32 v[192:193], v[198:199], v[192:193] op_sel:[0,1] op_sel_hi:[1,0] neg_lo:[0,1]
	v_pk_add_f32 v[198:199], v[172:173], v[206:207]
	v_pk_add_f32 v[172:173], v[172:173], v[206:207] neg_lo:[0,1] neg_hi:[0,1]
	v_pk_mul_f32 v[2:3], v[2:3], v[198:199] op_sel:[0,1] op_sel_hi:[1,0]
	v_pk_add_f32 v[206:207], v[202:203], v[218:219] op_sel:[0,1] op_sel_hi:[1,0] neg_hi:[0,1]
	v_pk_add_f32 v[202:203], v[202:203], v[218:219] op_sel:[0,1] op_sel_hi:[1,0] neg_lo:[0,1]
	v_pk_add_f32 v[218:219], v[174:175], v[182:183]
	v_pk_add_f32 v[174:175], v[174:175], v[182:183] neg_lo:[0,1] neg_hi:[0,1]
	v_pk_add_f32 v[182:183], v[178:179], v[176:177] op_sel:[0,1] op_sel_hi:[1,0] neg_hi:[0,1]
	v_pk_add_f32 v[176:177], v[178:179], v[176:177] op_sel:[0,1] op_sel_hi:[1,0] neg_lo:[0,1]
	v_pk_add_f32 v[178:179], v[164:165], v[184:185]
	v_pk_fma_f32 v[2:3], v[4:5], v[198:199], v[2:3] op_sel_hi:[0,1,1]
	v_pk_mul_f32 v[4:5], v[12:13], v[210:211] op_sel:[0,1] op_sel_hi:[1,0]
	s_and_b32 s10, s45, 0x3ff
	v_pk_fma_f32 v[4:5], v[6:7], v[210:211], v[4:5] op_sel_hi:[0,1,1]
	v_pk_mul_f32 v[6:7], v[20:21], v[178:179] op_sel:[0,1] op_sel_hi:[1,0]
	s_and_b32 s11, s11, 0xfffff800
	v_pk_fma_f32 v[6:7], v[8:9], v[178:179], v[6:7] op_sel_hi:[0,1,1]
	v_pk_mul_f32 v[8:9], v[14:15], v[220:221] op_sel:[0,1] op_sel_hi:[1,0]
	v_xor_b32_e32 v32, 0x80000000, v23
	v_xor_b32_e32 v44, 0x80000000, v27
	v_xor_b32_e32 v48, 0x80000000, v31
	v_xor_b32_e32 v52, 0x80000000, v43
	v_mov_b32_e32 v33, v23
	v_mov_b32_e32 v45, v27
	v_mov_b32_e32 v49, v31
	v_mov_b32_e32 v53, v43
	v_pk_add_f32 v[164:165], v[164:165], v[184:185] neg_lo:[0,1] neg_hi:[0,1]
	v_pk_add_f32 v[184:185], v[166:167], v[180:181] op_sel:[0,1] op_sel_hi:[1,0] neg_hi:[0,1]
	v_pk_add_f32 v[166:167], v[166:167], v[180:181] op_sel:[0,1] op_sel_hi:[1,0] neg_lo:[0,1]
	v_pk_add_f32 v[180:181], v[160:161], v[168:169]
	v_pk_fma_f32 v[8:9], v[10:11], v[220:221], v[8:9] op_sel_hi:[0,1,1]
	v_pk_mul_f32 v[10:11], v[24:25], v[218:219] op_sel:[0,1] op_sel_hi:[1,0]
	v_pk_mul_f32 v[12:13], v[28:29], v[212:213] op_sel:[0,1] op_sel_hi:[1,0]
	s_or_b32 s10, s11, s10
	v_xor_b32_e32 v56, 0x80000000, v47
	v_xor_b32_e32 v60, 0x80000000, v51
	v_xor_b32_e32 v64, 0x80000000, v55
	v_xor_b32_e32 v68, 0x80000000, v59
	v_xor_b32_e32 v72, 0x80000000, v63
	v_xor_b32_e32 v76, 0x80000000, v67
	v_xor_b32_e32 v80, 0x80000000, v71
	v_mov_b32_e32 v57, v47
	v_mov_b32_e32 v61, v51
	v_mov_b32_e32 v65, v55
	v_mov_b32_e32 v69, v59
	v_mov_b32_e32 v73, v63
	v_mov_b32_e32 v77, v67
	v_mov_b32_e32 v81, v71
	v_pk_add_f32 v[160:161], v[160:161], v[168:169] neg_lo:[0,1] neg_hi:[0,1]
	v_pk_add_f32 v[168:169], v[156:157], v[162:163]
	v_pk_fma_f32 v[10:11], v[16:17], v[218:219], v[10:11] op_sel_hi:[0,1,1]
	v_pk_fma_f32 v[12:13], v[18:19], v[212:213], v[12:13] op_sel_hi:[0,1,1]
	v_pk_mul_f32 v[14:15], v[32:33], v[180:181] op_sel:[0,1] op_sel_hi:[1,0]
	v_pk_mul_f32 v[16:17], v[44:45], v[222:223] op_sel:[0,1] op_sel_hi:[1,0]
	v_pk_mul_f32 v[18:19], v[48:49], v[206:207] op_sel:[0,1] op_sel_hi:[1,0]
	v_pk_mul_f32 v[20:21], v[52:53], v[216:217] op_sel:[0,1] op_sel_hi:[1,0]
	s_ashr_i32 s11, s10, 31
	v_xor_b32_e32 v84, 0x80000000, v75
	v_xor_b32_e32 v88, 0x80000000, v79
	v_xor_b32_e32 v92, 0x80000000, v83
	v_xor_b32_e32 v96, 0x80000000, v87
	v_xor_b32_e32 v100, 0x80000000, v91
	v_xor_b32_e32 v104, 0x80000000, v95
	v_xor_b32_e32 v108, 0x80000000, v99
	v_xor_b32_e32 v112, 0x80000000, v103
	v_xor_b32_e32 v116, 0x80000000, v107
	v_xor_b32_e32 v120, 0x80000000, v111
	v_xor_b32_e32 v124, 0x80000000, v115
	v_xor_b32_e32 v128, 0x80000000, v119
	v_xor_b32_e32 v130, 0x80000000, v123
	v_xor_b32_e32 v132, 0x80000000, v127
	v_mov_b32_e32 v85, v75
	v_mov_b32_e32 v89, v79
	v_mov_b32_e32 v93, v83
	v_mov_b32_e32 v97, v87
	v_mov_b32_e32 v101, v91
	v_mov_b32_e32 v105, v95
	v_mov_b32_e32 v109, v99
	v_mov_b32_e32 v113, v103
	v_mov_b32_e32 v117, v107
	v_mov_b32_e32 v121, v111
	v_mov_b32_e32 v125, v115
	v_mov_b32_e32 v129, v119
	v_mov_b32_e32 v131, v123
	v_mov_b32_e32 v133, v127
	v_pk_add_f32 v[156:157], v[156:157], v[162:163] neg_lo:[0,1] neg_hi:[0,1]
	v_pk_fma_f32 v[14:15], v[22:23], v[180:181], v[14:15] op_sel_hi:[0,1,1]
	v_pk_fma_f32 v[16:17], v[26:27], v[222:223], v[16:17] op_sel_hi:[0,1,1]
	v_pk_fma_f32 v[18:19], v[30:31], v[206:207], v[18:19] op_sel_hi:[0,1,1]
	v_pk_fma_f32 v[20:21], v[42:43], v[216:217], v[20:21] op_sel_hi:[0,1,1]
	v_pk_mul_f32 v[22:23], v[56:57], v[184:185] op_sel:[0,1] op_sel_hi:[1,0]
	v_pk_mul_f32 v[24:25], v[60:61], v[214:215] op_sel:[0,1] op_sel_hi:[1,0]
	v_pk_mul_f32 v[26:27], v[64:65], v[182:183] op_sel:[0,1] op_sel_hi:[1,0]
	v_pk_mul_f32 v[28:29], v[68:69], v[204:205] op_sel:[0,1] op_sel_hi:[1,0]
	v_pk_mul_f32 v[30:31], v[72:73], v[168:169] op_sel:[0,1] op_sel_hi:[1,0]
	v_pk_mul_f32 v[32:33], v[76:77], v[170:171] op_sel:[0,1] op_sel_hi:[1,0]
	v_pk_mul_f32 v[42:43], v[80:81], v[172:173] op_sel:[0,1] op_sel_hi:[1,0]
	s_lshl_b64 s[78:79], s[10:11], 15
	s_bitset1_b32 s10, 10
	v_pk_fma_f32 v[22:23], v[46:47], v[184:185], v[22:23] op_sel_hi:[0,1,1]
	v_pk_fma_f32 v[24:25], v[50:51], v[214:215], v[24:25] op_sel_hi:[0,1,1]
	v_pk_fma_f32 v[26:27], v[54:55], v[182:183], v[26:27] op_sel_hi:[0,1,1]
	v_pk_fma_f32 v[28:29], v[58:59], v[204:205], v[28:29] op_sel_hi:[0,1,1]
	v_pk_fma_f32 v[30:31], v[62:63], v[168:169], v[30:31] op_sel_hi:[0,1,1]
	v_pk_fma_f32 v[32:33], v[66:67], v[170:171], v[32:33] op_sel_hi:[0,1,1]
	v_pk_fma_f32 v[42:43], v[70:71], v[172:173], v[42:43] op_sel_hi:[0,1,1]
	v_pk_mul_f32 v[44:45], v[84:85], v[194:195] op_sel:[0,1] op_sel_hi:[1,0]
	v_pk_mul_f32 v[46:47], v[88:89], v[164:165] op_sel:[0,1] op_sel_hi:[1,0]
	v_pk_mul_f32 v[48:49], v[92:93], v[188:189] op_sel:[0,1] op_sel_hi:[1,0]
	v_pk_mul_f32 v[50:51], v[96:97], v[174:175] op_sel:[0,1] op_sel_hi:[1,0]
	v_pk_mul_f32 v[52:53], v[100:101], v[190:191] op_sel:[0,1] op_sel_hi:[1,0]
	v_pk_mul_f32 v[54:55], v[104:105], v[160:161] op_sel:[0,1] op_sel_hi:[1,0]
	v_pk_mul_f32 v[56:57], v[108:109], v[186:187] op_sel:[0,1] op_sel_hi:[1,0]
	v_pk_mul_f32 v[58:59], v[112:113], v[202:203] op_sel:[0,1] op_sel_hi:[1,0]
	v_pk_mul_f32 v[60:61], v[116:117], v[196:197] op_sel:[0,1] op_sel_hi:[1,0]
	v_pk_mul_f32 v[62:63], v[120:121], v[166:167] op_sel:[0,1] op_sel_hi:[1,0]
	v_pk_mul_f32 v[64:65], v[124:125], v[208:209] op_sel:[0,1] op_sel_hi:[1,0]
	v_pk_mul_f32 v[66:67], v[128:129], v[176:177] op_sel:[0,1] op_sel_hi:[1,0]
	v_pk_mul_f32 v[68:69], v[130:131], v[192:193] op_sel:[0,1] op_sel_hi:[1,0]
	v_pk_mul_f32 v[70:71], v[132:133], v[156:157] op_sel:[0,1] op_sel_hi:[1,0]
	s_ashr_i32 s11, s10, 31
	v_pk_fma_f32 v[44:45], v[74:75], v[194:195], v[44:45] op_sel_hi:[0,1,1]
	v_pk_fma_f32 v[46:47], v[78:79], v[164:165], v[46:47] op_sel_hi:[0,1,1]
	v_pk_fma_f32 v[48:49], v[82:83], v[188:189], v[48:49] op_sel_hi:[0,1,1]
	v_pk_fma_f32 v[50:51], v[86:87], v[174:175], v[50:51] op_sel_hi:[0,1,1]
	v_pk_fma_f32 v[52:53], v[90:91], v[190:191], v[52:53] op_sel_hi:[0,1,1]
	v_pk_fma_f32 v[54:55], v[94:95], v[160:161], v[54:55] op_sel_hi:[0,1,1]
	v_pk_fma_f32 v[56:57], v[98:99], v[186:187], v[56:57] op_sel_hi:[0,1,1]
	v_pk_fma_f32 v[58:59], v[102:103], v[202:203], v[58:59] op_sel_hi:[0,1,1]
	v_pk_fma_f32 v[60:61], v[106:107], v[196:197], v[60:61] op_sel_hi:[0,1,1]
	v_pk_fma_f32 v[62:63], v[110:111], v[166:167], v[62:63] op_sel_hi:[0,1,1]
	v_pk_fma_f32 v[64:65], v[114:115], v[208:209], v[64:65] op_sel_hi:[0,1,1]
	v_pk_fma_f32 v[66:67], v[118:119], v[176:177], v[66:67] op_sel_hi:[0,1,1]
	v_pk_fma_f32 v[68:69], v[122:123], v[192:193], v[68:69] op_sel_hi:[0,1,1]
	v_pk_fma_f32 v[70:71], v[126:127], v[156:157], v[70:71] op_sel_hi:[0,1,1]
	ds_write2_b64 v40, v[158:159], v[32:33] offset1:16
	ds_write2_b64 v40, v[16:17], v[56:57] offset0:33 offset1:49
	ds_write2_b64 v40, v[8:9], v[48:49] offset0:66 offset1:82
	ds_write2_b64 v40, v[24:25], v[64:65] offset0:99 offset1:115
	ds_write2_b64 v40, v[4:5], v[44:45] offset0:132 offset1:148
	ds_write2_b64 v40, v[20:21], v[60:61] offset0:165 offset1:181
	ds_write2_b64 v40, v[12:13], v[52:53] offset0:198 offset1:214
	ds_write2_b64 v40, v[28:29], v[68:69] offset0:231 offset1:247
	ds_write2_b64 v155, v[2:3], v[42:43] offset0:8 offset1:24
	ds_write2_b64 v155, v[18:19], v[58:59] offset0:41 offset1:57
	ds_write2_b64 v155, v[10:11], v[50:51] offset0:74 offset1:90
	ds_write2_b64 v155, v[26:27], v[66:67] offset0:107 offset1:123
	ds_write2_b64 v155, v[6:7], v[46:47] offset0:140 offset1:156
	ds_write2_b64 v155, v[22:23], v[62:63] offset0:173 offset1:189
	ds_write2_b64 v155, v[14:15], v[54:55] offset0:206 offset1:222
	ds_write2_b64 v155, v[30:31], v[70:71] offset0:239 offset1:255
	s_lshl_b64 s[10:11], s[10:11], 15
	v_lshl_add_u64 v[2:3], v[36:37], 0, s[78:79]
	s_waitcnt lgkmcnt(0)
	s_barrier
	global_load_dwordx4 v[6:9], v[2:3], off nt
	global_load_dwordx4 v[30:33], v[2:3], off offset:16 nt
	v_lshl_add_u64 v[2:3], v[36:37], 0, s[10:11]
	global_load_dwordx4 v[26:29], v[2:3], off nt
	global_load_dwordx4 v[18:21], v[2:3], off offset:16 nt
	v_mov_b32_e32 v120, 0
	s_and_saveexec_b64 s[10:11], s[0:1]
	s_cbranch_execz .LBB0_273
	global_load_ushort v120, v[2:3], off offset:32

.LBB0_275:
	s_or_b64 exec, exec, s[10:11]
	v_mov_b32_e32 v40, v1
	s_mov_b32 s73, s50
	v_ashrrev_i32_e32 v42, 31, v40
	v_lshrrev_b32_e32 v42, 23, v42
	v_add_u32_e32 v42, v40, v42
	v_ashrrev_i32_e32 v42, 9, v42
	v_mul_i32_i24_e32 v44, 0x200, v42
	v_sub_u32_e32 v70, v40, v44
	v_lshlrev_b32_e32 v40, 14, v42
	v_lshlrev_b32_e32 v42, 1, v70
	v_bfrev_b32_e32 v42, v42
	v_lshrrev_b32_e32 v42, 22, v42
	v_sub_u32_e32 v42, 0x400, v42
	v_bfrev_b32_e32 v42, v42
	v_lshrrev_b32_e32 v42, 18, v42
	v_and_b32_e32 v42, 0x3ff0, v42
	v_cmp_eq_u32_e64 s[10:11], 0, v70
	v_lshl_add_u32 v44, v70, 5, v40
	v_lshlrev_b32_e32 v45, 3, v44
	v_cndmask_b32_e64 v42, v42, 16, s[10:11]
	v_or_b32_e32 v40, v42, v40
	v_ashrrev_i32_e32 v44, 2, v44
	v_ashrrev_i32_e32 v42, 5, v40
	v_add3_u32 v44, 0, v45, v44
	v_lshlrev_b32_e32 v40, 3, v40
	v_lshlrev_b32_e32 v42, 3, v42
	v_add3_u32 v40, 0, v40, v42
	ds_read2_b64 v[46:49], v44 offset1:1
	ds_read2_b64 v[50:53], v44 offset0:2 offset1:3
	ds_read2_b64 v[76:79], v40 offset1:1
	ds_read2_b64 v[80:83], v40 offset0:2 offset1:3
	ds_read2_b64 v[54:57], v44 offset0:4 offset1:5
	ds_read2_b64 v[58:61], v44 offset0:6 offset1:7
	ds_read2_b64 v[84:87], v40 offset0:4 offset1:5
	ds_read2_b64 v[88:91], v40 offset0:6 offset1:7
	ds_read2_b64 v[62:65], v44 offset0:8 offset1:9
	ds_read2_b64 v[66:69], v44 offset0:10 offset1:11
	ds_read2_b64 v[100:103], v40 offset0:8 offset1:9
	ds_read2_b64 v[104:107], v40 offset0:10 offset1:11
	ds_read2_b64 v[72:75], v44 offset0:12 offset1:13
	ds_read2_b64 v[92:95], v44 offset0:14 offset1:15
	ds_read2_b64 v[108:111], v40 offset0:12 offset1:13
	ds_read2_b64 v[112:115], v40 offset0:14 offset1:15
	s_waitcnt lgkmcnt(7)
	v_pk_add_f32 v[96:97], v[46:47], v[62:63]
	v_pk_add_f32 v[46:47], v[46:47], v[62:63] neg_lo:[0,1] neg_hi:[0,1]
	v_pk_add_f32 v[62:63], v[48:49], v[64:65]
	v_pk_add_f32 v[48:49], v[48:49], v[64:65] neg_lo:[0,1] neg_hi:[0,1]
	s_waitcnt lgkmcnt(3)
	v_pk_add_f32 v[98:99], v[56:57], v[74:75]
	v_pk_mul_f32 v[64:65], v[48:49], s[62:63]
	v_pk_add_f32 v[56:57], v[56:57], v[74:75] neg_lo:[0,1] neg_hi:[0,1]
	v_pk_fma_f32 v[48:49], v[48:49], s[50:51], v[64:65] op_sel:[0,0,1] op_sel_hi:[1,0,0]
	v_pk_add_f32 v[64:65], v[50:51], v[66:67]
	v_pk_add_f32 v[50:51], v[50:51], v[66:67] neg_lo:[0,1] neg_hi:[0,1]
	s_mov_b32 s80, s63
	v_pk_mul_f32 v[74:75], v[56:57], s[72:73]
	s_mov_b32 s78, s69
	v_pk_mul_f32 v[66:67], v[50:51], s[68:69]
	v_pk_fma_f32 v[56:57], v[56:57], s[80:81], v[74:75] op_sel:[0,0,1] op_sel_hi:[1,0,0] neg_lo:[1,0,0] neg_hi:[1,0,0]
	s_waitcnt lgkmcnt(2)
	v_pk_add_f32 v[74:75], v[58:59], v[92:93]
	v_pk_add_f32 v[58:59], v[58:59], v[92:93] neg_lo:[0,1] neg_hi:[0,1]
	v_pk_fma_f32 v[50:51], v[50:51], s[78:79], v[66:67] op_sel:[0,0,1] op_sel_hi:[1,0,0]
	v_pk_add_f32 v[66:67], v[52:53], v[68:69]
	v_pk_add_f32 v[52:53], v[52:53], v[68:69] neg_lo:[0,1] neg_hi:[0,1]
	v_pk_mul_f32 v[92:93], v[58:59], s[68:69]
	v_pk_mul_f32 v[68:69], v[52:53], s[72:73]
	v_pk_fma_f32 v[58:59], v[58:59], s[78:79], v[92:93] op_sel:[0,0,1] op_sel_hi:[1,0,0] neg_lo:[1,0,0] neg_hi:[1,0,0]
	v_pk_add_f32 v[92:93], v[60:61], v[94:95]
	v_pk_add_f32 v[60:61], v[60:61], v[94:95] neg_lo:[0,1] neg_hi:[0,1]
	v_pk_fma_f32 v[52:53], v[52:53], s[80:81], v[68:69] op_sel:[0,0,1] op_sel_hi:[1,0,0]
	v_pk_add_f32 v[68:69], v[54:55], v[72:73]
	v_pk_add_f32 v[54:55], v[54:55], v[72:73] neg_lo:[0,1] neg_hi:[0,1]
	v_pk_mul_f32 v[94:95], v[60:61], s[62:63]
	v_pk_add_f32 v[116:117], v[66:67], v[92:93]
	v_pk_add_f32 v[66:67], v[66:67], v[92:93] neg_lo:[0,1] neg_hi:[0,1]
	v_xor_b32_e32 v73, 0x80000000, v54
	v_pk_fma_f32 v[60:61], v[60:61], s[50:51], v[94:95] op_sel:[0,0,1] op_sel_hi:[1,0,0] neg_lo:[1,0,0] neg_hi:[1,0,0]
	v_pk_add_f32 v[94:95], v[96:97], v[68:69]
	v_pk_add_f32 v[68:69], v[96:97], v[68:69] neg_lo:[0,1] neg_hi:[0,1]
	v_pk_add_f32 v[96:97], v[62:63], v[98:99]
	v_pk_add_f32 v[62:63], v[62:63], v[98:99] neg_lo:[0,1] neg_hi:[0,1]
	v_pk_mul_f32 v[92:93], v[66:67], s[68:69]
	v_mov_b32_e32 v72, v55
	v_pk_mul_f32 v[98:99], v[62:63], s[68:69]
	v_pk_fma_f32 v[66:67], v[66:67], s[78:79], v[92:93] op_sel:[0,0,1] op_sel_hi:[1,0,0] neg_lo:[1,0,0] neg_hi:[1,0,0]
	v_pk_add_f32 v[54:55], v[46:47], v[72:73]
	v_pk_add_f32 v[46:47], v[46:47], v[72:73] neg_lo:[0,1] neg_hi:[0,1]
	v_pk_add_f32 v[72:73], v[48:49], v[56:57]
	v_pk_add_f32 v[48:49], v[48:49], v[56:57] neg_lo:[0,1] neg_hi:[0,1]
	v_pk_add_f32 v[92:93], v[52:53], v[60:61]
	v_pk_add_f32 v[52:53], v[52:53], v[60:61] neg_lo:[0,1] neg_hi:[0,1]
	v_pk_fma_f32 v[62:63], v[62:63], s[78:79], v[98:99] op_sel:[0,0,1] op_sel_hi:[1,0,0]
	v_pk_add_f32 v[98:99], v[64:65], v[74:75]
	v_pk_mul_f32 v[56:57], v[48:49], s[68:69]
	v_pk_mul_f32 v[60:61], v[52:53], s[68:69]
	v_pk_fma_f32 v[48:49], v[48:49], s[78:79], v[56:57] op_sel:[0,0,1] op_sel_hi:[1,0,0]
	v_pk_add_f32 v[56:57], v[50:51], v[58:59]
	v_pk_fma_f32 v[52:53], v[52:53], s[78:79], v[60:61] op_sel:[0,0,1] op_sel_hi:[1,0,0] neg_lo:[1,0,0] neg_hi:[1,0,0]
	v_pk_add_f32 v[60:61], v[94:95], v[98:99]
	v_pk_add_f32 v[118:119], v[94:95], v[98:99] neg_lo:[0,1] neg_hi:[0,1]
	v_pk_add_f32 v[94:95], v[96:97], v[116:117]
	v_pk_add_f32 v[116:117], v[96:97], v[116:117] neg_lo:[0,1] neg_hi:[0,1]
	v_pk_add_f32 v[128:129], v[54:55], v[56:57]
	v_pk_add_f32 v[54:55], v[54:55], v[56:57] neg_lo:[0,1] neg_hi:[0,1]
	v_pk_add_f32 v[56:57], v[72:73], v[92:93]
	v_pk_add_f32 v[92:93], v[72:73], v[92:93] neg_lo:[0,1] neg_hi:[0,1]
	v_pk_add_f32 v[96:97], v[78:79], v[102:103]
	v_pk_add_f32 v[78:79], v[78:79], v[102:103] neg_lo:[0,1] neg_hi:[0,1]
	v_xor_b32_e32 v131, 0x80000000, v92
	v_mov_b32_e32 v130, v93
	v_pk_add_f32 v[92:93], v[76:77], v[100:101]
	v_pk_add_f32 v[76:77], v[76:77], v[100:101] neg_lo:[0,1] neg_hi:[0,1]
	v_pk_mul_f32 v[100:101], v[78:79], s[62:63]
	v_bfrev_b32_e32 v40, v70
	v_pk_fma_f32 v[78:79], v[78:79], s[50:51], v[100:101] op_sel:[0,0,1] op_sel_hi:[1,0,0]
	v_pk_add_f32 v[100:101], v[80:81], v[104:105]
	v_pk_add_f32 v[80:81], v[80:81], v[104:105] neg_lo:[0,1] neg_hi:[0,1]
	v_lshrrev_b32_e32 v40, 23, v40
	v_pk_mul_f32 v[102:103], v[80:81], s[68:69]
	v_cvt_f32_u32_e32 v40, v40
	v_pk_fma_f32 v[80:81], v[80:81], s[78:79], v[102:103] op_sel:[0,0,1] op_sel_hi:[1,0,0]
	v_pk_add_f32 v[102:103], v[82:83], v[106:107]
	v_pk_add_f32 v[82:83], v[82:83], v[106:107] neg_lo:[0,1] neg_hi:[0,1]
	v_mul_f32_e32 v40, 0x38000000, v40
	v_pk_mul_f32 v[104:105], v[82:83], s[72:73]
	v_ashrrev_i32_e32 v71, 31, v70
	v_pk_fma_f32 v[82:83], v[82:83], s[80:81], v[104:105] op_sel:[0,0,1] op_sel_hi:[1,0,0]
	s_waitcnt lgkmcnt(1)
	v_pk_add_f32 v[104:105], v[84:85], v[108:109]
	v_pk_add_f32 v[106:107], v[84:85], v[108:109] neg_lo:[0,1] neg_hi:[0,1]
	v_pk_add_f32 v[74:75], v[64:65], v[74:75] neg_lo:[0,1] neg_hi:[0,1]
	v_pk_add_f32 v[84:85], v[86:87], v[110:111]
	v_pk_add_f32 v[86:87], v[86:87], v[110:111] neg_lo:[0,1] neg_hi:[0,1]
	v_cndmask_b32_e64 v40, v40, v154, s[10:11]
	v_pk_mul_f32 v[108:109], v[86:87], s[72:73]
	v_lshl_add_u64 v[44:45], v[70:71], 3, s[26:27]
	v_pk_fma_f32 v[86:87], v[86:87], s[80:81], v[108:109] op_sel:[0,0,1] op_sel_hi:[1,0,0] neg_lo:[1,0,0] neg_hi:[1,0,0]
	s_waitcnt lgkmcnt(0)
	v_pk_add_f32 v[108:109], v[88:89], v[112:113]
	v_pk_add_f32 v[88:89], v[88:89], v[112:113] neg_lo:[0,1] neg_hi:[0,1]
	v_pk_mul_f32 v[110:111], v[88:89], s[68:69]
	v_pk_add_f32 v[50:51], v[50:51], v[58:59] neg_lo:[0,1] neg_hi:[0,1]
	v_pk_fma_f32 v[88:89], v[88:89], s[78:79], v[110:111] op_sel:[0,0,1] op_sel_hi:[1,0,0] neg_lo:[1,0,0] neg_hi:[1,0,0]
	v_pk_add_f32 v[110:111], v[90:91], v[114:115]
	v_pk_add_f32 v[90:91], v[90:91], v[114:115] neg_lo:[0,1] neg_hi:[0,1]
	v_pk_mul_f32 v[112:113], v[90:91], s[62:63]
	v_pk_add_f32 v[124:125], v[62:63], v[66:67]
	v_pk_fma_f32 v[90:91], v[90:91], s[50:51], v[112:113] op_sel:[0,0,1] op_sel_hi:[1,0,0] neg_lo:[1,0,0] neg_hi:[1,0,0]
	v_pk_add_f32 v[112:113], v[92:93], v[104:105]
	v_pk_add_f32 v[92:93], v[92:93], v[104:105] neg_lo:[0,1] neg_hi:[0,1]
	v_pk_add_f32 v[104:105], v[96:97], v[84:85]
	v_pk_add_f32 v[84:85], v[96:97], v[84:85] neg_lo:[0,1] neg_hi:[0,1]
	v_pk_add_f32 v[66:67], v[62:63], v[66:67] neg_lo:[0,1] neg_hi:[0,1]
	v_pk_mul_f32 v[96:97], v[84:85], s[68:69]
	v_cos_f32_e32 v71, v40
	v_pk_fma_f32 v[84:85], v[84:85], s[78:79], v[96:97] op_sel:[0,0,1] op_sel_hi:[1,0,0]
	v_pk_add_f32 v[96:97], v[100:101], v[108:109]
	v_pk_add_f32 v[108:109], v[100:101], v[108:109] neg_lo:[0,1] neg_hi:[0,1]
	v_cmp_ne_u32_e32 vcc, 0, v70
	s_nop 0
	s_nop 0
	v_pk_add_f32 v[100:101], v[102:103], v[110:111]
	v_pk_add_f32 v[102:103], v[102:103], v[110:111] neg_lo:[0,1] neg_hi:[0,1]
	v_xor_b32_e32 v59, 0x80000000, v50
	v_pk_mul_f32 v[110:111], v[102:103], s[68:69]
	v_pk_add_f32 v[64:65], v[68:69], v[74:75] op_sel:[0,1] op_sel_hi:[1,0] neg_hi:[0,1]
	v_pk_fma_f32 v[102:103], v[102:103], s[78:79], v[110:111] op_sel:[0,0,1] op_sel_hi:[1,0,0] neg_lo:[1,0,0] neg_hi:[1,0,0]
	v_pk_add_f32 v[110:111], v[76:77], v[106:107] op_sel:[0,1] op_sel_hi:[1,0] neg_hi:[0,1]
	v_pk_add_f32 v[76:77], v[76:77], v[106:107] op_sel:[0,1] op_sel_hi:[1,0] neg_lo:[0,1]
	v_pk_add_f32 v[106:107], v[78:79], v[86:87]
	v_pk_add_f32 v[78:79], v[78:79], v[86:87] neg_lo:[0,1] neg_hi:[0,1]
	v_pk_add_f32 v[122:123], v[68:69], v[74:75] op_sel:[0,1] op_sel_hi:[1,0] neg_lo:[0,1]
	v_pk_mul_f32 v[86:87], v[78:79], s[68:69]
	v_xor_b32_e32 v127, 0x80000000, v66
	v_pk_fma_f32 v[78:79], v[78:79], s[78:79], v[86:87] op_sel:[0,0,1] op_sel_hi:[1,0,0]
	v_pk_add_f32 v[86:87], v[80:81], v[88:89]
	v_pk_add_f32 v[88:89], v[80:81], v[88:89] neg_lo:[0,1] neg_hi:[0,1]
	v_mov_b32_e32 v58, v51
	v_pk_add_f32 v[80:81], v[82:83], v[90:91]
	v_pk_add_f32 v[82:83], v[82:83], v[90:91] neg_lo:[0,1] neg_hi:[0,1]
	v_mov_b32_e32 v126, v67
	v_pk_mul_f32 v[90:91], v[82:83], s[68:69]
	v_sin_f32_e32 v70, v40
	v_pk_fma_f32 v[82:83], v[82:83], s[78:79], v[90:91] op_sel:[0,0,1] op_sel_hi:[1,0,0] neg_lo:[1,0,0] neg_hi:[1,0,0]
	v_pk_add_f32 v[132:133], v[46:47], v[58:59]
	v_pk_add_f32 v[156:157], v[46:47], v[58:59] neg_lo:[0,1] neg_hi:[0,1]
	v_pk_add_f32 v[46:47], v[48:49], v[52:53]
	v_pk_add_f32 v[52:53], v[48:49], v[52:53] neg_lo:[0,1] neg_hi:[0,1]
	v_pk_add_f32 v[98:99], v[60:61], v[94:95]
	v_pk_add_f32 v[94:95], v[60:61], v[94:95] neg_lo:[0,1] neg_hi:[0,1]
	v_pk_add_f32 v[74:75], v[118:119], v[116:117] op_sel:[0,1] op_sel_hi:[1,0] neg_hi:[0,1]
	v_pk_add_f32 v[68:69], v[118:119], v[116:117] op_sel:[0,1] op_sel_hi:[1,0] neg_lo:[0,1]
	v_pk_add_f32 v[72:73], v[64:65], v[124:125]
	v_pk_add_f32 v[62:63], v[64:65], v[124:125] neg_lo:[0,1] neg_hi:[0,1]
	v_pk_add_f32 v[60:61], v[122:123], v[126:127]
	v_pk_add_f32 v[66:67], v[122:123], v[126:127] neg_lo:[0,1] neg_hi:[0,1]
	v_pk_add_f32 v[114:115], v[112:113], v[96:97]
	v_pk_add_f32 v[96:97], v[112:113], v[96:97] neg_lo:[0,1] neg_hi:[0,1]
	v_pk_add_f32 v[112:113], v[104:105], v[100:101]
	v_pk_add_f32 v[100:101], v[104:105], v[100:101] neg_lo:[0,1] neg_hi:[0,1]
	v_pk_add_f32 v[104:105], v[92:93], v[108:109] op_sel:[0,1] op_sel_hi:[1,0] neg_hi:[0,1]
	v_pk_add_f32 v[92:93], v[92:93], v[108:109] op_sel:[0,1] op_sel_hi:[1,0] neg_lo:[0,1]
	v_pk_add_f32 v[108:109], v[84:85], v[102:103]
	v_pk_add_f32 v[102:103], v[84:85], v[102:103] neg_lo:[0,1] neg_hi:[0,1]
	v_pk_add_f32 v[118:119], v[106:107], v[80:81]
	v_pk_add_f32 v[106:107], v[106:107], v[80:81] neg_lo:[0,1] neg_hi:[0,1]
	v_pk_add_f32 v[122:123], v[76:77], v[88:89] op_sel:[0,1] op_sel_hi:[1,0] neg_hi:[0,1]
	v_pk_add_f32 v[124:125], v[76:77], v[88:89] op_sel:[0,1] op_sel_hi:[1,0] neg_lo:[0,1]
	v_pk_add_f32 v[76:77], v[78:79], v[82:83] neg_lo:[0,1] neg_hi:[0,1]
	v_xor_b32_e32 v159, 0x80000000, v52
	v_pk_add_f32 v[64:65], v[128:129], v[56:57]
	v_pk_add_f32 v[50:51], v[128:129], v[56:57] neg_lo:[0,1] neg_hi:[0,1]
	v_mov_b32_e32 v158, v53
	v_pk_add_f32 v[116:117], v[110:111], v[86:87]
	v_pk_add_f32 v[110:111], v[110:111], v[86:87] neg_lo:[0,1] neg_hi:[0,1]
	v_pk_add_f32 v[126:127], v[78:79], v[82:83]
	v_xor_b32_e32 v129, 0x80000000, v76
	v_mov_b32_e32 v128, v77
	v_pk_add_f32 v[56:57], v[54:55], v[130:131]
	v_pk_add_f32 v[58:59], v[54:55], v[130:131] neg_lo:[0,1] neg_hi:[0,1]
	v_pk_add_f32 v[54:55], v[132:133], v[46:47]
	v_pk_add_f32 v[48:49], v[132:133], v[46:47] neg_lo:[0,1] neg_hi:[0,1]
	v_pk_add_f32 v[46:47], v[156:157], v[158:159]
	v_pk_add_f32 v[52:53], v[156:157], v[158:159] neg_lo:[0,1] neg_hi:[0,1]
	v_pk_add_f32 v[90:91], v[114:115], v[112:113]
	v_pk_add_f32 v[86:87], v[114:115], v[112:113] neg_lo:[0,1] neg_hi:[0,1]
	v_pk_add_f32 v[80:81], v[96:97], v[100:101] op_sel:[0,1] op_sel_hi:[1,0] neg_hi:[0,1]
	v_pk_add_f32 v[84:85], v[96:97], v[100:101] op_sel:[0,1] op_sel_hi:[1,0] neg_lo:[0,1]
	v_pk_add_f32 v[76:77], v[104:105], v[108:109]
	v_pk_add_f32 v[78:79], v[104:105], v[108:109] neg_lo:[0,1] neg_hi:[0,1]
	v_pk_add_f32 v[82:83], v[92:93], v[102:103] op_sel:[0,1] op_sel_hi:[1,0] neg_hi:[0,1]
	v_pk_add_f32 v[88:89], v[92:93], v[102:103] op_sel:[0,1] op_sel_hi:[1,0] neg_lo:[0,1]
	v_pk_add_f32 v[92:93], v[116:117], v[118:119]
	v_pk_add_f32 v[100:101], v[116:117], v[118:119] neg_lo:[0,1] neg_hi:[0,1]
	v_pk_add_f32 v[102:103], v[110:111], v[106:107] op_sel:[0,1] op_sel_hi:[1,0] neg_hi:[0,1]
	v_pk_add_f32 v[106:107], v[110:111], v[106:107] op_sel:[0,1] op_sel_hi:[1,0] neg_lo:[0,1]
	v_pk_add_f32 v[108:109], v[122:123], v[126:127]
	v_pk_add_f32 v[110:111], v[122:123], v[126:127] neg_lo:[0,1] neg_hi:[0,1]
	v_pk_add_f32 v[112:113], v[124:125], v[128:129]
	v_pk_add_f32 v[118:119], v[124:125], v[128:129] neg_lo:[0,1] neg_hi:[0,1]
	v_mul_f32_e32 v40, 0x3f3504f3, v71
	v_mul_f32_e32 v104, 0xbec3ef15, v71
	v_mul_f32_e32 v96, 0xbf6c835e, v71
	s_and_saveexec_b64 s[10:11], vcc
	s_xor_b64 s[10:11], exec, s[10:11]
	s_cbranch_execz .LBB0_277
	v_pk_add_f32 v[114:115], v[98:99], v[118:119]
	v_pk_add_f32 v[98:99], v[98:99], v[118:119] neg_lo:[0,1] neg_hi:[0,1]
	v_mul_f32_e32 v42, 0.5, v114
	v_pk_fma_f32 v[116:117], v[70:71], 0, v[70:71] op_sel:[0,0,1] op_sel_hi:[1,0,0] neg_lo:[1,0,0] neg_hi:[1,0,0]
	v_pk_fma_f32 v[118:119], v[70:71], 0, v[70:71] op_sel:[0,0,1] op_sel_hi:[1,0,0]
	v_mov_b32_e32 v114, v98
	v_mov_b32_e32 v117, v119
	v_pk_mul_f32 v[114:115], v[114:115], s[74:75]
	s_mov_b32 s78, s63
	v_pk_mul_f32 v[118:119], v[116:117], v[114:115] op_sel:[0,1] op_sel_hi:[1,0]
	v_pk_mul_f32 v[114:115], v[116:117], v[114:115]
	s_mov_b32 s79, s50
	v_sub_f32_e32 v97, v114, v115
	v_fma_mixlo_f16 v105, v99, s75, v97
	v_fma_f32 v97, v99, 0.5, -v97
	v_cvt_f16_f32_sdwa v97, -v97 dst_sel:WORD_1 dst_unused:UNUSED_PAD src0_sel:DWORD
	v_pk_add_f32 v[98:99], v[118:119], v[118:119] op_sel:[0,1] op_sel_hi:[0,1]
	s_waitcnt vmcnt(0)
	v_pk_add_f32 v[114:115], v[42:43], v[98:99]
	v_pk_add_f32 v[98:99], v[42:43], v[98:99] op_sel_hi:[0,1] neg_lo:[0,1] neg_hi:[0,1]
	v_cvt_pk_f16_f32 v42, v114, v99
	v_lshlrev_b32_e32 v98, 16, v105
	v_or_b32_sdwa v99, v97, v42 dst_sel:DWORD dst_unused:UNUSED_PAD src0_sel:DWORD src1_sel:WORD_1
	v_or_b32_sdwa v98, v98, v42 dst_sel:DWORD dst_unused:UNUSED_PAD src0_sel:DWORD src1_sel:WORD_0
	global_store_dwordx2 v[44:45], v[98:99], off
	v_pk_add_f32 v[98:99], v[94:95], v[112:113]
	v_pk_add_f32 v[94:95], v[94:95], v[112:113] neg_lo:[0,1] neg_hi:[0,1]
	v_mul_f32_e32 v42, 0.5, v98
	v_mov_b32_e32 v98, v71
	v_mov_b32_e32 v112, v71
	v_mov_b32_e32 v113, v70
	v_pk_fma_f32 v[114:115], v[70:71], 0, v[112:113] op_sel_hi:[1,0,1] neg_lo:[0,0,1] neg_hi:[0,0,1]
	v_pk_fma_f32 v[116:117], v[70:71], 0, v[98:99] op_sel_hi:[1,0,1]
	v_mov_b32_e32 v98, v94
	v_pk_mov_b32 v[114:115], v[114:115], v[116:117] op_sel:[1,0]
	v_pk_mul_f32 v[98:99], v[98:99], s[74:75]
	s_mov_b32 s51, s63
	v_pk_mul_f32 v[116:117], v[114:115], v[98:99] op_sel:[0,1] op_sel_hi:[1,0]
	v_pk_mul_f32 v[98:99], v[114:115], v[98:99]
	v_pk_add_f32 v[114:115], v[74:75], v[110:111]
	v_sub_f32_e32 v94, v98, v99
	v_fma_mixlo_f16 v97, v95, s75, v94
	v_fma_f32 v94, v95, 0.5, -v94
	v_cvt_f16_f32_sdwa v105, -v94 dst_sel:WORD_1 dst_unused:UNUSED_PAD src0_sel:DWORD
	v_pk_add_f32 v[94:95], v[116:117], v[116:117] op_sel:[0,1] op_sel_hi:[0,1]
	v_pk_add_f32 v[98:99], v[42:43], v[94:95]
	v_pk_add_f32 v[94:95], v[42:43], v[94:95] op_sel_hi:[0,1] neg_lo:[0,1] neg_hi:[0,1]
	v_cvt_pk_f16_f32 v42, v98, v95
	v_lshlrev_b32_e32 v94, 16, v97
	v_add_co_u32_e32 v98, vcc, s31, v44
	v_or_b32_sdwa v95, v105, v42 dst_sel:DWORD dst_unused:UNUSED_PAD src0_sel:DWORD src1_sel:WORD_1
	v_or_b32_sdwa v94, v94, v42 dst_sel:DWORD dst_unused:UNUSED_PAD src0_sel:DWORD src1_sel:WORD_0
	v_addc_co_u32_e32 v99, vcc, 0, v45, vcc
	global_store_dwordx2 v[98:99], v[94:95], off offset:-4096
	v_pk_mul_f32 v[94:95], v[112:113], s[68:69]
	v_pk_add_f32 v[74:75], v[74:75], v[110:111] neg_lo:[0,1] neg_hi:[0,1]
	v_mul_f32_e32 v42, 0.5, v114
	v_pk_add_f32 v[110:111], v[40:41], v[94:95] op_sel:[0,1] op_sel_hi:[0,1] neg_lo:[0,1] neg_hi:[0,1]
	v_pk_fma_f32 v[116:117], v[112:113], s[68:69], v[40:41] op_sel_hi:[1,1,0]
	v_mov_b32_e32 v114, v74
	v_mov_b32_e32 v111, v117
	v_pk_mul_f32 v[114:115], v[114:115], s[74:75]
	s_mov_b32 s45, s41
	v_pk_mul_f32 v[116:117], v[110:111], v[114:115] op_sel:[0,1] op_sel_hi:[1,0]
	v_pk_mul_f32 v[114:115], v[110:111], v[114:115]
	s_mov_b32 s65, s67
	v_sub_f32_e32 v40, v114, v115
	v_fma_mixlo_f16 v97, v75, s75, v40
	v_fma_f32 v40, v75, 0.5, -v40
	v_cvt_f16_f32_sdwa v40, -v40 dst_sel:WORD_1 dst_unused:UNUSED_PAD src0_sel:DWORD
	v_pk_add_f32 v[74:75], v[116:117], v[116:117] op_sel:[0,1] op_sel_hi:[0,1]
	v_pk_add_f32 v[114:115], v[42:43], v[74:75]
	v_pk_add_f32 v[74:75], v[42:43], v[74:75] op_sel_hi:[0,1] neg_lo:[0,1] neg_hi:[0,1]
	v_cvt_pk_f16_f32 v42, v114, v75
	v_lshlrev_b32_e32 v74, 16, v97
	v_or_b32_sdwa v75, v40, v42 dst_sel:DWORD dst_unused:UNUSED_PAD src0_sel:DWORD src1_sel:WORD_1
	v_or_b32_sdwa v74, v74, v42 dst_sel:DWORD dst_unused:UNUSED_PAD src0_sel:DWORD src1_sel:WORD_0
	global_store_dwordx2 v[98:99], v[74:75], off
	v_pk_fma_f32 v[74:75], v[112:113], s[68:69], v[94:95] op_sel:[0,0,1] op_sel_hi:[1,1,0] neg_lo:[0,0,1] neg_hi:[0,0,1]
	v_pk_add_f32 v[94:95], v[68:69], v[108:109]
	v_pk_add_f32 v[68:69], v[68:69], v[108:109] neg_lo:[0,1] neg_hi:[0,1]
	v_mul_f32_e32 v40, 0.5, v94
	v_mov_b32_e32 v94, v68
	v_pk_mul_f32 v[94:95], v[94:95], s[74:75]
	v_mov_b32_e32 v75, v110
	v_mov_b32_e32 v111, v74
	v_pk_mul_f32 v[74:75], v[74:75], v[94:95]
	v_pk_mul_f32 v[98:99], v[110:111], v[94:95]
	v_sub_f32_e32 v42, v74, v75
	v_fma_mixlo_f16 v94, v69, s75, v42
	v_fma_f32 v42, v69, 0.5, -v42
	v_cvt_f16_f32_sdwa v42, -v42 dst_sel:WORD_1 dst_unused:UNUSED_PAD src0_sel:DWORD
	v_pk_add_f32 v[68:69], v[98:99], v[98:99] op_sel:[1,0] op_sel_hi:[1,0]
	s_nop 0
	v_pk_add_f32 v[74:75], v[40:41], v[68:69]
	v_pk_add_f32 v[68:69], v[40:41], v[68:69] op_sel_hi:[0,1] neg_lo:[0,1] neg_hi:[0,1]
	v_cvt_pk_f16_f32 v40, v74, v69
	v_lshlrev_b32_e32 v68, 16, v94
	v_add_co_u32_e32 v74, vcc, s30, v44
	v_or_b32_sdwa v69, v42, v40 dst_sel:DWORD dst_unused:UNUSED_PAD src0_sel:DWORD src1_sel:WORD_1
	v_or_b32_sdwa v68, v68, v40 dst_sel:DWORD dst_unused:UNUSED_PAD src0_sel:DWORD src1_sel:WORD_0
	v_addc_co_u32_e32 v75, vcc, 0, v45, vcc
	global_store_dwordx2 v[74:75], v[68:69], off offset:-4096
	v_mov_b32_e32 v42, v71
	v_pk_mul_f32 v[68:69], v[70:71], s[78:79] op_sel_hi:[0,1]
	v_pk_add_f32 v[94:95], v[72:73], v[106:107]
	v_pk_add_f32 v[72:73], v[72:73], v[106:107] neg_lo:[0,1] neg_hi:[0,1]
	v_mul_f32_e32 v40, 0.5, v94
	v_pk_fma_f32 v[98:99], v[42:43], s[50:51], v[68:69] op_sel_hi:[0,1,1] neg_lo:[0,0,1] neg_hi:[0,0,1]
	v_pk_fma_f32 v[106:107], v[42:43], s[50:51], v[68:69] op_sel_hi:[0,1,1]
	v_mov_b32_e32 v94, v72
	v_mov_b32_e32 v108, v98
	v_mov_b32_e32 v109, v107
	v_pk_mul_f32 v[94:95], v[94:95], s[74:75]
	s_mov_b32 s78, s41
	v_pk_mul_f32 v[110:111], v[108:109], v[94:95] op_sel:[0,1] op_sel_hi:[1,0]
	v_pk_mul_f32 v[94:95], v[108:109], v[94:95]
	s_mov_b32 s79, s44
	v_sub_f32_e32 v72, v94, v95
	v_fma_mixlo_f16 v97, v73, s75, v72
	v_fma_f32 v72, v73, 0.5, -v72
	v_cvt_f16_f32_sdwa v105, -v72 dst_sel:WORD_1 dst_unused:UNUSED_PAD src0_sel:DWORD
	v_pk_add_f32 v[72:73], v[110:111], v[110:111] op_sel:[0,1] op_sel_hi:[0,1]
	v_pk_add_f32 v[94:95], v[40:41], v[72:73]
	v_pk_add_f32 v[72:73], v[40:41], v[72:73] op_sel_hi:[0,1] neg_lo:[0,1] neg_hi:[0,1]
	v_cvt_pk_f16_f32 v40, v94, v73
	v_lshlrev_b32_e32 v72, 16, v97
	v_or_b32_sdwa v73, v105, v40 dst_sel:DWORD dst_unused:UNUSED_PAD src0_sel:DWORD src1_sel:WORD_1
	v_or_b32_sdwa v72, v72, v40 dst_sel:DWORD dst_unused:UNUSED_PAD src0_sel:DWORD src1_sel:WORD_0
	global_store_dwordx2 v[74:75], v[72:73], off
	v_pk_add_f32 v[72:73], v[62:63], v[102:103]
	v_sub_f32_e32 v75, v63, v103
	v_mov_b32_e32 v105, v62
	v_pk_mov_b32 v[62:63], v[68:69], v[102:103] op_sel:[1,0]
	v_mul_f32_e32 v40, 0.5, v73
	v_pk_add_f32 v[62:63], v[104:105], v[62:63] neg_lo:[0,1] neg_hi:[0,1]
	v_mul_f32_e32 v74, 0.5, v72
	v_pk_mul_f32 v[94:95], v[62:63], v[40:41]
	s_nop 0
	v_mul_f32_e32 v62, v62, v95
	v_fma_f32 v40, -v98, v40, v62
	v_fma_mixlo_f16 v69, v75, s75, v40
	v_fma_f32 v40, v75, 0.5, -v40
	v_pk_fma_f32 v[102:103], v[98:99], v[94:95], v[94:95] op_sel:[0,1,0] op_sel_hi:[1,0,1]
	v_cvt_f16_f32_sdwa v40, -v40 dst_sel:WORD_1 dst_unused:UNUSED_PAD src0_sel:DWORD
	v_pk_add_f32 v[62:63], v[74:75], v[102:103]
	v_lshlrev_b32_e32 v69, 16, v69
	v_fma_f32 v63, v72, 0.5, -v102
	v_cvt_pk_f16_f32 v62, v62, v63
	v_add_co_u32_e32 v72, vcc, s33, v44
	v_or_b32_sdwa v63, v40, v62 dst_sel:DWORD dst_unused:UNUSED_PAD src0_sel:DWORD src1_sel:WORD_1
	v_or_b32_sdwa v62, v69, v62 dst_sel:DWORD dst_unused:UNUSED_PAD src0_sel:DWORD src1_sel:WORD_0
	v_addc_co_u32_e32 v73, vcc, 0, v45, vcc
	global_store_dwordx2 v[72:73], v[62:63], off offset:-4096
	v_pk_add_f32 v[62:63], v[100:101], v[60:61]
	v_pk_add_f32 v[60:61], v[60:61], v[100:101] neg_lo:[0,1] neg_hi:[0,1]
	v_mul_f32_e32 v40, 0.5, v62
	v_mov_b32_e32 v62, v60
	v_pk_mov_b32 v[74:75], v[98:99], v[106:107] op_sel:[1,0]
	v_pk_mul_f32 v[62:63], v[62:63], s[74:75]
	s_nop 0
	v_pk_mul_f32 v[94:95], v[74:75], v[62:63] op_sel:[0,1] op_sel_hi:[1,0]
	v_pk_mul_f32 v[62:63], v[74:75], v[62:63]
	s_nop 0
	v_sub_f32_e32 v60, v62, v63
	v_fma_mixlo_f16 v69, v61, s75, v60
	v_fma_f32 v60, v61, 0.5, -v60
	v_cvt_f16_f32_sdwa v97, -v60 dst_sel:WORD_1 dst_unused:UNUSED_PAD src0_sel:DWORD
	v_pk_add_f32 v[60:61], v[94:95], v[94:95] op_sel:[0,1] op_sel_hi:[0,1]
	v_pk_add_f32 v[62:63], v[40:41], v[60:61]
	v_pk_add_f32 v[60:61], v[40:41], v[60:61] op_sel_hi:[0,1] neg_lo:[0,1] neg_hi:[0,1]
	v_cvt_pk_f16_f32 v40, v62, v61
	v_lshlrev_b32_e32 v60, 16, v69
	v_or_b32_sdwa v61, v97, v40 dst_sel:DWORD dst_unused:UNUSED_PAD src0_sel:DWORD src1_sel:WORD_1
	v_or_b32_sdwa v60, v60, v40 dst_sel:DWORD dst_unused:UNUSED_PAD src0_sel:DWORD src1_sel:WORD_0
	global_store_dwordx2 v[72:73], v[60:61], off
	v_pk_add_f32 v[60:61], v[92:93], v[66:67]
	v_mov_b32_e32 v97, v66
	v_mov_b32_e32 v69, v92
	v_sub_f32_e32 v63, v67, v93
	v_mul_f32_e32 v40, 0.5, v61
	v_pk_add_f32 v[66:67], v[96:97], v[68:69] neg_lo:[0,1] neg_hi:[0,1]
	v_mul_f32_e32 v62, 0.5, v60
	v_pk_mul_f32 v[68:69], v[66:67], v[40:41]
	s_nop 0
	v_mul_f32_e32 v61, v66, v69
	v_fma_f32 v40, -v99, v40, v61
	v_fma_mixlo_f16 v61, v63, s75, v40
	v_fma_f32 v40, v63, 0.5, -v40
	v_cvt_f16_f32_sdwa v40, -v40 dst_sel:WORD_1 dst_unused:UNUSED_PAD src0_sel:DWORD
	v_pk_fma_f32 v[72:73], v[74:75], v[68:69], v[68:69] op_sel:[0,1,0] op_sel_hi:[1,0,1]
	v_pk_add_f32 v[66:67], v[64:65], v[88:89]
	v_pk_add_f32 v[62:63], v[62:63], v[72:73]
	v_fma_f32 v60, v60, 0.5, -v72
	v_cvt_pk_f16_f32 v60, v62, v60
	v_lshlrev_b32_e32 v62, 16, v61
	v_or_b32_sdwa v61, v40, v60 dst_sel:DWORD dst_unused:UNUSED_PAD src0_sel:DWORD src1_sel:WORD_1
	v_or_b32_sdwa v60, v62, v60 dst_sel:DWORD dst_unused:UNUSED_PAD src0_sel:DWORD src1_sel:WORD_0
	v_add_co_u32_e32 v62, vcc, s34, v44
	v_pk_add_f32 v[64:65], v[64:65], v[88:89] neg_lo:[0,1] neg_hi:[0,1]
	s_nop 0
	v_addc_co_u32_e32 v63, vcc, 0, v45, vcc
	global_store_dwordx2 v[62:63], v[60:61], off offset:-4096
	v_pk_mul_f32 v[60:61], v[70:71], s[44:45] op_sel_hi:[0,1]
	v_mul_f32_e32 v40, 0.5, v66
	v_pk_fma_f32 v[68:69], v[42:43], s[78:79], v[60:61] op_sel_hi:[0,1,1] neg_lo:[0,0,1] neg_hi:[0,0,1]
	v_pk_fma_f32 v[72:73], v[42:43], s[78:79], v[60:61] op_sel_hi:[0,1,1]
	v_mov_b32_e32 v66, v64
	v_mov_b32_e32 v74, v68
	v_mov_b32_e32 v75, v73
	v_pk_mul_f32 v[66:67], v[66:67], s[74:75]
	s_mov_b32 s78, s67
	v_pk_mul_f32 v[88:89], v[74:75], v[66:67] op_sel:[0,1] op_sel_hi:[1,0]
	v_pk_mul_f32 v[66:67], v[74:75], v[66:67]
	s_mov_b32 s79, s64
	v_sub_f32_e32 v64, v66, v67
	v_fma_mixlo_f16 v74, v65, s75, v64
	v_fma_f32 v64, v65, 0.5, -v64
	v_cvt_f16_f32_sdwa v75, -v64 dst_sel:WORD_1 dst_unused:UNUSED_PAD src0_sel:DWORD
	v_pk_add_f32 v[64:65], v[88:89], v[88:89] op_sel:[0,1] op_sel_hi:[0,1]
	v_pk_add_f32 v[66:67], v[40:41], v[64:65]
	v_pk_add_f32 v[64:65], v[40:41], v[64:65] op_sel_hi:[0,1] neg_lo:[0,1] neg_hi:[0,1]
	v_cvt_pk_f16_f32 v40, v66, v65
	v_lshlrev_b32_e32 v64, 16, v74
	v_or_b32_sdwa v65, v75, v40 dst_sel:DWORD dst_unused:UNUSED_PAD src0_sel:DWORD src1_sel:WORD_1
	v_or_b32_sdwa v64, v64, v40 dst_sel:DWORD dst_unused:UNUSED_PAD src0_sel:DWORD src1_sel:WORD_0
	global_store_dwordx2 v[62:63], v[64:65], off
	v_mul_f32_e32 v62, 0xbe47c5c2, v71
	v_pk_add_f32 v[64:65], v[50:51], v[82:83]
	v_sub_f32_e32 v67, v51, v83
	v_mov_b32_e32 v63, v50
	v_pk_mov_b32 v[50:51], v[60:61], v[82:83] op_sel:[1,0]
	v_mul_f32_e32 v40, 0.5, v65
	v_pk_add_f32 v[50:51], v[62:63], v[50:51] neg_lo:[0,1] neg_hi:[0,1]
	v_mul_f32_e32 v66, 0.5, v64
	v_pk_mul_f32 v[62:63], v[50:51], v[40:41]
	s_nop 0
	v_mul_f32_e32 v50, v50, v63
	v_fma_f32 v40, -v68, v40, v50
	v_fma_mixlo_f16 v61, v67, s75, v40
	v_fma_f32 v40, v67, 0.5, -v40
	v_pk_fma_f32 v[74:75], v[68:69], v[62:63], v[62:63] op_sel:[0,1,0] op_sel_hi:[1,0,1]
	v_cvt_f16_f32_sdwa v40, -v40 dst_sel:WORD_1 dst_unused:UNUSED_PAD src0_sel:DWORD
	v_pk_add_f32 v[50:51], v[66:67], v[74:75]
	v_lshlrev_b32_e32 v61, 16, v61
	v_fma_f32 v51, v64, 0.5, -v74
	v_cvt_pk_f16_f32 v50, v50, v51
	v_add_co_u32_e32 v62, vcc, s35, v44
	v_or_b32_sdwa v51, v40, v50 dst_sel:DWORD dst_unused:UNUSED_PAD src0_sel:DWORD src1_sel:WORD_1
	v_or_b32_sdwa v50, v61, v50 dst_sel:DWORD dst_unused:UNUSED_PAD src0_sel:DWORD src1_sel:WORD_0
	v_addc_co_u32_e32 v63, vcc, 0, v45, vcc
	global_store_dwordx2 v[62:63], v[50:51], off offset:-4096
	v_pk_mul_f32 v[50:51], v[70:71], s[64:65] op_sel_hi:[0,1]
	v_pk_add_f32 v[64:65], v[78:79], v[56:57]
	v_pk_add_f32 v[56:57], v[56:57], v[78:79] neg_lo:[0,1] neg_hi:[0,1]
	v_mul_f32_e32 v40, 0.5, v64
	v_pk_fma_f32 v[66:67], v[42:43], s[78:79], v[50:51] op_sel_hi:[0,1,1] neg_lo:[0,0,1] neg_hi:[0,0,1]
	v_pk_fma_f32 v[74:75], v[42:43], s[78:79], v[50:51] op_sel_hi:[0,1,1]
	v_mov_b32_e32 v64, v56
	v_mov_b32_e32 v78, v66
	v_mov_b32_e32 v79, v75
	v_pk_mul_f32 v[64:65], v[64:65], s[74:75]
	s_nop 0
	v_pk_mul_f32 v[82:83], v[78:79], v[64:65] op_sel:[0,1] op_sel_hi:[1,0]
	v_pk_mul_f32 v[64:65], v[78:79], v[64:65]
	s_nop 0
	v_sub_f32_e32 v42, v64, v65
	v_fma_mixlo_f16 v61, v57, s75, v42
	v_fma_f32 v42, v57, 0.5, -v42
	v_cvt_f16_f32_sdwa v42, -v42 dst_sel:WORD_1 dst_unused:UNUSED_PAD src0_sel:DWORD
	v_pk_add_f32 v[56:57], v[82:83], v[82:83] op_sel:[0,1] op_sel_hi:[0,1]
	v_pk_add_f32 v[64:65], v[40:41], v[56:57]
	v_pk_add_f32 v[56:57], v[40:41], v[56:57] op_sel_hi:[0,1] neg_lo:[0,1] neg_hi:[0,1]
	v_cvt_pk_f16_f32 v40, v64, v57
	v_lshlrev_b32_e32 v56, 16, v61
	v_or_b32_sdwa v57, v42, v40 dst_sel:DWORD dst_unused:UNUSED_PAD src0_sel:DWORD src1_sel:WORD_1
	v_or_b32_sdwa v56, v56, v40 dst_sel:DWORD dst_unused:UNUSED_PAD src0_sel:DWORD src1_sel:WORD_0
	global_store_dwordx2 v[62:63], v[56:57], off
	v_mul_f32_e32 v56, 0xbf54db31, v71
	v_pk_add_f32 v[62:63], v[76:77], v[58:59]
	v_sub_f32_e32 v61, v59, v77
	v_mov_b32_e32 v57, v58
	v_pk_mov_b32 v[58:59], v[50:51], v[76:77] op_sel:[1,0]
	v_mul_f32_e32 v40, 0.5, v63
	v_pk_add_f32 v[56:57], v[56:57], v[58:59] neg_lo:[0,1] neg_hi:[0,1]
	v_mul_f32_e32 v42, 0.5, v62
	v_pk_mul_f32 v[58:59], v[56:57], v[40:41]
	s_nop 0
	v_mul_f32_e32 v51, v56, v59
	v_fma_f32 v40, -v66, v40, v51
	v_fma_mixlo_f16 v51, v61, s75, v40
	v_fma_f32 v40, v61, 0.5, -v40
	v_cvt_f16_f32_sdwa v40, -v40 dst_sel:WORD_1 dst_unused:UNUSED_PAD src0_sel:DWORD
	v_pk_fma_f32 v[64:65], v[66:67], v[58:59], v[58:59] op_sel:[0,1,0] op_sel_hi:[1,0,1]
	v_lshlrev_b32_e32 v51, 16, v51
	v_pk_add_f32 v[56:57], v[42:43], v[64:65]
	v_fma_f32 v42, v62, 0.5, -v64
	v_cvt_pk_f16_f32 v42, v56, v42
	v_add_co_u32_e32 v58, vcc, s39, v44
	v_or_b32_sdwa v57, v40, v42 dst_sel:DWORD dst_unused:UNUSED_PAD src0_sel:DWORD src1_sel:WORD_1
	v_or_b32_sdwa v56, v51, v42 dst_sel:DWORD dst_unused:UNUSED_PAD src0_sel:DWORD src1_sel:WORD_0
	v_addc_co_u32_e32 v59, vcc, 0, v45, vcc
	global_store_dwordx2 v[58:59], v[56:57], off offset:-4096
	v_pk_add_f32 v[56:57], v[84:85], v[54:55]
	v_pk_add_f32 v[54:55], v[54:55], v[84:85] neg_lo:[0,1] neg_hi:[0,1]
	v_mul_f32_e32 v40, 0.5, v56
	v_mov_b32_e32 v56, v54
	v_pk_mov_b32 v[62:63], v[66:67], v[74:75] op_sel:[1,0]
	v_pk_mul_f32 v[56:57], v[56:57], s[74:75]
	s_nop 0
	v_pk_mul_f32 v[64:65], v[62:63], v[56:57] op_sel:[0,1] op_sel_hi:[1,0]
	v_pk_mul_f32 v[56:57], v[62:63], v[56:57]
	s_nop 0
	v_sub_f32_e32 v42, v56, v57
	v_fma_mixlo_f16 v51, v55, s75, v42
	v_fma_f32 v42, v55, 0.5, -v42
	v_cvt_f16_f32_sdwa v42, -v42 dst_sel:WORD_1 dst_unused:UNUSED_PAD src0_sel:DWORD
	v_pk_add_f32 v[54:55], v[64:65], v[64:65] op_sel:[0,1] op_sel_hi:[0,1]
	v_pk_add_f32 v[56:57], v[40:41], v[54:55]
	v_pk_add_f32 v[54:55], v[40:41], v[54:55] op_sel_hi:[0,1] neg_lo:[0,1] neg_hi:[0,1]
	v_cvt_pk_f16_f32 v40, v56, v55
	v_lshlrev_b32_e32 v51, 16, v51
	v_or_b32_sdwa v55, v42, v40 dst_sel:DWORD dst_unused:UNUSED_PAD src0_sel:DWORD src1_sel:WORD_1
	v_or_b32_sdwa v54, v51, v40 dst_sel:DWORD dst_unused:UNUSED_PAD src0_sel:DWORD src1_sel:WORD_0
	global_store_dwordx2 v[58:59], v[54:55], off
	v_mul_f32_e32 v54, 0xbf0e39da, v71
	v_pk_add_f32 v[56:57], v[80:81], v[48:49]
	v_mov_b32_e32 v55, v48
	v_mov_b32_e32 v51, v80
	v_sub_f32_e32 v58, v49, v81
	v_mul_f32_e32 v40, 0.5, v57
	v_pk_add_f32 v[48:49], v[54:55], v[50:51] neg_lo:[0,1] neg_hi:[0,1]
	v_mul_f32_e32 v42, 0.5, v56
	v_pk_mul_f32 v[50:51], v[48:49], v[40:41]
	s_nop 0
	v_mul_f32_e32 v48, v48, v51
	v_fma_f32 v40, -v67, v40, v48
	v_pk_fma_f32 v[54:55], v[62:63], v[50:51], v[50:51] op_sel:[0,1,0] op_sel_hi:[1,0,1]
	v_fma_mixlo_f16 v50, v58, s75, v40
	v_fma_f32 v40, v58, 0.5, -v40
	v_cvt_f16_f32_sdwa v40, -v40 dst_sel:WORD_1 dst_unused:UNUSED_PAD src0_sel:DWORD
	v_pk_add_f32 v[48:49], v[42:43], v[54:55]
	v_fma_f32 v42, v56, 0.5, -v54
	v_cvt_pk_f16_f32 v42, v48, v42
	v_lshlrev_b32_e32 v48, 16, v50
	v_add_co_u32_e32 v50, vcc, s43, v44
	v_or_b32_sdwa v49, v40, v42 dst_sel:DWORD dst_unused:UNUSED_PAD src0_sel:DWORD src1_sel:WORD_1
	v_or_b32_sdwa v48, v48, v42 dst_sel:DWORD dst_unused:UNUSED_PAD src0_sel:DWORD src1_sel:WORD_0
	v_addc_co_u32_e32 v51, vcc, 0, v45, vcc
	global_store_dwordx2 v[50:51], v[48:49], off offset:-4096
	v_pk_add_f32 v[48:49], v[86:87], v[46:47]
	v_pk_add_f32 v[46:47], v[46:47], v[86:87] neg_lo:[0,1] neg_hi:[0,1]
	v_mul_f32_e32 v40, 0.5, v48
	v_mov_b32_e32 v48, v46
	v_pk_mov_b32 v[54:55], v[68:69], v[72:73] op_sel:[1,0]
	v_pk_mul_f32 v[48:49], v[48:49], s[74:75]
	s_nop 0
	v_pk_mul_f32 v[56:57], v[54:55], v[48:49] op_sel:[0,1] op_sel_hi:[1,0]
	v_pk_mul_f32 v[48:49], v[54:55], v[48:49]
	s_nop 0
	v_sub_f32_e32 v42, v48, v49
	v_fma_mixlo_f16 v54, v47, s75, v42
	v_fma_f32 v42, v47, 0.5, -v42
	v_pk_add_f32 v[46:47], v[56:57], v[56:57] op_sel:[0,1] op_sel_hi:[0,1]
	v_pk_add_f32 v[48:49], v[40:41], v[46:47]
	v_pk_add_f32 v[46:47], v[40:41], v[46:47] op_sel_hi:[0,1] neg_lo:[0,1] neg_hi:[0,1]
	v_cvt_pk_f16_f32 v56, v48, v47
	v_pk_add_f32 v[46:47], v[52:53], v[90:91]
	v_pk_add_f32 v[48:49], v[52:53], v[90:91] neg_lo:[0,1] neg_hi:[0,1]
	v_mov_b32_e32 v52, v46
	v_mov_b32_e32 v53, v49
	v_mov_b32_e32 v49, v47
	v_pk_mul_f32 v[46:47], v[48:49], s[74:75]
	v_fma_f32 v40, v71, s40, -v60
	v_pk_mul_f32 v[48:49], v[68:69], v[46:47] op_sel:[1,0]
	v_lshlrev_b32_e32 v57, 16, v54
	v_pk_fma_f32 v[54:55], v[40:41], v[46:47], v[48:49] op_sel:[0,1,0] op_sel_hi:[1,0,1]
	v_pk_fma_f32 v[46:47], v[40:41], v[46:47], v[48:49] op_sel:[0,1,0] op_sel_hi:[0,0,1] neg_lo:[0,0,1] neg_hi:[0,0,1]
	v_mov_b32_e32 v55, v47
	v_pk_fma_f32 v[46:47], v[52:53], 0.5, v[54:55] op_sel_hi:[1,0,1]
	v_cvt_f16_f32_sdwa v42, -v42 dst_sel:WORD_1 dst_unused:UNUSED_PAD src0_sel:DWORD
	v_cvt_f16_f32_e32 v40, v46
	v_cvt_f16_f32_sdwa v48, v47 dst_sel:WORD_1 dst_unused:UNUSED_PAD src0_sel:DWORD
	v_or_b32_sdwa v46, v57, v56 dst_sel:DWORD dst_unused:UNUSED_PAD src0_sel:DWORD src1_sel:WORD_0
	v_or_b32_sdwa v47, v42, v56 dst_sel:DWORD dst_unused:UNUSED_PAD src0_sel:DWORD src1_sel:WORD_1
	v_pk_fma_f32 v[116:117], v[52:53], 0.5, v[54:55] op_sel_hi:[1,0,1] neg_lo:[0,0,1] neg_hi:[0,0,1]
	v_or_b32_e32 v114, v48, v40
	global_store_dwordx2 v[50:51], v[46:47], off

.LBB0_428:
	s_ashr_i32 s17, s16, 31
	s_lshl_b64 s[6:7], s[16:17], 2
	s_add_u32 s6, s48, s6
	s_addc_u32 s7, s49, s7
	global_load_dwordx2 v[40:41], v151, s[6:7]
	s_waitcnt vmcnt(0)
	v_cvt_f32_f16_e32 v36, v10
	v_cvt_f32_f16_sdwa v42, v10 dst_sel:DWORD dst_unused:UNUSED_PAD src0_sel:WORD_1
	v_cvt_f32_f16_e32 v43, v11
	v_cvt_f32_f16_e32 v45, v12
	v_cvt_f32_f16_sdwa v46, v12 dst_sel:DWORD dst_unused:UNUSED_PAD src0_sel:WORD_1
	v_cvt_f32_f16_e32 v47, v13
	v_cvt_f32_f16_sdwa v12, v13 dst_sel:DWORD dst_unused:UNUSED_PAD src0_sel:WORD_1
	v_cvt_f32_f16_e32 v13, v30
	v_cvt_f32_f16_sdwa v50, v26 dst_sel:DWORD dst_unused:UNUSED_PAD src0_sel:WORD_1
	v_cvt_f32_f16_e32 v51, v27
	v_cvt_f32_f16_sdwa v44, v11 dst_sel:DWORD dst_unused:UNUSED_PAD src0_sel:WORD_1
	v_cvt_f32_f16_sdwa v48, v30 dst_sel:DWORD dst_unused:UNUSED_PAD src0_sel:WORD_1
	v_cvt_f32_f16_e32 v49, v31
	v_cvt_f32_f16_sdwa v30, v31 dst_sel:DWORD dst_unused:UNUSED_PAD src0_sel:WORD_1
	v_cvt_f32_f16_e32 v31, v32
	v_cvt_f32_f16_sdwa v11, v33 dst_sel:DWORD dst_unused:UNUSED_PAD src0_sel:WORD_1
	v_cvt_f32_f16_sdwa v32, v32 dst_sel:DWORD dst_unused:UNUSED_PAD src0_sel:WORD_1
	v_cvt_f32_f16_e32 v33, v33
	v_cvt_f32_f16_sdwa v26, v27 dst_sel:DWORD dst_unused:UNUSED_PAD src0_sel:WORD_1
	v_cvt_f32_f16_e32 v27, v28
	v_cvt_f32_f16_sdwa v52, v28 dst_sel:DWORD dst_unused:UNUSED_PAD src0_sel:WORD_1
	v_cvt_f32_f16_e32 v53, v29
	v_cvt_f32_f16_e32 v28, v22
	v_cvt_f32_f16_sdwa v54, v22 dst_sel:DWORD dst_unused:UNUSED_PAD src0_sel:WORD_1
	v_cvt_f32_f16_e32 v55, v23
	v_cvt_f32_f16_sdwa v22, v23 dst_sel:DWORD dst_unused:UNUSED_PAD src0_sel:WORD_1
	v_cvt_f32_f16_e32 v23, v24
	v_cvt_f32_f16_sdwa v56, v24 dst_sel:DWORD dst_unused:UNUSED_PAD src0_sel:WORD_1
	v_cvt_f32_f16_e32 v57, v25
	v_cvt_f32_f16_sdwa v29, v29 dst_sel:DWORD dst_unused:UNUSED_PAD src0_sel:WORD_1
	v_cvt_f32_f16_sdwa v25, v25 dst_sel:DWORD dst_unused:UNUSED_PAD src0_sel:WORD_1
	v_cvt_f32_f16_e32 v24, v38
	v_cvt_f32_f16_sdwa v60, v19 dst_sel:DWORD dst_unused:UNUSED_PAD src0_sel:WORD_1
	v_cvt_f32_f16_e32 v61, v20
	v_cvt_f32_f16_e32 v38, v18
	v_cvt_f32_f16_e32 v59, v19
	v_mul_f32_e32 v19, 0x3b800000, v36
	v_pk_mul_f32 v[42:43], v[42:43], s[24:25] op_sel_hi:[1,0]
	v_pk_mul_f32 v[12:13], v[12:13], s[24:25] op_sel_hi:[1,0]
	v_pk_mul_f32 v[50:51], v[50:51], s[24:25] op_sel_hi:[1,0]
	v_pk_mul_f32 v[44:45], v[44:45], s[24:25] op_sel_hi:[1,0]
	v_pk_mul_f32 v[46:47], v[46:47], s[24:25] op_sel_hi:[1,0]
	v_pk_mul_f32 v[48:49], v[48:49], s[24:25] op_sel_hi:[1,0]
	v_pk_mul_f32 v[30:31], v[30:31], s[24:25] op_sel_hi:[1,0]
	v_mul_f32_e32 v11, 0x3b800000, v11
	v_pk_mul_f32 v[32:33], v[32:33], s[24:25] op_sel_hi:[1,0]
	v_pk_mul_f32 v[26:27], v[26:27], s[24:25] op_sel_hi:[1,0]
	v_pk_mul_f32 v[52:53], v[52:53], s[24:25] op_sel_hi:[1,0]
	v_pk_mul_f32 v[54:55], v[54:55], s[24:25] op_sel_hi:[1,0]
	v_pk_mul_f32 v[22:23], v[22:23], s[24:25] op_sel_hi:[1,0]
	v_pk_mul_f32 v[56:57], v[56:57], s[24:25] op_sel_hi:[1,0]
	ds_write2_b32 v131, v42, v43 offset0:1 offset1:2
	ds_write2_b32 v131, v44, v45 offset0:3 offset1:4
	ds_write2_b32 v131, v46, v47 offset0:5 offset1:6
	ds_write2_b32 v131, v12, v13 offset0:7 offset1:8
	ds_write2_b32 v131, v48, v49 offset0:9 offset1:10
	ds_write2_b32 v131, v30, v31 offset0:11 offset1:12
	ds_write2_b32 v131, v32, v33 offset0:13 offset1:14
	v_pk_mov_b32 v[12:13], v[50:51], v[50:51] op_sel:[1,0]
	v_pk_mul_f32 v[28:29], v[28:29], s[24:25] op_sel_hi:[1,0]
	v_pk_mul_f32 v[24:25], v[24:25], s[24:25] op_sel_hi:[1,0]
	v_pk_mov_b32 v[26:27], v[26:27], v[26:27] op_sel:[1,0]
	v_pk_mov_b32 v[30:31], v[52:53], v[52:53] op_sel:[1,0]
	v_pk_mov_b32 v[32:33], v[54:55], v[54:55] op_sel:[1,0]
	v_pk_mov_b32 v[22:23], v[22:23], v[22:23] op_sel:[1,0]
	v_pk_mov_b32 v[42:43], v[56:57], v[56:57] op_sel:[1,0]
	v_cvt_f32_f16_sdwa v58, v18 dst_sel:DWORD dst_unused:UNUSED_PAD src0_sel:WORD_1
	v_mul_f32_e32 v36, 0x3b800000, v38
	s_mov_b32 s6, s65
	v_pk_mul_f32 v[58:59], v[58:59], s[24:25] op_sel_hi:[1,0]
	v_fma_mix_f32 v10, v10, s24, v40 op_sel_hi:[1,0,0]
	s_nop 0
	v_cndmask_b32_e64 v10, v19, v10, s[4:5]
	ds_write2_b32 v131, v10, v11 offset1:15
	ds_write_b64 v132, v[12:13] offset:32824
	ds_write_b64 v133, v[26:27] offset:32824
	ds_write_b64 v134, v[30:31] offset:32824
	ds_write_b64 v135, v[28:29] offset:32824
	ds_write_b64 v136, v[32:33] offset:32824
	ds_write_b64 v137, v[22:23] offset:32824
	ds_write_b64 v138, v[42:43] offset:32824
	ds_write_b64 v139, v[24:25] offset:32824
	v_cvt_f32_f16_sdwa v10, v20 dst_sel:DWORD dst_unused:UNUSED_PAD src0_sel:WORD_1
	v_cvt_f32_f16_e32 v11, v21
	v_pk_mul_f32 v[12:13], v[60:61], s[24:25] op_sel_hi:[1,0]
	v_fma_mix_f32 v18, v18, s24, v41 op_sel_hi:[1,0,0]
	ds_write2_b32 v140, v12, v13 offset0:3 offset1:4
	v_cvt_f32_f16_sdwa v12, v21 dst_sel:DWORD dst_unused:UNUSED_PAD src0_sel:WORD_1
	v_cvt_f32_f16_e32 v13, v14
	v_cndmask_b32_e64 v36, v36, v18, s[4:5]
	v_cvt_f32_f16_sdwa v18, v14 dst_sel:DWORD dst_unused:UNUSED_PAD src0_sel:WORD_1
	v_cvt_f32_f16_e32 v19, v15
	v_pk_mul_f32 v[10:11], v[10:11], s[24:25] op_sel_hi:[1,0]
	ds_write2_b32 v140, v10, v11 offset0:5 offset1:6
	v_pk_mul_f32 v[10:11], v[12:13], s[24:25] op_sel_hi:[1,0]
	ds_write2_b32 v140, v10, v11 offset0:7 offset1:8
	v_pk_mul_f32 v[10:11], v[18:19], s[24:25] op_sel_hi:[1,0]
	ds_write2_b32 v140, v10, v11 offset0:9 offset1:10
	v_cvt_f32_f16_sdwa v10, v15 dst_sel:DWORD dst_unused:UNUSED_PAD src0_sel:WORD_1
	v_cvt_f32_f16_e32 v11, v16
	v_cvt_f32_f16_sdwa v12, v16 dst_sel:DWORD dst_unused:UNUSED_PAD src0_sel:WORD_1
	v_cvt_f32_f16_e32 v13, v17
	v_cvt_f32_f16_sdwa v14, v17 dst_sel:DWORD dst_unused:UNUSED_PAD src0_sel:WORD_1
	v_pk_mul_f32 v[10:11], v[10:11], s[24:25] op_sel_hi:[1,0]
	ds_write2_b32 v140, v10, v11 offset0:11 offset1:12
	v_pk_mul_f32 v[10:11], v[12:13], s[24:25] op_sel_hi:[1,0]
	ds_write2_b32 v140, v10, v11 offset0:13 offset1:14
	v_cvt_f32_f16_sdwa v10, v6 dst_sel:DWORD dst_unused:UNUSED_PAD src0_sel:WORD_1
	v_cvt_f32_f16_e32 v11, v7
	v_cvt_f32_f16_sdwa v6, v7 dst_sel:DWORD dst_unused:UNUSED_PAD src0_sel:WORD_1
	v_cvt_f32_f16_e32 v7, v8
	v_mul_f32_e32 v14, 0x3b800000, v14
	v_pk_mul_f32 v[10:11], v[10:11], s[24:25] op_sel_hi:[1,0]
	ds_write2_b32 v140, v58, v59 offset0:1 offset1:2
	v_pk_mov_b32 v[10:11], v[10:11], v[10:11] op_sel:[1,0]
	ds_write2_b32 v140, v36, v14 offset1:15
	ds_write_b64 v141, v[10:11] offset:32824
	v_cvt_f32_f16_sdwa v10, v8 dst_sel:DWORD dst_unused:UNUSED_PAD src0_sel:WORD_1
	v_cvt_f32_f16_e32 v11, v9
	v_pk_mul_f32 v[6:7], v[6:7], s[24:25] op_sel_hi:[1,0]
	s_nop 0
	v_pk_mov_b32 v[6:7], v[6:7], v[6:7] op_sel:[1,0]
	ds_write_b64 v142, v[6:7] offset:32824
	v_cvt_f32_f16_sdwa v7, v9 dst_sel:DWORD dst_unused:UNUSED_PAD src0_sel:WORD_1
	v_pk_mul_f32 v[8:9], v[10:11], s[24:25] op_sel_hi:[1,0]
	v_cvt_f32_f16_e32 v6, v2
	v_pk_mov_b32 v[8:9], v[8:9], v[8:9] op_sel:[1,0]
	ds_write_b64 v143, v[8:9] offset:32824
	v_cvt_f32_f16_sdwa v8, v2 dst_sel:DWORD dst_unused:UNUSED_PAD src0_sel:WORD_1
	v_cvt_f32_f16_e32 v9, v3
	v_cvt_f32_f16_sdwa v2, v3 dst_sel:DWORD dst_unused:UNUSED_PAD src0_sel:WORD_1
	v_cvt_f32_f16_e32 v3, v4
	v_pk_mul_f32 v[6:7], v[6:7], s[24:25] op_sel_hi:[1,0]
	ds_write_b64 v144, v[6:7] offset:32824
	v_pk_mul_f32 v[6:7], v[8:9], s[24:25] op_sel_hi:[1,0]
	v_pk_mul_f32 v[2:3], v[2:3], s[24:25] op_sel_hi:[1,0]
	v_pk_mov_b32 v[6:7], v[6:7], v[6:7] op_sel:[1,0]
	ds_write_b64 v145, v[6:7] offset:32824
	v_pk_mov_b32 v[2:3], v[2:3], v[2:3] op_sel:[1,0]
	v_cvt_f32_f16_sdwa v6, v4 dst_sel:DWORD dst_unused:UNUSED_PAD src0_sel:WORD_1
	v_cvt_f32_f16_e32 v7, v5
	ds_write_b64 v148, v[2:3] offset:32824
	v_cvt_f32_f16_sdwa v3, v5 dst_sel:DWORD dst_unused:UNUSED_PAD src0_sel:WORD_1
	v_cvt_f32_f16_e32 v2, v39
	v_pk_mul_f32 v[4:5], v[6:7], s[24:25] op_sel_hi:[1,0]
	v_pk_mul_f32 v[2:3], v[2:3], s[24:25] op_sel_hi:[1,0]
	v_pk_mov_b32 v[4:5], v[4:5], v[4:5] op_sel:[1,0]
	ds_write_b64 v149, v[4:5] offset:32824
	ds_write_b64 v150, v[2:3] offset:32824
	v_mov_b32_e32 v2, v130
	s_waitcnt lgkmcnt(0)
	s_barrier
	s_nop 0
	v_and_b32_e32 v3, 0xff, v2
	v_lshlrev_b32_e32 v4, 5, v2
	v_and_or_b32 v3, v4, s29, v3
	v_ashrrev_i32_e32 v4, 5, v3
	v_lshlrev_b32_e32 v3, 3, v3
	v_lshlrev_b32_e32 v6, 3, v4
	v_add3_u32 v36, 0, v3, v6
	ds_read_b64 v[154:155], v36
	ds_read_b64 v[156:157], v36 offset:2112
	ds_read_b64 v[158:159], v36 offset:4224
	ds_read_b64 v[160:161], v36 offset:6336
	ds_read_b64 v[162:163], v36 offset:8448
	ds_read_b64 v[164:165], v36 offset:10560
	ds_read_b64 v[166:167], v36 offset:12672
	ds_read_b64 v[168:169], v36 offset:14784
	ds_read_b64 v[170:171], v36 offset:16896
	ds_read_b64 v[172:173], v36 offset:19008
	ds_read_b64 v[174:175], v36 offset:21120
	ds_read_b64 v[176:177], v36 offset:23232
	ds_read_b64 v[178:179], v36 offset:25344
	ds_read_b64 v[180:181], v36 offset:27456
	ds_read_b64 v[182:183], v36 offset:29568
	ds_read_b64 v[184:185], v36 offset:31680
	ds_read_b64 v[186:187], v36 offset:33792
	ds_read_b64 v[188:189], v36 offset:35904
	ds_read_b64 v[190:191], v36 offset:38016
	ds_read_b64 v[192:193], v36 offset:40128
	ds_read_b64 v[194:195], v36 offset:42240
	ds_read_b64 v[196:197], v36 offset:44352
	ds_read_b64 v[198:199], v36 offset:46464
	ds_read_b64 v[204:205], v36 offset:48576
	ds_read_b64 v[206:207], v36 offset:50688
	ds_read_b64 v[208:209], v36 offset:52800
	ds_read_b64 v[210:211], v36 offset:54912
	ds_read_b64 v[212:213], v36 offset:57024
	ds_read_b64 v[214:215], v36 offset:59136
	ds_read_b64 v[216:217], v36 offset:61248
	ds_read_b64 v[218:219], v36 offset:63360
	ds_read_b64 v[220:221], v36 offset:65472
	s_waitcnt lgkmcnt(14)
	v_pk_add_f32 v[222:223], v[154:155], v[186:187]
	v_pk_add_f32 v[154:155], v[154:155], v[186:187] neg_lo:[0,1] neg_hi:[0,1]
	v_pk_add_f32 v[186:187], v[156:157], v[188:189]
	v_pk_add_f32 v[156:157], v[156:157], v[188:189] neg_lo:[0,1] neg_hi:[0,1]
	v_cvt_f32_ubyte0_e32 v2, v2
	v_pk_mul_f32 v[188:189], v[156:157], s[40:41]
	v_mul_f32_e32 v5, 0x39000000, v2
	v_pk_fma_f32 v[156:157], v[156:157], s[36:37], v[188:189] op_sel:[0,0,1] op_sel_hi:[1,0,0]
	s_waitcnt lgkmcnt(13)
	v_pk_add_f32 v[188:189], v[158:159], v[190:191]
	v_pk_add_f32 v[158:159], v[158:159], v[190:191] neg_lo:[0,1] neg_hi:[0,1]
	v_sin_f32_e32 v2, v5
	v_pk_mul_f32 v[190:191], v[158:159], s[44:45]
	v_cos_f32_e32 v4, v5
	v_pk_fma_f32 v[158:159], v[158:159], s[42:43], v[190:191] op_sel:[0,0,1] op_sel_hi:[1,0,0]
	s_waitcnt lgkmcnt(12)
	v_pk_add_f32 v[190:191], v[160:161], v[192:193]
	v_pk_add_f32 v[160:161], v[160:161], v[192:193] neg_lo:[0,1] neg_hi:[0,1]
	v_xor_b32_e32 v5, 0x80000000, v2
	v_pk_mul_f32 v[192:193], v[160:161], s[62:63]
	v_mov_b32_e32 v3, v5
	v_pk_fma_f32 v[160:161], v[160:161], s[50:51], v[192:193] op_sel:[0,0,1] op_sel_hi:[1,0,0]
	s_waitcnt lgkmcnt(11)
	v_pk_add_f32 v[192:193], v[162:163], v[194:195]
	v_pk_add_f32 v[162:163], v[162:163], v[194:195] neg_lo:[0,1] neg_hi:[0,1]
	v_pk_mul_f32 v[6:7], v[4:5], v[2:3] op_sel:[1,0] op_sel_hi:[0,1]
	v_pk_mul_f32 v[194:195], v[162:163], s[68:69]
	v_pk_fma_f32 v[6:7], v[4:5], v[4:5], v[6:7] op_sel_hi:[1,0,1]
	v_pk_fma_f32 v[162:163], v[162:163], s[64:65], v[194:195] op_sel:[0,0,1] op_sel_hi:[1,0,0]
	s_waitcnt lgkmcnt(10)
	v_pk_add_f32 v[194:195], v[164:165], v[196:197]
	v_pk_add_f32 v[164:165], v[164:165], v[196:197] neg_lo:[0,1] neg_hi:[0,1]
	v_xor_b32_e32 v12, 0x80000000, v7
	v_pk_mul_f32 v[196:197], v[164:165], s[70:71]
	v_mov_b32_e32 v13, v7
	v_pk_fma_f32 v[164:165], v[164:165], s[46:47], v[196:197] op_sel:[0,0,1] op_sel_hi:[1,0,0]
	s_waitcnt lgkmcnt(9)
	v_pk_add_f32 v[196:197], v[166:167], v[198:199]
	v_pk_add_f32 v[166:167], v[166:167], v[198:199] neg_lo:[0,1] neg_hi:[0,1]
	v_pk_mul_f32 v[10:11], v[6:7], v[12:13] op_sel:[1,0] op_sel_hi:[0,1]
	v_pk_mul_f32 v[198:199], v[166:167], s[76:77]
	v_pk_fma_f32 v[10:11], v[6:7], v[6:7], v[10:11] op_sel_hi:[1,0,1]
	v_pk_fma_f32 v[166:167], v[166:167], s[72:73], v[198:199] op_sel:[0,0,1] op_sel_hi:[1,0,0]
	s_waitcnt lgkmcnt(8)
	v_pk_add_f32 v[198:199], v[168:169], v[204:205]
	v_pk_add_f32 v[168:169], v[168:169], v[204:205] neg_lo:[0,1] neg_hi:[0,1]
	v_xor_b32_e32 v14, 0x80000000, v11
	v_pk_mul_f32 v[204:205], v[168:169], s[26:27]
	v_mov_b32_e32 v15, v11
	v_pk_fma_f32 v[168:169], v[168:169], s[38:39], v[204:205] op_sel:[0,0,1] op_sel_hi:[1,0,0]
	s_waitcnt lgkmcnt(7)
	v_pk_add_f32 v[204:205], v[170:171], v[206:207]
	v_pk_add_f32 v[206:207], v[170:171], v[206:207] neg_lo:[0,1] neg_hi:[0,1]
	v_pk_mul_f32 v[26:27], v[10:11], v[14:15] op_sel:[1,0] op_sel_hi:[0,1]
	s_waitcnt lgkmcnt(6)
	v_pk_add_f32 v[170:171], v[172:173], v[208:209]
	v_pk_add_f32 v[172:173], v[172:173], v[208:209] neg_lo:[0,1] neg_hi:[0,1]
	v_pk_fma_f32 v[26:27], v[10:11], v[10:11], v[26:27] op_sel_hi:[1,0,1]
	v_pk_mul_f32 v[208:209], v[172:173], s[26:27]
	v_pk_mul_f32 v[46:47], v[14:15], v[26:27] op_sel:[0,1] op_sel_hi:[1,0]
	v_pk_fma_f32 v[172:173], v[172:173], s[38:39], v[208:209] op_sel:[0,0,1] op_sel_hi:[1,0,0] neg_lo:[1,0,0] neg_hi:[1,0,0]
	s_waitcnt lgkmcnt(5)
	v_pk_add_f32 v[208:209], v[174:175], v[210:211]
	v_pk_add_f32 v[174:175], v[174:175], v[210:211] neg_lo:[0,1] neg_hi:[0,1]
	v_pk_fma_f32 v[46:47], v[10:11], v[26:27], v[46:47] op_sel_hi:[0,1,1]
	v_pk_mul_f32 v[210:211], v[174:175], s[76:77]
	v_pk_mul_f32 v[62:63], v[14:15], v[46:47] op_sel:[0,1] op_sel_hi:[1,0]
	v_pk_fma_f32 v[174:175], v[174:175], s[72:73], v[210:211] op_sel:[0,0,1] op_sel_hi:[1,0,0] neg_lo:[1,0,0] neg_hi:[1,0,0]
	s_waitcnt lgkmcnt(4)
	v_pk_add_f32 v[210:211], v[176:177], v[212:213]
	v_pk_add_f32 v[176:177], v[176:177], v[212:213] neg_lo:[0,1] neg_hi:[0,1]
	v_pk_fma_f32 v[62:63], v[10:11], v[46:47], v[62:63] op_sel_hi:[0,1,1]
	v_pk_mul_f32 v[212:213], v[176:177], s[70:71]
	v_pk_mul_f32 v[78:79], v[14:15], v[62:63] op_sel:[0,1] op_sel_hi:[1,0]
	v_pk_fma_f32 v[176:177], v[176:177], s[46:47], v[212:213] op_sel:[0,0,1] op_sel_hi:[1,0,0] neg_lo:[1,0,0] neg_hi:[1,0,0]
	s_waitcnt lgkmcnt(3)
	v_pk_add_f32 v[212:213], v[178:179], v[214:215]
	v_pk_add_f32 v[178:179], v[178:179], v[214:215] neg_lo:[0,1] neg_hi:[0,1]
	v_pk_fma_f32 v[78:79], v[10:11], v[62:63], v[78:79] op_sel_hi:[0,1,1]
	v_pk_mul_f32 v[214:215], v[178:179], s[68:69]
	v_pk_mul_f32 v[94:95], v[14:15], v[78:79] op_sel:[0,1] op_sel_hi:[1,0]
	v_pk_fma_f32 v[178:179], v[178:179], s[64:65], v[214:215] op_sel:[0,0,1] op_sel_hi:[1,0,0] neg_lo:[1,0,0] neg_hi:[1,0,0]
	s_waitcnt lgkmcnt(2)
	v_pk_add_f32 v[214:215], v[180:181], v[216:217]
	v_pk_add_f32 v[180:181], v[180:181], v[216:217] neg_lo:[0,1] neg_hi:[0,1]
	v_pk_fma_f32 v[94:95], v[10:11], v[78:79], v[94:95] op_sel_hi:[0,1,1]
	v_pk_mul_f32 v[216:217], v[180:181], s[62:63]
	v_pk_mul_f32 v[110:111], v[14:15], v[94:95] op_sel:[0,1] op_sel_hi:[1,0]
	v_pk_fma_f32 v[180:181], v[180:181], s[50:51], v[216:217] op_sel:[0,0,1] op_sel_hi:[1,0,0] neg_lo:[1,0,0] neg_hi:[1,0,0]
	s_waitcnt lgkmcnt(1)
	v_pk_add_f32 v[216:217], v[182:183], v[218:219]
	v_pk_add_f32 v[182:183], v[182:183], v[218:219] neg_lo:[0,1] neg_hi:[0,1]
	v_pk_mul_f32 v[8:9], v[2:3], v[6:7] op_sel:[0,1] op_sel_hi:[1,0]
	v_pk_mul_f32 v[218:219], v[182:183], s[44:45]
	v_pk_fma_f32 v[110:111], v[10:11], v[94:95], v[110:111] op_sel_hi:[0,1,1]
	v_pk_fma_f32 v[182:183], v[182:183], s[42:43], v[218:219] op_sel:[0,0,1] op_sel_hi:[1,0,0] neg_lo:[1,0,0] neg_hi:[1,0,0]
	s_waitcnt lgkmcnt(0)
	v_pk_add_f32 v[218:219], v[184:185], v[220:221]
	v_pk_add_f32 v[184:185], v[184:185], v[220:221] neg_lo:[0,1] neg_hi:[0,1]
	v_pk_fma_f32 v[8:9], v[4:5], v[6:7], v[8:9] op_sel_hi:[0,1,1]
	v_pk_mul_f32 v[220:221], v[184:185], s[40:41]
	v_pk_mul_f32 v[16:17], v[2:3], v[10:11] op_sel:[0,1] op_sel_hi:[1,0]
	v_pk_fma_f32 v[184:185], v[184:185], s[36:37], v[220:221] op_sel:[0,0,1] op_sel_hi:[1,0,0] neg_lo:[1,0,0] neg_hi:[1,0,0]
	v_pk_add_f32 v[220:221], v[222:223], v[204:205]
	v_pk_add_f32 v[204:205], v[222:223], v[204:205] neg_lo:[0,1] neg_hi:[0,1]
	v_pk_add_f32 v[222:223], v[186:187], v[170:171]
	v_pk_add_f32 v[170:171], v[186:187], v[170:171] neg_lo:[0,1] neg_hi:[0,1]
	v_pk_mul_f32 v[30:31], v[2:3], v[26:27] op_sel:[0,1] op_sel_hi:[1,0]
	v_pk_mul_f32 v[186:187], v[170:171], s[44:45]
	v_pk_mul_f32 v[50:51], v[2:3], v[46:47] op_sel:[0,1] op_sel_hi:[1,0]
	v_pk_fma_f32 v[170:171], v[170:171], s[42:43], v[186:187] op_sel:[0,0,1] op_sel_hi:[1,0,0]
	v_pk_add_f32 v[186:187], v[188:189], v[208:209]
	v_pk_add_f32 v[188:189], v[188:189], v[208:209] neg_lo:[0,1] neg_hi:[0,1]
	v_pk_mul_f32 v[66:67], v[2:3], v[62:63] op_sel:[0,1] op_sel_hi:[1,0]
	v_pk_mul_f32 v[208:209], v[188:189], s[68:69]
	v_pk_mul_f32 v[82:83], v[2:3], v[78:79] op_sel:[0,1] op_sel_hi:[1,0]
	v_pk_fma_f32 v[188:189], v[188:189], s[64:65], v[208:209] op_sel:[0,0,1] op_sel_hi:[1,0,0]
	v_pk_add_f32 v[208:209], v[190:191], v[210:211]
	v_pk_add_f32 v[190:191], v[190:191], v[210:211] neg_lo:[0,1] neg_hi:[0,1]
	v_pk_mul_f32 v[98:99], v[2:3], v[94:95] op_sel:[0,1] op_sel_hi:[1,0]
	v_pk_mul_f32 v[210:211], v[190:191], s[76:77]
	v_pk_mul_f32 v[114:115], v[2:3], v[110:111] op_sel:[0,1] op_sel_hi:[1,0]
	v_pk_fma_f32 v[190:191], v[190:191], s[72:73], v[210:211] op_sel:[0,0,1] op_sel_hi:[1,0,0]
	v_pk_add_f32 v[210:211], v[192:193], v[212:213]
	v_pk_add_f32 v[212:213], v[192:193], v[212:213] neg_lo:[0,1] neg_hi:[0,1]
	v_xor_b32_e32 v20, 0x80000000, v9
	v_pk_add_f32 v[192:193], v[194:195], v[214:215]
	v_pk_add_f32 v[194:195], v[194:195], v[214:215] neg_lo:[0,1] neg_hi:[0,1]
	v_mov_b32_e32 v21, v9
	v_pk_mul_f32 v[214:215], v[194:195], s[76:77]
	v_pk_fma_f32 v[16:17], v[4:5], v[10:11], v[16:17] op_sel_hi:[0,1,1]
	v_pk_fma_f32 v[194:195], v[194:195], s[72:73], v[214:215] op_sel:[0,0,1] op_sel_hi:[1,0,0] neg_lo:[1,0,0] neg_hi:[1,0,0]
	v_pk_add_f32 v[214:215], v[196:197], v[216:217]
	v_pk_add_f32 v[196:197], v[196:197], v[216:217] neg_lo:[0,1] neg_hi:[0,1]
	v_pk_mul_f32 v[18:19], v[12:13], v[10:11] op_sel:[0,1] op_sel_hi:[1,0]
	v_pk_mul_f32 v[216:217], v[196:197], s[68:69]
	v_pk_fma_f32 v[30:31], v[4:5], v[26:27], v[30:31] op_sel_hi:[0,1,1]
	v_pk_fma_f32 v[196:197], v[196:197], s[64:65], v[216:217] op_sel:[0,0,1] op_sel_hi:[1,0,0] neg_lo:[1,0,0] neg_hi:[1,0,0]
	v_pk_add_f32 v[216:217], v[198:199], v[218:219]
	v_pk_add_f32 v[198:199], v[198:199], v[218:219] neg_lo:[0,1] neg_hi:[0,1]
	v_pk_mul_f32 v[38:39], v[12:13], v[26:27] op_sel:[0,1] op_sel_hi:[1,0]
	v_pk_mul_f32 v[218:219], v[198:199], s[44:45]
	v_pk_fma_f32 v[50:51], v[4:5], v[46:47], v[50:51] op_sel_hi:[0,1,1]
	v_pk_fma_f32 v[198:199], v[198:199], s[42:43], v[218:219] op_sel:[0,0,1] op_sel_hi:[1,0,0] neg_lo:[1,0,0] neg_hi:[1,0,0]
	v_pk_add_f32 v[218:219], v[154:155], v[206:207] op_sel:[0,1] op_sel_hi:[1,0] neg_hi:[0,1]
	v_pk_add_f32 v[154:155], v[154:155], v[206:207] op_sel:[0,1] op_sel_hi:[1,0] neg_lo:[0,1]
	v_pk_add_f32 v[206:207], v[156:157], v[172:173]
	v_pk_add_f32 v[156:157], v[156:157], v[172:173] neg_lo:[0,1] neg_hi:[0,1]
	v_pk_mul_f32 v[54:55], v[12:13], v[46:47] op_sel:[0,1] op_sel_hi:[1,0]
	v_pk_mul_f32 v[172:173], v[156:157], s[44:45]
	v_pk_fma_f32 v[66:67], v[4:5], v[62:63], v[66:67] op_sel_hi:[0,1,1]
	v_pk_fma_f32 v[156:157], v[156:157], s[42:43], v[172:173] op_sel:[0,0,1] op_sel_hi:[1,0,0]
	v_pk_add_f32 v[172:173], v[158:159], v[174:175]
	v_pk_add_f32 v[158:159], v[158:159], v[174:175] neg_lo:[0,1] neg_hi:[0,1]
	v_pk_mul_f32 v[70:71], v[12:13], v[62:63] op_sel:[0,1] op_sel_hi:[1,0]
	v_pk_mul_f32 v[174:175], v[158:159], s[68:69]
	v_pk_fma_f32 v[82:83], v[4:5], v[78:79], v[82:83] op_sel_hi:[0,1,1]
	v_pk_fma_f32 v[158:159], v[158:159], s[64:65], v[174:175] op_sel:[0,0,1] op_sel_hi:[1,0,0]
	v_pk_add_f32 v[174:175], v[160:161], v[176:177]
	v_pk_add_f32 v[160:161], v[160:161], v[176:177] neg_lo:[0,1] neg_hi:[0,1]
	v_pk_mul_f32 v[86:87], v[12:13], v[78:79] op_sel:[0,1] op_sel_hi:[1,0]
	v_pk_mul_f32 v[176:177], v[160:161], s[76:77]
	v_pk_fma_f32 v[98:99], v[4:5], v[94:95], v[98:99] op_sel_hi:[0,1,1]
	v_pk_fma_f32 v[160:161], v[160:161], s[72:73], v[176:177] op_sel:[0,0,1] op_sel_hi:[1,0,0]
	v_pk_add_f32 v[176:177], v[162:163], v[178:179]
	v_pk_add_f32 v[178:179], v[162:163], v[178:179] neg_lo:[0,1] neg_hi:[0,1]
	v_pk_mul_f32 v[102:103], v[12:13], v[94:95] op_sel:[0,1] op_sel_hi:[1,0]
	v_pk_add_f32 v[162:163], v[164:165], v[180:181]
	v_pk_add_f32 v[164:165], v[164:165], v[180:181] neg_lo:[0,1] neg_hi:[0,1]
	v_pk_fma_f32 v[114:115], v[4:5], v[110:111], v[114:115] op_sel_hi:[0,1,1]
	v_pk_mul_f32 v[180:181], v[164:165], s[76:77]
	v_pk_mul_f32 v[118:119], v[12:13], v[110:111] op_sel:[0,1] op_sel_hi:[1,0]
	v_pk_fma_f32 v[164:165], v[164:165], s[72:73], v[180:181] op_sel:[0,0,1] op_sel_hi:[1,0,0] neg_lo:[1,0,0] neg_hi:[1,0,0]
	v_pk_add_f32 v[180:181], v[166:167], v[182:183]
	v_pk_add_f32 v[166:167], v[166:167], v[182:183] neg_lo:[0,1] neg_hi:[0,1]
	v_pk_fma_f32 v[18:19], v[6:7], v[10:11], v[18:19] op_sel_hi:[0,1,1]
	v_pk_mul_f32 v[182:183], v[166:167], s[68:69]
	v_pk_mul_f32 v[22:23], v[10:11], v[20:21] op_sel:[1,0] op_sel_hi:[0,1]
	v_pk_fma_f32 v[166:167], v[166:167], s[64:65], v[182:183] op_sel:[0,0,1] op_sel_hi:[1,0,0] neg_lo:[1,0,0] neg_hi:[1,0,0]
	v_pk_add_f32 v[182:183], v[168:169], v[184:185]
	v_pk_add_f32 v[168:169], v[168:169], v[184:185] neg_lo:[0,1] neg_hi:[0,1]
	v_pk_fma_f32 v[38:39], v[6:7], v[26:27], v[38:39] op_sel_hi:[0,1,1]
	v_pk_mul_f32 v[184:185], v[168:169], s[44:45]
	v_pk_mul_f32 v[42:43], v[20:21], v[26:27] op_sel:[0,1] op_sel_hi:[1,0]
	v_pk_fma_f32 v[168:169], v[168:169], s[42:43], v[184:185] op_sel:[0,0,1] op_sel_hi:[1,0,0] neg_lo:[1,0,0] neg_hi:[1,0,0]
	v_pk_add_f32 v[184:185], v[220:221], v[210:211]
	v_pk_add_f32 v[210:211], v[220:221], v[210:211] neg_lo:[0,1] neg_hi:[0,1]
	v_pk_add_f32 v[220:221], v[222:223], v[192:193]
	v_pk_add_f32 v[192:193], v[222:223], v[192:193] neg_lo:[0,1] neg_hi:[0,1]
	v_pk_fma_f32 v[54:55], v[6:7], v[46:47], v[54:55] op_sel_hi:[0,1,1]
	v_pk_mul_f32 v[222:223], v[192:193], s[68:69]
	v_pk_mul_f32 v[58:59], v[20:21], v[46:47] op_sel:[0,1] op_sel_hi:[1,0]
	v_pk_fma_f32 v[192:193], v[192:193], s[64:65], v[222:223] op_sel:[0,0,1] op_sel_hi:[1,0,0]
	v_pk_add_f32 v[222:223], v[186:187], v[214:215]
	v_pk_add_f32 v[214:215], v[186:187], v[214:215] neg_lo:[0,1] neg_hi:[0,1]
	v_pk_fma_f32 v[70:71], v[6:7], v[62:63], v[70:71] op_sel_hi:[0,1,1]
	v_pk_add_f32 v[186:187], v[208:209], v[216:217]
	v_pk_add_f32 v[208:209], v[208:209], v[216:217] neg_lo:[0,1] neg_hi:[0,1]
	v_pk_mul_f32 v[74:75], v[20:21], v[62:63] op_sel:[0,1] op_sel_hi:[1,0]
	v_pk_mul_f32 v[216:217], v[208:209], s[68:69]
	v_pk_fma_f32 v[86:87], v[6:7], v[78:79], v[86:87] op_sel_hi:[0,1,1]
	v_pk_fma_f32 v[208:209], v[208:209], s[64:65], v[216:217] op_sel:[0,0,1] op_sel_hi:[1,0,0] neg_lo:[1,0,0] neg_hi:[1,0,0]
	v_pk_add_f32 v[216:217], v[204:205], v[212:213] op_sel:[0,1] op_sel_hi:[1,0] neg_hi:[0,1]
	v_pk_add_f32 v[204:205], v[204:205], v[212:213] op_sel:[0,1] op_sel_hi:[1,0] neg_lo:[0,1]
	v_pk_add_f32 v[212:213], v[170:171], v[194:195]
	v_pk_add_f32 v[170:171], v[170:171], v[194:195] neg_lo:[0,1] neg_hi:[0,1]
	v_pk_mul_f32 v[90:91], v[20:21], v[78:79] op_sel:[0,1] op_sel_hi:[1,0]
	v_pk_mul_f32 v[194:195], v[170:171], s[68:69]
	v_pk_fma_f32 v[102:103], v[6:7], v[94:95], v[102:103] op_sel_hi:[0,1,1]
	v_pk_fma_f32 v[170:171], v[170:171], s[64:65], v[194:195] op_sel:[0,0,1] op_sel_hi:[1,0,0]
	v_pk_add_f32 v[194:195], v[188:189], v[196:197]
	v_pk_add_f32 v[196:197], v[188:189], v[196:197] neg_lo:[0,1] neg_hi:[0,1]
	v_pk_mul_f32 v[106:107], v[20:21], v[94:95] op_sel:[0,1] op_sel_hi:[1,0]
	v_pk_add_f32 v[188:189], v[190:191], v[198:199]
	v_pk_add_f32 v[190:191], v[190:191], v[198:199] neg_lo:[0,1] neg_hi:[0,1]
	v_pk_fma_f32 v[118:119], v[6:7], v[110:111], v[118:119] op_sel_hi:[0,1,1]
	v_pk_mul_f32 v[198:199], v[190:191], s[68:69]
	v_pk_mul_f32 v[122:123], v[20:21], v[110:111] op_sel:[0,1] op_sel_hi:[1,0]
	v_pk_fma_f32 v[190:191], v[190:191], s[64:65], v[198:199] op_sel:[0,0,1] op_sel_hi:[1,0,0] neg_lo:[1,0,0] neg_hi:[1,0,0]
	v_pk_add_f32 v[198:199], v[218:219], v[176:177]
	v_pk_add_f32 v[176:177], v[218:219], v[176:177] neg_lo:[0,1] neg_hi:[0,1]
	v_pk_add_f32 v[218:219], v[206:207], v[162:163]
	v_pk_add_f32 v[162:163], v[206:207], v[162:163] neg_lo:[0,1] neg_hi:[0,1]
	v_xor_b32_e32 v24, 0x80000000, v17
	v_pk_mul_f32 v[206:207], v[162:163], s[68:69]
	v_xor_b32_e32 v28, 0x80000000, v19
	v_pk_fma_f32 v[162:163], v[162:163], s[64:65], v[206:207] op_sel:[0,0,1] op_sel_hi:[1,0,0]
	v_pk_add_f32 v[206:207], v[172:173], v[180:181]
	v_pk_add_f32 v[180:181], v[172:173], v[180:181] neg_lo:[0,1] neg_hi:[0,1]
	v_pk_fma_f32 v[22:23], v[10:11], v[8:9], v[22:23] op_sel_hi:[1,0,1]
	v_pk_add_f32 v[172:173], v[174:175], v[182:183]
	v_pk_add_f32 v[174:175], v[174:175], v[182:183] neg_lo:[0,1] neg_hi:[0,1]
	v_pk_fma_f32 v[42:43], v[8:9], v[26:27], v[42:43] op_sel_hi:[0,1,1]
	v_pk_mul_f32 v[182:183], v[174:175], s[68:69]
	v_pk_fma_f32 v[58:59], v[8:9], v[46:47], v[58:59] op_sel_hi:[0,1,1]
	v_pk_fma_f32 v[174:175], v[174:175], s[64:65], v[182:183] op_sel:[0,0,1] op_sel_hi:[1,0,0] neg_lo:[1,0,0] neg_hi:[1,0,0]
	v_pk_add_f32 v[182:183], v[154:155], v[178:179] op_sel:[0,1] op_sel_hi:[1,0] neg_hi:[0,1]
	v_pk_add_f32 v[154:155], v[154:155], v[178:179] op_sel:[0,1] op_sel_hi:[1,0] neg_lo:[0,1]
	v_pk_add_f32 v[178:179], v[156:157], v[164:165]
	v_pk_add_f32 v[156:157], v[156:157], v[164:165] neg_lo:[0,1] neg_hi:[0,1]
	v_pk_fma_f32 v[74:75], v[8:9], v[62:63], v[74:75] op_sel_hi:[0,1,1]
	v_pk_mul_f32 v[164:165], v[156:157], s[68:69]
	v_pk_fma_f32 v[90:91], v[8:9], v[78:79], v[90:91] op_sel_hi:[0,1,1]
	v_pk_fma_f32 v[156:157], v[156:157], s[64:65], v[164:165] op_sel:[0,0,1] op_sel_hi:[1,0,0]
	v_pk_add_f32 v[164:165], v[158:159], v[166:167]
	v_pk_add_f32 v[166:167], v[158:159], v[166:167] neg_lo:[0,1] neg_hi:[0,1]
	v_pk_fma_f32 v[106:107], v[8:9], v[94:95], v[106:107] op_sel_hi:[0,1,1]
	v_pk_add_f32 v[158:159], v[160:161], v[168:169]
	v_pk_add_f32 v[160:161], v[160:161], v[168:169] neg_lo:[0,1] neg_hi:[0,1]
	v_pk_fma_f32 v[122:123], v[8:9], v[110:111], v[122:123] op_sel_hi:[0,1,1]
	v_pk_mul_f32 v[168:169], v[160:161], s[68:69]
	v_mov_b32_e32 v25, v17
	v_pk_fma_f32 v[160:161], v[160:161], s[64:65], v[168:169] op_sel:[0,0,1] op_sel_hi:[1,0,0] neg_lo:[1,0,0] neg_hi:[1,0,0]
	v_pk_add_f32 v[168:169], v[184:185], v[222:223]
	v_pk_add_f32 v[184:185], v[184:185], v[222:223] neg_lo:[0,1] neg_hi:[0,1]
	v_pk_add_f32 v[222:223], v[220:221], v[186:187]
	v_pk_add_f32 v[220:221], v[220:221], v[186:187] neg_lo:[0,1] neg_hi:[0,1]
	v_mov_b32_e32 v29, v19
	v_pk_add_f32 v[186:187], v[210:211], v[214:215] op_sel:[0,1] op_sel_hi:[1,0] neg_hi:[0,1]
	v_pk_add_f32 v[210:211], v[210:211], v[214:215] op_sel:[0,1] op_sel_hi:[1,0] neg_lo:[0,1]
	v_pk_add_f32 v[214:215], v[192:193], v[208:209]
	v_pk_add_f32 v[208:209], v[192:193], v[208:209] neg_lo:[0,1] neg_hi:[0,1]
	v_xor_b32_e32 v32, 0x80000000, v23
	v_pk_add_f32 v[192:193], v[216:217], v[194:195]
	v_pk_add_f32 v[194:195], v[216:217], v[194:195] neg_lo:[0,1] neg_hi:[0,1]
	v_pk_add_f32 v[216:217], v[212:213], v[188:189]
	v_pk_add_f32 v[212:213], v[212:213], v[188:189] neg_lo:[0,1] neg_hi:[0,1]
	v_xor_b32_e32 v40, 0x80000000, v27
	v_pk_add_f32 v[188:189], v[204:205], v[196:197] op_sel:[0,1] op_sel_hi:[1,0] neg_hi:[0,1]
	v_pk_add_f32 v[196:197], v[204:205], v[196:197] op_sel:[0,1] op_sel_hi:[1,0] neg_lo:[0,1]
	v_pk_add_f32 v[204:205], v[170:171], v[190:191]
	v_pk_add_f32 v[190:191], v[170:171], v[190:191] neg_lo:[0,1] neg_hi:[0,1]
	v_xor_b32_e32 v44, 0x80000000, v31
	v_pk_add_f32 v[170:171], v[198:199], v[206:207]
	v_pk_add_f32 v[198:199], v[198:199], v[206:207] neg_lo:[0,1] neg_hi:[0,1]
	v_pk_add_f32 v[206:207], v[218:219], v[172:173]
	v_pk_add_f32 v[218:219], v[218:219], v[172:173] neg_lo:[0,1] neg_hi:[0,1]
	v_xor_b32_e32 v48, 0x80000000, v39
	v_pk_add_f32 v[172:173], v[176:177], v[180:181] op_sel:[0,1] op_sel_hi:[1,0] neg_hi:[0,1]
	v_pk_add_f32 v[176:177], v[176:177], v[180:181] op_sel:[0,1] op_sel_hi:[1,0] neg_lo:[0,1]
	v_pk_add_f32 v[180:181], v[162:163], v[174:175]
	v_pk_add_f32 v[174:175], v[162:163], v[174:175] neg_lo:[0,1] neg_hi:[0,1]
	v_mov_b32_e32 v33, v23
	v_pk_add_f32 v[162:163], v[182:183], v[164:165]
	v_pk_add_f32 v[164:165], v[182:183], v[164:165] neg_lo:[0,1] neg_hi:[0,1]
	v_pk_add_f32 v[182:183], v[178:179], v[158:159]
	v_pk_add_f32 v[178:179], v[178:179], v[158:159] neg_lo:[0,1] neg_hi:[0,1]
	v_mov_b32_e32 v41, v27
	v_pk_add_f32 v[158:159], v[154:155], v[166:167] op_sel:[0,1] op_sel_hi:[1,0] neg_hi:[0,1]
	v_pk_add_f32 v[154:155], v[154:155], v[166:167] op_sel:[0,1] op_sel_hi:[1,0] neg_lo:[0,1]
	v_pk_add_f32 v[166:167], v[156:157], v[160:161]
	v_pk_add_f32 v[156:157], v[156:157], v[160:161] neg_lo:[0,1] neg_hi:[0,1]
	v_mov_b32_e32 v45, v31
	v_xor_b32_e32 v161, 0x80000000, v156
	v_mov_b32_e32 v160, v157
	v_pk_add_f32 v[156:157], v[168:169], v[222:223]
	v_pk_add_f32 v[168:169], v[168:169], v[222:223] neg_lo:[0,1] neg_hi:[0,1]
	v_pk_add_f32 v[222:223], v[184:185], v[220:221] op_sel:[0,1] op_sel_hi:[1,0] neg_hi:[0,1]
	v_pk_add_f32 v[184:185], v[184:185], v[220:221] op_sel:[0,1] op_sel_hi:[1,0] neg_lo:[0,1]
	v_pk_add_f32 v[220:221], v[186:187], v[214:215]
	v_pk_add_f32 v[186:187], v[186:187], v[214:215] neg_lo:[0,1] neg_hi:[0,1]
	v_pk_add_f32 v[214:215], v[210:211], v[208:209] op_sel:[0,1] op_sel_hi:[1,0] neg_hi:[0,1]
	v_pk_add_f32 v[208:209], v[210:211], v[208:209] op_sel:[0,1] op_sel_hi:[1,0] neg_lo:[0,1]
	v_pk_add_f32 v[210:211], v[192:193], v[216:217]
	v_pk_add_f32 v[192:193], v[192:193], v[216:217] neg_lo:[0,1] neg_hi:[0,1]
	v_pk_add_f32 v[216:217], v[194:195], v[212:213] op_sel:[0,1] op_sel_hi:[1,0] neg_hi:[0,1]
	v_pk_add_f32 v[194:195], v[194:195], v[212:213] op_sel:[0,1] op_sel_hi:[1,0] neg_lo:[0,1]
	v_pk_add_f32 v[212:213], v[188:189], v[204:205]
	v_pk_add_f32 v[188:189], v[188:189], v[204:205] neg_lo:[0,1] neg_hi:[0,1]
	v_pk_add_f32 v[204:205], v[196:197], v[190:191] op_sel:[0,1] op_sel_hi:[1,0] neg_hi:[0,1]
	v_pk_add_f32 v[190:191], v[196:197], v[190:191] op_sel:[0,1] op_sel_hi:[1,0] neg_lo:[0,1]
	v_pk_add_f32 v[196:197], v[170:171], v[206:207]
	v_pk_add_f32 v[170:171], v[170:171], v[206:207] neg_lo:[0,1] neg_hi:[0,1]
	v_pk_mul_f32 v[2:3], v[2:3], v[196:197] op_sel:[0,1] op_sel_hi:[1,0]
	v_pk_add_f32 v[206:207], v[198:199], v[218:219] op_sel:[0,1] op_sel_hi:[1,0] neg_hi:[0,1]
	v_pk_add_f32 v[198:199], v[198:199], v[218:219] op_sel:[0,1] op_sel_hi:[1,0] neg_lo:[0,1]
	v_pk_add_f32 v[218:219], v[172:173], v[180:181]
	v_pk_add_f32 v[172:173], v[172:173], v[180:181] neg_lo:[0,1] neg_hi:[0,1]
	v_pk_add_f32 v[180:181], v[176:177], v[174:175] op_sel:[0,1] op_sel_hi:[1,0] neg_hi:[0,1]
	v_pk_add_f32 v[174:175], v[176:177], v[174:175] op_sel:[0,1] op_sel_hi:[1,0] neg_lo:[0,1]
	v_pk_add_f32 v[176:177], v[162:163], v[182:183]
	v_pk_fma_f32 v[2:3], v[4:5], v[196:197], v[2:3] op_sel_hi:[0,1,1]
	v_pk_mul_f32 v[4:5], v[12:13], v[210:211] op_sel:[0,1] op_sel_hi:[1,0]
	v_mov_b32_e32 v49, v39
	v_pk_fma_f32 v[4:5], v[6:7], v[210:211], v[4:5] op_sel_hi:[0,1,1]
	v_pk_mul_f32 v[6:7], v[20:21], v[176:177] op_sel:[0,1] op_sel_hi:[1,0]
	v_pk_add_f32 v[162:163], v[162:163], v[182:183] neg_lo:[0,1] neg_hi:[0,1]
	v_pk_fma_f32 v[6:7], v[8:9], v[176:177], v[6:7] op_sel_hi:[0,1,1]
	v_pk_mul_f32 v[8:9], v[14:15], v[220:221] op_sel:[0,1] op_sel_hi:[1,0]
	v_pk_add_f32 v[182:183], v[164:165], v[178:179] op_sel:[0,1] op_sel_hi:[1,0] neg_hi:[0,1]
	v_pk_add_f32 v[164:165], v[164:165], v[178:179] op_sel:[0,1] op_sel_hi:[1,0] neg_lo:[0,1]
	v_pk_add_f32 v[178:179], v[158:159], v[166:167]
	v_pk_fma_f32 v[8:9], v[10:11], v[220:221], v[8:9] op_sel_hi:[0,1,1]
	v_pk_mul_f32 v[10:11], v[24:25], v[218:219] op_sel:[0,1] op_sel_hi:[1,0]
	v_pk_mul_f32 v[12:13], v[28:29], v[212:213] op_sel:[0,1] op_sel_hi:[1,0]
	v_xor_b32_e32 v52, 0x80000000, v43
	v_xor_b32_e32 v56, 0x80000000, v47
	v_xor_b32_e32 v60, 0x80000000, v51
	v_xor_b32_e32 v64, 0x80000000, v55
	v_xor_b32_e32 v68, 0x80000000, v59
	v_xor_b32_e32 v72, 0x80000000, v63
	v_xor_b32_e32 v76, 0x80000000, v67
	v_mov_b32_e32 v53, v43
	v_mov_b32_e32 v57, v47
	v_mov_b32_e32 v61, v51
	v_mov_b32_e32 v65, v55
	v_mov_b32_e32 v69, v59
	v_mov_b32_e32 v73, v63
	v_mov_b32_e32 v77, v67
	v_pk_add_f32 v[158:159], v[158:159], v[166:167] neg_lo:[0,1] neg_hi:[0,1]
	v_pk_add_f32 v[166:167], v[154:155], v[160:161]
	v_pk_fma_f32 v[10:11], v[16:17], v[218:219], v[10:11] op_sel_hi:[0,1,1]
	v_pk_fma_f32 v[12:13], v[18:19], v[212:213], v[12:13] op_sel_hi:[0,1,1]
	v_pk_mul_f32 v[14:15], v[32:33], v[178:179] op_sel:[0,1] op_sel_hi:[1,0]
	v_pk_mul_f32 v[16:17], v[40:41], v[222:223] op_sel:[0,1] op_sel_hi:[1,0]
	v_pk_mul_f32 v[18:19], v[44:45], v[206:207] op_sel:[0,1] op_sel_hi:[1,0]
	v_pk_mul_f32 v[20:21], v[48:49], v[216:217] op_sel:[0,1] op_sel_hi:[1,0]
	v_xor_b32_e32 v80, 0x80000000, v71
	v_xor_b32_e32 v84, 0x80000000, v75
	v_xor_b32_e32 v88, 0x80000000, v79
	v_xor_b32_e32 v92, 0x80000000, v83
	v_xor_b32_e32 v96, 0x80000000, v87
	v_xor_b32_e32 v100, 0x80000000, v91
	v_xor_b32_e32 v104, 0x80000000, v95
	v_xor_b32_e32 v108, 0x80000000, v99
	v_xor_b32_e32 v112, 0x80000000, v103
	v_xor_b32_e32 v116, 0x80000000, v107
	v_xor_b32_e32 v120, 0x80000000, v111
	v_xor_b32_e32 v124, 0x80000000, v115
	v_xor_b32_e32 v126, 0x80000000, v119
	v_xor_b32_e32 v128, 0x80000000, v123
	v_mov_b32_e32 v81, v71
	v_mov_b32_e32 v85, v75
	v_mov_b32_e32 v89, v79
	v_mov_b32_e32 v93, v83
	v_mov_b32_e32 v97, v87
	v_mov_b32_e32 v101, v91
	v_mov_b32_e32 v105, v95
	v_mov_b32_e32 v109, v99
	v_mov_b32_e32 v113, v103
	v_mov_b32_e32 v117, v107
	v_mov_b32_e32 v121, v111
	v_mov_b32_e32 v125, v115
	v_mov_b32_e32 v127, v119
	v_mov_b32_e32 v129, v123
	v_pk_add_f32 v[154:155], v[154:155], v[160:161] neg_lo:[0,1] neg_hi:[0,1]
	v_pk_fma_f32 v[14:15], v[22:23], v[178:179], v[14:15] op_sel_hi:[0,1,1]
	v_pk_fma_f32 v[16:17], v[26:27], v[222:223], v[16:17] op_sel_hi:[0,1,1]
	v_pk_fma_f32 v[18:19], v[30:31], v[206:207], v[18:19] op_sel_hi:[0,1,1]
	v_pk_fma_f32 v[20:21], v[38:39], v[216:217], v[20:21] op_sel_hi:[0,1,1]
	v_pk_mul_f32 v[22:23], v[52:53], v[182:183] op_sel:[0,1] op_sel_hi:[1,0]
	v_pk_mul_f32 v[24:25], v[56:57], v[214:215] op_sel:[0,1] op_sel_hi:[1,0]
	v_pk_mul_f32 v[26:27], v[60:61], v[180:181] op_sel:[0,1] op_sel_hi:[1,0]
	v_pk_mul_f32 v[28:29], v[64:65], v[204:205] op_sel:[0,1] op_sel_hi:[1,0]
	v_pk_mul_f32 v[30:31], v[68:69], v[166:167] op_sel:[0,1] op_sel_hi:[1,0]
	v_pk_mul_f32 v[32:33], v[72:73], v[168:169] op_sel:[0,1] op_sel_hi:[1,0]
	v_pk_mul_f32 v[38:39], v[76:77], v[170:171] op_sel:[0,1] op_sel_hi:[1,0]
	v_pk_fma_f32 v[22:23], v[42:43], v[182:183], v[22:23] op_sel_hi:[0,1,1]
	v_pk_fma_f32 v[24:25], v[46:47], v[214:215], v[24:25] op_sel_hi:[0,1,1]
	v_pk_fma_f32 v[26:27], v[50:51], v[180:181], v[26:27] op_sel_hi:[0,1,1]
	v_pk_fma_f32 v[28:29], v[54:55], v[204:205], v[28:29] op_sel_hi:[0,1,1]
	v_pk_fma_f32 v[30:31], v[58:59], v[166:167], v[30:31] op_sel_hi:[0,1,1]
	v_pk_fma_f32 v[32:33], v[62:63], v[168:169], v[32:33] op_sel_hi:[0,1,1]
	v_pk_fma_f32 v[38:39], v[66:67], v[170:171], v[38:39] op_sel_hi:[0,1,1]
	v_pk_mul_f32 v[40:41], v[80:81], v[192:193] op_sel:[0,1] op_sel_hi:[1,0]
	v_pk_mul_f32 v[42:43], v[84:85], v[162:163] op_sel:[0,1] op_sel_hi:[1,0]
	v_pk_mul_f32 v[44:45], v[88:89], v[186:187] op_sel:[0,1] op_sel_hi:[1,0]
	v_pk_mul_f32 v[46:47], v[92:93], v[172:173] op_sel:[0,1] op_sel_hi:[1,0]
	v_pk_mul_f32 v[48:49], v[96:97], v[188:189] op_sel:[0,1] op_sel_hi:[1,0]
	v_pk_mul_f32 v[50:51], v[100:101], v[158:159] op_sel:[0,1] op_sel_hi:[1,0]
	v_pk_mul_f32 v[52:53], v[104:105], v[184:185] op_sel:[0,1] op_sel_hi:[1,0]
	v_pk_mul_f32 v[54:55], v[108:109], v[198:199] op_sel:[0,1] op_sel_hi:[1,0]
	v_pk_mul_f32 v[56:57], v[112:113], v[194:195] op_sel:[0,1] op_sel_hi:[1,0]
	v_pk_mul_f32 v[58:59], v[116:117], v[164:165] op_sel:[0,1] op_sel_hi:[1,0]
	v_pk_mul_f32 v[60:61], v[120:121], v[208:209] op_sel:[0,1] op_sel_hi:[1,0]
	v_pk_mul_f32 v[62:63], v[124:125], v[174:175] op_sel:[0,1] op_sel_hi:[1,0]
	v_pk_mul_f32 v[64:65], v[126:127], v[190:191] op_sel:[0,1] op_sel_hi:[1,0]
	v_pk_mul_f32 v[66:67], v[128:129], v[154:155] op_sel:[0,1] op_sel_hi:[1,0]
	v_pk_fma_f32 v[40:41], v[70:71], v[192:193], v[40:41] op_sel_hi:[0,1,1]
	v_pk_fma_f32 v[42:43], v[74:75], v[162:163], v[42:43] op_sel_hi:[0,1,1]
	v_pk_fma_f32 v[44:45], v[78:79], v[186:187], v[44:45] op_sel_hi:[0,1,1]
	v_pk_fma_f32 v[46:47], v[82:83], v[172:173], v[46:47] op_sel_hi:[0,1,1]
	v_pk_fma_f32 v[48:49], v[86:87], v[188:189], v[48:49] op_sel_hi:[0,1,1]
	v_pk_fma_f32 v[50:51], v[90:91], v[158:159], v[50:51] op_sel_hi:[0,1,1]
	v_pk_fma_f32 v[52:53], v[94:95], v[184:185], v[52:53] op_sel_hi:[0,1,1]
	v_pk_fma_f32 v[54:55], v[98:99], v[198:199], v[54:55] op_sel_hi:[0,1,1]
	v_pk_fma_f32 v[56:57], v[102:103], v[194:195], v[56:57] op_sel_hi:[0,1,1]
	v_pk_fma_f32 v[58:59], v[106:107], v[164:165], v[58:59] op_sel_hi:[0,1,1]
	v_pk_fma_f32 v[60:61], v[110:111], v[208:209], v[60:61] op_sel_hi:[0,1,1]
	v_pk_fma_f32 v[62:63], v[114:115], v[174:175], v[62:63] op_sel_hi:[0,1,1]
	v_pk_fma_f32 v[64:65], v[118:119], v[190:191], v[64:65] op_sel_hi:[0,1,1]
	v_pk_fma_f32 v[66:67], v[122:123], v[154:155], v[66:67] op_sel_hi:[0,1,1]
	ds_write_b64 v36, v[156:157]
	ds_write_b64 v36, v[32:33] offset:2112
	ds_write_b64 v36, v[16:17] offset:4224
	ds_write_b64 v36, v[52:53] offset:6336
	ds_write_b64 v36, v[8:9] offset:8448
	ds_write_b64 v36, v[44:45] offset:10560
	ds_write_b64 v36, v[24:25] offset:12672
	ds_write_b64 v36, v[60:61] offset:14784
	ds_write_b64 v36, v[4:5] offset:16896
	ds_write_b64 v36, v[40:41] offset:19008
	ds_write_b64 v36, v[20:21] offset:21120
	ds_write_b64 v36, v[56:57] offset:23232
	ds_write_b64 v36, v[12:13] offset:25344
	ds_write_b64 v36, v[48:49] offset:27456
	ds_write_b64 v36, v[28:29] offset:29568
	ds_write_b64 v36, v[64:65] offset:31680
	ds_write_b64 v36, v[2:3] offset:33792
	ds_write_b64 v36, v[38:39] offset:35904
	ds_write_b64 v36, v[18:19] offset:38016
	ds_write_b64 v36, v[54:55] offset:40128
	ds_write_b64 v36, v[10:11] offset:42240
	ds_write_b64 v36, v[46:47] offset:44352
	ds_write_b64 v36, v[26:27] offset:46464
	ds_write_b64 v36, v[62:63] offset:48576
	ds_write_b64 v36, v[6:7] offset:50688
	ds_write_b64 v36, v[42:43] offset:52800
	ds_write_b64 v36, v[22:23] offset:54912
	ds_write_b64 v36, v[58:59] offset:57024
	ds_write_b64 v36, v[14:15] offset:59136
	ds_write_b64 v36, v[50:51] offset:61248
	ds_write_b64 v36, v[30:31] offset:63360
	ds_write_b64 v36, v[66:67] offset:65472
	v_mov_b32_e32 v3, v130
	s_waitcnt lgkmcnt(0)
	s_barrier
	s_nop 0
	v_and_b32_e32 v5, 15, v3
	v_cvt_f32_ubyte0_e32 v2, v5
	v_mul_f32_e32 v4, 0x3b800000, v2
	v_sin_f32_e32 v2, v4
	v_cos_f32_e32 v4, v4
	v_lshlrev_b32_e32 v66, 3, v5
	v_lshlrev_b32_e32 v36, 4, v3
	v_xor_b32_e32 v5, 0x80000000, v2
	v_mov_b32_e32 v3, v5
	v_pk_mul_f32 v[6:7], v[4:5], v[2:3] op_sel:[1,0] op_sel_hi:[0,1]
	v_pk_fma_f32 v[6:7], v[4:5], v[4:5], v[6:7] op_sel_hi:[1,0,1]
	s_nop 0
	v_xor_b32_e32 v12, 0x80000000, v7
	v_mov_b32_e32 v13, v7
	v_pk_mul_f32 v[10:11], v[6:7], v[12:13] op_sel:[1,0] op_sel_hi:[0,1]
	v_pk_fma_f32 v[10:11], v[6:7], v[6:7], v[10:11] op_sel_hi:[1,0,1]
	v_pk_mul_f32 v[8:9], v[2:3], v[6:7] op_sel:[0,1] op_sel_hi:[1,0]
	v_xor_b32_e32 v14, 0x80000000, v11
	v_mov_b32_e32 v15, v11
	v_pk_mul_f32 v[30:31], v[10:11], v[14:15] op_sel:[1,0] op_sel_hi:[0,1]
	v_pk_fma_f32 v[30:31], v[10:11], v[10:11], v[30:31] op_sel_hi:[1,0,1]
	v_pk_mul_f32 v[16:17], v[2:3], v[10:11] op_sel:[0,1] op_sel_hi:[1,0]
	v_pk_mul_f32 v[50:51], v[14:15], v[30:31] op_sel:[0,1] op_sel_hi:[1,0]
	v_pk_mul_f32 v[38:39], v[2:3], v[30:31] op_sel:[0,1] op_sel_hi:[1,0]
	v_pk_fma_f32 v[50:51], v[10:11], v[30:31], v[50:51] op_sel_hi:[0,1,1]
	v_pk_mul_f32 v[54:55], v[2:3], v[50:51] op_sel:[0,1] op_sel_hi:[1,0]
	v_pk_fma_f32 v[8:9], v[4:5], v[6:7], v[8:9] op_sel_hi:[0,1,1]
	v_pk_fma_f32 v[16:17], v[4:5], v[10:11], v[16:17] op_sel_hi:[0,1,1]
	v_pk_fma_f32 v[38:39], v[4:5], v[30:31], v[38:39] op_sel_hi:[0,1,1]
	v_pk_fma_f32 v[54:55], v[4:5], v[50:51], v[54:55] op_sel_hi:[0,1,1]
	v_and_b32_e32 v5, 0xffffff00, v36
	v_lshlrev_b32_e32 v36, 3, v5
	v_add3_u32 v36, 0, v66, v36
	v_ashrrev_i32_e32 v66, 2, v5
	v_add_u32_e32 v108, v36, v66
	ds_read2_b64 v[66:69], v108 offset1:16
	ds_read2_b64 v[70:73], v108 offset0:33 offset1:49
	ds_read2_b64 v[74:77], v108 offset0:66 offset1:82
	ds_read2_b64 v[78:81], v108 offset0:132 offset1:148
	ds_read2_b64 v[82:85], v108 offset0:99 offset1:115
	ds_read2_b64 v[86:89], v108 offset0:165 offset1:181
	ds_read2_b64 v[90:93], v108 offset0:198 offset1:214
	ds_read2_b64 v[94:97], v108 offset0:231 offset1:247
	s_waitcnt lgkmcnt(4)
	v_pk_add_f32 v[98:99], v[66:67], v[78:79]
	v_pk_add_f32 v[66:67], v[66:67], v[78:79] neg_lo:[0,1] neg_hi:[0,1]
	v_pk_add_f32 v[78:79], v[68:69], v[80:81]
	v_pk_add_f32 v[68:69], v[68:69], v[80:81] neg_lo:[0,1] neg_hi:[0,1]
	s_waitcnt lgkmcnt(1)
	v_pk_add_f32 v[100:101], v[76:77], v[92:93]
	v_pk_mul_f32 v[80:81], v[68:69], s[44:45]
	v_pk_add_f32 v[76:77], v[76:77], v[92:93] neg_lo:[0,1] neg_hi:[0,1]
	v_pk_fma_f32 v[68:69], v[68:69], s[42:43], v[80:81] op_sel:[0,0,1] op_sel_hi:[1,0,0]
	v_pk_add_f32 v[80:81], v[70:71], v[86:87]
	v_pk_add_f32 v[70:71], v[70:71], v[86:87] neg_lo:[0,1] neg_hi:[0,1]
	v_pk_mul_f32 v[92:93], v[76:77], s[76:77]
	v_pk_mul_f32 v[86:87], v[70:71], s[68:69]
	v_pk_fma_f32 v[76:77], v[76:77], s[72:73], v[92:93] op_sel:[0,0,1] op_sel_hi:[1,0,0] neg_lo:[1,0,0] neg_hi:[1,0,0]
	v_pk_fma_f32 v[70:71], v[70:71], s[64:65], v[86:87] op_sel:[0,0,1] op_sel_hi:[1,0,0]
	v_pk_add_f32 v[86:87], v[72:73], v[88:89]
	v_pk_add_f32 v[72:73], v[72:73], v[88:89] neg_lo:[0,1] neg_hi:[0,1]
	s_waitcnt lgkmcnt(0)
	v_pk_add_f32 v[92:93], v[82:83], v[94:95]
	v_pk_add_f32 v[82:83], v[82:83], v[94:95] neg_lo:[0,1] neg_hi:[0,1]
	v_pk_mul_f32 v[88:89], v[72:73], s[76:77]
	v_pk_mul_f32 v[94:95], v[82:83], s[68:69]
	v_pk_fma_f32 v[72:73], v[72:73], s[72:73], v[88:89] op_sel:[0,0,1] op_sel_hi:[1,0,0]
	v_pk_add_f32 v[88:89], v[74:75], v[90:91]
	v_pk_add_f32 v[90:91], v[74:75], v[90:91] neg_lo:[0,1] neg_hi:[0,1]
	v_pk_fma_f32 v[82:83], v[82:83], s[64:65], v[94:95] op_sel:[0,0,1] op_sel_hi:[1,0,0] neg_lo:[1,0,0] neg_hi:[1,0,0]
	v_pk_add_f32 v[94:95], v[84:85], v[96:97]
	v_pk_add_f32 v[84:85], v[84:85], v[96:97] neg_lo:[0,1] neg_hi:[0,1]
	v_pk_mul_f32 v[96:97], v[84:85], s[44:45]
	v_pk_fma_f32 v[84:85], v[84:85], s[42:43], v[96:97] op_sel:[0,0,1] op_sel_hi:[1,0,0] neg_lo:[1,0,0] neg_hi:[1,0,0]
	v_pk_add_f32 v[96:97], v[98:99], v[88:89]
	v_pk_add_f32 v[88:89], v[98:99], v[88:89] neg_lo:[0,1] neg_hi:[0,1]
	v_pk_add_f32 v[98:99], v[78:79], v[100:101]
	v_pk_add_f32 v[78:79], v[78:79], v[100:101] neg_lo:[0,1] neg_hi:[0,1]
	v_pk_add_f32 v[102:103], v[86:87], v[94:95]
	v_pk_add_f32 v[86:87], v[86:87], v[94:95] neg_lo:[0,1] neg_hi:[0,1]
	v_pk_add_f32 v[74:75], v[66:67], v[90:91] op_sel:[0,1] op_sel_hi:[1,0] neg_hi:[0,1]
	v_pk_add_f32 v[66:67], v[66:67], v[90:91] op_sel:[0,1] op_sel_hi:[1,0] neg_lo:[0,1]
	v_pk_add_f32 v[90:91], v[68:69], v[76:77]
	v_pk_add_f32 v[68:69], v[68:69], v[76:77] neg_lo:[0,1] neg_hi:[0,1]
	v_pk_mul_f32 v[100:101], v[78:79], s[68:69]
	v_pk_mul_f32 v[94:95], v[86:87], s[68:69]
	v_pk_mul_f32 v[76:77], v[68:69], s[68:69]
	v_pk_fma_f32 v[78:79], v[78:79], s[64:65], v[100:101] op_sel:[0,0,1] op_sel_hi:[1,0,0]
	v_pk_add_f32 v[100:101], v[80:81], v[92:93]
	v_pk_add_f32 v[92:93], v[80:81], v[92:93] neg_lo:[0,1] neg_hi:[0,1]
	v_pk_fma_f32 v[86:87], v[86:87], s[64:65], v[94:95] op_sel:[0,0,1] op_sel_hi:[1,0,0] neg_lo:[1,0,0] neg_hi:[1,0,0]
	v_pk_fma_f32 v[68:69], v[68:69], s[64:65], v[76:77] op_sel:[0,0,1] op_sel_hi:[1,0,0]
	v_pk_add_f32 v[76:77], v[70:71], v[82:83]
	v_pk_add_f32 v[94:95], v[72:73], v[84:85]
	v_pk_add_f32 v[72:73], v[72:73], v[84:85] neg_lo:[0,1] neg_hi:[0,1]
	v_pk_add_f32 v[70:71], v[70:71], v[82:83] neg_lo:[0,1] neg_hi:[0,1]
	v_pk_mul_f32 v[84:85], v[72:73], s[68:69]
	v_pk_add_f32 v[104:105], v[74:75], v[76:77]
	v_pk_add_f32 v[74:75], v[74:75], v[76:77] neg_lo:[0,1] neg_hi:[0,1]
	v_pk_add_f32 v[76:77], v[90:91], v[94:95]
	v_pk_add_f32 v[94:95], v[90:91], v[94:95] neg_lo:[0,1] neg_hi:[0,1]
	v_xor_b32_e32 v18, 0x80000000, v9
	v_mov_b32_e32 v19, v9
	v_pk_mul_f32 v[22:23], v[12:13], v[10:11] op_sel:[0,1] op_sel_hi:[1,0]
	v_xor_b32_e32 v83, 0x80000000, v70
	v_pk_fma_f32 v[72:73], v[72:73], s[64:65], v[84:85] op_sel:[0,0,1] op_sel_hi:[1,0,0] neg_lo:[1,0,0] neg_hi:[1,0,0]
	v_pk_add_f32 v[80:81], v[88:89], v[92:93] op_sel:[0,1] op_sel_hi:[1,0] neg_hi:[0,1]
	v_pk_add_f32 v[88:89], v[88:89], v[92:93] op_sel:[0,1] op_sel_hi:[1,0] neg_lo:[0,1]
	v_pk_add_f32 v[92:93], v[78:79], v[86:87]
	v_pk_add_f32 v[86:87], v[78:79], v[86:87] neg_lo:[0,1] neg_hi:[0,1]
	v_mov_b32_e32 v82, v71
	v_xor_b32_e32 v20, 0x80000000, v17
	v_mov_b32_e32 v21, v17
	v_pk_fma_f32 v[22:23], v[6:7], v[10:11], v[22:23] op_sel_hi:[0,1,1]
	v_pk_mul_f32 v[26:27], v[10:11], v[18:19] op_sel:[1,0] op_sel_hi:[0,1]
	v_pk_add_f32 v[70:71], v[66:67], v[82:83]
	v_pk_add_f32 v[66:67], v[66:67], v[82:83] neg_lo:[0,1] neg_hi:[0,1]
	v_pk_add_f32 v[82:83], v[68:69], v[72:73]
	v_pk_add_f32 v[72:73], v[68:69], v[72:73] neg_lo:[0,1] neg_hi:[0,1]
	v_pk_add_f32 v[90:91], v[74:75], v[94:95] op_sel:[0,1] op_sel_hi:[1,0] neg_hi:[0,1]
	v_xor_b32_e32 v24, 0x80000000, v23
	v_mov_b32_e32 v25, v23
	v_pk_fma_f32 v[26:27], v[10:11], v[8:9], v[26:27] op_sel_hi:[1,0,1]
	v_pk_add_f32 v[78:79], v[88:89], v[86:87] op_sel:[0,1] op_sel_hi:[1,0] neg_hi:[0,1]
	v_pk_add_f32 v[74:75], v[74:75], v[94:95] op_sel:[0,1] op_sel_hi:[1,0] neg_lo:[0,1]
	v_pk_mul_f32 v[94:95], v[20:21], v[90:91] op_sel:[0,1] op_sel_hi:[1,0]
	v_xor_b32_e32 v28, 0x80000000, v27
	v_mov_b32_e32 v29, v27
	v_pk_add_f32 v[84:85], v[96:97], v[100:101]
	v_pk_add_f32 v[96:97], v[96:97], v[100:101] neg_lo:[0,1] neg_hi:[0,1]
	v_pk_add_f32 v[100:101], v[98:99], v[102:103]
	v_pk_add_f32 v[68:69], v[66:67], v[72:73] op_sel:[0,1] op_sel_hi:[1,0] neg_hi:[0,1]
	v_pk_fma_f32 v[90:91], v[16:17], v[90:91], v[94:95] op_sel_hi:[0,1,1]
	v_pk_mul_f32 v[94:95], v[24:25], v[78:79] op_sel:[0,1] op_sel_hi:[1,0]
	v_xor_b32_e32 v32, 0x80000000, v31
	v_mov_b32_e32 v33, v31
	v_pk_mul_f32 v[42:43], v[12:13], v[30:31] op_sel:[0,1] op_sel_hi:[1,0]
	v_pk_add_f32 v[106:107], v[84:85], v[100:101]
	v_pk_add_f32 v[84:85], v[84:85], v[100:101] neg_lo:[0,1] neg_hi:[0,1]
	v_pk_fma_f32 v[78:79], v[22:23], v[78:79], v[94:95] op_sel_hi:[0,1,1]
	v_pk_mul_f32 v[94:95], v[28:29], v[68:69] op_sel:[0,1] op_sel_hi:[1,0]
	v_xor_b32_e32 v40, 0x80000000, v39
	v_mov_b32_e32 v41, v39
	v_pk_fma_f32 v[42:43], v[6:7], v[30:31], v[42:43] op_sel_hi:[0,1,1]
	v_pk_mul_f32 v[46:47], v[18:19], v[30:31] op_sel:[0,1] op_sel_hi:[1,0]
	v_pk_add_f32 v[86:87], v[88:89], v[86:87] op_sel:[0,1] op_sel_hi:[1,0] neg_lo:[0,1]
	v_pk_add_f32 v[88:89], v[104:105], v[76:77]
	v_pk_add_f32 v[76:77], v[104:105], v[76:77] neg_lo:[0,1] neg_hi:[0,1]
	v_pk_fma_f32 v[68:69], v[26:27], v[68:69], v[94:95] op_sel_hi:[0,1,1]
	v_pk_mul_f32 v[94:95], v[32:33], v[84:85] op_sel:[0,1] op_sel_hi:[1,0]
	v_xor_b32_e32 v44, 0x80000000, v43
	v_mov_b32_e32 v45, v43
	v_pk_fma_f32 v[46:47], v[8:9], v[30:31], v[46:47] op_sel_hi:[0,1,1]
	v_pk_add_f32 v[102:103], v[98:99], v[102:103] neg_lo:[0,1] neg_hi:[0,1]
	v_pk_add_f32 v[100:101], v[80:81], v[92:93]
	v_pk_add_f32 v[80:81], v[80:81], v[92:93] neg_lo:[0,1] neg_hi:[0,1]
	v_pk_fma_f32 v[84:85], v[30:31], v[84:85], v[94:95] op_sel_hi:[0,1,1]
	v_pk_mul_f32 v[94:95], v[40:41], v[76:77] op_sel:[0,1] op_sel_hi:[1,0]
	v_xor_b32_e32 v48, 0x80000000, v47
	v_mov_b32_e32 v49, v47
	v_pk_add_f32 v[92:93], v[70:71], v[82:83]
	v_pk_add_f32 v[70:71], v[70:71], v[82:83] neg_lo:[0,1] neg_hi:[0,1]
	v_pk_fma_f32 v[76:77], v[38:39], v[76:77], v[94:95] op_sel_hi:[0,1,1]
	v_pk_mul_f32 v[94:95], v[44:45], v[80:81] op_sel:[0,1] op_sel_hi:[1,0]
	v_xor_b32_e32 v52, 0x80000000, v51
	v_mov_b32_e32 v53, v51
	v_pk_mul_f32 v[58:59], v[12:13], v[50:51] op_sel:[0,1] op_sel_hi:[1,0]
	v_pk_add_f32 v[98:99], v[96:97], v[102:103] op_sel:[0,1] op_sel_hi:[1,0] neg_hi:[0,1]
	v_pk_add_f32 v[96:97], v[96:97], v[102:103] op_sel:[0,1] op_sel_hi:[1,0] neg_lo:[0,1]
	v_pk_fma_f32 v[80:81], v[42:43], v[80:81], v[94:95] op_sel_hi:[0,1,1]
	v_pk_mul_f32 v[94:95], v[48:49], v[70:71] op_sel:[0,1] op_sel_hi:[1,0]
	v_xor_b32_e32 v56, 0x80000000, v55
	v_mov_b32_e32 v57, v55
	v_pk_fma_f32 v[58:59], v[6:7], v[50:51], v[58:59] op_sel_hi:[0,1,1]
	v_pk_mul_f32 v[62:63], v[18:19], v[50:51] op_sel:[0,1] op_sel_hi:[1,0]
	v_pk_fma_f32 v[70:71], v[46:47], v[70:71], v[94:95] op_sel_hi:[0,1,1]
	v_pk_mul_f32 v[94:95], v[52:53], v[96:97] op_sel:[0,1] op_sel_hi:[1,0]
	v_xor_b32_e32 v60, 0x80000000, v59
	v_mov_b32_e32 v61, v59
	v_pk_fma_f32 v[62:63], v[8:9], v[50:51], v[62:63] op_sel_hi:[0,1,1]
	v_pk_add_f32 v[66:67], v[66:67], v[72:73] op_sel:[0,1] op_sel_hi:[1,0] neg_lo:[0,1]
	v_pk_mul_f32 v[72:73], v[2:3], v[88:89] op_sel:[0,1] op_sel_hi:[1,0]
	v_pk_fma_f32 v[94:95], v[50:51], v[96:97], v[94:95] op_sel_hi:[0,1,1]
	v_pk_mul_f32 v[96:97], v[56:57], v[74:75] op_sel:[0,1] op_sel_hi:[1,0]
	v_xor_b32_e32 v64, 0x80000000, v63
	v_mov_b32_e32 v65, v63
	v_pk_fma_f32 v[72:73], v[4:5], v[88:89], v[72:73] op_sel_hi:[0,1,1]
	v_pk_mul_f32 v[88:89], v[18:19], v[92:93] op_sel:[0,1] op_sel_hi:[1,0]
	v_pk_fma_f32 v[74:75], v[54:55], v[74:75], v[96:97] op_sel_hi:[0,1,1]
	v_pk_mul_f32 v[96:97], v[60:61], v[86:87] op_sel:[0,1] op_sel_hi:[1,0]
	v_add_u32_e32 v5, 0x2000, v5
	v_pk_mul_f32 v[82:83], v[12:13], v[100:101] op_sel:[0,1] op_sel_hi:[1,0]
	v_pk_fma_f32 v[88:89], v[8:9], v[92:93], v[88:89] op_sel_hi:[0,1,1]
	v_pk_mul_f32 v[92:93], v[14:15], v[98:99] op_sel:[0,1] op_sel_hi:[1,0]
	v_pk_fma_f32 v[86:87], v[58:59], v[86:87], v[96:97] op_sel_hi:[0,1,1]
	v_pk_mul_f32 v[96:97], v[64:65], v[66:67] op_sel:[0,1] op_sel_hi:[1,0]
	v_ashrrev_i32_e32 v5, 2, v5
	v_pk_fma_f32 v[82:83], v[6:7], v[100:101], v[82:83] op_sel_hi:[0,1,1]
	v_pk_fma_f32 v[92:93], v[10:11], v[98:99], v[92:93] op_sel_hi:[0,1,1]
	v_pk_fma_f32 v[66:67], v[62:63], v[66:67], v[96:97] op_sel_hi:[0,1,1]
	ds_write2_b64 v108, v[106:107], v[84:85] offset1:16
	ds_write2_b64 v108, v[92:93], v[94:95] offset0:33 offset1:49
	ds_write2_b64 v108, v[82:83], v[80:81] offset0:66 offset1:82
	ds_write2_b64 v108, v[78:79], v[86:87] offset0:99 offset1:115
	ds_write2_b64 v108, v[72:73], v[76:77] offset0:132 offset1:148
	ds_write2_b64 v108, v[90:91], v[74:75] offset0:165 offset1:181
	ds_write2_b64 v108, v[88:89], v[70:71] offset0:198 offset1:214
	ds_write2_b64 v108, v[68:69], v[66:67] offset0:231 offset1:247
	v_add3_u32 v36, v36, v5, s30
	ds_read2_b64 v[66:69], v36 offset1:16
	ds_read2_b64 v[70:73], v36 offset0:33 offset1:49
	ds_read2_b64 v[74:77], v36 offset0:66 offset1:82
	ds_read2_b64 v[78:81], v36 offset0:132 offset1:148
	ds_read2_b64 v[82:85], v36 offset0:99 offset1:115
	ds_read2_b64 v[86:89], v36 offset0:165 offset1:181
	ds_read2_b64 v[90:93], v36 offset0:198 offset1:214
	ds_read2_b64 v[94:97], v36 offset0:231 offset1:247
	s_waitcnt lgkmcnt(4)
	v_pk_add_f32 v[98:99], v[66:67], v[78:79]
	v_pk_add_f32 v[66:67], v[66:67], v[78:79] neg_lo:[0,1] neg_hi:[0,1]
	v_pk_add_f32 v[78:79], v[68:69], v[80:81]
	v_pk_add_f32 v[68:69], v[68:69], v[80:81] neg_lo:[0,1] neg_hi:[0,1]
	s_waitcnt lgkmcnt(1)
	v_pk_add_f32 v[100:101], v[76:77], v[92:93]
	v_pk_mul_f32 v[80:81], v[68:69], s[44:45]
	v_pk_add_f32 v[76:77], v[76:77], v[92:93] neg_lo:[0,1] neg_hi:[0,1]
	v_pk_fma_f32 v[68:69], v[68:69], s[42:43], v[80:81] op_sel:[0,0,1] op_sel_hi:[1,0,0]
	v_pk_add_f32 v[80:81], v[70:71], v[86:87]
	v_pk_add_f32 v[70:71], v[70:71], v[86:87] neg_lo:[0,1] neg_hi:[0,1]
	v_pk_mul_f32 v[92:93], v[76:77], s[76:77]
	v_pk_mul_f32 v[86:87], v[70:71], s[68:69]
	v_pk_fma_f32 v[76:77], v[76:77], s[72:73], v[92:93] op_sel:[0,0,1] op_sel_hi:[1,0,0] neg_lo:[1,0,0] neg_hi:[1,0,0]
	s_waitcnt lgkmcnt(0)
	v_pk_add_f32 v[92:93], v[82:83], v[94:95]
	v_pk_add_f32 v[82:83], v[82:83], v[94:95] neg_lo:[0,1] neg_hi:[0,1]
	v_pk_fma_f32 v[70:71], v[70:71], s[64:65], v[86:87] op_sel:[0,0,1] op_sel_hi:[1,0,0]
	v_pk_add_f32 v[86:87], v[72:73], v[88:89]
	v_pk_add_f32 v[72:73], v[72:73], v[88:89] neg_lo:[0,1] neg_hi:[0,1]
	v_pk_mul_f32 v[94:95], v[82:83], s[68:69]
	v_pk_mul_f32 v[88:89], v[72:73], s[76:77]
	v_pk_fma_f32 v[82:83], v[82:83], s[64:65], v[94:95] op_sel:[0,0,1] op_sel_hi:[1,0,0] neg_lo:[1,0,0] neg_hi:[1,0,0]
	v_pk_add_f32 v[94:95], v[84:85], v[96:97]
	v_pk_add_f32 v[84:85], v[84:85], v[96:97] neg_lo:[0,1] neg_hi:[0,1]
	v_pk_fma_f32 v[72:73], v[72:73], s[72:73], v[88:89] op_sel:[0,0,1] op_sel_hi:[1,0,0]
	v_pk_add_f32 v[88:89], v[74:75], v[90:91]
	v_pk_mul_f32 v[96:97], v[84:85], s[44:45]
	v_pk_add_f32 v[90:91], v[74:75], v[90:91] neg_lo:[0,1] neg_hi:[0,1]
	v_pk_fma_f32 v[84:85], v[84:85], s[42:43], v[96:97] op_sel:[0,0,1] op_sel_hi:[1,0,0] neg_lo:[1,0,0] neg_hi:[1,0,0]
	v_pk_add_f32 v[96:97], v[98:99], v[88:89]
	v_pk_add_f32 v[88:89], v[98:99], v[88:89] neg_lo:[0,1] neg_hi:[0,1]
	v_pk_add_f32 v[98:99], v[78:79], v[100:101]
	v_pk_add_f32 v[78:79], v[78:79], v[100:101] neg_lo:[0,1] neg_hi:[0,1]
	v_pk_add_f32 v[102:103], v[86:87], v[94:95]
	v_pk_add_f32 v[86:87], v[86:87], v[94:95] neg_lo:[0,1] neg_hi:[0,1]
	v_pk_mul_f32 v[100:101], v[78:79], s[68:69]
	v_pk_mul_f32 v[94:95], v[86:87], s[68:69]
	v_pk_fma_f32 v[78:79], v[78:79], s[64:65], v[100:101] op_sel:[0,0,1] op_sel_hi:[1,0,0]
	v_pk_add_f32 v[100:101], v[80:81], v[92:93]
	v_pk_add_f32 v[92:93], v[80:81], v[92:93] neg_lo:[0,1] neg_hi:[0,1]
	v_pk_fma_f32 v[86:87], v[86:87], s[64:65], v[94:95] op_sel:[0,0,1] op_sel_hi:[1,0,0] neg_lo:[1,0,0] neg_hi:[1,0,0]
	v_pk_add_f32 v[74:75], v[66:67], v[90:91] op_sel:[0,1] op_sel_hi:[1,0] neg_hi:[0,1]
	v_pk_add_f32 v[66:67], v[66:67], v[90:91] op_sel:[0,1] op_sel_hi:[1,0] neg_lo:[0,1]
	v_pk_add_f32 v[90:91], v[68:69], v[76:77]
	v_pk_add_f32 v[68:69], v[68:69], v[76:77] neg_lo:[0,1] neg_hi:[0,1]
	v_pk_add_f32 v[94:95], v[72:73], v[84:85]
	v_pk_add_f32 v[72:73], v[72:73], v[84:85] neg_lo:[0,1] neg_hi:[0,1]
	v_pk_mul_f32 v[76:77], v[68:69], s[68:69]
	v_pk_mul_f32 v[84:85], v[72:73], s[68:69]
	v_pk_fma_f32 v[68:69], v[68:69], s[64:65], v[76:77] op_sel:[0,0,1] op_sel_hi:[1,0,0]
	v_pk_add_f32 v[76:77], v[70:71], v[82:83]
	v_pk_fma_f32 v[72:73], v[72:73], s[64:65], v[84:85] op_sel:[0,0,1] op_sel_hi:[1,0,0] neg_lo:[1,0,0] neg_hi:[1,0,0]
	v_pk_add_f32 v[80:81], v[88:89], v[92:93] op_sel:[0,1] op_sel_hi:[1,0] neg_hi:[0,1]
	v_pk_add_f32 v[88:89], v[88:89], v[92:93] op_sel:[0,1] op_sel_hi:[1,0] neg_lo:[0,1]
	v_pk_add_f32 v[92:93], v[78:79], v[86:87]
	v_pk_add_f32 v[86:87], v[78:79], v[86:87] neg_lo:[0,1] neg_hi:[0,1]
	s_add_i32 s65, s65, s28
	v_pk_add_f32 v[82:83], v[70:71], v[82:83] neg_lo:[0,1] neg_hi:[0,1]
	s_nop 0
	v_pk_add_f32 v[104:105], v[74:75], v[76:77]
	v_pk_add_f32 v[74:75], v[74:75], v[76:77] neg_lo:[0,1] neg_hi:[0,1]
	v_pk_add_f32 v[76:77], v[90:91], v[94:95]
	s_cmpk_gt_i32 s65, 0x3ff
	s_nop 0
	v_pk_add_f32 v[84:85], v[96:97], v[100:101]
	v_pk_add_f32 v[96:97], v[96:97], v[100:101] neg_lo:[0,1] neg_hi:[0,1]
	v_pk_add_f32 v[100:101], v[98:99], v[102:103]
	s_nop 0
	v_pk_add_f32 v[78:79], v[88:89], v[86:87] op_sel:[0,1] op_sel_hi:[1,0] neg_hi:[0,1]
	v_pk_add_f32 v[86:87], v[88:89], v[86:87] op_sel:[0,1] op_sel_hi:[1,0] neg_lo:[0,1]
	v_pk_add_f32 v[88:89], v[104:105], v[76:77]
	s_cselect_b64 s[80:81], -1, 0
	s_cmpk_lt_i32 s65, 0x400
	v_pk_add_f32 v[98:99], v[98:99], v[102:103] neg_lo:[0,1] neg_hi:[0,1]
	v_pk_add_f32 v[70:71], v[66:67], v[82:83] op_sel:[0,1] op_sel_hi:[1,0] neg_hi:[0,1]
	v_pk_add_f32 v[66:67], v[66:67], v[82:83] op_sel:[0,1] op_sel_hi:[1,0] neg_lo:[0,1]
	v_pk_add_f32 v[82:83], v[68:69], v[72:73]
	v_pk_add_f32 v[106:107], v[84:85], v[100:101]
	v_pk_add_f32 v[84:85], v[84:85], v[100:101] neg_lo:[0,1] neg_hi:[0,1]
	v_pk_add_f32 v[100:101], v[80:81], v[92:93]
	v_pk_mul_f32 v[2:3], v[2:3], v[88:89] op_sel:[0,1] op_sel_hi:[1,0]
	s_cselect_b32 s6, s65, s6
	v_xor_b32_e32 v103, 0x80000000, v98
	v_pk_add_f32 v[90:91], v[90:91], v[94:95] neg_lo:[0,1] neg_hi:[0,1]
	v_mov_b32_e32 v102, v99
	v_pk_add_f32 v[80:81], v[80:81], v[92:93] neg_lo:[0,1] neg_hi:[0,1]
	v_pk_add_f32 v[92:93], v[70:71], v[82:83]
	v_pk_fma_f32 v[2:3], v[4:5], v[88:89], v[2:3] op_sel_hi:[0,1,1]
	v_pk_mul_f32 v[4:5], v[12:13], v[100:101] op_sel:[0,1] op_sel_hi:[1,0]
	s_lshl_b32 s8, s6, 1
	s_lshl_b32 s6, s6, 2
	v_xor_b32_e32 v95, 0x80000000, v90
	v_pk_add_f32 v[68:69], v[68:69], v[72:73] neg_lo:[0,1] neg_hi:[0,1]
	v_pk_add_f32 v[98:99], v[96:97], v[102:103]
	v_mov_b32_e32 v94, v91
	v_pk_fma_f32 v[4:5], v[6:7], v[100:101], v[4:5] op_sel_hi:[0,1,1]
	v_pk_mul_f32 v[6:7], v[18:19], v[92:93] op_sel:[0,1] op_sel_hi:[1,0]
	s_and_b32 s7, s8, 0x3fe
	s_and_b32 s6, s6, 0xfffff800
	v_xor_b32_e32 v73, 0x80000000, v68
	v_pk_add_f32 v[90:91], v[74:75], v[94:95]
	v_mov_b32_e32 v72, v69
	v_pk_fma_f32 v[6:7], v[8:9], v[92:93], v[6:7] op_sel_hi:[0,1,1]
	v_pk_mul_f32 v[8:9], v[14:15], v[98:99] op_sel:[0,1] op_sel_hi:[1,0]
	s_or_b32 s6, s7, s6
	v_pk_add_f32 v[68:69], v[66:67], v[72:73]
	v_pk_fma_f32 v[8:9], v[10:11], v[98:99], v[8:9] op_sel_hi:[0,1,1]
	v_pk_mul_f32 v[10:11], v[20:21], v[90:91] op_sel:[0,1] op_sel_hi:[1,0]
	s_ashr_i32 s7, s6, 31
	v_pk_add_f32 v[96:97], v[96:97], v[102:103] neg_lo:[0,1] neg_hi:[0,1]
	v_pk_add_f32 v[76:77], v[104:105], v[76:77] neg_lo:[0,1] neg_hi:[0,1]
	v_pk_add_f32 v[74:75], v[74:75], v[94:95] neg_lo:[0,1] neg_hi:[0,1]
	v_pk_add_f32 v[70:71], v[70:71], v[82:83] neg_lo:[0,1] neg_hi:[0,1]
	v_pk_add_f32 v[66:67], v[66:67], v[72:73] neg_lo:[0,1] neg_hi:[0,1]
	v_pk_fma_f32 v[10:11], v[16:17], v[90:91], v[10:11] op_sel_hi:[0,1,1]
	v_pk_mul_f32 v[12:13], v[24:25], v[78:79] op_sel:[0,1] op_sel_hi:[1,0]
	v_pk_mul_f32 v[14:15], v[28:29], v[68:69] op_sel:[0,1] op_sel_hi:[1,0]
	v_pk_mul_f32 v[16:17], v[32:33], v[84:85] op_sel:[0,1] op_sel_hi:[1,0]
	s_lshl_b64 s[82:83], s[6:7], 14
	s_bitset1_b32 s6, 10
	v_pk_fma_f32 v[12:13], v[22:23], v[78:79], v[12:13] op_sel_hi:[0,1,1]
	v_pk_fma_f32 v[14:15], v[26:27], v[68:69], v[14:15] op_sel_hi:[0,1,1]
	v_pk_fma_f32 v[16:17], v[30:31], v[84:85], v[16:17] op_sel_hi:[0,1,1]
	v_pk_mul_f32 v[18:19], v[40:41], v[76:77] op_sel:[0,1] op_sel_hi:[1,0]
	v_pk_mul_f32 v[20:21], v[44:45], v[80:81] op_sel:[0,1] op_sel_hi:[1,0]
	v_pk_mul_f32 v[22:23], v[48:49], v[70:71] op_sel:[0,1] op_sel_hi:[1,0]
	v_pk_mul_f32 v[24:25], v[52:53], v[96:97] op_sel:[0,1] op_sel_hi:[1,0]
	v_pk_mul_f32 v[26:27], v[56:57], v[74:75] op_sel:[0,1] op_sel_hi:[1,0]
	v_pk_mul_f32 v[28:29], v[60:61], v[86:87] op_sel:[0,1] op_sel_hi:[1,0]
	v_pk_mul_f32 v[30:31], v[64:65], v[66:67] op_sel:[0,1] op_sel_hi:[1,0]
	s_ashr_i32 s7, s6, 31
	v_pk_fma_f32 v[18:19], v[38:39], v[76:77], v[18:19] op_sel_hi:[0,1,1]
	v_pk_fma_f32 v[20:21], v[42:43], v[80:81], v[20:21] op_sel_hi:[0,1,1]
	v_pk_fma_f32 v[22:23], v[46:47], v[70:71], v[22:23] op_sel_hi:[0,1,1]
	v_pk_fma_f32 v[24:25], v[50:51], v[96:97], v[24:25] op_sel_hi:[0,1,1]
	v_pk_fma_f32 v[26:27], v[54:55], v[74:75], v[26:27] op_sel_hi:[0,1,1]
	v_pk_fma_f32 v[28:29], v[58:59], v[86:87], v[28:29] op_sel_hi:[0,1,1]
	v_pk_fma_f32 v[30:31], v[62:63], v[66:67], v[30:31] op_sel_hi:[0,1,1]
	ds_write2_b64 v36, v[106:107], v[16:17] offset1:16
	ds_write2_b64 v36, v[8:9], v[24:25] offset0:33 offset1:49
	ds_write2_b64 v36, v[4:5], v[20:21] offset0:66 offset1:82
	ds_write2_b64 v36, v[12:13], v[28:29] offset0:99 offset1:115
	ds_write2_b64 v36, v[2:3], v[18:19] offset0:132 offset1:148
	ds_write2_b64 v36, v[10:11], v[26:27] offset0:165 offset1:181
	ds_write2_b64 v36, v[6:7], v[22:23] offset0:198 offset1:214
	ds_write2_b64 v36, v[14:15], v[30:31] offset0:231 offset1:247
	s_lshl_b64 s[6:7], s[6:7], 14
	v_lshl_add_u64 v[2:3], v[34:35], 0, s[82:83]
	s_waitcnt lgkmcnt(0)
	s_barrier
	global_load_dwordx4 v[10:13], v[2:3], off nt
	global_load_dwordx4 v[30:33], v[2:3], off offset:16 nt
	v_lshl_add_u64 v[2:3], v[34:35], 0, s[6:7]
	global_load_dwordx4 v[26:29], v[2:3], off nt
	global_load_dwordx4 v[22:25], v[2:3], off offset:16 nt
	v_mov_b32_e32 v38, 0
	s_and_saveexec_b64 s[6:7], s[0:1]
	s_cbranch_execz .LBB0_430
	global_load_ushort v38, v[2:3], off offset:32

.LBB0_432:
	s_or_b64 exec, exec, s[6:7]
	v_mov_b32_e32 v36, v130
	s_mov_b32 s75, s42
	v_ashrrev_i32_e32 v40, 31, v36
	v_add_u32_sdwa v40, v36, v40 dst_sel:DWORD dst_unused:UNUSED_PAD src0_sel:DWORD src1_sel:BYTE_3
	v_ashrrev_i32_e32 v40, 8, v40
	v_mul_i32_i24_e32 v41, 0x100, v40
	v_sub_u32_e32 v66, v36, v41
	v_lshlrev_b32_e32 v41, 1, v66
	v_bfrev_b32_e32 v41, v41
	v_lshrrev_b32_e32 v41, 23, v41
	v_sub_u32_e32 v41, 0x200, v41
	v_bfrev_b32_e32 v41, v41
	v_lshrrev_b32_e32 v41, 19, v41
	v_and_b32_e32 v41, 0x1ff0, v41
	v_cmp_eq_u32_e64 s[6:7], 0, v66
	v_lshlrev_b32_e32 v40, 13, v40
	v_lshl_add_u32 v42, v66, 5, v40
	v_cndmask_b32_e64 v41, v41, 16, s[6:7]
	v_or_b32_e32 v40, v41, v40
	v_lshlrev_b32_e32 v43, 3, v42
	v_ashrrev_i32_e32 v42, 2, v42
	v_ashrrev_i32_e32 v41, 5, v40
	v_add3_u32 v88, 0, v43, v42
	v_lshlrev_b32_e32 v40, 3, v40
	v_lshlrev_b32_e32 v41, 3, v41
	v_add_u32_e32 v36, 0xffffff00, v36
	v_add3_u32 v40, 0, v40, v41
	ds_read2_b64 v[42:45], v88 offset1:1
	ds_read2_b64 v[46:49], v88 offset0:2 offset1:3
	ds_read2_b64 v[72:75], v40 offset1:1
	ds_read2_b64 v[76:79], v40 offset0:2 offset1:3
	ds_read2_b64 v[50:53], v88 offset0:4 offset1:5
	ds_read2_b64 v[54:57], v88 offset0:6 offset1:7
	ds_read2_b64 v[80:83], v40 offset0:4 offset1:5
	ds_read2_b64 v[84:87], v40 offset0:6 offset1:7
	ds_read2_b64 v[58:61], v88 offset0:8 offset1:9
	ds_read2_b64 v[62:65], v88 offset0:10 offset1:11
	ds_read2_b64 v[96:99], v40 offset0:8 offset1:9
	ds_read2_b64 v[100:103], v40 offset0:10 offset1:11
	ds_read2_b64 v[68:71], v88 offset0:12 offset1:13
	ds_read2_b64 v[88:91], v88 offset0:14 offset1:15
	ds_read2_b64 v[104:107], v40 offset0:12 offset1:13
	ds_read2_b64 v[108:111], v40 offset0:14 offset1:15
	v_mov_b32_e32 v40, s16
	v_cmp_gt_u32_e64 s[8:9], s33, v36
	s_waitcnt lgkmcnt(7)
	v_pk_add_f32 v[92:93], v[42:43], v[58:59]
	v_pk_add_f32 v[42:43], v[42:43], v[58:59] neg_lo:[0,1] neg_hi:[0,1]
	v_pk_add_f32 v[58:59], v[44:45], v[60:61]
	v_pk_add_f32 v[44:45], v[44:45], v[60:61] neg_lo:[0,1] neg_hi:[0,1]
	v_addc_co_u32_e64 v40, s[8:9], 0, v40, s[8:9]
	v_pk_mul_f32 v[60:61], v[44:45], s[44:45]
	s_waitcnt lgkmcnt(3)
	v_pk_add_f32 v[94:95], v[52:53], v[70:71]
	v_pk_add_f32 v[52:53], v[52:53], v[70:71] neg_lo:[0,1] neg_hi:[0,1]
	v_pk_fma_f32 v[44:45], v[44:45], s[42:43], v[60:61] op_sel:[0,0,1] op_sel_hi:[1,0,0]
	v_pk_add_f32 v[60:61], v[46:47], v[62:63]
	v_pk_add_f32 v[46:47], v[46:47], v[62:63] neg_lo:[0,1] neg_hi:[0,1]
	s_mov_b32 s67, s64
	s_mov_b32 s8, s45
	v_pk_mul_f32 v[70:71], v[52:53], s[74:75]
	v_pk_mul_f32 v[62:63], v[46:47], s[66:67]
	v_pk_fma_f32 v[52:53], v[52:53], s[8:9], v[70:71] op_sel:[0,0,1] op_sel_hi:[1,0,0] neg_lo:[1,0,0] neg_hi:[1,0,0]
	s_waitcnt lgkmcnt(2)
	v_pk_add_f32 v[70:71], v[54:55], v[88:89]
	v_pk_add_f32 v[54:55], v[54:55], v[88:89] neg_lo:[0,1] neg_hi:[0,1]
	v_pk_fma_f32 v[46:47], v[46:47], s[64:65], v[62:63] op_sel:[0,0,1] op_sel_hi:[1,0,0]
	v_pk_add_f32 v[62:63], v[48:49], v[64:65]
	v_pk_add_f32 v[48:49], v[48:49], v[64:65] neg_lo:[0,1] neg_hi:[0,1]
	v_pk_mul_f32 v[88:89], v[54:55], s[66:67]
	v_pk_mul_f32 v[64:65], v[48:49], s[74:75]
	v_pk_fma_f32 v[54:55], v[54:55], s[64:65], v[88:89] op_sel:[0,0,1] op_sel_hi:[1,0,0] neg_lo:[1,0,0] neg_hi:[1,0,0]
	v_pk_add_f32 v[88:89], v[56:57], v[90:91]
	v_pk_add_f32 v[56:57], v[56:57], v[90:91] neg_lo:[0,1] neg_hi:[0,1]
	v_pk_fma_f32 v[48:49], v[48:49], s[8:9], v[64:65] op_sel:[0,0,1] op_sel_hi:[1,0,0]
	v_pk_add_f32 v[64:65], v[50:51], v[68:69]
	v_pk_add_f32 v[50:51], v[50:51], v[68:69] neg_lo:[0,1] neg_hi:[0,1]
	v_pk_mul_f32 v[90:91], v[56:57], s[44:45]
	v_pk_add_f32 v[112:113], v[62:63], v[88:89]
	v_pk_add_f32 v[62:63], v[62:63], v[88:89] neg_lo:[0,1] neg_hi:[0,1]
	v_xor_b32_e32 v69, 0x80000000, v50
	v_pk_fma_f32 v[56:57], v[56:57], s[42:43], v[90:91] op_sel:[0,0,1] op_sel_hi:[1,0,0] neg_lo:[1,0,0] neg_hi:[1,0,0]
	v_pk_add_f32 v[90:91], v[92:93], v[64:65]
	v_pk_add_f32 v[64:65], v[92:93], v[64:65] neg_lo:[0,1] neg_hi:[0,1]
	v_pk_add_f32 v[92:93], v[58:59], v[94:95]
	v_pk_add_f32 v[58:59], v[58:59], v[94:95] neg_lo:[0,1] neg_hi:[0,1]
	v_pk_mul_f32 v[88:89], v[62:63], s[66:67]
	v_mov_b32_e32 v68, v51
	v_pk_mul_f32 v[94:95], v[58:59], s[66:67]
	v_pk_fma_f32 v[62:63], v[62:63], s[64:65], v[88:89] op_sel:[0,0,1] op_sel_hi:[1,0,0] neg_lo:[1,0,0] neg_hi:[1,0,0]
	v_pk_add_f32 v[50:51], v[42:43], v[68:69]
	v_pk_add_f32 v[42:43], v[42:43], v[68:69] neg_lo:[0,1] neg_hi:[0,1]
	v_pk_add_f32 v[68:69], v[44:45], v[52:53]
	v_pk_add_f32 v[44:45], v[44:45], v[52:53] neg_lo:[0,1] neg_hi:[0,1]
	v_pk_add_f32 v[88:89], v[48:49], v[56:57]
	v_pk_add_f32 v[48:49], v[48:49], v[56:57] neg_lo:[0,1] neg_hi:[0,1]
	v_pk_fma_f32 v[58:59], v[58:59], s[64:65], v[94:95] op_sel:[0,0,1] op_sel_hi:[1,0,0]
	v_pk_add_f32 v[94:95], v[60:61], v[70:71]
	v_pk_mul_f32 v[52:53], v[44:45], s[66:67]
	v_pk_mul_f32 v[56:57], v[48:49], s[66:67]
	v_pk_fma_f32 v[44:45], v[44:45], s[64:65], v[52:53] op_sel:[0,0,1] op_sel_hi:[1,0,0]
	v_pk_add_f32 v[52:53], v[46:47], v[54:55]
	v_pk_fma_f32 v[48:49], v[48:49], s[64:65], v[56:57] op_sel:[0,0,1] op_sel_hi:[1,0,0] neg_lo:[1,0,0] neg_hi:[1,0,0]
	v_pk_add_f32 v[56:57], v[90:91], v[94:95]
	v_pk_add_f32 v[114:115], v[90:91], v[94:95] neg_lo:[0,1] neg_hi:[0,1]
	v_pk_add_f32 v[90:91], v[92:93], v[112:113]
	v_pk_add_f32 v[112:113], v[92:93], v[112:113] neg_lo:[0,1] neg_hi:[0,1]
	v_pk_add_f32 v[122:123], v[50:51], v[52:53]
	v_pk_add_f32 v[50:51], v[50:51], v[52:53] neg_lo:[0,1] neg_hi:[0,1]
	v_pk_add_f32 v[52:53], v[68:69], v[88:89]
	v_pk_add_f32 v[88:89], v[68:69], v[88:89] neg_lo:[0,1] neg_hi:[0,1]
	v_pk_add_f32 v[92:93], v[74:75], v[98:99]
	v_pk_add_f32 v[74:75], v[74:75], v[98:99] neg_lo:[0,1] neg_hi:[0,1]
	v_xor_b32_e32 v125, 0x80000000, v88
	v_mov_b32_e32 v124, v89
	v_pk_add_f32 v[88:89], v[72:73], v[96:97]
	v_pk_add_f32 v[72:73], v[72:73], v[96:97] neg_lo:[0,1] neg_hi:[0,1]
	v_pk_mul_f32 v[96:97], v[74:75], s[44:45]
	v_bfrev_b32_e32 v36, v66
	v_pk_fma_f32 v[74:75], v[74:75], s[42:43], v[96:97] op_sel:[0,0,1] op_sel_hi:[1,0,0]
	v_pk_add_f32 v[96:97], v[76:77], v[100:101]
	v_pk_add_f32 v[76:77], v[76:77], v[100:101] neg_lo:[0,1] neg_hi:[0,1]
	v_ashrrev_i32_e32 v41, 31, v40
	v_pk_mul_f32 v[98:99], v[76:77], s[66:67]
	v_cvt_f32_ubyte3_e32 v36, v36
	v_pk_fma_f32 v[76:77], v[76:77], s[64:65], v[98:99] op_sel:[0,0,1] op_sel_hi:[1,0,0]
	v_pk_add_f32 v[98:99], v[78:79], v[102:103]
	v_pk_add_f32 v[78:79], v[78:79], v[102:103] neg_lo:[0,1] neg_hi:[0,1]
	v_lshlrev_b64 v[40:41], 15, v[40:41]
	v_pk_mul_f32 v[100:101], v[78:79], s[74:75]
	v_mul_f32_e32 v36, 0x38800000, v36
	v_pk_fma_f32 v[78:79], v[78:79], s[8:9], v[100:101] op_sel:[0,0,1] op_sel_hi:[1,0,0]
	s_waitcnt lgkmcnt(1)
	v_pk_add_f32 v[100:101], v[80:81], v[104:105]
	v_pk_add_f32 v[102:103], v[80:81], v[104:105] neg_lo:[0,1] neg_hi:[0,1]
	v_ashrrev_i32_e32 v67, 31, v66
	v_pk_add_f32 v[80:81], v[82:83], v[106:107]
	v_pk_add_f32 v[82:83], v[82:83], v[106:107] neg_lo:[0,1] neg_hi:[0,1]
	v_lshl_add_u64 v[40:41], s[18:19], 0, v[40:41]
	v_pk_mul_f32 v[104:105], v[82:83], s[74:75]
	v_pk_add_f32 v[60:61], v[60:61], v[70:71] neg_lo:[0,1] neg_hi:[0,1]
	v_pk_fma_f32 v[82:83], v[82:83], s[8:9], v[104:105] op_sel:[0,0,1] op_sel_hi:[1,0,0] neg_lo:[1,0,0] neg_hi:[1,0,0]
	s_waitcnt lgkmcnt(0)
	v_pk_add_f32 v[104:105], v[84:85], v[108:109]
	v_pk_add_f32 v[84:85], v[84:85], v[108:109] neg_lo:[0,1] neg_hi:[0,1]
	v_cndmask_b32_e64 v36, v36, v152, s[6:7]
	v_pk_mul_f32 v[106:107], v[84:85], s[66:67]
	v_lshl_add_u64 v[40:41], v[66:67], 3, v[40:41]
	v_pk_fma_f32 v[84:85], v[84:85], s[64:65], v[106:107] op_sel:[0,0,1] op_sel_hi:[1,0,0] neg_lo:[1,0,0] neg_hi:[1,0,0]
	v_pk_add_f32 v[106:107], v[86:87], v[110:111]
	v_pk_add_f32 v[86:87], v[86:87], v[110:111] neg_lo:[0,1] neg_hi:[0,1]
	v_xor_b32_e32 v71, 0x80000000, v60
	v_pk_mul_f32 v[108:109], v[86:87], s[44:45]
	v_pk_add_f32 v[46:47], v[46:47], v[54:55] neg_lo:[0,1] neg_hi:[0,1]
	v_pk_fma_f32 v[86:87], v[86:87], s[42:43], v[108:109] op_sel:[0,0,1] op_sel_hi:[1,0,0] neg_lo:[1,0,0] neg_hi:[1,0,0]
	v_pk_add_f32 v[108:109], v[88:89], v[100:101]
	v_pk_add_f32 v[88:89], v[88:89], v[100:101] neg_lo:[0,1] neg_hi:[0,1]
	v_pk_add_f32 v[100:101], v[92:93], v[80:81]
	v_pk_add_f32 v[80:81], v[92:93], v[80:81] neg_lo:[0,1] neg_hi:[0,1]
	v_mov_b32_e32 v70, v61
	v_pk_mul_f32 v[92:93], v[80:81], s[66:67]
	v_pk_add_f32 v[118:119], v[58:59], v[62:63]
	v_pk_fma_f32 v[80:81], v[80:81], s[64:65], v[92:93] op_sel:[0,0,1] op_sel_hi:[1,0,0]
	v_pk_add_f32 v[92:93], v[96:97], v[104:105]
	v_pk_add_f32 v[104:105], v[96:97], v[104:105] neg_lo:[0,1] neg_hi:[0,1]
	v_pk_add_f32 v[62:63], v[58:59], v[62:63] neg_lo:[0,1] neg_hi:[0,1]
	v_pk_add_f32 v[96:97], v[98:99], v[106:107]
	v_pk_add_f32 v[98:99], v[98:99], v[106:107] neg_lo:[0,1] neg_hi:[0,1]
	v_cos_f32_e32 v67, v36
	v_pk_mul_f32 v[106:107], v[98:99], s[66:67]
	v_cmp_ne_u32_e32 vcc, 0, v66
	v_pk_fma_f32 v[98:99], v[98:99], s[64:65], v[106:107] op_sel:[0,0,1] op_sel_hi:[1,0,0] neg_lo:[1,0,0] neg_hi:[1,0,0]
	v_pk_add_f32 v[106:107], v[72:73], v[102:103] op_sel:[0,1] op_sel_hi:[1,0] neg_hi:[0,1]
	v_pk_add_f32 v[72:73], v[72:73], v[102:103] op_sel:[0,1] op_sel_hi:[1,0] neg_lo:[0,1]
	v_pk_add_f32 v[102:103], v[74:75], v[82:83]
	v_pk_add_f32 v[74:75], v[74:75], v[82:83] neg_lo:[0,1] neg_hi:[0,1]
	v_xor_b32_e32 v55, 0x80000000, v46
	v_pk_mul_f32 v[82:83], v[74:75], s[66:67]
	v_pk_add_f32 v[116:117], v[64:65], v[70:71] neg_lo:[0,1] neg_hi:[0,1]
	v_pk_fma_f32 v[74:75], v[74:75], s[64:65], v[82:83] op_sel:[0,0,1] op_sel_hi:[1,0,0]
	v_pk_add_f32 v[82:83], v[76:77], v[84:85]
	v_pk_add_f32 v[84:85], v[76:77], v[84:85] neg_lo:[0,1] neg_hi:[0,1]
	v_xor_b32_e32 v121, 0x80000000, v62
	v_pk_add_f32 v[76:77], v[78:79], v[86:87]
	v_pk_add_f32 v[78:79], v[78:79], v[86:87] neg_lo:[0,1] neg_hi:[0,1]
	v_mov_b32_e32 v54, v47
	v_pk_mul_f32 v[86:87], v[78:79], s[66:67]
	v_mov_b32_e32 v120, v63
	v_pk_fma_f32 v[78:79], v[78:79], s[64:65], v[86:87] op_sel:[0,0,1] op_sel_hi:[1,0,0] neg_lo:[1,0,0] neg_hi:[1,0,0]
	v_pk_add_f32 v[86:87], v[108:109], v[92:93]
	v_pk_add_f32 v[92:93], v[108:109], v[92:93] neg_lo:[0,1] neg_hi:[0,1]
	v_pk_add_f32 v[108:109], v[100:101], v[96:97]
	v_pk_add_f32 v[96:97], v[100:101], v[96:97] neg_lo:[0,1] neg_hi:[0,1]
	v_sin_f32_e32 v66, v36
	v_pk_add_f32 v[60:61], v[64:65], v[70:71]
	v_pk_add_f32 v[126:127], v[42:43], v[54:55]
	v_pk_add_f32 v[128:129], v[42:43], v[54:55] neg_lo:[0,1] neg_hi:[0,1]
	v_pk_add_f32 v[42:43], v[44:45], v[48:49]
	v_pk_add_f32 v[48:49], v[44:45], v[48:49] neg_lo:[0,1] neg_hi:[0,1]
	v_pk_add_f32 v[94:95], v[56:57], v[90:91]
	v_pk_add_f32 v[90:91], v[56:57], v[90:91] neg_lo:[0,1] neg_hi:[0,1]
	v_pk_add_f32 v[70:71], v[114:115], v[112:113] op_sel:[0,1] op_sel_hi:[1,0] neg_hi:[0,1]
	v_pk_add_f32 v[64:65], v[114:115], v[112:113] op_sel:[0,1] op_sel_hi:[1,0] neg_lo:[0,1]
	v_pk_add_f32 v[56:57], v[116:117], v[120:121]
	v_pk_add_f32 v[62:63], v[116:117], v[120:121] neg_lo:[0,1] neg_hi:[0,1]
	v_xor_b32_e32 v101, 0x80000000, v96
	v_mov_b32_e32 v100, v97
	v_pk_add_f32 v[96:97], v[88:89], v[104:105] op_sel:[0,1] op_sel_hi:[1,0] neg_hi:[0,1]
	v_pk_add_f32 v[88:89], v[88:89], v[104:105] op_sel:[0,1] op_sel_hi:[1,0] neg_lo:[0,1]
	v_pk_add_f32 v[104:105], v[80:81], v[98:99]
	v_pk_add_f32 v[98:99], v[80:81], v[98:99] neg_lo:[0,1] neg_hi:[0,1]
	v_pk_add_f32 v[112:113], v[102:103], v[76:77]
	v_pk_add_f32 v[102:103], v[102:103], v[76:77] neg_lo:[0,1] neg_hi:[0,1]
	v_pk_add_f32 v[114:115], v[72:73], v[84:85] op_sel:[0,1] op_sel_hi:[1,0] neg_hi:[0,1]
	v_pk_add_f32 v[116:117], v[72:73], v[84:85] op_sel:[0,1] op_sel_hi:[1,0] neg_lo:[0,1]
	v_pk_add_f32 v[72:73], v[74:75], v[78:79] neg_lo:[0,1] neg_hi:[0,1]
	v_xor_b32_e32 v155, 0x80000000, v48
	v_pk_add_f32 v[68:69], v[60:61], v[118:119]
	v_pk_add_f32 v[58:59], v[60:61], v[118:119] neg_lo:[0,1] neg_hi:[0,1]
	v_mov_b32_e32 v154, v49
	v_pk_add_f32 v[110:111], v[106:107], v[82:83]
	v_pk_add_f32 v[106:107], v[106:107], v[82:83] neg_lo:[0,1] neg_hi:[0,1]
	v_pk_add_f32 v[118:119], v[74:75], v[78:79]
	v_xor_b32_e32 v121, 0x80000000, v72
	v_mov_b32_e32 v120, v73
	v_pk_add_f32 v[60:61], v[122:123], v[52:53]
	v_pk_add_f32 v[46:47], v[122:123], v[52:53] neg_lo:[0,1] neg_hi:[0,1]
	v_pk_add_f32 v[52:53], v[50:51], v[124:125]
	v_pk_add_f32 v[54:55], v[50:51], v[124:125] neg_lo:[0,1] neg_hi:[0,1]
	v_pk_add_f32 v[50:51], v[126:127], v[42:43]
	v_pk_add_f32 v[44:45], v[126:127], v[42:43] neg_lo:[0,1] neg_hi:[0,1]
	v_pk_add_f32 v[42:43], v[128:129], v[154:155]
	v_pk_add_f32 v[48:49], v[128:129], v[154:155] neg_lo:[0,1] neg_hi:[0,1]
	v_pk_add_f32 v[84:85], v[86:87], v[108:109]
	v_pk_add_f32 v[86:87], v[86:87], v[108:109] neg_lo:[0,1] neg_hi:[0,1]
	v_pk_add_f32 v[78:79], v[92:93], v[100:101]
	v_pk_add_f32 v[74:75], v[92:93], v[100:101] neg_lo:[0,1] neg_hi:[0,1]
	v_pk_add_f32 v[72:73], v[96:97], v[104:105]
	v_pk_add_f32 v[76:77], v[96:97], v[104:105] neg_lo:[0,1] neg_hi:[0,1]
	v_pk_add_f32 v[82:83], v[88:89], v[98:99] op_sel:[0,1] op_sel_hi:[1,0] neg_hi:[0,1]
	v_pk_add_f32 v[80:81], v[88:89], v[98:99] op_sel:[0,1] op_sel_hi:[1,0] neg_lo:[0,1]
	v_pk_add_f32 v[88:89], v[110:111], v[112:113]
	v_pk_add_f32 v[96:97], v[110:111], v[112:113] neg_lo:[0,1] neg_hi:[0,1]
	v_pk_add_f32 v[98:99], v[106:107], v[102:103] op_sel:[0,1] op_sel_hi:[1,0] neg_hi:[0,1]
	v_pk_add_f32 v[102:103], v[106:107], v[102:103] op_sel:[0,1] op_sel_hi:[1,0] neg_lo:[0,1]
	v_pk_add_f32 v[104:105], v[114:115], v[118:119]
	v_pk_add_f32 v[106:107], v[114:115], v[118:119] neg_lo:[0,1] neg_hi:[0,1]
	v_pk_add_f32 v[108:109], v[116:117], v[120:121]
	v_pk_add_f32 v[114:115], v[116:117], v[120:121] neg_lo:[0,1] neg_hi:[0,1]
	v_mul_f32_e32 v36, 0x3f3504f3, v67
	v_mul_f32_e32 v100, 0xbec3ef15, v67
	v_mul_f32_e32 v92, 0xbf6c835e, v67
	s_and_saveexec_b64 s[6:7], vcc
	s_xor_b64 s[6:7], exec, s[6:7]
	s_cbranch_execz .LBB0_434
	v_pk_add_f32 v[110:111], v[94:95], v[114:115]
	v_pk_add_f32 v[94:95], v[94:95], v[114:115] neg_lo:[0,1] neg_hi:[0,1]
	v_mul_f32_e32 v112, 0.5, v110
	v_pk_fma_f32 v[114:115], v[66:67], 0, v[66:67] op_sel:[0,0,1] op_sel_hi:[1,0,0] neg_lo:[1,0,0] neg_hi:[1,0,0]
	v_pk_fma_f32 v[116:117], v[66:67], 0, v[66:67] op_sel:[0,0,1] op_sel_hi:[1,0,0]
	v_mov_b32_e32 v110, v94
	v_mov_b32_e32 v115, v117
	v_pk_mul_f32 v[110:111], v[110:111], s[78:79]
	s_mov_b32 s8, s45
	v_pk_mul_f32 v[116:117], v[114:115], v[110:111] op_sel:[0,1] op_sel_hi:[1,0]
	v_pk_mul_f32 v[110:111], v[114:115], v[110:111]
	s_mov_b32 s9, s42
	v_sub_f32_e32 v93, v110, v111
	v_fma_mixlo_f16 v101, v95, s79, v93
	v_fma_f32 v93, v95, 0.5, -v93
	v_cvt_f16_f32_sdwa v93, -v93 dst_sel:WORD_1 dst_unused:UNUSED_PAD src0_sel:DWORD
	v_pk_add_f32 v[94:95], v[116:117], v[116:117] op_sel:[0,1] op_sel_hi:[0,1]
	v_pk_add_f32 v[110:111], v[112:113], v[94:95]
	v_pk_add_f32 v[94:95], v[112:113], v[94:95] op_sel_hi:[0,1] neg_lo:[0,1] neg_hi:[0,1]
	v_cvt_pk_f16_f32 v94, v110, v95
	v_lshlrev_b32_e32 v101, 16, v101
	v_or_b32_sdwa v95, v93, v94 dst_sel:DWORD dst_unused:UNUSED_PAD src0_sel:DWORD src1_sel:WORD_1
	v_or_b32_sdwa v94, v101, v94 dst_sel:DWORD dst_unused:UNUSED_PAD src0_sel:DWORD src1_sel:WORD_0
	global_store_dwordx2 v[40:41], v[94:95], off
	v_pk_add_f32 v[94:95], v[90:91], v[108:109]
	v_pk_add_f32 v[90:91], v[90:91], v[108:109] neg_lo:[0,1] neg_hi:[0,1]
	v_mul_f32_e32 v110, 0.5, v94
	v_mov_b32_e32 v94, v67
	v_mov_b32_e32 v108, v67
	v_mov_b32_e32 v109, v66
	v_pk_fma_f32 v[112:113], v[66:67], 0, v[108:109] op_sel_hi:[1,0,1] neg_lo:[0,0,1] neg_hi:[0,0,1]
	v_pk_fma_f32 v[114:115], v[66:67], 0, v[94:95] op_sel_hi:[1,0,1]
	v_mov_b32_e32 v94, v90
	v_pk_mov_b32 v[112:113], v[112:113], v[114:115] op_sel:[1,0]
	v_pk_mul_f32 v[94:95], v[94:95], s[78:79]
	s_mov_b32 s43, s45
	v_pk_mul_f32 v[114:115], v[112:113], v[94:95] op_sel:[0,1] op_sel_hi:[1,0]
	v_pk_mul_f32 v[94:95], v[112:113], v[94:95]
	v_pk_fma_f32 v[112:113], v[108:109], s[68:69], v[36:37] op_sel_hi:[1,1,0]
	v_sub_f32_e32 v90, v94, v95
	v_fma_mixlo_f16 v93, v91, s79, v90
	v_fma_f32 v90, v91, 0.5, -v90
	v_cvt_f16_f32_sdwa v101, -v90 dst_sel:WORD_1 dst_unused:UNUSED_PAD src0_sel:DWORD
	v_pk_add_f32 v[90:91], v[114:115], v[114:115] op_sel:[0,1] op_sel_hi:[0,1]
	v_pk_add_f32 v[94:95], v[110:111], v[90:91]
	v_pk_add_f32 v[90:91], v[110:111], v[90:91] op_sel_hi:[0,1] neg_lo:[0,1] neg_hi:[0,1]
	v_cvt_pk_f16_f32 v90, v94, v91
	v_lshlrev_b32_e32 v93, 16, v93
	v_or_b32_sdwa v91, v101, v90 dst_sel:DWORD dst_unused:UNUSED_PAD src0_sel:DWORD src1_sel:WORD_1
	v_or_b32_sdwa v90, v93, v90 dst_sel:DWORD dst_unused:UNUSED_PAD src0_sel:DWORD src1_sel:WORD_0
	global_store_dwordx2 v[40:41], v[90:91], off offset:2048
	v_pk_mul_f32 v[90:91], v[108:109], s[68:69]
	v_pk_add_f32 v[94:95], v[70:71], v[106:107]
	v_pk_add_f32 v[70:71], v[70:71], v[106:107] neg_lo:[0,1] neg_hi:[0,1]
	v_mul_f32_e32 v110, 0.5, v94
	v_pk_add_f32 v[106:107], v[36:37], v[90:91] op_sel:[0,1] op_sel_hi:[0,1] neg_lo:[0,1] neg_hi:[0,1]
	v_mov_b32_e32 v94, v70
	v_mov_b32_e32 v107, v113
	v_pk_mul_f32 v[94:95], v[94:95], s[78:79]
	v_mov_b32_e32 v101, v58
	v_pk_mul_f32 v[112:113], v[106:107], v[94:95] op_sel:[0,1] op_sel_hi:[1,0]
	v_pk_mul_f32 v[94:95], v[106:107], v[94:95]
	s_mov_b32 s39, s27
	v_sub_f32_e32 v36, v94, v95
	v_fma_mixlo_f16 v93, v71, s79, v36
	v_fma_f32 v36, v71, 0.5, -v36
	v_pk_add_f32 v[70:71], v[112:113], v[112:113] op_sel:[0,1] op_sel_hi:[0,1]
	v_cvt_f16_f32_sdwa v36, -v36 dst_sel:WORD_1 dst_unused:UNUSED_PAD src0_sel:DWORD
	v_pk_add_f32 v[94:95], v[110:111], v[70:71]
	v_pk_add_f32 v[70:71], v[110:111], v[70:71] op_sel_hi:[0,1] neg_lo:[0,1] neg_hi:[0,1]
	v_cvt_pk_f16_f32 v70, v94, v71
	v_add_co_u32_e32 v94, vcc, s34, v40
	v_lshlrev_b32_e32 v93, 16, v93
	s_nop 0
	v_addc_co_u32_e32 v95, vcc, 0, v41, vcc
	v_add_co_u32_e32 v110, vcc, s3, v40
	v_or_b32_sdwa v71, v36, v70 dst_sel:DWORD dst_unused:UNUSED_PAD src0_sel:DWORD src1_sel:WORD_1
	v_or_b32_sdwa v70, v93, v70 dst_sel:DWORD dst_unused:UNUSED_PAD src0_sel:DWORD src1_sel:WORD_0
	v_addc_co_u32_e32 v111, vcc, 0, v41, vcc
	global_store_dwordx2 v[110:111], v[70:71], off offset:-4096
	v_pk_fma_f32 v[70:71], v[108:109], s[68:69], v[90:91] op_sel:[0,0,1] op_sel_hi:[1,1,0] neg_lo:[0,0,1] neg_hi:[0,0,1]
	v_pk_add_f32 v[90:91], v[64:65], v[104:105]
	v_pk_add_f32 v[64:65], v[64:65], v[104:105] neg_lo:[0,1] neg_hi:[0,1]
	v_mul_f32_e32 v36, 0.5, v90
	v_mov_b32_e32 v90, v64
	v_pk_mul_f32 v[90:91], v[90:91], s[78:79]
	v_mov_b32_e32 v71, v106
	v_mov_b32_e32 v107, v70
	v_pk_mul_f32 v[70:71], v[70:71], v[90:91]
	v_pk_mul_f32 v[104:105], v[106:107], v[90:91]
	v_sub_f32_e32 v64, v70, v71
	v_fma_mixlo_f16 v90, v65, s79, v64
	v_fma_f32 v64, v65, 0.5, -v64
	v_cvt_f16_f32_sdwa v91, -v64 dst_sel:WORD_1 dst_unused:UNUSED_PAD src0_sel:DWORD
	v_pk_add_f32 v[64:65], v[104:105], v[104:105] op_sel:[1,0] op_sel_hi:[1,0]
	s_nop 0
	v_pk_add_f32 v[70:71], v[36:37], v[64:65]
	v_pk_add_f32 v[64:65], v[36:37], v[64:65] op_sel_hi:[0,1] neg_lo:[0,1] neg_hi:[0,1]
	v_cvt_pk_f16_f32 v36, v70, v65
	v_lshlrev_b32_e32 v64, 16, v90
	v_or_b32_sdwa v65, v91, v36 dst_sel:DWORD dst_unused:UNUSED_PAD src0_sel:DWORD src1_sel:WORD_1
	v_or_b32_sdwa v64, v64, v36 dst_sel:DWORD dst_unused:UNUSED_PAD src0_sel:DWORD src1_sel:WORD_0
	global_store_dwordx2 v[94:95], v[64:65], off offset:2048
	v_mov_b32_e32 v64, v67
	v_pk_mul_f32 v[70:71], v[66:67], s[8:9] op_sel_hi:[0,1]
	v_pk_add_f32 v[90:91], v[68:69], v[102:103]
	v_pk_add_f32 v[68:69], v[68:69], v[102:103] neg_lo:[0,1] neg_hi:[0,1]
	v_mul_f32_e32 v36, 0.5, v90
	v_pk_fma_f32 v[94:95], v[64:65], s[42:43], v[70:71] op_sel_hi:[0,1,1] neg_lo:[0,0,1] neg_hi:[0,0,1]
	v_pk_fma_f32 v[102:103], v[64:65], s[42:43], v[70:71] op_sel_hi:[0,1,1]
	v_mov_b32_e32 v90, v68
	v_mov_b32_e32 v104, v94
	v_mov_b32_e32 v105, v103
	v_pk_mul_f32 v[90:91], v[90:91], s[78:79]
	s_mov_b32 s8, s27
	v_pk_mul_f32 v[106:107], v[104:105], v[90:91] op_sel:[0,1] op_sel_hi:[1,0]
	v_pk_mul_f32 v[90:91], v[104:105], v[90:91]
	s_mov_b32 s9, s38
	v_sub_f32_e32 v65, v90, v91
	v_fma_mixlo_f16 v93, v69, s79, v65
	v_fma_f32 v65, v69, 0.5, -v65
	v_cvt_f16_f32_sdwa v65, -v65 dst_sel:WORD_1 dst_unused:UNUSED_PAD src0_sel:DWORD
	v_pk_add_f32 v[68:69], v[106:107], v[106:107] op_sel:[0,1] op_sel_hi:[0,1]
	v_pk_add_f32 v[90:91], v[36:37], v[68:69]
	v_pk_add_f32 v[68:69], v[36:37], v[68:69] op_sel_hi:[0,1] neg_lo:[0,1] neg_hi:[0,1]
	v_cvt_pk_f16_f32 v36, v90, v69
	v_lshlrev_b32_e32 v68, 16, v93
	v_or_b32_sdwa v69, v65, v36 dst_sel:DWORD dst_unused:UNUSED_PAD src0_sel:DWORD src1_sel:WORD_1
	v_or_b32_sdwa v68, v68, v36 dst_sel:DWORD dst_unused:UNUSED_PAD src0_sel:DWORD src1_sel:WORD_0
	global_store_dwordx2 v[110:111], v[68:69], off
	v_pk_add_f32 v[68:69], v[58:59], v[98:99]
	v_sub_f32_e32 v65, v59, v99
	v_pk_mov_b32 v[58:59], v[70:71], v[98:99] op_sel:[1,0]
	v_mul_f32_e32 v36, 0.5, v69
	v_pk_add_f32 v[58:59], v[100:101], v[58:59] neg_lo:[0,1] neg_hi:[0,1]
	v_mul_f32_e32 v90, 0.5, v68
	v_pk_mul_f32 v[98:99], v[58:59], v[36:37]
	v_mov_b32_e32 v93, v62
	v_mul_f32_e32 v58, v58, v99
	v_fma_f32 v36, -v94, v36, v58
	v_fma_mixlo_f16 v69, v65, s79, v36
	v_fma_f32 v36, v65, 0.5, -v36
	v_pk_fma_f32 v[100:101], v[94:95], v[98:99], v[98:99] op_sel:[0,1,0] op_sel_hi:[1,0,1]
	v_cvt_f16_f32_sdwa v36, -v36 dst_sel:WORD_1 dst_unused:UNUSED_PAD src0_sel:DWORD
	v_pk_add_f32 v[58:59], v[90:91], v[100:101]
	v_lshlrev_b32_e32 v65, 16, v69
	v_fma_f32 v59, v68, 0.5, -v100
	v_cvt_pk_f16_f32 v58, v58, v59
	v_or_b32_sdwa v59, v36, v58 dst_sel:DWORD dst_unused:UNUSED_PAD src0_sel:DWORD src1_sel:WORD_1
	v_or_b32_sdwa v58, v65, v58 dst_sel:DWORD dst_unused:UNUSED_PAD src0_sel:DWORD src1_sel:WORD_0
	global_store_dwordx2 v[110:111], v[58:59], off offset:2048
	v_pk_add_f32 v[58:59], v[96:97], v[56:57]
	v_pk_add_f32 v[56:57], v[56:57], v[96:97] neg_lo:[0,1] neg_hi:[0,1]
	v_mul_f32_e32 v36, 0.5, v58
	v_mov_b32_e32 v58, v56
	v_pk_mov_b32 v[68:69], v[94:95], v[102:103] op_sel:[1,0]
	v_pk_mul_f32 v[58:59], v[58:59], s[78:79]
	s_nop 0
	v_pk_mul_f32 v[90:91], v[68:69], v[58:59] op_sel:[0,1] op_sel_hi:[1,0]
	v_pk_mul_f32 v[58:59], v[68:69], v[58:59]
	s_nop 0
	v_sub_f32_e32 v56, v58, v59
	v_fma_mixlo_f16 v65, v57, s79, v56
	v_fma_f32 v56, v57, 0.5, -v56
	v_cvt_f16_f32_sdwa v71, -v56 dst_sel:WORD_1 dst_unused:UNUSED_PAD src0_sel:DWORD
	v_pk_add_f32 v[56:57], v[90:91], v[90:91] op_sel:[0,1] op_sel_hi:[0,1]
	v_pk_add_f32 v[58:59], v[36:37], v[56:57]
	v_pk_add_f32 v[56:57], v[36:37], v[56:57] op_sel_hi:[0,1] neg_lo:[0,1] neg_hi:[0,1]
	v_cvt_pk_f16_f32 v36, v58, v57
	v_add_co_u32_e32 v58, vcc, s35, v40
	v_lshlrev_b32_e32 v56, 16, v65
	s_nop 0
	v_addc_co_u32_e32 v59, vcc, 0, v41, vcc
	v_add_co_u32_e32 v90, vcc, s37, v40
	v_or_b32_sdwa v57, v71, v36 dst_sel:DWORD dst_unused:UNUSED_PAD src0_sel:DWORD src1_sel:WORD_1
	v_or_b32_sdwa v56, v56, v36 dst_sel:DWORD dst_unused:UNUSED_PAD src0_sel:DWORD src1_sel:WORD_0
	v_addc_co_u32_e32 v91, vcc, 0, v41, vcc
	global_store_dwordx2 v[90:91], v[56:57], off offset:-4096
	v_pk_add_f32 v[56:57], v[88:89], v[62:63]
	v_mov_b32_e32 v71, v88
	v_sub_f32_e32 v65, v63, v89
	v_mul_f32_e32 v36, 0.5, v57
	v_pk_add_f32 v[62:63], v[92:93], v[70:71] neg_lo:[0,1] neg_hi:[0,1]
	v_mul_f32_e32 v94, 0.5, v56
	v_pk_mul_f32 v[70:71], v[62:63], v[36:37]
	s_nop 0
	v_mul_f32_e32 v57, v62, v71
	v_fma_f32 v36, -v95, v36, v57
	v_fma_mixlo_f16 v57, v65, s79, v36
	v_fma_f32 v36, v65, 0.5, -v36
	v_cvt_f16_f32_sdwa v36, -v36 dst_sel:WORD_1 dst_unused:UNUSED_PAD src0_sel:DWORD
	v_pk_fma_f32 v[68:69], v[68:69], v[70:71], v[70:71] op_sel:[0,1,0] op_sel_hi:[1,0,1]
	s_nop 0
	v_pk_add_f32 v[62:63], v[94:95], v[68:69]
	v_fma_f32 v56, v56, 0.5, -v68
	v_cvt_pk_f16_f32 v56, v62, v56
	v_lshlrev_b32_e32 v62, 16, v57
	v_or_b32_sdwa v57, v36, v56 dst_sel:DWORD dst_unused:UNUSED_PAD src0_sel:DWORD src1_sel:WORD_1
	v_or_b32_sdwa v56, v62, v56 dst_sel:DWORD dst_unused:UNUSED_PAD src0_sel:DWORD src1_sel:WORD_0
	global_store_dwordx2 v[58:59], v[56:57], off offset:2048
	v_pk_mul_f32 v[56:57], v[66:67], s[38:39] op_sel_hi:[0,1]
	v_pk_add_f32 v[58:59], v[60:61], v[80:81]
	v_pk_add_f32 v[60:61], v[60:61], v[80:81] neg_lo:[0,1] neg_hi:[0,1]
	v_mul_f32_e32 v36, 0.5, v58
	v_pk_fma_f32 v[62:63], v[64:65], s[8:9], v[56:57] op_sel_hi:[0,1,1] neg_lo:[0,0,1] neg_hi:[0,0,1]
	v_pk_fma_f32 v[68:69], v[64:65], s[8:9], v[56:57] op_sel_hi:[0,1,1]
	v_mov_b32_e32 v58, v60
	v_mov_b32_e32 v70, v62
	v_mov_b32_e32 v71, v69
	v_pk_mul_f32 v[58:59], v[58:59], s[78:79]
	s_mov_b32 s8, s47
	v_pk_mul_f32 v[80:81], v[70:71], v[58:59] op_sel:[0,1] op_sel_hi:[1,0]
	v_pk_mul_f32 v[58:59], v[70:71], v[58:59]
	s_mov_b32 s9, s46
	v_sub_f32_e32 v58, v58, v59
	v_fma_mixlo_f16 v65, v61, s79, v58
	v_fma_f32 v58, v61, 0.5, -v58
	v_cvt_f16_f32_sdwa v70, -v58 dst_sel:WORD_1 dst_unused:UNUSED_PAD src0_sel:DWORD
	v_pk_add_f32 v[58:59], v[80:81], v[80:81] op_sel:[0,1] op_sel_hi:[0,1]
	v_pk_add_f32 v[60:61], v[36:37], v[58:59]
	v_pk_add_f32 v[58:59], v[36:37], v[58:59] op_sel_hi:[0,1] neg_lo:[0,1] neg_hi:[0,1]
	v_cvt_pk_f16_f32 v36, v60, v59
	v_lshlrev_b32_e32 v58, 16, v65
	v_or_b32_sdwa v59, v70, v36 dst_sel:DWORD dst_unused:UNUSED_PAD src0_sel:DWORD src1_sel:WORD_1
	v_or_b32_sdwa v58, v58, v36 dst_sel:DWORD dst_unused:UNUSED_PAD src0_sel:DWORD src1_sel:WORD_0
	global_store_dwordx2 v[90:91], v[58:59], off
	v_mul_f32_e32 v58, 0xbe47c5c2, v67
	v_pk_add_f32 v[60:61], v[46:47], v[82:83]
	v_sub_f32_e32 v65, v47, v83
	v_mov_b32_e32 v59, v46
	v_pk_mov_b32 v[46:47], v[56:57], v[82:83] op_sel:[1,0]
	v_mul_f32_e32 v36, 0.5, v61
	v_pk_add_f32 v[46:47], v[58:59], v[46:47] neg_lo:[0,1] neg_hi:[0,1]
	v_mul_f32_e32 v70, 0.5, v60
	v_pk_mul_f32 v[58:59], v[46:47], v[36:37]
	s_nop 0
	v_mul_f32_e32 v46, v46, v59
	v_fma_f32 v36, -v62, v36, v46
	v_fma_mixlo_f16 v57, v65, s79, v36
	v_fma_f32 v36, v65, 0.5, -v36
	v_pk_fma_f32 v[80:81], v[62:63], v[58:59], v[58:59] op_sel:[0,1,0] op_sel_hi:[1,0,1]
	v_cvt_f16_f32_sdwa v36, -v36 dst_sel:WORD_1 dst_unused:UNUSED_PAD src0_sel:DWORD
	v_pk_add_f32 v[46:47], v[70:71], v[80:81]
	v_lshlrev_b32_e32 v57, 16, v57
	v_fma_f32 v47, v60, 0.5, -v80
	v_cvt_pk_f16_f32 v46, v46, v47
	v_or_b32_sdwa v47, v36, v46 dst_sel:DWORD dst_unused:UNUSED_PAD src0_sel:DWORD src1_sel:WORD_1
	v_or_b32_sdwa v46, v57, v46 dst_sel:DWORD dst_unused:UNUSED_PAD src0_sel:DWORD src1_sel:WORD_0
	global_store_dwordx2 v[90:91], v[46:47], off offset:2048
	v_pk_mul_f32 v[46:47], v[66:67], s[8:9] op_sel_hi:[0,1]
	v_pk_add_f32 v[58:59], v[76:77], v[52:53]
	v_pk_add_f32 v[52:53], v[52:53], v[76:77] neg_lo:[0,1] neg_hi:[0,1]
	v_mul_f32_e32 v36, 0.5, v58
	v_pk_fma_f32 v[60:61], v[64:65], s[46:47], v[46:47] op_sel_hi:[0,1,1] neg_lo:[0,0,1] neg_hi:[0,0,1]
	v_pk_fma_f32 v[64:65], v[64:65], s[46:47], v[46:47] op_sel_hi:[0,1,1]
	v_mov_b32_e32 v58, v52
	v_mov_b32_e32 v70, v60
	v_mov_b32_e32 v71, v65
	v_pk_mul_f32 v[58:59], v[58:59], s[78:79]
	s_nop 0
	v_pk_mul_f32 v[76:77], v[70:71], v[58:59] op_sel:[0,1] op_sel_hi:[1,0]
	v_pk_mul_f32 v[58:59], v[70:71], v[58:59]
	s_nop 0
	v_sub_f32_e32 v52, v58, v59
	v_fma_mixlo_f16 v57, v53, s79, v52
	v_fma_f32 v52, v53, 0.5, -v52
	v_cvt_f16_f32_sdwa v66, -v52 dst_sel:WORD_1 dst_unused:UNUSED_PAD src0_sel:DWORD
	v_pk_add_f32 v[52:53], v[76:77], v[76:77] op_sel:[0,1] op_sel_hi:[0,1]
	v_pk_add_f32 v[58:59], v[36:37], v[52:53]
	v_pk_add_f32 v[52:53], v[36:37], v[52:53] op_sel_hi:[0,1] neg_lo:[0,1] neg_hi:[0,1]
	v_cvt_pk_f16_f32 v36, v58, v53
	v_add_co_u32_e32 v58, vcc, s51, v40
	v_lshlrev_b32_e32 v52, 16, v57
	s_nop 0
	v_addc_co_u32_e32 v59, vcc, 0, v41, vcc
	v_add_co_u32_e32 v70, vcc, s60, v40
	v_or_b32_sdwa v53, v66, v36 dst_sel:DWORD dst_unused:UNUSED_PAD src0_sel:DWORD src1_sel:WORD_1
	v_or_b32_sdwa v52, v52, v36 dst_sel:DWORD dst_unused:UNUSED_PAD src0_sel:DWORD src1_sel:WORD_0
	v_addc_co_u32_e32 v71, vcc, 0, v41, vcc
	global_store_dwordx2 v[70:71], v[52:53], off offset:-4096
	v_mul_f32_e32 v52, 0xbf54db31, v67
	v_pk_add_f32 v[76:77], v[72:73], v[54:55]
	v_sub_f32_e32 v57, v55, v73
	v_mov_b32_e32 v53, v54
	v_pk_mov_b32 v[54:55], v[46:47], v[72:73] op_sel:[1,0]
	v_mul_f32_e32 v36, 0.5, v77
	v_pk_add_f32 v[52:53], v[52:53], v[54:55] neg_lo:[0,1] neg_hi:[0,1]
	v_mul_f32_e32 v66, 0.5, v76
	v_pk_mul_f32 v[54:55], v[52:53], v[36:37]
	s_nop 0
	v_mul_f32_e32 v47, v52, v55
	v_fma_f32 v36, -v60, v36, v47
	v_fma_mixlo_f16 v47, v57, s79, v36
	v_fma_f32 v36, v57, 0.5, -v36
	v_pk_fma_f32 v[72:73], v[60:61], v[54:55], v[54:55] op_sel:[0,1,0] op_sel_hi:[1,0,1]
	v_cvt_f16_f32_sdwa v36, -v36 dst_sel:WORD_1 dst_unused:UNUSED_PAD src0_sel:DWORD
	v_pk_add_f32 v[52:53], v[66:67], v[72:73]
	v_lshlrev_b32_e32 v47, 16, v47
	v_fma_f32 v53, v76, 0.5, -v72
	v_cvt_pk_f16_f32 v52, v52, v53
	v_or_b32_sdwa v53, v36, v52 dst_sel:DWORD dst_unused:UNUSED_PAD src0_sel:DWORD src1_sel:WORD_1
	v_or_b32_sdwa v52, v47, v52 dst_sel:DWORD dst_unused:UNUSED_PAD src0_sel:DWORD src1_sel:WORD_0
	global_store_dwordx2 v[58:59], v[52:53], off offset:2048
	v_pk_add_f32 v[52:53], v[74:75], v[50:51]
	v_pk_add_f32 v[50:51], v[50:51], v[74:75] neg_lo:[0,1] neg_hi:[0,1]
	v_mul_f32_e32 v36, 0.5, v52
	v_mov_b32_e32 v52, v50
	v_pk_mov_b32 v[54:55], v[60:61], v[64:65] op_sel:[1,0]
	v_pk_mul_f32 v[52:53], v[52:53], s[78:79]
	s_nop 0
	v_pk_mul_f32 v[58:59], v[54:55], v[52:53] op_sel:[0,1] op_sel_hi:[1,0]
	v_pk_mul_f32 v[52:53], v[54:55], v[52:53]
	s_nop 0
	v_sub_f32_e32 v47, v52, v53
	v_fma_mixlo_f16 v57, v51, s79, v47
	v_fma_f32 v47, v51, 0.5, -v47
	v_cvt_f16_f32_sdwa v47, -v47 dst_sel:WORD_1 dst_unused:UNUSED_PAD src0_sel:DWORD
	v_pk_add_f32 v[50:51], v[58:59], v[58:59] op_sel:[0,1] op_sel_hi:[0,1]
	v_pk_add_f32 v[52:53], v[36:37], v[50:51]
	v_pk_add_f32 v[50:51], v[36:37], v[50:51] op_sel_hi:[0,1] neg_lo:[0,1] neg_hi:[0,1]
	v_cvt_pk_f16_f32 v36, v52, v51
	v_lshlrev_b32_e32 v50, 16, v57
	v_or_b32_sdwa v51, v47, v36 dst_sel:DWORD dst_unused:UNUSED_PAD src0_sel:DWORD src1_sel:WORD_1
	v_or_b32_sdwa v50, v50, v36 dst_sel:DWORD dst_unused:UNUSED_PAD src0_sel:DWORD src1_sel:WORD_0
	global_store_dwordx2 v[70:71], v[50:51], off
	v_mul_f32_e32 v50, 0xbf0e39da, v67
	v_pk_add_f32 v[52:53], v[78:79], v[44:45]
	v_mov_b32_e32 v51, v44
	v_mov_b32_e32 v47, v78
	v_sub_f32_e32 v57, v45, v79
	v_mul_f32_e32 v36, 0.5, v53
	v_pk_add_f32 v[44:45], v[50:51], v[46:47] neg_lo:[0,1] neg_hi:[0,1]
	v_mul_f32_e32 v58, 0.5, v52
	v_pk_mul_f32 v[46:47], v[44:45], v[36:37]
	s_nop 0
	v_mul_f32_e32 v44, v44, v47
	v_fma_f32 v36, -v61, v36, v44
	v_pk_fma_f32 v[50:51], v[54:55], v[46:47], v[46:47] op_sel:[0,1,0] op_sel_hi:[1,0,1]
	v_fma_mixlo_f16 v46, v57, s79, v36
	v_fma_f32 v36, v57, 0.5, -v36
	v_cvt_f16_f32_sdwa v36, -v36 dst_sel:WORD_1 dst_unused:UNUSED_PAD src0_sel:DWORD
	v_pk_add_f32 v[44:45], v[58:59], v[50:51]
	v_lshlrev_b32_e32 v46, 16, v46
	v_fma_f32 v45, v52, 0.5, -v50
	v_cvt_pk_f16_f32 v44, v44, v45
	v_or_b32_sdwa v45, v36, v44 dst_sel:DWORD dst_unused:UNUSED_PAD src0_sel:DWORD src1_sel:WORD_1
	v_or_b32_sdwa v44, v46, v44 dst_sel:DWORD dst_unused:UNUSED_PAD src0_sel:DWORD src1_sel:WORD_0
	global_store_dwordx2 v[70:71], v[44:45], off offset:2048
	v_pk_add_f32 v[44:45], v[86:87], v[42:43]
	v_pk_add_f32 v[42:43], v[42:43], v[86:87] neg_lo:[0,1] neg_hi:[0,1]
	v_mul_f32_e32 v36, 0.5, v44
	v_mov_b32_e32 v44, v42
	v_pk_mov_b32 v[46:47], v[62:63], v[68:69] op_sel:[1,0]
	v_pk_mul_f32 v[44:45], v[44:45], s[78:79]
	s_nop 0
	v_pk_mul_f32 v[50:51], v[46:47], v[44:45] op_sel:[0,1] op_sel_hi:[1,0]
	v_pk_mul_f32 v[44:45], v[46:47], v[44:45]
	s_nop 0
	v_sub_f32_e32 v42, v44, v45
	v_fma_mixlo_f16 v46, v43, s79, v42
	v_fma_f32 v42, v43, 0.5, -v42
	v_cvt_f16_f32_sdwa v47, -v42 dst_sel:WORD_1 dst_unused:UNUSED_PAD src0_sel:DWORD
	v_pk_add_f32 v[42:43], v[50:51], v[50:51] op_sel:[0,1] op_sel_hi:[0,1]
	v_pk_add_f32 v[44:45], v[36:37], v[42:43]
	v_pk_add_f32 v[42:43], v[36:37], v[42:43] op_sel_hi:[0,1] neg_lo:[0,1] neg_hi:[0,1]
	v_cvt_pk_f16_f32 v36, v44, v43
	v_lshlrev_b32_e32 v42, 16, v46
	v_or_b32_sdwa v43, v47, v36 dst_sel:DWORD dst_unused:UNUSED_PAD src0_sel:DWORD src1_sel:WORD_1
	v_pk_add_f32 v[44:45], v[48:49], v[84:85]
	v_pk_add_f32 v[46:47], v[48:49], v[84:85] neg_lo:[0,1] neg_hi:[0,1]
	v_mov_b32_e32 v48, v44
	v_mov_b32_e32 v49, v47
	v_mov_b32_e32 v47, v45
	v_pk_mul_f32 v[44:45], v[46:47], s[78:79]
	v_or_b32_sdwa v42, v42, v36 dst_sel:DWORD dst_unused:UNUSED_PAD src0_sel:DWORD src1_sel:WORD_0
	v_fma_f32 v36, v67, s26, -v56
	v_pk_mul_f32 v[46:47], v[62:63], v[44:45] op_sel:[1,0]
	s_nop 0
	v_pk_fma_f32 v[50:51], v[36:37], v[44:45], v[46:47] op_sel:[0,1,0] op_sel_hi:[1,0,1]
	v_pk_fma_f32 v[44:45], v[36:37], v[44:45], v[46:47] op_sel:[0,1,0] op_sel_hi:[0,0,1] neg_lo:[0,0,1] neg_hi:[0,0,1]
	v_mov_b32_e32 v51, v45
	v_pk_fma_f32 v[44:45], v[48:49], 0.5, v[50:51] op_sel_hi:[1,0,1]
	v_pk_fma_f32 v[112:113], v[48:49], 0.5, v[50:51] op_sel_hi:[1,0,1] neg_lo:[0,0,1] neg_hi:[0,0,1]
	v_cvt_f16_f32_e32 v36, v44
	v_cvt_f16_f32_sdwa v46, v45 dst_sel:WORD_1 dst_unused:UNUSED_PAD src0_sel:DWORD
	v_add_co_u32_e32 v44, vcc, s61, v40
	v_or_b32_e32 v110, v46, v36
	s_nop 0
	v_addc_co_u32_e32 v45, vcc, 0, v41, vcc
	global_store_dwordx2 v[44:45], v[42:43], off

.LBB0_499:
	v_mov_b32_e32 v2, v210
	s_mov_b32 s43, s8
	v_and_b32_e32 v3, 0x1ff, v2
	v_lshlrev_b32_e32 v2, 5, v2
	v_and_or_b32 v2, v2, s94, v3
	v_ashrrev_i32_e32 v4, 5, v2
	v_lshlrev_b32_e32 v2, 3, v2
	v_lshlrev_b32_e32 v4, 3, v4
	v_add3_u32 v18, 0, v2, v4
	ds_read_b64 v[128:129], v18
	ds_read_b64 v[134:135], v18 offset:4224
	ds_read_b64 v[136:137], v18 offset:8448
	ds_read_b64 v[138:139], v18 offset:12672
	ds_read_b64 v[140:141], v18 offset:16896
	ds_read_b64 v[142:143], v18 offset:21120
	ds_read_b64 v[132:133], v18 offset:25344
	ds_read_b64 v[130:131], v18 offset:29568
	ds_read_b64 v[144:145], v18 offset:33792
	ds_read_b64 v[148:149], v18 offset:38016
	ds_read_b64 v[150:151], v18 offset:42240
	ds_read_b64 v[152:153], v18 offset:46464
	s_waitcnt lgkmcnt(10)
	v_pk_mul_f32 v[162:163], v[134:135], s[10:11]
	s_mov_b32 s74, s11
	v_pk_fma_f32 v[162:163], v[134:135], s[8:9], v[162:163] op_sel:[0,0,1] op_sel_hi:[1,0,0]
	s_waitcnt lgkmcnt(2)
	v_pk_mul_f32 v[178:179], v[148:149], s[42:43]
	v_pk_add_f32 v[194:195], v[134:135], v[148:149]
	v_pk_add_f32 v[134:135], v[134:135], v[148:149] neg_lo:[0,1] neg_hi:[0,1]
	v_pk_mul_f32 v[164:165], v[136:137], s[18:19]
	s_mov_b32 s41, s16
	v_pk_fma_f32 v[178:179], v[148:149], s[74:75], v[178:179] op_sel:[0,0,1] op_sel_hi:[1,0,0] neg_lo:[1,0,0] neg_hi:[1,0,0]
	v_pk_mul_f32 v[148:149], v[134:135], s[18:19]
	v_pk_fma_f32 v[164:165], v[136:137], s[16:17], v[164:165] op_sel:[0,0,1] op_sel_hi:[1,0,0]
	s_mov_b32 s80, s19
	s_waitcnt lgkmcnt(1)
	v_pk_mul_f32 v[180:181], v[150:151], s[40:41]
	v_pk_fma_f32 v[134:135], v[134:135], s[16:17], v[148:149] op_sel:[0,0,1] op_sel_hi:[1,0,0]
	v_pk_add_f32 v[148:149], v[136:137], v[150:151]
	v_pk_add_f32 v[136:137], v[136:137], v[150:151] neg_lo:[0,1] neg_hi:[0,1]
	v_pk_mul_f32 v[166:167], v[138:139], s[26:27]
	s_mov_b32 s78, s37
	s_mov_b32 s39, s24
	v_pk_fma_f32 v[180:181], v[150:151], s[80:81], v[180:181] op_sel:[0,0,1] op_sel_hi:[1,0,0] neg_lo:[1,0,0] neg_hi:[1,0,0]
	v_pk_mul_f32 v[150:151], v[136:137], s[36:37]
	ds_read_b64 v[154:155], v18 offset:50688
	ds_read_b64 v[156:157], v18 offset:54912
	ds_read_b64 v[158:159], v18 offset:59136
	ds_read_b64 v[160:161], v18 offset:63360
	v_pk_fma_f32 v[166:167], v[138:139], s[24:25], v[166:167] op_sel:[0,0,1] op_sel_hi:[1,0,0]
	s_mov_b32 s0, s27
	s_waitcnt lgkmcnt(4)
	v_pk_mul_f32 v[182:183], v[152:153], s[38:39]
	v_pk_fma_f32 v[136:137], v[136:137], s[78:79], v[150:151] op_sel:[0,0,1] op_sel_hi:[1,0,0]
	v_pk_add_f32 v[150:151], v[138:139], v[152:153]
	v_pk_add_f32 v[138:139], v[138:139], v[152:153] neg_lo:[0,1] neg_hi:[0,1]
	v_pk_mul_f32 v[168:169], v[140:141], s[36:37]
	v_pk_fma_f32 v[182:183], v[152:153], s[0:1], v[182:183] op_sel:[0,0,1] op_sel_hi:[1,0,0] neg_lo:[1,0,0] neg_hi:[1,0,0]
	v_pk_mul_f32 v[152:153], v[138:139], s[40:41]
	v_pk_fma_f32 v[168:169], v[140:141], s[78:79], v[168:169] op_sel:[0,0,1] op_sel_hi:[1,0,0]
	v_pk_mul_f32 v[170:171], v[142:143], s[38:39]
	s_waitcnt lgkmcnt(3)
	v_pk_mul_f32 v[184:185], v[154:155], s[36:37]
	v_pk_fma_f32 v[138:139], v[138:139], s[80:81], v[152:153] op_sel:[0,0,1] op_sel_hi:[1,0,0]
	v_pk_add_f32 v[152:153], v[140:141], v[154:155]
	v_pk_add_f32 v[140:141], v[140:141], v[154:155] neg_lo:[0,1] neg_hi:[0,1]
	v_pk_fma_f32 v[170:171], v[142:143], s[0:1], v[170:171] op_sel:[0,0,1] op_sel_hi:[1,0,0]
	v_pk_fma_f32 v[184:185], v[154:155], s[78:79], v[184:185] op_sel:[0,0,1] op_sel_hi:[1,0,0] neg_lo:[1,0,0] neg_hi:[1,0,0]
	s_waitcnt lgkmcnt(2)
	v_pk_mul_f32 v[186:187], v[156:157], s[26:27]
	v_xor_b32_e32 v155, 0x80000000, v140
	v_mov_b32_e32 v154, v141
	v_pk_add_f32 v[140:141], v[142:143], v[156:157]
	v_pk_add_f32 v[142:143], v[142:143], v[156:157] neg_lo:[0,1] neg_hi:[0,1]
	v_pk_mul_f32 v[172:173], v[132:133], s[40:41]
	v_pk_fma_f32 v[186:187], v[156:157], s[24:25], v[186:187] op_sel:[0,0,1] op_sel_hi:[1,0,0] neg_lo:[1,0,0] neg_hi:[1,0,0]
	v_pk_mul_f32 v[156:157], v[142:143], s[40:41]
	v_pk_fma_f32 v[172:173], v[132:133], s[80:81], v[172:173] op_sel:[0,0,1] op_sel_hi:[1,0,0]
	s_waitcnt lgkmcnt(1)
	v_pk_mul_f32 v[188:189], v[158:159], s[18:19]
	v_pk_fma_f32 v[142:143], v[142:143], s[80:81], v[156:157] op_sel:[0,0,1] op_sel_hi:[1,0,0] neg_lo:[1,0,0] neg_hi:[1,0,0]
	v_pk_add_f32 v[156:157], v[132:133], v[158:159]
	v_pk_add_f32 v[132:133], v[132:133], v[158:159] neg_lo:[0,1] neg_hi:[0,1]
	v_pk_mul_f32 v[174:175], v[130:131], s[42:43]
	v_pk_fma_f32 v[188:189], v[158:159], s[16:17], v[188:189] op_sel:[0,0,1] op_sel_hi:[1,0,0] neg_lo:[1,0,0] neg_hi:[1,0,0]
	v_pk_mul_f32 v[158:159], v[132:133], s[36:37]
	v_pk_fma_f32 v[174:175], v[130:131], s[74:75], v[174:175] op_sel:[0,0,1] op_sel_hi:[1,0,0]
	s_waitcnt lgkmcnt(0)
	v_pk_mul_f32 v[190:191], v[160:161], s[10:11]
	v_pk_fma_f32 v[132:133], v[132:133], s[78:79], v[158:159] op_sel:[0,0,1] op_sel_hi:[1,0,0] neg_lo:[1,0,0] neg_hi:[1,0,0]
	v_pk_add_f32 v[158:159], v[130:131], v[160:161]
	v_pk_add_f32 v[130:131], v[130:131], v[160:161] neg_lo:[0,1] neg_hi:[0,1]
	v_xor_b32_e32 v177, 0x80000000, v144
	v_mov_b32_e32 v176, v145
	v_pk_fma_f32 v[190:191], v[160:161], s[8:9], v[190:191] op_sel:[0,0,1] op_sel_hi:[1,0,0] neg_lo:[1,0,0] neg_hi:[1,0,0]
	v_pk_mul_f32 v[160:161], v[130:131], s[18:19]
	v_pk_add_f32 v[192:193], v[128:129], v[144:145]
	v_pk_add_f32 v[144:145], v[128:129], v[144:145] neg_lo:[0,1] neg_hi:[0,1]
	v_pk_fma_f32 v[130:131], v[130:131], s[16:17], v[160:161] op_sel:[0,0,1] op_sel_hi:[1,0,0] neg_lo:[1,0,0] neg_hi:[1,0,0]
	v_pk_add_f32 v[160:161], v[128:129], v[176:177]
	v_pk_add_f32 v[128:129], v[128:129], v[176:177] neg_lo:[0,1] neg_hi:[0,1]
	v_pk_add_f32 v[176:177], v[162:163], v[178:179]
	v_pk_add_f32 v[162:163], v[162:163], v[178:179] neg_lo:[0,1] neg_hi:[0,1]
	v_cvt_f32_u32_e32 v2, v3
	v_pk_mul_f32 v[178:179], v[162:163], s[18:19]
	s_add_i32 s76, s72, s48
	v_pk_fma_f32 v[162:163], v[162:163], s[16:17], v[178:179] op_sel:[0,0,1] op_sel_hi:[1,0,0]
	v_pk_add_f32 v[178:179], v[164:165], v[180:181]
	v_pk_add_f32 v[164:165], v[164:165], v[180:181] neg_lo:[0,1] neg_hi:[0,1]
	v_mul_f32_e32 v2, 0x38800000, v2
	v_pk_mul_f32 v[180:181], v[164:165], s[36:37]
	v_sin_f32_e32 v34, v2
	v_pk_fma_f32 v[164:165], v[164:165], s[78:79], v[180:181] op_sel:[0,0,1] op_sel_hi:[1,0,0]
	v_pk_add_f32 v[180:181], v[166:167], v[182:183]
	v_pk_add_f32 v[166:167], v[166:167], v[182:183] neg_lo:[0,1] neg_hi:[0,1]
	v_cos_f32_e32 v30, v2
	v_pk_mul_f32 v[182:183], v[166:167], s[40:41]
	v_xor_b32_e32 v31, 0x80000000, v34
	v_pk_fma_f32 v[166:167], v[166:167], s[80:81], v[182:183] op_sel:[0,0,1] op_sel_hi:[1,0,0]
	v_pk_add_f32 v[182:183], v[168:169], v[184:185]
	v_pk_add_f32 v[184:185], v[168:169], v[184:185] neg_lo:[0,1] neg_hi:[0,1]
	v_mov_b32_e32 v35, v31
	v_pk_add_f32 v[168:169], v[170:171], v[186:187]
	v_pk_add_f32 v[170:171], v[170:171], v[186:187] neg_lo:[0,1] neg_hi:[0,1]
	v_pk_mul_f32 v[2:3], v[30:31], v[34:35] op_sel:[1,0] op_sel_hi:[0,1]
	v_pk_mul_f32 v[186:187], v[170:171], s[40:41]
	v_pk_fma_f32 v[44:45], v[30:31], v[30:31], v[2:3] op_sel_hi:[1,0,1]
	v_pk_fma_f32 v[170:171], v[170:171], s[80:81], v[186:187] op_sel:[0,0,1] op_sel_hi:[1,0,0] neg_lo:[1,0,0] neg_hi:[1,0,0]
	v_pk_add_f32 v[186:187], v[172:173], v[188:189]
	v_pk_add_f32 v[172:173], v[172:173], v[188:189] neg_lo:[0,1] neg_hi:[0,1]
	v_pk_mul_f32 v[2:3], v[34:35], v[44:45] op_sel:[0,1] op_sel_hi:[1,0]
	v_pk_mul_f32 v[188:189], v[172:173], s[36:37]
	v_xor_b32_e32 v54, 0x80000000, v45
	v_pk_fma_f32 v[172:173], v[172:173], s[78:79], v[188:189] op_sel:[0,0,1] op_sel_hi:[1,0,0] neg_lo:[1,0,0] neg_hi:[1,0,0]
	v_pk_add_f32 v[188:189], v[174:175], v[190:191]
	v_pk_add_f32 v[174:175], v[174:175], v[190:191] neg_lo:[0,1] neg_hi:[0,1]
	v_mov_b32_e32 v55, v45
	v_pk_mul_f32 v[190:191], v[174:175], s[18:19]
	v_pk_fma_f32 v[46:47], v[30:31], v[44:45], v[2:3] op_sel_hi:[0,1,1]
	v_pk_fma_f32 v[174:175], v[174:175], s[16:17], v[190:191] op_sel:[0,0,1] op_sel_hi:[1,0,0] neg_lo:[1,0,0] neg_hi:[1,0,0]
	v_pk_add_f32 v[190:191], v[192:193], v[152:153]
	v_pk_add_f32 v[152:153], v[192:193], v[152:153] neg_lo:[0,1] neg_hi:[0,1]
	v_pk_add_f32 v[192:193], v[194:195], v[140:141]
	v_pk_add_f32 v[140:141], v[194:195], v[140:141] neg_lo:[0,1] neg_hi:[0,1]
	v_pk_mul_f32 v[2:3], v[44:45], v[54:55] op_sel:[1,0] op_sel_hi:[0,1]
	v_pk_mul_f32 v[194:195], v[140:141], s[36:37]
	v_pk_fma_f32 v[52:53], v[44:45], v[44:45], v[2:3] op_sel_hi:[1,0,1]
	v_pk_fma_f32 v[140:141], v[140:141], s[78:79], v[194:195] op_sel:[0,0,1] op_sel_hi:[1,0,0]
	v_pk_add_f32 v[194:195], v[148:149], v[156:157]
	v_pk_add_f32 v[156:157], v[148:149], v[156:157] neg_lo:[0,1] neg_hi:[0,1]
	v_xor_b32_e32 v58, 0x80000000, v53
	v_pk_add_f32 v[148:149], v[150:151], v[158:159]
	v_pk_add_f32 v[150:151], v[150:151], v[158:159] neg_lo:[0,1] neg_hi:[0,1]
	v_mov_b32_e32 v59, v53
	v_pk_mul_f32 v[158:159], v[150:151], s[36:37]
	v_pk_mul_f32 v[2:3], v[52:53], v[58:59] op_sel:[1,0] op_sel_hi:[0,1]
	v_pk_fma_f32 v[150:151], v[150:151], s[78:79], v[158:159] op_sel:[0,0,1] op_sel_hi:[1,0,0] neg_lo:[1,0,0] neg_hi:[1,0,0]
	v_pk_add_f32 v[158:159], v[144:145], v[154:155]
	v_pk_add_f32 v[144:145], v[144:145], v[154:155] neg_lo:[0,1] neg_hi:[0,1]
	v_pk_add_f32 v[154:155], v[134:135], v[142:143]
	v_pk_add_f32 v[134:135], v[134:135], v[142:143] neg_lo:[0,1] neg_hi:[0,1]
	v_pk_fma_f32 v[48:49], v[52:53], v[52:53], v[2:3] op_sel_hi:[1,0,1]
	v_pk_mul_f32 v[142:143], v[134:135], s[36:37]
	v_pk_mul_f32 v[2:3], v[58:59], v[48:49] op_sel:[0,1] op_sel_hi:[1,0]
	v_pk_fma_f32 v[134:135], v[134:135], s[78:79], v[142:143] op_sel:[0,0,1] op_sel_hi:[1,0,0]
	v_pk_add_f32 v[142:143], v[136:137], v[132:133]
	v_pk_add_f32 v[136:137], v[136:137], v[132:133] neg_lo:[0,1] neg_hi:[0,1]
	v_pk_fma_f32 v[36:37], v[52:53], v[48:49], v[2:3] op_sel_hi:[0,1,1]
	v_pk_add_f32 v[132:133], v[138:139], v[130:131]
	v_pk_add_f32 v[130:131], v[138:139], v[130:131] neg_lo:[0,1] neg_hi:[0,1]
	v_pk_mul_f32 v[2:3], v[58:59], v[36:37] op_sel:[0,1] op_sel_hi:[1,0]
	v_pk_mul_f32 v[138:139], v[130:131], s[36:37]
	v_pk_fma_f32 v[26:27], v[52:53], v[36:37], v[2:3] op_sel_hi:[0,1,1]
	v_pk_fma_f32 v[130:131], v[130:131], s[78:79], v[138:139] op_sel:[0,0,1] op_sel_hi:[1,0,0] neg_lo:[1,0,0] neg_hi:[1,0,0]
	v_pk_add_f32 v[138:139], v[160:161], v[182:183]
	v_pk_add_f32 v[160:161], v[160:161], v[182:183] neg_lo:[0,1] neg_hi:[0,1]
	v_pk_add_f32 v[182:183], v[176:177], v[168:169]
	v_pk_add_f32 v[168:169], v[176:177], v[168:169] neg_lo:[0,1] neg_hi:[0,1]
	v_pk_mul_f32 v[2:3], v[58:59], v[26:27] op_sel:[0,1] op_sel_hi:[1,0]
	v_pk_mul_f32 v[176:177], v[168:169], s[36:37]
	v_pk_fma_f32 v[20:21], v[52:53], v[26:27], v[2:3] op_sel_hi:[0,1,1]
	v_pk_fma_f32 v[168:169], v[168:169], s[78:79], v[176:177] op_sel:[0,0,1] op_sel_hi:[1,0,0]
	v_pk_add_f32 v[176:177], v[178:179], v[186:187]
	v_pk_add_f32 v[186:187], v[178:179], v[186:187] neg_lo:[0,1] neg_hi:[0,1]
	v_pk_mul_f32 v[2:3], v[58:59], v[20:21] op_sel:[0,1] op_sel_hi:[1,0]
	v_pk_add_f32 v[178:179], v[180:181], v[188:189]
	v_pk_add_f32 v[180:181], v[180:181], v[188:189] neg_lo:[0,1] neg_hi:[0,1]
	v_pk_fma_f32 v[10:11], v[52:53], v[20:21], v[2:3] op_sel_hi:[0,1,1]
	v_pk_mul_f32 v[188:189], v[180:181], s[36:37]
	v_pk_mul_f32 v[2:3], v[58:59], v[10:11] op_sel:[0,1] op_sel_hi:[1,0]
	v_pk_fma_f32 v[180:181], v[180:181], s[78:79], v[188:189] op_sel:[0,0,1] op_sel_hi:[1,0,0] neg_lo:[1,0,0] neg_hi:[1,0,0]
	v_pk_add_f32 v[188:189], v[128:129], v[184:185] op_sel:[0,1] op_sel_hi:[1,0] neg_hi:[0,1]
	v_pk_add_f32 v[128:129], v[128:129], v[184:185] op_sel:[0,1] op_sel_hi:[1,0] neg_lo:[0,1]
	v_pk_add_f32 v[184:185], v[162:163], v[170:171]
	v_pk_add_f32 v[162:163], v[162:163], v[170:171] neg_lo:[0,1] neg_hi:[0,1]
	v_pk_fma_f32 v[4:5], v[52:53], v[10:11], v[2:3] op_sel_hi:[0,1,1]
	v_pk_mul_f32 v[170:171], v[162:163], s[36:37]
	v_pk_mul_f32 v[8:9], v[54:55], v[4:5] op_sel:[0,1] op_sel_hi:[1,0]
	v_pk_fma_f32 v[162:163], v[162:163], s[78:79], v[170:171] op_sel:[0,0,1] op_sel_hi:[1,0,0]
	v_pk_add_f32 v[170:171], v[164:165], v[172:173]
	v_pk_add_f32 v[172:173], v[164:165], v[172:173] neg_lo:[0,1] neg_hi:[0,1]
	v_pk_mul_f32 v[14:15], v[34:35], v[4:5] op_sel:[0,1] op_sel_hi:[1,0]
	v_pk_add_f32 v[164:165], v[166:167], v[174:175]
	v_pk_add_f32 v[166:167], v[166:167], v[174:175] neg_lo:[0,1] neg_hi:[0,1]
	v_pk_mul_f32 v[32:33], v[54:55], v[10:11] op_sel:[0,1] op_sel_hi:[1,0]
	v_pk_mul_f32 v[174:175], v[166:167], s[36:37]
	v_pk_mul_f32 v[40:41], v[34:35], v[10:11] op_sel:[0,1] op_sel_hi:[1,0]
	v_pk_fma_f32 v[166:167], v[166:167], s[78:79], v[174:175] op_sel:[0,0,1] op_sel_hi:[1,0,0] neg_lo:[1,0,0] neg_hi:[1,0,0]
	v_pk_add_f32 v[174:175], v[190:191], v[194:195]
	v_pk_add_f32 v[190:191], v[190:191], v[194:195] neg_lo:[0,1] neg_hi:[0,1]
	v_pk_add_f32 v[194:195], v[192:193], v[148:149]
	v_pk_add_f32 v[192:193], v[192:193], v[148:149] neg_lo:[0,1] neg_hi:[0,1]
	v_pk_mul_f32 v[62:63], v[54:55], v[20:21] op_sel:[0,1] op_sel_hi:[1,0]
	v_pk_add_f32 v[148:149], v[152:153], v[156:157] op_sel:[0,1] op_sel_hi:[1,0] neg_hi:[0,1]
	v_pk_add_f32 v[152:153], v[152:153], v[156:157] op_sel:[0,1] op_sel_hi:[1,0] neg_lo:[0,1]
	v_pk_add_f32 v[156:157], v[140:141], v[150:151]
	v_pk_add_f32 v[150:151], v[140:141], v[150:151] neg_lo:[0,1] neg_hi:[0,1]
	v_pk_mul_f32 v[66:67], v[34:35], v[20:21] op_sel:[0,1] op_sel_hi:[1,0]
	v_pk_add_f32 v[140:141], v[158:159], v[142:143]
	v_pk_add_f32 v[142:143], v[158:159], v[142:143] neg_lo:[0,1] neg_hi:[0,1]
	v_pk_add_f32 v[158:159], v[154:155], v[132:133]
	v_pk_add_f32 v[154:155], v[154:155], v[132:133] neg_lo:[0,1] neg_hi:[0,1]
	v_pk_mul_f32 v[78:79], v[54:55], v[26:27] op_sel:[0,1] op_sel_hi:[1,0]
	v_pk_add_f32 v[132:133], v[144:145], v[136:137] op_sel:[0,1] op_sel_hi:[1,0] neg_hi:[0,1]
	v_pk_add_f32 v[136:137], v[144:145], v[136:137] op_sel:[0,1] op_sel_hi:[1,0] neg_lo:[0,1]
	v_pk_add_f32 v[144:145], v[134:135], v[130:131]
	v_pk_add_f32 v[134:135], v[134:135], v[130:131] neg_lo:[0,1] neg_hi:[0,1]
	v_pk_mul_f32 v[82:83], v[34:35], v[26:27] op_sel:[0,1] op_sel_hi:[1,0]
	v_pk_add_f32 v[130:131], v[138:139], v[176:177]
	v_pk_add_f32 v[138:139], v[138:139], v[176:177] neg_lo:[0,1] neg_hi:[0,1]
	v_pk_add_f32 v[176:177], v[182:183], v[178:179]
	v_pk_add_f32 v[182:183], v[182:183], v[178:179] neg_lo:[0,1] neg_hi:[0,1]
	v_pk_mul_f32 v[92:93], v[54:55], v[36:37] op_sel:[0,1] op_sel_hi:[1,0]
	v_pk_add_f32 v[178:179], v[160:161], v[186:187] op_sel:[0,1] op_sel_hi:[1,0] neg_hi:[0,1]
	v_pk_add_f32 v[160:161], v[160:161], v[186:187] op_sel:[0,1] op_sel_hi:[1,0] neg_lo:[0,1]
	v_pk_add_f32 v[186:187], v[168:169], v[180:181]
	v_pk_add_f32 v[180:181], v[168:169], v[180:181] neg_lo:[0,1] neg_hi:[0,1]
	v_pk_mul_f32 v[96:97], v[34:35], v[36:37] op_sel:[0,1] op_sel_hi:[1,0]
	v_pk_add_f32 v[168:169], v[188:189], v[170:171]
	v_pk_add_f32 v[170:171], v[188:189], v[170:171] neg_lo:[0,1] neg_hi:[0,1]
	v_pk_add_f32 v[188:189], v[184:185], v[164:165]
	v_pk_add_f32 v[184:185], v[184:185], v[164:165] neg_lo:[0,1] neg_hi:[0,1]
	v_pk_mul_f32 v[106:107], v[54:55], v[48:49] op_sel:[0,1] op_sel_hi:[1,0]
	v_pk_add_f32 v[164:165], v[128:129], v[172:173] op_sel:[0,1] op_sel_hi:[1,0] neg_hi:[0,1]
	v_pk_add_f32 v[128:129], v[128:129], v[172:173] op_sel:[0,1] op_sel_hi:[1,0] neg_lo:[0,1]
	v_pk_add_f32 v[172:173], v[162:163], v[166:167]
	v_pk_add_f32 v[162:163], v[162:163], v[166:167] neg_lo:[0,1] neg_hi:[0,1]
	v_pk_mul_f32 v[110:111], v[34:35], v[48:49] op_sel:[0,1] op_sel_hi:[1,0]
	v_xor_b32_e32 v167, 0x80000000, v162
	v_mov_b32_e32 v166, v163
	v_pk_add_f32 v[162:163], v[174:175], v[194:195]
	v_pk_add_f32 v[174:175], v[174:175], v[194:195] neg_lo:[0,1] neg_hi:[0,1]
	v_pk_add_f32 v[194:195], v[190:191], v[192:193] op_sel:[0,1] op_sel_hi:[1,0] neg_hi:[0,1]
	v_pk_add_f32 v[190:191], v[190:191], v[192:193] op_sel:[0,1] op_sel_hi:[1,0] neg_lo:[0,1]
	v_pk_add_f32 v[192:193], v[148:149], v[156:157]
	v_pk_add_f32 v[148:149], v[148:149], v[156:157] neg_lo:[0,1] neg_hi:[0,1]
	v_pk_add_f32 v[156:157], v[152:153], v[150:151] op_sel:[0,1] op_sel_hi:[1,0] neg_hi:[0,1]
	v_pk_add_f32 v[150:151], v[152:153], v[150:151] op_sel:[0,1] op_sel_hi:[1,0] neg_lo:[0,1]
	v_pk_add_f32 v[152:153], v[140:141], v[158:159]
	v_pk_add_f32 v[140:141], v[140:141], v[158:159] neg_lo:[0,1] neg_hi:[0,1]
	v_pk_add_f32 v[158:159], v[142:143], v[154:155] op_sel:[0,1] op_sel_hi:[1,0] neg_hi:[0,1]
	v_pk_add_f32 v[142:143], v[142:143], v[154:155] op_sel:[0,1] op_sel_hi:[1,0] neg_lo:[0,1]
	v_pk_add_f32 v[154:155], v[132:133], v[144:145]
	v_pk_add_f32 v[132:133], v[132:133], v[144:145] neg_lo:[0,1] neg_hi:[0,1]
	v_pk_add_f32 v[144:145], v[136:137], v[134:135] op_sel:[0,1] op_sel_hi:[1,0] neg_hi:[0,1]
	v_pk_add_f32 v[134:135], v[136:137], v[134:135] op_sel:[0,1] op_sel_hi:[1,0] neg_lo:[0,1]
	v_pk_add_f32 v[136:137], v[130:131], v[176:177]
	v_pk_mul_f32 v[120:121], v[54:55], v[52:53] op_sel:[0,1] op_sel_hi:[1,0]
	v_pk_mul_f32 v[124:125], v[34:35], v[52:53] op_sel:[0,1] op_sel_hi:[1,0]
	v_pk_mul_f32 v[34:35], v[34:35], v[136:137] op_sel:[0,1] op_sel_hi:[1,0]
	v_xor_b32_e32 v72, 0x80000000, v47
	v_mov_b32_e32 v73, v47
	v_pk_fma_f32 v[8:9], v[44:45], v[4:5], v[8:9] op_sel_hi:[0,1,1]
	v_pk_fma_f32 v[14:15], v[30:31], v[4:5], v[14:15] op_sel_hi:[0,1,1]
	v_xor_b32_e32 v22, 0x80000000, v5
	v_pk_fma_f32 v[32:33], v[44:45], v[10:11], v[32:33] op_sel_hi:[0,1,1]
	v_pk_fma_f32 v[40:41], v[30:31], v[10:11], v[40:41] op_sel_hi:[0,1,1]
	v_pk_fma_f32 v[62:63], v[44:45], v[20:21], v[62:63] op_sel_hi:[0,1,1]
	v_pk_fma_f32 v[66:67], v[30:31], v[20:21], v[66:67] op_sel_hi:[0,1,1]
	v_pk_fma_f32 v[78:79], v[44:45], v[26:27], v[78:79] op_sel_hi:[0,1,1]
	v_pk_fma_f32 v[82:83], v[30:31], v[26:27], v[82:83] op_sel_hi:[0,1,1]
	v_pk_fma_f32 v[92:93], v[44:45], v[36:37], v[92:93] op_sel_hi:[0,1,1]
	v_pk_fma_f32 v[96:97], v[30:31], v[36:37], v[96:97] op_sel_hi:[0,1,1]
	v_pk_fma_f32 v[106:107], v[44:45], v[48:49], v[106:107] op_sel_hi:[0,1,1]
	v_pk_fma_f32 v[110:111], v[30:31], v[48:49], v[110:111] op_sel_hi:[0,1,1]
	v_pk_fma_f32 v[120:121], v[44:45], v[52:53], v[120:121] op_sel_hi:[0,1,1]
	v_pk_fma_f32 v[124:125], v[30:31], v[52:53], v[124:125] op_sel_hi:[0,1,1]
	v_mov_b32_e32 v23, v5
	v_pk_add_f32 v[130:131], v[130:131], v[176:177] neg_lo:[0,1] neg_hi:[0,1]
	v_pk_add_f32 v[176:177], v[138:139], v[182:183] op_sel:[0,1] op_sel_hi:[1,0] neg_hi:[0,1]
	v_pk_add_f32 v[138:139], v[138:139], v[182:183] op_sel:[0,1] op_sel_hi:[1,0] neg_lo:[0,1]
	v_pk_add_f32 v[182:183], v[178:179], v[186:187]
	v_pk_add_f32 v[178:179], v[178:179], v[186:187] neg_lo:[0,1] neg_hi:[0,1]
	v_pk_add_f32 v[186:187], v[160:161], v[180:181] op_sel:[0,1] op_sel_hi:[1,0] neg_hi:[0,1]
	v_pk_add_f32 v[160:161], v[160:161], v[180:181] op_sel:[0,1] op_sel_hi:[1,0] neg_lo:[0,1]
	v_pk_add_f32 v[180:181], v[168:169], v[188:189]
	v_pk_fma_f32 v[30:31], v[30:31], v[136:137], v[34:35] op_sel_hi:[0,1,1]
	v_pk_mul_f32 v[34:35], v[54:55], v[152:153] op_sel:[0,1] op_sel_hi:[1,0]
	v_pk_mul_f32 v[2:3], v[72:73], v[4:5] op_sel:[0,1] op_sel_hi:[1,0]
	v_xor_b32_e32 v12, 0x80000000, v9
	v_pk_mul_f32 v[24:25], v[72:73], v[10:11] op_sel:[0,1] op_sel_hi:[1,0]
	v_xor_b32_e32 v38, 0x80000000, v33
	v_xor_b32_e32 v50, 0x80000000, v11
	v_pk_mul_f32 v[56:57], v[72:73], v[20:21] op_sel:[0,1] op_sel_hi:[1,0]
	v_xor_b32_e32 v64, 0x80000000, v63
	v_xor_b32_e32 v70, 0x80000000, v21
	v_pk_mul_f32 v[74:75], v[72:73], v[26:27] op_sel:[0,1] op_sel_hi:[1,0]
	v_xor_b32_e32 v80, 0x80000000, v79
	v_xor_b32_e32 v86, 0x80000000, v27
	v_pk_mul_f32 v[88:89], v[72:73], v[36:37] op_sel:[0,1] op_sel_hi:[1,0]
	v_xor_b32_e32 v94, 0x80000000, v93
	v_xor_b32_e32 v100, 0x80000000, v37
	v_pk_mul_f32 v[102:103], v[72:73], v[48:49] op_sel:[0,1] op_sel_hi:[1,0]
	v_xor_b32_e32 v108, 0x80000000, v107
	v_xor_b32_e32 v114, 0x80000000, v49
	v_pk_mul_f32 v[116:117], v[52:53], v[72:73] op_sel:[1,0] op_sel_hi:[0,1]
	v_xor_b32_e32 v122, 0x80000000, v121
	v_mov_b32_e32 v123, v121
	v_mov_b32_e32 v115, v49
	v_mov_b32_e32 v109, v107
	v_mov_b32_e32 v101, v37
	v_mov_b32_e32 v95, v93
	v_mov_b32_e32 v87, v27
	v_mov_b32_e32 v81, v79
	v_mov_b32_e32 v71, v21
	v_mov_b32_e32 v65, v63
	v_mov_b32_e32 v51, v11
	v_mov_b32_e32 v39, v33
	v_mov_b32_e32 v13, v9
	v_pk_fma_f32 v[34:35], v[44:45], v[152:153], v[34:35] op_sel_hi:[0,1,1]
	v_pk_mul_f32 v[44:45], v[72:73], v[180:181] op_sel:[0,1] op_sel_hi:[1,0]
	v_pk_mul_f32 v[22:23], v[150:151], v[22:23] op_sel:[1,0] op_sel_hi:[0,1]
	v_pk_fma_f32 v[2:3], v[46:47], v[4:5], v[2:3] op_sel_hi:[0,1,1]
	v_pk_fma_f32 v[24:25], v[46:47], v[10:11], v[24:25] op_sel_hi:[0,1,1]
	v_pk_fma_f32 v[56:57], v[46:47], v[20:21], v[56:57] op_sel_hi:[0,1,1]
	v_pk_fma_f32 v[74:75], v[46:47], v[26:27], v[74:75] op_sel_hi:[0,1,1]
	v_xor_b32_e32 v84, 0x80000000, v83
	v_pk_fma_f32 v[88:89], v[46:47], v[36:37], v[88:89] op_sel_hi:[0,1,1]
	v_pk_fma_f32 v[102:103], v[46:47], v[48:49], v[102:103] op_sel_hi:[0,1,1]
	v_pk_fma_f32 v[116:117], v[52:53], v[46:47], v[116:117] op_sel_hi:[1,0,1]
	v_mov_b32_e32 v85, v83
	v_pk_fma_f32 v[44:45], v[46:47], v[180:181], v[44:45] op_sel_hi:[0,1,1]
	v_pk_mul_f32 v[46:47], v[58:59], v[192:193] op_sel:[0,1] op_sel_hi:[1,0]
	v_pk_mul_f32 v[54:55], v[122:123], v[154:155] op_sel:[0,1] op_sel_hi:[1,0]
	v_pk_mul_f32 v[72:73], v[114:115], v[194:195] op_sel:[0,1] op_sel_hi:[1,0]
	v_pk_mul_f32 v[108:109], v[108:109], v[158:159] op_sel:[0,1] op_sel_hi:[1,0]
	v_pk_mul_f32 v[100:101], v[100:101], v[156:157] op_sel:[0,1] op_sel_hi:[1,0]
	v_pk_mul_f32 v[94:95], v[94:95], v[144:145] op_sel:[0,1] op_sel_hi:[1,0]
	v_pk_mul_f32 v[86:87], v[174:175], v[86:87] op_sel:[1,0] op_sel_hi:[0,1]
	v_pk_mul_f32 v[80:81], v[140:141], v[80:81] op_sel:[1,0] op_sel_hi:[0,1]
	v_pk_mul_f32 v[70:71], v[148:149], v[70:71] op_sel:[1,0] op_sel_hi:[0,1]
	v_pk_mul_f32 v[64:65], v[132:133], v[64:65] op_sel:[1,0] op_sel_hi:[0,1]
	v_pk_mul_f32 v[50:51], v[190:191], v[50:51] op_sel:[1,0] op_sel_hi:[0,1]
	v_pk_mul_f32 v[38:39], v[142:143], v[38:39] op_sel:[1,0] op_sel_hi:[0,1]
	v_pk_fma_f32 v[4:5], v[150:151], v[4:5], v[22:23] op_sel_hi:[1,0,1]
	v_pk_mul_f32 v[12:13], v[134:135], v[12:13] op_sel:[1,0] op_sel_hi:[0,1]
	v_xor_b32_e32 v112, 0x80000000, v111
	v_mov_b32_e32 v113, v111
	v_pk_fma_f32 v[46:47], v[52:53], v[192:193], v[46:47] op_sel_hi:[0,1,1]
	v_pk_fma_f32 v[54:55], v[120:121], v[154:155], v[54:55] op_sel_hi:[0,1,1]
	v_pk_fma_f32 v[48:49], v[48:49], v[194:195], v[72:73] op_sel_hi:[0,1,1]
	v_pk_fma_f32 v[106:107], v[106:107], v[158:159], v[108:109] op_sel_hi:[0,1,1]
	v_pk_fma_f32 v[36:37], v[36:37], v[156:157], v[100:101] op_sel_hi:[0,1,1]
	v_pk_fma_f32 v[92:93], v[92:93], v[144:145], v[94:95] op_sel_hi:[0,1,1]
	v_pk_fma_f32 v[26:27], v[174:175], v[26:27], v[86:87] op_sel_hi:[1,0,1]
	v_pk_mul_f32 v[84:85], v[130:131], v[84:85] op_sel:[1,0] op_sel_hi:[0,1]
	v_pk_fma_f32 v[78:79], v[140:141], v[78:79], v[80:81] op_sel_hi:[1,0,1]
	v_pk_fma_f32 v[20:21], v[148:149], v[20:21], v[70:71] op_sel_hi:[1,0,1]
	v_pk_fma_f32 v[62:63], v[132:133], v[62:63], v[64:65] op_sel_hi:[1,0,1]
	v_pk_fma_f32 v[10:11], v[190:191], v[10:11], v[50:51] op_sel_hi:[1,0,1]
	v_pk_fma_f32 v[32:33], v[142:143], v[32:33], v[38:39] op_sel_hi:[1,0,1]
	v_pk_fma_f32 v[8:9], v[134:135], v[8:9], v[12:13] op_sel_hi:[1,0,1]
	ds_write_b64 v18, v[162:163]
	ds_write_b64 v18, v[26:27] offset:4224
	ds_write_b64 v18, v[48:49] offset:8448
	ds_write_b64 v18, v[10:11] offset:12672
	ds_write_b64 v18, v[46:47] offset:16896
	ds_write_b64 v18, v[20:21] offset:21120
	ds_write_b64 v18, v[36:37] offset:25344
	ds_write_b64 v18, v[4:5] offset:29568
	ds_write_b64 v18, v[34:35] offset:33792
	ds_write_b64 v18, v[78:79] offset:38016
	ds_write_b64 v18, v[106:107] offset:42240
	ds_write_b64 v18, v[32:33] offset:46464
	ds_write_b64 v18, v[54:55] offset:50688
	ds_write_b64 v18, v[62:63] offset:54912
	ds_write_b64 v18, v[92:93] offset:59136
	ds_write_b64 v18, v[8:9] offset:63360
	v_add_u32_e32 v4, 0x10800, v18
	v_xor_b32_e32 v42, 0x80000000, v41
	v_mov_b32_e32 v43, v41
	v_pk_mul_f32 v[72:73], v[112:113], v[176:177] op_sel:[0,1] op_sel_hi:[1,0]
	v_pk_fma_f32 v[82:83], v[130:131], v[82:83], v[84:85] op_sel_hi:[1,0,1]
	ds_write_b64 v4, v[30:31]
	v_add_u32_e32 v4, 0x11880, v18
	v_xor_b32_e32 v126, 0x80000000, v125
	v_mov_b32_e32 v127, v125
	v_pk_fma_f32 v[72:73], v[110:111], v[176:177], v[72:73] op_sel_hi:[0,1,1]
	v_pk_mul_f32 v[42:43], v[138:139], v[42:43] op_sel:[1,0] op_sel_hi:[0,1]
	ds_write_b64 v4, v[82:83]
	v_add_u32_e32 v4, 0x12900, v18
	v_xor_b32_e32 v68, 0x80000000, v67
	v_mov_b32_e32 v69, v67
	v_pk_mul_f32 v[52:53], v[126:127], v[182:183] op_sel:[0,1] op_sel_hi:[1,0]
	v_pk_fma_f32 v[40:41], v[138:139], v[40:41], v[42:43] op_sel_hi:[1,0,1]
	ds_write_b64 v4, v[72:73]
	v_add_u32_e32 v4, 0x13980, v18
	v_xor_b32_e32 v98, 0x80000000, v97
	v_mov_b32_e32 v99, v97
	v_pk_fma_f32 v[52:53], v[124:125], v[182:183], v[52:53] op_sel_hi:[0,1,1]
	v_pk_mul_f32 v[68:69], v[178:179], v[68:69] op_sel:[1,0] op_sel_hi:[0,1]
	ds_write_b64 v4, v[40:41]
	v_add_u32_e32 v4, 0x14a00, v18
	v_xor_b32_e32 v16, 0x80000000, v15
	v_mov_b32_e32 v17, v15
	v_pk_mul_f32 v[98:99], v[98:99], v[186:187] op_sel:[0,1] op_sel_hi:[1,0]
	v_pk_fma_f32 v[66:67], v[178:179], v[66:67], v[68:69] op_sel_hi:[1,0,1]
	ds_write_b64 v4, v[52:53]
	v_add_u32_e32 v4, 0x15a80, v18
	v_pk_fma_f32 v[96:97], v[96:97], v[186:187], v[98:99] op_sel_hi:[0,1,1]
	v_pk_mul_f32 v[16:17], v[160:161], v[16:17] op_sel:[1,0] op_sel_hi:[0,1]
	ds_write_b64 v4, v[66:67]
	v_add_u32_e32 v4, 0x16b00, v18
	v_xor_b32_e32 v76, 0x80000000, v75
	v_mov_b32_e32 v77, v75
	v_pk_add_f32 v[168:169], v[168:169], v[188:189] neg_lo:[0,1] neg_hi:[0,1]
	v_pk_fma_f32 v[14:15], v[160:161], v[14:15], v[16:17] op_sel_hi:[1,0,1]
	ds_write_b64 v4, v[96:97]
	v_add_u32_e32 v4, 0x17b80, v18
	v_xor_b32_e32 v104, 0x80000000, v103
	v_mov_b32_e32 v105, v103
	v_pk_add_f32 v[188:189], v[170:171], v[184:185] op_sel:[0,1] op_sel_hi:[1,0] neg_hi:[0,1]
	v_pk_mul_f32 v[76:77], v[168:169], v[76:77] op_sel:[1,0] op_sel_hi:[0,1]
	ds_write_b64 v4, v[14:15]
	v_add_u32_e32 v4, 0x18c00, v18
	v_xor_b32_e32 v28, 0x80000000, v25
	v_mov_b32_e32 v29, v25
	v_pk_add_f32 v[170:171], v[170:171], v[184:185] op_sel:[0,1] op_sel_hi:[1,0] neg_lo:[0,1]
	v_pk_mul_f32 v[104:105], v[104:105], v[188:189] op_sel:[0,1] op_sel_hi:[1,0]
	v_pk_fma_f32 v[74:75], v[168:169], v[74:75], v[76:77] op_sel_hi:[1,0,1]
	ds_write_b64 v4, v[44:45]
	v_add_u32_e32 v4, 0x19c80, v18
	v_xor_b32_e32 v118, 0x80000000, v117
	v_mov_b32_e32 v119, v117
	v_pk_add_f32 v[184:185], v[164:165], v[172:173]
	v_pk_fma_f32 v[102:103], v[102:103], v[188:189], v[104:105] op_sel_hi:[0,1,1]
	v_pk_mul_f32 v[28:29], v[170:171], v[28:29] op_sel:[1,0] op_sel_hi:[0,1]
	ds_write_b64 v4, v[74:75]
	v_add_u32_e32 v4, 0x1ad00, v18
	v_xor_b32_e32 v60, 0x80000000, v57
	v_mov_b32_e32 v61, v57
	v_pk_add_f32 v[164:165], v[164:165], v[172:173] neg_lo:[0,1] neg_hi:[0,1]
	v_pk_mul_f32 v[58:59], v[118:119], v[184:185] op_sel:[0,1] op_sel_hi:[1,0]
	v_pk_fma_f32 v[24:25], v[170:171], v[24:25], v[28:29] op_sel_hi:[1,0,1]
	ds_write_b64 v4, v[102:103]
	v_add_u32_e32 v4, 0x1bd80, v18
	v_xor_b32_e32 v90, 0x80000000, v89
	v_mov_b32_e32 v91, v89
	v_pk_add_f32 v[172:173], v[128:129], v[166:167]
	v_pk_fma_f32 v[58:59], v[116:117], v[184:185], v[58:59] op_sel_hi:[0,1,1]
	v_pk_mul_f32 v[60:61], v[164:165], v[60:61] op_sel:[1,0] op_sel_hi:[0,1]
	ds_write_b64 v4, v[24:25]
	v_add_u32_e32 v4, 0x1ce00, v18
	v_xor_b32_e32 v6, 0x80000000, v3
	v_mov_b32_e32 v7, v3
	v_pk_add_f32 v[128:129], v[128:129], v[166:167] neg_lo:[0,1] neg_hi:[0,1]
	v_pk_mul_f32 v[90:91], v[90:91], v[172:173] op_sel:[0,1] op_sel_hi:[1,0]
	v_pk_fma_f32 v[56:57], v[164:165], v[56:57], v[60:61] op_sel_hi:[1,0,1]
	ds_write_b64 v4, v[58:59]
	v_add_u32_e32 v4, 0x1de80, v18
	v_pk_fma_f32 v[88:89], v[88:89], v[172:173], v[90:91] op_sel_hi:[0,1,1]
	v_pk_mul_f32 v[6:7], v[128:129], v[6:7] op_sel:[1,0] op_sel_hi:[0,1]
	ds_write_b64 v4, v[56:57]
	v_add_u32_e32 v4, 0x1ef00, v18
	v_pk_fma_f32 v[2:3], v[128:129], v[2:3], v[6:7] op_sel_hi:[1,0,1]
	ds_write_b64 v4, v[88:89]
	v_add_u32_e32 v4, 0x1ff80, v18
	ds_write_b64 v4, v[2:3]
	v_mov_b32_e32 v2, v210
	s_waitcnt lgkmcnt(0)
	s_barrier
	s_ashr_i32 s77, s76, 31
	v_and_b32_e32 v3, 15, v2
	v_lshlrev_b32_e32 v2, 5, v2
	v_and_b32_e32 v4, 0xfffffe00, v2
	v_lshl_add_u32 v5, v4, 3, 0
	v_lshlrev_b32_e32 v6, 3, v3
	v_ashrrev_i32_e32 v7, 2, v4
	v_add3_u32 v18, v5, v6, v7
	v_add_u32_e32 v196, 0x800, v18
	ds_read2_b64 v[128:131], v18 offset1:16
	ds_read2_b64 v[132:135], v18 offset0:33 offset1:49
	ds_read2_b64 v[136:139], v18 offset0:66 offset1:82
	ds_read2_b64 v[140:143], v18 offset0:99 offset1:115
	ds_read2_b64 v[148:151], v18 offset0:132 offset1:148
	ds_read2_b64 v[152:155], v18 offset0:165 offset1:181
	ds_read2_b64 v[156:159], v18 offset0:198 offset1:214
	ds_read2_b64 v[160:163], v18 offset0:231 offset1:247
	ds_read2_b64 v[164:167], v196 offset0:8 offset1:24
	ds_read2_b64 v[168:171], v196 offset0:41 offset1:57
	ds_read2_b64 v[172:175], v196 offset0:74 offset1:90
	ds_read2_b64 v[176:179], v196 offset0:107 offset1:123
	ds_read2_b64 v[180:183], v196 offset0:140 offset1:156
	ds_read2_b64 v[184:187], v196 offset0:173 offset1:189
	ds_read2_b64 v[188:191], v196 offset0:206 offset1:222
	ds_read2_b64 v[192:195], v196 offset0:239 offset1:255
	s_waitcnt lgkmcnt(7)
	v_pk_add_f32 v[144:145], v[128:129], v[164:165]
	v_pk_add_f32 v[128:129], v[128:129], v[164:165] neg_lo:[0,1] neg_hi:[0,1]
	v_pk_add_f32 v[164:165], v[130:131], v[166:167]
	v_pk_add_f32 v[130:131], v[130:131], v[166:167] neg_lo:[0,1] neg_hi:[0,1]
	v_cvt_f32_ubyte0_e32 v2, v3
	v_pk_mul_f32 v[166:167], v[130:131], s[10:11]
	v_mul_f32_e32 v3, 0x3b000000, v2
	v_pk_fma_f32 v[130:131], v[130:131], s[8:9], v[166:167] op_sel:[0,0,1] op_sel_hi:[1,0,0]
	s_waitcnt lgkmcnt(6)
	v_pk_add_f32 v[166:167], v[132:133], v[168:169]
	v_pk_add_f32 v[132:133], v[132:133], v[168:169] neg_lo:[0,1] neg_hi:[0,1]
	v_sin_f32_e32 v2, v3
	v_pk_mul_f32 v[168:169], v[132:133], s[18:19]
	v_cos_f32_e32 v4, v3
	v_pk_fma_f32 v[132:133], v[132:133], s[16:17], v[168:169] op_sel:[0,0,1] op_sel_hi:[1,0,0]
	v_pk_add_f32 v[168:169], v[134:135], v[170:171]
	v_pk_add_f32 v[134:135], v[134:135], v[170:171] neg_lo:[0,1] neg_hi:[0,1]
	v_xor_b32_e32 v5, 0x80000000, v2
	v_pk_mul_f32 v[170:171], v[134:135], s[26:27]
	v_mov_b32_e32 v3, v5
	v_pk_fma_f32 v[134:135], v[134:135], s[24:25], v[170:171] op_sel:[0,0,1] op_sel_hi:[1,0,0]
	s_waitcnt lgkmcnt(5)
	v_pk_add_f32 v[170:171], v[136:137], v[172:173]
	v_pk_add_f32 v[136:137], v[136:137], v[172:173] neg_lo:[0,1] neg_hi:[0,1]
	v_pk_mul_f32 v[6:7], v[4:5], v[2:3] op_sel:[1,0] op_sel_hi:[0,1]
	v_pk_mul_f32 v[172:173], v[136:137], s[36:37]
	v_pk_fma_f32 v[6:7], v[4:5], v[4:5], v[6:7] op_sel_hi:[1,0,1]
	v_pk_fma_f32 v[136:137], v[136:137], s[78:79], v[172:173] op_sel:[0,0,1] op_sel_hi:[1,0,0]
	v_pk_add_f32 v[172:173], v[138:139], v[174:175]
	v_pk_add_f32 v[138:139], v[138:139], v[174:175] neg_lo:[0,1] neg_hi:[0,1]
	v_xor_b32_e32 v12, 0x80000000, v7
	v_pk_mul_f32 v[174:175], v[138:139], s[38:39]
	v_mov_b32_e32 v13, v7
	v_pk_fma_f32 v[138:139], v[138:139], s[0:1], v[174:175] op_sel:[0,0,1] op_sel_hi:[1,0,0]
	s_waitcnt lgkmcnt(4)
	v_pk_add_f32 v[174:175], v[140:141], v[176:177]
	v_pk_add_f32 v[140:141], v[140:141], v[176:177] neg_lo:[0,1] neg_hi:[0,1]
	v_pk_mul_f32 v[10:11], v[6:7], v[12:13] op_sel:[1,0] op_sel_hi:[0,1]
	v_pk_mul_f32 v[176:177], v[140:141], s[40:41]
	v_pk_fma_f32 v[10:11], v[6:7], v[6:7], v[10:11] op_sel_hi:[1,0,1]
	v_pk_fma_f32 v[140:141], v[140:141], s[80:81], v[176:177] op_sel:[0,0,1] op_sel_hi:[1,0,0]
	v_pk_add_f32 v[176:177], v[142:143], v[178:179]
	v_pk_add_f32 v[142:143], v[142:143], v[178:179] neg_lo:[0,1] neg_hi:[0,1]
	v_xor_b32_e32 v14, 0x80000000, v11
	v_pk_mul_f32 v[178:179], v[142:143], s[42:43]
	v_mov_b32_e32 v15, v11
	v_pk_fma_f32 v[142:143], v[142:143], s[74:75], v[178:179] op_sel:[0,0,1] op_sel_hi:[1,0,0]
	s_waitcnt lgkmcnt(3)
	v_pk_add_f32 v[178:179], v[148:149], v[180:181]
	v_pk_add_f32 v[180:181], v[148:149], v[180:181] neg_lo:[0,1] neg_hi:[0,1]
	v_pk_mul_f32 v[28:29], v[10:11], v[14:15] op_sel:[1,0] op_sel_hi:[0,1]
	v_pk_add_f32 v[148:149], v[150:151], v[182:183]
	v_pk_add_f32 v[150:151], v[150:151], v[182:183] neg_lo:[0,1] neg_hi:[0,1]
	v_pk_fma_f32 v[28:29], v[10:11], v[10:11], v[28:29] op_sel_hi:[1,0,1]
	v_pk_mul_f32 v[182:183], v[150:151], s[42:43]
	v_pk_mul_f32 v[44:45], v[14:15], v[28:29] op_sel:[0,1] op_sel_hi:[1,0]
	v_pk_fma_f32 v[150:151], v[150:151], s[74:75], v[182:183] op_sel:[0,0,1] op_sel_hi:[1,0,0] neg_lo:[1,0,0] neg_hi:[1,0,0]
	s_waitcnt lgkmcnt(2)
	v_pk_add_f32 v[182:183], v[152:153], v[184:185]
	v_pk_add_f32 v[152:153], v[152:153], v[184:185] neg_lo:[0,1] neg_hi:[0,1]
	v_pk_fma_f32 v[44:45], v[10:11], v[28:29], v[44:45] op_sel_hi:[0,1,1]
	v_pk_mul_f32 v[184:185], v[152:153], s[40:41]
	v_pk_mul_f32 v[60:61], v[14:15], v[44:45] op_sel:[0,1] op_sel_hi:[1,0]
	v_pk_fma_f32 v[152:153], v[152:153], s[80:81], v[184:185] op_sel:[0,0,1] op_sel_hi:[1,0,0] neg_lo:[1,0,0] neg_hi:[1,0,0]
	v_pk_add_f32 v[184:185], v[154:155], v[186:187]
	v_pk_add_f32 v[154:155], v[154:155], v[186:187] neg_lo:[0,1] neg_hi:[0,1]
	v_pk_fma_f32 v[60:61], v[10:11], v[44:45], v[60:61] op_sel_hi:[0,1,1]
	v_pk_mul_f32 v[186:187], v[154:155], s[38:39]
	v_pk_mul_f32 v[76:77], v[14:15], v[60:61] op_sel:[0,1] op_sel_hi:[1,0]
	v_pk_fma_f32 v[154:155], v[154:155], s[0:1], v[186:187] op_sel:[0,0,1] op_sel_hi:[1,0,0] neg_lo:[1,0,0] neg_hi:[1,0,0]
	s_waitcnt lgkmcnt(1)
	v_pk_add_f32 v[186:187], v[156:157], v[188:189]
	v_pk_add_f32 v[156:157], v[156:157], v[188:189] neg_lo:[0,1] neg_hi:[0,1]
	v_pk_fma_f32 v[76:77], v[10:11], v[60:61], v[76:77] op_sel_hi:[0,1,1]
	v_pk_mul_f32 v[188:189], v[156:157], s[36:37]
	v_pk_mul_f32 v[92:93], v[14:15], v[76:77] op_sel:[0,1] op_sel_hi:[1,0]
	v_pk_fma_f32 v[156:157], v[156:157], s[78:79], v[188:189] op_sel:[0,0,1] op_sel_hi:[1,0,0] neg_lo:[1,0,0] neg_hi:[1,0,0]
	v_pk_add_f32 v[188:189], v[158:159], v[190:191]
	v_pk_add_f32 v[158:159], v[158:159], v[190:191] neg_lo:[0,1] neg_hi:[0,1]
	v_pk_fma_f32 v[92:93], v[10:11], v[76:77], v[92:93] op_sel_hi:[0,1,1]
	v_pk_mul_f32 v[190:191], v[158:159], s[26:27]
	v_pk_mul_f32 v[108:109], v[14:15], v[92:93] op_sel:[0,1] op_sel_hi:[1,0]
	v_pk_fma_f32 v[158:159], v[158:159], s[24:25], v[190:191] op_sel:[0,0,1] op_sel_hi:[1,0,0] neg_lo:[1,0,0] neg_hi:[1,0,0]
	s_waitcnt lgkmcnt(0)
	v_pk_add_f32 v[190:191], v[160:161], v[192:193]
	v_pk_add_f32 v[160:161], v[160:161], v[192:193] neg_lo:[0,1] neg_hi:[0,1]
	v_pk_mul_f32 v[8:9], v[2:3], v[6:7] op_sel:[0,1] op_sel_hi:[1,0]
	v_pk_mul_f32 v[192:193], v[160:161], s[18:19]
	v_pk_fma_f32 v[108:109], v[10:11], v[92:93], v[108:109] op_sel_hi:[0,1,1]
	v_pk_fma_f32 v[160:161], v[160:161], s[16:17], v[192:193] op_sel:[0,0,1] op_sel_hi:[1,0,0] neg_lo:[1,0,0] neg_hi:[1,0,0]
	v_pk_add_f32 v[192:193], v[162:163], v[194:195]
	v_pk_add_f32 v[162:163], v[162:163], v[194:195] neg_lo:[0,1] neg_hi:[0,1]
	v_pk_fma_f32 v[8:9], v[4:5], v[6:7], v[8:9] op_sel_hi:[0,1,1]
	v_pk_mul_f32 v[194:195], v[162:163], s[10:11]
	v_pk_mul_f32 v[16:17], v[2:3], v[10:11] op_sel:[0,1] op_sel_hi:[1,0]
	v_pk_fma_f32 v[162:163], v[162:163], s[8:9], v[194:195] op_sel:[0,0,1] op_sel_hi:[1,0,0] neg_lo:[1,0,0] neg_hi:[1,0,0]
	v_pk_add_f32 v[194:195], v[144:145], v[178:179]
	v_pk_add_f32 v[144:145], v[144:145], v[178:179] neg_lo:[0,1] neg_hi:[0,1]
	v_pk_add_f32 v[178:179], v[164:165], v[148:149]
	v_pk_add_f32 v[148:149], v[164:165], v[148:149] neg_lo:[0,1] neg_hi:[0,1]
	v_pk_mul_f32 v[32:33], v[2:3], v[28:29] op_sel:[0,1] op_sel_hi:[1,0]
	v_pk_mul_f32 v[164:165], v[148:149], s[18:19]
	v_pk_mul_f32 v[48:49], v[2:3], v[44:45] op_sel:[0,1] op_sel_hi:[1,0]
	v_pk_fma_f32 v[148:149], v[148:149], s[16:17], v[164:165] op_sel:[0,0,1] op_sel_hi:[1,0,0]
	v_pk_add_f32 v[164:165], v[166:167], v[182:183]
	v_pk_add_f32 v[166:167], v[166:167], v[182:183] neg_lo:[0,1] neg_hi:[0,1]
	v_pk_mul_f32 v[64:65], v[2:3], v[60:61] op_sel:[0,1] op_sel_hi:[1,0]
	v_pk_mul_f32 v[182:183], v[166:167], s[36:37]
	v_pk_mul_f32 v[80:81], v[2:3], v[76:77] op_sel:[0,1] op_sel_hi:[1,0]
	v_pk_fma_f32 v[166:167], v[166:167], s[78:79], v[182:183] op_sel:[0,0,1] op_sel_hi:[1,0,0]
	v_pk_add_f32 v[182:183], v[168:169], v[184:185]
	v_pk_add_f32 v[168:169], v[168:169], v[184:185] neg_lo:[0,1] neg_hi:[0,1]
	v_pk_mul_f32 v[96:97], v[2:3], v[92:93] op_sel:[0,1] op_sel_hi:[1,0]
	v_pk_mul_f32 v[184:185], v[168:169], s[40:41]
	v_pk_mul_f32 v[112:113], v[2:3], v[108:109] op_sel:[0,1] op_sel_hi:[1,0]
	v_pk_fma_f32 v[168:169], v[168:169], s[80:81], v[184:185] op_sel:[0,0,1] op_sel_hi:[1,0,0]
	v_pk_add_f32 v[184:185], v[170:171], v[186:187]
	v_pk_add_f32 v[186:187], v[170:171], v[186:187] neg_lo:[0,1] neg_hi:[0,1]
	v_xor_b32_e32 v22, 0x80000000, v9
	v_pk_add_f32 v[170:171], v[172:173], v[188:189]
	v_pk_add_f32 v[172:173], v[172:173], v[188:189] neg_lo:[0,1] neg_hi:[0,1]
	v_mov_b32_e32 v23, v9
	v_pk_mul_f32 v[188:189], v[172:173], s[40:41]
	v_pk_fma_f32 v[16:17], v[4:5], v[10:11], v[16:17] op_sel_hi:[0,1,1]
	v_pk_fma_f32 v[172:173], v[172:173], s[80:81], v[188:189] op_sel:[0,0,1] op_sel_hi:[1,0,0] neg_lo:[1,0,0] neg_hi:[1,0,0]
	v_pk_add_f32 v[188:189], v[174:175], v[190:191]
	v_pk_add_f32 v[174:175], v[174:175], v[190:191] neg_lo:[0,1] neg_hi:[0,1]
	v_pk_mul_f32 v[20:21], v[12:13], v[10:11] op_sel:[0,1] op_sel_hi:[1,0]
	v_pk_mul_f32 v[190:191], v[174:175], s[36:37]
	v_pk_fma_f32 v[32:33], v[4:5], v[28:29], v[32:33] op_sel_hi:[0,1,1]
	v_pk_fma_f32 v[174:175], v[174:175], s[78:79], v[190:191] op_sel:[0,0,1] op_sel_hi:[1,0,0] neg_lo:[1,0,0] neg_hi:[1,0,0]
	v_pk_add_f32 v[190:191], v[176:177], v[192:193]
	v_pk_add_f32 v[176:177], v[176:177], v[192:193] neg_lo:[0,1] neg_hi:[0,1]
	v_pk_mul_f32 v[36:37], v[12:13], v[28:29] op_sel:[0,1] op_sel_hi:[1,0]
	v_pk_mul_f32 v[192:193], v[176:177], s[18:19]
	v_pk_fma_f32 v[48:49], v[4:5], v[44:45], v[48:49] op_sel_hi:[0,1,1]
	v_pk_fma_f32 v[176:177], v[176:177], s[16:17], v[192:193] op_sel:[0,0,1] op_sel_hi:[1,0,0] neg_lo:[1,0,0] neg_hi:[1,0,0]
	v_pk_add_f32 v[192:193], v[128:129], v[180:181] op_sel:[0,1] op_sel_hi:[1,0] neg_hi:[0,1]
	v_pk_add_f32 v[128:129], v[128:129], v[180:181] op_sel:[0,1] op_sel_hi:[1,0] neg_lo:[0,1]
	v_pk_add_f32 v[180:181], v[130:131], v[150:151]
	v_pk_add_f32 v[130:131], v[130:131], v[150:151] neg_lo:[0,1] neg_hi:[0,1]
	v_pk_mul_f32 v[52:53], v[12:13], v[44:45] op_sel:[0,1] op_sel_hi:[1,0]
	v_pk_mul_f32 v[150:151], v[130:131], s[18:19]
	v_pk_fma_f32 v[64:65], v[4:5], v[60:61], v[64:65] op_sel_hi:[0,1,1]
	v_pk_fma_f32 v[130:131], v[130:131], s[16:17], v[150:151] op_sel:[0,0,1] op_sel_hi:[1,0,0]
	v_pk_add_f32 v[150:151], v[132:133], v[152:153]
	v_pk_add_f32 v[132:133], v[132:133], v[152:153] neg_lo:[0,1] neg_hi:[0,1]
	v_pk_mul_f32 v[68:69], v[12:13], v[60:61] op_sel:[0,1] op_sel_hi:[1,0]
	v_pk_mul_f32 v[152:153], v[132:133], s[36:37]
	v_pk_fma_f32 v[80:81], v[4:5], v[76:77], v[80:81] op_sel_hi:[0,1,1]
	v_pk_fma_f32 v[132:133], v[132:133], s[78:79], v[152:153] op_sel:[0,0,1] op_sel_hi:[1,0,0]
	v_pk_add_f32 v[152:153], v[134:135], v[154:155]
	v_pk_add_f32 v[134:135], v[134:135], v[154:155] neg_lo:[0,1] neg_hi:[0,1]
	v_pk_mul_f32 v[84:85], v[12:13], v[76:77] op_sel:[0,1] op_sel_hi:[1,0]
	v_pk_mul_f32 v[154:155], v[134:135], s[40:41]
	v_pk_fma_f32 v[96:97], v[4:5], v[92:93], v[96:97] op_sel_hi:[0,1,1]
	v_pk_fma_f32 v[134:135], v[134:135], s[80:81], v[154:155] op_sel:[0,0,1] op_sel_hi:[1,0,0]
	v_pk_add_f32 v[154:155], v[136:137], v[156:157]
	v_pk_add_f32 v[156:157], v[136:137], v[156:157] neg_lo:[0,1] neg_hi:[0,1]
	v_pk_mul_f32 v[100:101], v[12:13], v[92:93] op_sel:[0,1] op_sel_hi:[1,0]
	v_pk_add_f32 v[136:137], v[138:139], v[158:159]
	v_pk_add_f32 v[138:139], v[138:139], v[158:159] neg_lo:[0,1] neg_hi:[0,1]
	v_pk_fma_f32 v[112:113], v[4:5], v[108:109], v[112:113] op_sel_hi:[0,1,1]
	v_pk_mul_f32 v[158:159], v[138:139], s[40:41]
	v_pk_mul_f32 v[116:117], v[12:13], v[108:109] op_sel:[0,1] op_sel_hi:[1,0]
	v_pk_fma_f32 v[138:139], v[138:139], s[80:81], v[158:159] op_sel:[0,0,1] op_sel_hi:[1,0,0] neg_lo:[1,0,0] neg_hi:[1,0,0]
	v_pk_add_f32 v[158:159], v[140:141], v[160:161]
	v_pk_add_f32 v[140:141], v[140:141], v[160:161] neg_lo:[0,1] neg_hi:[0,1]
	v_pk_fma_f32 v[20:21], v[6:7], v[10:11], v[20:21] op_sel_hi:[0,1,1]
	v_pk_mul_f32 v[160:161], v[140:141], s[36:37]
	v_pk_mul_f32 v[24:25], v[10:11], v[22:23] op_sel:[1,0] op_sel_hi:[0,1]
	v_pk_fma_f32 v[140:141], v[140:141], s[78:79], v[160:161] op_sel:[0,0,1] op_sel_hi:[1,0,0] neg_lo:[1,0,0] neg_hi:[1,0,0]
	v_pk_add_f32 v[160:161], v[142:143], v[162:163]
	v_pk_add_f32 v[142:143], v[142:143], v[162:163] neg_lo:[0,1] neg_hi:[0,1]
	v_pk_fma_f32 v[36:37], v[6:7], v[28:29], v[36:37] op_sel_hi:[0,1,1]
	v_pk_mul_f32 v[162:163], v[142:143], s[18:19]
	v_pk_mul_f32 v[40:41], v[22:23], v[28:29] op_sel:[0,1] op_sel_hi:[1,0]
	v_pk_fma_f32 v[142:143], v[142:143], s[16:17], v[162:163] op_sel:[0,0,1] op_sel_hi:[1,0,0] neg_lo:[1,0,0] neg_hi:[1,0,0]
	v_pk_add_f32 v[162:163], v[194:195], v[184:185]
	v_pk_add_f32 v[184:185], v[194:195], v[184:185] neg_lo:[0,1] neg_hi:[0,1]
	v_pk_add_f32 v[194:195], v[178:179], v[170:171]
	v_pk_add_f32 v[170:171], v[178:179], v[170:171] neg_lo:[0,1] neg_hi:[0,1]
	v_pk_fma_f32 v[52:53], v[6:7], v[44:45], v[52:53] op_sel_hi:[0,1,1]
	v_pk_mul_f32 v[178:179], v[170:171], s[36:37]
	v_pk_mul_f32 v[56:57], v[22:23], v[44:45] op_sel:[0,1] op_sel_hi:[1,0]
	v_pk_fma_f32 v[170:171], v[170:171], s[78:79], v[178:179] op_sel:[0,0,1] op_sel_hi:[1,0,0]
	v_pk_add_f32 v[178:179], v[164:165], v[188:189]
	v_pk_add_f32 v[188:189], v[164:165], v[188:189] neg_lo:[0,1] neg_hi:[0,1]
	v_pk_fma_f32 v[68:69], v[6:7], v[60:61], v[68:69] op_sel_hi:[0,1,1]
	v_pk_add_f32 v[164:165], v[182:183], v[190:191]
	v_pk_add_f32 v[182:183], v[182:183], v[190:191] neg_lo:[0,1] neg_hi:[0,1]
	v_pk_mul_f32 v[72:73], v[22:23], v[60:61] op_sel:[0,1] op_sel_hi:[1,0]
	v_pk_mul_f32 v[190:191], v[182:183], s[36:37]
	v_pk_fma_f32 v[84:85], v[6:7], v[76:77], v[84:85] op_sel_hi:[0,1,1]
	v_pk_fma_f32 v[182:183], v[182:183], s[78:79], v[190:191] op_sel:[0,0,1] op_sel_hi:[1,0,0] neg_lo:[1,0,0] neg_hi:[1,0,0]
	v_pk_add_f32 v[190:191], v[144:145], v[186:187] op_sel:[0,1] op_sel_hi:[1,0] neg_hi:[0,1]
	v_pk_add_f32 v[144:145], v[144:145], v[186:187] op_sel:[0,1] op_sel_hi:[1,0] neg_lo:[0,1]
	v_pk_add_f32 v[186:187], v[148:149], v[172:173]
	v_pk_add_f32 v[148:149], v[148:149], v[172:173] neg_lo:[0,1] neg_hi:[0,1]
	v_pk_mul_f32 v[88:89], v[22:23], v[76:77] op_sel:[0,1] op_sel_hi:[1,0]
	v_pk_mul_f32 v[172:173], v[148:149], s[36:37]
	v_pk_fma_f32 v[100:101], v[6:7], v[92:93], v[100:101] op_sel_hi:[0,1,1]
	v_pk_fma_f32 v[148:149], v[148:149], s[78:79], v[172:173] op_sel:[0,0,1] op_sel_hi:[1,0,0]
	v_pk_add_f32 v[172:173], v[166:167], v[174:175]
	v_pk_add_f32 v[174:175], v[166:167], v[174:175] neg_lo:[0,1] neg_hi:[0,1]
	v_pk_mul_f32 v[104:105], v[22:23], v[92:93] op_sel:[0,1] op_sel_hi:[1,0]
	v_pk_add_f32 v[166:167], v[168:169], v[176:177]
	v_pk_add_f32 v[168:169], v[168:169], v[176:177] neg_lo:[0,1] neg_hi:[0,1]
	v_pk_fma_f32 v[116:117], v[6:7], v[108:109], v[116:117] op_sel_hi:[0,1,1]
	v_pk_mul_f32 v[176:177], v[168:169], s[36:37]
	v_pk_mul_f32 v[120:121], v[22:23], v[108:109] op_sel:[0,1] op_sel_hi:[1,0]
	v_pk_fma_f32 v[168:169], v[168:169], s[78:79], v[176:177] op_sel:[0,0,1] op_sel_hi:[1,0,0] neg_lo:[1,0,0] neg_hi:[1,0,0]
	v_pk_add_f32 v[176:177], v[192:193], v[154:155]
	v_pk_add_f32 v[154:155], v[192:193], v[154:155] neg_lo:[0,1] neg_hi:[0,1]
	v_pk_add_f32 v[192:193], v[180:181], v[136:137]
	v_pk_add_f32 v[136:137], v[180:181], v[136:137] neg_lo:[0,1] neg_hi:[0,1]
	v_xor_b32_e32 v26, 0x80000000, v17
	v_pk_mul_f32 v[180:181], v[136:137], s[36:37]
	v_xor_b32_e32 v30, 0x80000000, v21
	v_pk_fma_f32 v[136:137], v[136:137], s[78:79], v[180:181] op_sel:[0,0,1] op_sel_hi:[1,0,0]
	v_pk_add_f32 v[180:181], v[150:151], v[158:159]
	v_pk_add_f32 v[158:159], v[150:151], v[158:159] neg_lo:[0,1] neg_hi:[0,1]
	v_pk_fma_f32 v[24:25], v[10:11], v[8:9], v[24:25] op_sel_hi:[1,0,1]
	v_pk_add_f32 v[150:151], v[152:153], v[160:161]
	v_pk_add_f32 v[152:153], v[152:153], v[160:161] neg_lo:[0,1] neg_hi:[0,1]
	v_pk_fma_f32 v[40:41], v[8:9], v[28:29], v[40:41] op_sel_hi:[0,1,1]
	v_pk_mul_f32 v[160:161], v[152:153], s[36:37]
	v_pk_fma_f32 v[56:57], v[8:9], v[44:45], v[56:57] op_sel_hi:[0,1,1]
	v_pk_fma_f32 v[152:153], v[152:153], s[78:79], v[160:161] op_sel:[0,0,1] op_sel_hi:[1,0,0] neg_lo:[1,0,0] neg_hi:[1,0,0]
	v_pk_add_f32 v[160:161], v[128:129], v[156:157] op_sel:[0,1] op_sel_hi:[1,0] neg_hi:[0,1]
	v_pk_add_f32 v[128:129], v[128:129], v[156:157] op_sel:[0,1] op_sel_hi:[1,0] neg_lo:[0,1]
	v_pk_add_f32 v[156:157], v[130:131], v[138:139]
	v_pk_add_f32 v[130:131], v[130:131], v[138:139] neg_lo:[0,1] neg_hi:[0,1]
	v_pk_fma_f32 v[72:73], v[8:9], v[60:61], v[72:73] op_sel_hi:[0,1,1]
	v_pk_mul_f32 v[138:139], v[130:131], s[36:37]
	v_pk_fma_f32 v[88:89], v[8:9], v[76:77], v[88:89] op_sel_hi:[0,1,1]
	v_pk_fma_f32 v[130:131], v[130:131], s[78:79], v[138:139] op_sel:[0,0,1] op_sel_hi:[1,0,0]
	v_pk_add_f32 v[138:139], v[132:133], v[140:141]
	v_pk_add_f32 v[140:141], v[132:133], v[140:141] neg_lo:[0,1] neg_hi:[0,1]
	v_pk_fma_f32 v[104:105], v[8:9], v[92:93], v[104:105] op_sel_hi:[0,1,1]
	v_pk_add_f32 v[132:133], v[134:135], v[142:143]
	v_pk_add_f32 v[134:135], v[134:135], v[142:143] neg_lo:[0,1] neg_hi:[0,1]
	v_pk_fma_f32 v[120:121], v[8:9], v[108:109], v[120:121] op_sel_hi:[0,1,1]
	v_pk_mul_f32 v[142:143], v[134:135], s[36:37]
	v_mov_b32_e32 v27, v17
	v_pk_fma_f32 v[134:135], v[134:135], s[78:79], v[142:143] op_sel:[0,0,1] op_sel_hi:[1,0,0] neg_lo:[1,0,0] neg_hi:[1,0,0]
	v_pk_add_f32 v[142:143], v[162:163], v[178:179]
	v_pk_add_f32 v[162:163], v[162:163], v[178:179] neg_lo:[0,1] neg_hi:[0,1]
	v_pk_add_f32 v[178:179], v[194:195], v[164:165]
	v_pk_add_f32 v[194:195], v[194:195], v[164:165] neg_lo:[0,1] neg_hi:[0,1]
	v_mov_b32_e32 v31, v21
	v_pk_add_f32 v[164:165], v[184:185], v[188:189] op_sel:[0,1] op_sel_hi:[1,0] neg_hi:[0,1]
	v_pk_add_f32 v[184:185], v[184:185], v[188:189] op_sel:[0,1] op_sel_hi:[1,0] neg_lo:[0,1]
	v_pk_add_f32 v[188:189], v[170:171], v[182:183]
	v_pk_add_f32 v[182:183], v[170:171], v[182:183] neg_lo:[0,1] neg_hi:[0,1]
	v_xor_b32_e32 v34, 0x80000000, v25
	v_pk_add_f32 v[170:171], v[190:191], v[172:173]
	v_pk_add_f32 v[172:173], v[190:191], v[172:173] neg_lo:[0,1] neg_hi:[0,1]
	v_pk_add_f32 v[190:191], v[186:187], v[166:167]
	v_pk_add_f32 v[186:187], v[186:187], v[166:167] neg_lo:[0,1] neg_hi:[0,1]
	v_xor_b32_e32 v38, 0x80000000, v29
	v_pk_add_f32 v[166:167], v[144:145], v[174:175] op_sel:[0,1] op_sel_hi:[1,0] neg_hi:[0,1]
	v_pk_add_f32 v[144:145], v[144:145], v[174:175] op_sel:[0,1] op_sel_hi:[1,0] neg_lo:[0,1]
	v_pk_add_f32 v[174:175], v[148:149], v[168:169]
	v_pk_add_f32 v[168:169], v[148:149], v[168:169] neg_lo:[0,1] neg_hi:[0,1]
	v_xor_b32_e32 v42, 0x80000000, v33
	v_pk_add_f32 v[148:149], v[176:177], v[180:181]
	v_pk_add_f32 v[176:177], v[176:177], v[180:181] neg_lo:[0,1] neg_hi:[0,1]
	v_pk_add_f32 v[180:181], v[192:193], v[150:151]
	v_pk_add_f32 v[192:193], v[192:193], v[150:151] neg_lo:[0,1] neg_hi:[0,1]
	v_xor_b32_e32 v46, 0x80000000, v37
	v_pk_add_f32 v[150:151], v[154:155], v[158:159] op_sel:[0,1] op_sel_hi:[1,0] neg_hi:[0,1]
	v_pk_add_f32 v[154:155], v[154:155], v[158:159] op_sel:[0,1] op_sel_hi:[1,0] neg_lo:[0,1]
	v_pk_add_f32 v[158:159], v[136:137], v[152:153]
	v_pk_add_f32 v[152:153], v[136:137], v[152:153] neg_lo:[0,1] neg_hi:[0,1]
	v_mov_b32_e32 v35, v25
	v_pk_add_f32 v[136:137], v[160:161], v[138:139]
	v_pk_add_f32 v[138:139], v[160:161], v[138:139] neg_lo:[0,1] neg_hi:[0,1]
	v_pk_add_f32 v[160:161], v[156:157], v[132:133]
	v_pk_add_f32 v[156:157], v[156:157], v[132:133] neg_lo:[0,1] neg_hi:[0,1]
	v_mov_b32_e32 v39, v29
	v_pk_add_f32 v[132:133], v[128:129], v[140:141] op_sel:[0,1] op_sel_hi:[1,0] neg_hi:[0,1]
	v_pk_add_f32 v[128:129], v[128:129], v[140:141] op_sel:[0,1] op_sel_hi:[1,0] neg_lo:[0,1]
	v_pk_add_f32 v[140:141], v[130:131], v[134:135]
	v_pk_add_f32 v[130:131], v[130:131], v[134:135] neg_lo:[0,1] neg_hi:[0,1]
	v_mov_b32_e32 v43, v33
	v_xor_b32_e32 v135, 0x80000000, v130
	v_mov_b32_e32 v134, v131
	v_pk_add_f32 v[130:131], v[142:143], v[178:179]
	v_pk_add_f32 v[142:143], v[142:143], v[178:179] neg_lo:[0,1] neg_hi:[0,1]
	v_pk_add_f32 v[178:179], v[162:163], v[194:195] op_sel:[0,1] op_sel_hi:[1,0] neg_hi:[0,1]
	v_pk_add_f32 v[162:163], v[162:163], v[194:195] op_sel:[0,1] op_sel_hi:[1,0] neg_lo:[0,1]
	v_pk_add_f32 v[194:195], v[164:165], v[188:189]
	v_pk_add_f32 v[164:165], v[164:165], v[188:189] neg_lo:[0,1] neg_hi:[0,1]
	v_pk_add_f32 v[188:189], v[184:185], v[182:183] op_sel:[0,1] op_sel_hi:[1,0] neg_hi:[0,1]
	v_pk_add_f32 v[182:183], v[184:185], v[182:183] op_sel:[0,1] op_sel_hi:[1,0] neg_lo:[0,1]
	v_pk_add_f32 v[184:185], v[170:171], v[190:191]
	v_pk_add_f32 v[170:171], v[170:171], v[190:191] neg_lo:[0,1] neg_hi:[0,1]
	v_pk_add_f32 v[190:191], v[172:173], v[186:187] op_sel:[0,1] op_sel_hi:[1,0] neg_hi:[0,1]
	v_pk_add_f32 v[172:173], v[172:173], v[186:187] op_sel:[0,1] op_sel_hi:[1,0] neg_lo:[0,1]
	v_pk_add_f32 v[186:187], v[166:167], v[174:175]
	v_pk_add_f32 v[166:167], v[166:167], v[174:175] neg_lo:[0,1] neg_hi:[0,1]
	v_pk_add_f32 v[174:175], v[144:145], v[168:169] op_sel:[0,1] op_sel_hi:[1,0] neg_hi:[0,1]
	v_pk_add_f32 v[144:145], v[144:145], v[168:169] op_sel:[0,1] op_sel_hi:[1,0] neg_lo:[0,1]
	v_pk_add_f32 v[168:169], v[148:149], v[180:181]
	v_pk_add_f32 v[148:149], v[148:149], v[180:181] neg_lo:[0,1] neg_hi:[0,1]
	v_pk_mul_f32 v[2:3], v[2:3], v[168:169] op_sel:[0,1] op_sel_hi:[1,0]
	v_pk_add_f32 v[180:181], v[176:177], v[192:193] op_sel:[0,1] op_sel_hi:[1,0] neg_hi:[0,1]
	v_pk_add_f32 v[176:177], v[176:177], v[192:193] op_sel:[0,1] op_sel_hi:[1,0] neg_lo:[0,1]
	v_pk_add_f32 v[192:193], v[150:151], v[158:159]
	v_pk_add_f32 v[150:151], v[150:151], v[158:159] neg_lo:[0,1] neg_hi:[0,1]
	v_pk_add_f32 v[158:159], v[154:155], v[152:153] op_sel:[0,1] op_sel_hi:[1,0] neg_hi:[0,1]
	v_pk_add_f32 v[152:153], v[154:155], v[152:153] op_sel:[0,1] op_sel_hi:[1,0] neg_lo:[0,1]
	v_pk_add_f32 v[154:155], v[136:137], v[160:161]
	v_pk_fma_f32 v[2:3], v[4:5], v[168:169], v[2:3] op_sel_hi:[0,1,1]
	v_pk_mul_f32 v[4:5], v[12:13], v[184:185] op_sel:[0,1] op_sel_hi:[1,0]
	v_mov_b32_e32 v47, v37
	v_pk_fma_f32 v[4:5], v[6:7], v[184:185], v[4:5] op_sel_hi:[0,1,1]
	v_pk_mul_f32 v[6:7], v[22:23], v[154:155] op_sel:[0,1] op_sel_hi:[1,0]
	v_pk_add_f32 v[136:137], v[136:137], v[160:161] neg_lo:[0,1] neg_hi:[0,1]
	v_pk_fma_f32 v[6:7], v[8:9], v[154:155], v[6:7] op_sel_hi:[0,1,1]
	v_pk_mul_f32 v[8:9], v[14:15], v[194:195] op_sel:[0,1] op_sel_hi:[1,0]
	v_pk_add_f32 v[160:161], v[138:139], v[156:157] op_sel:[0,1] op_sel_hi:[1,0] neg_hi:[0,1]
	v_pk_add_f32 v[138:139], v[138:139], v[156:157] op_sel:[0,1] op_sel_hi:[1,0] neg_lo:[0,1]
	v_pk_add_f32 v[156:157], v[132:133], v[140:141]
	v_pk_fma_f32 v[8:9], v[10:11], v[194:195], v[8:9] op_sel_hi:[0,1,1]
	v_pk_mul_f32 v[10:11], v[26:27], v[192:193] op_sel:[0,1] op_sel_hi:[1,0]
	v_pk_mul_f32 v[12:13], v[30:31], v[186:187] op_sel:[0,1] op_sel_hi:[1,0]
	v_xor_b32_e32 v50, 0x80000000, v41
	v_xor_b32_e32 v54, 0x80000000, v45
	v_xor_b32_e32 v58, 0x80000000, v49
	v_xor_b32_e32 v62, 0x80000000, v53
	v_xor_b32_e32 v66, 0x80000000, v57
	v_xor_b32_e32 v70, 0x80000000, v61
	v_xor_b32_e32 v74, 0x80000000, v65
	v_mov_b32_e32 v51, v41
	v_mov_b32_e32 v55, v45
	v_mov_b32_e32 v59, v49
	v_mov_b32_e32 v63, v53
	v_mov_b32_e32 v67, v57
	v_mov_b32_e32 v71, v61
	v_mov_b32_e32 v75, v65
	v_pk_add_f32 v[132:133], v[132:133], v[140:141] neg_lo:[0,1] neg_hi:[0,1]
	v_pk_add_f32 v[140:141], v[128:129], v[134:135]
	v_pk_fma_f32 v[10:11], v[16:17], v[192:193], v[10:11] op_sel_hi:[0,1,1]
	v_pk_fma_f32 v[12:13], v[20:21], v[186:187], v[12:13] op_sel_hi:[0,1,1]
	v_pk_mul_f32 v[14:15], v[34:35], v[156:157] op_sel:[0,1] op_sel_hi:[1,0]
	v_pk_mul_f32 v[16:17], v[38:39], v[178:179] op_sel:[0,1] op_sel_hi:[1,0]
	v_pk_mul_f32 v[20:21], v[42:43], v[180:181] op_sel:[0,1] op_sel_hi:[1,0]
	v_pk_mul_f32 v[22:23], v[46:47], v[190:191] op_sel:[0,1] op_sel_hi:[1,0]
	v_xor_b32_e32 v78, 0x80000000, v69
	v_xor_b32_e32 v82, 0x80000000, v73
	v_xor_b32_e32 v86, 0x80000000, v77
	v_xor_b32_e32 v90, 0x80000000, v81
	v_xor_b32_e32 v94, 0x80000000, v85
	v_xor_b32_e32 v98, 0x80000000, v89
	v_xor_b32_e32 v102, 0x80000000, v93
	v_xor_b32_e32 v106, 0x80000000, v97
	v_xor_b32_e32 v110, 0x80000000, v101
	v_xor_b32_e32 v114, 0x80000000, v105
	v_xor_b32_e32 v118, 0x80000000, v109
	v_xor_b32_e32 v122, 0x80000000, v113
	v_xor_b32_e32 v124, 0x80000000, v117
	v_xor_b32_e32 v126, 0x80000000, v121
	v_mov_b32_e32 v79, v69
	v_mov_b32_e32 v83, v73
	v_mov_b32_e32 v87, v77
	v_mov_b32_e32 v91, v81
	v_mov_b32_e32 v95, v85
	v_mov_b32_e32 v99, v89
	v_mov_b32_e32 v103, v93
	v_mov_b32_e32 v107, v97
	v_mov_b32_e32 v111, v101
	v_mov_b32_e32 v115, v105
	v_mov_b32_e32 v119, v109
	v_mov_b32_e32 v123, v113
	v_mov_b32_e32 v125, v117
	v_mov_b32_e32 v127, v121
	v_pk_add_f32 v[128:129], v[128:129], v[134:135] neg_lo:[0,1] neg_hi:[0,1]
	v_pk_fma_f32 v[14:15], v[24:25], v[156:157], v[14:15] op_sel_hi:[0,1,1]
	v_pk_fma_f32 v[16:17], v[28:29], v[178:179], v[16:17] op_sel_hi:[0,1,1]
	v_pk_fma_f32 v[20:21], v[32:33], v[180:181], v[20:21] op_sel_hi:[0,1,1]
	v_pk_fma_f32 v[22:23], v[36:37], v[190:191], v[22:23] op_sel_hi:[0,1,1]
	v_pk_mul_f32 v[24:25], v[50:51], v[160:161] op_sel:[0,1] op_sel_hi:[1,0]
	v_pk_mul_f32 v[26:27], v[54:55], v[188:189] op_sel:[0,1] op_sel_hi:[1,0]
	v_pk_mul_f32 v[28:29], v[58:59], v[158:159] op_sel:[0,1] op_sel_hi:[1,0]
	v_pk_mul_f32 v[30:31], v[62:63], v[174:175] op_sel:[0,1] op_sel_hi:[1,0]
	v_pk_mul_f32 v[32:33], v[66:67], v[140:141] op_sel:[0,1] op_sel_hi:[1,0]
	v_pk_mul_f32 v[34:35], v[70:71], v[142:143] op_sel:[0,1] op_sel_hi:[1,0]
	v_pk_mul_f32 v[36:37], v[74:75], v[148:149] op_sel:[0,1] op_sel_hi:[1,0]
	v_pk_fma_f32 v[24:25], v[40:41], v[160:161], v[24:25] op_sel_hi:[0,1,1]
	v_pk_fma_f32 v[26:27], v[44:45], v[188:189], v[26:27] op_sel_hi:[0,1,1]
	v_pk_fma_f32 v[28:29], v[48:49], v[158:159], v[28:29] op_sel_hi:[0,1,1]
	v_pk_fma_f32 v[30:31], v[52:53], v[174:175], v[30:31] op_sel_hi:[0,1,1]
	v_pk_fma_f32 v[32:33], v[56:57], v[140:141], v[32:33] op_sel_hi:[0,1,1]
	v_pk_fma_f32 v[34:35], v[60:61], v[142:143], v[34:35] op_sel_hi:[0,1,1]
	v_pk_fma_f32 v[36:37], v[64:65], v[148:149], v[36:37] op_sel_hi:[0,1,1]
	v_pk_mul_f32 v[38:39], v[78:79], v[170:171] op_sel:[0,1] op_sel_hi:[1,0]
	v_pk_mul_f32 v[40:41], v[82:83], v[136:137] op_sel:[0,1] op_sel_hi:[1,0]
	v_pk_mul_f32 v[42:43], v[86:87], v[164:165] op_sel:[0,1] op_sel_hi:[1,0]
	v_pk_mul_f32 v[44:45], v[90:91], v[150:151] op_sel:[0,1] op_sel_hi:[1,0]
	v_pk_mul_f32 v[46:47], v[94:95], v[166:167] op_sel:[0,1] op_sel_hi:[1,0]
	v_pk_mul_f32 v[48:49], v[98:99], v[132:133] op_sel:[0,1] op_sel_hi:[1,0]
	v_pk_mul_f32 v[50:51], v[102:103], v[162:163] op_sel:[0,1] op_sel_hi:[1,0]
	v_pk_mul_f32 v[52:53], v[106:107], v[176:177] op_sel:[0,1] op_sel_hi:[1,0]
	v_pk_mul_f32 v[54:55], v[110:111], v[172:173] op_sel:[0,1] op_sel_hi:[1,0]
	v_pk_mul_f32 v[56:57], v[114:115], v[138:139] op_sel:[0,1] op_sel_hi:[1,0]
	v_pk_mul_f32 v[58:59], v[118:119], v[182:183] op_sel:[0,1] op_sel_hi:[1,0]
	v_pk_mul_f32 v[60:61], v[122:123], v[152:153] op_sel:[0,1] op_sel_hi:[1,0]
	v_pk_mul_f32 v[62:63], v[124:125], v[144:145] op_sel:[0,1] op_sel_hi:[1,0]
	v_pk_mul_f32 v[64:65], v[126:127], v[128:129] op_sel:[0,1] op_sel_hi:[1,0]
	v_pk_fma_f32 v[38:39], v[68:69], v[170:171], v[38:39] op_sel_hi:[0,1,1]
	v_pk_fma_f32 v[40:41], v[72:73], v[136:137], v[40:41] op_sel_hi:[0,1,1]
	v_pk_fma_f32 v[42:43], v[76:77], v[164:165], v[42:43] op_sel_hi:[0,1,1]
	v_pk_fma_f32 v[44:45], v[80:81], v[150:151], v[44:45] op_sel_hi:[0,1,1]
	v_pk_fma_f32 v[46:47], v[84:85], v[166:167], v[46:47] op_sel_hi:[0,1,1]
	v_pk_fma_f32 v[48:49], v[88:89], v[132:133], v[48:49] op_sel_hi:[0,1,1]
	v_pk_fma_f32 v[50:51], v[92:93], v[162:163], v[50:51] op_sel_hi:[0,1,1]
	v_pk_fma_f32 v[52:53], v[96:97], v[176:177], v[52:53] op_sel_hi:[0,1,1]
	v_pk_fma_f32 v[54:55], v[100:101], v[172:173], v[54:55] op_sel_hi:[0,1,1]
	v_pk_fma_f32 v[56:57], v[104:105], v[138:139], v[56:57] op_sel_hi:[0,1,1]
	v_pk_fma_f32 v[58:59], v[108:109], v[182:183], v[58:59] op_sel_hi:[0,1,1]
	v_pk_fma_f32 v[60:61], v[112:113], v[152:153], v[60:61] op_sel_hi:[0,1,1]
	v_pk_fma_f32 v[62:63], v[116:117], v[144:145], v[62:63] op_sel_hi:[0,1,1]
	v_pk_fma_f32 v[64:65], v[120:121], v[128:129], v[64:65] op_sel_hi:[0,1,1]
	ds_write2_b64 v18, v[130:131], v[34:35] offset1:16
	ds_write2_b64 v18, v[16:17], v[50:51] offset0:33 offset1:49
	ds_write2_b64 v18, v[8:9], v[42:43] offset0:66 offset1:82
	ds_write2_b64 v18, v[26:27], v[58:59] offset0:99 offset1:115
	ds_write2_b64 v18, v[4:5], v[38:39] offset0:132 offset1:148
	ds_write2_b64 v18, v[22:23], v[54:55] offset0:165 offset1:181
	ds_write2_b64 v18, v[12:13], v[46:47] offset0:198 offset1:214
	ds_write2_b64 v18, v[30:31], v[62:63] offset0:231 offset1:247
	ds_write2_b64 v196, v[2:3], v[36:37] offset0:8 offset1:24
	ds_write2_b64 v196, v[20:21], v[52:53] offset0:41 offset1:57
	ds_write2_b64 v196, v[10:11], v[44:45] offset0:74 offset1:90
	ds_write2_b64 v196, v[28:29], v[60:61] offset0:107 offset1:123
	ds_write2_b64 v196, v[6:7], v[40:41] offset0:140 offset1:156
	ds_write2_b64 v196, v[24:25], v[56:57] offset0:173 offset1:189
	ds_write2_b64 v196, v[14:15], v[48:49] offset0:206 offset1:222
	ds_write2_b64 v196, v[32:33], v[64:65] offset0:239 offset1:255
	v_ashrrev_i32_e32 v2, 31, v210
	v_lshrrev_b32_e32 v2, 23, v2
	v_add_u32_e32 v2, v210, v2
	s_lshl_b64 s[74:75], s[76:77], 16
	v_and_b32_e32 v2, 0xfffffe00, v2
	s_add_u32 s0, s54, s74
	v_sub_u32_e32 v2, v210, v2
	s_addc_u32 s1, s55, s75
	v_ashrrev_i32_e32 v3, 31, v2
	v_lshl_add_u64 v[14:15], v[2:3], 3, s[0:1]
	v_add_co_u32_e32 v2, vcc, s92, v14
	s_mov_b32 s0, 0x8000
	s_nop 0
	v_addc_co_u32_e32 v3, vcc, 0, v15, vcc
	v_add_co_u32_e32 v4, vcc, s95, v14
	s_waitcnt lgkmcnt(0)
	s_nop 0
	v_addc_co_u32_e32 v5, vcc, 0, v15, vcc
	v_add_co_u32_e32 v8, vcc, s96, v14
	s_barrier
	s_nop 0
	v_addc_co_u32_e32 v9, vcc, 0, v15, vcc
	global_load_dwordx2 v[24:25], v[4:5], off offset:-4096 nt
	global_load_dwordx2 v[12:13], v[4:5], off nt
	global_load_dwordx2 v[6:7], v[8:9], off offset:-4096 nt
	s_nop 0
	global_load_dwordx2 v[4:5], v[8:9], off nt
	v_add_co_u32_e32 v8, vcc, s0, v14
	s_waitcnt vmcnt(3)
	v_cvt_f32_f16_sdwa v174, v24 dst_sel:DWORD dst_unused:UNUSED_PAD src0_sel:WORD_1
	v_addc_co_u32_e32 v9, vcc, 0, v15, vcc
	v_add_co_u32_e32 v10, vcc, s34, v14
	v_cvt_f32_f16_e32 v175, v25
	s_nop 0
	v_addc_co_u32_e32 v11, vcc, 0, v15, vcc
	global_load_dwordx2 v[16:17], v[8:9], off offset:-4096 nt
	global_load_dwordx2 v[122:123], v[8:9], off nt
	global_load_dwordx2 v[46:47], v[10:11], off offset:-4096 nt
	global_load_dwordx2 v[36:37], v[10:11], off nt
	v_add_co_u32_e32 v8, vcc, s35, v14
	v_cvt_f32_f16_sdwa v177, v25 dst_sel:DWORD dst_unused:UNUSED_PAD src0_sel:WORD_1
	s_nop 0
	v_addc_co_u32_e32 v9, vcc, 0, v15, vcc
	v_add_co_u32_e32 v22, vcc, s30, v14
	v_cvt_f32_f16_e32 v176, v24
	s_nop 0
	v_addc_co_u32_e32 v23, vcc, 0, v15, vcc
	global_load_dwordx2 v[26:27], v[8:9], off offset:-4096 nt
	global_load_dwordx2 v[20:21], v[8:9], off nt
	global_load_dwordx2 v[10:11], v[22:23], off offset:-4096 nt
	s_nop 0
	global_load_dwordx2 v[8:9], v[22:23], off nt
	v_add_co_u32_e32 v22, vcc, s31, v14
	s_waitcnt vmcnt(10)
	v_cvt_f32_f16_sdwa v164, v12 dst_sel:DWORD dst_unused:UNUSED_PAD src0_sel:WORD_1
	v_addc_co_u32_e32 v23, vcc, 0, v15, vcc
	global_load_dwordx2 v[30:31], v[2:3], off offset:-4096 nt
	global_load_dwordx2 v[28:29], v[2:3], off nt
	s_nop 0
	global_load_dwordx2 v[2:3], v[22:23], off nt
	global_load_dwordx2 v[32:33], v[14:15], off nt
	v_mov_b32_e32 v14, v210
	v_cvt_f32_f16_e32 v165, v13
	v_ashrrev_i32_e32 v15, 31, v14
	v_lshrrev_b32_e32 v15, 23, v15
	v_add_u32_e32 v15, v14, v15
	v_ashrrev_i32_e32 v15, 9, v15
	v_mul_i32_i24_e32 v18, 0x200, v15
	v_sub_u32_e32 v18, v14, v18
	v_lshlrev_b32_e32 v14, 14, v15
	v_lshlrev_b32_e32 v15, 1, v18
	v_bfrev_b32_e32 v15, v15
	v_lshrrev_b32_e32 v15, 22, v15
	v_sub_u32_e32 v15, 0x400, v15
	v_bfrev_b32_e32 v15, v15
	v_lshrrev_b32_e32 v15, 18, v15
	v_and_b32_e32 v15, 0x3ff0, v15
	v_cmp_eq_u32_e64 s[0:1], 0, v18
	v_lshl_add_u32 v22, v18, 5, v14
	v_lshl_add_u32 v23, v22, 3, 0
	v_cndmask_b32_e64 v15, v15, 16, s[0:1]
	v_or_b32_e32 v14, v15, v14
	v_ashrrev_i32_e32 v22, 2, v22
	v_ashrrev_i32_e32 v15, 5, v14
	v_add_u32_e32 v211, v23, v22
	v_lshlrev_b32_e32 v14, 3, v14
	v_lshlrev_b32_e32 v15, 3, v15
	v_add3_u32 v212, 0, v14, v15
	ds_read2_b64 v[38:41], v211 offset1:1
	ds_read2_b64 v[42:45], v211 offset0:2 offset1:3
	ds_read2_b64 v[48:51], v212 offset1:1
	ds_read2_b64 v[52:55], v212 offset0:2 offset1:3
	ds_read2_b64 v[56:59], v211 offset0:4 offset1:5
	ds_read2_b64 v[60:63], v211 offset0:6 offset1:7
	ds_read2_b64 v[68:71], v212 offset0:4 offset1:5
	ds_read2_b64 v[72:75], v212 offset0:6 offset1:7
	ds_read2_b64 v[64:67], v211 offset0:8 offset1:9
	ds_read2_b64 v[76:79], v211 offset0:10 offset1:11
	ds_read2_b64 v[80:83], v212 offset0:8 offset1:9
	ds_read2_b64 v[98:101], v212 offset0:10 offset1:11
	ds_read2_b64 v[84:87], v211 offset0:12 offset1:13
	ds_read2_b64 v[88:91], v211 offset0:14 offset1:15
	ds_read2_b64 v[102:105], v212 offset0:12 offset1:13
	ds_read2_b64 v[106:109], v212 offset0:14 offset1:15
	s_waitcnt lgkmcnt(7)
	v_pk_add_f32 v[14:15], v[38:39], v[64:65]
	v_pk_add_f32 v[22:23], v[38:39], v[64:65] neg_lo:[0,1] neg_hi:[0,1]
	v_pk_add_f32 v[38:39], v[40:41], v[66:67] neg_lo:[0,1] neg_hi:[0,1]
	v_pk_add_f32 v[34:35], v[40:41], v[66:67]
	v_pk_mul_f32 v[40:41], v[38:39], s[18:19]
	v_cmp_ne_u32_e32 vcc, 0, v18
	v_pk_fma_f32 v[38:39], v[38:39], s[16:17], v[40:41] op_sel:[0,0,1] op_sel_hi:[1,0,0]
	s_waitcnt lgkmcnt(6)
	v_pk_add_f32 v[40:41], v[42:43], v[76:77]
	v_pk_add_f32 v[42:43], v[42:43], v[76:77] neg_lo:[0,1] neg_hi:[0,1]
	v_bfrev_b32_e32 v18, v18
	v_pk_mul_f32 v[64:65], v[42:43], s[36:37]
	v_lshrrev_b32_e32 v18, 23, v18
	v_pk_fma_f32 v[42:43], v[42:43], s[78:79], v[64:65] op_sel:[0,0,1] op_sel_hi:[1,0,0]
	v_pk_add_f32 v[64:65], v[44:45], v[78:79]
	v_pk_add_f32 v[44:45], v[44:45], v[78:79] neg_lo:[0,1] neg_hi:[0,1]
	s_waitcnt lgkmcnt(3)
	v_pk_add_f32 v[78:79], v[58:59], v[86:87]
	v_pk_mul_f32 v[66:67], v[44:45], s[40:41]
	v_pk_add_f32 v[58:59], v[58:59], v[86:87] neg_lo:[0,1] neg_hi:[0,1]
	v_pk_fma_f32 v[44:45], v[44:45], s[80:81], v[66:67] op_sel:[0,0,1] op_sel_hi:[1,0,0]
	v_pk_add_f32 v[66:67], v[56:57], v[84:85]
	v_pk_add_f32 v[76:77], v[56:57], v[84:85] neg_lo:[0,1] neg_hi:[0,1]
	v_pk_mul_f32 v[84:85], v[58:59], s[40:41]
	v_pk_fma_f32 v[58:59], v[58:59], s[80:81], v[84:85] op_sel:[0,0,1] op_sel_hi:[1,0,0] neg_lo:[1,0,0] neg_hi:[1,0,0]
	s_waitcnt lgkmcnt(2)
	v_pk_add_f32 v[84:85], v[60:61], v[88:89]
	v_pk_add_f32 v[60:61], v[60:61], v[88:89] neg_lo:[0,1] neg_hi:[0,1]
	v_pk_mul_f32 v[86:87], v[60:61], s[36:37]
	v_pk_add_f32 v[56:57], v[22:23], v[76:77] op_sel:[0,1] op_sel_hi:[1,0] neg_hi:[0,1]
	v_pk_fma_f32 v[60:61], v[60:61], s[78:79], v[86:87] op_sel:[0,0,1] op_sel_hi:[1,0,0] neg_lo:[1,0,0] neg_hi:[1,0,0]
	v_pk_add_f32 v[86:87], v[62:63], v[90:91]
	v_pk_add_f32 v[62:63], v[62:63], v[90:91] neg_lo:[0,1] neg_hi:[0,1]
	v_pk_add_f32 v[90:91], v[64:65], v[86:87]
	v_pk_mul_f32 v[88:89], v[62:63], s[18:19]
	v_pk_add_f32 v[64:65], v[64:65], v[86:87] neg_lo:[0,1] neg_hi:[0,1]
	v_pk_fma_f32 v[62:63], v[62:63], s[16:17], v[88:89] op_sel:[0,0,1] op_sel_hi:[1,0,0] neg_lo:[1,0,0] neg_hi:[1,0,0]
	v_pk_add_f32 v[88:89], v[14:15], v[66:67]
	v_pk_add_f32 v[14:15], v[14:15], v[66:67] neg_lo:[0,1] neg_hi:[0,1]
	v_pk_add_f32 v[66:67], v[34:35], v[78:79]
	v_pk_add_f32 v[34:35], v[34:35], v[78:79] neg_lo:[0,1] neg_hi:[0,1]
	v_pk_add_f32 v[22:23], v[22:23], v[76:77] op_sel:[0,1] op_sel_hi:[1,0] neg_lo:[0,1]
	v_pk_mul_f32 v[78:79], v[34:35], s[36:37]
	v_pk_add_f32 v[76:77], v[38:39], v[58:59]
	v_pk_add_f32 v[38:39], v[38:39], v[58:59] neg_lo:[0,1] neg_hi:[0,1]
	v_pk_fma_f32 v[34:35], v[34:35], s[78:79], v[78:79] op_sel:[0,0,1] op_sel_hi:[1,0,0]
	v_pk_add_f32 v[78:79], v[40:41], v[84:85]
	v_pk_add_f32 v[84:85], v[40:41], v[84:85] neg_lo:[0,1] neg_hi:[0,1]
	v_pk_mul_f32 v[86:87], v[64:65], s[36:37]
	v_pk_mul_f32 v[58:59], v[38:39], s[36:37]
	v_pk_fma_f32 v[64:65], v[64:65], s[78:79], v[86:87] op_sel:[0,0,1] op_sel_hi:[1,0,0] neg_lo:[1,0,0] neg_hi:[1,0,0]
	v_pk_fma_f32 v[38:39], v[38:39], s[78:79], v[58:59] op_sel:[0,0,1] op_sel_hi:[1,0,0]
	v_pk_add_f32 v[58:59], v[42:43], v[60:61]
	v_pk_add_f32 v[86:87], v[44:45], v[62:63]
	v_pk_add_f32 v[44:45], v[44:45], v[62:63] neg_lo:[0,1] neg_hi:[0,1]
	v_pk_mul_f32 v[62:63], v[44:45], s[36:37]
	v_pk_add_f32 v[40:41], v[14:15], v[84:85] op_sel:[0,1] op_sel_hi:[1,0] neg_hi:[0,1]
	v_pk_add_f32 v[14:15], v[14:15], v[84:85] op_sel:[0,1] op_sel_hi:[1,0] neg_lo:[0,1]
	v_pk_add_f32 v[84:85], v[34:35], v[64:65]
	v_pk_add_f32 v[64:65], v[34:35], v[64:65] neg_lo:[0,1] neg_hi:[0,1]
	v_pk_add_f32 v[94:95], v[56:57], v[58:59]
	v_pk_add_f32 v[56:57], v[56:57], v[58:59] neg_lo:[0,1] neg_hi:[0,1]
	v_pk_add_f32 v[58:59], v[76:77], v[86:87]
	v_pk_fma_f32 v[44:45], v[44:45], s[78:79], v[62:63] op_sel:[0,0,1] op_sel_hi:[1,0,0] neg_lo:[1,0,0] neg_hi:[1,0,0]
	v_pk_add_f32 v[62:63], v[88:89], v[78:79]
	v_pk_add_f32 v[78:79], v[88:89], v[78:79] neg_lo:[0,1] neg_hi:[0,1]
	v_pk_add_f32 v[88:89], v[66:67], v[90:91]
	v_pk_add_f32 v[110:111], v[76:77], v[86:87] neg_lo:[0,1] neg_hi:[0,1]
	v_pk_add_f32 v[86:87], v[94:95], v[58:59]
	v_pk_add_f32 v[34:35], v[94:95], v[58:59] neg_lo:[0,1] neg_hi:[0,1]
	v_pk_add_f32 v[58:59], v[50:51], v[82:83]
	v_pk_add_f32 v[50:51], v[50:51], v[82:83] neg_lo:[0,1] neg_hi:[0,1]
	v_pk_add_f32 v[60:61], v[42:43], v[60:61] neg_lo:[0,1] neg_hi:[0,1]
	v_pk_add_f32 v[148:149], v[62:63], v[88:89]
	v_pk_add_f32 v[138:139], v[62:63], v[88:89] neg_lo:[0,1] neg_hi:[0,1]
	v_pk_mul_f32 v[62:63], v[50:51], s[18:19]
	v_pk_add_f32 v[90:91], v[66:67], v[90:91] neg_lo:[0,1] neg_hi:[0,1]
	v_pk_fma_f32 v[50:51], v[50:51], s[16:17], v[62:63] op_sel:[0,0,1] op_sel_hi:[1,0,0]
	v_pk_add_f32 v[62:63], v[52:53], v[98:99]
	v_pk_add_f32 v[52:53], v[52:53], v[98:99] neg_lo:[0,1] neg_hi:[0,1]
	v_pk_add_f32 v[112:113], v[22:23], v[60:61] op_sel:[0,1] op_sel_hi:[1,0] neg_hi:[0,1]
	v_pk_add_f32 v[114:115], v[22:23], v[60:61] op_sel:[0,1] op_sel_hi:[1,0] neg_lo:[0,1]
	v_pk_add_f32 v[96:97], v[40:41], v[84:85]
	v_pk_add_f32 v[66:67], v[40:41], v[84:85] neg_lo:[0,1] neg_hi:[0,1]
	v_pk_add_f32 v[60:61], v[14:15], v[64:65] op_sel:[0,1] op_sel_hi:[1,0] neg_hi:[0,1]
	v_pk_add_f32 v[84:85], v[14:15], v[64:65] op_sel:[0,1] op_sel_hi:[1,0] neg_lo:[0,1]
	v_pk_mul_f32 v[64:65], v[52:53], s[36:37]
	v_pk_fma_f32 v[52:53], v[52:53], s[78:79], v[64:65] op_sel:[0,0,1] op_sel_hi:[1,0,0]
	v_pk_add_f32 v[64:65], v[54:55], v[100:101]
	v_pk_add_f32 v[54:55], v[54:55], v[100:101] neg_lo:[0,1] neg_hi:[0,1]
	v_pk_mul_f32 v[76:77], v[54:55], s[40:41]
	v_pk_add_f32 v[92:93], v[78:79], v[90:91] op_sel:[0,1] op_sel_hi:[1,0] neg_hi:[0,1]
	v_pk_fma_f32 v[54:55], v[54:55], s[80:81], v[76:77] op_sel:[0,0,1] op_sel_hi:[1,0,0]
	s_waitcnt lgkmcnt(1)
	v_pk_add_f32 v[76:77], v[68:69], v[102:103]
	v_pk_add_f32 v[68:69], v[68:69], v[102:103] neg_lo:[0,1] neg_hi:[0,1]
	v_pk_add_f32 v[88:89], v[78:79], v[90:91] op_sel:[0,1] op_sel_hi:[1,0] neg_lo:[0,1]
	v_xor_b32_e32 v79, 0x80000000, v68
	v_mov_b32_e32 v78, v69
	v_pk_add_f32 v[68:69], v[70:71], v[104:105]
	v_pk_add_f32 v[70:71], v[70:71], v[104:105] neg_lo:[0,1] neg_hi:[0,1]
	v_pk_add_f32 v[22:23], v[38:39], v[44:45]
	v_pk_add_f32 v[116:117], v[38:39], v[44:45] neg_lo:[0,1] neg_hi:[0,1]
	v_pk_add_f32 v[40:41], v[56:57], v[110:111] op_sel:[0,1] op_sel_hi:[1,0] neg_hi:[0,1]
	v_pk_add_f32 v[44:45], v[56:57], v[110:111] op_sel:[0,1] op_sel_hi:[1,0] neg_lo:[0,1]
	v_pk_add_f32 v[56:57], v[48:49], v[80:81]
	v_pk_add_f32 v[48:49], v[48:49], v[80:81] neg_lo:[0,1] neg_hi:[0,1]
	v_pk_mul_f32 v[80:81], v[70:71], s[40:41]
	v_cvt_f32_u32_e32 v18, v18
	v_pk_fma_f32 v[70:71], v[70:71], s[80:81], v[80:81] op_sel:[0,0,1] op_sel_hi:[1,0,0] neg_lo:[1,0,0] neg_hi:[1,0,0]
	s_waitcnt lgkmcnt(0)
	v_pk_add_f32 v[80:81], v[72:73], v[106:107]
	v_pk_add_f32 v[72:73], v[72:73], v[106:107] neg_lo:[0,1] neg_hi:[0,1]
	v_mul_f32_e32 v18, 0x38000000, v18
	v_pk_mul_f32 v[82:83], v[72:73], s[36:37]
	v_cndmask_b32_e64 v18, v18, v208, s[0:1]
	v_pk_fma_f32 v[72:73], v[72:73], s[78:79], v[82:83] op_sel:[0,0,1] op_sel_hi:[1,0,0] neg_lo:[1,0,0] neg_hi:[1,0,0]
	v_pk_add_f32 v[82:83], v[74:75], v[108:109]
	v_pk_add_f32 v[74:75], v[74:75], v[108:109] neg_lo:[0,1] neg_hi:[0,1]
	s_nop 0
	v_pk_mul_f32 v[90:91], v[74:75], s[18:19]
	v_pk_fma_f32 v[74:75], v[74:75], s[16:17], v[90:91] op_sel:[0,0,1] op_sel_hi:[1,0,0] neg_lo:[1,0,0] neg_hi:[1,0,0]
	v_pk_add_f32 v[90:91], v[56:57], v[76:77]
	v_pk_add_f32 v[56:57], v[56:57], v[76:77] neg_lo:[0,1] neg_hi:[0,1]
	v_pk_add_f32 v[76:77], v[58:59], v[68:69]
	v_pk_add_f32 v[58:59], v[58:59], v[68:69] neg_lo:[0,1] neg_hi:[0,1]
	v_pk_add_f32 v[14:15], v[114:115], v[116:117] op_sel:[0,1] op_sel_hi:[1,0] neg_hi:[0,1]
	v_pk_mul_f32 v[68:69], v[58:59], s[36:37]
	v_pk_add_f32 v[38:39], v[114:115], v[116:117] op_sel:[0,1] op_sel_hi:[1,0] neg_lo:[0,1]
	v_pk_fma_f32 v[58:59], v[58:59], s[78:79], v[68:69] op_sel:[0,0,1] op_sel_hi:[1,0,0]
	v_pk_add_f32 v[68:69], v[62:63], v[80:81]
	v_pk_add_f32 v[80:81], v[62:63], v[80:81] neg_lo:[0,1] neg_hi:[0,1]
	s_waitcnt vmcnt(0)
	v_cvt_f32_f16_e32 v193, v33
	s_nop 0
	s_nop 0
	v_pk_add_f32 v[62:63], v[64:65], v[82:83]
	v_pk_add_f32 v[64:65], v[64:65], v[82:83] neg_lo:[0,1] neg_hi:[0,1]
	v_cvt_f32_f16_sdwa v192, v32 dst_sel:DWORD dst_unused:UNUSED_PAD src0_sel:WORD_1
	v_pk_mul_f32 v[82:83], v[64:65], s[36:37]
	v_cvt_f32_f16_e32 v194, v32
	v_pk_fma_f32 v[64:65], v[64:65], s[78:79], v[82:83] op_sel:[0,0,1] op_sel_hi:[1,0,0] neg_lo:[1,0,0] neg_hi:[1,0,0]
	v_pk_add_f32 v[82:83], v[48:49], v[78:79]
	v_pk_add_f32 v[48:49], v[48:49], v[78:79] neg_lo:[0,1] neg_hi:[0,1]
	v_pk_add_f32 v[78:79], v[50:51], v[70:71]
	v_pk_add_f32 v[50:51], v[50:51], v[70:71] neg_lo:[0,1] neg_hi:[0,1]
	v_cvt_f32_f16_sdwa v195, v33 dst_sel:DWORD dst_unused:UNUSED_PAD src0_sel:WORD_1
	v_pk_mul_f32 v[70:71], v[50:51], s[36:37]
	v_cvt_f32_f16_sdwa v170, v30 dst_sel:DWORD dst_unused:UNUSED_PAD src0_sel:WORD_1
	v_pk_fma_f32 v[50:51], v[50:51], s[78:79], v[70:71] op_sel:[0,0,1] op_sel_hi:[1,0,0]
	v_pk_add_f32 v[70:71], v[52:53], v[72:73]
	v_pk_add_f32 v[72:73], v[52:53], v[72:73] neg_lo:[0,1] neg_hi:[0,1]
	v_cvt_f32_f16_e32 v171, v31
	s_nop 0
	s_nop 0
	v_pk_add_f32 v[52:53], v[54:55], v[74:75]
	v_pk_add_f32 v[54:55], v[54:55], v[74:75] neg_lo:[0,1] neg_hi:[0,1]
	v_cvt_f32_f16_sdwa v185, v31 dst_sel:DWORD dst_unused:UNUSED_PAD src0_sel:WORD_1
	v_pk_mul_f32 v[74:75], v[54:55], s[36:37]
	v_cvt_f32_f16_e32 v184, v30
	v_pk_fma_f32 v[54:55], v[54:55], s[78:79], v[74:75] op_sel:[0,0,1] op_sel_hi:[1,0,0] neg_lo:[1,0,0] neg_hi:[1,0,0]
	v_pk_add_f32 v[74:75], v[90:91], v[68:69]
	v_pk_add_f32 v[68:69], v[90:91], v[68:69] neg_lo:[0,1] neg_hi:[0,1]
	v_pk_add_f32 v[90:91], v[76:77], v[62:63]
	v_pk_add_f32 v[62:63], v[76:77], v[62:63] neg_lo:[0,1] neg_hi:[0,1]
	v_cvt_f32_f16_sdwa v172, v28 dst_sel:DWORD dst_unused:UNUSED_PAD src0_sel:WORD_1
	v_xor_b32_e32 v77, 0x80000000, v62
	v_mov_b32_e32 v76, v63
	v_pk_add_f32 v[62:63], v[56:57], v[80:81] op_sel:[0,1] op_sel_hi:[1,0] neg_hi:[0,1]
	v_pk_add_f32 v[56:57], v[56:57], v[80:81] op_sel:[0,1] op_sel_hi:[1,0] neg_lo:[0,1]
	v_pk_add_f32 v[80:81], v[58:59], v[64:65]
	v_pk_add_f32 v[58:59], v[58:59], v[64:65] neg_lo:[0,1] neg_hi:[0,1]
	v_cvt_f32_f16_e32 v173, v29
	v_xor_b32_e32 v65, 0x80000000, v58
	v_mov_b32_e32 v64, v59
	v_pk_add_f32 v[58:59], v[82:83], v[70:71]
	v_pk_add_f32 v[70:71], v[82:83], v[70:71] neg_lo:[0,1] neg_hi:[0,1]
	v_pk_add_f32 v[82:83], v[78:79], v[52:53]
	v_pk_add_f32 v[52:53], v[78:79], v[52:53] neg_lo:[0,1] neg_hi:[0,1]
	v_pk_add_f32 v[118:119], v[58:59], v[82:83]
	v_pk_add_f32 v[134:135], v[58:59], v[82:83] neg_lo:[0,1] neg_hi:[0,1]
	v_cos_f32_e32 v83, v18
	v_sin_f32_e32 v82, v18
	v_cvt_f32_f16_sdwa v181, v29 dst_sel:DWORD dst_unused:UNUSED_PAD src0_sel:WORD_1
	v_cvt_f32_f16_e32 v180, v28
	v_cvt_f32_f16_sdwa v167, v13 dst_sel:DWORD dst_unused:UNUSED_PAD src0_sel:WORD_1
	v_cvt_f32_f16_e32 v166, v12
	v_cvt_f32_f16_e32 v154, v6
	v_cvt_f32_f16_e32 v155, v7
	v_cvt_f32_f16_sdwa v157, v7 dst_sel:DWORD dst_unused:UNUSED_PAD src0_sel:WORD_1
	v_cvt_f32_f16_sdwa v156, v6 dst_sel:DWORD dst_unused:UNUSED_PAD src0_sel:WORD_1
	v_cvt_f32_f16_sdwa v140, v4 dst_sel:DWORD dst_unused:UNUSED_PAD src0_sel:WORD_1
	v_cvt_f32_f16_e32 v141, v5
	v_cvt_f32_f16_sdwa v143, v5 dst_sel:DWORD dst_unused:UNUSED_PAD src0_sel:WORD_1
	v_cvt_f32_f16_e32 v142, v4
	v_cvt_f32_f16_e32 v124, v16
	v_cvt_f32_f16_e32 v125, v17
	v_cvt_f32_f16_sdwa v127, v17 dst_sel:DWORD dst_unused:UNUSED_PAD src0_sel:WORD_1
	v_cvt_f32_f16_sdwa v126, v16 dst_sel:DWORD dst_unused:UNUSED_PAD src0_sel:WORD_1
	v_cvt_f32_f16_sdwa v114, v122 dst_sel:DWORD dst_unused:UNUSED_PAD src0_sel:WORD_1
	v_cvt_f32_f16_e32 v115, v123
	v_cvt_f32_f16_sdwa v117, v123 dst_sel:DWORD dst_unused:UNUSED_PAD src0_sel:WORD_1
	v_cvt_f32_f16_e32 v116, v122
	v_xor_b32_e32 v79, 0x80000000, v52
	v_mov_b32_e32 v78, v53
	v_pk_add_f32 v[52:53], v[48:49], v[72:73] op_sel:[0,1] op_sel_hi:[1,0] neg_hi:[0,1]
	v_pk_add_f32 v[48:49], v[48:49], v[72:73] op_sel:[0,1] op_sel_hi:[1,0] neg_lo:[0,1]
	v_pk_add_f32 v[72:73], v[50:51], v[54:55]
	v_pk_add_f32 v[50:51], v[50:51], v[54:55] neg_lo:[0,1] neg_hi:[0,1]
	v_pk_fma_f32 v[160:161], v[82:83], 0, v[82:83] op_sel:[0,0,1] op_sel_hi:[1,0,0] neg_lo:[1,0,0] neg_hi:[1,0,0]
	v_xor_b32_e32 v55, 0x80000000, v50
	v_mov_b32_e32 v54, v51
	v_pk_fma_f32 v[198:199], v[82:83], 0, v[82:83] op_sel:[0,0,1] op_sel_hi:[1,0,0]
	v_pk_add_f32 v[42:43], v[112:113], v[22:23]
	v_pk_add_f32 v[22:23], v[112:113], v[22:23] neg_lo:[0,1] neg_hi:[0,1]
	v_pk_add_f32 v[98:99], v[74:75], v[90:91]
	v_pk_add_f32 v[100:101], v[74:75], v[90:91] neg_lo:[0,1] neg_hi:[0,1]
	v_pk_add_f32 v[102:103], v[68:69], v[76:77]
	v_pk_add_f32 v[106:107], v[68:69], v[76:77] neg_lo:[0,1] neg_hi:[0,1]
	v_pk_add_f32 v[104:105], v[62:63], v[80:81]
	v_pk_add_f32 v[108:109], v[62:63], v[80:81] neg_lo:[0,1] neg_hi:[0,1]
	v_pk_add_f32 v[110:111], v[56:57], v[64:65]
	v_pk_add_f32 v[112:113], v[56:57], v[64:65] neg_lo:[0,1] neg_hi:[0,1]
	v_pk_add_f32 v[152:153], v[70:71], v[78:79]
	v_pk_add_f32 v[162:163], v[70:71], v[78:79] neg_lo:[0,1] neg_hi:[0,1]
	v_pk_add_f32 v[178:179], v[52:53], v[72:73]
	v_pk_add_f32 v[182:183], v[52:53], v[72:73] neg_lo:[0,1] neg_hi:[0,1]
	v_pk_add_f32 v[188:189], v[48:49], v[54:55]
	v_pk_add_f32 v[196:197], v[48:49], v[54:55] neg_lo:[0,1] neg_hi:[0,1]
	v_pk_mul_f32 v[186:187], v[82:83], 0 op_sel_hi:[1,0]
	v_mov_b32_e32 v190, v160
	v_mov_b32_e32 v191, v199
	v_mul_f32_e32 v18, 0x3f3504f3, v83
	v_mul_f32_e32 v158, 0xbec3ef15, v83
	v_mul_f32_e32 v132, 0xbf6c835e, v83
	s_and_saveexec_b64 s[0:1], vcc
	s_xor_b64 s[0:1], exec, s[0:1]
	s_cbranch_execz .LBB0_501
	v_pk_add_f32 v[4:5], v[148:149], v[196:197]
	v_pk_add_f32 v[6:7], v[148:149], v[196:197] neg_lo:[0,1] neg_hi:[0,1]
	v_mul_f32_e32 v4, 0.5, v4
	v_mul_f32_e32 v12, 0.5, v7
	v_mov_b32_e32 v7, v5
	v_pk_mul_f32 v[6:7], v[6:7], s[44:45]
	v_pk_mov_b32 v[16:17], v[198:199], v[160:161] op_sel:[1,0]
	v_pk_mul_f32 v[24:25], v[190:191], v[6:7] op_sel:[0,1] op_sel_hi:[1,0]
	v_pk_mul_f32 v[6:7], v[190:191], v[6:7]
	v_pk_add_f32 v[24:25], v[24:25], v[24:25] op_sel:[0,1] op_sel_hi:[0,1]
	v_pk_add_f32 v[28:29], v[4:5], v[24:25]
	v_pk_add_f32 v[4:5], v[4:5], v[24:25] op_sel_hi:[0,1] neg_lo:[0,1] neg_hi:[0,1]
	v_mov_b32_e32 v29, v5
	v_pk_add_f32 v[4:5], v[6:7], v[6:7] op_sel:[0,1] op_sel_hi:[0,1] neg_lo:[0,1] neg_hi:[0,1]
	v_pk_add_f32 v[6:7], v[12:13], v[4:5]
	v_pk_add_f32 v[4:5], v[12:13], v[4:5] op_sel_hi:[0,1] neg_lo:[0,1] neg_hi:[0,1]
	v_mov_b32_e32 v7, v5
	v_pk_mul_f32 v[4:5], v[6:7], v[194:195]
	v_pk_mul_f32 v[6:7], v[6:7], v[192:193]
	v_pk_fma_f32 v[4:5], v[28:29], v[192:193], v[4:5]
	v_pk_fma_f32 v[6:7], v[28:29], v[194:195], v[6:7] neg_lo:[0,0,1] neg_hi:[0,0,1]
	s_mov_b32 s78, s19
	v_pk_add_f32 v[12:13], v[6:7], v[4:5] op_sel:[0,1] op_sel_hi:[1,0] neg_lo:[0,1] neg_hi:[0,1]
	v_pk_add_f32 v[28:29], v[6:7], v[4:5] op_sel:[0,1] op_sel_hi:[1,0]
	v_pk_add_f32 v[4:5], v[4:5], v[6:7] op_sel:[1,0] op_sel_hi:[0,1] neg_lo:[0,1] neg_hi:[0,1]
	v_mov_b32_e32 v13, v29
	v_pk_mul_f32 v[12:13], v[12:13], 0.5 op_sel_hi:[1,0]
	v_mov_b32_e32 v29, v5
	v_mul_f32_e32 v24, v190, v12
	v_pk_fma_f32 v[30:31], v[190:191], v[12:13], v[24:25] op_sel_hi:[1,1,0] neg_lo:[1,0,0] neg_hi:[1,0,0]
	v_mul_f32_e32 v24, v160, v13
	v_pk_fma_f32 v[12:13], v[16:17], v[12:13], v[24:25] op_sel_hi:[1,1,0]
	v_mov_b32_e32 v16, v83
	v_mov_b32_e32 v30, v12
	v_pk_fma_f32 v[4:5], v[28:29], 0.5, v[12:13] op_sel_hi:[1,0,1] neg_lo:[0,0,1] neg_hi:[0,0,1]
	v_pk_fma_f32 v[122:123], v[28:29], 0.5, v[30:31] op_sel_hi:[1,0,1]
	v_pk_fma_f32 v[6:7], v[28:29], 0.5, v[30:31] op_sel_hi:[1,0,1] neg_lo:[1,0,0] neg_hi:[1,0,0]
	v_mov_b32_e32 v5, v123
	v_pk_mul_f32 v[24:25], v[4:5], s[6:7] op_sel_hi:[1,0]
	v_pk_add_f32 v[4:5], v[138:139], v[188:189]
	v_pk_add_f32 v[12:13], v[138:139], v[188:189] neg_lo:[0,1] neg_hi:[0,1]
	v_mov_b32_e32 v17, v82
	v_mul_f32_e32 v6, 0.5, v13
	v_pk_add_f32 v[28:29], v[186:187], v[16:17] neg_lo:[0,1] neg_hi:[0,1]
	v_pk_add_f32 v[30:31], v[186:187], v[16:17]
	v_mov_b32_e32 v13, v5
	v_pk_mov_b32 v[32:33], v[28:29], v[30:31] op_sel:[1,0]
	v_pk_mul_f32 v[12:13], v[12:13], s[44:45]
	v_mul_f32_e32 v4, 0.5, v4
	v_pk_mul_f32 v[48:49], v[32:33], v[12:13] op_sel:[0,1] op_sel_hi:[1,0]
	v_pk_mul_f32 v[12:13], v[32:33], v[12:13]
	v_pk_add_f32 v[48:49], v[48:49], v[48:49] op_sel:[0,1] op_sel_hi:[0,1]
	v_pk_add_f32 v[50:51], v[4:5], v[48:49]
	v_pk_add_f32 v[4:5], v[4:5], v[48:49] op_sel_hi:[0,1] neg_lo:[0,1] neg_hi:[0,1]
	v_mov_b32_e32 v51, v5
	v_pk_add_f32 v[4:5], v[12:13], v[12:13] op_sel:[0,1] op_sel_hi:[0,1] neg_lo:[0,1] neg_hi:[0,1]
	v_pk_add_f32 v[12:13], v[6:7], v[4:5]
	v_pk_add_f32 v[4:5], v[6:7], v[4:5] op_sel_hi:[0,1] neg_lo:[0,1] neg_hi:[0,1]
	v_mov_b32_e32 v13, v5
	v_pk_mul_f32 v[4:5], v[12:13], v[184:185]
	v_pk_mul_f32 v[12:13], v[12:13], v[170:171]
	v_pk_fma_f32 v[4:5], v[50:51], v[170:171], v[4:5]
	v_pk_fma_f32 v[12:13], v[50:51], v[184:185], v[12:13] neg_lo:[0,0,1] neg_hi:[0,0,1]
	v_mov_b32_e32 v31, v29
	v_pk_add_f32 v[48:49], v[12:13], v[4:5] op_sel:[0,1] op_sel_hi:[1,0] neg_lo:[0,1] neg_hi:[0,1]
	v_pk_add_f32 v[50:51], v[12:13], v[4:5] op_sel:[0,1] op_sel_hi:[1,0]
	v_pk_add_f32 v[4:5], v[4:5], v[12:13] op_sel:[1,0] op_sel_hi:[0,1] neg_lo:[0,1] neg_hi:[0,1]
	v_mov_b32_e32 v49, v51
	v_pk_mul_f32 v[48:49], v[48:49], 0.5 op_sel_hi:[1,0]
	v_mov_b32_e32 v51, v5
	v_mul_f32_e32 v6, v29, v48
	v_pk_fma_f32 v[32:33], v[32:33], v[48:49], v[6:7] op_sel_hi:[1,1,0] neg_lo:[1,0,0] neg_hi:[1,0,0]
	v_mul_f32_e32 v6, v29, v49
	v_pk_fma_f32 v[28:29], v[30:31], v[48:49], v[6:7] op_sel_hi:[1,1,0]
	v_pk_mul_f32 v[12:13], v[16:17], s[36:37]
	v_mov_b32_e32 v32, v28
	v_pk_fma_f32 v[4:5], v[50:51], 0.5, v[28:29] op_sel_hi:[1,0,1] neg_lo:[0,0,1] neg_hi:[0,0,1]
	v_pk_fma_f32 v[138:139], v[50:51], 0.5, v[32:33] op_sel_hi:[1,0,1]
	v_pk_add_f32 v[16:17], v[92:93], v[182:183]
	v_mov_b32_e32 v5, v139
	v_pk_add_f32 v[28:29], v[92:93], v[182:183] neg_lo:[0,1] neg_hi:[0,1]
	v_pk_mul_f32 v[30:31], v[4:5], s[6:7] op_sel_hi:[1,0]
	v_pk_fma_f32 v[4:5], v[50:51], 0.5, v[32:33] op_sel_hi:[1,0,1] neg_lo:[1,0,0] neg_hi:[1,0,0]
	v_mul_f32_e32 v6, 0.5, v29
	v_pk_add_f32 v[32:33], v[18:19], v[12:13] op_sel:[0,1] op_sel_hi:[0,1] neg_lo:[0,1] neg_hi:[0,1]
	v_pk_add_f32 v[48:49], v[18:19], v[12:13] op_sel:[0,1] op_sel_hi:[0,1]
	v_mov_b32_e32 v29, v17
	v_mul_f32_e32 v4, 0.5, v16
	v_mov_b32_e32 v50, v32
	v_mov_b32_e32 v51, v49
	v_pk_mul_f32 v[16:17], v[28:29], s[44:45]
	v_pk_mov_b32 v[48:49], v[48:49], v[32:33] op_sel:[1,0]
	v_pk_mul_f32 v[28:29], v[50:51], v[16:17] op_sel:[0,1] op_sel_hi:[1,0]
	v_pk_mul_f32 v[16:17], v[50:51], v[16:17]
	v_pk_add_f32 v[28:29], v[28:29], v[28:29] op_sel:[0,1] op_sel_hi:[0,1]
	v_pk_add_f32 v[52:53], v[4:5], v[28:29]
	v_pk_add_f32 v[28:29], v[4:5], v[28:29] op_sel_hi:[0,1] neg_lo:[0,1] neg_hi:[0,1]
	v_pk_add_f32 v[16:17], v[16:17], v[16:17] op_sel:[0,1] op_sel_hi:[0,1] neg_lo:[0,1] neg_hi:[0,1]
	v_mov_b32_e32 v53, v29
	v_pk_add_f32 v[28:29], v[6:7], v[16:17]
	v_pk_add_f32 v[16:17], v[6:7], v[16:17] op_sel_hi:[0,1] neg_lo:[0,1] neg_hi:[0,1]
	v_mov_b32_e32 v29, v17
	v_pk_mul_f32 v[16:17], v[28:29], v[180:181]
	v_pk_mul_f32 v[28:29], v[28:29], v[172:173]
	v_pk_fma_f32 v[16:17], v[52:53], v[172:173], v[16:17]
	v_pk_fma_f32 v[28:29], v[52:53], v[180:181], v[28:29] neg_lo:[0,0,1] neg_hi:[0,0,1]
	v_sub_f32_e32 v6, v89, v179
	v_pk_add_f32 v[52:53], v[28:29], v[16:17] op_sel:[0,1] op_sel_hi:[1,0] neg_lo:[0,1] neg_hi:[0,1]
	v_pk_add_f32 v[54:55], v[28:29], v[16:17] op_sel:[0,1] op_sel_hi:[1,0]
	v_pk_add_f32 v[16:17], v[16:17], v[28:29] op_sel:[1,0] op_sel_hi:[0,1] neg_lo:[0,1] neg_hi:[0,1]
	v_mov_b32_e32 v53, v55
	v_pk_mul_f32 v[52:53], v[52:53], 0.5 op_sel_hi:[1,0]
	v_mov_b32_e32 v55, v17
	v_mul_f32_e32 v4, v32, v52
	v_pk_fma_f32 v[56:57], v[50:51], v[52:53], v[4:5] op_sel_hi:[1,1,0] neg_lo:[1,0,0] neg_hi:[1,0,0]
	v_mul_f32_e32 v4, v32, v53
	v_pk_fma_f32 v[48:49], v[48:49], v[52:53], v[4:5] op_sel_hi:[1,1,0]
	v_pk_add_f32 v[28:29], v[88:89], v[178:179]
	v_mov_b32_e32 v56, v48
	v_pk_fma_f32 v[16:17], v[54:55], 0.5, v[48:49] op_sel_hi:[1,0,1] neg_lo:[0,0,1] neg_hi:[0,0,1]
	v_mov_b32_e32 v48, v12
	v_mov_b32_e32 v49, v88
	v_pk_mov_b32 v[12:13], v[12:13], v[178:179] op_sel:[1,0]
	v_mul_f32_e32 v18, 0.5, v29
	v_pk_add_f32 v[12:13], v[48:49], v[12:13] neg_lo:[0,1] neg_hi:[0,1]
	v_mul_f32_e32 v4, 0.5, v28
	v_pk_mul_f32 v[48:49], v[12:13], v[18:19]
	v_mov_b32_e32 v13, v32
	v_pk_fma_f32 v[50:51], v[50:51], v[48:49], v[48:49] op_sel:[0,1,0] op_sel_hi:[1,0,1]
	v_mov_b32_e32 v48, v49
	v_mov_b32_e32 v49, v18
	v_pk_mul_f32 v[48:49], v[12:13], v[48:49]
	v_pk_add_f32 v[52:53], v[4:5], v[50:51]
	v_mul_f32_e32 v6, 0.5, v6
	v_fma_f32 v53, v28, 0.5, -v50
	v_pk_add_f32 v[28:29], v[48:49], v[48:49] op_sel:[0,1] op_sel_hi:[0,1] neg_lo:[0,1] neg_hi:[0,1]
	v_pk_add_f32 v[48:49], v[6:7], v[28:29]
	v_pk_add_f32 v[28:29], v[6:7], v[28:29] op_sel_hi:[0,1] neg_lo:[0,1] neg_hi:[0,1]
	v_mov_b32_e32 v49, v29
	v_pk_mul_f32 v[28:29], v[48:49], v[176:177]
	v_pk_mul_f32 v[48:49], v[48:49], v[174:175]
	v_pk_fma_f32 v[28:29], v[52:53], v[174:175], v[28:29]
	v_pk_fma_f32 v[48:49], v[52:53], v[176:177], v[48:49] neg_lo:[0,0,1] neg_hi:[0,0,1]
	v_pk_fma_f32 v[92:93], v[54:55], 0.5, v[56:57] op_sel_hi:[1,0,1]
	v_pk_add_f32 v[50:51], v[48:49], v[28:29] op_sel:[0,1] op_sel_hi:[1,0] neg_lo:[0,1] neg_hi:[0,1]
	v_pk_add_f32 v[52:53], v[48:49], v[28:29] op_sel:[0,1] op_sel_hi:[1,0]
	v_mov_b32_e32 v17, v93
	v_mov_b32_e32 v51, v53
	v_pk_mul_f32 v[50:51], v[50:51], 0.5 op_sel_hi:[1,0]
	v_pk_mul_f32 v[64:65], v[16:17], s[6:7] op_sel_hi:[1,0]
	v_mul_f32_e32 v4, v12, v50
	v_pk_fma_f32 v[16:17], v[54:55], 0.5, v[56:57] op_sel_hi:[1,0,1] neg_lo:[1,0,0] neg_hi:[1,0,0]
	v_pk_fma_f32 v[54:55], v[12:13], v[50:51], v[4:5] op_sel_hi:[1,1,0] neg_lo:[1,0,0] neg_hi:[1,0,0]
	v_mov_b32_e32 v33, v12
	v_mul_f32_e32 v4, v12, v51
	v_pk_fma_f32 v[12:13], v[32:33], v[50:51], v[4:5] op_sel_hi:[1,1,0]
	v_pk_add_f32 v[28:29], v[28:29], v[48:49] op_sel:[1,0] op_sel_hi:[0,1] neg_lo:[0,1] neg_hi:[0,1]
	v_mov_b32_e32 v53, v29
	v_mov_b32_e32 v54, v12
	v_pk_fma_f32 v[12:13], v[52:53], 0.5, v[12:13] op_sel_hi:[1,0,1] neg_lo:[0,0,1] neg_hi:[0,0,1]
	v_pk_fma_f32 v[88:89], v[52:53], 0.5, v[54:55] op_sel_hi:[1,0,1]
	s_mov_b32 s79, s16
	v_mov_b32_e32 v13, v89
	v_pk_mul_f32 v[68:69], v[12:13], s[6:7] op_sel_hi:[1,0]
	v_pk_fma_f32 v[12:13], v[52:53], 0.5, v[54:55] op_sel_hi:[1,0,1] neg_lo:[1,0,0] neg_hi:[1,0,0]
	v_mov_b32_e32 v4, v83
	s_mov_b32 s17, s19
	v_pk_mul_f32 v[48:49], v[82:83], s[78:79] op_sel_hi:[0,1]
	v_pk_add_f32 v[28:29], v[96:97], v[162:163]
	v_pk_add_f32 v[32:33], v[96:97], v[162:163] neg_lo:[0,1] neg_hi:[0,1]
	v_pk_fma_f32 v[52:53], v[4:5], s[16:17], v[48:49] op_sel_hi:[0,1,1] neg_lo:[0,0,1] neg_hi:[0,0,1]
	v_mul_f32_e32 v12, 0.5, v33
	v_pk_fma_f32 v[50:51], v[4:5], s[16:17], v[48:49] op_sel_hi:[0,1,1]
	v_mov_b32_e32 v33, v29
	v_mul_f32_e32 v6, 0.5, v28
	v_mov_b32_e32 v54, v52
	v_mov_b32_e32 v55, v51
	v_pk_mul_f32 v[28:29], v[32:33], s[44:45]
	v_pk_mov_b32 v[56:57], v[50:51], v[52:53] op_sel:[1,0]
	v_pk_mul_f32 v[32:33], v[54:55], v[28:29] op_sel:[0,1] op_sel_hi:[1,0]
	v_pk_mul_f32 v[28:29], v[54:55], v[28:29]
	v_pk_add_f32 v[32:33], v[32:33], v[32:33] op_sel:[0,1] op_sel_hi:[0,1]
	v_pk_add_f32 v[58:59], v[6:7], v[32:33]
	v_pk_add_f32 v[32:33], v[6:7], v[32:33] op_sel_hi:[0,1] neg_lo:[0,1] neg_hi:[0,1]
	v_pk_add_f32 v[28:29], v[28:29], v[28:29] op_sel:[0,1] op_sel_hi:[0,1] neg_lo:[0,1] neg_hi:[0,1]
	v_mov_b32_e32 v59, v33
	v_pk_add_f32 v[32:33], v[12:13], v[28:29]
	v_pk_add_f32 v[28:29], v[12:13], v[28:29] op_sel_hi:[0,1] neg_lo:[0,1] neg_hi:[0,1]
	v_mov_b32_e32 v33, v29
	v_pk_mul_f32 v[28:29], v[32:33], v[166:167]
	v_pk_mul_f32 v[32:33], v[32:33], v[164:165]
	v_pk_fma_f32 v[28:29], v[58:59], v[164:165], v[28:29]
	v_pk_fma_f32 v[32:33], v[58:59], v[166:167], v[32:33] neg_lo:[0,0,1] neg_hi:[0,0,1]
	v_mov_b32_e32 v159, v66
	v_pk_add_f32 v[58:59], v[32:33], v[28:29] op_sel:[0,1] op_sel_hi:[1,0] neg_lo:[0,1] neg_hi:[0,1]
	v_pk_add_f32 v[70:71], v[32:33], v[28:29] op_sel:[0,1] op_sel_hi:[1,0]
	v_pk_add_f32 v[28:29], v[28:29], v[32:33] op_sel:[1,0] op_sel_hi:[0,1] neg_lo:[0,1] neg_hi:[0,1]
	v_mov_b32_e32 v59, v71
	v_pk_mul_f32 v[58:59], v[58:59], 0.5 op_sel_hi:[1,0]
	v_mov_b32_e32 v71, v29
	v_mul_f32_e32 v6, v52, v58
	v_pk_fma_f32 v[72:73], v[54:55], v[58:59], v[6:7] op_sel_hi:[1,1,0] neg_lo:[1,0,0] neg_hi:[1,0,0]
	v_mul_f32_e32 v6, v52, v59
	v_pk_fma_f32 v[56:57], v[56:57], v[58:59], v[6:7] op_sel_hi:[1,1,0]
	v_sub_f32_e32 v12, v67, v153
	v_mov_b32_e32 v72, v56
	v_pk_fma_f32 v[28:29], v[70:71], 0.5, v[56:57] op_sel_hi:[1,0,1] neg_lo:[0,0,1] neg_hi:[0,0,1]
	v_pk_fma_f32 v[96:97], v[70:71], 0.5, v[72:73] op_sel_hi:[1,0,1]
	v_pk_mov_b32 v[56:57], v[48:49], v[152:153] op_sel:[1,0]
	v_mov_b32_e32 v29, v97
	v_pk_mul_f32 v[62:63], v[28:29], s[6:7] op_sel_hi:[1,0]
	v_pk_add_f32 v[28:29], v[66:67], v[152:153]
	v_pk_add_f32 v[56:57], v[158:159], v[56:57] neg_lo:[0,1] neg_hi:[0,1]
	v_mul_f32_e32 v18, 0.5, v29
	v_pk_mul_f32 v[58:59], v[56:57], v[18:19]
	v_mul_f32_e32 v6, 0.5, v28
	v_pk_fma_f32 v[54:55], v[54:55], v[58:59], v[58:59] op_sel:[0,1,0] op_sel_hi:[1,0,1]
	v_mov_b32_e32 v66, v56
	v_mov_b32_e32 v67, v52
	v_mov_b32_e32 v58, v59
	v_mov_b32_e32 v59, v18
	v_pk_mul_f32 v[58:59], v[66:67], v[58:59]
	v_pk_add_f32 v[66:67], v[6:7], v[54:55]
	v_mul_f32_e32 v12, 0.5, v12
	v_fma_f32 v67, v28, 0.5, -v54
	v_pk_add_f32 v[28:29], v[58:59], v[58:59] op_sel:[0,1] op_sel_hi:[0,1] neg_lo:[0,1] neg_hi:[0,1]
	v_pk_add_f32 v[54:55], v[12:13], v[28:29]
	v_pk_add_f32 v[28:29], v[12:13], v[28:29] op_sel_hi:[0,1] neg_lo:[0,1] neg_hi:[0,1]
	v_mov_b32_e32 v55, v29
	v_pk_mul_f32 v[28:29], v[54:55], v[156:157]
	v_pk_mul_f32 v[54:55], v[54:55], v[154:155]
	v_pk_fma_f32 v[32:33], v[70:71], 0.5, v[72:73] op_sel_hi:[1,0,1] neg_lo:[1,0,0] neg_hi:[1,0,0]
	v_pk_fma_f32 v[58:59], v[66:67], v[154:155], v[28:29] neg_lo:[0,0,1] neg_hi:[0,0,1]
	v_pk_fma_f32 v[28:29], v[66:67], v[154:155], v[28:29]
	v_pk_fma_f32 v[70:71], v[66:67], v[156:157], v[54:55]
	v_pk_fma_f32 v[54:55], v[66:67], v[156:157], v[54:55] neg_lo:[0,0,1] neg_hi:[0,0,1]
	v_pk_add_f32 v[72:73], v[58:59], v[28:29] op_sel:[0,1] op_sel_hi:[1,0]
	v_pk_add_f32 v[66:67], v[70:71], v[54:55] op_sel_hi:[0,1] neg_lo:[0,1] neg_hi:[0,1]
	v_pk_add_f32 v[28:29], v[58:59], v[28:29] op_sel_hi:[0,1] neg_lo:[0,1] neg_hi:[0,1]
	v_pk_add_f32 v[54:55], v[70:71], v[54:55] op_sel:[0,1] op_sel_hi:[1,0]
	v_mov_b32_e32 v73, v67
	v_mov_b32_e32 v55, v29
	v_pk_mul_f32 v[28:29], v[54:55], 0.5 op_sel_hi:[1,0]
	v_mov_b32_e32 v133, v84
	v_pk_mul_f32 v[54:55], v[52:53], v[28:29] op_sel:[0,1] op_sel_hi:[0,0]
	v_pk_fma_f32 v[58:59], v[56:57], v[28:29], v[54:55] op_sel_hi:[0,1,1]
	v_pk_fma_f32 v[28:29], v[56:57], v[28:29], v[54:55] op_sel_hi:[0,1,1] neg_lo:[0,0,1] neg_hi:[0,0,1]
	v_mov_b32_e32 v28, v58
	v_pk_fma_f32 v[54:55], v[72:73], 0.5, v[58:59] op_sel_hi:[1,0,1] neg_lo:[0,0,1] neg_hi:[0,0,1]
	v_pk_fma_f32 v[66:67], v[72:73], 0.5, v[28:29] op_sel_hi:[1,0,1]
	v_pk_add_f32 v[56:57], v[60:61], v[134:135] neg_lo:[0,1] neg_hi:[0,1]
	v_mov_b32_e32 v55, v67
	v_pk_mul_f32 v[90:91], v[54:55], s[6:7] op_sel_hi:[1,0]
	v_pk_add_f32 v[54:55], v[134:135], v[60:61]
	v_mul_f32_e32 v12, 0.5, v57
	v_mov_b32_e32 v57, v55
	v_mul_f32_e32 v6, 0.5, v54
	v_pk_mov_b32 v[58:59], v[52:53], v[50:51] op_sel:[1,0]
	v_pk_mul_f32 v[54:55], v[56:57], s[44:45]
	v_pk_fma_f32 v[28:29], v[72:73], 0.5, v[28:29] op_sel_hi:[1,0,1] neg_lo:[1,0,0] neg_hi:[1,0,0]
	v_pk_mul_f32 v[56:57], v[58:59], v[54:55] op_sel:[0,1] op_sel_hi:[1,0]
	v_pk_mul_f32 v[54:55], v[58:59], v[54:55]
	v_pk_add_f32 v[56:57], v[56:57], v[56:57] op_sel:[0,1] op_sel_hi:[0,1]
	v_pk_add_f32 v[60:61], v[6:7], v[56:57]
	v_pk_add_f32 v[56:57], v[6:7], v[56:57] op_sel_hi:[0,1] neg_lo:[0,1] neg_hi:[0,1]
	v_pk_add_f32 v[54:55], v[54:55], v[54:55] op_sel:[0,1] op_sel_hi:[0,1] neg_lo:[0,1] neg_hi:[0,1]
	v_mov_b32_e32 v61, v57
	v_pk_add_f32 v[56:57], v[12:13], v[54:55]
	v_pk_add_f32 v[54:55], v[12:13], v[54:55] op_sel_hi:[0,1] neg_lo:[0,1] neg_hi:[0,1]
	v_mov_b32_e32 v57, v55
	v_pk_mul_f32 v[54:55], v[56:57], v[142:143]
	v_pk_mul_f32 v[56:57], v[56:57], v[140:141]
	v_pk_fma_f32 v[54:55], v[60:61], v[140:141], v[54:55]
	v_pk_fma_f32 v[56:57], v[60:61], v[142:143], v[56:57] neg_lo:[0,0,1] neg_hi:[0,0,1]
	v_mov_b32_e32 v51, v53
	v_pk_add_f32 v[60:61], v[56:57], v[54:55] op_sel:[0,1] op_sel_hi:[1,0] neg_lo:[0,1] neg_hi:[0,1]
	v_pk_add_f32 v[70:71], v[56:57], v[54:55] op_sel:[0,1] op_sel_hi:[1,0]
	v_pk_add_f32 v[54:55], v[54:55], v[56:57] op_sel:[1,0] op_sel_hi:[0,1] neg_lo:[0,1] neg_hi:[0,1]
	v_mov_b32_e32 v61, v71
	v_pk_mul_f32 v[60:61], v[60:61], 0.5 op_sel_hi:[1,0]
	v_mov_b32_e32 v71, v55
	v_mul_f32_e32 v6, v53, v60
	v_pk_fma_f32 v[72:73], v[58:59], v[60:61], v[6:7] op_sel_hi:[1,1,0] neg_lo:[1,0,0] neg_hi:[1,0,0]
	v_mul_f32_e32 v6, v53, v61
	v_pk_fma_f32 v[50:51], v[50:51], v[60:61], v[6:7] op_sel_hi:[1,1,0]
	v_pk_add_f32 v[54:55], v[118:119], v[84:85]
	v_mov_b32_e32 v72, v50
	v_mov_b32_e32 v49, v118
	v_pk_fma_f32 v[50:51], v[70:71], 0.5, v[50:51] op_sel_hi:[1,0,1] neg_lo:[0,0,1] neg_hi:[0,0,1]
	v_pk_fma_f32 v[60:61], v[70:71], 0.5, v[72:73] op_sel_hi:[1,0,1]
	v_mul_f32_e32 v18, 0.5, v55
	v_pk_add_f32 v[48:49], v[132:133], v[48:49] neg_lo:[0,1] neg_hi:[0,1]
	v_mov_b32_e32 v51, v61
	v_pk_mul_f32 v[56:57], v[48:49], v[18:19]
	v_pk_mul_f32 v[94:95], v[50:51], s[6:7] op_sel_hi:[1,0]
	v_pk_fma_f32 v[50:51], v[70:71], 0.5, v[72:73] op_sel_hi:[1,0,1] neg_lo:[1,0,0] neg_hi:[1,0,0]
	v_mul_f32_e32 v6, 0.5, v54
	v_pk_fma_f32 v[58:59], v[58:59], v[56:57], v[56:57] op_sel:[0,1,0] op_sel_hi:[1,0,1]
	v_mov_b32_e32 v70, v48
	v_mov_b32_e32 v71, v53
	v_mov_b32_e32 v56, v57
	v_mov_b32_e32 v57, v18
	v_sub_f32_e32 v12, v85, v119
	v_pk_mul_f32 v[56:57], v[70:71], v[56:57]
	v_pk_add_f32 v[70:71], v[6:7], v[58:59]
	v_mul_f32_e32 v12, 0.5, v12
	v_fma_f32 v71, v54, 0.5, -v58
	v_pk_add_f32 v[54:55], v[56:57], v[56:57] op_sel:[0,1] op_sel_hi:[0,1] neg_lo:[0,1] neg_hi:[0,1]
	v_pk_add_f32 v[56:57], v[12:13], v[54:55]
	v_pk_add_f32 v[54:55], v[12:13], v[54:55] op_sel_hi:[0,1] neg_lo:[0,1] neg_hi:[0,1]
	v_mov_b32_e32 v57, v55
	v_pk_mul_f32 v[54:55], v[56:57], v[126:127]
	v_pk_mul_f32 v[56:57], v[56:57], v[124:125]
	v_pk_fma_f32 v[58:59], v[70:71], v[124:125], v[54:55] neg_lo:[0,0,1] neg_hi:[0,0,1]
	v_pk_fma_f32 v[54:55], v[70:71], v[124:125], v[54:55]
	v_pk_fma_f32 v[72:73], v[70:71], v[126:127], v[56:57]
	v_pk_fma_f32 v[56:57], v[70:71], v[126:127], v[56:57] neg_lo:[0,0,1] neg_hi:[0,0,1]
	v_pk_add_f32 v[70:71], v[58:59], v[54:55] op_sel:[0,1] op_sel_hi:[1,0]
	v_pk_add_f32 v[74:75], v[72:73], v[56:57] op_sel_hi:[0,1] neg_lo:[0,1] neg_hi:[0,1]
	v_pk_add_f32 v[54:55], v[58:59], v[54:55] op_sel_hi:[0,1] neg_lo:[0,1] neg_hi:[0,1]
	v_pk_add_f32 v[56:57], v[72:73], v[56:57] op_sel:[0,1] op_sel_hi:[1,0]
	v_mov_b32_e32 v71, v75
	v_mov_b32_e32 v57, v55
	v_pk_mul_f32 v[54:55], v[56:57], 0.5 op_sel_hi:[1,0]
	s_mov_b32 s78, s11
	v_pk_mul_f32 v[52:53], v[52:53], v[54:55] op_sel:[1,1] op_sel_hi:[1,0]
	s_mov_b32 s79, s8
	v_pk_fma_f32 v[56:57], v[48:49], v[54:55], v[52:53] op_sel_hi:[0,1,1]
	v_pk_fma_f32 v[48:49], v[48:49], v[54:55], v[52:53] op_sel_hi:[0,1,1] neg_lo:[0,0,1] neg_hi:[0,0,1]
	v_mov_b32_e32 v48, v56
	v_pk_fma_f32 v[52:53], v[70:71], 0.5, v[56:57] op_sel_hi:[1,0,1] neg_lo:[0,0,1] neg_hi:[0,0,1]
	v_pk_fma_f32 v[84:85], v[70:71], 0.5, v[48:49] op_sel_hi:[1,0,1]
	s_mov_b32 s9, s11
	v_mov_b32_e32 v53, v85
	v_pk_mul_f32 v[80:81], v[52:53], s[6:7] op_sel_hi:[1,0]
	v_pk_mul_f32 v[118:119], v[82:83], s[78:79] op_sel_hi:[0,1]
	v_pk_add_f32 v[52:53], v[86:87], v[112:113]
	v_pk_add_f32 v[54:55], v[86:87], v[112:113] neg_lo:[0,1] neg_hi:[0,1]
	v_pk_fma_f32 v[58:59], v[4:5], s[8:9], v[118:119] op_sel_hi:[0,1,1] neg_lo:[0,0,1] neg_hi:[0,0,1]
	v_mul_f32_e32 v12, 0.5, v55
	v_pk_fma_f32 v[72:73], v[4:5], s[8:9], v[118:119] op_sel_hi:[0,1,1]
	v_mov_b32_e32 v55, v53
	v_mul_f32_e32 v6, 0.5, v52
	v_mov_b32_e32 v56, v58
	v_mov_b32_e32 v57, v73
	v_pk_mul_f32 v[52:53], v[54:55], s[44:45]
	v_pk_fma_f32 v[48:49], v[70:71], 0.5, v[48:49] op_sel_hi:[1,0,1] neg_lo:[1,0,0] neg_hi:[1,0,0]
	v_pk_mul_f32 v[54:55], v[56:57], v[52:53] op_sel:[0,1] op_sel_hi:[1,0]
	v_pk_mul_f32 v[52:53], v[56:57], v[52:53]
	v_pk_add_f32 v[54:55], v[54:55], v[54:55] op_sel:[0,1] op_sel_hi:[0,1]
	v_pk_add_f32 v[74:75], v[6:7], v[54:55]
	v_pk_add_f32 v[54:55], v[6:7], v[54:55] op_sel_hi:[0,1] neg_lo:[0,1] neg_hi:[0,1]
	v_pk_add_f32 v[52:53], v[52:53], v[52:53] op_sel:[0,1] op_sel_hi:[0,1] neg_lo:[0,1] neg_hi:[0,1]
	v_mov_b32_e32 v75, v55
	v_pk_add_f32 v[54:55], v[12:13], v[52:53]
	v_pk_add_f32 v[52:53], v[12:13], v[52:53] op_sel_hi:[0,1] neg_lo:[0,1] neg_hi:[0,1]
	v_mov_b32_e32 v55, v53
	v_pk_mul_f32 v[52:53], v[54:55], v[116:117]
	v_pk_mul_f32 v[54:55], v[54:55], v[114:115]
	v_pk_fma_f32 v[52:53], v[74:75], v[114:115], v[52:53]
	v_pk_fma_f32 v[54:55], v[74:75], v[116:117], v[54:55] neg_lo:[0,0,1] neg_hi:[0,0,1]
	v_pk_mov_b32 v[70:71], v[72:73], v[58:59] op_sel:[1,0]
	v_pk_add_f32 v[74:75], v[54:55], v[52:53] op_sel:[0,1] op_sel_hi:[1,0] neg_lo:[0,1] neg_hi:[0,1]
	v_pk_add_f32 v[76:77], v[54:55], v[52:53] op_sel:[0,1] op_sel_hi:[1,0]
	v_pk_add_f32 v[52:53], v[52:53], v[54:55] op_sel:[1,0] op_sel_hi:[0,1] neg_lo:[0,1] neg_hi:[0,1]
	v_mov_b32_e32 v75, v77
	v_pk_mul_f32 v[74:75], v[74:75], 0.5 op_sel_hi:[1,0]
	v_mov_b32_e32 v77, v53
	v_mul_f32_e32 v6, v58, v74
	v_pk_fma_f32 v[112:113], v[56:57], v[74:75], v[6:7] op_sel_hi:[1,1,0] neg_lo:[1,0,0] neg_hi:[1,0,0]
	v_mul_f32_e32 v6, v58, v75
	v_pk_fma_f32 v[70:71], v[70:71], v[74:75], v[6:7] op_sel_hi:[1,1,0]
	v_pk_add_f32 v[54:55], v[34:35], v[110:111]
	v_mov_b32_e32 v112, v70
	v_pk_fma_f32 v[52:53], v[76:77], 0.5, v[70:71] op_sel_hi:[1,0,1] neg_lo:[0,0,1] neg_hi:[0,0,1]
	v_pk_fma_f32 v[86:87], v[76:77], 0.5, v[112:113] op_sel_hi:[1,0,1]
	v_sub_f32_e32 v12, v35, v111
	v_mov_b32_e32 v53, v87
	v_pk_mul_f32 v[78:79], v[52:53], s[6:7] op_sel_hi:[1,0]
	v_mul_f32_e32 v52, 0xbe47c5c2, v83
	v_mov_b32_e32 v53, v34
	v_pk_mov_b32 v[34:35], v[118:119], v[110:111] op_sel:[1,0]
	v_mul_f32_e32 v18, 0.5, v55
	v_pk_add_f32 v[34:35], v[52:53], v[34:35] neg_lo:[0,1] neg_hi:[0,1]
	v_mov_b32_e32 v71, v58
	v_pk_mul_f32 v[52:53], v[34:35], v[18:19]
	v_mov_b32_e32 v70, v34
	v_pk_fma_f32 v[56:57], v[56:57], v[52:53], v[52:53] op_sel:[0,1,0] op_sel_hi:[1,0,1]
	v_mov_b32_e32 v52, v53
	v_mov_b32_e32 v53, v18
	v_mul_f32_e32 v6, 0.5, v54
	v_pk_mul_f32 v[52:53], v[70:71], v[52:53]
	v_cvt_f32_f16_e32 v70, v46
	v_cvt_f32_f16_e32 v71, v47
	v_cvt_f32_f16_sdwa v47, v47 dst_sel:DWORD dst_unused:UNUSED_PAD src0_sel:WORD_1
	v_cvt_f32_f16_sdwa v46, v46 dst_sel:DWORD dst_unused:UNUSED_PAD src0_sel:WORD_1
	v_pk_fma_f32 v[74:75], v[76:77], 0.5, v[112:113] op_sel_hi:[1,0,1] neg_lo:[1,0,0] neg_hi:[1,0,0]
	v_mul_f32_e32 v12, 0.5, v12
	v_pk_add_f32 v[76:77], v[6:7], v[56:57]
	v_pk_add_f32 v[52:53], v[52:53], v[52:53] op_sel:[0,1] op_sel_hi:[0,1] neg_lo:[0,1] neg_hi:[0,1]
	v_fma_f32 v77, v54, 0.5, -v56
	v_pk_add_f32 v[54:55], v[12:13], v[52:53]
	v_pk_add_f32 v[52:53], v[12:13], v[52:53] op_sel_hi:[0,1] neg_lo:[0,1] neg_hi:[0,1]
	v_mov_b32_e32 v55, v53
	v_pk_mul_f32 v[52:53], v[54:55], v[46:47]
	v_pk_mul_f32 v[54:55], v[54:55], v[70:71]
	v_pk_fma_f32 v[56:57], v[76:77], v[70:71], v[52:53] neg_lo:[0,0,1] neg_hi:[0,0,1]
	v_pk_fma_f32 v[52:53], v[76:77], v[70:71], v[52:53]
	v_pk_fma_f32 v[70:71], v[76:77], v[46:47], v[54:55]
	v_pk_fma_f32 v[46:47], v[76:77], v[46:47], v[54:55] neg_lo:[0,0,1] neg_hi:[0,0,1]
	v_pk_add_f32 v[54:55], v[56:57], v[52:53] op_sel:[0,1] op_sel_hi:[1,0]
	v_pk_add_f32 v[76:77], v[70:71], v[46:47] op_sel_hi:[0,1] neg_lo:[0,1] neg_hi:[0,1]
	v_pk_add_f32 v[52:53], v[56:57], v[52:53] op_sel_hi:[0,1] neg_lo:[0,1] neg_hi:[0,1]
	v_pk_add_f32 v[46:47], v[70:71], v[46:47] op_sel:[0,1] op_sel_hi:[1,0]
	v_mov_b32_e32 v55, v77
	v_mov_b32_e32 v47, v53
	v_pk_mul_f32 v[46:47], v[46:47], 0.5 op_sel_hi:[1,0]
	s_mov_b32 s25, s27
	v_pk_mul_f32 v[52:53], v[58:59], v[46:47] op_sel:[0,1] op_sel_hi:[0,0]
	v_pk_fma_f32 v[56:57], v[34:35], v[46:47], v[52:53] op_sel_hi:[0,1,1]
	v_pk_fma_f32 v[46:47], v[34:35], v[46:47], v[52:53] op_sel_hi:[0,1,1] neg_lo:[0,0,1] neg_hi:[0,0,1]
	v_mov_b32_e32 v46, v56
	v_pk_fma_f32 v[52:53], v[54:55], 0.5, v[56:57] op_sel_hi:[1,0,1] neg_lo:[0,0,1] neg_hi:[0,0,1]
	v_pk_fma_f32 v[34:35], v[54:55], 0.5, v[46:47] op_sel_hi:[1,0,1]
	s_mov_b32 s78, s27
	v_mov_b32_e32 v53, v35
	v_pk_mul_f32 v[136:137], v[52:53], s[6:7] op_sel_hi:[1,0]
	v_pk_fma_f32 v[52:53], v[54:55], 0.5, v[46:47] op_sel_hi:[1,0,1] neg_lo:[1,0,0] neg_hi:[1,0,0]
	s_mov_b32 s79, s24
	v_pk_mul_f32 v[46:47], v[82:83], s[24:25] op_sel_hi:[0,1]
	v_pk_add_f32 v[54:55], v[108:109], v[40:41]
	v_pk_add_f32 v[40:41], v[40:41], v[108:109] neg_lo:[0,1] neg_hi:[0,1]
	v_pk_fma_f32 v[108:109], v[4:5], s[78:79], v[46:47] op_sel_hi:[0,1,1] neg_lo:[0,0,1] neg_hi:[0,0,1]
	v_mul_f32_e32 v12, 0.5, v41
	v_pk_fma_f32 v[70:71], v[4:5], s[78:79], v[46:47] op_sel_hi:[0,1,1]
	v_mov_b32_e32 v41, v55
	v_mov_b32_e32 v56, v108
	v_mov_b32_e32 v57, v71
	v_pk_mul_f32 v[40:41], v[40:41], s[44:45]
	v_mul_f32_e32 v6, 0.5, v54
	v_pk_mul_f32 v[54:55], v[56:57], v[40:41] op_sel:[0,1] op_sel_hi:[1,0]
	v_cvt_f32_f16_sdwa v76, v36 dst_sel:DWORD dst_unused:UNUSED_PAD src0_sel:WORD_1
	v_cvt_f32_f16_e32 v77, v37
	v_cvt_f32_f16_sdwa v37, v37 dst_sel:DWORD dst_unused:UNUSED_PAD src0_sel:WORD_1
	v_cvt_f32_f16_e32 v36, v36
	v_pk_mul_f32 v[40:41], v[56:57], v[40:41]
	v_pk_add_f32 v[54:55], v[54:55], v[54:55] op_sel:[0,1] op_sel_hi:[0,1]
	v_pk_add_f32 v[112:113], v[6:7], v[54:55]
	v_pk_add_f32 v[54:55], v[6:7], v[54:55] op_sel_hi:[0,1] neg_lo:[0,1] neg_hi:[0,1]
	v_pk_add_f32 v[40:41], v[40:41], v[40:41] op_sel:[0,1] op_sel_hi:[0,1] neg_lo:[0,1] neg_hi:[0,1]
	v_mov_b32_e32 v113, v55
	v_pk_add_f32 v[54:55], v[12:13], v[40:41]
	v_pk_add_f32 v[40:41], v[12:13], v[40:41] op_sel_hi:[0,1] neg_lo:[0,1] neg_hi:[0,1]
	v_mov_b32_e32 v55, v41
	v_pk_mul_f32 v[40:41], v[54:55], v[36:37]
	v_pk_mul_f32 v[54:55], v[54:55], v[76:77]
	v_pk_fma_f32 v[40:41], v[112:113], v[76:77], v[40:41]
	v_pk_fma_f32 v[36:37], v[112:113], v[36:37], v[54:55] neg_lo:[0,0,1] neg_hi:[0,0,1]
	v_pk_mov_b32 v[110:111], v[70:71], v[108:109] op_sel:[1,0]
	v_pk_add_f32 v[54:55], v[36:37], v[40:41] op_sel:[0,1] op_sel_hi:[1,0] neg_lo:[0,1] neg_hi:[0,1]
	v_pk_add_f32 v[76:77], v[36:37], v[40:41] op_sel:[0,1] op_sel_hi:[1,0]
	v_pk_add_f32 v[36:37], v[40:41], v[36:37] op_sel:[1,0] op_sel_hi:[0,1] neg_lo:[0,1] neg_hi:[0,1]
	v_mov_b32_e32 v55, v77
	v_pk_mul_f32 v[54:55], v[54:55], 0.5 op_sel_hi:[1,0]
	v_mov_b32_e32 v77, v37
	v_mul_f32_e32 v4, v108, v54
	v_pk_fma_f32 v[112:113], v[56:57], v[54:55], v[4:5] op_sel_hi:[1,1,0] neg_lo:[1,0,0] neg_hi:[1,0,0]
	v_mul_f32_e32 v4, v108, v55
	v_pk_fma_f32 v[54:55], v[110:111], v[54:55], v[4:5] op_sel_hi:[1,1,0]
	v_sub_f32_e32 v6, v45, v105
	v_mov_b32_e32 v112, v54
	v_pk_fma_f32 v[40:41], v[76:77], 0.5, v[54:55] op_sel_hi:[1,0,1] neg_lo:[0,0,1] neg_hi:[0,0,1]
	v_pk_fma_f32 v[36:37], v[76:77], 0.5, v[112:113] op_sel_hi:[1,0,1]
	v_pk_add_f32 v[54:55], v[104:105], v[44:45]
	v_mov_b32_e32 v41, v37
	v_pk_mul_f32 v[130:131], v[40:41], s[6:7] op_sel_hi:[1,0]
	v_mul_f32_e32 v40, 0xbf54db31, v83
	v_mov_b32_e32 v41, v44
	v_pk_mov_b32 v[44:45], v[46:47], v[104:105] op_sel:[1,0]
	v_mul_f32_e32 v18, 0.5, v55
	v_pk_add_f32 v[40:41], v[40:41], v[44:45] neg_lo:[0,1] neg_hi:[0,1]
	v_mov_b32_e32 v105, v108
	v_pk_mul_f32 v[44:45], v[40:41], v[18:19]
	v_mov_b32_e32 v104, v40
	v_pk_fma_f32 v[56:57], v[56:57], v[44:45], v[44:45] op_sel:[0,1,0] op_sel_hi:[1,0,1]
	v_mov_b32_e32 v44, v45
	v_mov_b32_e32 v45, v18
	v_mul_f32_e32 v4, 0.5, v54
	v_pk_mul_f32 v[44:45], v[104:105], v[44:45]
	v_cvt_f32_f16_e32 v104, v26
	v_cvt_f32_f16_e32 v105, v27
	v_cvt_f32_f16_sdwa v27, v27 dst_sel:DWORD dst_unused:UNUSED_PAD src0_sel:WORD_1
	v_cvt_f32_f16_sdwa v26, v26 dst_sel:DWORD dst_unused:UNUSED_PAD src0_sel:WORD_1
	v_mul_f32_e32 v6, 0.5, v6
	v_pk_add_f32 v[110:111], v[4:5], v[56:57]
	v_pk_add_f32 v[44:45], v[44:45], v[44:45] op_sel:[0,1] op_sel_hi:[0,1] neg_lo:[0,1] neg_hi:[0,1]
	v_fma_f32 v111, v54, 0.5, -v56
	v_pk_add_f32 v[54:55], v[6:7], v[44:45]
	v_pk_add_f32 v[44:45], v[6:7], v[44:45] op_sel_hi:[0,1] neg_lo:[0,1] neg_hi:[0,1]
	v_mov_b32_e32 v55, v45
	v_pk_mul_f32 v[44:45], v[54:55], v[26:27]
	v_pk_mul_f32 v[54:55], v[54:55], v[104:105]
	v_pk_fma_f32 v[56:57], v[110:111], v[104:105], v[44:45] neg_lo:[0,0,1] neg_hi:[0,0,1]
	v_pk_fma_f32 v[44:45], v[110:111], v[104:105], v[44:45]
	v_pk_fma_f32 v[104:105], v[110:111], v[26:27], v[54:55]
	v_pk_fma_f32 v[26:27], v[110:111], v[26:27], v[54:55] neg_lo:[0,0,1] neg_hi:[0,0,1]
	v_pk_add_f32 v[54:55], v[56:57], v[44:45] op_sel:[0,1] op_sel_hi:[1,0]
	v_pk_add_f32 v[110:111], v[104:105], v[26:27] op_sel_hi:[0,1] neg_lo:[0,1] neg_hi:[0,1]
	v_pk_add_f32 v[44:45], v[56:57], v[44:45] op_sel_hi:[0,1] neg_lo:[0,1] neg_hi:[0,1]
	v_pk_add_f32 v[26:27], v[104:105], v[26:27] op_sel:[0,1] op_sel_hi:[1,0]
	v_mov_b32_e32 v55, v111
	v_mov_b32_e32 v27, v45
	v_pk_mul_f32 v[26:27], v[26:27], 0.5 op_sel_hi:[1,0]
	v_mov_b32_e32 v47, v102
	v_pk_mul_f32 v[44:45], v[108:109], v[26:27] op_sel:[0,1] op_sel_hi:[0,0]
	v_pk_fma_f32 v[56:57], v[40:41], v[26:27], v[44:45] op_sel_hi:[0,1,1]
	v_pk_fma_f32 v[40:41], v[40:41], v[26:27], v[44:45] op_sel_hi:[0,1,1] neg_lo:[0,0,1] neg_hi:[0,0,1]
	v_mov_b32_e32 v40, v56
	v_pk_fma_f32 v[44:45], v[54:55], 0.5, v[56:57] op_sel_hi:[1,0,1] neg_lo:[0,0,1] neg_hi:[0,0,1]
	v_pk_fma_f32 v[26:27], v[54:55], 0.5, v[40:41] op_sel_hi:[1,0,1]
	v_pk_fma_f32 v[56:57], v[54:55], 0.5, v[40:41] op_sel_hi:[1,0,1] neg_lo:[1,0,0] neg_hi:[1,0,0]
	v_pk_add_f32 v[40:41], v[106:107], v[42:43]
	v_pk_add_f32 v[42:43], v[42:43], v[106:107] neg_lo:[0,1] neg_hi:[0,1]
	v_mov_b32_e32 v45, v27
	v_mul_f32_e32 v6, 0.5, v43
	v_mov_b32_e32 v43, v41
	v_pk_mul_f32 v[120:121], v[44:45], s[6:7] op_sel_hi:[1,0]
	v_mul_f32_e32 v4, 0.5, v40
	v_pk_mov_b32 v[44:45], v[108:109], v[70:71] op_sel:[1,0]
	v_pk_mul_f32 v[40:41], v[42:43], s[44:45]
	v_cvt_f32_f16_sdwa v54, v20 dst_sel:DWORD dst_unused:UNUSED_PAD src0_sel:WORD_1
	v_pk_mul_f32 v[42:43], v[44:45], v[40:41] op_sel:[0,1] op_sel_hi:[1,0]
	v_cvt_f32_f16_e32 v55, v21
	v_cvt_f32_f16_sdwa v21, v21 dst_sel:DWORD dst_unused:UNUSED_PAD src0_sel:WORD_1
	v_cvt_f32_f16_e32 v20, v20
	v_pk_mul_f32 v[40:41], v[44:45], v[40:41]
	v_pk_add_f32 v[42:43], v[42:43], v[42:43] op_sel:[0,1] op_sel_hi:[0,1]
	v_pk_add_f32 v[104:105], v[4:5], v[42:43]
	v_pk_add_f32 v[42:43], v[4:5], v[42:43] op_sel_hi:[0,1] neg_lo:[0,1] neg_hi:[0,1]
	v_pk_add_f32 v[40:41], v[40:41], v[40:41] op_sel:[0,1] op_sel_hi:[0,1] neg_lo:[0,1] neg_hi:[0,1]
	v_mov_b32_e32 v105, v43
	v_pk_add_f32 v[42:43], v[6:7], v[40:41]
	v_pk_add_f32 v[40:41], v[6:7], v[40:41] op_sel_hi:[0,1] neg_lo:[0,1] neg_hi:[0,1]
	v_mov_b32_e32 v43, v41
	v_pk_mul_f32 v[40:41], v[42:43], v[20:21]
	v_pk_mul_f32 v[42:43], v[42:43], v[54:55]
	v_pk_fma_f32 v[40:41], v[104:105], v[54:55], v[40:41]
	v_pk_fma_f32 v[20:21], v[104:105], v[20:21], v[42:43] neg_lo:[0,0,1] neg_hi:[0,0,1]
	v_mov_b32_e32 v71, v109
	v_pk_add_f32 v[42:43], v[20:21], v[40:41] op_sel:[0,1] op_sel_hi:[1,0] neg_lo:[0,1] neg_hi:[0,1]
	v_pk_add_f32 v[54:55], v[20:21], v[40:41] op_sel:[0,1] op_sel_hi:[1,0]
	v_pk_add_f32 v[20:21], v[40:41], v[20:21] op_sel:[1,0] op_sel_hi:[0,1] neg_lo:[0,1] neg_hi:[0,1]
	v_mov_b32_e32 v43, v55
	v_pk_mul_f32 v[42:43], v[42:43], 0.5 op_sel_hi:[1,0]
	v_mov_b32_e32 v55, v21
	v_mul_f32_e32 v4, v109, v42
	v_pk_fma_f32 v[104:105], v[44:45], v[42:43], v[4:5] op_sel_hi:[1,1,0] neg_lo:[1,0,0] neg_hi:[1,0,0]
	v_mul_f32_e32 v4, v109, v43
	v_pk_fma_f32 v[42:43], v[70:71], v[42:43], v[4:5] op_sel_hi:[1,1,0]
	v_sub_f32_e32 v6, v23, v103
	v_mov_b32_e32 v104, v42
	v_pk_fma_f32 v[40:41], v[54:55], 0.5, v[42:43] op_sel_hi:[1,0,1] neg_lo:[0,0,1] neg_hi:[0,0,1]
	v_pk_fma_f32 v[20:21], v[54:55], 0.5, v[104:105] op_sel_hi:[1,0,1]
	v_pk_add_f32 v[42:43], v[102:103], v[22:23]
	v_mov_b32_e32 v41, v21
	v_pk_mul_f32 v[128:129], v[40:41], s[6:7] op_sel_hi:[1,0]
	v_mul_f32_e32 v40, 0xbf0e39da, v83
	v_mov_b32_e32 v41, v22
	v_mul_f32_e32 v18, 0.5, v43
	v_pk_add_f32 v[22:23], v[40:41], v[46:47] neg_lo:[0,1] neg_hi:[0,1]
	v_mov_b32_e32 v47, v109
	v_pk_mul_f32 v[40:41], v[22:23], v[18:19]
	v_mov_b32_e32 v46, v22
	v_pk_fma_f32 v[44:45], v[44:45], v[40:41], v[40:41] op_sel:[0,1,0] op_sel_hi:[1,0,1]
	v_mov_b32_e32 v40, v41
	v_mov_b32_e32 v41, v18
	v_mul_f32_e32 v4, 0.5, v42
	v_pk_mul_f32 v[40:41], v[46:47], v[40:41]
	v_cvt_f32_f16_e32 v46, v10
	v_cvt_f32_f16_e32 v47, v11
	v_cvt_f32_f16_sdwa v11, v11 dst_sel:DWORD dst_unused:UNUSED_PAD src0_sel:WORD_1
	v_cvt_f32_f16_sdwa v10, v10 dst_sel:DWORD dst_unused:UNUSED_PAD src0_sel:WORD_1
	v_pk_fma_f32 v[70:71], v[54:55], 0.5, v[104:105] op_sel_hi:[1,0,1] neg_lo:[1,0,0] neg_hi:[1,0,0]
	v_mul_f32_e32 v6, 0.5, v6
	v_pk_add_f32 v[54:55], v[4:5], v[44:45]
	v_pk_add_f32 v[40:41], v[40:41], v[40:41] op_sel:[0,1] op_sel_hi:[0,1] neg_lo:[0,1] neg_hi:[0,1]
	v_fma_f32 v55, v42, 0.5, -v44
	v_pk_add_f32 v[42:43], v[6:7], v[40:41]
	v_pk_add_f32 v[40:41], v[6:7], v[40:41] op_sel_hi:[0,1] neg_lo:[0,1] neg_hi:[0,1]
	v_mov_b32_e32 v43, v41
	v_pk_mul_f32 v[40:41], v[42:43], v[10:11]
	v_pk_mul_f32 v[42:43], v[42:43], v[46:47]
	v_pk_fma_f32 v[44:45], v[54:55], v[46:47], v[40:41] neg_lo:[0,0,1] neg_hi:[0,0,1]
	v_pk_fma_f32 v[40:41], v[54:55], v[46:47], v[40:41]
	v_pk_fma_f32 v[46:47], v[54:55], v[10:11], v[42:43]
	v_pk_fma_f32 v[10:11], v[54:55], v[10:11], v[42:43] neg_lo:[0,0,1] neg_hi:[0,0,1]
	v_pk_add_f32 v[42:43], v[44:45], v[40:41] op_sel:[0,1] op_sel_hi:[1,0]
	v_pk_add_f32 v[54:55], v[46:47], v[10:11] op_sel_hi:[0,1] neg_lo:[0,1] neg_hi:[0,1]
	v_pk_add_f32 v[40:41], v[44:45], v[40:41] op_sel_hi:[0,1] neg_lo:[0,1] neg_hi:[0,1]
	v_pk_add_f32 v[10:11], v[46:47], v[10:11] op_sel:[0,1] op_sel_hi:[1,0]
	v_mov_b32_e32 v43, v55
	v_mov_b32_e32 v11, v41
	v_pk_mul_f32 v[10:11], v[10:11], 0.5 op_sel_hi:[1,0]
	v_mov_b32_e32 v119, v98
	v_pk_mul_f32 v[40:41], v[108:109], v[10:11] op_sel:[1,1] op_sel_hi:[1,0]
	v_pk_fma_f32 v[76:77], v[76:77], 0.5, v[112:113] op_sel_hi:[1,0,1] neg_lo:[1,0,0] neg_hi:[1,0,0]
	v_pk_fma_f32 v[44:45], v[22:23], v[10:11], v[40:41] op_sel_hi:[0,1,1]
	v_pk_fma_f32 v[10:11], v[22:23], v[10:11], v[40:41] op_sel_hi:[0,1,1] neg_lo:[0,0,1] neg_hi:[0,0,1]
	v_mov_b32_e32 v10, v44
	v_pk_fma_f32 v[22:23], v[42:43], 0.5, v[44:45] op_sel_hi:[1,0,1] neg_lo:[0,0,1] neg_hi:[0,0,1]
	v_pk_fma_f32 v[40:41], v[42:43], 0.5, v[10:11] op_sel_hi:[1,0,1]
	v_pk_fma_f32 v[54:55], v[42:43], 0.5, v[10:11] op_sel_hi:[1,0,1] neg_lo:[1,0,0] neg_hi:[1,0,0]
	v_pk_add_f32 v[10:11], v[100:101], v[14:15]
	v_pk_add_f32 v[14:15], v[14:15], v[100:101] neg_lo:[0,1] neg_hi:[0,1]
	v_mov_b32_e32 v23, v41
	v_mul_f32_e32 v6, 0.5, v15
	v_mov_b32_e32 v15, v11
	v_pk_mul_f32 v[150:151], v[22:23], s[6:7] op_sel_hi:[1,0]
	v_mul_f32_e32 v4, 0.5, v10
	v_pk_mov_b32 v[22:23], v[58:59], v[72:73] op_sel:[1,0]
	v_pk_mul_f32 v[10:11], v[14:15], s[44:45]
	v_cvt_f32_f16_sdwa v42, v8 dst_sel:DWORD dst_unused:UNUSED_PAD src0_sel:WORD_1
	v_pk_mul_f32 v[14:15], v[22:23], v[10:11] op_sel:[0,1] op_sel_hi:[1,0]
	v_cvt_f32_f16_e32 v43, v9
	v_cvt_f32_f16_sdwa v9, v9 dst_sel:DWORD dst_unused:UNUSED_PAD src0_sel:WORD_1
	v_cvt_f32_f16_e32 v8, v8
	v_pk_mul_f32 v[10:11], v[22:23], v[10:11]
	v_pk_add_f32 v[14:15], v[14:15], v[14:15] op_sel:[0,1] op_sel_hi:[0,1]
	v_pk_add_f32 v[44:45], v[4:5], v[14:15]
	v_pk_add_f32 v[14:15], v[4:5], v[14:15] op_sel_hi:[0,1] neg_lo:[0,1] neg_hi:[0,1]
	v_pk_add_f32 v[10:11], v[10:11], v[10:11] op_sel:[0,1] op_sel_hi:[0,1] neg_lo:[0,1] neg_hi:[0,1]
	v_mov_b32_e32 v45, v15
	v_pk_add_f32 v[14:15], v[6:7], v[10:11]
	v_pk_add_f32 v[10:11], v[6:7], v[10:11] op_sel_hi:[0,1] neg_lo:[0,1] neg_hi:[0,1]
	v_mov_b32_e32 v15, v11
	v_pk_mul_f32 v[10:11], v[14:15], v[8:9]
	v_pk_mul_f32 v[14:15], v[14:15], v[42:43]
	v_pk_fma_f32 v[10:11], v[44:45], v[42:43], v[10:11]
	v_pk_fma_f32 v[8:9], v[44:45], v[8:9], v[14:15] neg_lo:[0,0,1] neg_hi:[0,0,1]
	v_mov_b32_e32 v73, v59
	v_pk_add_f32 v[14:15], v[8:9], v[10:11] op_sel:[0,1] op_sel_hi:[1,0] neg_lo:[0,1] neg_hi:[0,1]
	v_pk_add_f32 v[42:43], v[8:9], v[10:11] op_sel:[0,1] op_sel_hi:[1,0]
	v_pk_add_f32 v[8:9], v[10:11], v[8:9] op_sel:[1,0] op_sel_hi:[0,1] neg_lo:[0,1] neg_hi:[0,1]
	v_mov_b32_e32 v15, v43
	v_pk_mul_f32 v[14:15], v[14:15], 0.5 op_sel_hi:[1,0]
	v_mov_b32_e32 v43, v9
	v_mul_f32_e32 v4, v59, v14
	v_pk_fma_f32 v[44:45], v[22:23], v[14:15], v[4:5] op_sel_hi:[1,1,0] neg_lo:[1,0,0] neg_hi:[1,0,0]
	v_mul_f32_e32 v4, v59, v15
	v_pk_fma_f32 v[14:15], v[72:73], v[14:15], v[4:5] op_sel_hi:[1,1,0]
	v_sub_f32_e32 v6, v39, v99
	v_mov_b32_e32 v44, v14
	v_pk_fma_f32 v[8:9], v[42:43], 0.5, v[14:15] op_sel_hi:[1,0,1] neg_lo:[0,0,1] neg_hi:[0,0,1]
	v_pk_fma_f32 v[10:11], v[42:43], 0.5, v[44:45] op_sel_hi:[1,0,1]
	v_pk_add_f32 v[14:15], v[98:99], v[38:39]
	v_mov_b32_e32 v9, v11
	v_pk_mul_f32 v[168:169], v[8:9], s[6:7] op_sel_hi:[1,0]
	v_mul_f32_e32 v8, 0xbf7b14be, v83
	v_mov_b32_e32 v9, v38
	v_mul_f32_e32 v18, 0.5, v15
	v_pk_add_f32 v[8:9], v[8:9], v[118:119] neg_lo:[0,1] neg_hi:[0,1]
	v_pk_fma_f32 v[72:73], v[42:43], 0.5, v[44:45] op_sel_hi:[1,0,1] neg_lo:[1,0,0] neg_hi:[1,0,0]
	v_pk_mul_f32 v[38:39], v[8:9], v[18:19]
	v_mov_b32_e32 v42, v8
	v_pk_fma_f32 v[22:23], v[22:23], v[38:39], v[38:39] op_sel:[0,1,0] op_sel_hi:[1,0,1]
	v_mov_b32_e32 v43, v59
	v_mov_b32_e32 v38, v39
	v_mov_b32_e32 v39, v18
	v_mul_f32_e32 v4, 0.5, v14
	v_pk_mul_f32 v[38:39], v[42:43], v[38:39]
	v_cvt_f32_f16_e32 v44, v2
	v_cvt_f32_f16_e32 v45, v3
	v_cvt_f32_f16_sdwa v3, v3 dst_sel:DWORD dst_unused:UNUSED_PAD src0_sel:WORD_1
	v_cvt_f32_f16_sdwa v2, v2 dst_sel:DWORD dst_unused:UNUSED_PAD src0_sel:WORD_1
	v_mul_f32_e32 v6, 0.5, v6
	v_pk_add_f32 v[46:47], v[4:5], v[22:23]
	v_fma_f32 v4, v14, 0.5, -v22
	v_pk_add_f32 v[22:23], v[38:39], v[38:39] op_sel:[0,1] op_sel_hi:[0,1] neg_lo:[0,1] neg_hi:[0,1]
	v_pk_add_f32 v[38:39], v[6:7], v[22:23]
	v_pk_add_f32 v[22:23], v[6:7], v[22:23] op_sel_hi:[0,1] neg_lo:[0,1] neg_hi:[0,1]
	v_mov_b32_e32 v39, v23
	v_mov_b32_e32 v14, v46
	v_mov_b32_e32 v15, v4
	v_pk_mul_f32 v[22:23], v[4:5], v[44:45] op_sel_hi:[0,1]
	v_pk_mul_f32 v[82:83], v[38:39], v[2:3]
	v_pk_mul_f32 v[46:47], v[46:47], v[2:3]
	v_pk_mul_f32 v[38:39], v[38:39], v[44:45]
	v_pk_fma_f32 v[98:99], v[14:15], v[44:45], v[82:83] neg_lo:[0,0,1] neg_hi:[0,0,1]
	v_pk_fma_f32 v[2:3], v[14:15], v[2:3], v[38:39] neg_lo:[0,0,1] neg_hi:[0,0,1]
	v_add_f32_e32 v4, v23, v83
	v_add_f32_e32 v6, v46, v38
	v_pk_add_f32 v[22:23], v[6:7], v[2:3] op_sel_hi:[0,1] neg_lo:[0,1] neg_hi:[0,1]
	v_pk_add_f32 v[38:39], v[98:99], v[4:5] op_sel_hi:[1,0] neg_lo:[0,1] neg_hi:[0,1]
	v_pk_add_f32 v[2:3], v[6:7], v[2:3] op_sel_hi:[0,1]
	v_mov_b32_e32 v39, v3
	v_pk_mul_f32 v[2:3], v[38:39], 0.5 op_sel_hi:[1,0]
	v_pk_add_f32 v[14:15], v[98:99], v[4:5] op_sel_hi:[1,0]
	v_mul_f32_e32 v4, v59, v3
	v_pk_fma_f32 v[38:39], v[42:43], v[2:3], v[4:5] op_sel_hi:[1,1,0] neg_lo:[0,0,1] neg_hi:[0,0,1]
	v_pk_mov_b32 v[42:43], v[58:59], v[8:9] op_sel:[1,0]
	v_mul_f32_e32 v4, v8, v3
	v_pk_fma_f32 v[2:3], v[42:43], v[2:3], v[4:5] op_sel_hi:[1,1,0]
	v_mov_b32_e32 v15, v23
	v_pk_fma_f32 v[8:9], v[14:15], 0.5, v[2:3] op_sel_hi:[1,0,1] neg_lo:[0,0,1] neg_hi:[0,0,1]
	v_pk_fma_f32 v[42:43], v[14:15], 0.5, v[38:39] op_sel_hi:[1,0,0]
	v_pk_fma_f32 v[2:3], v[14:15], 0.5, v[2:3] op_sel_hi:[1,0,1]
	v_mov_b32_e32 v9, v43
	v_pk_fma_f32 v[58:59], v[22:23], 0.5, v[38:39] op_sel_hi:[1,0,0] neg_lo:[1,0,0] neg_hi:[1,0,0]
	v_pk_mul_f32 v[144:145], v[8:9], s[6:7] op_sel_hi:[1,0]
	v_mov_b32_e32 v58, v2
	v_mov_b32_e32 v72, v10
	v_mov_b32_e32 v54, v40
	v_mov_b32_e32 v70, v20
	v_mov_b32_e32 v56, v26
	v_mov_b32_e32 v76, v36
	v_mov_b32_e32 v52, v34
	v_mov_b32_e32 v74, v86
	v_mov_b32_e32 v48, v84
	v_mov_b32_e32 v50, v60
	v_mov_b32_e32 v28, v66
	v_mov_b32_e32 v32, v96
	v_mov_b32_e32 v12, v88
	v_mov_b32_e32 v16, v92
	v_mov_b32_e32 v4, v138
	v_mov_b32_e32 v6, v122

.LBB0_534:
	v_mov_b32_e32 v2, v210
	s_mov_b32 s43, s8
	v_and_b32_e32 v3, 0xff, v2
	v_lshlrev_b32_e32 v4, 5, v2
	v_and_or_b32 v3, v4, s33, v3
	v_ashrrev_i32_e32 v4, 5, v3
	v_lshlrev_b32_e32 v3, 3, v3
	v_lshlrev_b32_e32 v4, 3, v4
	v_add3_u32 v18, 0, v3, v4
	ds_read_b64 v[128:129], v18
	ds_read_b64 v[132:133], v18 offset:2112
	ds_read_b64 v[134:135], v18 offset:4224
	ds_read_b64 v[136:137], v18 offset:6336
	ds_read_b64 v[138:139], v18 offset:8448
	ds_read_b64 v[140:141], v18 offset:10560
	ds_read_b64 v[142:143], v18 offset:12672
	ds_read_b64 v[130:131], v18 offset:14784
	ds_read_b64 v[144:145], v18 offset:16896
	ds_read_b64 v[148:149], v18 offset:19008
	ds_read_b64 v[150:151], v18 offset:21120
	ds_read_b64 v[152:153], v18 offset:23232
	s_waitcnt lgkmcnt(10)
	v_pk_mul_f32 v[162:163], v[132:133], s[10:11]
	s_mov_b32 s64, s11
	v_pk_fma_f32 v[162:163], v[132:133], s[8:9], v[162:163] op_sel:[0,0,1] op_sel_hi:[1,0,0]
	s_waitcnt lgkmcnt(2)
	v_pk_mul_f32 v[178:179], v[148:149], s[42:43]
	v_pk_add_f32 v[194:195], v[132:133], v[148:149]
	v_pk_add_f32 v[132:133], v[132:133], v[148:149] neg_lo:[0,1] neg_hi:[0,1]
	v_pk_mul_f32 v[164:165], v[134:135], s[18:19]
	s_mov_b32 s41, s16
	v_pk_fma_f32 v[178:179], v[148:149], s[64:65], v[178:179] op_sel:[0,0,1] op_sel_hi:[1,0,0] neg_lo:[1,0,0] neg_hi:[1,0,0]
	v_pk_mul_f32 v[148:149], v[132:133], s[18:19]
	v_pk_fma_f32 v[164:165], v[134:135], s[16:17], v[164:165] op_sel:[0,0,1] op_sel_hi:[1,0,0]
	s_mov_b32 s68, s19
	s_waitcnt lgkmcnt(1)
	v_pk_mul_f32 v[180:181], v[150:151], s[40:41]
	v_pk_fma_f32 v[132:133], v[132:133], s[16:17], v[148:149] op_sel:[0,0,1] op_sel_hi:[1,0,0]
	v_pk_add_f32 v[148:149], v[134:135], v[150:151]
	v_pk_add_f32 v[134:135], v[134:135], v[150:151] neg_lo:[0,1] neg_hi:[0,1]
	v_pk_mul_f32 v[166:167], v[136:137], s[26:27]
	s_mov_b32 s66, s37
	s_mov_b32 s39, s24
	v_pk_fma_f32 v[180:181], v[150:151], s[68:69], v[180:181] op_sel:[0,0,1] op_sel_hi:[1,0,0] neg_lo:[1,0,0] neg_hi:[1,0,0]
	v_pk_mul_f32 v[150:151], v[134:135], s[36:37]
	ds_read_b64 v[154:155], v18 offset:25344
	ds_read_b64 v[156:157], v18 offset:27456
	ds_read_b64 v[158:159], v18 offset:29568
	ds_read_b64 v[160:161], v18 offset:31680
	v_pk_fma_f32 v[166:167], v[136:137], s[24:25], v[166:167] op_sel:[0,0,1] op_sel_hi:[1,0,0]
	s_mov_b32 s0, s27
	s_waitcnt lgkmcnt(4)
	v_pk_mul_f32 v[182:183], v[152:153], s[38:39]
	v_pk_fma_f32 v[134:135], v[134:135], s[66:67], v[150:151] op_sel:[0,0,1] op_sel_hi:[1,0,0]
	v_pk_add_f32 v[150:151], v[136:137], v[152:153]
	v_pk_add_f32 v[136:137], v[136:137], v[152:153] neg_lo:[0,1] neg_hi:[0,1]
	v_pk_mul_f32 v[168:169], v[138:139], s[36:37]
	v_pk_fma_f32 v[182:183], v[152:153], s[0:1], v[182:183] op_sel:[0,0,1] op_sel_hi:[1,0,0] neg_lo:[1,0,0] neg_hi:[1,0,0]
	v_pk_mul_f32 v[152:153], v[136:137], s[40:41]
	v_pk_fma_f32 v[168:169], v[138:139], s[66:67], v[168:169] op_sel:[0,0,1] op_sel_hi:[1,0,0]
	v_pk_mul_f32 v[170:171], v[140:141], s[38:39]
	s_waitcnt lgkmcnt(3)
	v_pk_mul_f32 v[184:185], v[154:155], s[36:37]
	v_pk_fma_f32 v[136:137], v[136:137], s[68:69], v[152:153] op_sel:[0,0,1] op_sel_hi:[1,0,0]
	v_pk_add_f32 v[152:153], v[138:139], v[154:155]
	v_pk_add_f32 v[138:139], v[138:139], v[154:155] neg_lo:[0,1] neg_hi:[0,1]
	v_pk_fma_f32 v[170:171], v[140:141], s[0:1], v[170:171] op_sel:[0,0,1] op_sel_hi:[1,0,0]
	v_pk_fma_f32 v[184:185], v[154:155], s[66:67], v[184:185] op_sel:[0,0,1] op_sel_hi:[1,0,0] neg_lo:[1,0,0] neg_hi:[1,0,0]
	s_waitcnt lgkmcnt(2)
	v_pk_mul_f32 v[186:187], v[156:157], s[26:27]
	v_xor_b32_e32 v155, 0x80000000, v138
	v_mov_b32_e32 v154, v139
	v_pk_add_f32 v[138:139], v[140:141], v[156:157]
	v_pk_add_f32 v[140:141], v[140:141], v[156:157] neg_lo:[0,1] neg_hi:[0,1]
	v_pk_mul_f32 v[172:173], v[142:143], s[40:41]
	v_pk_fma_f32 v[186:187], v[156:157], s[24:25], v[186:187] op_sel:[0,0,1] op_sel_hi:[1,0,0] neg_lo:[1,0,0] neg_hi:[1,0,0]
	v_pk_mul_f32 v[156:157], v[140:141], s[40:41]
	v_pk_fma_f32 v[172:173], v[142:143], s[68:69], v[172:173] op_sel:[0,0,1] op_sel_hi:[1,0,0]
	s_waitcnt lgkmcnt(1)
	v_pk_mul_f32 v[188:189], v[158:159], s[18:19]
	v_pk_fma_f32 v[140:141], v[140:141], s[68:69], v[156:157] op_sel:[0,0,1] op_sel_hi:[1,0,0] neg_lo:[1,0,0] neg_hi:[1,0,0]
	v_pk_add_f32 v[156:157], v[142:143], v[158:159]
	v_pk_add_f32 v[142:143], v[142:143], v[158:159] neg_lo:[0,1] neg_hi:[0,1]
	v_pk_mul_f32 v[174:175], v[130:131], s[42:43]
	v_pk_fma_f32 v[188:189], v[158:159], s[16:17], v[188:189] op_sel:[0,0,1] op_sel_hi:[1,0,0] neg_lo:[1,0,0] neg_hi:[1,0,0]
	v_pk_mul_f32 v[158:159], v[142:143], s[36:37]
	v_pk_fma_f32 v[174:175], v[130:131], s[64:65], v[174:175] op_sel:[0,0,1] op_sel_hi:[1,0,0]
	s_waitcnt lgkmcnt(0)
	v_pk_mul_f32 v[190:191], v[160:161], s[10:11]
	v_pk_fma_f32 v[142:143], v[142:143], s[66:67], v[158:159] op_sel:[0,0,1] op_sel_hi:[1,0,0] neg_lo:[1,0,0] neg_hi:[1,0,0]
	v_pk_add_f32 v[158:159], v[130:131], v[160:161]
	v_pk_add_f32 v[130:131], v[130:131], v[160:161] neg_lo:[0,1] neg_hi:[0,1]
	v_xor_b32_e32 v177, 0x80000000, v144
	v_mov_b32_e32 v176, v145
	v_pk_fma_f32 v[190:191], v[160:161], s[8:9], v[190:191] op_sel:[0,0,1] op_sel_hi:[1,0,0] neg_lo:[1,0,0] neg_hi:[1,0,0]
	v_pk_mul_f32 v[160:161], v[130:131], s[18:19]
	v_pk_add_f32 v[192:193], v[128:129], v[144:145]
	v_pk_add_f32 v[144:145], v[128:129], v[144:145] neg_lo:[0,1] neg_hi:[0,1]
	v_pk_fma_f32 v[130:131], v[130:131], s[16:17], v[160:161] op_sel:[0,0,1] op_sel_hi:[1,0,0] neg_lo:[1,0,0] neg_hi:[1,0,0]
	v_pk_add_f32 v[160:161], v[128:129], v[176:177]
	v_pk_add_f32 v[128:129], v[128:129], v[176:177] neg_lo:[0,1] neg_hi:[0,1]
	v_pk_add_f32 v[176:177], v[162:163], v[178:179]
	v_pk_add_f32 v[162:163], v[162:163], v[178:179] neg_lo:[0,1] neg_hi:[0,1]
	v_cvt_f32_ubyte0_e32 v2, v2
	v_pk_mul_f32 v[178:179], v[162:163], s[18:19]
	v_mul_f32_e32 v2, 0x39000000, v2
	v_pk_fma_f32 v[162:163], v[162:163], s[16:17], v[178:179] op_sel:[0,0,1] op_sel_hi:[1,0,0]
	v_pk_add_f32 v[178:179], v[164:165], v[180:181]
	v_pk_add_f32 v[164:165], v[164:165], v[180:181] neg_lo:[0,1] neg_hi:[0,1]
	v_sin_f32_e32 v34, v2
	v_pk_mul_f32 v[180:181], v[164:165], s[36:37]
	v_cos_f32_e32 v30, v2
	v_pk_fma_f32 v[164:165], v[164:165], s[66:67], v[180:181] op_sel:[0,0,1] op_sel_hi:[1,0,0]
	v_pk_add_f32 v[180:181], v[166:167], v[182:183]
	v_pk_add_f32 v[166:167], v[166:167], v[182:183] neg_lo:[0,1] neg_hi:[0,1]
	v_xor_b32_e32 v31, 0x80000000, v34
	v_pk_mul_f32 v[182:183], v[166:167], s[40:41]
	v_mov_b32_e32 v35, v31
	v_pk_fma_f32 v[166:167], v[166:167], s[68:69], v[182:183] op_sel:[0,0,1] op_sel_hi:[1,0,0]
	v_pk_add_f32 v[182:183], v[168:169], v[184:185]
	v_pk_add_f32 v[184:185], v[168:169], v[184:185] neg_lo:[0,1] neg_hi:[0,1]
	v_pk_mul_f32 v[2:3], v[30:31], v[34:35] op_sel:[1,0] op_sel_hi:[0,1]
	v_pk_add_f32 v[168:169], v[170:171], v[186:187]
	v_pk_add_f32 v[170:171], v[170:171], v[186:187] neg_lo:[0,1] neg_hi:[0,1]
	v_pk_fma_f32 v[44:45], v[30:31], v[30:31], v[2:3] op_sel_hi:[1,0,1]
	v_pk_mul_f32 v[186:187], v[170:171], s[40:41]
	v_pk_mul_f32 v[2:3], v[34:35], v[44:45] op_sel:[0,1] op_sel_hi:[1,0]
	v_pk_fma_f32 v[170:171], v[170:171], s[68:69], v[186:187] op_sel:[0,0,1] op_sel_hi:[1,0,0] neg_lo:[1,0,0] neg_hi:[1,0,0]
	v_pk_add_f32 v[186:187], v[172:173], v[188:189]
	v_pk_add_f32 v[172:173], v[172:173], v[188:189] neg_lo:[0,1] neg_hi:[0,1]
	v_xor_b32_e32 v54, 0x80000000, v45
	v_pk_mul_f32 v[188:189], v[172:173], s[36:37]
	v_mov_b32_e32 v55, v45
	v_pk_fma_f32 v[172:173], v[172:173], s[66:67], v[188:189] op_sel:[0,0,1] op_sel_hi:[1,0,0] neg_lo:[1,0,0] neg_hi:[1,0,0]
	v_pk_add_f32 v[188:189], v[174:175], v[190:191]
	v_pk_add_f32 v[174:175], v[174:175], v[190:191] neg_lo:[0,1] neg_hi:[0,1]
	v_pk_fma_f32 v[46:47], v[30:31], v[44:45], v[2:3] op_sel_hi:[0,1,1]
	v_pk_mul_f32 v[190:191], v[174:175], s[18:19]
	v_pk_mul_f32 v[2:3], v[44:45], v[54:55] op_sel:[1,0] op_sel_hi:[0,1]
	v_pk_fma_f32 v[174:175], v[174:175], s[16:17], v[190:191] op_sel:[0,0,1] op_sel_hi:[1,0,0] neg_lo:[1,0,0] neg_hi:[1,0,0]
	v_pk_add_f32 v[190:191], v[192:193], v[152:153]
	v_pk_add_f32 v[152:153], v[192:193], v[152:153] neg_lo:[0,1] neg_hi:[0,1]
	v_pk_add_f32 v[192:193], v[194:195], v[138:139]
	v_pk_add_f32 v[138:139], v[194:195], v[138:139] neg_lo:[0,1] neg_hi:[0,1]
	v_pk_fma_f32 v[52:53], v[44:45], v[44:45], v[2:3] op_sel_hi:[1,0,1]
	v_pk_mul_f32 v[194:195], v[138:139], s[36:37]
	v_xor_b32_e32 v58, 0x80000000, v53
	v_pk_fma_f32 v[138:139], v[138:139], s[66:67], v[194:195] op_sel:[0,0,1] op_sel_hi:[1,0,0]
	v_pk_add_f32 v[194:195], v[148:149], v[156:157]
	v_pk_add_f32 v[156:157], v[148:149], v[156:157] neg_lo:[0,1] neg_hi:[0,1]
	v_mov_b32_e32 v59, v53
	v_pk_add_f32 v[148:149], v[150:151], v[158:159]
	v_pk_add_f32 v[150:151], v[150:151], v[158:159] neg_lo:[0,1] neg_hi:[0,1]
	v_pk_mul_f32 v[2:3], v[52:53], v[58:59] op_sel:[1,0] op_sel_hi:[0,1]
	v_pk_mul_f32 v[158:159], v[150:151], s[36:37]
	v_pk_fma_f32 v[48:49], v[52:53], v[52:53], v[2:3] op_sel_hi:[1,0,1]
	v_pk_fma_f32 v[150:151], v[150:151], s[66:67], v[158:159] op_sel:[0,0,1] op_sel_hi:[1,0,0] neg_lo:[1,0,0] neg_hi:[1,0,0]
	v_pk_add_f32 v[158:159], v[144:145], v[154:155]
	v_pk_add_f32 v[144:145], v[144:145], v[154:155] neg_lo:[0,1] neg_hi:[0,1]
	v_pk_add_f32 v[154:155], v[132:133], v[140:141]
	v_pk_add_f32 v[132:133], v[132:133], v[140:141] neg_lo:[0,1] neg_hi:[0,1]
	v_pk_mul_f32 v[2:3], v[58:59], v[48:49] op_sel:[0,1] op_sel_hi:[1,0]
	v_pk_mul_f32 v[140:141], v[132:133], s[36:37]
	v_pk_fma_f32 v[36:37], v[52:53], v[48:49], v[2:3] op_sel_hi:[0,1,1]
	v_pk_fma_f32 v[132:133], v[132:133], s[66:67], v[140:141] op_sel:[0,0,1] op_sel_hi:[1,0,0]
	v_pk_add_f32 v[140:141], v[134:135], v[142:143]
	v_pk_add_f32 v[142:143], v[134:135], v[142:143] neg_lo:[0,1] neg_hi:[0,1]
	v_pk_mul_f32 v[2:3], v[58:59], v[36:37] op_sel:[0,1] op_sel_hi:[1,0]
	v_pk_add_f32 v[134:135], v[136:137], v[130:131]
	v_pk_add_f32 v[130:131], v[136:137], v[130:131] neg_lo:[0,1] neg_hi:[0,1]
	v_pk_fma_f32 v[26:27], v[52:53], v[36:37], v[2:3] op_sel_hi:[0,1,1]
	v_pk_mul_f32 v[136:137], v[130:131], s[36:37]
	v_pk_mul_f32 v[2:3], v[58:59], v[26:27] op_sel:[0,1] op_sel_hi:[1,0]
	v_pk_fma_f32 v[130:131], v[130:131], s[66:67], v[136:137] op_sel:[0,0,1] op_sel_hi:[1,0,0] neg_lo:[1,0,0] neg_hi:[1,0,0]
	v_pk_add_f32 v[136:137], v[160:161], v[182:183]
	v_pk_add_f32 v[160:161], v[160:161], v[182:183] neg_lo:[0,1] neg_hi:[0,1]
	v_pk_add_f32 v[182:183], v[176:177], v[168:169]
	v_pk_add_f32 v[168:169], v[176:177], v[168:169] neg_lo:[0,1] neg_hi:[0,1]
	v_pk_fma_f32 v[20:21], v[52:53], v[26:27], v[2:3] op_sel_hi:[0,1,1]
	v_pk_mul_f32 v[176:177], v[168:169], s[36:37]
	v_pk_mul_f32 v[2:3], v[58:59], v[20:21] op_sel:[0,1] op_sel_hi:[1,0]
	v_pk_fma_f32 v[168:169], v[168:169], s[66:67], v[176:177] op_sel:[0,0,1] op_sel_hi:[1,0,0]
	v_pk_add_f32 v[176:177], v[178:179], v[186:187]
	v_pk_add_f32 v[186:187], v[178:179], v[186:187] neg_lo:[0,1] neg_hi:[0,1]
	v_pk_fma_f32 v[10:11], v[52:53], v[20:21], v[2:3] op_sel_hi:[0,1,1]
	v_pk_add_f32 v[178:179], v[180:181], v[188:189]
	v_pk_add_f32 v[180:181], v[180:181], v[188:189] neg_lo:[0,1] neg_hi:[0,1]
	v_pk_mul_f32 v[2:3], v[58:59], v[10:11] op_sel:[0,1] op_sel_hi:[1,0]
	v_pk_mul_f32 v[188:189], v[180:181], s[36:37]
	v_pk_fma_f32 v[4:5], v[52:53], v[10:11], v[2:3] op_sel_hi:[0,1,1]
	v_pk_fma_f32 v[180:181], v[180:181], s[66:67], v[188:189] op_sel:[0,0,1] op_sel_hi:[1,0,0] neg_lo:[1,0,0] neg_hi:[1,0,0]
	v_pk_add_f32 v[188:189], v[128:129], v[184:185] op_sel:[0,1] op_sel_hi:[1,0] neg_hi:[0,1]
	v_pk_add_f32 v[128:129], v[128:129], v[184:185] op_sel:[0,1] op_sel_hi:[1,0] neg_lo:[0,1]
	v_pk_add_f32 v[184:185], v[162:163], v[170:171]
	v_pk_add_f32 v[162:163], v[162:163], v[170:171] neg_lo:[0,1] neg_hi:[0,1]
	v_xor_b32_e32 v72, 0x80000000, v47
	v_pk_mul_f32 v[170:171], v[162:163], s[36:37]
	v_mov_b32_e32 v73, v47
	v_pk_fma_f32 v[162:163], v[162:163], s[66:67], v[170:171] op_sel:[0,0,1] op_sel_hi:[1,0,0]
	v_pk_add_f32 v[170:171], v[164:165], v[172:173]
	v_pk_add_f32 v[172:173], v[164:165], v[172:173] neg_lo:[0,1] neg_hi:[0,1]
	v_pk_mul_f32 v[2:3], v[72:73], v[4:5] op_sel:[0,1] op_sel_hi:[1,0]
	v_pk_add_f32 v[164:165], v[166:167], v[174:175]
	v_pk_add_f32 v[166:167], v[166:167], v[174:175] neg_lo:[0,1] neg_hi:[0,1]
	v_pk_mul_f32 v[14:15], v[34:35], v[4:5] op_sel:[0,1] op_sel_hi:[1,0]
	v_pk_mul_f32 v[174:175], v[166:167], s[36:37]
	v_pk_mul_f32 v[40:41], v[34:35], v[10:11] op_sel:[0,1] op_sel_hi:[1,0]
	v_pk_fma_f32 v[166:167], v[166:167], s[66:67], v[174:175] op_sel:[0,0,1] op_sel_hi:[1,0,0] neg_lo:[1,0,0] neg_hi:[1,0,0]
	v_pk_add_f32 v[174:175], v[190:191], v[194:195]
	v_pk_add_f32 v[190:191], v[190:191], v[194:195] neg_lo:[0,1] neg_hi:[0,1]
	v_pk_add_f32 v[194:195], v[192:193], v[148:149]
	v_pk_add_f32 v[192:193], v[192:193], v[148:149] neg_lo:[0,1] neg_hi:[0,1]
	v_pk_mul_f32 v[66:67], v[34:35], v[20:21] op_sel:[0,1] op_sel_hi:[1,0]
	v_pk_add_f32 v[148:149], v[152:153], v[156:157] op_sel:[0,1] op_sel_hi:[1,0] neg_hi:[0,1]
	v_pk_add_f32 v[152:153], v[152:153], v[156:157] op_sel:[0,1] op_sel_hi:[1,0] neg_lo:[0,1]
	v_pk_add_f32 v[156:157], v[138:139], v[150:151]
	v_pk_add_f32 v[150:151], v[138:139], v[150:151] neg_lo:[0,1] neg_hi:[0,1]
	v_pk_mul_f32 v[82:83], v[34:35], v[26:27] op_sel:[0,1] op_sel_hi:[1,0]
	v_pk_add_f32 v[138:139], v[158:159], v[140:141]
	v_pk_add_f32 v[140:141], v[158:159], v[140:141] neg_lo:[0,1] neg_hi:[0,1]
	v_pk_add_f32 v[158:159], v[154:155], v[134:135]
	v_pk_add_f32 v[154:155], v[154:155], v[134:135] neg_lo:[0,1] neg_hi:[0,1]
	v_pk_mul_f32 v[96:97], v[34:35], v[36:37] op_sel:[0,1] op_sel_hi:[1,0]
	v_pk_add_f32 v[134:135], v[144:145], v[142:143] op_sel:[0,1] op_sel_hi:[1,0] neg_hi:[0,1]
	v_pk_add_f32 v[142:143], v[144:145], v[142:143] op_sel:[0,1] op_sel_hi:[1,0] neg_lo:[0,1]
	v_pk_add_f32 v[144:145], v[132:133], v[130:131]
	v_pk_add_f32 v[132:133], v[132:133], v[130:131] neg_lo:[0,1] neg_hi:[0,1]
	v_pk_mul_f32 v[110:111], v[34:35], v[48:49] op_sel:[0,1] op_sel_hi:[1,0]
	v_pk_add_f32 v[130:131], v[136:137], v[176:177]
	v_pk_add_f32 v[136:137], v[136:137], v[176:177] neg_lo:[0,1] neg_hi:[0,1]
	v_pk_add_f32 v[176:177], v[182:183], v[178:179]
	v_pk_add_f32 v[182:183], v[182:183], v[178:179] neg_lo:[0,1] neg_hi:[0,1]
	v_pk_mul_f32 v[124:125], v[34:35], v[52:53] op_sel:[0,1] op_sel_hi:[1,0]
	v_pk_add_f32 v[178:179], v[160:161], v[186:187] op_sel:[0,1] op_sel_hi:[1,0] neg_hi:[0,1]
	v_pk_add_f32 v[160:161], v[160:161], v[186:187] op_sel:[0,1] op_sel_hi:[1,0] neg_lo:[0,1]
	v_pk_add_f32 v[186:187], v[168:169], v[180:181]
	v_pk_add_f32 v[180:181], v[168:169], v[180:181] neg_lo:[0,1] neg_hi:[0,1]
	v_pk_fma_f32 v[2:3], v[46:47], v[4:5], v[2:3] op_sel_hi:[0,1,1]
	v_pk_add_f32 v[168:169], v[188:189], v[170:171]
	v_pk_add_f32 v[170:171], v[188:189], v[170:171] neg_lo:[0,1] neg_hi:[0,1]
	v_pk_add_f32 v[188:189], v[184:185], v[164:165]
	v_pk_add_f32 v[184:185], v[184:185], v[164:165] neg_lo:[0,1] neg_hi:[0,1]
	v_pk_mul_f32 v[8:9], v[54:55], v[4:5] op_sel:[0,1] op_sel_hi:[1,0]
	v_pk_add_f32 v[164:165], v[128:129], v[172:173] op_sel:[0,1] op_sel_hi:[1,0] neg_hi:[0,1]
	v_pk_add_f32 v[128:129], v[128:129], v[172:173] op_sel:[0,1] op_sel_hi:[1,0] neg_lo:[0,1]
	v_pk_add_f32 v[172:173], v[162:163], v[166:167]
	v_pk_add_f32 v[162:163], v[162:163], v[166:167] neg_lo:[0,1] neg_hi:[0,1]
	v_pk_fma_f32 v[14:15], v[30:31], v[4:5], v[14:15] op_sel_hi:[0,1,1]
	v_xor_b32_e32 v167, 0x80000000, v162
	v_mov_b32_e32 v166, v163
	v_pk_add_f32 v[162:163], v[174:175], v[194:195]
	v_pk_add_f32 v[174:175], v[174:175], v[194:195] neg_lo:[0,1] neg_hi:[0,1]
	v_pk_add_f32 v[194:195], v[190:191], v[192:193] op_sel:[0,1] op_sel_hi:[1,0] neg_hi:[0,1]
	v_pk_add_f32 v[190:191], v[190:191], v[192:193] op_sel:[0,1] op_sel_hi:[1,0] neg_lo:[0,1]
	v_pk_add_f32 v[192:193], v[148:149], v[156:157]
	v_pk_add_f32 v[148:149], v[148:149], v[156:157] neg_lo:[0,1] neg_hi:[0,1]
	v_pk_add_f32 v[156:157], v[152:153], v[150:151] op_sel:[0,1] op_sel_hi:[1,0] neg_hi:[0,1]
	v_pk_add_f32 v[150:151], v[152:153], v[150:151] op_sel:[0,1] op_sel_hi:[1,0] neg_lo:[0,1]
	v_pk_add_f32 v[152:153], v[138:139], v[158:159]
	v_pk_add_f32 v[138:139], v[138:139], v[158:159] neg_lo:[0,1] neg_hi:[0,1]
	v_pk_add_f32 v[158:159], v[140:141], v[154:155] op_sel:[0,1] op_sel_hi:[1,0] neg_hi:[0,1]
	v_pk_add_f32 v[140:141], v[140:141], v[154:155] op_sel:[0,1] op_sel_hi:[1,0] neg_lo:[0,1]
	v_pk_add_f32 v[154:155], v[134:135], v[144:145]
	v_pk_add_f32 v[134:135], v[134:135], v[144:145] neg_lo:[0,1] neg_hi:[0,1]
	v_pk_add_f32 v[144:145], v[142:143], v[132:133] op_sel:[0,1] op_sel_hi:[1,0] neg_hi:[0,1]
	v_pk_add_f32 v[132:133], v[142:143], v[132:133] op_sel:[0,1] op_sel_hi:[1,0] neg_lo:[0,1]
	v_pk_add_f32 v[142:143], v[130:131], v[176:177]
	v_pk_mul_f32 v[24:25], v[72:73], v[10:11] op_sel:[0,1] op_sel_hi:[1,0]
	v_pk_mul_f32 v[34:35], v[34:35], v[142:143] op_sel:[0,1] op_sel_hi:[1,0]
	v_pk_mul_f32 v[32:33], v[54:55], v[10:11] op_sel:[0,1] op_sel_hi:[1,0]
	v_pk_fma_f32 v[40:41], v[30:31], v[10:11], v[40:41] op_sel_hi:[0,1,1]
	v_pk_mul_f32 v[56:57], v[72:73], v[20:21] op_sel:[0,1] op_sel_hi:[1,0]
	v_pk_mul_f32 v[62:63], v[54:55], v[20:21] op_sel:[0,1] op_sel_hi:[1,0]
	v_pk_fma_f32 v[66:67], v[30:31], v[20:21], v[66:67] op_sel_hi:[0,1,1]
	v_pk_mul_f32 v[74:75], v[72:73], v[26:27] op_sel:[0,1] op_sel_hi:[1,0]
	v_pk_mul_f32 v[78:79], v[54:55], v[26:27] op_sel:[0,1] op_sel_hi:[1,0]
	v_pk_fma_f32 v[82:83], v[30:31], v[26:27], v[82:83] op_sel_hi:[0,1,1]
	v_pk_mul_f32 v[88:89], v[72:73], v[36:37] op_sel:[0,1] op_sel_hi:[1,0]
	v_pk_mul_f32 v[92:93], v[54:55], v[36:37] op_sel:[0,1] op_sel_hi:[1,0]
	v_pk_fma_f32 v[96:97], v[30:31], v[36:37], v[96:97] op_sel_hi:[0,1,1]
	v_pk_mul_f32 v[102:103], v[72:73], v[48:49] op_sel:[0,1] op_sel_hi:[1,0]
	v_pk_mul_f32 v[106:107], v[54:55], v[48:49] op_sel:[0,1] op_sel_hi:[1,0]
	v_pk_fma_f32 v[110:111], v[30:31], v[48:49], v[110:111] op_sel_hi:[0,1,1]
	v_pk_mul_f32 v[116:117], v[52:53], v[72:73] op_sel:[1,0] op_sel_hi:[0,1]
	v_pk_mul_f32 v[120:121], v[54:55], v[52:53] op_sel:[0,1] op_sel_hi:[1,0]
	v_pk_fma_f32 v[124:125], v[30:31], v[52:53], v[124:125] op_sel_hi:[0,1,1]
	v_pk_add_f32 v[130:131], v[130:131], v[176:177] neg_lo:[0,1] neg_hi:[0,1]
	v_pk_add_f32 v[176:177], v[136:137], v[182:183] op_sel:[0,1] op_sel_hi:[1,0] neg_hi:[0,1]
	v_pk_add_f32 v[136:137], v[136:137], v[182:183] op_sel:[0,1] op_sel_hi:[1,0] neg_lo:[0,1]
	v_pk_add_f32 v[182:183], v[178:179], v[186:187]
	v_pk_add_f32 v[178:179], v[178:179], v[186:187] neg_lo:[0,1] neg_hi:[0,1]
	v_pk_add_f32 v[186:187], v[160:161], v[180:181] op_sel:[0,1] op_sel_hi:[1,0] neg_hi:[0,1]
	v_pk_add_f32 v[160:161], v[160:161], v[180:181] op_sel:[0,1] op_sel_hi:[1,0] neg_lo:[0,1]
	v_pk_add_f32 v[180:181], v[168:169], v[188:189]
	v_pk_fma_f32 v[30:31], v[30:31], v[142:143], v[34:35] op_sel_hi:[0,1,1]
	v_pk_mul_f32 v[34:35], v[54:55], v[152:153] op_sel:[0,1] op_sel_hi:[1,0]
	v_xor_b32_e32 v6, 0x80000000, v3
	v_pk_fma_f32 v[8:9], v[44:45], v[4:5], v[8:9] op_sel_hi:[0,1,1]
	v_pk_fma_f32 v[24:25], v[46:47], v[10:11], v[24:25] op_sel_hi:[0,1,1]
	v_pk_fma_f32 v[32:33], v[44:45], v[10:11], v[32:33] op_sel_hi:[0,1,1]
	v_pk_fma_f32 v[56:57], v[46:47], v[20:21], v[56:57] op_sel_hi:[0,1,1]
	v_pk_fma_f32 v[62:63], v[44:45], v[20:21], v[62:63] op_sel_hi:[0,1,1]
	v_pk_fma_f32 v[74:75], v[46:47], v[26:27], v[74:75] op_sel_hi:[0,1,1]
	v_pk_fma_f32 v[78:79], v[44:45], v[26:27], v[78:79] op_sel_hi:[0,1,1]
	v_pk_fma_f32 v[88:89], v[46:47], v[36:37], v[88:89] op_sel_hi:[0,1,1]
	v_pk_fma_f32 v[92:93], v[44:45], v[36:37], v[92:93] op_sel_hi:[0,1,1]
	v_pk_fma_f32 v[102:103], v[46:47], v[48:49], v[102:103] op_sel_hi:[0,1,1]
	v_pk_fma_f32 v[106:107], v[44:45], v[48:49], v[106:107] op_sel_hi:[0,1,1]
	v_xor_b32_e32 v114, 0x80000000, v49
	v_pk_fma_f32 v[116:117], v[52:53], v[46:47], v[116:117] op_sel_hi:[1,0,1]
	v_pk_fma_f32 v[120:121], v[44:45], v[52:53], v[120:121] op_sel_hi:[0,1,1]
	v_mov_b32_e32 v115, v49
	v_mov_b32_e32 v7, v3
	v_pk_add_f32 v[168:169], v[168:169], v[188:189] neg_lo:[0,1] neg_hi:[0,1]
	v_pk_add_f32 v[188:189], v[170:171], v[184:185] op_sel:[0,1] op_sel_hi:[1,0] neg_hi:[0,1]
	v_pk_add_f32 v[170:171], v[170:171], v[184:185] op_sel:[0,1] op_sel_hi:[1,0] neg_lo:[0,1]
	v_pk_add_f32 v[184:185], v[164:165], v[172:173]
	v_pk_add_f32 v[164:165], v[164:165], v[172:173] neg_lo:[0,1] neg_hi:[0,1]
	v_pk_add_f32 v[172:173], v[128:129], v[166:167]
	v_pk_add_f32 v[128:129], v[128:129], v[166:167] neg_lo:[0,1] neg_hi:[0,1]
	v_pk_fma_f32 v[34:35], v[44:45], v[152:153], v[34:35] op_sel_hi:[0,1,1]
	v_pk_mul_f32 v[44:45], v[72:73], v[180:181] op_sel:[0,1] op_sel_hi:[1,0]
	v_xor_b32_e32 v12, 0x80000000, v9
	v_xor_b32_e32 v16, 0x80000000, v15
	v_xor_b32_e32 v22, 0x80000000, v5
	v_xor_b32_e32 v28, 0x80000000, v25
	v_xor_b32_e32 v38, 0x80000000, v33
	v_xor_b32_e32 v42, 0x80000000, v41
	v_xor_b32_e32 v50, 0x80000000, v11
	v_xor_b32_e32 v60, 0x80000000, v57
	v_xor_b32_e32 v64, 0x80000000, v63
	v_xor_b32_e32 v68, 0x80000000, v67
	v_xor_b32_e32 v70, 0x80000000, v21
	v_xor_b32_e32 v76, 0x80000000, v75
	v_xor_b32_e32 v80, 0x80000000, v79
	v_xor_b32_e32 v84, 0x80000000, v83
	v_xor_b32_e32 v86, 0x80000000, v27
	v_xor_b32_e32 v90, 0x80000000, v89
	v_xor_b32_e32 v94, 0x80000000, v93
	v_xor_b32_e32 v98, 0x80000000, v97
	v_xor_b32_e32 v100, 0x80000000, v37
	v_xor_b32_e32 v104, 0x80000000, v103
	v_xor_b32_e32 v108, 0x80000000, v107
	v_xor_b32_e32 v112, 0x80000000, v111
	v_xor_b32_e32 v118, 0x80000000, v117
	v_xor_b32_e32 v122, 0x80000000, v121
	v_xor_b32_e32 v126, 0x80000000, v125
	v_mov_b32_e32 v127, v125
	v_mov_b32_e32 v123, v121
	v_mov_b32_e32 v119, v117
	v_mov_b32_e32 v113, v111
	v_mov_b32_e32 v109, v107
	v_mov_b32_e32 v105, v103
	v_mov_b32_e32 v101, v37
	v_mov_b32_e32 v99, v97
	v_mov_b32_e32 v95, v93
	v_mov_b32_e32 v91, v89
	v_mov_b32_e32 v87, v27
	v_mov_b32_e32 v85, v83
	v_mov_b32_e32 v81, v79
	v_mov_b32_e32 v77, v75
	v_mov_b32_e32 v71, v21
	v_mov_b32_e32 v69, v67
	v_mov_b32_e32 v65, v63
	v_mov_b32_e32 v61, v57
	v_mov_b32_e32 v51, v11
	v_mov_b32_e32 v43, v41
	v_mov_b32_e32 v39, v33
	v_mov_b32_e32 v29, v25
	v_mov_b32_e32 v23, v5
	v_mov_b32_e32 v17, v15
	v_mov_b32_e32 v13, v9
	v_pk_fma_f32 v[44:45], v[46:47], v[180:181], v[44:45] op_sel_hi:[0,1,1]
	v_pk_mul_f32 v[46:47], v[58:59], v[192:193] op_sel:[0,1] op_sel_hi:[1,0]
	v_pk_mul_f32 v[72:73], v[114:115], v[194:195] op_sel:[0,1] op_sel_hi:[1,0]
	v_pk_mul_f32 v[6:7], v[128:129], v[6:7] op_sel:[1,0] op_sel_hi:[0,1]
	v_pk_fma_f32 v[46:47], v[52:53], v[192:193], v[46:47] op_sel_hi:[0,1,1]
	v_pk_mul_f32 v[52:53], v[126:127], v[182:183] op_sel:[0,1] op_sel_hi:[1,0]
	v_pk_mul_f32 v[54:55], v[122:123], v[154:155] op_sel:[0,1] op_sel_hi:[1,0]
	v_pk_mul_f32 v[58:59], v[118:119], v[184:185] op_sel:[0,1] op_sel_hi:[1,0]
	v_pk_fma_f32 v[48:49], v[48:49], v[194:195], v[72:73] op_sel_hi:[0,1,1]
	v_pk_mul_f32 v[72:73], v[112:113], v[176:177] op_sel:[0,1] op_sel_hi:[1,0]
	v_pk_mul_f32 v[108:109], v[108:109], v[158:159] op_sel:[0,1] op_sel_hi:[1,0]
	v_pk_mul_f32 v[104:105], v[104:105], v[188:189] op_sel:[0,1] op_sel_hi:[1,0]
	v_pk_mul_f32 v[100:101], v[100:101], v[156:157] op_sel:[0,1] op_sel_hi:[1,0]
	v_pk_mul_f32 v[98:99], v[98:99], v[186:187] op_sel:[0,1] op_sel_hi:[1,0]
	v_pk_mul_f32 v[94:95], v[94:95], v[144:145] op_sel:[0,1] op_sel_hi:[1,0]
	v_pk_mul_f32 v[90:91], v[90:91], v[172:173] op_sel:[0,1] op_sel_hi:[1,0]
	v_pk_mul_f32 v[86:87], v[174:175], v[86:87] op_sel:[1,0] op_sel_hi:[0,1]
	v_pk_mul_f32 v[84:85], v[130:131], v[84:85] op_sel:[1,0] op_sel_hi:[0,1]
	v_pk_mul_f32 v[80:81], v[138:139], v[80:81] op_sel:[1,0] op_sel_hi:[0,1]
	v_pk_mul_f32 v[76:77], v[168:169], v[76:77] op_sel:[1,0] op_sel_hi:[0,1]
	v_pk_mul_f32 v[70:71], v[148:149], v[70:71] op_sel:[1,0] op_sel_hi:[0,1]
	v_pk_mul_f32 v[68:69], v[178:179], v[68:69] op_sel:[1,0] op_sel_hi:[0,1]
	v_pk_mul_f32 v[64:65], v[134:135], v[64:65] op_sel:[1,0] op_sel_hi:[0,1]
	v_pk_mul_f32 v[60:61], v[164:165], v[60:61] op_sel:[1,0] op_sel_hi:[0,1]
	v_pk_mul_f32 v[50:51], v[190:191], v[50:51] op_sel:[1,0] op_sel_hi:[0,1]
	v_pk_mul_f32 v[42:43], v[136:137], v[42:43] op_sel:[1,0] op_sel_hi:[0,1]
	v_pk_mul_f32 v[38:39], v[140:141], v[38:39] op_sel:[1,0] op_sel_hi:[0,1]
	v_pk_mul_f32 v[28:29], v[170:171], v[28:29] op_sel:[1,0] op_sel_hi:[0,1]
	v_pk_mul_f32 v[22:23], v[150:151], v[22:23] op_sel:[1,0] op_sel_hi:[0,1]
	v_pk_mul_f32 v[16:17], v[160:161], v[16:17] op_sel:[1,0] op_sel_hi:[0,1]
	v_pk_mul_f32 v[12:13], v[132:133], v[12:13] op_sel:[1,0] op_sel_hi:[0,1]
	v_pk_fma_f32 v[2:3], v[128:129], v[2:3], v[6:7] op_sel_hi:[1,0,1]
	v_pk_fma_f32 v[52:53], v[124:125], v[182:183], v[52:53] op_sel_hi:[0,1,1]
	v_pk_fma_f32 v[54:55], v[120:121], v[154:155], v[54:55] op_sel_hi:[0,1,1]
	v_pk_fma_f32 v[58:59], v[116:117], v[184:185], v[58:59] op_sel_hi:[0,1,1]
	v_pk_fma_f32 v[72:73], v[110:111], v[176:177], v[72:73] op_sel_hi:[0,1,1]
	v_pk_fma_f32 v[106:107], v[106:107], v[158:159], v[108:109] op_sel_hi:[0,1,1]
	v_pk_fma_f32 v[102:103], v[102:103], v[188:189], v[104:105] op_sel_hi:[0,1,1]
	v_pk_fma_f32 v[36:37], v[36:37], v[156:157], v[100:101] op_sel_hi:[0,1,1]
	v_pk_fma_f32 v[96:97], v[96:97], v[186:187], v[98:99] op_sel_hi:[0,1,1]
	v_pk_fma_f32 v[92:93], v[92:93], v[144:145], v[94:95] op_sel_hi:[0,1,1]
	v_pk_fma_f32 v[88:89], v[88:89], v[172:173], v[90:91] op_sel_hi:[0,1,1]
	v_pk_fma_f32 v[26:27], v[174:175], v[26:27], v[86:87] op_sel_hi:[1,0,1]
	v_pk_fma_f32 v[82:83], v[130:131], v[82:83], v[84:85] op_sel_hi:[1,0,1]
	v_pk_fma_f32 v[78:79], v[138:139], v[78:79], v[80:81] op_sel_hi:[1,0,1]
	v_pk_fma_f32 v[74:75], v[168:169], v[74:75], v[76:77] op_sel_hi:[1,0,1]
	v_pk_fma_f32 v[20:21], v[148:149], v[20:21], v[70:71] op_sel_hi:[1,0,1]
	v_pk_fma_f32 v[66:67], v[178:179], v[66:67], v[68:69] op_sel_hi:[1,0,1]
	v_pk_fma_f32 v[62:63], v[134:135], v[62:63], v[64:65] op_sel_hi:[1,0,1]
	v_pk_fma_f32 v[56:57], v[164:165], v[56:57], v[60:61] op_sel_hi:[1,0,1]
	v_pk_fma_f32 v[10:11], v[190:191], v[10:11], v[50:51] op_sel_hi:[1,0,1]
	v_pk_fma_f32 v[40:41], v[136:137], v[40:41], v[42:43] op_sel_hi:[1,0,1]
	v_pk_fma_f32 v[32:33], v[140:141], v[32:33], v[38:39] op_sel_hi:[1,0,1]
	v_pk_fma_f32 v[24:25], v[170:171], v[24:25], v[28:29] op_sel_hi:[1,0,1]
	v_pk_fma_f32 v[4:5], v[150:151], v[4:5], v[22:23] op_sel_hi:[1,0,1]
	v_pk_fma_f32 v[14:15], v[160:161], v[14:15], v[16:17] op_sel_hi:[1,0,1]
	v_pk_fma_f32 v[8:9], v[132:133], v[8:9], v[12:13] op_sel_hi:[1,0,1]
	ds_write_b64 v18, v[162:163]
	ds_write_b64 v18, v[26:27] offset:2112
	ds_write_b64 v18, v[48:49] offset:4224
	ds_write_b64 v18, v[10:11] offset:6336
	ds_write_b64 v18, v[46:47] offset:8448
	ds_write_b64 v18, v[20:21] offset:10560
	ds_write_b64 v18, v[36:37] offset:12672
	ds_write_b64 v18, v[4:5] offset:14784
	ds_write_b64 v18, v[34:35] offset:16896
	ds_write_b64 v18, v[78:79] offset:19008
	ds_write_b64 v18, v[106:107] offset:21120
	ds_write_b64 v18, v[32:33] offset:23232
	ds_write_b64 v18, v[54:55] offset:25344
	ds_write_b64 v18, v[62:63] offset:27456
	ds_write_b64 v18, v[92:93] offset:29568
	ds_write_b64 v18, v[8:9] offset:31680
	ds_write_b64 v18, v[30:31] offset:33792
	ds_write_b64 v18, v[82:83] offset:35904
	ds_write_b64 v18, v[72:73] offset:38016
	ds_write_b64 v18, v[40:41] offset:40128
	ds_write_b64 v18, v[52:53] offset:42240
	ds_write_b64 v18, v[66:67] offset:44352
	ds_write_b64 v18, v[96:97] offset:46464
	ds_write_b64 v18, v[14:15] offset:48576
	ds_write_b64 v18, v[44:45] offset:50688
	ds_write_b64 v18, v[74:75] offset:52800
	ds_write_b64 v18, v[102:103] offset:54912
	ds_write_b64 v18, v[24:25] offset:57024
	ds_write_b64 v18, v[58:59] offset:59136
	ds_write_b64 v18, v[56:57] offset:61248
	ds_write_b64 v18, v[88:89] offset:63360
	ds_write_b64 v18, v[2:3] offset:65472
	v_mov_b32_e32 v3, v210
	s_waitcnt lgkmcnt(0)
	s_barrier
	s_add_i32 s64, s62, s48
	v_and_b32_e32 v5, 15, v3
	v_cvt_f32_ubyte0_e32 v2, v5
	v_mul_f32_e32 v4, 0x3b800000, v2
	v_sin_f32_e32 v2, v4
	v_cos_f32_e32 v4, v4
	v_lshlrev_b32_e32 v64, 3, v5
	v_lshlrev_b32_e32 v18, 4, v3
	v_xor_b32_e32 v5, 0x80000000, v2
	v_mov_b32_e32 v3, v5
	v_pk_mul_f32 v[6:7], v[4:5], v[2:3] op_sel:[1,0] op_sel_hi:[0,1]
	v_pk_fma_f32 v[6:7], v[4:5], v[4:5], v[6:7] op_sel_hi:[1,0,1]
	s_ashr_i32 s65, s64, 31
	v_xor_b32_e32 v12, 0x80000000, v7
	v_mov_b32_e32 v13, v7
	v_pk_mul_f32 v[10:11], v[6:7], v[12:13] op_sel:[1,0] op_sel_hi:[0,1]
	v_pk_fma_f32 v[10:11], v[6:7], v[6:7], v[10:11] op_sel_hi:[1,0,1]
	v_pk_mul_f32 v[8:9], v[2:3], v[6:7] op_sel:[0,1] op_sel_hi:[1,0]
	v_xor_b32_e32 v14, 0x80000000, v11
	v_mov_b32_e32 v15, v11
	v_pk_mul_f32 v[32:33], v[10:11], v[14:15] op_sel:[1,0] op_sel_hi:[0,1]
	v_pk_fma_f32 v[32:33], v[10:11], v[10:11], v[32:33] op_sel_hi:[1,0,1]
	v_pk_mul_f32 v[16:17], v[2:3], v[10:11] op_sel:[0,1] op_sel_hi:[1,0]
	v_pk_mul_f32 v[48:49], v[14:15], v[32:33] op_sel:[0,1] op_sel_hi:[1,0]
	v_pk_mul_f32 v[36:37], v[2:3], v[32:33] op_sel:[0,1] op_sel_hi:[1,0]
	v_pk_fma_f32 v[48:49], v[10:11], v[32:33], v[48:49] op_sel_hi:[0,1,1]
	v_pk_mul_f32 v[52:53], v[2:3], v[48:49] op_sel:[0,1] op_sel_hi:[1,0]
	v_pk_fma_f32 v[8:9], v[4:5], v[6:7], v[8:9] op_sel_hi:[0,1,1]
	v_pk_fma_f32 v[16:17], v[4:5], v[10:11], v[16:17] op_sel_hi:[0,1,1]
	v_pk_fma_f32 v[36:37], v[4:5], v[32:33], v[36:37] op_sel_hi:[0,1,1]
	v_pk_fma_f32 v[52:53], v[4:5], v[48:49], v[52:53] op_sel_hi:[0,1,1]
	v_and_b32_e32 v5, 0xffffff00, v18
	v_lshlrev_b32_e32 v18, 3, v5
	v_add3_u32 v18, 0, v64, v18
	v_ashrrev_i32_e32 v64, 2, v5
	v_add_u32_e32 v106, v18, v64
	ds_read2_b64 v[64:67], v106 offset1:16
	ds_read2_b64 v[68:71], v106 offset0:33 offset1:49
	ds_read2_b64 v[72:75], v106 offset0:66 offset1:82
	ds_read2_b64 v[76:79], v106 offset0:132 offset1:148
	ds_read2_b64 v[80:83], v106 offset0:99 offset1:115
	ds_read2_b64 v[84:87], v106 offset0:165 offset1:181
	ds_read2_b64 v[88:91], v106 offset0:198 offset1:214
	ds_read2_b64 v[92:95], v106 offset0:231 offset1:247
	s_waitcnt lgkmcnt(4)
	v_pk_add_f32 v[96:97], v[64:65], v[76:77]
	v_pk_add_f32 v[64:65], v[64:65], v[76:77] neg_lo:[0,1] neg_hi:[0,1]
	v_pk_add_f32 v[76:77], v[66:67], v[78:79]
	v_pk_add_f32 v[66:67], v[66:67], v[78:79] neg_lo:[0,1] neg_hi:[0,1]
	s_waitcnt lgkmcnt(1)
	v_pk_add_f32 v[98:99], v[74:75], v[90:91]
	v_pk_mul_f32 v[78:79], v[66:67], s[18:19]
	v_pk_add_f32 v[74:75], v[74:75], v[90:91] neg_lo:[0,1] neg_hi:[0,1]
	v_pk_fma_f32 v[66:67], v[66:67], s[16:17], v[78:79] op_sel:[0,0,1] op_sel_hi:[1,0,0]
	v_pk_add_f32 v[78:79], v[68:69], v[84:85]
	v_pk_add_f32 v[68:69], v[68:69], v[84:85] neg_lo:[0,1] neg_hi:[0,1]
	v_pk_mul_f32 v[90:91], v[74:75], s[40:41]
	v_pk_mul_f32 v[84:85], v[68:69], s[36:37]
	v_pk_fma_f32 v[74:75], v[74:75], s[68:69], v[90:91] op_sel:[0,0,1] op_sel_hi:[1,0,0] neg_lo:[1,0,0] neg_hi:[1,0,0]
	v_pk_fma_f32 v[68:69], v[68:69], s[66:67], v[84:85] op_sel:[0,0,1] op_sel_hi:[1,0,0]
	v_pk_add_f32 v[84:85], v[70:71], v[86:87]
	v_pk_add_f32 v[70:71], v[70:71], v[86:87] neg_lo:[0,1] neg_hi:[0,1]
	s_waitcnt lgkmcnt(0)
	v_pk_add_f32 v[90:91], v[80:81], v[92:93]
	v_pk_add_f32 v[80:81], v[80:81], v[92:93] neg_lo:[0,1] neg_hi:[0,1]
	v_pk_mul_f32 v[86:87], v[70:71], s[40:41]
	v_pk_mul_f32 v[92:93], v[80:81], s[36:37]
	v_pk_fma_f32 v[70:71], v[70:71], s[68:69], v[86:87] op_sel:[0,0,1] op_sel_hi:[1,0,0]
	v_pk_add_f32 v[86:87], v[72:73], v[88:89]
	v_pk_add_f32 v[88:89], v[72:73], v[88:89] neg_lo:[0,1] neg_hi:[0,1]
	v_pk_fma_f32 v[80:81], v[80:81], s[66:67], v[92:93] op_sel:[0,0,1] op_sel_hi:[1,0,0] neg_lo:[1,0,0] neg_hi:[1,0,0]
	v_pk_add_f32 v[92:93], v[82:83], v[94:95]
	v_pk_add_f32 v[82:83], v[82:83], v[94:95] neg_lo:[0,1] neg_hi:[0,1]
	v_pk_mul_f32 v[94:95], v[82:83], s[18:19]
	v_pk_fma_f32 v[82:83], v[82:83], s[16:17], v[94:95] op_sel:[0,0,1] op_sel_hi:[1,0,0] neg_lo:[1,0,0] neg_hi:[1,0,0]
	v_pk_add_f32 v[94:95], v[96:97], v[86:87]
	v_pk_add_f32 v[86:87], v[96:97], v[86:87] neg_lo:[0,1] neg_hi:[0,1]
	v_pk_add_f32 v[96:97], v[76:77], v[98:99]
	v_pk_add_f32 v[76:77], v[76:77], v[98:99] neg_lo:[0,1] neg_hi:[0,1]
	v_pk_add_f32 v[100:101], v[84:85], v[92:93]
	v_pk_add_f32 v[84:85], v[84:85], v[92:93] neg_lo:[0,1] neg_hi:[0,1]
	v_pk_add_f32 v[72:73], v[64:65], v[88:89] op_sel:[0,1] op_sel_hi:[1,0] neg_hi:[0,1]
	v_pk_add_f32 v[64:65], v[64:65], v[88:89] op_sel:[0,1] op_sel_hi:[1,0] neg_lo:[0,1]
	v_pk_add_f32 v[88:89], v[66:67], v[74:75]
	v_pk_add_f32 v[66:67], v[66:67], v[74:75] neg_lo:[0,1] neg_hi:[0,1]
	v_pk_mul_f32 v[98:99], v[76:77], s[36:37]
	v_pk_mul_f32 v[92:93], v[84:85], s[36:37]
	v_pk_mul_f32 v[74:75], v[66:67], s[36:37]
	v_pk_fma_f32 v[76:77], v[76:77], s[66:67], v[98:99] op_sel:[0,0,1] op_sel_hi:[1,0,0]
	v_pk_add_f32 v[98:99], v[78:79], v[90:91]
	v_pk_add_f32 v[90:91], v[78:79], v[90:91] neg_lo:[0,1] neg_hi:[0,1]
	v_pk_fma_f32 v[84:85], v[84:85], s[66:67], v[92:93] op_sel:[0,0,1] op_sel_hi:[1,0,0] neg_lo:[1,0,0] neg_hi:[1,0,0]
	v_pk_fma_f32 v[66:67], v[66:67], s[66:67], v[74:75] op_sel:[0,0,1] op_sel_hi:[1,0,0]
	v_pk_add_f32 v[74:75], v[68:69], v[80:81]
	v_pk_add_f32 v[92:93], v[70:71], v[82:83]
	v_pk_add_f32 v[70:71], v[70:71], v[82:83] neg_lo:[0,1] neg_hi:[0,1]
	v_pk_add_f32 v[68:69], v[68:69], v[80:81] neg_lo:[0,1] neg_hi:[0,1]
	v_pk_mul_f32 v[82:83], v[70:71], s[36:37]
	v_pk_add_f32 v[102:103], v[72:73], v[74:75]
	v_pk_add_f32 v[72:73], v[72:73], v[74:75] neg_lo:[0,1] neg_hi:[0,1]
	v_pk_add_f32 v[74:75], v[88:89], v[92:93]
	v_pk_add_f32 v[92:93], v[88:89], v[92:93] neg_lo:[0,1] neg_hi:[0,1]
	v_xor_b32_e32 v20, 0x80000000, v9
	v_mov_b32_e32 v21, v9
	v_pk_mul_f32 v[24:25], v[12:13], v[10:11] op_sel:[0,1] op_sel_hi:[1,0]
	v_xor_b32_e32 v81, 0x80000000, v68
	v_pk_fma_f32 v[70:71], v[70:71], s[66:67], v[82:83] op_sel:[0,0,1] op_sel_hi:[1,0,0] neg_lo:[1,0,0] neg_hi:[1,0,0]
	v_pk_add_f32 v[78:79], v[86:87], v[90:91] op_sel:[0,1] op_sel_hi:[1,0] neg_hi:[0,1]
	v_pk_add_f32 v[86:87], v[86:87], v[90:91] op_sel:[0,1] op_sel_hi:[1,0] neg_lo:[0,1]
	v_pk_add_f32 v[90:91], v[76:77], v[84:85]
	v_pk_add_f32 v[84:85], v[76:77], v[84:85] neg_lo:[0,1] neg_hi:[0,1]
	v_mov_b32_e32 v80, v69
	v_xor_b32_e32 v22, 0x80000000, v17
	v_mov_b32_e32 v23, v17
	v_pk_fma_f32 v[24:25], v[6:7], v[10:11], v[24:25] op_sel_hi:[0,1,1]
	v_pk_mul_f32 v[28:29], v[10:11], v[20:21] op_sel:[1,0] op_sel_hi:[0,1]
	v_pk_add_f32 v[68:69], v[64:65], v[80:81]
	v_pk_add_f32 v[64:65], v[64:65], v[80:81] neg_lo:[0,1] neg_hi:[0,1]
	v_pk_add_f32 v[80:81], v[66:67], v[70:71]
	v_pk_add_f32 v[70:71], v[66:67], v[70:71] neg_lo:[0,1] neg_hi:[0,1]
	v_pk_add_f32 v[88:89], v[72:73], v[92:93] op_sel:[0,1] op_sel_hi:[1,0] neg_hi:[0,1]
	v_xor_b32_e32 v26, 0x80000000, v25
	v_mov_b32_e32 v27, v25
	v_pk_fma_f32 v[28:29], v[10:11], v[8:9], v[28:29] op_sel_hi:[1,0,1]
	v_pk_add_f32 v[76:77], v[86:87], v[84:85] op_sel:[0,1] op_sel_hi:[1,0] neg_hi:[0,1]
	v_pk_add_f32 v[72:73], v[72:73], v[92:93] op_sel:[0,1] op_sel_hi:[1,0] neg_lo:[0,1]
	v_pk_mul_f32 v[92:93], v[22:23], v[88:89] op_sel:[0,1] op_sel_hi:[1,0]
	v_xor_b32_e32 v30, 0x80000000, v29
	v_mov_b32_e32 v31, v29
	v_pk_add_f32 v[82:83], v[94:95], v[98:99]
	v_pk_add_f32 v[94:95], v[94:95], v[98:99] neg_lo:[0,1] neg_hi:[0,1]
	v_pk_add_f32 v[98:99], v[96:97], v[100:101]
	v_pk_add_f32 v[66:67], v[64:65], v[70:71] op_sel:[0,1] op_sel_hi:[1,0] neg_hi:[0,1]
	v_pk_fma_f32 v[88:89], v[16:17], v[88:89], v[92:93] op_sel_hi:[0,1,1]
	v_pk_mul_f32 v[92:93], v[26:27], v[76:77] op_sel:[0,1] op_sel_hi:[1,0]
	v_xor_b32_e32 v34, 0x80000000, v33
	v_mov_b32_e32 v35, v33
	v_pk_mul_f32 v[40:41], v[12:13], v[32:33] op_sel:[0,1] op_sel_hi:[1,0]
	v_pk_add_f32 v[104:105], v[82:83], v[98:99]
	v_pk_add_f32 v[82:83], v[82:83], v[98:99] neg_lo:[0,1] neg_hi:[0,1]
	v_pk_fma_f32 v[76:77], v[24:25], v[76:77], v[92:93] op_sel_hi:[0,1,1]
	v_pk_mul_f32 v[92:93], v[30:31], v[66:67] op_sel:[0,1] op_sel_hi:[1,0]
	v_xor_b32_e32 v38, 0x80000000, v37
	v_mov_b32_e32 v39, v37
	v_pk_fma_f32 v[40:41], v[6:7], v[32:33], v[40:41] op_sel_hi:[0,1,1]
	v_pk_mul_f32 v[44:45], v[20:21], v[32:33] op_sel:[0,1] op_sel_hi:[1,0]
	v_pk_add_f32 v[84:85], v[86:87], v[84:85] op_sel:[0,1] op_sel_hi:[1,0] neg_lo:[0,1]
	v_pk_add_f32 v[86:87], v[102:103], v[74:75]
	v_pk_add_f32 v[74:75], v[102:103], v[74:75] neg_lo:[0,1] neg_hi:[0,1]
	v_pk_fma_f32 v[66:67], v[28:29], v[66:67], v[92:93] op_sel_hi:[0,1,1]
	v_pk_mul_f32 v[92:93], v[34:35], v[82:83] op_sel:[0,1] op_sel_hi:[1,0]
	v_xor_b32_e32 v42, 0x80000000, v41
	v_mov_b32_e32 v43, v41
	v_pk_fma_f32 v[44:45], v[8:9], v[32:33], v[44:45] op_sel_hi:[0,1,1]
	v_pk_add_f32 v[100:101], v[96:97], v[100:101] neg_lo:[0,1] neg_hi:[0,1]
	v_pk_add_f32 v[98:99], v[78:79], v[90:91]
	v_pk_add_f32 v[78:79], v[78:79], v[90:91] neg_lo:[0,1] neg_hi:[0,1]
	v_pk_fma_f32 v[82:83], v[32:33], v[82:83], v[92:93] op_sel_hi:[0,1,1]
	v_pk_mul_f32 v[92:93], v[38:39], v[74:75] op_sel:[0,1] op_sel_hi:[1,0]
	v_xor_b32_e32 v46, 0x80000000, v45
	v_mov_b32_e32 v47, v45
	v_pk_add_f32 v[90:91], v[68:69], v[80:81]
	v_pk_add_f32 v[68:69], v[68:69], v[80:81] neg_lo:[0,1] neg_hi:[0,1]
	v_pk_fma_f32 v[74:75], v[36:37], v[74:75], v[92:93] op_sel_hi:[0,1,1]
	v_pk_mul_f32 v[92:93], v[42:43], v[78:79] op_sel:[0,1] op_sel_hi:[1,0]
	v_xor_b32_e32 v50, 0x80000000, v49
	v_mov_b32_e32 v51, v49
	v_pk_mul_f32 v[56:57], v[12:13], v[48:49] op_sel:[0,1] op_sel_hi:[1,0]
	v_pk_add_f32 v[96:97], v[94:95], v[100:101] op_sel:[0,1] op_sel_hi:[1,0] neg_hi:[0,1]
	v_pk_add_f32 v[94:95], v[94:95], v[100:101] op_sel:[0,1] op_sel_hi:[1,0] neg_lo:[0,1]
	v_pk_fma_f32 v[78:79], v[40:41], v[78:79], v[92:93] op_sel_hi:[0,1,1]
	v_pk_mul_f32 v[92:93], v[46:47], v[68:69] op_sel:[0,1] op_sel_hi:[1,0]
	v_xor_b32_e32 v54, 0x80000000, v53
	v_mov_b32_e32 v55, v53
	v_pk_fma_f32 v[56:57], v[6:7], v[48:49], v[56:57] op_sel_hi:[0,1,1]
	v_pk_mul_f32 v[60:61], v[20:21], v[48:49] op_sel:[0,1] op_sel_hi:[1,0]
	v_pk_fma_f32 v[68:69], v[44:45], v[68:69], v[92:93] op_sel_hi:[0,1,1]
	v_pk_mul_f32 v[92:93], v[50:51], v[94:95] op_sel:[0,1] op_sel_hi:[1,0]
	v_xor_b32_e32 v58, 0x80000000, v57
	v_mov_b32_e32 v59, v57
	v_pk_fma_f32 v[60:61], v[8:9], v[48:49], v[60:61] op_sel_hi:[0,1,1]
	v_pk_add_f32 v[64:65], v[64:65], v[70:71] op_sel:[0,1] op_sel_hi:[1,0] neg_lo:[0,1]
	v_pk_mul_f32 v[70:71], v[2:3], v[86:87] op_sel:[0,1] op_sel_hi:[1,0]
	v_pk_fma_f32 v[92:93], v[48:49], v[94:95], v[92:93] op_sel_hi:[0,1,1]
	v_pk_mul_f32 v[94:95], v[54:55], v[72:73] op_sel:[0,1] op_sel_hi:[1,0]
	v_xor_b32_e32 v62, 0x80000000, v61
	v_mov_b32_e32 v63, v61
	v_pk_fma_f32 v[70:71], v[4:5], v[86:87], v[70:71] op_sel_hi:[0,1,1]
	v_pk_mul_f32 v[86:87], v[20:21], v[90:91] op_sel:[0,1] op_sel_hi:[1,0]
	v_pk_fma_f32 v[72:73], v[52:53], v[72:73], v[94:95] op_sel_hi:[0,1,1]
	v_pk_mul_f32 v[94:95], v[58:59], v[84:85] op_sel:[0,1] op_sel_hi:[1,0]
	v_add_u32_e32 v5, 0x2000, v5
	v_pk_mul_f32 v[80:81], v[12:13], v[98:99] op_sel:[0,1] op_sel_hi:[1,0]
	v_pk_fma_f32 v[86:87], v[8:9], v[90:91], v[86:87] op_sel_hi:[0,1,1]
	v_pk_mul_f32 v[90:91], v[14:15], v[96:97] op_sel:[0,1] op_sel_hi:[1,0]
	v_pk_fma_f32 v[84:85], v[56:57], v[84:85], v[94:95] op_sel_hi:[0,1,1]
	v_pk_mul_f32 v[94:95], v[62:63], v[64:65] op_sel:[0,1] op_sel_hi:[1,0]
	v_ashrrev_i32_e32 v5, 2, v5
	v_pk_fma_f32 v[80:81], v[6:7], v[98:99], v[80:81] op_sel_hi:[0,1,1]
	v_pk_fma_f32 v[90:91], v[10:11], v[96:97], v[90:91] op_sel_hi:[0,1,1]
	v_pk_fma_f32 v[64:65], v[60:61], v[64:65], v[94:95] op_sel_hi:[0,1,1]
	ds_write2_b64 v106, v[104:105], v[82:83] offset1:16
	ds_write2_b64 v106, v[90:91], v[92:93] offset0:33 offset1:49
	ds_write2_b64 v106, v[80:81], v[78:79] offset0:66 offset1:82
	ds_write2_b64 v106, v[76:77], v[84:85] offset0:99 offset1:115
	ds_write2_b64 v106, v[70:71], v[74:75] offset0:132 offset1:148
	ds_write2_b64 v106, v[88:89], v[72:73] offset0:165 offset1:181
	ds_write2_b64 v106, v[86:87], v[68:69] offset0:198 offset1:214
	ds_write2_b64 v106, v[66:67], v[64:65] offset0:231 offset1:247
	v_add3_u32 v18, v18, v5, s5
	ds_read2_b64 v[64:67], v18 offset1:16
	ds_read2_b64 v[68:71], v18 offset0:33 offset1:49
	ds_read2_b64 v[72:75], v18 offset0:66 offset1:82
	ds_read2_b64 v[76:79], v18 offset0:132 offset1:148
	ds_read2_b64 v[80:83], v18 offset0:99 offset1:115
	ds_read2_b64 v[84:87], v18 offset0:165 offset1:181
	ds_read2_b64 v[88:91], v18 offset0:198 offset1:214
	ds_read2_b64 v[92:95], v18 offset0:231 offset1:247
	s_waitcnt lgkmcnt(4)
	v_pk_add_f32 v[96:97], v[64:65], v[76:77]
	v_pk_add_f32 v[64:65], v[64:65], v[76:77] neg_lo:[0,1] neg_hi:[0,1]
	v_pk_add_f32 v[76:77], v[66:67], v[78:79]
	v_pk_add_f32 v[66:67], v[66:67], v[78:79] neg_lo:[0,1] neg_hi:[0,1]
	s_waitcnt lgkmcnt(1)
	v_pk_add_f32 v[98:99], v[74:75], v[90:91]
	v_pk_mul_f32 v[78:79], v[66:67], s[18:19]
	v_pk_add_f32 v[74:75], v[74:75], v[90:91] neg_lo:[0,1] neg_hi:[0,1]
	v_pk_fma_f32 v[66:67], v[66:67], s[16:17], v[78:79] op_sel:[0,0,1] op_sel_hi:[1,0,0]
	v_pk_add_f32 v[78:79], v[68:69], v[84:85]
	v_pk_add_f32 v[68:69], v[68:69], v[84:85] neg_lo:[0,1] neg_hi:[0,1]
	v_pk_mul_f32 v[90:91], v[74:75], s[40:41]
	v_pk_mul_f32 v[84:85], v[68:69], s[36:37]
	v_pk_fma_f32 v[74:75], v[74:75], s[68:69], v[90:91] op_sel:[0,0,1] op_sel_hi:[1,0,0] neg_lo:[1,0,0] neg_hi:[1,0,0]
	s_waitcnt lgkmcnt(0)
	v_pk_add_f32 v[90:91], v[80:81], v[92:93]
	v_pk_add_f32 v[80:81], v[80:81], v[92:93] neg_lo:[0,1] neg_hi:[0,1]
	v_pk_fma_f32 v[68:69], v[68:69], s[66:67], v[84:85] op_sel:[0,0,1] op_sel_hi:[1,0,0]
	v_pk_add_f32 v[84:85], v[70:71], v[86:87]
	v_pk_add_f32 v[70:71], v[70:71], v[86:87] neg_lo:[0,1] neg_hi:[0,1]
	v_pk_mul_f32 v[92:93], v[80:81], s[36:37]
	v_pk_mul_f32 v[86:87], v[70:71], s[40:41]
	v_pk_fma_f32 v[80:81], v[80:81], s[66:67], v[92:93] op_sel:[0,0,1] op_sel_hi:[1,0,0] neg_lo:[1,0,0] neg_hi:[1,0,0]
	v_pk_add_f32 v[92:93], v[82:83], v[94:95]
	v_pk_add_f32 v[82:83], v[82:83], v[94:95] neg_lo:[0,1] neg_hi:[0,1]
	v_pk_fma_f32 v[70:71], v[70:71], s[68:69], v[86:87] op_sel:[0,0,1] op_sel_hi:[1,0,0]
	v_pk_add_f32 v[86:87], v[72:73], v[88:89]
	v_pk_mul_f32 v[94:95], v[82:83], s[18:19]
	v_pk_add_f32 v[88:89], v[72:73], v[88:89] neg_lo:[0,1] neg_hi:[0,1]
	v_pk_fma_f32 v[82:83], v[82:83], s[16:17], v[94:95] op_sel:[0,0,1] op_sel_hi:[1,0,0] neg_lo:[1,0,0] neg_hi:[1,0,0]
	v_pk_add_f32 v[94:95], v[96:97], v[86:87]
	v_pk_add_f32 v[86:87], v[96:97], v[86:87] neg_lo:[0,1] neg_hi:[0,1]
	v_pk_add_f32 v[96:97], v[76:77], v[98:99]
	v_pk_add_f32 v[76:77], v[76:77], v[98:99] neg_lo:[0,1] neg_hi:[0,1]
	v_pk_mul_f32 v[98:99], v[76:77], s[36:37]
	v_pk_add_f32 v[100:101], v[84:85], v[92:93]
	v_pk_add_f32 v[84:85], v[84:85], v[92:93] neg_lo:[0,1] neg_hi:[0,1]
	v_pk_fma_f32 v[76:77], v[76:77], s[66:67], v[98:99] op_sel:[0,0,1] op_sel_hi:[1,0,0]
	v_pk_add_f32 v[98:99], v[78:79], v[90:91]
	v_pk_add_f32 v[90:91], v[78:79], v[90:91] neg_lo:[0,1] neg_hi:[0,1]
	v_pk_mul_f32 v[92:93], v[84:85], s[36:37]
	v_pk_add_f32 v[72:73], v[64:65], v[88:89] op_sel:[0,1] op_sel_hi:[1,0] neg_hi:[0,1]
	v_pk_add_f32 v[64:65], v[64:65], v[88:89] op_sel:[0,1] op_sel_hi:[1,0] neg_lo:[0,1]
	v_pk_add_f32 v[88:89], v[66:67], v[74:75]
	v_pk_add_f32 v[66:67], v[66:67], v[74:75] neg_lo:[0,1] neg_hi:[0,1]
	v_pk_fma_f32 v[84:85], v[84:85], s[66:67], v[92:93] op_sel:[0,0,1] op_sel_hi:[1,0,0] neg_lo:[1,0,0] neg_hi:[1,0,0]
	v_pk_mul_f32 v[74:75], v[66:67], s[36:37]
	v_pk_fma_f32 v[66:67], v[66:67], s[66:67], v[74:75] op_sel:[0,0,1] op_sel_hi:[1,0,0]
	v_pk_add_f32 v[74:75], v[68:69], v[80:81]
	v_pk_add_f32 v[92:93], v[70:71], v[82:83]
	v_pk_add_f32 v[70:71], v[70:71], v[82:83] neg_lo:[0,1] neg_hi:[0,1]
	v_pk_add_f32 v[78:79], v[86:87], v[90:91] op_sel:[0,1] op_sel_hi:[1,0] neg_hi:[0,1]
	v_pk_add_f32 v[86:87], v[86:87], v[90:91] op_sel:[0,1] op_sel_hi:[1,0] neg_lo:[0,1]
	v_pk_add_f32 v[90:91], v[76:77], v[84:85]
	v_pk_add_f32 v[84:85], v[76:77], v[84:85] neg_lo:[0,1] neg_hi:[0,1]
	v_pk_add_f32 v[80:81], v[68:69], v[80:81] neg_lo:[0,1] neg_hi:[0,1]
	v_pk_mul_f32 v[82:83], v[70:71], s[36:37]
	v_pk_add_f32 v[102:103], v[72:73], v[74:75]
	v_pk_add_f32 v[72:73], v[72:73], v[74:75] neg_lo:[0,1] neg_hi:[0,1]
	v_pk_add_f32 v[74:75], v[88:89], v[92:93]
	v_pk_fma_f32 v[70:71], v[70:71], s[66:67], v[82:83] op_sel:[0,0,1] op_sel_hi:[1,0,0] neg_lo:[1,0,0] neg_hi:[1,0,0]
	v_pk_add_f32 v[82:83], v[94:95], v[98:99]
	v_pk_add_f32 v[94:95], v[94:95], v[98:99] neg_lo:[0,1] neg_hi:[0,1]
	v_pk_add_f32 v[98:99], v[96:97], v[100:101]
	v_pk_add_f32 v[76:77], v[86:87], v[84:85] op_sel:[0,1] op_sel_hi:[1,0] neg_hi:[0,1]
	v_pk_add_f32 v[84:85], v[86:87], v[84:85] op_sel:[0,1] op_sel_hi:[1,0] neg_lo:[0,1]
	v_pk_add_f32 v[86:87], v[102:103], v[74:75]
	v_pk_add_f32 v[96:97], v[96:97], v[100:101] neg_lo:[0,1] neg_hi:[0,1]
	v_pk_add_f32 v[68:69], v[64:65], v[80:81] op_sel:[0,1] op_sel_hi:[1,0] neg_hi:[0,1]
	v_pk_add_f32 v[64:65], v[64:65], v[80:81] op_sel:[0,1] op_sel_hi:[1,0] neg_lo:[0,1]
	v_pk_add_f32 v[80:81], v[66:67], v[70:71]
	v_pk_add_f32 v[104:105], v[82:83], v[98:99]
	v_pk_add_f32 v[82:83], v[82:83], v[98:99] neg_lo:[0,1] neg_hi:[0,1]
	v_pk_add_f32 v[98:99], v[78:79], v[90:91]
	v_pk_mul_f32 v[2:3], v[2:3], v[86:87] op_sel:[0,1] op_sel_hi:[1,0]
	v_xor_b32_e32 v101, 0x80000000, v96
	v_pk_add_f32 v[88:89], v[88:89], v[92:93] neg_lo:[0,1] neg_hi:[0,1]
	v_mov_b32_e32 v100, v97
	v_pk_add_f32 v[78:79], v[78:79], v[90:91] neg_lo:[0,1] neg_hi:[0,1]
	v_pk_add_f32 v[90:91], v[68:69], v[80:81]
	v_pk_fma_f32 v[2:3], v[4:5], v[86:87], v[2:3] op_sel_hi:[0,1,1]
	v_pk_mul_f32 v[4:5], v[12:13], v[98:99] op_sel:[0,1] op_sel_hi:[1,0]
	v_xor_b32_e32 v93, 0x80000000, v88
	v_pk_add_f32 v[66:67], v[66:67], v[70:71] neg_lo:[0,1] neg_hi:[0,1]
	v_pk_add_f32 v[96:97], v[94:95], v[100:101]
	v_mov_b32_e32 v92, v89
	v_pk_fma_f32 v[4:5], v[6:7], v[98:99], v[4:5] op_sel_hi:[0,1,1]
	v_pk_mul_f32 v[6:7], v[20:21], v[90:91] op_sel:[0,1] op_sel_hi:[1,0]
	v_xor_b32_e32 v71, 0x80000000, v66
	v_pk_add_f32 v[88:89], v[72:73], v[92:93]
	v_mov_b32_e32 v70, v67
	v_pk_fma_f32 v[6:7], v[8:9], v[90:91], v[6:7] op_sel_hi:[0,1,1]
	v_pk_mul_f32 v[8:9], v[14:15], v[96:97] op_sel:[0,1] op_sel_hi:[1,0]
	v_pk_add_f32 v[66:67], v[64:65], v[70:71]
	v_pk_fma_f32 v[8:9], v[10:11], v[96:97], v[8:9] op_sel_hi:[0,1,1]
	v_pk_mul_f32 v[10:11], v[22:23], v[88:89] op_sel:[0,1] op_sel_hi:[1,0]
	v_pk_add_f32 v[94:95], v[94:95], v[100:101] neg_lo:[0,1] neg_hi:[0,1]
	v_pk_add_f32 v[74:75], v[102:103], v[74:75] neg_lo:[0,1] neg_hi:[0,1]
	v_pk_add_f32 v[72:73], v[72:73], v[92:93] neg_lo:[0,1] neg_hi:[0,1]
	v_pk_add_f32 v[68:69], v[68:69], v[80:81] neg_lo:[0,1] neg_hi:[0,1]
	v_pk_add_f32 v[64:65], v[64:65], v[70:71] neg_lo:[0,1] neg_hi:[0,1]
	v_pk_fma_f32 v[10:11], v[16:17], v[88:89], v[10:11] op_sel_hi:[0,1,1]
	v_pk_mul_f32 v[12:13], v[26:27], v[76:77] op_sel:[0,1] op_sel_hi:[1,0]
	v_pk_mul_f32 v[14:15], v[30:31], v[66:67] op_sel:[0,1] op_sel_hi:[1,0]
	v_pk_mul_f32 v[16:17], v[34:35], v[82:83] op_sel:[0,1] op_sel_hi:[1,0]
	v_pk_fma_f32 v[12:13], v[24:25], v[76:77], v[12:13] op_sel_hi:[0,1,1]
	v_pk_fma_f32 v[14:15], v[28:29], v[66:67], v[14:15] op_sel_hi:[0,1,1]
	v_pk_fma_f32 v[16:17], v[32:33], v[82:83], v[16:17] op_sel_hi:[0,1,1]
	v_pk_mul_f32 v[20:21], v[38:39], v[74:75] op_sel:[0,1] op_sel_hi:[1,0]
	v_pk_mul_f32 v[22:23], v[42:43], v[78:79] op_sel:[0,1] op_sel_hi:[1,0]
	v_pk_mul_f32 v[24:25], v[46:47], v[68:69] op_sel:[0,1] op_sel_hi:[1,0]
	v_pk_mul_f32 v[26:27], v[50:51], v[94:95] op_sel:[0,1] op_sel_hi:[1,0]
	v_pk_mul_f32 v[28:29], v[54:55], v[72:73] op_sel:[0,1] op_sel_hi:[1,0]
	v_pk_mul_f32 v[30:31], v[58:59], v[84:85] op_sel:[0,1] op_sel_hi:[1,0]
	v_pk_mul_f32 v[32:33], v[62:63], v[64:65] op_sel:[0,1] op_sel_hi:[1,0]
	v_pk_fma_f32 v[20:21], v[36:37], v[74:75], v[20:21] op_sel_hi:[0,1,1]
	v_pk_fma_f32 v[22:23], v[40:41], v[78:79], v[22:23] op_sel_hi:[0,1,1]
	v_pk_fma_f32 v[24:25], v[44:45], v[68:69], v[24:25] op_sel_hi:[0,1,1]
	v_pk_fma_f32 v[26:27], v[48:49], v[94:95], v[26:27] op_sel_hi:[0,1,1]
	v_pk_fma_f32 v[28:29], v[52:53], v[72:73], v[28:29] op_sel_hi:[0,1,1]
	v_pk_fma_f32 v[30:31], v[56:57], v[84:85], v[30:31] op_sel_hi:[0,1,1]
	v_pk_fma_f32 v[32:33], v[60:61], v[64:65], v[32:33] op_sel_hi:[0,1,1]
	ds_write2_b64 v18, v[104:105], v[16:17] offset1:16
	ds_write2_b64 v18, v[8:9], v[26:27] offset0:33 offset1:49
	ds_write2_b64 v18, v[4:5], v[22:23] offset0:66 offset1:82
	ds_write2_b64 v18, v[12:13], v[30:31] offset0:99 offset1:115
	ds_write2_b64 v18, v[2:3], v[20:21] offset0:132 offset1:148
	ds_write2_b64 v18, v[10:11], v[28:29] offset0:165 offset1:181
	ds_write2_b64 v18, v[6:7], v[24:25] offset0:198 offset1:214
	ds_write2_b64 v18, v[14:15], v[32:33] offset0:231 offset1:247
	v_ashrrev_i32_e32 v2, 31, v210
	v_add_u32_sdwa v2, v210, v2 dst_sel:DWORD dst_unused:UNUSED_PAD src0_sel:DWORD src1_sel:BYTE_3
	s_lshl_b64 s[0:1], s[64:65], 15
	v_and_b32_e32 v2, 0xffffff00, v2
	s_add_u32 s0, s29, s0
	v_sub_u32_e32 v2, v210, v2
	s_addc_u32 s1, s85, s1
	v_ashrrev_i32_e32 v3, 31, v2
	v_lshl_add_u64 v[14:15], v[2:3], 3, s[0:1]
	s_movk_i32 s0, 0x1000
	v_add_co_u32_e32 v16, vcc, s0, v14
	s_movk_i32 s0, 0x3000
	s_nop 0
	v_addc_co_u32_e32 v17, vcc, 0, v15, vcc
	v_add_co_u32_e32 v2, vcc, s92, v14
	s_waitcnt lgkmcnt(0)
	s_nop 0
	v_addc_co_u32_e32 v3, vcc, 0, v15, vcc
	v_add_co_u32_e32 v22, vcc, s0, v14
	s_movk_i32 s0, 0x5000
	s_nop 0
	v_addc_co_u32_e32 v23, vcc, 0, v15, vcc
	v_add_co_u32_e32 v8, vcc, s95, v14
	s_barrier
	s_nop 0
	v_addc_co_u32_e32 v9, vcc, 0, v15, vcc
	v_add_co_u32_e32 v26, vcc, s0, v14
	s_nop 1
	v_addc_co_u32_e32 v27, vcc, 0, v15, vcc
	v_add_co_u32_e32 v10, vcc, s96, v14
	global_load_dwordx2 v[12:13], v[2:3], off nt
	global_load_dwordx2 v[6:7], v[2:3], off offset:2048 nt
	global_load_dwordx2 v[4:5], v[8:9], off offset:-4096 nt
	global_load_dwordx2 v[122:123], v[8:9], off nt
	v_addc_co_u32_e32 v11, vcc, 0, v15, vcc
	v_add_co_u32_e32 v28, vcc, s97, v14
	global_load_dwordx2 v[46:47], v[8:9], off offset:2048 nt
	global_load_dwordx2 v[38:39], v[10:11], off offset:-4096 nt
	global_load_dwordx2 v[20:21], v[10:11], off nt
	s_nop 0
	global_load_dwordx2 v[10:11], v[10:11], off offset:2048 nt
	v_addc_co_u32_e32 v29, vcc, 0, v15, vcc
	global_load_dwordx2 v[24:25], v[2:3], off offset:-4096 nt
	s_nop 0
	global_load_dwordx2 v[26:27], v[26:27], off offset:2048 nt
	s_nop 0
	global_load_dwordx2 v[8:9], v[28:29], off nt
	global_load_dwordx2 v[2:3], v[28:29], off offset:2048 nt
	global_load_dwordx2 v[30:31], v[14:15], off offset:2048 nt
	s_nop 0
	global_load_dwordx2 v[28:29], v[16:17], off offset:2048 nt
	s_nop 0
	global_load_dwordx2 v[16:17], v[22:23], off offset:2048 nt
	global_load_dwordx2 v[32:33], v[14:15], off nt
	v_mov_b32_e32 v14, v210
	s_waitcnt vmcnt(15)
	v_cvt_f32_f16_sdwa v164, v12 dst_sel:DWORD dst_unused:UNUSED_PAD src0_sel:WORD_1
	v_ashrrev_i32_e32 v15, 31, v14
	v_add_u32_sdwa v15, v14, v15 dst_sel:DWORD dst_unused:UNUSED_PAD src0_sel:DWORD src1_sel:BYTE_3
	v_ashrrev_i32_e32 v15, 8, v15
	v_mul_i32_i24_e32 v18, 0x100, v15
	v_sub_u32_e32 v18, v14, v18
	v_lshlrev_b32_e32 v14, 13, v15
	v_lshlrev_b32_e32 v15, 1, v18
	v_bfrev_b32_e32 v15, v15
	v_lshrrev_b32_e32 v15, 23, v15
	v_sub_u32_e32 v15, 0x200, v15
	v_bfrev_b32_e32 v15, v15
	v_lshrrev_b32_e32 v15, 19, v15
	v_and_b32_e32 v15, 0x1ff0, v15
	v_cmp_eq_u32_e64 s[0:1], 0, v18
	v_lshl_add_u32 v22, v18, 5, v14
	v_lshl_add_u32 v23, v22, 3, 0
	v_cndmask_b32_e64 v15, v15, 16, s[0:1]
	v_or_b32_e32 v14, v15, v14
	v_ashrrev_i32_e32 v22, 2, v22
	v_ashrrev_i32_e32 v15, 5, v14
	v_add_u32_e32 v211, v23, v22
	v_lshlrev_b32_e32 v14, 3, v14
	v_lshlrev_b32_e32 v15, 3, v15
	v_add3_u32 v212, 0, v14, v15
	ds_read2_b64 v[34:37], v211 offset1:1
	ds_read2_b64 v[40:43], v211 offset0:2 offset1:3
	ds_read2_b64 v[48:51], v212 offset1:1
	ds_read2_b64 v[52:55], v212 offset0:2 offset1:3
	ds_read2_b64 v[56:59], v211 offset0:4 offset1:5
	ds_read2_b64 v[60:63], v211 offset0:6 offset1:7
	ds_read2_b64 v[68:71], v212 offset0:4 offset1:5
	ds_read2_b64 v[72:75], v212 offset0:6 offset1:7
	ds_read2_b64 v[64:67], v211 offset0:8 offset1:9
	ds_read2_b64 v[76:79], v211 offset0:10 offset1:11
	ds_read2_b64 v[80:83], v212 offset0:8 offset1:9
	ds_read2_b64 v[98:101], v212 offset0:10 offset1:11
	ds_read2_b64 v[84:87], v211 offset0:12 offset1:13
	ds_read2_b64 v[88:91], v211 offset0:14 offset1:15
	ds_read2_b64 v[102:105], v212 offset0:12 offset1:13
	ds_read2_b64 v[106:109], v212 offset0:14 offset1:15
	s_waitcnt lgkmcnt(7)
	v_pk_add_f32 v[14:15], v[34:35], v[64:65]
	v_pk_add_f32 v[22:23], v[34:35], v[64:65] neg_lo:[0,1] neg_hi:[0,1]
	v_pk_add_f32 v[34:35], v[36:37], v[66:67]
	v_pk_add_f32 v[36:37], v[36:37], v[66:67] neg_lo:[0,1] neg_hi:[0,1]
	v_cmp_ne_u32_e32 vcc, 0, v18
	v_pk_mul_f32 v[44:45], v[36:37], s[18:19]
	v_bfrev_b32_e32 v18, v18
	v_pk_fma_f32 v[36:37], v[36:37], s[16:17], v[44:45] op_sel:[0,0,1] op_sel_hi:[1,0,0]
	s_waitcnt lgkmcnt(6)
	v_pk_add_f32 v[44:45], v[40:41], v[76:77]
	v_pk_add_f32 v[40:41], v[40:41], v[76:77] neg_lo:[0,1] neg_hi:[0,1]
	v_cvt_f32_ubyte3_e32 v18, v18
	v_pk_mul_f32 v[64:65], v[40:41], s[36:37]
	v_mul_f32_e32 v18, 0x38800000, v18
	v_pk_fma_f32 v[40:41], v[40:41], s[66:67], v[64:65] op_sel:[0,0,1] op_sel_hi:[1,0,0]
	v_pk_add_f32 v[64:65], v[42:43], v[78:79]
	v_pk_add_f32 v[42:43], v[42:43], v[78:79] neg_lo:[0,1] neg_hi:[0,1]
	s_waitcnt lgkmcnt(3)
	v_pk_add_f32 v[78:79], v[58:59], v[86:87]
	v_pk_mul_f32 v[66:67], v[42:43], s[40:41]
	v_pk_add_f32 v[58:59], v[58:59], v[86:87] neg_lo:[0,1] neg_hi:[0,1]
	v_pk_fma_f32 v[42:43], v[42:43], s[68:69], v[66:67] op_sel:[0,0,1] op_sel_hi:[1,0,0]
	v_pk_add_f32 v[66:67], v[56:57], v[84:85]
	v_pk_add_f32 v[76:77], v[56:57], v[84:85] neg_lo:[0,1] neg_hi:[0,1]
	v_pk_mul_f32 v[84:85], v[58:59], s[40:41]
	v_pk_fma_f32 v[58:59], v[58:59], s[68:69], v[84:85] op_sel:[0,0,1] op_sel_hi:[1,0,0] neg_lo:[1,0,0] neg_hi:[1,0,0]
	s_waitcnt lgkmcnt(2)
	v_pk_add_f32 v[84:85], v[60:61], v[88:89]
	v_pk_add_f32 v[60:61], v[60:61], v[88:89] neg_lo:[0,1] neg_hi:[0,1]
	v_pk_mul_f32 v[86:87], v[60:61], s[36:37]
	v_pk_add_f32 v[56:57], v[22:23], v[76:77] op_sel:[0,1] op_sel_hi:[1,0] neg_hi:[0,1]
	v_pk_fma_f32 v[60:61], v[60:61], s[66:67], v[86:87] op_sel:[0,0,1] op_sel_hi:[1,0,0] neg_lo:[1,0,0] neg_hi:[1,0,0]
	v_pk_add_f32 v[86:87], v[62:63], v[90:91]
	v_pk_add_f32 v[62:63], v[62:63], v[90:91] neg_lo:[0,1] neg_hi:[0,1]
	v_pk_add_f32 v[90:91], v[64:65], v[86:87]
	v_pk_mul_f32 v[88:89], v[62:63], s[18:19]
	v_pk_add_f32 v[64:65], v[64:65], v[86:87] neg_lo:[0,1] neg_hi:[0,1]
	v_pk_fma_f32 v[62:63], v[62:63], s[16:17], v[88:89] op_sel:[0,0,1] op_sel_hi:[1,0,0] neg_lo:[1,0,0] neg_hi:[1,0,0]
	v_pk_add_f32 v[88:89], v[14:15], v[66:67]
	v_pk_add_f32 v[14:15], v[14:15], v[66:67] neg_lo:[0,1] neg_hi:[0,1]
	v_pk_add_f32 v[66:67], v[34:35], v[78:79]
	v_pk_add_f32 v[34:35], v[34:35], v[78:79] neg_lo:[0,1] neg_hi:[0,1]
	v_pk_add_f32 v[22:23], v[22:23], v[76:77] op_sel:[0,1] op_sel_hi:[1,0] neg_lo:[0,1]
	v_pk_mul_f32 v[78:79], v[34:35], s[36:37]
	v_pk_add_f32 v[76:77], v[36:37], v[58:59]
	v_pk_add_f32 v[36:37], v[36:37], v[58:59] neg_lo:[0,1] neg_hi:[0,1]
	v_pk_fma_f32 v[34:35], v[34:35], s[66:67], v[78:79] op_sel:[0,0,1] op_sel_hi:[1,0,0]
	v_pk_add_f32 v[78:79], v[44:45], v[84:85]
	v_pk_add_f32 v[84:85], v[44:45], v[84:85] neg_lo:[0,1] neg_hi:[0,1]
	v_pk_mul_f32 v[86:87], v[64:65], s[36:37]
	v_pk_mul_f32 v[58:59], v[36:37], s[36:37]
	v_pk_fma_f32 v[64:65], v[64:65], s[66:67], v[86:87] op_sel:[0,0,1] op_sel_hi:[1,0,0] neg_lo:[1,0,0] neg_hi:[1,0,0]
	v_pk_fma_f32 v[36:37], v[36:37], s[66:67], v[58:59] op_sel:[0,0,1] op_sel_hi:[1,0,0]
	v_pk_add_f32 v[58:59], v[40:41], v[60:61]
	v_pk_add_f32 v[86:87], v[42:43], v[62:63]
	v_pk_add_f32 v[42:43], v[42:43], v[62:63] neg_lo:[0,1] neg_hi:[0,1]
	v_pk_mul_f32 v[62:63], v[42:43], s[36:37]
	v_pk_add_f32 v[44:45], v[14:15], v[84:85] op_sel:[0,1] op_sel_hi:[1,0] neg_hi:[0,1]
	v_pk_add_f32 v[14:15], v[14:15], v[84:85] op_sel:[0,1] op_sel_hi:[1,0] neg_lo:[0,1]
	v_pk_add_f32 v[84:85], v[34:35], v[64:65]
	v_pk_add_f32 v[64:65], v[34:35], v[64:65] neg_lo:[0,1] neg_hi:[0,1]
	v_pk_add_f32 v[94:95], v[56:57], v[58:59]
	v_pk_add_f32 v[56:57], v[56:57], v[58:59] neg_lo:[0,1] neg_hi:[0,1]
	v_pk_add_f32 v[58:59], v[76:77], v[86:87]
	v_pk_fma_f32 v[42:43], v[42:43], s[66:67], v[62:63] op_sel:[0,0,1] op_sel_hi:[1,0,0] neg_lo:[1,0,0] neg_hi:[1,0,0]
	v_pk_add_f32 v[62:63], v[88:89], v[78:79]
	v_pk_add_f32 v[78:79], v[88:89], v[78:79] neg_lo:[0,1] neg_hi:[0,1]
	v_pk_add_f32 v[88:89], v[66:67], v[90:91]
	v_pk_add_f32 v[110:111], v[76:77], v[86:87] neg_lo:[0,1] neg_hi:[0,1]
	v_pk_add_f32 v[86:87], v[94:95], v[58:59]
	v_pk_add_f32 v[34:35], v[94:95], v[58:59] neg_lo:[0,1] neg_hi:[0,1]
	v_pk_add_f32 v[58:59], v[50:51], v[82:83]
	v_pk_add_f32 v[50:51], v[50:51], v[82:83] neg_lo:[0,1] neg_hi:[0,1]
	v_pk_add_f32 v[60:61], v[40:41], v[60:61] neg_lo:[0,1] neg_hi:[0,1]
	v_pk_add_f32 v[148:149], v[62:63], v[88:89]
	v_pk_add_f32 v[138:139], v[62:63], v[88:89] neg_lo:[0,1] neg_hi:[0,1]
	v_pk_mul_f32 v[62:63], v[50:51], s[18:19]
	v_pk_add_f32 v[90:91], v[66:67], v[90:91] neg_lo:[0,1] neg_hi:[0,1]
	v_pk_fma_f32 v[50:51], v[50:51], s[16:17], v[62:63] op_sel:[0,0,1] op_sel_hi:[1,0,0]
	v_pk_add_f32 v[62:63], v[52:53], v[98:99]
	v_pk_add_f32 v[52:53], v[52:53], v[98:99] neg_lo:[0,1] neg_hi:[0,1]
	v_pk_add_f32 v[112:113], v[22:23], v[60:61] op_sel:[0,1] op_sel_hi:[1,0] neg_hi:[0,1]
	v_pk_add_f32 v[114:115], v[22:23], v[60:61] op_sel:[0,1] op_sel_hi:[1,0] neg_lo:[0,1]
	v_pk_add_f32 v[96:97], v[44:45], v[84:85]
	v_pk_add_f32 v[66:67], v[44:45], v[84:85] neg_lo:[0,1] neg_hi:[0,1]
	v_pk_add_f32 v[60:61], v[14:15], v[64:65] op_sel:[0,1] op_sel_hi:[1,0] neg_hi:[0,1]
	v_pk_add_f32 v[84:85], v[14:15], v[64:65] op_sel:[0,1] op_sel_hi:[1,0] neg_lo:[0,1]
	v_pk_mul_f32 v[64:65], v[52:53], s[36:37]
	v_pk_fma_f32 v[52:53], v[52:53], s[66:67], v[64:65] op_sel:[0,0,1] op_sel_hi:[1,0,0]
	v_pk_add_f32 v[64:65], v[54:55], v[100:101]
	v_pk_add_f32 v[54:55], v[54:55], v[100:101] neg_lo:[0,1] neg_hi:[0,1]
	v_pk_mul_f32 v[76:77], v[54:55], s[40:41]
	v_pk_add_f32 v[92:93], v[78:79], v[90:91] op_sel:[0,1] op_sel_hi:[1,0] neg_hi:[0,1]
	v_pk_fma_f32 v[54:55], v[54:55], s[68:69], v[76:77] op_sel:[0,0,1] op_sel_hi:[1,0,0]
	s_waitcnt lgkmcnt(1)
	v_pk_add_f32 v[76:77], v[68:69], v[102:103]
	v_pk_add_f32 v[68:69], v[68:69], v[102:103] neg_lo:[0,1] neg_hi:[0,1]
	v_pk_add_f32 v[88:89], v[78:79], v[90:91] op_sel:[0,1] op_sel_hi:[1,0] neg_lo:[0,1]
	v_xor_b32_e32 v79, 0x80000000, v68
	v_mov_b32_e32 v78, v69
	v_pk_add_f32 v[68:69], v[70:71], v[104:105]
	v_pk_add_f32 v[70:71], v[70:71], v[104:105] neg_lo:[0,1] neg_hi:[0,1]
	v_pk_add_f32 v[40:41], v[56:57], v[110:111] op_sel:[0,1] op_sel_hi:[1,0] neg_hi:[0,1]
	v_pk_add_f32 v[44:45], v[56:57], v[110:111] op_sel:[0,1] op_sel_hi:[1,0] neg_lo:[0,1]
	v_pk_add_f32 v[56:57], v[48:49], v[80:81]
	v_pk_add_f32 v[48:49], v[48:49], v[80:81] neg_lo:[0,1] neg_hi:[0,1]
	v_pk_mul_f32 v[80:81], v[70:71], s[40:41]
	v_cndmask_b32_e64 v18, v18, v208, s[0:1]
	v_pk_fma_f32 v[70:71], v[70:71], s[68:69], v[80:81] op_sel:[0,0,1] op_sel_hi:[1,0,0] neg_lo:[1,0,0] neg_hi:[1,0,0]
	s_waitcnt lgkmcnt(0)
	v_pk_add_f32 v[80:81], v[72:73], v[106:107]
	v_pk_add_f32 v[72:73], v[72:73], v[106:107] neg_lo:[0,1] neg_hi:[0,1]
	v_pk_add_f32 v[22:23], v[36:37], v[42:43]
	v_pk_mul_f32 v[82:83], v[72:73], s[36:37]
	v_pk_add_f32 v[116:117], v[36:37], v[42:43] neg_lo:[0,1] neg_hi:[0,1]
	v_pk_fma_f32 v[72:73], v[72:73], s[66:67], v[82:83] op_sel:[0,0,1] op_sel_hi:[1,0,0] neg_lo:[1,0,0] neg_hi:[1,0,0]
	v_pk_add_f32 v[82:83], v[74:75], v[108:109]
	v_pk_add_f32 v[74:75], v[74:75], v[108:109] neg_lo:[0,1] neg_hi:[0,1]
	v_pk_mul_f32 v[90:91], v[74:75], s[18:19]
	v_pk_fma_f32 v[74:75], v[74:75], s[16:17], v[90:91] op_sel:[0,0,1] op_sel_hi:[1,0,0] neg_lo:[1,0,0] neg_hi:[1,0,0]
	v_pk_add_f32 v[90:91], v[56:57], v[76:77]
	v_pk_add_f32 v[56:57], v[56:57], v[76:77] neg_lo:[0,1] neg_hi:[0,1]
	v_pk_add_f32 v[76:77], v[58:59], v[68:69]
	v_pk_add_f32 v[58:59], v[58:59], v[68:69] neg_lo:[0,1] neg_hi:[0,1]
	v_pk_add_f32 v[14:15], v[114:115], v[116:117] op_sel:[0,1] op_sel_hi:[1,0] neg_hi:[0,1]
	v_pk_mul_f32 v[68:69], v[58:59], s[36:37]
	v_pk_add_f32 v[36:37], v[114:115], v[116:117] op_sel:[0,1] op_sel_hi:[1,0] neg_lo:[0,1]
	v_pk_fma_f32 v[58:59], v[58:59], s[66:67], v[68:69] op_sel:[0,0,1] op_sel_hi:[1,0,0]
	v_pk_add_f32 v[68:69], v[62:63], v[80:81]
	v_pk_add_f32 v[80:81], v[62:63], v[80:81] neg_lo:[0,1] neg_hi:[0,1]
	s_waitcnt vmcnt(0)
	v_cvt_f32_f16_e32 v193, v33
	s_nop 0
	s_nop 0
	v_pk_add_f32 v[62:63], v[64:65], v[82:83]
	v_pk_add_f32 v[64:65], v[64:65], v[82:83] neg_lo:[0,1] neg_hi:[0,1]
	v_cvt_f32_f16_sdwa v192, v32 dst_sel:DWORD dst_unused:UNUSED_PAD src0_sel:WORD_1
	v_pk_mul_f32 v[82:83], v[64:65], s[36:37]
	v_cvt_f32_f16_e32 v194, v32
	v_pk_fma_f32 v[64:65], v[64:65], s[66:67], v[82:83] op_sel:[0,0,1] op_sel_hi:[1,0,0] neg_lo:[1,0,0] neg_hi:[1,0,0]
	v_pk_add_f32 v[82:83], v[48:49], v[78:79]
	v_pk_add_f32 v[48:49], v[48:49], v[78:79] neg_lo:[0,1] neg_hi:[0,1]
	v_pk_add_f32 v[78:79], v[50:51], v[70:71]
	v_pk_add_f32 v[50:51], v[50:51], v[70:71] neg_lo:[0,1] neg_hi:[0,1]
	v_cvt_f32_f16_sdwa v195, v33 dst_sel:DWORD dst_unused:UNUSED_PAD src0_sel:WORD_1
	v_pk_mul_f32 v[70:71], v[50:51], s[36:37]
	v_cvt_f32_f16_sdwa v170, v30 dst_sel:DWORD dst_unused:UNUSED_PAD src0_sel:WORD_1
	v_pk_fma_f32 v[50:51], v[50:51], s[66:67], v[70:71] op_sel:[0,0,1] op_sel_hi:[1,0,0]
	v_pk_add_f32 v[70:71], v[52:53], v[72:73]
	v_pk_add_f32 v[72:73], v[52:53], v[72:73] neg_lo:[0,1] neg_hi:[0,1]
	v_cvt_f32_f16_e32 v171, v31
	s_nop 0
	s_nop 0
	v_pk_add_f32 v[52:53], v[54:55], v[74:75]
	v_pk_add_f32 v[54:55], v[54:55], v[74:75] neg_lo:[0,1] neg_hi:[0,1]
	v_cvt_f32_f16_sdwa v185, v31 dst_sel:DWORD dst_unused:UNUSED_PAD src0_sel:WORD_1
	v_pk_mul_f32 v[74:75], v[54:55], s[36:37]
	v_cvt_f32_f16_e32 v184, v30
	v_pk_fma_f32 v[54:55], v[54:55], s[66:67], v[74:75] op_sel:[0,0,1] op_sel_hi:[1,0,0] neg_lo:[1,0,0] neg_hi:[1,0,0]
	v_pk_add_f32 v[74:75], v[90:91], v[68:69]
	v_pk_add_f32 v[68:69], v[90:91], v[68:69] neg_lo:[0,1] neg_hi:[0,1]
	v_pk_add_f32 v[90:91], v[76:77], v[62:63]
	v_pk_add_f32 v[62:63], v[76:77], v[62:63] neg_lo:[0,1] neg_hi:[0,1]
	v_cvt_f32_f16_sdwa v172, v24 dst_sel:DWORD dst_unused:UNUSED_PAD src0_sel:WORD_1
	v_xor_b32_e32 v77, 0x80000000, v62
	v_mov_b32_e32 v76, v63
	v_pk_add_f32 v[62:63], v[56:57], v[80:81] op_sel:[0,1] op_sel_hi:[1,0] neg_hi:[0,1]
	v_pk_add_f32 v[56:57], v[56:57], v[80:81] op_sel:[0,1] op_sel_hi:[1,0] neg_lo:[0,1]
	v_pk_add_f32 v[80:81], v[58:59], v[64:65]
	v_pk_add_f32 v[58:59], v[58:59], v[64:65] neg_lo:[0,1] neg_hi:[0,1]
	v_cvt_f32_f16_e32 v173, v25
	v_xor_b32_e32 v65, 0x80000000, v58
	v_mov_b32_e32 v64, v59
	v_pk_add_f32 v[58:59], v[82:83], v[70:71]
	v_pk_add_f32 v[70:71], v[82:83], v[70:71] neg_lo:[0,1] neg_hi:[0,1]
	v_pk_add_f32 v[82:83], v[78:79], v[52:53]
	v_pk_add_f32 v[52:53], v[78:79], v[52:53] neg_lo:[0,1] neg_hi:[0,1]
	v_pk_add_f32 v[118:119], v[58:59], v[82:83]
	v_pk_add_f32 v[134:135], v[58:59], v[82:83] neg_lo:[0,1] neg_hi:[0,1]
	v_cos_f32_e32 v83, v18
	v_sin_f32_e32 v82, v18
	v_cvt_f32_f16_sdwa v181, v25 dst_sel:DWORD dst_unused:UNUSED_PAD src0_sel:WORD_1
	v_cvt_f32_f16_e32 v180, v24
	v_cvt_f32_f16_sdwa v174, v28 dst_sel:DWORD dst_unused:UNUSED_PAD src0_sel:WORD_1
	v_cvt_f32_f16_e32 v175, v29
	v_cvt_f32_f16_sdwa v179, v29 dst_sel:DWORD dst_unused:UNUSED_PAD src0_sel:WORD_1
	v_cvt_f32_f16_e32 v178, v28
	v_cvt_f32_f16_e32 v165, v13
	v_cvt_f32_f16_sdwa v167, v13 dst_sel:DWORD dst_unused:UNUSED_PAD src0_sel:WORD_1
	v_cvt_f32_f16_e32 v166, v12
	v_cvt_f32_f16_e32 v154, v6
	v_cvt_f32_f16_e32 v155, v7
	v_cvt_f32_f16_sdwa v157, v7 dst_sel:DWORD dst_unused:UNUSED_PAD src0_sel:WORD_1
	v_cvt_f32_f16_sdwa v156, v6 dst_sel:DWORD dst_unused:UNUSED_PAD src0_sel:WORD_1
	v_cvt_f32_f16_sdwa v140, v4 dst_sel:DWORD dst_unused:UNUSED_PAD src0_sel:WORD_1
	v_cvt_f32_f16_e32 v141, v5
	v_cvt_f32_f16_sdwa v143, v5 dst_sel:DWORD dst_unused:UNUSED_PAD src0_sel:WORD_1
	v_cvt_f32_f16_e32 v142, v4
	v_cvt_f32_f16_e32 v124, v16
	v_cvt_f32_f16_e32 v125, v17
	v_cvt_f32_f16_sdwa v127, v17 dst_sel:DWORD dst_unused:UNUSED_PAD src0_sel:WORD_1
	v_cvt_f32_f16_sdwa v126, v16 dst_sel:DWORD dst_unused:UNUSED_PAD src0_sel:WORD_1
	v_cvt_f32_f16_sdwa v114, v122 dst_sel:DWORD dst_unused:UNUSED_PAD src0_sel:WORD_1
	v_cvt_f32_f16_e32 v115, v123
	v_cvt_f32_f16_sdwa v117, v123 dst_sel:DWORD dst_unused:UNUSED_PAD src0_sel:WORD_1
	v_cvt_f32_f16_e32 v116, v122
	v_xor_b32_e32 v79, 0x80000000, v52
	v_mov_b32_e32 v78, v53
	v_pk_add_f32 v[52:53], v[48:49], v[72:73] op_sel:[0,1] op_sel_hi:[1,0] neg_hi:[0,1]
	v_pk_add_f32 v[48:49], v[48:49], v[72:73] op_sel:[0,1] op_sel_hi:[1,0] neg_lo:[0,1]
	v_pk_add_f32 v[72:73], v[50:51], v[54:55]
	v_pk_add_f32 v[50:51], v[50:51], v[54:55] neg_lo:[0,1] neg_hi:[0,1]
	v_pk_fma_f32 v[160:161], v[82:83], 0, v[82:83] op_sel:[0,0,1] op_sel_hi:[1,0,0] neg_lo:[1,0,0] neg_hi:[1,0,0]
	v_xor_b32_e32 v55, 0x80000000, v50
	v_mov_b32_e32 v54, v51
	v_pk_fma_f32 v[198:199], v[82:83], 0, v[82:83] op_sel:[0,0,1] op_sel_hi:[1,0,0]
	v_pk_add_f32 v[42:43], v[112:113], v[22:23]
	v_pk_add_f32 v[22:23], v[112:113], v[22:23] neg_lo:[0,1] neg_hi:[0,1]
	v_pk_add_f32 v[98:99], v[74:75], v[90:91]
	v_pk_add_f32 v[100:101], v[74:75], v[90:91] neg_lo:[0,1] neg_hi:[0,1]
	v_pk_add_f32 v[102:103], v[68:69], v[76:77]
	v_pk_add_f32 v[106:107], v[68:69], v[76:77] neg_lo:[0,1] neg_hi:[0,1]
	v_pk_add_f32 v[104:105], v[62:63], v[80:81]
	v_pk_add_f32 v[108:109], v[62:63], v[80:81] neg_lo:[0,1] neg_hi:[0,1]
	v_pk_add_f32 v[110:111], v[56:57], v[64:65]
	v_pk_add_f32 v[112:113], v[56:57], v[64:65] neg_lo:[0,1] neg_hi:[0,1]
	v_pk_add_f32 v[152:153], v[70:71], v[78:79]
	v_pk_add_f32 v[162:163], v[70:71], v[78:79] neg_lo:[0,1] neg_hi:[0,1]
	v_pk_add_f32 v[176:177], v[52:53], v[72:73]
	v_pk_add_f32 v[182:183], v[52:53], v[72:73] neg_lo:[0,1] neg_hi:[0,1]
	v_pk_add_f32 v[188:189], v[48:49], v[54:55]
	v_pk_add_f32 v[196:197], v[48:49], v[54:55] neg_lo:[0,1] neg_hi:[0,1]
	v_pk_mul_f32 v[186:187], v[82:83], 0 op_sel_hi:[1,0]
	v_mov_b32_e32 v190, v160
	v_mov_b32_e32 v191, v199
	v_mul_f32_e32 v18, 0x3f3504f3, v83
	v_mul_f32_e32 v158, 0xbec3ef15, v83
	v_mul_f32_e32 v132, 0xbf6c835e, v83
	s_and_saveexec_b64 s[0:1], vcc
	s_xor_b64 s[0:1], exec, s[0:1]
	s_cbranch_execz .LBB0_536
	v_pk_add_f32 v[4:5], v[148:149], v[196:197]
	v_pk_add_f32 v[6:7], v[148:149], v[196:197] neg_lo:[0,1] neg_hi:[0,1]
	v_mul_f32_e32 v4, 0.5, v4
	v_mul_f32_e32 v12, 0.5, v7
	v_mov_b32_e32 v7, v5
	v_pk_mul_f32 v[6:7], v[6:7], s[44:45]
	v_pk_mov_b32 v[16:17], v[198:199], v[160:161] op_sel:[1,0]
	v_pk_mul_f32 v[24:25], v[190:191], v[6:7] op_sel:[0,1] op_sel_hi:[1,0]
	v_pk_mul_f32 v[6:7], v[190:191], v[6:7]
	v_pk_add_f32 v[24:25], v[24:25], v[24:25] op_sel:[0,1] op_sel_hi:[0,1]
	v_pk_add_f32 v[28:29], v[4:5], v[24:25]
	v_pk_add_f32 v[4:5], v[4:5], v[24:25] op_sel_hi:[0,1] neg_lo:[0,1] neg_hi:[0,1]
	v_mov_b32_e32 v29, v5
	v_pk_add_f32 v[4:5], v[6:7], v[6:7] op_sel:[0,1] op_sel_hi:[0,1] neg_lo:[0,1] neg_hi:[0,1]
	v_pk_add_f32 v[6:7], v[12:13], v[4:5]
	v_pk_add_f32 v[4:5], v[12:13], v[4:5] op_sel_hi:[0,1] neg_lo:[0,1] neg_hi:[0,1]
	v_mov_b32_e32 v7, v5
	v_pk_mul_f32 v[4:5], v[6:7], v[194:195]
	v_pk_mul_f32 v[6:7], v[6:7], v[192:193]
	v_pk_fma_f32 v[4:5], v[28:29], v[192:193], v[4:5]
	v_pk_fma_f32 v[6:7], v[28:29], v[194:195], v[6:7] neg_lo:[0,0,1] neg_hi:[0,0,1]
	s_mov_b32 s66, s19
	v_pk_add_f32 v[12:13], v[6:7], v[4:5] op_sel:[0,1] op_sel_hi:[1,0] neg_lo:[0,1] neg_hi:[0,1]
	v_pk_add_f32 v[28:29], v[6:7], v[4:5] op_sel:[0,1] op_sel_hi:[1,0]
	v_pk_add_f32 v[4:5], v[4:5], v[6:7] op_sel:[1,0] op_sel_hi:[0,1] neg_lo:[0,1] neg_hi:[0,1]
	v_mov_b32_e32 v13, v29
	v_pk_mul_f32 v[12:13], v[12:13], 0.5 op_sel_hi:[1,0]
	v_mov_b32_e32 v29, v5
	v_mul_f32_e32 v24, v190, v12
	v_pk_fma_f32 v[30:31], v[190:191], v[12:13], v[24:25] op_sel_hi:[1,1,0] neg_lo:[1,0,0] neg_hi:[1,0,0]
	v_mul_f32_e32 v24, v160, v13
	v_pk_fma_f32 v[12:13], v[16:17], v[12:13], v[24:25] op_sel_hi:[1,1,0]
	v_mov_b32_e32 v16, v83
	v_mov_b32_e32 v30, v12
	v_pk_fma_f32 v[4:5], v[28:29], 0.5, v[12:13] op_sel_hi:[1,0,1] neg_lo:[0,0,1] neg_hi:[0,0,1]
	v_pk_fma_f32 v[122:123], v[28:29], 0.5, v[30:31] op_sel_hi:[1,0,1]
	v_pk_fma_f32 v[6:7], v[28:29], 0.5, v[30:31] op_sel_hi:[1,0,1] neg_lo:[1,0,0] neg_hi:[1,0,0]
	v_mov_b32_e32 v5, v123
	v_pk_mul_f32 v[24:25], v[4:5], s[46:47] op_sel_hi:[1,0]
	v_pk_add_f32 v[4:5], v[138:139], v[188:189]
	v_pk_add_f32 v[12:13], v[138:139], v[188:189] neg_lo:[0,1] neg_hi:[0,1]
	v_mov_b32_e32 v17, v82
	v_mul_f32_e32 v6, 0.5, v13
	v_pk_add_f32 v[28:29], v[186:187], v[16:17] neg_lo:[0,1] neg_hi:[0,1]
	v_pk_add_f32 v[30:31], v[186:187], v[16:17]
	v_mov_b32_e32 v13, v5
	v_pk_mov_b32 v[32:33], v[28:29], v[30:31] op_sel:[1,0]
	v_pk_mul_f32 v[12:13], v[12:13], s[44:45]
	v_mul_f32_e32 v4, 0.5, v4
	v_pk_mul_f32 v[48:49], v[32:33], v[12:13] op_sel:[0,1] op_sel_hi:[1,0]
	v_pk_mul_f32 v[12:13], v[32:33], v[12:13]
	v_pk_add_f32 v[48:49], v[48:49], v[48:49] op_sel:[0,1] op_sel_hi:[0,1]
	v_pk_add_f32 v[50:51], v[4:5], v[48:49]
	v_pk_add_f32 v[4:5], v[4:5], v[48:49] op_sel_hi:[0,1] neg_lo:[0,1] neg_hi:[0,1]
	v_mov_b32_e32 v51, v5
	v_pk_add_f32 v[4:5], v[12:13], v[12:13] op_sel:[0,1] op_sel_hi:[0,1] neg_lo:[0,1] neg_hi:[0,1]
	v_pk_add_f32 v[12:13], v[6:7], v[4:5]
	v_pk_add_f32 v[4:5], v[6:7], v[4:5] op_sel_hi:[0,1] neg_lo:[0,1] neg_hi:[0,1]
	v_mov_b32_e32 v13, v5
	v_pk_mul_f32 v[4:5], v[12:13], v[184:185]
	v_pk_mul_f32 v[12:13], v[12:13], v[170:171]
	v_pk_fma_f32 v[4:5], v[50:51], v[170:171], v[4:5]
	v_pk_fma_f32 v[12:13], v[50:51], v[184:185], v[12:13] neg_lo:[0,0,1] neg_hi:[0,0,1]
	v_mov_b32_e32 v31, v29
	v_pk_add_f32 v[48:49], v[12:13], v[4:5] op_sel:[0,1] op_sel_hi:[1,0] neg_lo:[0,1] neg_hi:[0,1]
	v_pk_add_f32 v[50:51], v[12:13], v[4:5] op_sel:[0,1] op_sel_hi:[1,0]
	v_pk_add_f32 v[4:5], v[4:5], v[12:13] op_sel:[1,0] op_sel_hi:[0,1] neg_lo:[0,1] neg_hi:[0,1]
	v_mov_b32_e32 v49, v51
	v_pk_mul_f32 v[48:49], v[48:49], 0.5 op_sel_hi:[1,0]
	v_mov_b32_e32 v51, v5
	v_mul_f32_e32 v6, v29, v48
	v_pk_fma_f32 v[32:33], v[32:33], v[48:49], v[6:7] op_sel_hi:[1,1,0] neg_lo:[1,0,0] neg_hi:[1,0,0]
	v_mul_f32_e32 v6, v29, v49
	v_pk_fma_f32 v[28:29], v[30:31], v[48:49], v[6:7] op_sel_hi:[1,1,0]
	v_pk_mul_f32 v[12:13], v[16:17], s[36:37]
	v_mov_b32_e32 v32, v28
	v_pk_fma_f32 v[4:5], v[50:51], 0.5, v[28:29] op_sel_hi:[1,0,1] neg_lo:[0,0,1] neg_hi:[0,0,1]
	v_pk_fma_f32 v[138:139], v[50:51], 0.5, v[32:33] op_sel_hi:[1,0,1]
	v_pk_add_f32 v[16:17], v[92:93], v[182:183]
	v_mov_b32_e32 v5, v139
	v_pk_add_f32 v[28:29], v[92:93], v[182:183] neg_lo:[0,1] neg_hi:[0,1]
	v_pk_mul_f32 v[30:31], v[4:5], s[46:47] op_sel_hi:[1,0]
	v_pk_fma_f32 v[4:5], v[50:51], 0.5, v[32:33] op_sel_hi:[1,0,1] neg_lo:[1,0,0] neg_hi:[1,0,0]
	v_mul_f32_e32 v6, 0.5, v29
	v_pk_add_f32 v[32:33], v[18:19], v[12:13] op_sel:[0,1] op_sel_hi:[0,1] neg_lo:[0,1] neg_hi:[0,1]
	v_pk_add_f32 v[48:49], v[18:19], v[12:13] op_sel:[0,1] op_sel_hi:[0,1]
	v_mov_b32_e32 v29, v17
	v_mul_f32_e32 v4, 0.5, v16
	v_mov_b32_e32 v50, v32
	v_mov_b32_e32 v51, v49
	v_pk_mul_f32 v[16:17], v[28:29], s[44:45]
	v_pk_mov_b32 v[48:49], v[48:49], v[32:33] op_sel:[1,0]
	v_pk_mul_f32 v[28:29], v[50:51], v[16:17] op_sel:[0,1] op_sel_hi:[1,0]
	v_pk_mul_f32 v[16:17], v[50:51], v[16:17]
	v_pk_add_f32 v[28:29], v[28:29], v[28:29] op_sel:[0,1] op_sel_hi:[0,1]
	v_pk_add_f32 v[52:53], v[4:5], v[28:29]
	v_pk_add_f32 v[28:29], v[4:5], v[28:29] op_sel_hi:[0,1] neg_lo:[0,1] neg_hi:[0,1]
	v_pk_add_f32 v[16:17], v[16:17], v[16:17] op_sel:[0,1] op_sel_hi:[0,1] neg_lo:[0,1] neg_hi:[0,1]
	v_mov_b32_e32 v53, v29
	v_pk_add_f32 v[28:29], v[6:7], v[16:17]
	v_pk_add_f32 v[16:17], v[6:7], v[16:17] op_sel_hi:[0,1] neg_lo:[0,1] neg_hi:[0,1]
	v_mov_b32_e32 v29, v17
	v_pk_mul_f32 v[16:17], v[28:29], v[180:181]
	v_pk_mul_f32 v[28:29], v[28:29], v[172:173]
	v_pk_fma_f32 v[16:17], v[52:53], v[172:173], v[16:17]
	v_pk_fma_f32 v[28:29], v[52:53], v[180:181], v[28:29] neg_lo:[0,0,1] neg_hi:[0,0,1]
	v_sub_f32_e32 v6, v89, v177
	v_pk_add_f32 v[52:53], v[28:29], v[16:17] op_sel:[0,1] op_sel_hi:[1,0] neg_lo:[0,1] neg_hi:[0,1]
	v_pk_add_f32 v[54:55], v[28:29], v[16:17] op_sel:[0,1] op_sel_hi:[1,0]
	v_pk_add_f32 v[16:17], v[16:17], v[28:29] op_sel:[1,0] op_sel_hi:[0,1] neg_lo:[0,1] neg_hi:[0,1]
	v_mov_b32_e32 v53, v55
	v_pk_mul_f32 v[52:53], v[52:53], 0.5 op_sel_hi:[1,0]
	v_mov_b32_e32 v55, v17
	v_mul_f32_e32 v4, v32, v52
	v_pk_fma_f32 v[56:57], v[50:51], v[52:53], v[4:5] op_sel_hi:[1,1,0] neg_lo:[1,0,0] neg_hi:[1,0,0]
	v_mul_f32_e32 v4, v32, v53
	v_pk_fma_f32 v[48:49], v[48:49], v[52:53], v[4:5] op_sel_hi:[1,1,0]
	v_pk_add_f32 v[28:29], v[88:89], v[176:177]
	v_mov_b32_e32 v56, v48
	v_pk_fma_f32 v[16:17], v[54:55], 0.5, v[48:49] op_sel_hi:[1,0,1] neg_lo:[0,0,1] neg_hi:[0,0,1]
	v_mov_b32_e32 v48, v12
	v_mov_b32_e32 v49, v88
	v_pk_mov_b32 v[12:13], v[12:13], v[176:177] op_sel:[1,0]
	v_mul_f32_e32 v18, 0.5, v29
	v_pk_add_f32 v[12:13], v[48:49], v[12:13] neg_lo:[0,1] neg_hi:[0,1]
	v_mul_f32_e32 v4, 0.5, v28
	v_pk_mul_f32 v[48:49], v[12:13], v[18:19]
	v_mov_b32_e32 v13, v32
	v_pk_fma_f32 v[50:51], v[50:51], v[48:49], v[48:49] op_sel:[0,1,0] op_sel_hi:[1,0,1]
	v_mov_b32_e32 v48, v49
	v_mov_b32_e32 v49, v18
	v_pk_mul_f32 v[48:49], v[12:13], v[48:49]
	v_pk_add_f32 v[52:53], v[4:5], v[50:51]
	v_mul_f32_e32 v6, 0.5, v6
	v_fma_f32 v53, v28, 0.5, -v50
	v_pk_add_f32 v[28:29], v[48:49], v[48:49] op_sel:[0,1] op_sel_hi:[0,1] neg_lo:[0,1] neg_hi:[0,1]
	v_pk_add_f32 v[48:49], v[6:7], v[28:29]
	v_pk_add_f32 v[28:29], v[6:7], v[28:29] op_sel_hi:[0,1] neg_lo:[0,1] neg_hi:[0,1]
	v_mov_b32_e32 v49, v29
	v_pk_mul_f32 v[28:29], v[48:49], v[178:179]
	v_pk_mul_f32 v[48:49], v[48:49], v[174:175]
	v_pk_fma_f32 v[28:29], v[52:53], v[174:175], v[28:29]
	v_pk_fma_f32 v[48:49], v[52:53], v[178:179], v[48:49] neg_lo:[0,0,1] neg_hi:[0,0,1]
	v_pk_fma_f32 v[92:93], v[54:55], 0.5, v[56:57] op_sel_hi:[1,0,1]
	v_pk_add_f32 v[50:51], v[48:49], v[28:29] op_sel:[0,1] op_sel_hi:[1,0] neg_lo:[0,1] neg_hi:[0,1]
	v_pk_add_f32 v[52:53], v[48:49], v[28:29] op_sel:[0,1] op_sel_hi:[1,0]
	v_mov_b32_e32 v17, v93
	v_mov_b32_e32 v51, v53
	v_pk_mul_f32 v[50:51], v[50:51], 0.5 op_sel_hi:[1,0]
	v_pk_mul_f32 v[64:65], v[16:17], s[46:47] op_sel_hi:[1,0]
	v_mul_f32_e32 v4, v12, v50
	v_pk_fma_f32 v[16:17], v[54:55], 0.5, v[56:57] op_sel_hi:[1,0,1] neg_lo:[1,0,0] neg_hi:[1,0,0]
	v_pk_fma_f32 v[54:55], v[12:13], v[50:51], v[4:5] op_sel_hi:[1,1,0] neg_lo:[1,0,0] neg_hi:[1,0,0]
	v_mov_b32_e32 v33, v12
	v_mul_f32_e32 v4, v12, v51
	v_pk_fma_f32 v[12:13], v[32:33], v[50:51], v[4:5] op_sel_hi:[1,1,0]
	v_pk_add_f32 v[28:29], v[28:29], v[48:49] op_sel:[1,0] op_sel_hi:[0,1] neg_lo:[0,1] neg_hi:[0,1]
	v_mov_b32_e32 v53, v29
	v_mov_b32_e32 v54, v12
	v_pk_fma_f32 v[12:13], v[52:53], 0.5, v[12:13] op_sel_hi:[1,0,1] neg_lo:[0,0,1] neg_hi:[0,0,1]
	v_pk_fma_f32 v[88:89], v[52:53], 0.5, v[54:55] op_sel_hi:[1,0,1]
	s_mov_b32 s67, s16
	v_mov_b32_e32 v13, v89
	v_pk_mul_f32 v[68:69], v[12:13], s[46:47] op_sel_hi:[1,0]
	v_pk_fma_f32 v[12:13], v[52:53], 0.5, v[54:55] op_sel_hi:[1,0,1] neg_lo:[1,0,0] neg_hi:[1,0,0]
	v_mov_b32_e32 v4, v83
	s_mov_b32 s17, s19
	v_pk_mul_f32 v[48:49], v[82:83], s[66:67] op_sel_hi:[0,1]
	v_pk_add_f32 v[28:29], v[96:97], v[162:163]
	v_pk_add_f32 v[32:33], v[96:97], v[162:163] neg_lo:[0,1] neg_hi:[0,1]
	v_pk_fma_f32 v[52:53], v[4:5], s[16:17], v[48:49] op_sel_hi:[0,1,1] neg_lo:[0,0,1] neg_hi:[0,0,1]
	v_mul_f32_e32 v12, 0.5, v33
	v_pk_fma_f32 v[50:51], v[4:5], s[16:17], v[48:49] op_sel_hi:[0,1,1]
	v_mov_b32_e32 v33, v29
	v_mul_f32_e32 v6, 0.5, v28
	v_mov_b32_e32 v54, v52
	v_mov_b32_e32 v55, v51
	v_pk_mul_f32 v[28:29], v[32:33], s[44:45]
	v_pk_mov_b32 v[56:57], v[50:51], v[52:53] op_sel:[1,0]
	v_pk_mul_f32 v[32:33], v[54:55], v[28:29] op_sel:[0,1] op_sel_hi:[1,0]
	v_pk_mul_f32 v[28:29], v[54:55], v[28:29]
	v_pk_add_f32 v[32:33], v[32:33], v[32:33] op_sel:[0,1] op_sel_hi:[0,1]
	v_pk_add_f32 v[58:59], v[6:7], v[32:33]
	v_pk_add_f32 v[32:33], v[6:7], v[32:33] op_sel_hi:[0,1] neg_lo:[0,1] neg_hi:[0,1]
	v_pk_add_f32 v[28:29], v[28:29], v[28:29] op_sel:[0,1] op_sel_hi:[0,1] neg_lo:[0,1] neg_hi:[0,1]
	v_mov_b32_e32 v59, v33
	v_pk_add_f32 v[32:33], v[12:13], v[28:29]
	v_pk_add_f32 v[28:29], v[12:13], v[28:29] op_sel_hi:[0,1] neg_lo:[0,1] neg_hi:[0,1]
	v_mov_b32_e32 v33, v29
	v_pk_mul_f32 v[28:29], v[32:33], v[166:167]
	v_pk_mul_f32 v[32:33], v[32:33], v[164:165]
	v_pk_fma_f32 v[28:29], v[58:59], v[164:165], v[28:29]
	v_pk_fma_f32 v[32:33], v[58:59], v[166:167], v[32:33] neg_lo:[0,0,1] neg_hi:[0,0,1]
	v_mov_b32_e32 v159, v66
	v_pk_add_f32 v[58:59], v[32:33], v[28:29] op_sel:[0,1] op_sel_hi:[1,0] neg_lo:[0,1] neg_hi:[0,1]
	v_pk_add_f32 v[70:71], v[32:33], v[28:29] op_sel:[0,1] op_sel_hi:[1,0]
	v_pk_add_f32 v[28:29], v[28:29], v[32:33] op_sel:[1,0] op_sel_hi:[0,1] neg_lo:[0,1] neg_hi:[0,1]
	v_mov_b32_e32 v59, v71
	v_pk_mul_f32 v[58:59], v[58:59], 0.5 op_sel_hi:[1,0]
	v_mov_b32_e32 v71, v29
	v_mul_f32_e32 v6, v52, v58
	v_pk_fma_f32 v[72:73], v[54:55], v[58:59], v[6:7] op_sel_hi:[1,1,0] neg_lo:[1,0,0] neg_hi:[1,0,0]
	v_mul_f32_e32 v6, v52, v59
	v_pk_fma_f32 v[56:57], v[56:57], v[58:59], v[6:7] op_sel_hi:[1,1,0]
	v_sub_f32_e32 v12, v67, v153
	v_mov_b32_e32 v72, v56
	v_pk_fma_f32 v[28:29], v[70:71], 0.5, v[56:57] op_sel_hi:[1,0,1] neg_lo:[0,0,1] neg_hi:[0,0,1]
	v_pk_fma_f32 v[96:97], v[70:71], 0.5, v[72:73] op_sel_hi:[1,0,1]
	v_pk_mov_b32 v[56:57], v[48:49], v[152:153] op_sel:[1,0]
	v_mov_b32_e32 v29, v97
	v_pk_mul_f32 v[62:63], v[28:29], s[46:47] op_sel_hi:[1,0]
	v_pk_add_f32 v[28:29], v[66:67], v[152:153]
	v_pk_add_f32 v[56:57], v[158:159], v[56:57] neg_lo:[0,1] neg_hi:[0,1]
	v_mul_f32_e32 v18, 0.5, v29
	v_pk_mul_f32 v[58:59], v[56:57], v[18:19]
	v_mul_f32_e32 v6, 0.5, v28
	v_pk_fma_f32 v[54:55], v[54:55], v[58:59], v[58:59] op_sel:[0,1,0] op_sel_hi:[1,0,1]
	v_mov_b32_e32 v66, v56
	v_mov_b32_e32 v67, v52
	v_mov_b32_e32 v58, v59
	v_mov_b32_e32 v59, v18
	v_pk_mul_f32 v[58:59], v[66:67], v[58:59]
	v_pk_add_f32 v[66:67], v[6:7], v[54:55]
	v_mul_f32_e32 v12, 0.5, v12
	v_fma_f32 v67, v28, 0.5, -v54
	v_pk_add_f32 v[28:29], v[58:59], v[58:59] op_sel:[0,1] op_sel_hi:[0,1] neg_lo:[0,1] neg_hi:[0,1]
	v_pk_add_f32 v[54:55], v[12:13], v[28:29]
	v_pk_add_f32 v[28:29], v[12:13], v[28:29] op_sel_hi:[0,1] neg_lo:[0,1] neg_hi:[0,1]
	v_mov_b32_e32 v55, v29
	v_pk_mul_f32 v[28:29], v[54:55], v[156:157]
	v_pk_mul_f32 v[54:55], v[54:55], v[154:155]
	v_pk_fma_f32 v[32:33], v[70:71], 0.5, v[72:73] op_sel_hi:[1,0,1] neg_lo:[1,0,0] neg_hi:[1,0,0]
	v_pk_fma_f32 v[58:59], v[66:67], v[154:155], v[28:29] neg_lo:[0,0,1] neg_hi:[0,0,1]
	v_pk_fma_f32 v[28:29], v[66:67], v[154:155], v[28:29]
	v_pk_fma_f32 v[70:71], v[66:67], v[156:157], v[54:55]
	v_pk_fma_f32 v[54:55], v[66:67], v[156:157], v[54:55] neg_lo:[0,0,1] neg_hi:[0,0,1]
	v_pk_add_f32 v[72:73], v[58:59], v[28:29] op_sel:[0,1] op_sel_hi:[1,0]
	v_pk_add_f32 v[66:67], v[70:71], v[54:55] op_sel_hi:[0,1] neg_lo:[0,1] neg_hi:[0,1]
	v_pk_add_f32 v[28:29], v[58:59], v[28:29] op_sel_hi:[0,1] neg_lo:[0,1] neg_hi:[0,1]
	v_pk_add_f32 v[54:55], v[70:71], v[54:55] op_sel:[0,1] op_sel_hi:[1,0]
	v_mov_b32_e32 v73, v67
	v_mov_b32_e32 v55, v29
	v_pk_mul_f32 v[28:29], v[54:55], 0.5 op_sel_hi:[1,0]
	v_mov_b32_e32 v133, v84
	v_pk_mul_f32 v[54:55], v[52:53], v[28:29] op_sel:[0,1] op_sel_hi:[0,0]
	v_pk_fma_f32 v[58:59], v[56:57], v[28:29], v[54:55] op_sel_hi:[0,1,1]
	v_pk_fma_f32 v[28:29], v[56:57], v[28:29], v[54:55] op_sel_hi:[0,1,1] neg_lo:[0,0,1] neg_hi:[0,0,1]
	v_mov_b32_e32 v28, v58
	v_pk_fma_f32 v[54:55], v[72:73], 0.5, v[58:59] op_sel_hi:[1,0,1] neg_lo:[0,0,1] neg_hi:[0,0,1]
	v_pk_fma_f32 v[66:67], v[72:73], 0.5, v[28:29] op_sel_hi:[1,0,1]
	v_pk_add_f32 v[56:57], v[60:61], v[134:135] neg_lo:[0,1] neg_hi:[0,1]
	v_mov_b32_e32 v55, v67
	v_pk_mul_f32 v[90:91], v[54:55], s[46:47] op_sel_hi:[1,0]
	v_pk_add_f32 v[54:55], v[134:135], v[60:61]
	v_mul_f32_e32 v12, 0.5, v57
	v_mov_b32_e32 v57, v55
	v_mul_f32_e32 v6, 0.5, v54
	v_pk_mov_b32 v[58:59], v[52:53], v[50:51] op_sel:[1,0]
	v_pk_mul_f32 v[54:55], v[56:57], s[44:45]
	v_pk_fma_f32 v[28:29], v[72:73], 0.5, v[28:29] op_sel_hi:[1,0,1] neg_lo:[1,0,0] neg_hi:[1,0,0]
	v_pk_mul_f32 v[56:57], v[58:59], v[54:55] op_sel:[0,1] op_sel_hi:[1,0]
	v_pk_mul_f32 v[54:55], v[58:59], v[54:55]
	v_pk_add_f32 v[56:57], v[56:57], v[56:57] op_sel:[0,1] op_sel_hi:[0,1]
	v_pk_add_f32 v[60:61], v[6:7], v[56:57]
	v_pk_add_f32 v[56:57], v[6:7], v[56:57] op_sel_hi:[0,1] neg_lo:[0,1] neg_hi:[0,1]
	v_pk_add_f32 v[54:55], v[54:55], v[54:55] op_sel:[0,1] op_sel_hi:[0,1] neg_lo:[0,1] neg_hi:[0,1]
	v_mov_b32_e32 v61, v57
	v_pk_add_f32 v[56:57], v[12:13], v[54:55]
	v_pk_add_f32 v[54:55], v[12:13], v[54:55] op_sel_hi:[0,1] neg_lo:[0,1] neg_hi:[0,1]
	v_mov_b32_e32 v57, v55
	v_pk_mul_f32 v[54:55], v[56:57], v[142:143]
	v_pk_mul_f32 v[56:57], v[56:57], v[140:141]
	v_pk_fma_f32 v[54:55], v[60:61], v[140:141], v[54:55]
	v_pk_fma_f32 v[56:57], v[60:61], v[142:143], v[56:57] neg_lo:[0,0,1] neg_hi:[0,0,1]
	v_mov_b32_e32 v51, v53
	v_pk_add_f32 v[60:61], v[56:57], v[54:55] op_sel:[0,1] op_sel_hi:[1,0] neg_lo:[0,1] neg_hi:[0,1]
	v_pk_add_f32 v[70:71], v[56:57], v[54:55] op_sel:[0,1] op_sel_hi:[1,0]
	v_pk_add_f32 v[54:55], v[54:55], v[56:57] op_sel:[1,0] op_sel_hi:[0,1] neg_lo:[0,1] neg_hi:[0,1]
	v_mov_b32_e32 v61, v71
	v_pk_mul_f32 v[60:61], v[60:61], 0.5 op_sel_hi:[1,0]
	v_mov_b32_e32 v71, v55
	v_mul_f32_e32 v6, v53, v60
	v_pk_fma_f32 v[72:73], v[58:59], v[60:61], v[6:7] op_sel_hi:[1,1,0] neg_lo:[1,0,0] neg_hi:[1,0,0]
	v_mul_f32_e32 v6, v53, v61
	v_pk_fma_f32 v[50:51], v[50:51], v[60:61], v[6:7] op_sel_hi:[1,1,0]
	v_pk_add_f32 v[54:55], v[118:119], v[84:85]
	v_mov_b32_e32 v72, v50
	v_mov_b32_e32 v49, v118
	v_pk_fma_f32 v[50:51], v[70:71], 0.5, v[50:51] op_sel_hi:[1,0,1] neg_lo:[0,0,1] neg_hi:[0,0,1]
	v_pk_fma_f32 v[60:61], v[70:71], 0.5, v[72:73] op_sel_hi:[1,0,1]
	v_mul_f32_e32 v18, 0.5, v55
	v_pk_add_f32 v[48:49], v[132:133], v[48:49] neg_lo:[0,1] neg_hi:[0,1]
	v_mov_b32_e32 v51, v61
	v_pk_mul_f32 v[56:57], v[48:49], v[18:19]
	v_pk_mul_f32 v[94:95], v[50:51], s[46:47] op_sel_hi:[1,0]
	v_pk_fma_f32 v[50:51], v[70:71], 0.5, v[72:73] op_sel_hi:[1,0,1] neg_lo:[1,0,0] neg_hi:[1,0,0]
	v_mul_f32_e32 v6, 0.5, v54
	v_pk_fma_f32 v[58:59], v[58:59], v[56:57], v[56:57] op_sel:[0,1,0] op_sel_hi:[1,0,1]
	v_mov_b32_e32 v70, v48
	v_mov_b32_e32 v71, v53
	v_mov_b32_e32 v56, v57
	v_mov_b32_e32 v57, v18
	v_sub_f32_e32 v12, v85, v119
	v_pk_mul_f32 v[56:57], v[70:71], v[56:57]
	v_pk_add_f32 v[70:71], v[6:7], v[58:59]
	v_mul_f32_e32 v12, 0.5, v12
	v_fma_f32 v71, v54, 0.5, -v58
	v_pk_add_f32 v[54:55], v[56:57], v[56:57] op_sel:[0,1] op_sel_hi:[0,1] neg_lo:[0,1] neg_hi:[0,1]
	v_pk_add_f32 v[56:57], v[12:13], v[54:55]
	v_pk_add_f32 v[54:55], v[12:13], v[54:55] op_sel_hi:[0,1] neg_lo:[0,1] neg_hi:[0,1]
	v_mov_b32_e32 v57, v55
	v_pk_mul_f32 v[54:55], v[56:57], v[126:127]
	v_pk_mul_f32 v[56:57], v[56:57], v[124:125]
	v_pk_fma_f32 v[58:59], v[70:71], v[124:125], v[54:55] neg_lo:[0,0,1] neg_hi:[0,0,1]
	v_pk_fma_f32 v[54:55], v[70:71], v[124:125], v[54:55]
	v_pk_fma_f32 v[72:73], v[70:71], v[126:127], v[56:57]
	v_pk_fma_f32 v[56:57], v[70:71], v[126:127], v[56:57] neg_lo:[0,0,1] neg_hi:[0,0,1]
	v_pk_add_f32 v[70:71], v[58:59], v[54:55] op_sel:[0,1] op_sel_hi:[1,0]
	v_pk_add_f32 v[74:75], v[72:73], v[56:57] op_sel_hi:[0,1] neg_lo:[0,1] neg_hi:[0,1]
	v_pk_add_f32 v[54:55], v[58:59], v[54:55] op_sel_hi:[0,1] neg_lo:[0,1] neg_hi:[0,1]
	v_pk_add_f32 v[56:57], v[72:73], v[56:57] op_sel:[0,1] op_sel_hi:[1,0]
	v_mov_b32_e32 v71, v75
	v_mov_b32_e32 v57, v55
	v_pk_mul_f32 v[54:55], v[56:57], 0.5 op_sel_hi:[1,0]
	s_mov_b32 s66, s11
	v_pk_mul_f32 v[52:53], v[52:53], v[54:55] op_sel:[1,1] op_sel_hi:[1,0]
	s_mov_b32 s67, s8
	v_pk_fma_f32 v[56:57], v[48:49], v[54:55], v[52:53] op_sel_hi:[0,1,1]
	v_pk_fma_f32 v[48:49], v[48:49], v[54:55], v[52:53] op_sel_hi:[0,1,1] neg_lo:[0,0,1] neg_hi:[0,0,1]
	v_mov_b32_e32 v48, v56
	v_pk_fma_f32 v[52:53], v[70:71], 0.5, v[56:57] op_sel_hi:[1,0,1] neg_lo:[0,0,1] neg_hi:[0,0,1]
	v_pk_fma_f32 v[84:85], v[70:71], 0.5, v[48:49] op_sel_hi:[1,0,1]
	s_mov_b32 s9, s11
	v_mov_b32_e32 v53, v85
	v_pk_mul_f32 v[80:81], v[52:53], s[46:47] op_sel_hi:[1,0]
	v_pk_mul_f32 v[118:119], v[82:83], s[66:67] op_sel_hi:[0,1]
	v_pk_add_f32 v[52:53], v[86:87], v[112:113]
	v_pk_add_f32 v[54:55], v[86:87], v[112:113] neg_lo:[0,1] neg_hi:[0,1]
	v_pk_fma_f32 v[58:59], v[4:5], s[8:9], v[118:119] op_sel_hi:[0,1,1] neg_lo:[0,0,1] neg_hi:[0,0,1]
	v_mul_f32_e32 v12, 0.5, v55
	v_pk_fma_f32 v[72:73], v[4:5], s[8:9], v[118:119] op_sel_hi:[0,1,1]
	v_mov_b32_e32 v55, v53
	v_mul_f32_e32 v6, 0.5, v52
	v_mov_b32_e32 v56, v58
	v_mov_b32_e32 v57, v73
	v_pk_mul_f32 v[52:53], v[54:55], s[44:45]
	v_pk_fma_f32 v[48:49], v[70:71], 0.5, v[48:49] op_sel_hi:[1,0,1] neg_lo:[1,0,0] neg_hi:[1,0,0]
	v_pk_mul_f32 v[54:55], v[56:57], v[52:53] op_sel:[0,1] op_sel_hi:[1,0]
	v_pk_mul_f32 v[52:53], v[56:57], v[52:53]
	v_pk_add_f32 v[54:55], v[54:55], v[54:55] op_sel:[0,1] op_sel_hi:[0,1]
	v_pk_add_f32 v[74:75], v[6:7], v[54:55]
	v_pk_add_f32 v[54:55], v[6:7], v[54:55] op_sel_hi:[0,1] neg_lo:[0,1] neg_hi:[0,1]
	v_pk_add_f32 v[52:53], v[52:53], v[52:53] op_sel:[0,1] op_sel_hi:[0,1] neg_lo:[0,1] neg_hi:[0,1]
	v_mov_b32_e32 v75, v55
	v_pk_add_f32 v[54:55], v[12:13], v[52:53]
	v_pk_add_f32 v[52:53], v[12:13], v[52:53] op_sel_hi:[0,1] neg_lo:[0,1] neg_hi:[0,1]
	v_mov_b32_e32 v55, v53
	v_pk_mul_f32 v[52:53], v[54:55], v[116:117]
	v_pk_mul_f32 v[54:55], v[54:55], v[114:115]
	v_pk_fma_f32 v[52:53], v[74:75], v[114:115], v[52:53]
	v_pk_fma_f32 v[54:55], v[74:75], v[116:117], v[54:55] neg_lo:[0,0,1] neg_hi:[0,0,1]
	v_pk_mov_b32 v[70:71], v[72:73], v[58:59] op_sel:[1,0]
	v_pk_add_f32 v[74:75], v[54:55], v[52:53] op_sel:[0,1] op_sel_hi:[1,0] neg_lo:[0,1] neg_hi:[0,1]
	v_pk_add_f32 v[76:77], v[54:55], v[52:53] op_sel:[0,1] op_sel_hi:[1,0]
	v_pk_add_f32 v[52:53], v[52:53], v[54:55] op_sel:[1,0] op_sel_hi:[0,1] neg_lo:[0,1] neg_hi:[0,1]
	v_mov_b32_e32 v75, v77
	v_pk_mul_f32 v[74:75], v[74:75], 0.5 op_sel_hi:[1,0]
	v_mov_b32_e32 v77, v53
	v_mul_f32_e32 v6, v58, v74
	v_pk_fma_f32 v[112:113], v[56:57], v[74:75], v[6:7] op_sel_hi:[1,1,0] neg_lo:[1,0,0] neg_hi:[1,0,0]
	v_mul_f32_e32 v6, v58, v75
	v_pk_fma_f32 v[70:71], v[70:71], v[74:75], v[6:7] op_sel_hi:[1,1,0]
	v_pk_add_f32 v[54:55], v[34:35], v[110:111]
	v_mov_b32_e32 v112, v70
	v_pk_fma_f32 v[52:53], v[76:77], 0.5, v[70:71] op_sel_hi:[1,0,1] neg_lo:[0,0,1] neg_hi:[0,0,1]
	v_pk_fma_f32 v[86:87], v[76:77], 0.5, v[112:113] op_sel_hi:[1,0,1]
	v_sub_f32_e32 v12, v35, v111
	v_mov_b32_e32 v53, v87
	v_pk_mul_f32 v[78:79], v[52:53], s[46:47] op_sel_hi:[1,0]
	v_mul_f32_e32 v52, 0xbe47c5c2, v83
	v_mov_b32_e32 v53, v34
	v_pk_mov_b32 v[34:35], v[118:119], v[110:111] op_sel:[1,0]
	v_mul_f32_e32 v18, 0.5, v55
	v_pk_add_f32 v[34:35], v[52:53], v[34:35] neg_lo:[0,1] neg_hi:[0,1]
	v_mov_b32_e32 v71, v58
	v_pk_mul_f32 v[52:53], v[34:35], v[18:19]
	v_mov_b32_e32 v70, v34
	v_pk_fma_f32 v[56:57], v[56:57], v[52:53], v[52:53] op_sel:[0,1,0] op_sel_hi:[1,0,1]
	v_mov_b32_e32 v52, v53
	v_mov_b32_e32 v53, v18
	v_mul_f32_e32 v6, 0.5, v54
	v_pk_mul_f32 v[52:53], v[70:71], v[52:53]
	v_cvt_f32_f16_e32 v70, v46
	v_cvt_f32_f16_e32 v71, v47
	v_cvt_f32_f16_sdwa v47, v47 dst_sel:DWORD dst_unused:UNUSED_PAD src0_sel:WORD_1
	v_cvt_f32_f16_sdwa v46, v46 dst_sel:DWORD dst_unused:UNUSED_PAD src0_sel:WORD_1
	v_pk_fma_f32 v[74:75], v[76:77], 0.5, v[112:113] op_sel_hi:[1,0,1] neg_lo:[1,0,0] neg_hi:[1,0,0]
	v_mul_f32_e32 v12, 0.5, v12
	v_pk_add_f32 v[76:77], v[6:7], v[56:57]
	v_pk_add_f32 v[52:53], v[52:53], v[52:53] op_sel:[0,1] op_sel_hi:[0,1] neg_lo:[0,1] neg_hi:[0,1]
	v_fma_f32 v77, v54, 0.5, -v56
	v_pk_add_f32 v[54:55], v[12:13], v[52:53]
	v_pk_add_f32 v[52:53], v[12:13], v[52:53] op_sel_hi:[0,1] neg_lo:[0,1] neg_hi:[0,1]
	v_mov_b32_e32 v55, v53
	v_pk_mul_f32 v[52:53], v[54:55], v[46:47]
	v_pk_mul_f32 v[54:55], v[54:55], v[70:71]
	v_pk_fma_f32 v[56:57], v[76:77], v[70:71], v[52:53] neg_lo:[0,0,1] neg_hi:[0,0,1]
	v_pk_fma_f32 v[52:53], v[76:77], v[70:71], v[52:53]
	v_pk_fma_f32 v[70:71], v[76:77], v[46:47], v[54:55]
	v_pk_fma_f32 v[46:47], v[76:77], v[46:47], v[54:55] neg_lo:[0,0,1] neg_hi:[0,0,1]
	v_pk_add_f32 v[54:55], v[56:57], v[52:53] op_sel:[0,1] op_sel_hi:[1,0]
	v_pk_add_f32 v[76:77], v[70:71], v[46:47] op_sel_hi:[0,1] neg_lo:[0,1] neg_hi:[0,1]
	v_pk_add_f32 v[52:53], v[56:57], v[52:53] op_sel_hi:[0,1] neg_lo:[0,1] neg_hi:[0,1]
	v_pk_add_f32 v[46:47], v[70:71], v[46:47] op_sel:[0,1] op_sel_hi:[1,0]
	v_mov_b32_e32 v55, v77
	v_mov_b32_e32 v47, v53
	v_pk_mul_f32 v[46:47], v[46:47], 0.5 op_sel_hi:[1,0]
	s_mov_b32 s25, s27
	v_pk_mul_f32 v[52:53], v[58:59], v[46:47] op_sel:[0,1] op_sel_hi:[0,0]
	v_pk_fma_f32 v[56:57], v[34:35], v[46:47], v[52:53] op_sel_hi:[0,1,1]
	v_pk_fma_f32 v[46:47], v[34:35], v[46:47], v[52:53] op_sel_hi:[0,1,1] neg_lo:[0,0,1] neg_hi:[0,0,1]
	v_mov_b32_e32 v46, v56
	v_pk_fma_f32 v[52:53], v[54:55], 0.5, v[56:57] op_sel_hi:[1,0,1] neg_lo:[0,0,1] neg_hi:[0,0,1]
	v_pk_fma_f32 v[34:35], v[54:55], 0.5, v[46:47] op_sel_hi:[1,0,1]
	s_mov_b32 s66, s27
	v_mov_b32_e32 v53, v35
	v_pk_mul_f32 v[136:137], v[52:53], s[46:47] op_sel_hi:[1,0]
	v_pk_fma_f32 v[52:53], v[54:55], 0.5, v[46:47] op_sel_hi:[1,0,1] neg_lo:[1,0,0] neg_hi:[1,0,0]
	s_mov_b32 s67, s24
	v_pk_mul_f32 v[46:47], v[82:83], s[24:25] op_sel_hi:[0,1]
	v_pk_add_f32 v[54:55], v[108:109], v[40:41]
	v_pk_add_f32 v[40:41], v[40:41], v[108:109] neg_lo:[0,1] neg_hi:[0,1]
	v_pk_fma_f32 v[108:109], v[4:5], s[66:67], v[46:47] op_sel_hi:[0,1,1] neg_lo:[0,0,1] neg_hi:[0,0,1]
	v_mul_f32_e32 v12, 0.5, v41
	v_pk_fma_f32 v[70:71], v[4:5], s[66:67], v[46:47] op_sel_hi:[0,1,1]
	v_mov_b32_e32 v41, v55
	v_mov_b32_e32 v56, v108
	v_mov_b32_e32 v57, v71
	v_pk_mul_f32 v[40:41], v[40:41], s[44:45]
	v_mul_f32_e32 v6, 0.5, v54
	v_pk_mul_f32 v[54:55], v[56:57], v[40:41] op_sel:[0,1] op_sel_hi:[1,0]
	v_cvt_f32_f16_sdwa v76, v38 dst_sel:DWORD dst_unused:UNUSED_PAD src0_sel:WORD_1
	v_cvt_f32_f16_e32 v77, v39
	v_cvt_f32_f16_sdwa v39, v39 dst_sel:DWORD dst_unused:UNUSED_PAD src0_sel:WORD_1
	v_cvt_f32_f16_e32 v38, v38
	v_pk_mul_f32 v[40:41], v[56:57], v[40:41]
	v_pk_add_f32 v[54:55], v[54:55], v[54:55] op_sel:[0,1] op_sel_hi:[0,1]
	v_pk_add_f32 v[112:113], v[6:7], v[54:55]
	v_pk_add_f32 v[54:55], v[6:7], v[54:55] op_sel_hi:[0,1] neg_lo:[0,1] neg_hi:[0,1]
	v_pk_add_f32 v[40:41], v[40:41], v[40:41] op_sel:[0,1] op_sel_hi:[0,1] neg_lo:[0,1] neg_hi:[0,1]
	v_mov_b32_e32 v113, v55
	v_pk_add_f32 v[54:55], v[12:13], v[40:41]
	v_pk_add_f32 v[40:41], v[12:13], v[40:41] op_sel_hi:[0,1] neg_lo:[0,1] neg_hi:[0,1]
	v_mov_b32_e32 v55, v41
	v_pk_mul_f32 v[40:41], v[54:55], v[38:39]
	v_pk_mul_f32 v[54:55], v[54:55], v[76:77]
	v_pk_fma_f32 v[40:41], v[112:113], v[76:77], v[40:41]
	v_pk_fma_f32 v[38:39], v[112:113], v[38:39], v[54:55] neg_lo:[0,0,1] neg_hi:[0,0,1]
	v_pk_mov_b32 v[110:111], v[70:71], v[108:109] op_sel:[1,0]
	v_pk_add_f32 v[54:55], v[38:39], v[40:41] op_sel:[0,1] op_sel_hi:[1,0] neg_lo:[0,1] neg_hi:[0,1]
	v_pk_add_f32 v[76:77], v[38:39], v[40:41] op_sel:[0,1] op_sel_hi:[1,0]
	v_pk_add_f32 v[38:39], v[40:41], v[38:39] op_sel:[1,0] op_sel_hi:[0,1] neg_lo:[0,1] neg_hi:[0,1]
	v_mov_b32_e32 v55, v77
	v_pk_mul_f32 v[54:55], v[54:55], 0.5 op_sel_hi:[1,0]
	v_mov_b32_e32 v77, v39
	v_mul_f32_e32 v4, v108, v54
	v_pk_fma_f32 v[112:113], v[56:57], v[54:55], v[4:5] op_sel_hi:[1,1,0] neg_lo:[1,0,0] neg_hi:[1,0,0]
	v_mul_f32_e32 v4, v108, v55
	v_pk_fma_f32 v[54:55], v[110:111], v[54:55], v[4:5] op_sel_hi:[1,1,0]
	v_sub_f32_e32 v6, v45, v105
	v_mov_b32_e32 v112, v54
	v_pk_fma_f32 v[40:41], v[76:77], 0.5, v[54:55] op_sel_hi:[1,0,1] neg_lo:[0,0,1] neg_hi:[0,0,1]
	v_pk_fma_f32 v[38:39], v[76:77], 0.5, v[112:113] op_sel_hi:[1,0,1]
	v_pk_add_f32 v[54:55], v[104:105], v[44:45]
	v_mov_b32_e32 v41, v39
	v_pk_mul_f32 v[130:131], v[40:41], s[46:47] op_sel_hi:[1,0]
	v_mul_f32_e32 v40, 0xbf54db31, v83
	v_mov_b32_e32 v41, v44
	v_pk_mov_b32 v[44:45], v[46:47], v[104:105] op_sel:[1,0]
	v_mul_f32_e32 v18, 0.5, v55
	v_pk_add_f32 v[40:41], v[40:41], v[44:45] neg_lo:[0,1] neg_hi:[0,1]
	v_mov_b32_e32 v105, v108
	v_pk_mul_f32 v[44:45], v[40:41], v[18:19]
	v_mov_b32_e32 v104, v40
	v_pk_fma_f32 v[56:57], v[56:57], v[44:45], v[44:45] op_sel:[0,1,0] op_sel_hi:[1,0,1]
	v_mov_b32_e32 v44, v45
	v_mov_b32_e32 v45, v18
	v_mul_f32_e32 v4, 0.5, v54
	v_pk_mul_f32 v[44:45], v[104:105], v[44:45]
	v_cvt_f32_f16_e32 v104, v26
	v_cvt_f32_f16_e32 v105, v27
	v_cvt_f32_f16_sdwa v27, v27 dst_sel:DWORD dst_unused:UNUSED_PAD src0_sel:WORD_1
	v_cvt_f32_f16_sdwa v26, v26 dst_sel:DWORD dst_unused:UNUSED_PAD src0_sel:WORD_1
	v_mul_f32_e32 v6, 0.5, v6
	v_pk_add_f32 v[110:111], v[4:5], v[56:57]
	v_pk_add_f32 v[44:45], v[44:45], v[44:45] op_sel:[0,1] op_sel_hi:[0,1] neg_lo:[0,1] neg_hi:[0,1]
	v_fma_f32 v111, v54, 0.5, -v56
	v_pk_add_f32 v[54:55], v[6:7], v[44:45]
	v_pk_add_f32 v[44:45], v[6:7], v[44:45] op_sel_hi:[0,1] neg_lo:[0,1] neg_hi:[0,1]
	v_mov_b32_e32 v55, v45
	v_pk_mul_f32 v[44:45], v[54:55], v[26:27]
	v_pk_mul_f32 v[54:55], v[54:55], v[104:105]
	v_pk_fma_f32 v[56:57], v[110:111], v[104:105], v[44:45] neg_lo:[0,0,1] neg_hi:[0,0,1]
	v_pk_fma_f32 v[44:45], v[110:111], v[104:105], v[44:45]
	v_pk_fma_f32 v[104:105], v[110:111], v[26:27], v[54:55]
	v_pk_fma_f32 v[26:27], v[110:111], v[26:27], v[54:55] neg_lo:[0,0,1] neg_hi:[0,0,1]
	v_pk_add_f32 v[54:55], v[56:57], v[44:45] op_sel:[0,1] op_sel_hi:[1,0]
	v_pk_add_f32 v[110:111], v[104:105], v[26:27] op_sel_hi:[0,1] neg_lo:[0,1] neg_hi:[0,1]
	v_pk_add_f32 v[44:45], v[56:57], v[44:45] op_sel_hi:[0,1] neg_lo:[0,1] neg_hi:[0,1]
	v_pk_add_f32 v[26:27], v[104:105], v[26:27] op_sel:[0,1] op_sel_hi:[1,0]
	v_mov_b32_e32 v55, v111
	v_mov_b32_e32 v27, v45
	v_pk_mul_f32 v[26:27], v[26:27], 0.5 op_sel_hi:[1,0]
	v_mov_b32_e32 v47, v102
	v_pk_mul_f32 v[44:45], v[108:109], v[26:27] op_sel:[0,1] op_sel_hi:[0,0]
	v_pk_fma_f32 v[56:57], v[40:41], v[26:27], v[44:45] op_sel_hi:[0,1,1]
	v_pk_fma_f32 v[40:41], v[40:41], v[26:27], v[44:45] op_sel_hi:[0,1,1] neg_lo:[0,0,1] neg_hi:[0,0,1]
	v_mov_b32_e32 v40, v56
	v_pk_fma_f32 v[44:45], v[54:55], 0.5, v[56:57] op_sel_hi:[1,0,1] neg_lo:[0,0,1] neg_hi:[0,0,1]
	v_pk_fma_f32 v[26:27], v[54:55], 0.5, v[40:41] op_sel_hi:[1,0,1]
	v_pk_fma_f32 v[56:57], v[54:55], 0.5, v[40:41] op_sel_hi:[1,0,1] neg_lo:[1,0,0] neg_hi:[1,0,0]
	v_pk_add_f32 v[40:41], v[106:107], v[42:43]
	v_pk_add_f32 v[42:43], v[42:43], v[106:107] neg_lo:[0,1] neg_hi:[0,1]
	v_mov_b32_e32 v45, v27
	v_mul_f32_e32 v6, 0.5, v43
	v_mov_b32_e32 v43, v41
	v_pk_mul_f32 v[120:121], v[44:45], s[46:47] op_sel_hi:[1,0]
	v_mul_f32_e32 v4, 0.5, v40
	v_pk_mov_b32 v[44:45], v[108:109], v[70:71] op_sel:[1,0]
	v_pk_mul_f32 v[40:41], v[42:43], s[44:45]
	v_cvt_f32_f16_sdwa v54, v20 dst_sel:DWORD dst_unused:UNUSED_PAD src0_sel:WORD_1
	v_pk_mul_f32 v[42:43], v[44:45], v[40:41] op_sel:[0,1] op_sel_hi:[1,0]
	v_cvt_f32_f16_e32 v55, v21
	v_cvt_f32_f16_sdwa v21, v21 dst_sel:DWORD dst_unused:UNUSED_PAD src0_sel:WORD_1
	v_cvt_f32_f16_e32 v20, v20
	v_pk_mul_f32 v[40:41], v[44:45], v[40:41]
	v_pk_add_f32 v[42:43], v[42:43], v[42:43] op_sel:[0,1] op_sel_hi:[0,1]
	v_pk_add_f32 v[104:105], v[4:5], v[42:43]
	v_pk_add_f32 v[42:43], v[4:5], v[42:43] op_sel_hi:[0,1] neg_lo:[0,1] neg_hi:[0,1]
	v_pk_add_f32 v[40:41], v[40:41], v[40:41] op_sel:[0,1] op_sel_hi:[0,1] neg_lo:[0,1] neg_hi:[0,1]
	v_mov_b32_e32 v105, v43
	v_pk_add_f32 v[42:43], v[6:7], v[40:41]
	v_pk_add_f32 v[40:41], v[6:7], v[40:41] op_sel_hi:[0,1] neg_lo:[0,1] neg_hi:[0,1]
	v_mov_b32_e32 v43, v41
	v_pk_mul_f32 v[40:41], v[42:43], v[20:21]
	v_pk_mul_f32 v[42:43], v[42:43], v[54:55]
	v_pk_fma_f32 v[40:41], v[104:105], v[54:55], v[40:41]
	v_pk_fma_f32 v[20:21], v[104:105], v[20:21], v[42:43] neg_lo:[0,0,1] neg_hi:[0,0,1]
	v_mov_b32_e32 v71, v109
	v_pk_add_f32 v[42:43], v[20:21], v[40:41] op_sel:[0,1] op_sel_hi:[1,0] neg_lo:[0,1] neg_hi:[0,1]
	v_pk_add_f32 v[54:55], v[20:21], v[40:41] op_sel:[0,1] op_sel_hi:[1,0]
	v_pk_add_f32 v[20:21], v[40:41], v[20:21] op_sel:[1,0] op_sel_hi:[0,1] neg_lo:[0,1] neg_hi:[0,1]
	v_mov_b32_e32 v43, v55
	v_pk_mul_f32 v[42:43], v[42:43], 0.5 op_sel_hi:[1,0]
	v_mov_b32_e32 v55, v21
	v_mul_f32_e32 v4, v109, v42
	v_pk_fma_f32 v[104:105], v[44:45], v[42:43], v[4:5] op_sel_hi:[1,1,0] neg_lo:[1,0,0] neg_hi:[1,0,0]
	v_mul_f32_e32 v4, v109, v43
	v_pk_fma_f32 v[42:43], v[70:71], v[42:43], v[4:5] op_sel_hi:[1,1,0]
	v_sub_f32_e32 v6, v23, v103
	v_mov_b32_e32 v104, v42
	v_pk_fma_f32 v[40:41], v[54:55], 0.5, v[42:43] op_sel_hi:[1,0,1] neg_lo:[0,0,1] neg_hi:[0,0,1]
	v_pk_fma_f32 v[20:21], v[54:55], 0.5, v[104:105] op_sel_hi:[1,0,1]
	v_pk_add_f32 v[42:43], v[102:103], v[22:23]
	v_mov_b32_e32 v41, v21
	v_pk_mul_f32 v[128:129], v[40:41], s[46:47] op_sel_hi:[1,0]
	v_mul_f32_e32 v40, 0xbf0e39da, v83
	v_mov_b32_e32 v41, v22
	v_mul_f32_e32 v18, 0.5, v43
	v_pk_add_f32 v[22:23], v[40:41], v[46:47] neg_lo:[0,1] neg_hi:[0,1]
	v_mov_b32_e32 v47, v109
	v_pk_mul_f32 v[40:41], v[22:23], v[18:19]
	v_mov_b32_e32 v46, v22
	v_pk_fma_f32 v[44:45], v[44:45], v[40:41], v[40:41] op_sel:[0,1,0] op_sel_hi:[1,0,1]
	v_mov_b32_e32 v40, v41
	v_mov_b32_e32 v41, v18
	v_mul_f32_e32 v4, 0.5, v42
	v_pk_mul_f32 v[40:41], v[46:47], v[40:41]
	v_cvt_f32_f16_e32 v46, v10
	v_cvt_f32_f16_e32 v47, v11
	v_cvt_f32_f16_sdwa v11, v11 dst_sel:DWORD dst_unused:UNUSED_PAD src0_sel:WORD_1
	v_cvt_f32_f16_sdwa v10, v10 dst_sel:DWORD dst_unused:UNUSED_PAD src0_sel:WORD_1
	v_pk_fma_f32 v[70:71], v[54:55], 0.5, v[104:105] op_sel_hi:[1,0,1] neg_lo:[1,0,0] neg_hi:[1,0,0]
	v_mul_f32_e32 v6, 0.5, v6
	v_pk_add_f32 v[54:55], v[4:5], v[44:45]
	v_pk_add_f32 v[40:41], v[40:41], v[40:41] op_sel:[0,1] op_sel_hi:[0,1] neg_lo:[0,1] neg_hi:[0,1]
	v_fma_f32 v55, v42, 0.5, -v44
	v_pk_add_f32 v[42:43], v[6:7], v[40:41]
	v_pk_add_f32 v[40:41], v[6:7], v[40:41] op_sel_hi:[0,1] neg_lo:[0,1] neg_hi:[0,1]
	v_mov_b32_e32 v43, v41
	v_pk_mul_f32 v[40:41], v[42:43], v[10:11]
	v_pk_mul_f32 v[42:43], v[42:43], v[46:47]
	v_pk_fma_f32 v[44:45], v[54:55], v[46:47], v[40:41] neg_lo:[0,0,1] neg_hi:[0,0,1]
	v_pk_fma_f32 v[40:41], v[54:55], v[46:47], v[40:41]
	v_pk_fma_f32 v[46:47], v[54:55], v[10:11], v[42:43]
	v_pk_fma_f32 v[10:11], v[54:55], v[10:11], v[42:43] neg_lo:[0,0,1] neg_hi:[0,0,1]
	v_pk_add_f32 v[42:43], v[44:45], v[40:41] op_sel:[0,1] op_sel_hi:[1,0]
	v_pk_add_f32 v[54:55], v[46:47], v[10:11] op_sel_hi:[0,1] neg_lo:[0,1] neg_hi:[0,1]
	v_pk_add_f32 v[40:41], v[44:45], v[40:41] op_sel_hi:[0,1] neg_lo:[0,1] neg_hi:[0,1]
	v_pk_add_f32 v[10:11], v[46:47], v[10:11] op_sel:[0,1] op_sel_hi:[1,0]
	v_mov_b32_e32 v43, v55
	v_mov_b32_e32 v11, v41
	v_pk_mul_f32 v[10:11], v[10:11], 0.5 op_sel_hi:[1,0]
	v_mov_b32_e32 v119, v98
	v_pk_mul_f32 v[40:41], v[108:109], v[10:11] op_sel:[1,1] op_sel_hi:[1,0]
	v_pk_fma_f32 v[76:77], v[76:77], 0.5, v[112:113] op_sel_hi:[1,0,1] neg_lo:[1,0,0] neg_hi:[1,0,0]
	v_pk_fma_f32 v[44:45], v[22:23], v[10:11], v[40:41] op_sel_hi:[0,1,1]
	v_pk_fma_f32 v[10:11], v[22:23], v[10:11], v[40:41] op_sel_hi:[0,1,1] neg_lo:[0,0,1] neg_hi:[0,0,1]
	v_mov_b32_e32 v10, v44
	v_pk_fma_f32 v[22:23], v[42:43], 0.5, v[44:45] op_sel_hi:[1,0,1] neg_lo:[0,0,1] neg_hi:[0,0,1]
	v_pk_fma_f32 v[40:41], v[42:43], 0.5, v[10:11] op_sel_hi:[1,0,1]
	v_pk_fma_f32 v[54:55], v[42:43], 0.5, v[10:11] op_sel_hi:[1,0,1] neg_lo:[1,0,0] neg_hi:[1,0,0]
	v_pk_add_f32 v[10:11], v[100:101], v[14:15]
	v_pk_add_f32 v[14:15], v[14:15], v[100:101] neg_lo:[0,1] neg_hi:[0,1]
	v_mov_b32_e32 v23, v41
	v_mul_f32_e32 v6, 0.5, v15
	v_mov_b32_e32 v15, v11
	v_pk_mul_f32 v[150:151], v[22:23], s[46:47] op_sel_hi:[1,0]
	v_mul_f32_e32 v4, 0.5, v10
	v_pk_mov_b32 v[22:23], v[58:59], v[72:73] op_sel:[1,0]
	v_pk_mul_f32 v[10:11], v[14:15], s[44:45]
	v_cvt_f32_f16_sdwa v42, v8 dst_sel:DWORD dst_unused:UNUSED_PAD src0_sel:WORD_1
	v_pk_mul_f32 v[14:15], v[22:23], v[10:11] op_sel:[0,1] op_sel_hi:[1,0]
	v_cvt_f32_f16_e32 v43, v9
	v_cvt_f32_f16_sdwa v9, v9 dst_sel:DWORD dst_unused:UNUSED_PAD src0_sel:WORD_1
	v_cvt_f32_f16_e32 v8, v8
	v_pk_mul_f32 v[10:11], v[22:23], v[10:11]
	v_pk_add_f32 v[14:15], v[14:15], v[14:15] op_sel:[0,1] op_sel_hi:[0,1]
	v_pk_add_f32 v[44:45], v[4:5], v[14:15]
	v_pk_add_f32 v[14:15], v[4:5], v[14:15] op_sel_hi:[0,1] neg_lo:[0,1] neg_hi:[0,1]
	v_pk_add_f32 v[10:11], v[10:11], v[10:11] op_sel:[0,1] op_sel_hi:[0,1] neg_lo:[0,1] neg_hi:[0,1]
	v_mov_b32_e32 v45, v15
	v_pk_add_f32 v[14:15], v[6:7], v[10:11]
	v_pk_add_f32 v[10:11], v[6:7], v[10:11] op_sel_hi:[0,1] neg_lo:[0,1] neg_hi:[0,1]
	v_mov_b32_e32 v15, v11
	v_pk_mul_f32 v[10:11], v[14:15], v[8:9]
	v_pk_mul_f32 v[14:15], v[14:15], v[42:43]
	v_pk_fma_f32 v[10:11], v[44:45], v[42:43], v[10:11]
	v_pk_fma_f32 v[8:9], v[44:45], v[8:9], v[14:15] neg_lo:[0,0,1] neg_hi:[0,0,1]
	v_mov_b32_e32 v73, v59
	v_pk_add_f32 v[14:15], v[8:9], v[10:11] op_sel:[0,1] op_sel_hi:[1,0] neg_lo:[0,1] neg_hi:[0,1]
	v_pk_add_f32 v[42:43], v[8:9], v[10:11] op_sel:[0,1] op_sel_hi:[1,0]
	v_pk_add_f32 v[8:9], v[10:11], v[8:9] op_sel:[1,0] op_sel_hi:[0,1] neg_lo:[0,1] neg_hi:[0,1]
	v_mov_b32_e32 v15, v43
	v_pk_mul_f32 v[14:15], v[14:15], 0.5 op_sel_hi:[1,0]
	v_mov_b32_e32 v43, v9
	v_mul_f32_e32 v4, v59, v14
	v_pk_fma_f32 v[44:45], v[22:23], v[14:15], v[4:5] op_sel_hi:[1,1,0] neg_lo:[1,0,0] neg_hi:[1,0,0]
	v_mul_f32_e32 v4, v59, v15
	v_pk_fma_f32 v[14:15], v[72:73], v[14:15], v[4:5] op_sel_hi:[1,1,0]
	v_sub_f32_e32 v6, v37, v99
	v_mov_b32_e32 v44, v14
	v_pk_fma_f32 v[8:9], v[42:43], 0.5, v[14:15] op_sel_hi:[1,0,1] neg_lo:[0,0,1] neg_hi:[0,0,1]
	v_pk_fma_f32 v[10:11], v[42:43], 0.5, v[44:45] op_sel_hi:[1,0,1]
	v_pk_add_f32 v[14:15], v[98:99], v[36:37]
	v_mov_b32_e32 v9, v11
	v_pk_mul_f32 v[168:169], v[8:9], s[46:47] op_sel_hi:[1,0]
	v_mul_f32_e32 v8, 0xbf7b14be, v83
	v_mov_b32_e32 v9, v36
	v_mul_f32_e32 v18, 0.5, v15
	v_pk_add_f32 v[8:9], v[8:9], v[118:119] neg_lo:[0,1] neg_hi:[0,1]
	v_pk_fma_f32 v[72:73], v[42:43], 0.5, v[44:45] op_sel_hi:[1,0,1] neg_lo:[1,0,0] neg_hi:[1,0,0]
	v_pk_mul_f32 v[36:37], v[8:9], v[18:19]
	v_mov_b32_e32 v42, v8
	v_pk_fma_f32 v[22:23], v[22:23], v[36:37], v[36:37] op_sel:[0,1,0] op_sel_hi:[1,0,1]
	v_mov_b32_e32 v43, v59
	v_mov_b32_e32 v36, v37
	v_mov_b32_e32 v37, v18
	v_mul_f32_e32 v4, 0.5, v14
	v_pk_mul_f32 v[36:37], v[42:43], v[36:37]
	v_cvt_f32_f16_e32 v44, v2
	v_cvt_f32_f16_e32 v45, v3
	v_cvt_f32_f16_sdwa v3, v3 dst_sel:DWORD dst_unused:UNUSED_PAD src0_sel:WORD_1
	v_cvt_f32_f16_sdwa v2, v2 dst_sel:DWORD dst_unused:UNUSED_PAD src0_sel:WORD_1
	v_mul_f32_e32 v6, 0.5, v6
	v_pk_add_f32 v[46:47], v[4:5], v[22:23]
	v_fma_f32 v4, v14, 0.5, -v22
	v_pk_add_f32 v[22:23], v[36:37], v[36:37] op_sel:[0,1] op_sel_hi:[0,1] neg_lo:[0,1] neg_hi:[0,1]
	v_pk_add_f32 v[36:37], v[6:7], v[22:23]
	v_pk_add_f32 v[22:23], v[6:7], v[22:23] op_sel_hi:[0,1] neg_lo:[0,1] neg_hi:[0,1]
	v_mov_b32_e32 v37, v23
	v_mov_b32_e32 v14, v46
	v_mov_b32_e32 v15, v4
	v_pk_mul_f32 v[22:23], v[4:5], v[44:45] op_sel_hi:[0,1]
	v_pk_mul_f32 v[82:83], v[36:37], v[2:3]
	v_pk_mul_f32 v[46:47], v[46:47], v[2:3]
	v_pk_mul_f32 v[36:37], v[36:37], v[44:45]
	v_pk_fma_f32 v[98:99], v[14:15], v[44:45], v[82:83] neg_lo:[0,0,1] neg_hi:[0,0,1]
	v_pk_fma_f32 v[2:3], v[14:15], v[2:3], v[36:37] neg_lo:[0,0,1] neg_hi:[0,0,1]
	v_add_f32_e32 v4, v23, v83
	v_add_f32_e32 v6, v46, v36
	v_pk_add_f32 v[22:23], v[6:7], v[2:3] op_sel_hi:[0,1] neg_lo:[0,1] neg_hi:[0,1]
	v_pk_add_f32 v[36:37], v[98:99], v[4:5] op_sel_hi:[1,0] neg_lo:[0,1] neg_hi:[0,1]
	v_pk_add_f32 v[2:3], v[6:7], v[2:3] op_sel_hi:[0,1]
	v_mov_b32_e32 v37, v3
	v_pk_mul_f32 v[2:3], v[36:37], 0.5 op_sel_hi:[1,0]
	v_pk_add_f32 v[14:15], v[98:99], v[4:5] op_sel_hi:[1,0]
	v_mul_f32_e32 v4, v59, v3
	v_pk_fma_f32 v[36:37], v[42:43], v[2:3], v[4:5] op_sel_hi:[1,1,0] neg_lo:[0,0,1] neg_hi:[0,0,1]
	v_pk_mov_b32 v[42:43], v[58:59], v[8:9] op_sel:[1,0]
	v_mul_f32_e32 v4, v8, v3
	v_pk_fma_f32 v[2:3], v[42:43], v[2:3], v[4:5] op_sel_hi:[1,1,0]
	v_mov_b32_e32 v15, v23
	v_pk_fma_f32 v[8:9], v[14:15], 0.5, v[2:3] op_sel_hi:[1,0,1] neg_lo:[0,0,1] neg_hi:[0,0,1]
	v_pk_fma_f32 v[42:43], v[14:15], 0.5, v[36:37] op_sel_hi:[1,0,0]
	v_pk_fma_f32 v[2:3], v[14:15], 0.5, v[2:3] op_sel_hi:[1,0,1]
	v_mov_b32_e32 v9, v43
	v_pk_fma_f32 v[58:59], v[22:23], 0.5, v[36:37] op_sel_hi:[1,0,0] neg_lo:[1,0,0] neg_hi:[1,0,0]
	v_pk_mul_f32 v[144:145], v[8:9], s[46:47] op_sel_hi:[1,0]
	v_mov_b32_e32 v58, v2
	v_mov_b32_e32 v72, v10
	v_mov_b32_e32 v54, v40
	v_mov_b32_e32 v70, v20
	v_mov_b32_e32 v56, v26
	v_mov_b32_e32 v76, v38
	v_mov_b32_e32 v52, v34
	v_mov_b32_e32 v74, v86
	v_mov_b32_e32 v48, v84
	v_mov_b32_e32 v50, v60
	v_mov_b32_e32 v28, v66
	v_mov_b32_e32 v32, v96
	v_mov_b32_e32 v12, v88
	v_mov_b32_e32 v16, v92
	v_mov_b32_e32 v4, v138
	v_mov_b32_e32 v6, v122

.LBB0_560:
	s_or_b64 exec, exec, s[0:1]
	v_mov_b32_e32 v2, v142
	s_waitcnt lgkmcnt(0)
	s_barrier
	s_mov_b32 s41, s38
	v_and_b32_e32 v4, 0x1ff, v2
	v_lshlrev_b32_e32 v2, 5, v2
	v_and_or_b32 v2, v2, s34, v4
	v_ashrrev_i32_e32 v6, 5, v2
	v_lshlrev_b32_e32 v2, 3, v2
	v_lshlrev_b32_e32 v7, 3, v6
	v_add3_u32 v2, 0, v2, v7
	v_add_u32_e32 v143, 0x10800, v2
	ds_read_b64 v[128:129], v2
	ds_read_b64 v[130:131], v2 offset:4224
	ds_read_b64 v[144:145], v2 offset:8448
	ds_read_b64 v[148:149], v2 offset:12672
	ds_read_b64 v[150:151], v2 offset:16896
	ds_read_b64 v[152:153], v2 offset:21120
	ds_read_b64 v[154:155], v2 offset:25344
	ds_read_b64 v[156:157], v2 offset:29568
	ds_read_b64 v[158:159], v2 offset:33792
	ds_read_b64 v[160:161], v2 offset:38016
	ds_read_b64 v[162:163], v2 offset:42240
	ds_read_b64 v[164:165], v2 offset:46464
	ds_read_b64 v[166:167], v2 offset:50688
	ds_read_b64 v[168:169], v2 offset:54912
	ds_read_b64 v[170:171], v2 offset:59136
	ds_read_b64 v[172:173], v2 offset:63360
	v_add_u32_e32 v212, 0x11880, v2
	v_add_u32_e32 v213, 0x12900, v2
	v_add_u32_e32 v214, 0x13980, v2
	ds_read_b64 v[174:175], v143
	ds_read_b64 v[176:177], v212
	ds_read_b64 v[178:179], v213
	ds_read_b64 v[180:181], v214
	v_add_u32_e32 v215, 0x14a00, v2
	s_waitcnt lgkmcnt(3)
	v_pk_add_f32 v[210:211], v[128:129], v[174:175]
	v_pk_add_f32 v[128:129], v[128:129], v[174:175] neg_lo:[0,1] neg_hi:[0,1]
	s_waitcnt lgkmcnt(2)
	v_pk_add_f32 v[174:175], v[130:131], v[176:177]
	v_pk_add_f32 v[130:131], v[130:131], v[176:177] neg_lo:[0,1] neg_hi:[0,1]
	v_add_u32_e32 v216, 0x15a80, v2
	v_pk_mul_f32 v[176:177], v[130:131], s[20:21]
	v_add_u32_e32 v217, 0x16b00, v2
	v_pk_fma_f32 v[130:131], v[130:131], s[10:11], v[176:177] op_sel:[0,0,1] op_sel_hi:[1,0,0]
	s_waitcnt lgkmcnt(1)
	v_pk_add_f32 v[176:177], v[144:145], v[178:179]
	v_pk_add_f32 v[144:145], v[144:145], v[178:179] neg_lo:[0,1] neg_hi:[0,1]
	v_add_u32_e32 v218, 0x17b80, v2
	v_pk_mul_f32 v[178:179], v[144:145], s[24:25]
	ds_read_b64 v[182:183], v215
	ds_read_b64 v[184:185], v216
	ds_read_b64 v[186:187], v217
	ds_read_b64 v[188:189], v218
	v_pk_fma_f32 v[144:145], v[144:145], s[22:23], v[178:179] op_sel:[0,0,1] op_sel_hi:[1,0,0]
	s_waitcnt lgkmcnt(4)
	v_pk_add_f32 v[178:179], v[148:149], v[180:181]
	v_pk_add_f32 v[148:149], v[148:149], v[180:181] neg_lo:[0,1] neg_hi:[0,1]
	s_mov_b32 s43, s26
	v_pk_mul_f32 v[180:181], v[148:149], s[36:37]
	s_mov_b32 s0, s37
	v_pk_fma_f32 v[148:149], v[148:149], s[26:27], v[180:181] op_sel:[0,0,1] op_sel_hi:[1,0,0]
	s_waitcnt lgkmcnt(3)
	v_pk_add_f32 v[180:181], v[150:151], v[182:183]
	v_pk_add_f32 v[150:151], v[150:151], v[182:183] neg_lo:[0,1] neg_hi:[0,1]
	s_mov_b32 s45, s22
	v_pk_mul_f32 v[182:183], v[150:151], s[40:41]
	v_add_u32_e32 v219, 0x18c00, v2
	v_pk_fma_f32 v[150:151], v[150:151], s[38:39], v[182:183] op_sel:[0,0,1] op_sel_hi:[1,0,0]
	s_waitcnt lgkmcnt(2)
	v_pk_add_f32 v[182:183], v[152:153], v[184:185]
	v_pk_add_f32 v[152:153], v[152:153], v[184:185] neg_lo:[0,1] neg_hi:[0,1]
	s_mov_b32 s50, s25
	v_pk_mul_f32 v[184:185], v[152:153], s[42:43]
	v_add_u32_e32 v220, 0x19c80, v2
	v_pk_fma_f32 v[152:153], v[152:153], s[0:1], v[184:185] op_sel:[0,0,1] op_sel_hi:[1,0,0]
	s_waitcnt lgkmcnt(1)
	v_pk_add_f32 v[184:185], v[154:155], v[186:187]
	v_pk_add_f32 v[154:155], v[154:155], v[186:187] neg_lo:[0,1] neg_hi:[0,1]
	v_add_u32_e32 v221, 0x1ad00, v2
	v_pk_mul_f32 v[186:187], v[154:155], s[44:45]
	v_add_u32_e32 v222, 0x1bd80, v2
	ds_read_b64 v[190:191], v219
	ds_read_b64 v[192:193], v220
	ds_read_b64 v[194:195], v221
	ds_read_b64 v[196:197], v222
	v_pk_fma_f32 v[154:155], v[154:155], s[50:51], v[186:187] op_sel:[0,0,1] op_sel_hi:[1,0,0]
	s_waitcnt lgkmcnt(4)
	v_pk_add_f32 v[186:187], v[156:157], v[188:189]
	v_pk_add_f32 v[156:157], v[156:157], v[188:189] neg_lo:[0,1] neg_hi:[0,1]
	v_add_u32_e32 v223, 0x1ce00, v2
	v_pk_mul_f32 v[188:189], v[156:157], s[8:9]
	v_add_u32_e32 v224, 0x1de80, v2
	v_pk_fma_f32 v[156:157], v[156:157], s[16:17], v[188:189] op_sel:[0,0,1] op_sel_hi:[1,0,0]
	s_waitcnt lgkmcnt(3)
	v_pk_add_f32 v[188:189], v[158:159], v[190:191]
	v_pk_add_f32 v[190:191], v[158:159], v[190:191] neg_lo:[0,1] neg_hi:[0,1]
	v_add_u32_e32 v225, 0x1ef00, v2
	s_waitcnt lgkmcnt(2)
	v_pk_add_f32 v[158:159], v[160:161], v[192:193]
	v_pk_add_f32 v[160:161], v[160:161], v[192:193] neg_lo:[0,1] neg_hi:[0,1]
	v_add_u32_e32 v226, 0x1ff80, v2
	v_pk_mul_f32 v[192:193], v[160:161], s[8:9]
	ds_read_b64 v[198:199], v223
	ds_read_b64 v[204:205], v224
	ds_read_b64 v[206:207], v225
	ds_read_b64 v[208:209], v226
	v_pk_fma_f32 v[160:161], v[160:161], s[16:17], v[192:193] op_sel:[0,0,1] op_sel_hi:[1,0,0] neg_lo:[1,0,0] neg_hi:[1,0,0]
	s_waitcnt lgkmcnt(5)
	v_pk_add_f32 v[192:193], v[162:163], v[194:195]
	v_pk_add_f32 v[162:163], v[162:163], v[194:195] neg_lo:[0,1] neg_hi:[0,1]
	v_cvt_f32_u32_e32 v5, v4
	v_pk_mul_f32 v[194:195], v[162:163], s[44:45]
	v_mul_f32_e32 v5, 0x38800000, v5
	v_pk_fma_f32 v[162:163], v[162:163], s[50:51], v[194:195] op_sel:[0,0,1] op_sel_hi:[1,0,0] neg_lo:[1,0,0] neg_hi:[1,0,0]
	s_waitcnt lgkmcnt(4)
	v_pk_add_f32 v[194:195], v[164:165], v[196:197]
	v_pk_add_f32 v[164:165], v[164:165], v[196:197] neg_lo:[0,1] neg_hi:[0,1]
	v_sin_f32_e32 v4, v5
	v_pk_mul_f32 v[196:197], v[164:165], s[42:43]
	v_cos_f32_e32 v6, v5
	v_pk_fma_f32 v[164:165], v[164:165], s[0:1], v[196:197] op_sel:[0,0,1] op_sel_hi:[1,0,0] neg_lo:[1,0,0] neg_hi:[1,0,0]
	s_waitcnt lgkmcnt(3)
	v_pk_add_f32 v[196:197], v[166:167], v[198:199]
	v_pk_add_f32 v[166:167], v[166:167], v[198:199] neg_lo:[0,1] neg_hi:[0,1]
	v_xor_b32_e32 v7, 0x80000000, v4
	v_pk_mul_f32 v[198:199], v[166:167], s[40:41]
	v_mov_b32_e32 v5, v7
	v_pk_fma_f32 v[166:167], v[166:167], s[38:39], v[198:199] op_sel:[0,0,1] op_sel_hi:[1,0,0] neg_lo:[1,0,0] neg_hi:[1,0,0]
	s_waitcnt lgkmcnt(2)
	v_pk_add_f32 v[198:199], v[168:169], v[204:205]
	v_pk_add_f32 v[168:169], v[168:169], v[204:205] neg_lo:[0,1] neg_hi:[0,1]
	v_pk_mul_f32 v[8:9], v[6:7], v[4:5] op_sel:[1,0] op_sel_hi:[0,1]
	v_pk_mul_f32 v[204:205], v[168:169], s[36:37]
	v_pk_fma_f32 v[8:9], v[6:7], v[6:7], v[8:9] op_sel_hi:[1,0,1]
	v_pk_fma_f32 v[168:169], v[168:169], s[26:27], v[204:205] op_sel:[0,0,1] op_sel_hi:[1,0,0] neg_lo:[1,0,0] neg_hi:[1,0,0]
	s_waitcnt lgkmcnt(1)
	v_pk_add_f32 v[204:205], v[170:171], v[206:207]
	v_pk_add_f32 v[170:171], v[170:171], v[206:207] neg_lo:[0,1] neg_hi:[0,1]
	v_xor_b32_e32 v14, 0x80000000, v9
	v_pk_mul_f32 v[206:207], v[170:171], s[24:25]
	v_mov_b32_e32 v15, v9
	v_pk_fma_f32 v[170:171], v[170:171], s[22:23], v[206:207] op_sel:[0,0,1] op_sel_hi:[1,0,0] neg_lo:[1,0,0] neg_hi:[1,0,0]
	s_waitcnt lgkmcnt(0)
	v_pk_add_f32 v[206:207], v[172:173], v[208:209]
	v_pk_add_f32 v[172:173], v[172:173], v[208:209] neg_lo:[0,1] neg_hi:[0,1]
	v_pk_mul_f32 v[12:13], v[8:9], v[14:15] op_sel:[1,0] op_sel_hi:[0,1]
	v_pk_mul_f32 v[208:209], v[172:173], s[20:21]
	v_pk_fma_f32 v[12:13], v[8:9], v[8:9], v[12:13] op_sel_hi:[1,0,1]
	v_pk_fma_f32 v[172:173], v[172:173], s[10:11], v[208:209] op_sel:[0,0,1] op_sel_hi:[1,0,0] neg_lo:[1,0,0] neg_hi:[1,0,0]
	v_pk_add_f32 v[208:209], v[210:211], v[188:189]
	v_pk_add_f32 v[188:189], v[210:211], v[188:189] neg_lo:[0,1] neg_hi:[0,1]
	v_pk_add_f32 v[210:211], v[174:175], v[158:159]
	v_pk_add_f32 v[158:159], v[174:175], v[158:159] neg_lo:[0,1] neg_hi:[0,1]
	v_xor_b32_e32 v16, 0x80000000, v13
	v_pk_mul_f32 v[174:175], v[158:159], s[24:25]
	v_mov_b32_e32 v17, v13
	v_pk_fma_f32 v[158:159], v[158:159], s[22:23], v[174:175] op_sel:[0,0,1] op_sel_hi:[1,0,0]
	v_pk_add_f32 v[174:175], v[176:177], v[192:193]
	v_pk_add_f32 v[176:177], v[176:177], v[192:193] neg_lo:[0,1] neg_hi:[0,1]
	v_pk_mul_f32 v[28:29], v[12:13], v[16:17] op_sel:[1,0] op_sel_hi:[0,1]
	v_pk_mul_f32 v[192:193], v[176:177], s[40:41]
	v_pk_fma_f32 v[28:29], v[12:13], v[12:13], v[28:29] op_sel_hi:[1,0,1]
	v_pk_fma_f32 v[176:177], v[176:177], s[38:39], v[192:193] op_sel:[0,0,1] op_sel_hi:[1,0,0]
	v_pk_add_f32 v[192:193], v[178:179], v[194:195]
	v_pk_add_f32 v[178:179], v[178:179], v[194:195] neg_lo:[0,1] neg_hi:[0,1]
	v_pk_mul_f32 v[44:45], v[16:17], v[28:29] op_sel:[0,1] op_sel_hi:[1,0]
	v_pk_mul_f32 v[194:195], v[178:179], s[44:45]
	v_pk_fma_f32 v[44:45], v[12:13], v[28:29], v[44:45] op_sel_hi:[0,1,1]
	v_pk_fma_f32 v[178:179], v[178:179], s[50:51], v[194:195] op_sel:[0,0,1] op_sel_hi:[1,0,0]
	v_pk_add_f32 v[194:195], v[180:181], v[196:197]
	v_pk_add_f32 v[196:197], v[180:181], v[196:197] neg_lo:[0,1] neg_hi:[0,1]
	v_pk_mul_f32 v[60:61], v[16:17], v[44:45] op_sel:[0,1] op_sel_hi:[1,0]
	v_pk_add_f32 v[180:181], v[182:183], v[198:199]
	v_pk_add_f32 v[182:183], v[182:183], v[198:199] neg_lo:[0,1] neg_hi:[0,1]
	v_pk_fma_f32 v[60:61], v[12:13], v[44:45], v[60:61] op_sel_hi:[0,1,1]
	v_pk_mul_f32 v[198:199], v[182:183], s[44:45]
	v_pk_mul_f32 v[76:77], v[16:17], v[60:61] op_sel:[0,1] op_sel_hi:[1,0]
	v_pk_fma_f32 v[182:183], v[182:183], s[50:51], v[198:199] op_sel:[0,0,1] op_sel_hi:[1,0,0] neg_lo:[1,0,0] neg_hi:[1,0,0]
	v_pk_add_f32 v[198:199], v[184:185], v[204:205]
	v_pk_add_f32 v[184:185], v[184:185], v[204:205] neg_lo:[0,1] neg_hi:[0,1]
	v_pk_fma_f32 v[76:77], v[12:13], v[60:61], v[76:77] op_sel_hi:[0,1,1]
	v_pk_mul_f32 v[204:205], v[184:185], s[40:41]
	v_pk_mul_f32 v[92:93], v[16:17], v[76:77] op_sel:[0,1] op_sel_hi:[1,0]
	v_pk_fma_f32 v[184:185], v[184:185], s[38:39], v[204:205] op_sel:[0,0,1] op_sel_hi:[1,0,0] neg_lo:[1,0,0] neg_hi:[1,0,0]
	v_pk_add_f32 v[204:205], v[186:187], v[206:207]
	v_pk_add_f32 v[186:187], v[186:187], v[206:207] neg_lo:[0,1] neg_hi:[0,1]
	v_pk_fma_f32 v[92:93], v[12:13], v[76:77], v[92:93] op_sel_hi:[0,1,1]
	v_pk_mul_f32 v[206:207], v[186:187], s[24:25]
	v_pk_mul_f32 v[108:109], v[16:17], v[92:93] op_sel:[0,1] op_sel_hi:[1,0]
	v_pk_fma_f32 v[186:187], v[186:187], s[22:23], v[206:207] op_sel:[0,0,1] op_sel_hi:[1,0,0] neg_lo:[1,0,0] neg_hi:[1,0,0]
	v_pk_add_f32 v[206:207], v[128:129], v[190:191] op_sel:[0,1] op_sel_hi:[1,0] neg_hi:[0,1]
	v_pk_add_f32 v[128:129], v[128:129], v[190:191] op_sel:[0,1] op_sel_hi:[1,0] neg_lo:[0,1]
	v_pk_add_f32 v[190:191], v[130:131], v[160:161]
	v_pk_add_f32 v[130:131], v[130:131], v[160:161] neg_lo:[0,1] neg_hi:[0,1]
	v_pk_mul_f32 v[10:11], v[4:5], v[8:9] op_sel:[0,1] op_sel_hi:[1,0]
	v_pk_mul_f32 v[160:161], v[130:131], s[24:25]
	v_pk_fma_f32 v[108:109], v[12:13], v[92:93], v[108:109] op_sel_hi:[0,1,1]
	v_pk_fma_f32 v[130:131], v[130:131], s[22:23], v[160:161] op_sel:[0,0,1] op_sel_hi:[1,0,0]
	v_pk_add_f32 v[160:161], v[144:145], v[162:163]
	v_pk_add_f32 v[144:145], v[144:145], v[162:163] neg_lo:[0,1] neg_hi:[0,1]
	v_pk_fma_f32 v[10:11], v[6:7], v[8:9], v[10:11] op_sel_hi:[0,1,1]
	v_pk_mul_f32 v[162:163], v[144:145], s[40:41]
	v_pk_mul_f32 v[18:19], v[4:5], v[12:13] op_sel:[0,1] op_sel_hi:[1,0]
	v_pk_fma_f32 v[144:145], v[144:145], s[38:39], v[162:163] op_sel:[0,0,1] op_sel_hi:[1,0,0]
	v_pk_add_f32 v[162:163], v[148:149], v[164:165]
	v_pk_add_f32 v[148:149], v[148:149], v[164:165] neg_lo:[0,1] neg_hi:[0,1]
	v_pk_mul_f32 v[32:33], v[4:5], v[28:29] op_sel:[0,1] op_sel_hi:[1,0]
	v_pk_mul_f32 v[164:165], v[148:149], s[44:45]
	v_pk_mul_f32 v[48:49], v[4:5], v[44:45] op_sel:[0,1] op_sel_hi:[1,0]
	v_pk_fma_f32 v[148:149], v[148:149], s[50:51], v[164:165] op_sel:[0,0,1] op_sel_hi:[1,0,0]
	v_pk_add_f32 v[164:165], v[150:151], v[166:167]
	v_pk_add_f32 v[166:167], v[150:151], v[166:167] neg_lo:[0,1] neg_hi:[0,1]
	v_pk_mul_f32 v[64:65], v[4:5], v[60:61] op_sel:[0,1] op_sel_hi:[1,0]
	v_pk_add_f32 v[150:151], v[152:153], v[168:169]
	v_pk_add_f32 v[152:153], v[152:153], v[168:169] neg_lo:[0,1] neg_hi:[0,1]
	v_pk_mul_f32 v[80:81], v[4:5], v[76:77] op_sel:[0,1] op_sel_hi:[1,0]
	v_pk_mul_f32 v[168:169], v[152:153], s[44:45]
	v_pk_mul_f32 v[96:97], v[4:5], v[92:93] op_sel:[0,1] op_sel_hi:[1,0]
	v_pk_fma_f32 v[152:153], v[152:153], s[50:51], v[168:169] op_sel:[0,0,1] op_sel_hi:[1,0,0] neg_lo:[1,0,0] neg_hi:[1,0,0]
	v_pk_add_f32 v[168:169], v[154:155], v[170:171]
	v_pk_add_f32 v[154:155], v[154:155], v[170:171] neg_lo:[0,1] neg_hi:[0,1]
	v_pk_mul_f32 v[112:113], v[4:5], v[108:109] op_sel:[0,1] op_sel_hi:[1,0]
	v_pk_mul_f32 v[170:171], v[154:155], s[40:41]
	v_xor_b32_e32 v22, 0x80000000, v11
	v_pk_fma_f32 v[154:155], v[154:155], s[38:39], v[170:171] op_sel:[0,0,1] op_sel_hi:[1,0,0] neg_lo:[1,0,0] neg_hi:[1,0,0]
	v_pk_add_f32 v[170:171], v[156:157], v[172:173]
	v_pk_add_f32 v[156:157], v[156:157], v[172:173] neg_lo:[0,1] neg_hi:[0,1]
	v_mov_b32_e32 v23, v11
	v_pk_mul_f32 v[172:173], v[156:157], s[24:25]
	v_pk_fma_f32 v[18:19], v[6:7], v[12:13], v[18:19] op_sel_hi:[0,1,1]
	v_pk_fma_f32 v[156:157], v[156:157], s[22:23], v[172:173] op_sel:[0,0,1] op_sel_hi:[1,0,0] neg_lo:[1,0,0] neg_hi:[1,0,0]
	v_pk_add_f32 v[172:173], v[208:209], v[194:195]
	v_pk_add_f32 v[194:195], v[208:209], v[194:195] neg_lo:[0,1] neg_hi:[0,1]
	v_pk_add_f32 v[208:209], v[210:211], v[180:181]
	v_pk_add_f32 v[180:181], v[210:211], v[180:181] neg_lo:[0,1] neg_hi:[0,1]
	v_pk_mul_f32 v[20:21], v[14:15], v[12:13] op_sel:[0,1] op_sel_hi:[1,0]
	v_pk_mul_f32 v[210:211], v[180:181], s[40:41]
	v_pk_fma_f32 v[32:33], v[6:7], v[28:29], v[32:33] op_sel_hi:[0,1,1]
	v_pk_fma_f32 v[180:181], v[180:181], s[38:39], v[210:211] op_sel:[0,0,1] op_sel_hi:[1,0,0]
	v_pk_add_f32 v[210:211], v[174:175], v[198:199]
	v_pk_add_f32 v[198:199], v[174:175], v[198:199] neg_lo:[0,1] neg_hi:[0,1]
	v_pk_mul_f32 v[36:37], v[14:15], v[28:29] op_sel:[0,1] op_sel_hi:[1,0]
	v_pk_add_f32 v[174:175], v[192:193], v[204:205]
	v_pk_add_f32 v[192:193], v[192:193], v[204:205] neg_lo:[0,1] neg_hi:[0,1]
	v_pk_fma_f32 v[48:49], v[6:7], v[44:45], v[48:49] op_sel_hi:[0,1,1]
	v_pk_mul_f32 v[204:205], v[192:193], s[40:41]
	v_pk_mul_f32 v[52:53], v[14:15], v[44:45] op_sel:[0,1] op_sel_hi:[1,0]
	v_pk_fma_f32 v[192:193], v[192:193], s[38:39], v[204:205] op_sel:[0,0,1] op_sel_hi:[1,0,0] neg_lo:[1,0,0] neg_hi:[1,0,0]
	v_pk_add_f32 v[204:205], v[188:189], v[196:197] op_sel:[0,1] op_sel_hi:[1,0] neg_hi:[0,1]
	v_pk_add_f32 v[188:189], v[188:189], v[196:197] op_sel:[0,1] op_sel_hi:[1,0] neg_lo:[0,1]
	v_pk_add_f32 v[196:197], v[158:159], v[182:183]
	v_pk_add_f32 v[158:159], v[158:159], v[182:183] neg_lo:[0,1] neg_hi:[0,1]
	v_pk_fma_f32 v[64:65], v[6:7], v[60:61], v[64:65] op_sel_hi:[0,1,1]
	v_pk_mul_f32 v[182:183], v[158:159], s[40:41]
	v_pk_mul_f32 v[68:69], v[14:15], v[60:61] op_sel:[0,1] op_sel_hi:[1,0]
	v_pk_fma_f32 v[158:159], v[158:159], s[38:39], v[182:183] op_sel:[0,0,1] op_sel_hi:[1,0,0]
	v_pk_add_f32 v[182:183], v[176:177], v[184:185]
	v_pk_add_f32 v[184:185], v[176:177], v[184:185] neg_lo:[0,1] neg_hi:[0,1]
	v_pk_fma_f32 v[80:81], v[6:7], v[76:77], v[80:81] op_sel_hi:[0,1,1]
	v_pk_add_f32 v[176:177], v[178:179], v[186:187]
	v_pk_add_f32 v[178:179], v[178:179], v[186:187] neg_lo:[0,1] neg_hi:[0,1]
	v_pk_mul_f32 v[84:85], v[14:15], v[76:77] op_sel:[0,1] op_sel_hi:[1,0]
	v_pk_mul_f32 v[186:187], v[178:179], s[40:41]
	v_pk_fma_f32 v[96:97], v[6:7], v[92:93], v[96:97] op_sel_hi:[0,1,1]
	v_pk_fma_f32 v[178:179], v[178:179], s[38:39], v[186:187] op_sel:[0,0,1] op_sel_hi:[1,0,0] neg_lo:[1,0,0] neg_hi:[1,0,0]
	v_pk_add_f32 v[186:187], v[206:207], v[164:165]
	v_pk_add_f32 v[164:165], v[206:207], v[164:165] neg_lo:[0,1] neg_hi:[0,1]
	v_pk_add_f32 v[206:207], v[190:191], v[150:151]
	v_pk_add_f32 v[150:151], v[190:191], v[150:151] neg_lo:[0,1] neg_hi:[0,1]
	v_pk_mul_f32 v[100:101], v[14:15], v[92:93] op_sel:[0,1] op_sel_hi:[1,0]
	v_pk_mul_f32 v[190:191], v[150:151], s[40:41]
	v_pk_fma_f32 v[112:113], v[6:7], v[108:109], v[112:113] op_sel_hi:[0,1,1]
	v_pk_fma_f32 v[150:151], v[150:151], s[38:39], v[190:191] op_sel:[0,0,1] op_sel_hi:[1,0,0]
	v_pk_add_f32 v[190:191], v[160:161], v[168:169]
	v_pk_add_f32 v[168:169], v[160:161], v[168:169] neg_lo:[0,1] neg_hi:[0,1]
	v_pk_mul_f32 v[116:117], v[14:15], v[108:109] op_sel:[0,1] op_sel_hi:[1,0]
	v_pk_add_f32 v[160:161], v[162:163], v[170:171]
	v_pk_add_f32 v[162:163], v[162:163], v[170:171] neg_lo:[0,1] neg_hi:[0,1]
	v_pk_fma_f32 v[20:21], v[8:9], v[12:13], v[20:21] op_sel_hi:[0,1,1]
	v_pk_mul_f32 v[170:171], v[162:163], s[40:41]
	v_pk_mul_f32 v[24:25], v[12:13], v[22:23] op_sel:[1,0] op_sel_hi:[0,1]
	v_pk_fma_f32 v[162:163], v[162:163], s[38:39], v[170:171] op_sel:[0,0,1] op_sel_hi:[1,0,0] neg_lo:[1,0,0] neg_hi:[1,0,0]
	v_pk_add_f32 v[170:171], v[128:129], v[166:167] op_sel:[0,1] op_sel_hi:[1,0] neg_hi:[0,1]
	v_pk_add_f32 v[128:129], v[128:129], v[166:167] op_sel:[0,1] op_sel_hi:[1,0] neg_lo:[0,1]
	v_pk_add_f32 v[166:167], v[130:131], v[152:153]
	v_pk_add_f32 v[130:131], v[130:131], v[152:153] neg_lo:[0,1] neg_hi:[0,1]
	v_pk_fma_f32 v[36:37], v[8:9], v[28:29], v[36:37] op_sel_hi:[0,1,1]
	v_pk_mul_f32 v[152:153], v[130:131], s[40:41]
	v_pk_mul_f32 v[40:41], v[22:23], v[28:29] op_sel:[0,1] op_sel_hi:[1,0]
	v_pk_fma_f32 v[130:131], v[130:131], s[38:39], v[152:153] op_sel:[0,0,1] op_sel_hi:[1,0,0]
	v_pk_add_f32 v[152:153], v[144:145], v[154:155]
	v_pk_add_f32 v[154:155], v[144:145], v[154:155] neg_lo:[0,1] neg_hi:[0,1]
	v_pk_fma_f32 v[52:53], v[8:9], v[44:45], v[52:53] op_sel_hi:[0,1,1]
	v_pk_add_f32 v[144:145], v[148:149], v[156:157]
	v_pk_add_f32 v[148:149], v[148:149], v[156:157] neg_lo:[0,1] neg_hi:[0,1]
	v_pk_mul_f32 v[56:57], v[22:23], v[44:45] op_sel:[0,1] op_sel_hi:[1,0]
	v_pk_mul_f32 v[156:157], v[148:149], s[40:41]
	v_pk_fma_f32 v[68:69], v[8:9], v[60:61], v[68:69] op_sel_hi:[0,1,1]
	v_pk_fma_f32 v[148:149], v[148:149], s[38:39], v[156:157] op_sel:[0,0,1] op_sel_hi:[1,0,0] neg_lo:[1,0,0] neg_hi:[1,0,0]
	v_pk_add_f32 v[156:157], v[172:173], v[210:211]
	v_pk_add_f32 v[172:173], v[172:173], v[210:211] neg_lo:[0,1] neg_hi:[0,1]
	v_pk_add_f32 v[210:211], v[208:209], v[174:175]
	v_pk_add_f32 v[208:209], v[208:209], v[174:175] neg_lo:[0,1] neg_hi:[0,1]
	v_pk_mul_f32 v[72:73], v[22:23], v[60:61] op_sel:[0,1] op_sel_hi:[1,0]
	v_pk_add_f32 v[174:175], v[194:195], v[198:199] op_sel:[0,1] op_sel_hi:[1,0] neg_hi:[0,1]
	v_pk_add_f32 v[194:195], v[194:195], v[198:199] op_sel:[0,1] op_sel_hi:[1,0] neg_lo:[0,1]
	v_pk_add_f32 v[198:199], v[180:181], v[192:193]
	v_pk_add_f32 v[192:193], v[180:181], v[192:193] neg_lo:[0,1] neg_hi:[0,1]
	v_pk_fma_f32 v[84:85], v[8:9], v[76:77], v[84:85] op_sel_hi:[0,1,1]
	v_pk_add_f32 v[180:181], v[204:205], v[182:183]
	v_pk_add_f32 v[182:183], v[204:205], v[182:183] neg_lo:[0,1] neg_hi:[0,1]
	v_pk_add_f32 v[204:205], v[196:197], v[176:177]
	v_pk_add_f32 v[196:197], v[196:197], v[176:177] neg_lo:[0,1] neg_hi:[0,1]
	v_pk_mul_f32 v[88:89], v[22:23], v[76:77] op_sel:[0,1] op_sel_hi:[1,0]
	v_pk_add_f32 v[176:177], v[188:189], v[184:185] op_sel:[0,1] op_sel_hi:[1,0] neg_hi:[0,1]
	v_pk_add_f32 v[184:185], v[188:189], v[184:185] op_sel:[0,1] op_sel_hi:[1,0] neg_lo:[0,1]
	v_pk_add_f32 v[188:189], v[158:159], v[178:179]
	v_pk_add_f32 v[178:179], v[158:159], v[178:179] neg_lo:[0,1] neg_hi:[0,1]
	v_pk_fma_f32 v[100:101], v[8:9], v[92:93], v[100:101] op_sel_hi:[0,1,1]
	v_pk_add_f32 v[158:159], v[186:187], v[190:191]
	v_pk_add_f32 v[186:187], v[186:187], v[190:191] neg_lo:[0,1] neg_hi:[0,1]
	v_pk_add_f32 v[190:191], v[206:207], v[160:161]
	v_pk_add_f32 v[206:207], v[206:207], v[160:161] neg_lo:[0,1] neg_hi:[0,1]
	v_pk_mul_f32 v[104:105], v[22:23], v[92:93] op_sel:[0,1] op_sel_hi:[1,0]
	v_pk_add_f32 v[160:161], v[164:165], v[168:169] op_sel:[0,1] op_sel_hi:[1,0] neg_hi:[0,1]
	v_pk_add_f32 v[164:165], v[164:165], v[168:169] op_sel:[0,1] op_sel_hi:[1,0] neg_lo:[0,1]
	v_pk_add_f32 v[168:169], v[150:151], v[162:163]
	v_pk_add_f32 v[162:163], v[150:151], v[162:163] neg_lo:[0,1] neg_hi:[0,1]
	v_pk_fma_f32 v[116:117], v[8:9], v[108:109], v[116:117] op_sel_hi:[0,1,1]
	v_pk_add_f32 v[150:151], v[170:171], v[152:153]
	v_pk_add_f32 v[152:153], v[170:171], v[152:153] neg_lo:[0,1] neg_hi:[0,1]
	v_pk_add_f32 v[170:171], v[166:167], v[144:145]
	v_pk_add_f32 v[166:167], v[166:167], v[144:145] neg_lo:[0,1] neg_hi:[0,1]
	v_pk_mul_f32 v[120:121], v[22:23], v[108:109] op_sel:[0,1] op_sel_hi:[1,0]
	v_pk_add_f32 v[144:145], v[128:129], v[154:155] op_sel:[0,1] op_sel_hi:[1,0] neg_hi:[0,1]
	v_pk_add_f32 v[128:129], v[128:129], v[154:155] op_sel:[0,1] op_sel_hi:[1,0] neg_lo:[0,1]
	v_pk_add_f32 v[154:155], v[130:131], v[148:149]
	v_pk_add_f32 v[130:131], v[130:131], v[148:149] neg_lo:[0,1] neg_hi:[0,1]
	v_xor_b32_e32 v26, 0x80000000, v19
	v_xor_b32_e32 v149, 0x80000000, v130
	v_mov_b32_e32 v148, v131
	v_pk_add_f32 v[130:131], v[156:157], v[210:211]
	v_pk_add_f32 v[156:157], v[156:157], v[210:211] neg_lo:[0,1] neg_hi:[0,1]
	v_pk_add_f32 v[210:211], v[172:173], v[208:209] op_sel:[0,1] op_sel_hi:[1,0] neg_hi:[0,1]
	v_pk_add_f32 v[172:173], v[172:173], v[208:209] op_sel:[0,1] op_sel_hi:[1,0] neg_lo:[0,1]
	v_pk_add_f32 v[208:209], v[174:175], v[198:199]
	v_pk_add_f32 v[174:175], v[174:175], v[198:199] neg_lo:[0,1] neg_hi:[0,1]
	v_pk_add_f32 v[198:199], v[194:195], v[192:193] op_sel:[0,1] op_sel_hi:[1,0] neg_hi:[0,1]
	v_pk_add_f32 v[192:193], v[194:195], v[192:193] op_sel:[0,1] op_sel_hi:[1,0] neg_lo:[0,1]
	v_pk_add_f32 v[194:195], v[180:181], v[204:205]
	v_pk_add_f32 v[180:181], v[180:181], v[204:205] neg_lo:[0,1] neg_hi:[0,1]
	v_pk_add_f32 v[204:205], v[182:183], v[196:197] op_sel:[0,1] op_sel_hi:[1,0] neg_hi:[0,1]
	v_pk_add_f32 v[182:183], v[182:183], v[196:197] op_sel:[0,1] op_sel_hi:[1,0] neg_lo:[0,1]
	v_pk_add_f32 v[196:197], v[176:177], v[188:189]
	v_pk_add_f32 v[176:177], v[176:177], v[188:189] neg_lo:[0,1] neg_hi:[0,1]
	v_pk_add_f32 v[188:189], v[184:185], v[178:179] op_sel:[0,1] op_sel_hi:[1,0] neg_hi:[0,1]
	v_pk_add_f32 v[178:179], v[184:185], v[178:179] op_sel:[0,1] op_sel_hi:[1,0] neg_lo:[0,1]
	v_pk_add_f32 v[184:185], v[158:159], v[190:191]
	v_pk_add_f32 v[158:159], v[158:159], v[190:191] neg_lo:[0,1] neg_hi:[0,1]
	v_pk_mul_f32 v[4:5], v[4:5], v[184:185] op_sel:[0,1] op_sel_hi:[1,0]
	v_pk_add_f32 v[190:191], v[186:187], v[206:207] op_sel:[0,1] op_sel_hi:[1,0] neg_hi:[0,1]
	v_pk_add_f32 v[186:187], v[186:187], v[206:207] op_sel:[0,1] op_sel_hi:[1,0] neg_lo:[0,1]
	v_pk_add_f32 v[206:207], v[160:161], v[168:169]
	v_pk_add_f32 v[160:161], v[160:161], v[168:169] neg_lo:[0,1] neg_hi:[0,1]
	v_pk_add_f32 v[168:169], v[164:165], v[162:163] op_sel:[0,1] op_sel_hi:[1,0] neg_hi:[0,1]
	v_pk_add_f32 v[162:163], v[164:165], v[162:163] op_sel:[0,1] op_sel_hi:[1,0] neg_lo:[0,1]
	v_pk_add_f32 v[164:165], v[150:151], v[170:171]
	v_pk_fma_f32 v[4:5], v[6:7], v[184:185], v[4:5] op_sel_hi:[0,1,1]
	v_pk_mul_f32 v[6:7], v[14:15], v[194:195] op_sel:[0,1] op_sel_hi:[1,0]
	v_xor_b32_e32 v30, 0x80000000, v21
	v_pk_fma_f32 v[6:7], v[8:9], v[194:195], v[6:7] op_sel_hi:[0,1,1]
	v_pk_mul_f32 v[8:9], v[22:23], v[164:165] op_sel:[0,1] op_sel_hi:[1,0]
	v_pk_fma_f32 v[24:25], v[12:13], v[10:11], v[24:25] op_sel_hi:[1,0,1]
	v_pk_fma_f32 v[40:41], v[10:11], v[28:29], v[40:41] op_sel_hi:[0,1,1]
	v_pk_fma_f32 v[56:57], v[10:11], v[44:45], v[56:57] op_sel_hi:[0,1,1]
	v_pk_fma_f32 v[72:73], v[10:11], v[60:61], v[72:73] op_sel_hi:[0,1,1]
	v_pk_fma_f32 v[88:89], v[10:11], v[76:77], v[88:89] op_sel_hi:[0,1,1]
	v_pk_fma_f32 v[104:105], v[10:11], v[92:93], v[104:105] op_sel_hi:[0,1,1]
	v_pk_fma_f32 v[120:121], v[10:11], v[108:109], v[120:121] op_sel_hi:[0,1,1]
	v_mov_b32_e32 v27, v19
	v_mov_b32_e32 v31, v21
	v_pk_fma_f32 v[8:9], v[10:11], v[164:165], v[8:9] op_sel_hi:[0,1,1]
	v_pk_mul_f32 v[10:11], v[16:17], v[208:209] op_sel:[0,1] op_sel_hi:[1,0]
	v_xor_b32_e32 v34, 0x80000000, v25
	v_xor_b32_e32 v38, 0x80000000, v29
	v_xor_b32_e32 v42, 0x80000000, v33
	v_xor_b32_e32 v46, 0x80000000, v37
	v_mov_b32_e32 v35, v25
	v_mov_b32_e32 v39, v29
	v_mov_b32_e32 v43, v33
	v_mov_b32_e32 v47, v37
	v_pk_add_f32 v[150:151], v[150:151], v[170:171] neg_lo:[0,1] neg_hi:[0,1]
	v_pk_add_f32 v[170:171], v[152:153], v[166:167] op_sel:[0,1] op_sel_hi:[1,0] neg_hi:[0,1]
	v_pk_add_f32 v[152:153], v[152:153], v[166:167] op_sel:[0,1] op_sel_hi:[1,0] neg_lo:[0,1]
	v_pk_add_f32 v[166:167], v[144:145], v[154:155]
	v_pk_fma_f32 v[10:11], v[12:13], v[208:209], v[10:11] op_sel_hi:[0,1,1]
	v_pk_mul_f32 v[12:13], v[26:27], v[206:207] op_sel:[0,1] op_sel_hi:[1,0]
	v_pk_mul_f32 v[14:15], v[30:31], v[196:197] op_sel:[0,1] op_sel_hi:[1,0]
	v_xor_b32_e32 v50, 0x80000000, v41
	v_xor_b32_e32 v54, 0x80000000, v45
	v_xor_b32_e32 v58, 0x80000000, v49
	v_xor_b32_e32 v62, 0x80000000, v53
	v_xor_b32_e32 v66, 0x80000000, v57
	v_xor_b32_e32 v70, 0x80000000, v61
	v_xor_b32_e32 v74, 0x80000000, v65
	v_mov_b32_e32 v51, v41
	v_mov_b32_e32 v55, v45
	v_mov_b32_e32 v59, v49
	v_mov_b32_e32 v63, v53
	v_mov_b32_e32 v67, v57
	v_mov_b32_e32 v71, v61
	v_mov_b32_e32 v75, v65
	v_pk_add_f32 v[144:145], v[144:145], v[154:155] neg_lo:[0,1] neg_hi:[0,1]
	v_pk_add_f32 v[154:155], v[128:129], v[148:149]
	v_pk_fma_f32 v[12:13], v[18:19], v[206:207], v[12:13] op_sel_hi:[0,1,1]
	v_pk_fma_f32 v[14:15], v[20:21], v[196:197], v[14:15] op_sel_hi:[0,1,1]
	v_pk_mul_f32 v[16:17], v[34:35], v[166:167] op_sel:[0,1] op_sel_hi:[1,0]
	v_pk_mul_f32 v[18:19], v[38:39], v[210:211] op_sel:[0,1] op_sel_hi:[1,0]
	v_pk_mul_f32 v[20:21], v[42:43], v[190:191] op_sel:[0,1] op_sel_hi:[1,0]
	v_pk_mul_f32 v[22:23], v[46:47], v[204:205] op_sel:[0,1] op_sel_hi:[1,0]
	v_xor_b32_e32 v78, 0x80000000, v69
	v_xor_b32_e32 v82, 0x80000000, v73
	v_xor_b32_e32 v86, 0x80000000, v77
	v_xor_b32_e32 v90, 0x80000000, v81
	v_xor_b32_e32 v94, 0x80000000, v85
	v_xor_b32_e32 v98, 0x80000000, v89
	v_xor_b32_e32 v102, 0x80000000, v93
	v_xor_b32_e32 v106, 0x80000000, v97
	v_xor_b32_e32 v110, 0x80000000, v101
	v_xor_b32_e32 v114, 0x80000000, v105
	v_xor_b32_e32 v118, 0x80000000, v109
	v_xor_b32_e32 v122, 0x80000000, v113
	v_xor_b32_e32 v124, 0x80000000, v117
	v_xor_b32_e32 v126, 0x80000000, v121
	v_mov_b32_e32 v79, v69
	v_mov_b32_e32 v83, v73
	v_mov_b32_e32 v87, v77
	v_mov_b32_e32 v91, v81
	v_mov_b32_e32 v95, v85
	v_mov_b32_e32 v99, v89
	v_mov_b32_e32 v103, v93
	v_mov_b32_e32 v107, v97
	v_mov_b32_e32 v111, v101
	v_mov_b32_e32 v115, v105
	v_mov_b32_e32 v119, v109
	v_mov_b32_e32 v123, v113
	v_mov_b32_e32 v125, v117
	v_mov_b32_e32 v127, v121
	v_pk_add_f32 v[128:129], v[128:129], v[148:149] neg_lo:[0,1] neg_hi:[0,1]
	v_pk_fma_f32 v[16:17], v[24:25], v[166:167], v[16:17] op_sel_hi:[0,1,1]
	v_pk_fma_f32 v[18:19], v[28:29], v[210:211], v[18:19] op_sel_hi:[0,1,1]
	v_pk_fma_f32 v[20:21], v[32:33], v[190:191], v[20:21] op_sel_hi:[0,1,1]
	v_pk_fma_f32 v[22:23], v[36:37], v[204:205], v[22:23] op_sel_hi:[0,1,1]
	v_pk_mul_f32 v[24:25], v[50:51], v[170:171] op_sel:[0,1] op_sel_hi:[1,0]
	v_pk_mul_f32 v[26:27], v[54:55], v[198:199] op_sel:[0,1] op_sel_hi:[1,0]
	v_pk_mul_f32 v[28:29], v[58:59], v[168:169] op_sel:[0,1] op_sel_hi:[1,0]
	v_pk_mul_f32 v[30:31], v[62:63], v[188:189] op_sel:[0,1] op_sel_hi:[1,0]
	v_pk_mul_f32 v[32:33], v[66:67], v[154:155] op_sel:[0,1] op_sel_hi:[1,0]
	v_pk_mul_f32 v[34:35], v[70:71], v[156:157] op_sel:[0,1] op_sel_hi:[1,0]
	v_pk_mul_f32 v[36:37], v[74:75], v[158:159] op_sel:[0,1] op_sel_hi:[1,0]
	v_pk_fma_f32 v[24:25], v[40:41], v[170:171], v[24:25] op_sel_hi:[0,1,1]
	v_pk_fma_f32 v[26:27], v[44:45], v[198:199], v[26:27] op_sel_hi:[0,1,1]
	v_pk_fma_f32 v[28:29], v[48:49], v[168:169], v[28:29] op_sel_hi:[0,1,1]
	v_pk_fma_f32 v[30:31], v[52:53], v[188:189], v[30:31] op_sel_hi:[0,1,1]
	v_pk_fma_f32 v[32:33], v[56:57], v[154:155], v[32:33] op_sel_hi:[0,1,1]
	v_pk_fma_f32 v[34:35], v[60:61], v[156:157], v[34:35] op_sel_hi:[0,1,1]
	v_pk_fma_f32 v[36:37], v[64:65], v[158:159], v[36:37] op_sel_hi:[0,1,1]
	v_pk_mul_f32 v[38:39], v[78:79], v[180:181] op_sel:[0,1] op_sel_hi:[1,0]
	v_pk_mul_f32 v[40:41], v[82:83], v[150:151] op_sel:[0,1] op_sel_hi:[1,0]
	v_pk_mul_f32 v[42:43], v[86:87], v[174:175] op_sel:[0,1] op_sel_hi:[1,0]
	v_pk_mul_f32 v[44:45], v[90:91], v[160:161] op_sel:[0,1] op_sel_hi:[1,0]
	v_pk_mul_f32 v[46:47], v[94:95], v[176:177] op_sel:[0,1] op_sel_hi:[1,0]
	v_pk_mul_f32 v[48:49], v[98:99], v[144:145] op_sel:[0,1] op_sel_hi:[1,0]
	v_pk_mul_f32 v[50:51], v[102:103], v[172:173] op_sel:[0,1] op_sel_hi:[1,0]
	v_pk_mul_f32 v[52:53], v[106:107], v[186:187] op_sel:[0,1] op_sel_hi:[1,0]
	v_pk_mul_f32 v[54:55], v[110:111], v[182:183] op_sel:[0,1] op_sel_hi:[1,0]
	v_pk_mul_f32 v[56:57], v[114:115], v[152:153] op_sel:[0,1] op_sel_hi:[1,0]
	v_pk_mul_f32 v[58:59], v[118:119], v[192:193] op_sel:[0,1] op_sel_hi:[1,0]
	v_pk_mul_f32 v[60:61], v[122:123], v[162:163] op_sel:[0,1] op_sel_hi:[1,0]
	v_pk_mul_f32 v[62:63], v[124:125], v[178:179] op_sel:[0,1] op_sel_hi:[1,0]
	v_pk_mul_f32 v[64:65], v[126:127], v[128:129] op_sel:[0,1] op_sel_hi:[1,0]
	v_pk_fma_f32 v[38:39], v[68:69], v[180:181], v[38:39] op_sel_hi:[0,1,1]
	v_pk_fma_f32 v[40:41], v[72:73], v[150:151], v[40:41] op_sel_hi:[0,1,1]
	v_pk_fma_f32 v[42:43], v[76:77], v[174:175], v[42:43] op_sel_hi:[0,1,1]
	v_pk_fma_f32 v[44:45], v[80:81], v[160:161], v[44:45] op_sel_hi:[0,1,1]
	v_pk_fma_f32 v[46:47], v[84:85], v[176:177], v[46:47] op_sel_hi:[0,1,1]
	v_pk_fma_f32 v[48:49], v[88:89], v[144:145], v[48:49] op_sel_hi:[0,1,1]
	v_pk_fma_f32 v[50:51], v[92:93], v[172:173], v[50:51] op_sel_hi:[0,1,1]
	v_pk_fma_f32 v[52:53], v[96:97], v[186:187], v[52:53] op_sel_hi:[0,1,1]
	v_pk_fma_f32 v[54:55], v[100:101], v[182:183], v[54:55] op_sel_hi:[0,1,1]
	v_pk_fma_f32 v[56:57], v[104:105], v[152:153], v[56:57] op_sel_hi:[0,1,1]
	v_pk_fma_f32 v[58:59], v[108:109], v[192:193], v[58:59] op_sel_hi:[0,1,1]
	v_pk_fma_f32 v[60:61], v[112:113], v[162:163], v[60:61] op_sel_hi:[0,1,1]
	v_pk_fma_f32 v[62:63], v[116:117], v[178:179], v[62:63] op_sel_hi:[0,1,1]
	v_pk_fma_f32 v[64:65], v[120:121], v[128:129], v[64:65] op_sel_hi:[0,1,1]
	ds_write_b64 v2, v[130:131]
	ds_write_b64 v2, v[34:35] offset:4224
	ds_write_b64 v2, v[18:19] offset:8448
	ds_write_b64 v2, v[50:51] offset:12672
	ds_write_b64 v2, v[10:11] offset:16896
	ds_write_b64 v2, v[42:43] offset:21120
	ds_write_b64 v2, v[26:27] offset:25344
	ds_write_b64 v2, v[58:59] offset:29568
	ds_write_b64 v2, v[6:7] offset:33792
	ds_write_b64 v2, v[38:39] offset:38016
	ds_write_b64 v2, v[22:23] offset:42240
	ds_write_b64 v2, v[54:55] offset:46464
	ds_write_b64 v2, v[14:15] offset:50688
	ds_write_b64 v2, v[46:47] offset:54912
	ds_write_b64 v2, v[30:31] offset:59136
	ds_write_b64 v2, v[62:63] offset:63360
	ds_write_b64 v143, v[4:5]
	ds_write_b64 v212, v[36:37]
	ds_write_b64 v213, v[20:21]
	ds_write_b64 v214, v[52:53]
	ds_write_b64 v215, v[12:13]
	ds_write_b64 v216, v[44:45]
	ds_write_b64 v217, v[28:29]
	ds_write_b64 v218, v[60:61]
	ds_write_b64 v219, v[8:9]
	ds_write_b64 v220, v[40:41]
	ds_write_b64 v221, v[24:25]
	ds_write_b64 v222, v[56:57]
	ds_write_b64 v223, v[16:17]
	ds_write_b64 v224, v[48:49]
	ds_write_b64 v225, v[32:33]
	ds_write_b64 v226, v[64:65]
	v_mov_b32_e32 v2, v142
	s_waitcnt lgkmcnt(0)
	s_barrier
	s_nop 0
	v_and_b32_e32 v4, 15, v2
	v_lshlrev_b32_e32 v2, 5, v2
	v_and_b32_e32 v2, 0xfffffe00, v2
	v_lshl_add_u32 v5, v2, 3, 0
	v_lshlrev_b32_e32 v7, 3, v4
	v_ashrrev_i32_e32 v2, 2, v2
	v_add3_u32 v2, v5, v7, v2
	v_add_u32_e32 v143, 0x800, v2
	ds_read2_b64 v[128:131], v2 offset1:16
	ds_read2_b64 v[148:151], v2 offset0:33 offset1:49
	ds_read2_b64 v[152:155], v2 offset0:66 offset1:82
	ds_read2_b64 v[156:159], v2 offset0:99 offset1:115
	ds_read2_b64 v[160:163], v2 offset0:132 offset1:148
	ds_read2_b64 v[164:167], v2 offset0:165 offset1:181
	ds_read2_b64 v[168:171], v2 offset0:198 offset1:214
	ds_read2_b64 v[172:175], v2 offset0:231 offset1:247
	ds_read2_b64 v[176:179], v143 offset0:8 offset1:24
	ds_read2_b64 v[180:183], v143 offset0:41 offset1:57
	ds_read2_b64 v[184:187], v143 offset0:74 offset1:90
	ds_read2_b64 v[188:191], v143 offset0:107 offset1:123
	ds_read2_b64 v[192:195], v143 offset0:140 offset1:156
	ds_read2_b64 v[196:199], v143 offset0:173 offset1:189
	ds_read2_b64 v[204:207], v143 offset0:206 offset1:222
	ds_read2_b64 v[208:211], v143 offset0:239 offset1:255
	s_waitcnt lgkmcnt(7)
	v_pk_add_f32 v[144:145], v[128:129], v[176:177]
	v_pk_add_f32 v[128:129], v[128:129], v[176:177] neg_lo:[0,1] neg_hi:[0,1]
	v_pk_add_f32 v[176:177], v[130:131], v[178:179]
	v_pk_add_f32 v[130:131], v[130:131], v[178:179] neg_lo:[0,1] neg_hi:[0,1]
	v_cvt_f32_ubyte0_e32 v4, v4
	v_pk_mul_f32 v[178:179], v[130:131], s[20:21]
	v_mul_f32_e32 v6, 0x3b000000, v4
	v_pk_fma_f32 v[130:131], v[130:131], s[10:11], v[178:179] op_sel:[0,0,1] op_sel_hi:[1,0,0]
	s_waitcnt lgkmcnt(6)
	v_pk_add_f32 v[178:179], v[148:149], v[180:181]
	v_pk_add_f32 v[148:149], v[148:149], v[180:181] neg_lo:[0,1] neg_hi:[0,1]
	v_sin_f32_e32 v4, v6
	v_pk_mul_f32 v[180:181], v[148:149], s[24:25]
	v_cos_f32_e32 v6, v6
	v_pk_fma_f32 v[148:149], v[148:149], s[22:23], v[180:181] op_sel:[0,0,1] op_sel_hi:[1,0,0]
	v_pk_add_f32 v[180:181], v[150:151], v[182:183]
	v_pk_add_f32 v[150:151], v[150:151], v[182:183] neg_lo:[0,1] neg_hi:[0,1]
	v_xor_b32_e32 v7, 0x80000000, v4
	v_pk_mul_f32 v[182:183], v[150:151], s[36:37]
	v_mov_b32_e32 v5, v7
	v_pk_fma_f32 v[150:151], v[150:151], s[26:27], v[182:183] op_sel:[0,0,1] op_sel_hi:[1,0,0]
	s_waitcnt lgkmcnt(5)
	v_pk_add_f32 v[182:183], v[152:153], v[184:185]
	v_pk_add_f32 v[152:153], v[152:153], v[184:185] neg_lo:[0,1] neg_hi:[0,1]
	v_pk_mul_f32 v[8:9], v[6:7], v[4:5] op_sel:[1,0] op_sel_hi:[0,1]
	v_pk_mul_f32 v[184:185], v[152:153], s[40:41]
	v_pk_fma_f32 v[8:9], v[6:7], v[6:7], v[8:9] op_sel_hi:[1,0,1]
	v_pk_fma_f32 v[152:153], v[152:153], s[38:39], v[184:185] op_sel:[0,0,1] op_sel_hi:[1,0,0]
	v_pk_add_f32 v[184:185], v[154:155], v[186:187]
	v_pk_add_f32 v[154:155], v[154:155], v[186:187] neg_lo:[0,1] neg_hi:[0,1]
	v_xor_b32_e32 v14, 0x80000000, v9
	v_pk_mul_f32 v[186:187], v[154:155], s[42:43]
	v_mov_b32_e32 v15, v9
	v_pk_fma_f32 v[154:155], v[154:155], s[0:1], v[186:187] op_sel:[0,0,1] op_sel_hi:[1,0,0]
	s_waitcnt lgkmcnt(4)
	v_pk_add_f32 v[186:187], v[156:157], v[188:189]
	v_pk_add_f32 v[156:157], v[156:157], v[188:189] neg_lo:[0,1] neg_hi:[0,1]
	v_pk_mul_f32 v[12:13], v[8:9], v[14:15] op_sel:[1,0] op_sel_hi:[0,1]
	v_pk_mul_f32 v[188:189], v[156:157], s[44:45]
	v_pk_fma_f32 v[12:13], v[8:9], v[8:9], v[12:13] op_sel_hi:[1,0,1]
	v_pk_fma_f32 v[156:157], v[156:157], s[50:51], v[188:189] op_sel:[0,0,1] op_sel_hi:[1,0,0]
	v_pk_add_f32 v[188:189], v[158:159], v[190:191]
	v_pk_add_f32 v[158:159], v[158:159], v[190:191] neg_lo:[0,1] neg_hi:[0,1]
	v_xor_b32_e32 v16, 0x80000000, v13
	v_pk_mul_f32 v[190:191], v[158:159], s[8:9]
	v_mov_b32_e32 v17, v13
	v_pk_fma_f32 v[158:159], v[158:159], s[16:17], v[190:191] op_sel:[0,0,1] op_sel_hi:[1,0,0]
	s_waitcnt lgkmcnt(3)
	v_pk_add_f32 v[190:191], v[160:161], v[192:193]
	v_pk_add_f32 v[192:193], v[160:161], v[192:193] neg_lo:[0,1] neg_hi:[0,1]
	v_pk_mul_f32 v[28:29], v[12:13], v[16:17] op_sel:[1,0] op_sel_hi:[0,1]
	v_pk_add_f32 v[160:161], v[162:163], v[194:195]
	v_pk_add_f32 v[162:163], v[162:163], v[194:195] neg_lo:[0,1] neg_hi:[0,1]
	v_pk_fma_f32 v[28:29], v[12:13], v[12:13], v[28:29] op_sel_hi:[1,0,1]
	v_pk_mul_f32 v[194:195], v[162:163], s[8:9]
	v_pk_mul_f32 v[44:45], v[16:17], v[28:29] op_sel:[0,1] op_sel_hi:[1,0]
	v_pk_fma_f32 v[162:163], v[162:163], s[16:17], v[194:195] op_sel:[0,0,1] op_sel_hi:[1,0,0] neg_lo:[1,0,0] neg_hi:[1,0,0]
	s_waitcnt lgkmcnt(2)
	v_pk_add_f32 v[194:195], v[164:165], v[196:197]
	v_pk_add_f32 v[164:165], v[164:165], v[196:197] neg_lo:[0,1] neg_hi:[0,1]
	v_pk_fma_f32 v[44:45], v[12:13], v[28:29], v[44:45] op_sel_hi:[0,1,1]
	v_pk_mul_f32 v[196:197], v[164:165], s[44:45]
	v_pk_mul_f32 v[60:61], v[16:17], v[44:45] op_sel:[0,1] op_sel_hi:[1,0]
	v_pk_fma_f32 v[164:165], v[164:165], s[50:51], v[196:197] op_sel:[0,0,1] op_sel_hi:[1,0,0] neg_lo:[1,0,0] neg_hi:[1,0,0]
	v_pk_add_f32 v[196:197], v[166:167], v[198:199]
	v_pk_add_f32 v[166:167], v[166:167], v[198:199] neg_lo:[0,1] neg_hi:[0,1]
	v_pk_fma_f32 v[60:61], v[12:13], v[44:45], v[60:61] op_sel_hi:[0,1,1]
	v_pk_mul_f32 v[198:199], v[166:167], s[42:43]
	v_pk_mul_f32 v[76:77], v[16:17], v[60:61] op_sel:[0,1] op_sel_hi:[1,0]
	v_pk_fma_f32 v[166:167], v[166:167], s[0:1], v[198:199] op_sel:[0,0,1] op_sel_hi:[1,0,0] neg_lo:[1,0,0] neg_hi:[1,0,0]
	s_waitcnt lgkmcnt(1)
	v_pk_add_f32 v[198:199], v[168:169], v[204:205]
	v_pk_add_f32 v[168:169], v[168:169], v[204:205] neg_lo:[0,1] neg_hi:[0,1]
	v_pk_fma_f32 v[76:77], v[12:13], v[60:61], v[76:77] op_sel_hi:[0,1,1]
	v_pk_mul_f32 v[204:205], v[168:169], s[40:41]
	v_pk_mul_f32 v[92:93], v[16:17], v[76:77] op_sel:[0,1] op_sel_hi:[1,0]
	v_pk_fma_f32 v[168:169], v[168:169], s[38:39], v[204:205] op_sel:[0,0,1] op_sel_hi:[1,0,0] neg_lo:[1,0,0] neg_hi:[1,0,0]
	v_pk_add_f32 v[204:205], v[170:171], v[206:207]
	v_pk_add_f32 v[170:171], v[170:171], v[206:207] neg_lo:[0,1] neg_hi:[0,1]
	v_pk_fma_f32 v[92:93], v[12:13], v[76:77], v[92:93] op_sel_hi:[0,1,1]
	v_pk_mul_f32 v[206:207], v[170:171], s[36:37]
	v_pk_mul_f32 v[108:109], v[16:17], v[92:93] op_sel:[0,1] op_sel_hi:[1,0]
	v_pk_fma_f32 v[170:171], v[170:171], s[26:27], v[206:207] op_sel:[0,0,1] op_sel_hi:[1,0,0] neg_lo:[1,0,0] neg_hi:[1,0,0]
	s_waitcnt lgkmcnt(0)
	v_pk_add_f32 v[206:207], v[172:173], v[208:209]
	v_pk_add_f32 v[172:173], v[172:173], v[208:209] neg_lo:[0,1] neg_hi:[0,1]
	v_pk_mul_f32 v[10:11], v[4:5], v[8:9] op_sel:[0,1] op_sel_hi:[1,0]
	v_pk_mul_f32 v[208:209], v[172:173], s[24:25]
	v_pk_fma_f32 v[108:109], v[12:13], v[92:93], v[108:109] op_sel_hi:[0,1,1]
	v_pk_fma_f32 v[172:173], v[172:173], s[22:23], v[208:209] op_sel:[0,0,1] op_sel_hi:[1,0,0] neg_lo:[1,0,0] neg_hi:[1,0,0]
	v_pk_add_f32 v[208:209], v[174:175], v[210:211]
	v_pk_add_f32 v[174:175], v[174:175], v[210:211] neg_lo:[0,1] neg_hi:[0,1]
	v_pk_fma_f32 v[10:11], v[6:7], v[8:9], v[10:11] op_sel_hi:[0,1,1]
	v_pk_mul_f32 v[210:211], v[174:175], s[20:21]
	v_pk_mul_f32 v[18:19], v[4:5], v[12:13] op_sel:[0,1] op_sel_hi:[1,0]
	v_pk_fma_f32 v[174:175], v[174:175], s[10:11], v[210:211] op_sel:[0,0,1] op_sel_hi:[1,0,0] neg_lo:[1,0,0] neg_hi:[1,0,0]
	v_pk_add_f32 v[210:211], v[144:145], v[190:191]
	v_pk_add_f32 v[144:145], v[144:145], v[190:191] neg_lo:[0,1] neg_hi:[0,1]
	v_pk_add_f32 v[190:191], v[176:177], v[160:161]
	v_pk_add_f32 v[160:161], v[176:177], v[160:161] neg_lo:[0,1] neg_hi:[0,1]
	v_pk_mul_f32 v[32:33], v[4:5], v[28:29] op_sel:[0,1] op_sel_hi:[1,0]
	v_pk_mul_f32 v[176:177], v[160:161], s[24:25]
	v_pk_mul_f32 v[48:49], v[4:5], v[44:45] op_sel:[0,1] op_sel_hi:[1,0]
	v_pk_fma_f32 v[160:161], v[160:161], s[22:23], v[176:177] op_sel:[0,0,1] op_sel_hi:[1,0,0]
	v_pk_add_f32 v[176:177], v[178:179], v[194:195]
	v_pk_add_f32 v[178:179], v[178:179], v[194:195] neg_lo:[0,1] neg_hi:[0,1]
	v_pk_mul_f32 v[64:65], v[4:5], v[60:61] op_sel:[0,1] op_sel_hi:[1,0]
	v_pk_mul_f32 v[194:195], v[178:179], s[40:41]
	v_pk_mul_f32 v[80:81], v[4:5], v[76:77] op_sel:[0,1] op_sel_hi:[1,0]
	v_pk_fma_f32 v[178:179], v[178:179], s[38:39], v[194:195] op_sel:[0,0,1] op_sel_hi:[1,0,0]
	v_pk_add_f32 v[194:195], v[180:181], v[196:197]
	v_pk_add_f32 v[180:181], v[180:181], v[196:197] neg_lo:[0,1] neg_hi:[0,1]
	v_pk_mul_f32 v[96:97], v[4:5], v[92:93] op_sel:[0,1] op_sel_hi:[1,0]
	v_pk_mul_f32 v[196:197], v[180:181], s[44:45]
	v_pk_mul_f32 v[112:113], v[4:5], v[108:109] op_sel:[0,1] op_sel_hi:[1,0]
	v_pk_fma_f32 v[180:181], v[180:181], s[50:51], v[196:197] op_sel:[0,0,1] op_sel_hi:[1,0,0]
	v_pk_add_f32 v[196:197], v[182:183], v[198:199]
	v_pk_add_f32 v[198:199], v[182:183], v[198:199] neg_lo:[0,1] neg_hi:[0,1]
	v_xor_b32_e32 v22, 0x80000000, v11
	v_pk_add_f32 v[182:183], v[184:185], v[204:205]
	v_pk_add_f32 v[184:185], v[184:185], v[204:205] neg_lo:[0,1] neg_hi:[0,1]
	v_mov_b32_e32 v23, v11
	v_pk_mul_f32 v[204:205], v[184:185], s[44:45]
	v_pk_fma_f32 v[18:19], v[6:7], v[12:13], v[18:19] op_sel_hi:[0,1,1]
	v_pk_fma_f32 v[184:185], v[184:185], s[50:51], v[204:205] op_sel:[0,0,1] op_sel_hi:[1,0,0] neg_lo:[1,0,0] neg_hi:[1,0,0]
	v_pk_add_f32 v[204:205], v[186:187], v[206:207]
	v_pk_add_f32 v[186:187], v[186:187], v[206:207] neg_lo:[0,1] neg_hi:[0,1]
	v_pk_mul_f32 v[20:21], v[14:15], v[12:13] op_sel:[0,1] op_sel_hi:[1,0]
	v_pk_mul_f32 v[206:207], v[186:187], s[40:41]
	v_pk_fma_f32 v[32:33], v[6:7], v[28:29], v[32:33] op_sel_hi:[0,1,1]
	v_pk_fma_f32 v[186:187], v[186:187], s[38:39], v[206:207] op_sel:[0,0,1] op_sel_hi:[1,0,0] neg_lo:[1,0,0] neg_hi:[1,0,0]
	v_pk_add_f32 v[206:207], v[188:189], v[208:209]
	v_pk_add_f32 v[188:189], v[188:189], v[208:209] neg_lo:[0,1] neg_hi:[0,1]
	v_pk_mul_f32 v[36:37], v[14:15], v[28:29] op_sel:[0,1] op_sel_hi:[1,0]
	v_pk_mul_f32 v[208:209], v[188:189], s[24:25]
	v_pk_fma_f32 v[48:49], v[6:7], v[44:45], v[48:49] op_sel_hi:[0,1,1]
	v_pk_fma_f32 v[188:189], v[188:189], s[22:23], v[208:209] op_sel:[0,0,1] op_sel_hi:[1,0,0] neg_lo:[1,0,0] neg_hi:[1,0,0]
	v_pk_add_f32 v[208:209], v[128:129], v[192:193] op_sel:[0,1] op_sel_hi:[1,0] neg_hi:[0,1]
	v_pk_add_f32 v[128:129], v[128:129], v[192:193] op_sel:[0,1] op_sel_hi:[1,0] neg_lo:[0,1]
	v_pk_add_f32 v[192:193], v[130:131], v[162:163]
	v_pk_add_f32 v[130:131], v[130:131], v[162:163] neg_lo:[0,1] neg_hi:[0,1]
	v_pk_mul_f32 v[52:53], v[14:15], v[44:45] op_sel:[0,1] op_sel_hi:[1,0]
	v_pk_mul_f32 v[162:163], v[130:131], s[24:25]
	v_pk_fma_f32 v[64:65], v[6:7], v[60:61], v[64:65] op_sel_hi:[0,1,1]
	v_pk_fma_f32 v[130:131], v[130:131], s[22:23], v[162:163] op_sel:[0,0,1] op_sel_hi:[1,0,0]
	v_pk_add_f32 v[162:163], v[148:149], v[164:165]
	v_pk_add_f32 v[148:149], v[148:149], v[164:165] neg_lo:[0,1] neg_hi:[0,1]
	v_pk_mul_f32 v[68:69], v[14:15], v[60:61] op_sel:[0,1] op_sel_hi:[1,0]
	v_pk_mul_f32 v[164:165], v[148:149], s[40:41]
	v_pk_fma_f32 v[80:81], v[6:7], v[76:77], v[80:81] op_sel_hi:[0,1,1]
	v_pk_fma_f32 v[148:149], v[148:149], s[38:39], v[164:165] op_sel:[0,0,1] op_sel_hi:[1,0,0]
	v_pk_add_f32 v[164:165], v[150:151], v[166:167]
	v_pk_add_f32 v[150:151], v[150:151], v[166:167] neg_lo:[0,1] neg_hi:[0,1]
	v_pk_mul_f32 v[84:85], v[14:15], v[76:77] op_sel:[0,1] op_sel_hi:[1,0]
	v_pk_mul_f32 v[166:167], v[150:151], s[44:45]
	v_pk_fma_f32 v[96:97], v[6:7], v[92:93], v[96:97] op_sel_hi:[0,1,1]
	v_pk_fma_f32 v[150:151], v[150:151], s[50:51], v[166:167] op_sel:[0,0,1] op_sel_hi:[1,0,0]
	v_pk_add_f32 v[166:167], v[152:153], v[168:169]
	v_pk_add_f32 v[168:169], v[152:153], v[168:169] neg_lo:[0,1] neg_hi:[0,1]
	v_pk_mul_f32 v[100:101], v[14:15], v[92:93] op_sel:[0,1] op_sel_hi:[1,0]
	v_pk_add_f32 v[152:153], v[154:155], v[170:171]
	v_pk_add_f32 v[154:155], v[154:155], v[170:171] neg_lo:[0,1] neg_hi:[0,1]
	v_pk_fma_f32 v[112:113], v[6:7], v[108:109], v[112:113] op_sel_hi:[0,1,1]
	v_pk_mul_f32 v[170:171], v[154:155], s[44:45]
	v_pk_mul_f32 v[116:117], v[14:15], v[108:109] op_sel:[0,1] op_sel_hi:[1,0]
	v_pk_fma_f32 v[154:155], v[154:155], s[50:51], v[170:171] op_sel:[0,0,1] op_sel_hi:[1,0,0] neg_lo:[1,0,0] neg_hi:[1,0,0]
	v_pk_add_f32 v[170:171], v[156:157], v[172:173]
	v_pk_add_f32 v[156:157], v[156:157], v[172:173] neg_lo:[0,1] neg_hi:[0,1]
	v_pk_fma_f32 v[20:21], v[8:9], v[12:13], v[20:21] op_sel_hi:[0,1,1]
	v_pk_mul_f32 v[172:173], v[156:157], s[40:41]
	v_pk_mul_f32 v[24:25], v[12:13], v[22:23] op_sel:[1,0] op_sel_hi:[0,1]
	v_pk_fma_f32 v[156:157], v[156:157], s[38:39], v[172:173] op_sel:[0,0,1] op_sel_hi:[1,0,0] neg_lo:[1,0,0] neg_hi:[1,0,0]
	v_pk_add_f32 v[172:173], v[158:159], v[174:175]
	v_pk_add_f32 v[158:159], v[158:159], v[174:175] neg_lo:[0,1] neg_hi:[0,1]
	v_pk_fma_f32 v[36:37], v[8:9], v[28:29], v[36:37] op_sel_hi:[0,1,1]
	v_pk_mul_f32 v[174:175], v[158:159], s[24:25]
	v_pk_mul_f32 v[40:41], v[22:23], v[28:29] op_sel:[0,1] op_sel_hi:[1,0]
	v_pk_fma_f32 v[158:159], v[158:159], s[22:23], v[174:175] op_sel:[0,0,1] op_sel_hi:[1,0,0] neg_lo:[1,0,0] neg_hi:[1,0,0]
	v_pk_add_f32 v[174:175], v[210:211], v[196:197]
	v_pk_add_f32 v[196:197], v[210:211], v[196:197] neg_lo:[0,1] neg_hi:[0,1]
	v_pk_add_f32 v[210:211], v[190:191], v[182:183]
	v_pk_add_f32 v[182:183], v[190:191], v[182:183] neg_lo:[0,1] neg_hi:[0,1]
	v_pk_fma_f32 v[52:53], v[8:9], v[44:45], v[52:53] op_sel_hi:[0,1,1]
	v_pk_mul_f32 v[190:191], v[182:183], s[40:41]
	v_pk_mul_f32 v[56:57], v[22:23], v[44:45] op_sel:[0,1] op_sel_hi:[1,0]
	v_pk_fma_f32 v[182:183], v[182:183], s[38:39], v[190:191] op_sel:[0,0,1] op_sel_hi:[1,0,0]
	v_pk_add_f32 v[190:191], v[176:177], v[204:205]
	v_pk_add_f32 v[204:205], v[176:177], v[204:205] neg_lo:[0,1] neg_hi:[0,1]
	v_pk_fma_f32 v[68:69], v[8:9], v[60:61], v[68:69] op_sel_hi:[0,1,1]
	v_pk_add_f32 v[176:177], v[194:195], v[206:207]
	v_pk_add_f32 v[194:195], v[194:195], v[206:207] neg_lo:[0,1] neg_hi:[0,1]
	v_pk_mul_f32 v[72:73], v[22:23], v[60:61] op_sel:[0,1] op_sel_hi:[1,0]
	v_pk_mul_f32 v[206:207], v[194:195], s[40:41]
	v_pk_fma_f32 v[84:85], v[8:9], v[76:77], v[84:85] op_sel_hi:[0,1,1]
	v_pk_fma_f32 v[194:195], v[194:195], s[38:39], v[206:207] op_sel:[0,0,1] op_sel_hi:[1,0,0] neg_lo:[1,0,0] neg_hi:[1,0,0]
	v_pk_add_f32 v[206:207], v[144:145], v[198:199] op_sel:[0,1] op_sel_hi:[1,0] neg_hi:[0,1]
	v_pk_add_f32 v[144:145], v[144:145], v[198:199] op_sel:[0,1] op_sel_hi:[1,0] neg_lo:[0,1]
	v_pk_add_f32 v[198:199], v[160:161], v[184:185]
	v_pk_add_f32 v[160:161], v[160:161], v[184:185] neg_lo:[0,1] neg_hi:[0,1]
	v_pk_mul_f32 v[88:89], v[22:23], v[76:77] op_sel:[0,1] op_sel_hi:[1,0]
	v_pk_mul_f32 v[184:185], v[160:161], s[40:41]
	v_pk_fma_f32 v[100:101], v[8:9], v[92:93], v[100:101] op_sel_hi:[0,1,1]
	v_pk_fma_f32 v[160:161], v[160:161], s[38:39], v[184:185] op_sel:[0,0,1] op_sel_hi:[1,0,0]
	v_pk_add_f32 v[184:185], v[178:179], v[186:187]
	v_pk_add_f32 v[186:187], v[178:179], v[186:187] neg_lo:[0,1] neg_hi:[0,1]
	v_pk_mul_f32 v[104:105], v[22:23], v[92:93] op_sel:[0,1] op_sel_hi:[1,0]
	v_pk_add_f32 v[178:179], v[180:181], v[188:189]
	v_pk_add_f32 v[180:181], v[180:181], v[188:189] neg_lo:[0,1] neg_hi:[0,1]
	v_pk_fma_f32 v[116:117], v[8:9], v[108:109], v[116:117] op_sel_hi:[0,1,1]
	v_pk_mul_f32 v[188:189], v[180:181], s[40:41]
	v_pk_mul_f32 v[120:121], v[22:23], v[108:109] op_sel:[0,1] op_sel_hi:[1,0]
	v_pk_fma_f32 v[180:181], v[180:181], s[38:39], v[188:189] op_sel:[0,0,1] op_sel_hi:[1,0,0] neg_lo:[1,0,0] neg_hi:[1,0,0]
	v_pk_add_f32 v[188:189], v[208:209], v[166:167]
	v_pk_add_f32 v[166:167], v[208:209], v[166:167] neg_lo:[0,1] neg_hi:[0,1]
	v_pk_add_f32 v[208:209], v[192:193], v[152:153]
	v_pk_add_f32 v[152:153], v[192:193], v[152:153] neg_lo:[0,1] neg_hi:[0,1]
	v_xor_b32_e32 v26, 0x80000000, v19
	v_pk_mul_f32 v[192:193], v[152:153], s[40:41]
	v_xor_b32_e32 v30, 0x80000000, v21
	v_pk_fma_f32 v[152:153], v[152:153], s[38:39], v[192:193] op_sel:[0,0,1] op_sel_hi:[1,0,0]
	v_pk_add_f32 v[192:193], v[162:163], v[170:171]
	v_pk_add_f32 v[170:171], v[162:163], v[170:171] neg_lo:[0,1] neg_hi:[0,1]
	v_pk_fma_f32 v[24:25], v[12:13], v[10:11], v[24:25] op_sel_hi:[1,0,1]
	v_pk_add_f32 v[162:163], v[164:165], v[172:173]
	v_pk_add_f32 v[164:165], v[164:165], v[172:173] neg_lo:[0,1] neg_hi:[0,1]
	v_pk_fma_f32 v[40:41], v[10:11], v[28:29], v[40:41] op_sel_hi:[0,1,1]
	v_pk_mul_f32 v[172:173], v[164:165], s[40:41]
	v_pk_fma_f32 v[56:57], v[10:11], v[44:45], v[56:57] op_sel_hi:[0,1,1]
	v_pk_fma_f32 v[164:165], v[164:165], s[38:39], v[172:173] op_sel:[0,0,1] op_sel_hi:[1,0,0] neg_lo:[1,0,0] neg_hi:[1,0,0]
	v_pk_add_f32 v[172:173], v[128:129], v[168:169] op_sel:[0,1] op_sel_hi:[1,0] neg_hi:[0,1]
	v_pk_add_f32 v[128:129], v[128:129], v[168:169] op_sel:[0,1] op_sel_hi:[1,0] neg_lo:[0,1]
	v_pk_add_f32 v[168:169], v[130:131], v[154:155]
	v_pk_add_f32 v[130:131], v[130:131], v[154:155] neg_lo:[0,1] neg_hi:[0,1]
	v_pk_fma_f32 v[72:73], v[10:11], v[60:61], v[72:73] op_sel_hi:[0,1,1]
	v_pk_mul_f32 v[154:155], v[130:131], s[40:41]
	v_pk_fma_f32 v[88:89], v[10:11], v[76:77], v[88:89] op_sel_hi:[0,1,1]
	v_pk_fma_f32 v[130:131], v[130:131], s[38:39], v[154:155] op_sel:[0,0,1] op_sel_hi:[1,0,0]
	v_pk_add_f32 v[154:155], v[148:149], v[156:157]
	v_pk_add_f32 v[156:157], v[148:149], v[156:157] neg_lo:[0,1] neg_hi:[0,1]
	v_pk_fma_f32 v[104:105], v[10:11], v[92:93], v[104:105] op_sel_hi:[0,1,1]
	v_pk_add_f32 v[148:149], v[150:151], v[158:159]
	v_pk_add_f32 v[150:151], v[150:151], v[158:159] neg_lo:[0,1] neg_hi:[0,1]
	v_pk_fma_f32 v[120:121], v[10:11], v[108:109], v[120:121] op_sel_hi:[0,1,1]
	v_pk_mul_f32 v[158:159], v[150:151], s[40:41]
	v_mov_b32_e32 v27, v19
	v_pk_fma_f32 v[150:151], v[150:151], s[38:39], v[158:159] op_sel:[0,0,1] op_sel_hi:[1,0,0] neg_lo:[1,0,0] neg_hi:[1,0,0]
	v_pk_add_f32 v[158:159], v[174:175], v[190:191]
	v_pk_add_f32 v[174:175], v[174:175], v[190:191] neg_lo:[0,1] neg_hi:[0,1]
	v_pk_add_f32 v[190:191], v[210:211], v[176:177]
	v_pk_add_f32 v[210:211], v[210:211], v[176:177] neg_lo:[0,1] neg_hi:[0,1]
	v_mov_b32_e32 v31, v21
	v_pk_add_f32 v[176:177], v[196:197], v[204:205] op_sel:[0,1] op_sel_hi:[1,0] neg_hi:[0,1]
	v_pk_add_f32 v[196:197], v[196:197], v[204:205] op_sel:[0,1] op_sel_hi:[1,0] neg_lo:[0,1]
	v_pk_add_f32 v[204:205], v[182:183], v[194:195]
	v_pk_add_f32 v[194:195], v[182:183], v[194:195] neg_lo:[0,1] neg_hi:[0,1]
	v_xor_b32_e32 v34, 0x80000000, v25
	v_pk_add_f32 v[182:183], v[206:207], v[184:185]
	v_pk_add_f32 v[184:185], v[206:207], v[184:185] neg_lo:[0,1] neg_hi:[0,1]
	v_pk_add_f32 v[206:207], v[198:199], v[178:179]
	v_pk_add_f32 v[198:199], v[198:199], v[178:179] neg_lo:[0,1] neg_hi:[0,1]
	v_xor_b32_e32 v38, 0x80000000, v29
	v_pk_add_f32 v[178:179], v[144:145], v[186:187] op_sel:[0,1] op_sel_hi:[1,0] neg_hi:[0,1]
	v_pk_add_f32 v[144:145], v[144:145], v[186:187] op_sel:[0,1] op_sel_hi:[1,0] neg_lo:[0,1]
	v_pk_add_f32 v[186:187], v[160:161], v[180:181]
	v_pk_add_f32 v[180:181], v[160:161], v[180:181] neg_lo:[0,1] neg_hi:[0,1]
	v_xor_b32_e32 v42, 0x80000000, v33
	v_pk_add_f32 v[160:161], v[188:189], v[192:193]
	v_pk_add_f32 v[188:189], v[188:189], v[192:193] neg_lo:[0,1] neg_hi:[0,1]
	v_pk_add_f32 v[192:193], v[208:209], v[162:163]
	v_pk_add_f32 v[208:209], v[208:209], v[162:163] neg_lo:[0,1] neg_hi:[0,1]
	v_xor_b32_e32 v46, 0x80000000, v37
	v_pk_add_f32 v[162:163], v[166:167], v[170:171] op_sel:[0,1] op_sel_hi:[1,0] neg_hi:[0,1]
	v_pk_add_f32 v[166:167], v[166:167], v[170:171] op_sel:[0,1] op_sel_hi:[1,0] neg_lo:[0,1]
	v_pk_add_f32 v[170:171], v[152:153], v[164:165]
	v_pk_add_f32 v[164:165], v[152:153], v[164:165] neg_lo:[0,1] neg_hi:[0,1]
	v_mov_b32_e32 v35, v25
	v_pk_add_f32 v[152:153], v[172:173], v[154:155]
	v_pk_add_f32 v[154:155], v[172:173], v[154:155] neg_lo:[0,1] neg_hi:[0,1]
	v_pk_add_f32 v[172:173], v[168:169], v[148:149]
	v_pk_add_f32 v[168:169], v[168:169], v[148:149] neg_lo:[0,1] neg_hi:[0,1]
	v_mov_b32_e32 v39, v29
	v_pk_add_f32 v[148:149], v[128:129], v[156:157] op_sel:[0,1] op_sel_hi:[1,0] neg_hi:[0,1]
	v_pk_add_f32 v[128:129], v[128:129], v[156:157] op_sel:[0,1] op_sel_hi:[1,0] neg_lo:[0,1]
	v_pk_add_f32 v[156:157], v[130:131], v[150:151]
	v_pk_add_f32 v[130:131], v[130:131], v[150:151] neg_lo:[0,1] neg_hi:[0,1]
	v_mov_b32_e32 v43, v33
	v_xor_b32_e32 v151, 0x80000000, v130
	v_mov_b32_e32 v150, v131
	v_pk_add_f32 v[130:131], v[158:159], v[190:191]
	v_pk_add_f32 v[158:159], v[158:159], v[190:191] neg_lo:[0,1] neg_hi:[0,1]
	v_pk_add_f32 v[190:191], v[174:175], v[210:211] op_sel:[0,1] op_sel_hi:[1,0] neg_hi:[0,1]
	v_pk_add_f32 v[174:175], v[174:175], v[210:211] op_sel:[0,1] op_sel_hi:[1,0] neg_lo:[0,1]
	v_pk_add_f32 v[210:211], v[176:177], v[204:205]
	v_pk_add_f32 v[176:177], v[176:177], v[204:205] neg_lo:[0,1] neg_hi:[0,1]
	v_pk_add_f32 v[204:205], v[196:197], v[194:195] op_sel:[0,1] op_sel_hi:[1,0] neg_hi:[0,1]
	v_pk_add_f32 v[194:195], v[196:197], v[194:195] op_sel:[0,1] op_sel_hi:[1,0] neg_lo:[0,1]
	v_pk_add_f32 v[196:197], v[182:183], v[206:207]
	v_pk_add_f32 v[182:183], v[182:183], v[206:207] neg_lo:[0,1] neg_hi:[0,1]
	v_pk_add_f32 v[206:207], v[184:185], v[198:199] op_sel:[0,1] op_sel_hi:[1,0] neg_hi:[0,1]
	v_pk_add_f32 v[184:185], v[184:185], v[198:199] op_sel:[0,1] op_sel_hi:[1,0] neg_lo:[0,1]
	v_pk_add_f32 v[198:199], v[178:179], v[186:187]
	v_pk_add_f32 v[178:179], v[178:179], v[186:187] neg_lo:[0,1] neg_hi:[0,1]
	v_pk_add_f32 v[186:187], v[144:145], v[180:181] op_sel:[0,1] op_sel_hi:[1,0] neg_hi:[0,1]
	v_pk_add_f32 v[144:145], v[144:145], v[180:181] op_sel:[0,1] op_sel_hi:[1,0] neg_lo:[0,1]
	v_pk_add_f32 v[180:181], v[160:161], v[192:193]
	v_pk_add_f32 v[160:161], v[160:161], v[192:193] neg_lo:[0,1] neg_hi:[0,1]
	v_pk_mul_f32 v[4:5], v[4:5], v[180:181] op_sel:[0,1] op_sel_hi:[1,0]
	v_pk_add_f32 v[192:193], v[188:189], v[208:209] op_sel:[0,1] op_sel_hi:[1,0] neg_hi:[0,1]
	v_pk_add_f32 v[188:189], v[188:189], v[208:209] op_sel:[0,1] op_sel_hi:[1,0] neg_lo:[0,1]
	v_pk_add_f32 v[208:209], v[162:163], v[170:171]
	v_pk_add_f32 v[162:163], v[162:163], v[170:171] neg_lo:[0,1] neg_hi:[0,1]
	v_pk_add_f32 v[170:171], v[166:167], v[164:165] op_sel:[0,1] op_sel_hi:[1,0] neg_hi:[0,1]
	v_pk_add_f32 v[164:165], v[166:167], v[164:165] op_sel:[0,1] op_sel_hi:[1,0] neg_lo:[0,1]
	v_pk_add_f32 v[166:167], v[152:153], v[172:173]
	v_pk_fma_f32 v[4:5], v[6:7], v[180:181], v[4:5] op_sel_hi:[0,1,1]
	v_pk_mul_f32 v[6:7], v[14:15], v[196:197] op_sel:[0,1] op_sel_hi:[1,0]
	v_mov_b32_e32 v47, v37
	v_pk_fma_f32 v[6:7], v[8:9], v[196:197], v[6:7] op_sel_hi:[0,1,1]
	v_pk_mul_f32 v[8:9], v[22:23], v[166:167] op_sel:[0,1] op_sel_hi:[1,0]
	v_pk_add_f32 v[152:153], v[152:153], v[172:173] neg_lo:[0,1] neg_hi:[0,1]
	v_pk_fma_f32 v[8:9], v[10:11], v[166:167], v[8:9] op_sel_hi:[0,1,1]
	v_pk_mul_f32 v[10:11], v[16:17], v[210:211] op_sel:[0,1] op_sel_hi:[1,0]
	v_pk_add_f32 v[172:173], v[154:155], v[168:169] op_sel:[0,1] op_sel_hi:[1,0] neg_hi:[0,1]
	v_pk_add_f32 v[154:155], v[154:155], v[168:169] op_sel:[0,1] op_sel_hi:[1,0] neg_lo:[0,1]
	v_pk_add_f32 v[168:169], v[148:149], v[156:157]
	v_pk_fma_f32 v[10:11], v[12:13], v[210:211], v[10:11] op_sel_hi:[0,1,1]
	v_pk_mul_f32 v[12:13], v[26:27], v[208:209] op_sel:[0,1] op_sel_hi:[1,0]
	v_pk_mul_f32 v[14:15], v[30:31], v[198:199] op_sel:[0,1] op_sel_hi:[1,0]
	v_xor_b32_e32 v50, 0x80000000, v41
	v_xor_b32_e32 v54, 0x80000000, v45
	v_xor_b32_e32 v58, 0x80000000, v49
	v_xor_b32_e32 v62, 0x80000000, v53
	v_xor_b32_e32 v66, 0x80000000, v57
	v_xor_b32_e32 v70, 0x80000000, v61
	v_xor_b32_e32 v74, 0x80000000, v65
	v_mov_b32_e32 v51, v41
	v_mov_b32_e32 v55, v45
	v_mov_b32_e32 v59, v49
	v_mov_b32_e32 v63, v53
	v_mov_b32_e32 v67, v57
	v_mov_b32_e32 v71, v61
	v_mov_b32_e32 v75, v65
	v_pk_add_f32 v[148:149], v[148:149], v[156:157] neg_lo:[0,1] neg_hi:[0,1]
	v_pk_add_f32 v[156:157], v[128:129], v[150:151]
	v_pk_fma_f32 v[12:13], v[18:19], v[208:209], v[12:13] op_sel_hi:[0,1,1]
	v_pk_fma_f32 v[14:15], v[20:21], v[198:199], v[14:15] op_sel_hi:[0,1,1]
	v_pk_mul_f32 v[16:17], v[34:35], v[168:169] op_sel:[0,1] op_sel_hi:[1,0]
	v_pk_mul_f32 v[18:19], v[38:39], v[190:191] op_sel:[0,1] op_sel_hi:[1,0]
	v_pk_mul_f32 v[20:21], v[42:43], v[192:193] op_sel:[0,1] op_sel_hi:[1,0]
	v_pk_mul_f32 v[22:23], v[46:47], v[206:207] op_sel:[0,1] op_sel_hi:[1,0]
	v_xor_b32_e32 v78, 0x80000000, v69
	v_xor_b32_e32 v82, 0x80000000, v73
	v_xor_b32_e32 v86, 0x80000000, v77
	v_xor_b32_e32 v90, 0x80000000, v81
	v_xor_b32_e32 v94, 0x80000000, v85
	v_xor_b32_e32 v98, 0x80000000, v89
	v_xor_b32_e32 v102, 0x80000000, v93
	v_xor_b32_e32 v106, 0x80000000, v97
	v_xor_b32_e32 v110, 0x80000000, v101
	v_xor_b32_e32 v114, 0x80000000, v105
	v_xor_b32_e32 v118, 0x80000000, v109
	v_xor_b32_e32 v122, 0x80000000, v113
	v_xor_b32_e32 v124, 0x80000000, v117
	v_xor_b32_e32 v126, 0x80000000, v121
	v_mov_b32_e32 v79, v69
	v_mov_b32_e32 v83, v73
	v_mov_b32_e32 v87, v77
	v_mov_b32_e32 v91, v81
	v_mov_b32_e32 v95, v85
	v_mov_b32_e32 v99, v89
	v_mov_b32_e32 v103, v93
	v_mov_b32_e32 v107, v97
	v_mov_b32_e32 v111, v101
	v_mov_b32_e32 v115, v105
	v_mov_b32_e32 v119, v109
	v_mov_b32_e32 v123, v113
	v_mov_b32_e32 v125, v117
	v_mov_b32_e32 v127, v121
	v_pk_add_f32 v[128:129], v[128:129], v[150:151] neg_lo:[0,1] neg_hi:[0,1]
	v_pk_fma_f32 v[16:17], v[24:25], v[168:169], v[16:17] op_sel_hi:[0,1,1]
	v_pk_fma_f32 v[18:19], v[28:29], v[190:191], v[18:19] op_sel_hi:[0,1,1]
	v_pk_fma_f32 v[20:21], v[32:33], v[192:193], v[20:21] op_sel_hi:[0,1,1]
	v_pk_fma_f32 v[22:23], v[36:37], v[206:207], v[22:23] op_sel_hi:[0,1,1]
	v_pk_mul_f32 v[24:25], v[50:51], v[172:173] op_sel:[0,1] op_sel_hi:[1,0]
	v_pk_mul_f32 v[26:27], v[54:55], v[204:205] op_sel:[0,1] op_sel_hi:[1,0]
	v_pk_mul_f32 v[28:29], v[58:59], v[170:171] op_sel:[0,1] op_sel_hi:[1,0]
	v_pk_mul_f32 v[30:31], v[62:63], v[186:187] op_sel:[0,1] op_sel_hi:[1,0]
	v_pk_mul_f32 v[32:33], v[66:67], v[156:157] op_sel:[0,1] op_sel_hi:[1,0]
	v_pk_mul_f32 v[34:35], v[70:71], v[158:159] op_sel:[0,1] op_sel_hi:[1,0]
	v_pk_mul_f32 v[36:37], v[74:75], v[160:161] op_sel:[0,1] op_sel_hi:[1,0]
	v_pk_fma_f32 v[24:25], v[40:41], v[172:173], v[24:25] op_sel_hi:[0,1,1]
	v_pk_fma_f32 v[26:27], v[44:45], v[204:205], v[26:27] op_sel_hi:[0,1,1]
	v_pk_fma_f32 v[28:29], v[48:49], v[170:171], v[28:29] op_sel_hi:[0,1,1]
	v_pk_fma_f32 v[30:31], v[52:53], v[186:187], v[30:31] op_sel_hi:[0,1,1]
	v_pk_fma_f32 v[32:33], v[56:57], v[156:157], v[32:33] op_sel_hi:[0,1,1]
	v_pk_fma_f32 v[34:35], v[60:61], v[158:159], v[34:35] op_sel_hi:[0,1,1]
	v_pk_fma_f32 v[36:37], v[64:65], v[160:161], v[36:37] op_sel_hi:[0,1,1]
	v_pk_mul_f32 v[38:39], v[78:79], v[182:183] op_sel:[0,1] op_sel_hi:[1,0]
	v_pk_mul_f32 v[40:41], v[82:83], v[152:153] op_sel:[0,1] op_sel_hi:[1,0]
	v_pk_mul_f32 v[42:43], v[86:87], v[176:177] op_sel:[0,1] op_sel_hi:[1,0]
	v_pk_mul_f32 v[44:45], v[90:91], v[162:163] op_sel:[0,1] op_sel_hi:[1,0]
	v_pk_mul_f32 v[46:47], v[94:95], v[178:179] op_sel:[0,1] op_sel_hi:[1,0]
	v_pk_mul_f32 v[48:49], v[98:99], v[148:149] op_sel:[0,1] op_sel_hi:[1,0]
	v_pk_mul_f32 v[50:51], v[102:103], v[174:175] op_sel:[0,1] op_sel_hi:[1,0]
	v_pk_mul_f32 v[52:53], v[106:107], v[188:189] op_sel:[0,1] op_sel_hi:[1,0]
	v_pk_mul_f32 v[54:55], v[110:111], v[184:185] op_sel:[0,1] op_sel_hi:[1,0]
	v_pk_mul_f32 v[56:57], v[114:115], v[154:155] op_sel:[0,1] op_sel_hi:[1,0]
	v_pk_mul_f32 v[58:59], v[118:119], v[194:195] op_sel:[0,1] op_sel_hi:[1,0]
	v_pk_mul_f32 v[60:61], v[122:123], v[164:165] op_sel:[0,1] op_sel_hi:[1,0]
	v_pk_mul_f32 v[62:63], v[124:125], v[144:145] op_sel:[0,1] op_sel_hi:[1,0]
	v_pk_mul_f32 v[64:65], v[126:127], v[128:129] op_sel:[0,1] op_sel_hi:[1,0]
	v_pk_fma_f32 v[38:39], v[68:69], v[182:183], v[38:39] op_sel_hi:[0,1,1]
	v_pk_fma_f32 v[40:41], v[72:73], v[152:153], v[40:41] op_sel_hi:[0,1,1]
	v_pk_fma_f32 v[42:43], v[76:77], v[176:177], v[42:43] op_sel_hi:[0,1,1]
	v_pk_fma_f32 v[44:45], v[80:81], v[162:163], v[44:45] op_sel_hi:[0,1,1]
	v_pk_fma_f32 v[46:47], v[84:85], v[178:179], v[46:47] op_sel_hi:[0,1,1]
	v_pk_fma_f32 v[48:49], v[88:89], v[148:149], v[48:49] op_sel_hi:[0,1,1]
	v_pk_fma_f32 v[50:51], v[92:93], v[174:175], v[50:51] op_sel_hi:[0,1,1]
	v_pk_fma_f32 v[52:53], v[96:97], v[188:189], v[52:53] op_sel_hi:[0,1,1]
	v_pk_fma_f32 v[54:55], v[100:101], v[184:185], v[54:55] op_sel_hi:[0,1,1]
	v_pk_fma_f32 v[56:57], v[104:105], v[154:155], v[56:57] op_sel_hi:[0,1,1]
	v_pk_fma_f32 v[58:59], v[108:109], v[194:195], v[58:59] op_sel_hi:[0,1,1]
	v_pk_fma_f32 v[60:61], v[112:113], v[164:165], v[60:61] op_sel_hi:[0,1,1]
	v_pk_fma_f32 v[62:63], v[116:117], v[144:145], v[62:63] op_sel_hi:[0,1,1]
	v_pk_fma_f32 v[64:65], v[120:121], v[128:129], v[64:65] op_sel_hi:[0,1,1]
	ds_write2_b64 v2, v[130:131], v[34:35] offset1:16
	ds_write2_b64 v2, v[18:19], v[50:51] offset0:33 offset1:49
	ds_write2_b64 v2, v[10:11], v[42:43] offset0:66 offset1:82
	ds_write2_b64 v2, v[26:27], v[58:59] offset0:99 offset1:115
	ds_write2_b64 v2, v[6:7], v[38:39] offset0:132 offset1:148
	ds_write2_b64 v2, v[22:23], v[54:55] offset0:165 offset1:181
	ds_write2_b64 v2, v[14:15], v[46:47] offset0:198 offset1:214
	ds_write2_b64 v2, v[30:31], v[62:63] offset0:231 offset1:247
	ds_write2_b64 v143, v[4:5], v[36:37] offset0:8 offset1:24
	ds_write2_b64 v143, v[20:21], v[52:53] offset0:41 offset1:57
	ds_write2_b64 v143, v[12:13], v[44:45] offset0:74 offset1:90
	ds_write2_b64 v143, v[28:29], v[60:61] offset0:107 offset1:123
	ds_write2_b64 v143, v[8:9], v[40:41] offset0:140 offset1:156
	ds_write2_b64 v143, v[24:25], v[56:57] offset0:173 offset1:189
	ds_write2_b64 v143, v[16:17], v[48:49] offset0:206 offset1:222
	ds_write2_b64 v143, v[32:33], v[64:65] offset0:239 offset1:255
	s_waitcnt lgkmcnt(0)
	s_barrier
	s_nop 0
	v_ashrrev_i32_e32 v2, 31, v142
	v_lshrrev_b32_e32 v2, 23, v2
	v_add_u32_e32 v2, v142, v2
	v_ashrrev_i32_e32 v2, 9, v2
	v_mul_i32_i24_e32 v4, 0x200, v2
	v_sub_u32_e32 v144, v142, v4
	v_lshlrev_b32_e32 v143, 14, v2
	v_lshlrev_b32_e32 v2, 1, v144
	v_bfrev_b32_e32 v2, v2
	v_lshrrev_b32_e32 v2, 22, v2
	v_sub_u32_e32 v2, 0x400, v2
	v_bfrev_b32_e32 v2, v2
	v_lshrrev_b32_e32 v2, 18, v2
	v_and_b32_e32 v2, 0x3ff0, v2
	v_cmp_eq_u32_e32 vcc, 0, v144
	v_lshl_add_u32 v4, v144, 5, v143
	v_lshlrev_b32_e32 v5, 3, v4
	v_cndmask_b32_e64 v2, v2, 16, vcc
	v_ashrrev_i32_e32 v4, 2, v4
	v_or_b32_e32 v2, v2, v143
	v_add3_u32 v56, 0, v5, v4
	v_ashrrev_i32_e32 v4, 5, v2
	v_lshlrev_b32_e32 v2, 3, v2
	v_lshlrev_b32_e32 v4, 3, v4
	v_add3_u32 v2, 0, v2, v4
	ds_read2_b64 v[4:7], v56 offset1:1
	ds_read2_b64 v[8:11], v56 offset0:2 offset1:3
	ds_read2_b64 v[12:15], v2 offset1:1
	ds_read2_b64 v[16:19], v2 offset0:2 offset1:3
	ds_read2_b64 v[20:23], v56 offset0:4 offset1:5
	ds_read2_b64 v[24:27], v56 offset0:6 offset1:7
	ds_read2_b64 v[28:31], v2 offset0:4 offset1:5
	ds_read2_b64 v[32:35], v2 offset0:6 offset1:7
	ds_read2_b64 v[36:39], v56 offset0:8 offset1:9
	ds_read2_b64 v[40:43], v56 offset0:10 offset1:11
	ds_read2_b64 v[48:51], v2 offset0:8 offset1:9
	ds_read2_b64 v[52:55], v2 offset0:10 offset1:11
	ds_read2_b64 v[44:47], v56 offset0:12 offset1:13
	ds_read2_b64 v[56:59], v56 offset0:14 offset1:15
	ds_read2_b64 v[70:73], v2 offset0:12 offset1:13
	ds_read2_b64 v[98:101], v2 offset0:14 offset1:15
	s_waitcnt lgkmcnt(7)
	v_pk_add_f32 v[60:61], v[4:5], v[36:37]
	v_pk_add_f32 v[4:5], v[4:5], v[36:37] neg_lo:[0,1] neg_hi:[0,1]
	v_pk_add_f32 v[36:37], v[6:7], v[38:39]
	v_pk_add_f32 v[6:7], v[6:7], v[38:39] neg_lo:[0,1] neg_hi:[0,1]
	s_waitcnt lgkmcnt(3)
	v_pk_add_f32 v[62:63], v[22:23], v[46:47]
	v_pk_mul_f32 v[38:39], v[6:7], s[24:25]
	v_pk_add_f32 v[22:23], v[22:23], v[46:47] neg_lo:[0,1] neg_hi:[0,1]
	v_pk_fma_f32 v[6:7], v[6:7], s[22:23], v[38:39] op_sel:[0,0,1] op_sel_hi:[1,0,0]
	v_pk_add_f32 v[38:39], v[8:9], v[40:41]
	v_pk_add_f32 v[8:9], v[8:9], v[40:41] neg_lo:[0,1] neg_hi:[0,1]
	v_pk_mul_f32 v[46:47], v[22:23], s[44:45]
	v_pk_mul_f32 v[40:41], v[8:9], s[40:41]
	v_pk_fma_f32 v[22:23], v[22:23], s[50:51], v[46:47] op_sel:[0,0,1] op_sel_hi:[1,0,0] neg_lo:[1,0,0] neg_hi:[1,0,0]
	v_pk_fma_f32 v[8:9], v[8:9], s[38:39], v[40:41] op_sel:[0,0,1] op_sel_hi:[1,0,0]
	v_pk_add_f32 v[40:41], v[10:11], v[42:43]
	v_pk_add_f32 v[10:11], v[10:11], v[42:43] neg_lo:[0,1] neg_hi:[0,1]
	s_waitcnt lgkmcnt(2)
	v_pk_add_f32 v[46:47], v[24:25], v[56:57]
	v_pk_add_f32 v[24:25], v[24:25], v[56:57] neg_lo:[0,1] neg_hi:[0,1]
	v_pk_mul_f32 v[42:43], v[10:11], s[44:45]
	v_pk_mul_f32 v[56:57], v[24:25], s[40:41]
	v_pk_fma_f32 v[10:11], v[10:11], s[50:51], v[42:43] op_sel:[0,0,1] op_sel_hi:[1,0,0]
	v_pk_add_f32 v[42:43], v[20:21], v[44:45]
	v_pk_add_f32 v[44:45], v[20:21], v[44:45] neg_lo:[0,1] neg_hi:[0,1]
	v_pk_fma_f32 v[24:25], v[24:25], s[38:39], v[56:57] op_sel:[0,0,1] op_sel_hi:[1,0,0] neg_lo:[1,0,0] neg_hi:[1,0,0]
	v_pk_add_f32 v[56:57], v[26:27], v[58:59]
	v_pk_add_f32 v[26:27], v[26:27], v[58:59] neg_lo:[0,1] neg_hi:[0,1]
	v_pk_mul_f32 v[58:59], v[26:27], s[24:25]
	v_pk_add_f32 v[64:65], v[40:41], v[56:57]
	v_pk_add_f32 v[40:41], v[40:41], v[56:57] neg_lo:[0,1] neg_hi:[0,1]
	v_pk_fma_f32 v[26:27], v[26:27], s[22:23], v[58:59] op_sel:[0,0,1] op_sel_hi:[1,0,0] neg_lo:[1,0,0] neg_hi:[1,0,0]
	v_pk_mul_f32 v[56:57], v[40:41], s[40:41]
	v_pk_add_f32 v[20:21], v[4:5], v[44:45] op_sel:[0,1] op_sel_hi:[1,0] neg_hi:[0,1]
	v_pk_add_f32 v[4:5], v[4:5], v[44:45] op_sel:[0,1] op_sel_hi:[1,0] neg_lo:[0,1]
	v_pk_add_f32 v[44:45], v[6:7], v[22:23]
	v_pk_add_f32 v[6:7], v[6:7], v[22:23] neg_lo:[0,1] neg_hi:[0,1]
	v_pk_fma_f32 v[40:41], v[40:41], s[38:39], v[56:57] op_sel:[0,0,1] op_sel_hi:[1,0,0] neg_lo:[1,0,0] neg_hi:[1,0,0]
	v_pk_mul_f32 v[22:23], v[6:7], s[40:41]
	v_pk_add_f32 v[56:57], v[10:11], v[26:27]
	v_pk_add_f32 v[10:11], v[10:11], v[26:27] neg_lo:[0,1] neg_hi:[0,1]
	v_pk_add_f32 v[58:59], v[60:61], v[42:43]
	v_pk_add_f32 v[42:43], v[60:61], v[42:43] neg_lo:[0,1] neg_hi:[0,1]
	v_pk_add_f32 v[60:61], v[36:37], v[62:63]
	v_pk_add_f32 v[36:37], v[36:37], v[62:63] neg_lo:[0,1] neg_hi:[0,1]
	v_pk_fma_f32 v[6:7], v[6:7], s[38:39], v[22:23] op_sel:[0,0,1] op_sel_hi:[1,0,0]
	v_pk_add_f32 v[22:23], v[8:9], v[24:25]
	v_pk_add_f32 v[24:25], v[8:9], v[24:25] neg_lo:[0,1] neg_hi:[0,1]
	v_pk_mul_f32 v[26:27], v[10:11], s[40:41]
	v_pk_mul_f32 v[62:63], v[36:37], s[40:41]
	v_pk_fma_f32 v[10:11], v[10:11], s[38:39], v[26:27] op_sel:[0,0,1] op_sel_hi:[1,0,0] neg_lo:[1,0,0] neg_hi:[1,0,0]
	v_pk_fma_f32 v[36:37], v[36:37], s[38:39], v[62:63] op_sel:[0,0,1] op_sel_hi:[1,0,0]
	v_pk_add_f32 v[62:63], v[38:39], v[46:47]
	v_pk_add_f32 v[66:67], v[20:21], v[22:23]
	v_pk_add_f32 v[20:21], v[20:21], v[22:23] neg_lo:[0,1] neg_hi:[0,1]
	v_pk_add_f32 v[22:23], v[44:45], v[56:57]
	v_pk_add_f32 v[44:45], v[44:45], v[56:57] neg_lo:[0,1] neg_hi:[0,1]
	v_pk_add_f32 v[8:9], v[4:5], v[24:25] op_sel:[0,1] op_sel_hi:[1,0] neg_hi:[0,1]
	v_pk_add_f32 v[4:5], v[4:5], v[24:25] op_sel:[0,1] op_sel_hi:[1,0] neg_lo:[0,1]
	v_pk_add_f32 v[24:25], v[6:7], v[10:11]
	v_pk_add_f32 v[10:11], v[6:7], v[10:11] neg_lo:[0,1] neg_hi:[0,1]
	v_pk_add_f32 v[26:27], v[58:59], v[62:63]
	v_pk_add_f32 v[58:59], v[58:59], v[62:63] neg_lo:[0,1] neg_hi:[0,1]
	v_pk_add_f32 v[62:63], v[60:61], v[64:65]
	v_pk_add_f32 v[60:61], v[60:61], v[64:65] neg_lo:[0,1] neg_hi:[0,1]
	v_xor_b32_e32 v57, 0x80000000, v44
	v_mov_b32_e32 v56, v45
	v_xor_b32_e32 v65, 0x80000000, v60
	v_pk_add_f32 v[130:131], v[26:27], v[62:63]
	v_pk_add_f32 v[92:93], v[26:27], v[62:63] neg_lo:[0,1] neg_hi:[0,1]
	v_mov_b32_e32 v64, v61
	v_pk_add_f32 v[62:63], v[20:21], v[56:57]
	v_pk_add_f32 v[78:79], v[20:21], v[56:57] neg_lo:[0,1] neg_hi:[0,1]
	v_pk_add_f32 v[56:57], v[4:5], v[10:11] op_sel:[0,1] op_sel_hi:[1,0] neg_hi:[0,1]
	v_pk_add_f32 v[90:91], v[4:5], v[10:11] op_sel:[0,1] op_sel_hi:[1,0] neg_lo:[0,1]
	v_pk_add_f32 v[10:11], v[14:15], v[50:51] neg_lo:[0,1] neg_hi:[0,1]
	v_pk_add_f32 v[46:47], v[38:39], v[46:47] neg_lo:[0,1] neg_hi:[0,1]
	v_pk_add_f32 v[84:85], v[58:59], v[64:65]
	v_pk_add_f32 v[86:87], v[58:59], v[64:65] neg_lo:[0,1] neg_hi:[0,1]
	v_pk_add_f32 v[80:81], v[8:9], v[24:25]
	v_pk_add_f32 v[64:65], v[8:9], v[24:25] neg_lo:[0,1] neg_hi:[0,1]
	v_pk_add_f32 v[4:5], v[12:13], v[48:49]
	v_pk_add_f32 v[6:7], v[12:13], v[48:49] neg_lo:[0,1] neg_hi:[0,1]
	v_pk_add_f32 v[8:9], v[14:15], v[50:51]
	v_pk_mul_f32 v[12:13], v[10:11], s[24:25]
	v_pk_add_f32 v[14:15], v[16:17], v[52:53] neg_lo:[0,1] neg_hi:[0,1]
	v_pk_fma_f32 v[10:11], v[10:11], s[22:23], v[12:13] op_sel:[0,0,1] op_sel_hi:[1,0,0]
	v_pk_add_f32 v[12:13], v[16:17], v[52:53]
	v_pk_mul_f32 v[16:17], v[14:15], s[40:41]
	v_pk_add_f32 v[38:39], v[42:43], v[46:47] op_sel:[0,1] op_sel_hi:[1,0] neg_hi:[0,1]
	v_pk_add_f32 v[42:43], v[42:43], v[46:47] op_sel:[0,1] op_sel_hi:[1,0] neg_lo:[0,1]
	v_pk_add_f32 v[46:47], v[36:37], v[40:41]
	v_pk_fma_f32 v[14:15], v[14:15], s[38:39], v[16:17] op_sel:[0,0,1] op_sel_hi:[1,0,0]
	v_pk_add_f32 v[16:17], v[18:19], v[54:55]
	v_pk_add_f32 v[18:19], v[18:19], v[54:55] neg_lo:[0,1] neg_hi:[0,1]
	v_pk_add_f32 v[88:89], v[38:39], v[46:47]
	v_pk_add_f32 v[68:69], v[38:39], v[46:47] neg_lo:[0,1] neg_hi:[0,1]
	v_pk_add_f32 v[96:97], v[66:67], v[22:23]
	v_pk_add_f32 v[46:47], v[66:67], v[22:23] neg_lo:[0,1] neg_hi:[0,1]
	v_pk_mul_f32 v[20:21], v[18:19], s[44:45]
	s_waitcnt lgkmcnt(1)
	v_pk_add_f32 v[24:25], v[28:29], v[70:71] neg_lo:[0,1] neg_hi:[0,1]
	v_pk_add_f32 v[26:27], v[30:31], v[72:73] neg_lo:[0,1] neg_hi:[0,1]
	v_pk_fma_f32 v[18:19], v[18:19], s[50:51], v[20:21] op_sel:[0,0,1] op_sel_hi:[1,0,0]
	v_pk_add_f32 v[20:21], v[28:29], v[70:71]
	v_pk_add_f32 v[22:23], v[30:31], v[72:73]
	v_pk_mul_f32 v[28:29], v[26:27], s[44:45]
	s_waitcnt lgkmcnt(0)
	v_pk_add_f32 v[30:31], v[32:33], v[98:99] neg_lo:[0,1] neg_hi:[0,1]
	v_pk_fma_f32 v[26:27], v[26:27], s[50:51], v[28:29] op_sel:[0,0,1] op_sel_hi:[1,0,0] neg_lo:[1,0,0] neg_hi:[1,0,0]
	v_pk_add_f32 v[28:29], v[32:33], v[98:99]
	v_pk_mul_f32 v[32:33], v[30:31], s[40:41]
	v_pk_add_f32 v[36:37], v[36:37], v[40:41] neg_lo:[0,1] neg_hi:[0,1]
	v_pk_fma_f32 v[30:31], v[30:31], s[38:39], v[32:33] op_sel:[0,0,1] op_sel_hi:[1,0,0] neg_lo:[1,0,0] neg_hi:[1,0,0]
	v_pk_add_f32 v[32:33], v[34:35], v[100:101]
	v_pk_add_f32 v[34:35], v[34:35], v[100:101] neg_lo:[0,1] neg_hi:[0,1]
	v_xor_b32_e32 v41, 0x80000000, v36
	v_mov_b32_e32 v40, v37
	v_pk_mul_f32 v[36:37], v[34:35], s[24:25]
	v_mov_b32_e32 v2, v130
	v_pk_fma_f32 v[34:35], v[34:35], s[22:23], v[36:37] op_sel:[0,0,1] op_sel_hi:[1,0,0] neg_lo:[1,0,0] neg_hi:[1,0,0]
	v_pk_add_f32 v[36:37], v[4:5], v[20:21]
	v_pk_add_f32 v[4:5], v[4:5], v[20:21] neg_lo:[0,1] neg_hi:[0,1]
	v_pk_add_f32 v[20:21], v[8:9], v[22:23]
	v_pk_add_f32 v[8:9], v[8:9], v[22:23] neg_lo:[0,1] neg_hi:[0,1]
	v_cmp_ne_u32_e64 s[0:1], 0, v144
	v_pk_mul_f32 v[22:23], v[8:9], s[40:41]
	v_pk_add_f32 v[74:75], v[42:43], v[40:41]
	v_pk_fma_f32 v[8:9], v[8:9], s[38:39], v[22:23] op_sel:[0,0,1] op_sel_hi:[1,0,0]
	v_pk_add_f32 v[22:23], v[12:13], v[28:29]
	v_pk_add_f32 v[28:29], v[12:13], v[28:29] neg_lo:[0,1] neg_hi:[0,1]
	v_pk_add_f32 v[94:95], v[42:43], v[40:41] neg_lo:[0,1] neg_hi:[0,1]
	v_pk_add_f32 v[12:13], v[16:17], v[32:33]
	v_pk_add_f32 v[16:17], v[16:17], v[32:33] neg_lo:[0,1] neg_hi:[0,1]
	s_nop 0
	v_pk_mul_f32 v[32:33], v[16:17], s[40:41]
	s_nop 0
	v_pk_fma_f32 v[16:17], v[16:17], s[38:39], v[32:33] op_sel:[0,0,1] op_sel_hi:[1,0,0] neg_lo:[1,0,0] neg_hi:[1,0,0]
	v_pk_add_f32 v[32:33], v[6:7], v[24:25] op_sel:[0,1] op_sel_hi:[1,0] neg_hi:[0,1]
	v_pk_add_f32 v[6:7], v[6:7], v[24:25] op_sel:[0,1] op_sel_hi:[1,0] neg_lo:[0,1]
	v_pk_add_f32 v[24:25], v[10:11], v[26:27]
	v_pk_add_f32 v[10:11], v[10:11], v[26:27] neg_lo:[0,1] neg_hi:[0,1]
	s_nop 0
	v_pk_mul_f32 v[26:27], v[10:11], s[40:41]
	s_nop 0
	v_pk_fma_f32 v[10:11], v[10:11], s[38:39], v[26:27] op_sel:[0,0,1] op_sel_hi:[1,0,0]
	v_pk_add_f32 v[26:27], v[14:15], v[30:31]
	v_pk_add_f32 v[30:31], v[14:15], v[30:31] neg_lo:[0,1] neg_hi:[0,1]
	s_nop 0
	v_pk_add_f32 v[14:15], v[18:19], v[34:35]
	v_pk_add_f32 v[18:19], v[18:19], v[34:35] neg_lo:[0,1] neg_hi:[0,1]
	s_nop 0
	v_pk_mul_f32 v[34:35], v[18:19], s[40:41]
	s_nop 0
	v_pk_fma_f32 v[18:19], v[18:19], s[38:39], v[34:35] op_sel:[0,0,1] op_sel_hi:[1,0,0] neg_lo:[1,0,0] neg_hi:[1,0,0]
	v_pk_add_f32 v[34:35], v[36:37], v[22:23]
	v_pk_add_f32 v[22:23], v[36:37], v[22:23] neg_lo:[0,1] neg_hi:[0,1]
	v_pk_add_f32 v[36:37], v[20:21], v[12:13]
	v_pk_add_f32 v[12:13], v[20:21], v[12:13] neg_lo:[0,1] neg_hi:[0,1]
	v_pk_add_f32 v[98:99], v[34:35], v[36:37]
	v_xor_b32_e32 v21, 0x80000000, v12
	v_mov_b32_e32 v20, v13
	v_pk_add_f32 v[12:13], v[4:5], v[28:29] op_sel:[0,1] op_sel_hi:[1,0] neg_hi:[0,1]
	v_pk_add_f32 v[4:5], v[4:5], v[28:29] op_sel:[0,1] op_sel_hi:[1,0] neg_lo:[0,1]
	v_pk_add_f32 v[28:29], v[8:9], v[16:17]
	v_pk_add_f32 v[8:9], v[8:9], v[16:17] neg_lo:[0,1] neg_hi:[0,1]
	v_pk_add_f32 v[100:101], v[34:35], v[36:37] neg_lo:[0,1] neg_hi:[0,1]
	v_xor_b32_e32 v17, 0x80000000, v8
	v_mov_b32_e32 v16, v9
	v_pk_add_f32 v[8:9], v[32:33], v[26:27]
	v_pk_add_f32 v[26:27], v[32:33], v[26:27] neg_lo:[0,1] neg_hi:[0,1]
	v_pk_add_f32 v[32:33], v[24:25], v[14:15]
	v_pk_add_f32 v[14:15], v[24:25], v[14:15] neg_lo:[0,1] neg_hi:[0,1]
	v_pk_add_f32 v[102:103], v[22:23], v[20:21]
	v_xor_b32_e32 v25, 0x80000000, v14
	v_mov_b32_e32 v24, v15
	v_pk_add_f32 v[14:15], v[6:7], v[30:31] op_sel:[0,1] op_sel_hi:[1,0] neg_hi:[0,1]
	v_pk_add_f32 v[6:7], v[6:7], v[30:31] op_sel:[0,1] op_sel_hi:[1,0] neg_lo:[0,1]
	v_pk_add_f32 v[30:31], v[10:11], v[18:19]
	v_pk_add_f32 v[10:11], v[10:11], v[18:19] neg_lo:[0,1] neg_hi:[0,1]
	v_pk_add_f32 v[104:105], v[22:23], v[20:21] neg_lo:[0,1] neg_hi:[0,1]
	v_xor_b32_e32 v19, 0x80000000, v10
	v_mov_b32_e32 v18, v11
	v_pk_add_f32 v[106:107], v[12:13], v[28:29]
	v_pk_add_f32 v[108:109], v[12:13], v[28:29] neg_lo:[0,1] neg_hi:[0,1]
	v_pk_add_f32 v[110:111], v[4:5], v[16:17]
	v_pk_add_f32 v[112:113], v[4:5], v[16:17] neg_lo:[0,1] neg_hi:[0,1]
	v_pk_add_f32 v[114:115], v[8:9], v[32:33]
	v_pk_add_f32 v[116:117], v[8:9], v[32:33] neg_lo:[0,1] neg_hi:[0,1]
	v_pk_add_f32 v[118:119], v[26:27], v[24:25]
	v_pk_add_f32 v[120:121], v[26:27], v[24:25] neg_lo:[0,1] neg_hi:[0,1]
	v_pk_add_f32 v[122:123], v[14:15], v[30:31]
	v_pk_add_f32 v[124:125], v[14:15], v[30:31] neg_lo:[0,1] neg_hi:[0,1]
	v_pk_add_f32 v[126:127], v[6:7], v[18:19]
	v_pk_add_f32 v[128:129], v[6:7], v[18:19] neg_lo:[0,1] neg_hi:[0,1]
	v_mov_b32_e32 v4, v131
	v_mov_b32_e32 v5, v3
	v_mov_b64_e32 v[6:7], v[2:3]
	s_and_saveexec_b64 s[50:51], s[0:1]
	s_xor_b64 s[0:1], exec, s[50:51]
	s_cbranch_execz .LBB0_562
	v_pk_add_f32 v[4:5], v[96:97], v[112:113]
	v_pk_add_f32 v[24:25], v[96:97], v[112:113] neg_lo:[0,1] neg_hi:[0,1]
	v_pk_add_f32 v[148:149], v[130:131], v[128:129]
	v_pk_add_f32 v[8:9], v[130:131], v[128:129] neg_lo:[0,1] neg_hi:[0,1]
	v_pk_add_f32 v[128:129], v[126:127], v[92:93]
	v_pk_add_f32 v[10:11], v[126:127], v[92:93] neg_lo:[0,1] neg_hi:[0,1]
	v_pk_add_f32 v[92:93], v[84:85], v[124:125]
	v_pk_add_f32 v[12:13], v[84:85], v[124:125] neg_lo:[0,1] neg_hi:[0,1]
	v_pk_add_f32 v[84:85], v[122:123], v[86:87]
	v_pk_add_f32 v[14:15], v[122:123], v[86:87] neg_lo:[0,1] neg_hi:[0,1]
	v_pk_add_f32 v[86:87], v[88:89], v[120:121]
	v_pk_add_f32 v[16:17], v[88:89], v[120:121] neg_lo:[0,1] neg_hi:[0,1]
	v_pk_add_f32 v[88:89], v[118:119], v[68:69]
	v_pk_add_f32 v[18:19], v[118:119], v[68:69] neg_lo:[0,1] neg_hi:[0,1]
	v_pk_add_f32 v[68:69], v[74:75], v[116:117]
	v_pk_add_f32 v[20:21], v[74:75], v[116:117] neg_lo:[0,1] neg_hi:[0,1]
	v_pk_add_f32 v[74:75], v[114:115], v[94:95]
	v_pk_add_f32 v[22:23], v[114:115], v[94:95] neg_lo:[0,1] neg_hi:[0,1]
	v_mov_b32_e32 v6, v4
	v_mov_b32_e32 v7, v25
	v_pk_mov_b32 v[4:5], v[4:5], v[24:25] op_sel:[1,0]
	v_pk_add_f32 v[94:95], v[110:111], v[46:47]
	v_pk_add_f32 v[24:25], v[110:111], v[46:47] neg_lo:[0,1] neg_hi:[0,1]
	v_pk_add_f32 v[46:47], v[62:63], v[108:109]
	v_pk_add_f32 v[26:27], v[62:63], v[108:109] neg_lo:[0,1] neg_hi:[0,1]
	v_pk_add_f32 v[62:63], v[106:107], v[78:79]
	v_pk_add_f32 v[28:29], v[106:107], v[78:79] neg_lo:[0,1] neg_hi:[0,1]
	v_pk_add_f32 v[78:79], v[80:81], v[104:105]
	v_pk_add_f32 v[30:31], v[80:81], v[104:105] neg_lo:[0,1] neg_hi:[0,1]
	v_pk_add_f32 v[80:81], v[102:103], v[64:65]
	v_pk_add_f32 v[32:33], v[102:103], v[64:65] neg_lo:[0,1] neg_hi:[0,1]
	v_pk_add_f32 v[64:65], v[56:57], v[100:101]
	v_pk_add_f32 v[34:35], v[56:57], v[100:101] neg_lo:[0,1] neg_hi:[0,1]
	v_pk_add_f32 v[56:57], v[98:99], v[90:91]
	v_pk_add_f32 v[36:37], v[98:99], v[90:91] neg_lo:[0,1] neg_hi:[0,1]
	v_pk_mul_f32 v[6:7], v[6:7], 0.5 op_sel_hi:[1,0]
	v_pk_mul_f32 v[4:5], v[4:5], s[46:47]
	v_mov_b32_e32 v39, v8
	v_mov_b32_e32 v38, v149
	v_mov_b32_e32 v41, v10
	v_mov_b32_e32 v40, v129
	v_mov_b32_e32 v43, v12
	v_mov_b32_e32 v42, v93
	v_mov_b32_e32 v45, v14
	v_mov_b32_e32 v44, v85
	v_mov_b32_e32 v49, v16
	v_mov_b32_e32 v48, v87
	v_mov_b32_e32 v51, v18
	v_mov_b32_e32 v50, v89
	v_mov_b32_e32 v53, v20
	v_mov_b32_e32 v52, v69
	v_mov_b32_e32 v55, v22
	v_mov_b32_e32 v54, v75
	v_mov_b32_e32 v59, v24
	v_mov_b32_e32 v58, v95
	v_mov_b32_e32 v61, v26
	v_mov_b32_e32 v60, v47
	v_mov_b32_e32 v67, v28
	v_mov_b32_e32 v66, v63
	v_mov_b32_e32 v71, v30
	v_mov_b32_e32 v70, v79
	v_mov_b32_e32 v73, v32
	v_mov_b32_e32 v72, v81
	v_mov_b32_e32 v77, v34
	v_mov_b32_e32 v76, v65
	v_mov_b32_e32 v83, v36
	v_mov_b32_e32 v82, v57
	v_mov_b32_e32 v8, v148
	v_mov_b32_e32 v10, v128
	v_mov_b32_e32 v12, v92
	v_mov_b32_e32 v14, v84
	v_mov_b32_e32 v16, v86
	v_mov_b32_e32 v18, v88
	v_mov_b32_e32 v20, v68
	v_mov_b32_e32 v22, v74
	v_mov_b32_e32 v24, v94
	v_mov_b32_e32 v26, v46
	v_mov_b32_e32 v28, v62
	v_mov_b32_e32 v30, v78
	v_mov_b32_e32 v32, v80
	v_mov_b32_e32 v34, v64
	v_mov_b32_e32 v36, v56

.LBB0_574:
	s_or_b64 exec, exec, s[0:1]
	v_mov_b32_e32 v2, v142
	s_waitcnt lgkmcnt(0)
	s_barrier
	s_mov_b32 s19, s16
	v_and_b32_e32 v4, 0xff, v2
	v_lshlrev_b32_e32 v5, 5, v2
	v_and_or_b32 v4, v5, s68, v4
	v_ashrrev_i32_e32 v5, 5, v4
	v_cvt_f32_ubyte0_e32 v2, v2
	v_lshlrev_b32_e32 v7, 3, v4
	v_mul_f32_e32 v2, 0x39000000, v2
	v_lshlrev_b32_e32 v5, 3, v5
	v_sin_f32_e32 v4, v2
	v_cos_f32_e32 v6, v2
	v_add3_u32 v2, 0, v7, v5
	ds_read_b64 v[128:129], v2
	ds_read_b64 v[130:131], v2 offset:2112
	ds_read_b64 v[144:145], v2 offset:4224
	ds_read_b64 v[148:149], v2 offset:6336
	ds_read_b64 v[150:151], v2 offset:8448
	ds_read_b64 v[152:153], v2 offset:10560
	ds_read_b64 v[154:155], v2 offset:12672
	ds_read_b64 v[156:157], v2 offset:14784
	ds_read_b64 v[158:159], v2 offset:16896
	ds_read_b64 v[160:161], v2 offset:19008
	ds_read_b64 v[162:163], v2 offset:21120
	ds_read_b64 v[164:165], v2 offset:23232
	ds_read_b64 v[166:167], v2 offset:25344
	ds_read_b64 v[168:169], v2 offset:27456
	ds_read_b64 v[170:171], v2 offset:29568
	ds_read_b64 v[172:173], v2 offset:31680
	ds_read_b64 v[174:175], v2 offset:33792
	ds_read_b64 v[176:177], v2 offset:35904
	ds_read_b64 v[178:179], v2 offset:38016
	ds_read_b64 v[180:181], v2 offset:40128
	ds_read_b64 v[182:183], v2 offset:42240
	ds_read_b64 v[184:185], v2 offset:44352
	ds_read_b64 v[186:187], v2 offset:46464
	ds_read_b64 v[188:189], v2 offset:48576
	ds_read_b64 v[190:191], v2 offset:50688
	ds_read_b64 v[192:193], v2 offset:52800
	ds_read_b64 v[194:195], v2 offset:54912
	ds_read_b64 v[196:197], v2 offset:57024
	ds_read_b64 v[198:199], v2 offset:59136
	ds_read_b64 v[204:205], v2 offset:61248
	ds_read_b64 v[206:207], v2 offset:63360
	ds_read_b64 v[208:209], v2 offset:65472
	s_waitcnt lgkmcnt(14)
	v_pk_add_f32 v[210:211], v[128:129], v[174:175]
	v_pk_add_f32 v[128:129], v[128:129], v[174:175] neg_lo:[0,1] neg_hi:[0,1]
	v_pk_add_f32 v[174:175], v[130:131], v[176:177]
	v_pk_add_f32 v[130:131], v[130:131], v[176:177] neg_lo:[0,1] neg_hi:[0,1]
	s_mov_b32 s0, s9
	v_pk_mul_f32 v[176:177], v[130:131], s[18:19]
	s_mov_b32 s41, s38
	v_pk_fma_f32 v[130:131], v[130:131], s[0:1], v[176:177] op_sel:[0,0,1] op_sel_hi:[1,0,0]
	s_waitcnt lgkmcnt(13)
	v_pk_add_f32 v[176:177], v[144:145], v[178:179]
	v_pk_add_f32 v[144:145], v[144:145], v[178:179] neg_lo:[0,1] neg_hi:[0,1]
	s_mov_b32 s43, s26
	v_pk_mul_f32 v[178:179], v[144:145], s[24:25]
	s_mov_b32 s62, s37
	v_pk_fma_f32 v[144:145], v[144:145], s[22:23], v[178:179] op_sel:[0,0,1] op_sel_hi:[1,0,0]
	s_waitcnt lgkmcnt(12)
	v_pk_add_f32 v[178:179], v[148:149], v[180:181]
	v_pk_add_f32 v[148:149], v[148:149], v[180:181] neg_lo:[0,1] neg_hi:[0,1]
	s_mov_b32 s45, s22
	v_pk_mul_f32 v[180:181], v[148:149], s[36:37]
	s_mov_b32 s50, s25
	v_pk_fma_f32 v[148:149], v[148:149], s[26:27], v[180:181] op_sel:[0,0,1] op_sel_hi:[1,0,0]
	s_waitcnt lgkmcnt(11)
	v_pk_add_f32 v[180:181], v[150:151], v[182:183]
	v_pk_add_f32 v[150:151], v[150:151], v[182:183] neg_lo:[0,1] neg_hi:[0,1]
	v_xor_b32_e32 v7, 0x80000000, v4
	v_pk_mul_f32 v[182:183], v[150:151], s[40:41]
	v_mov_b32_e32 v5, v7
	v_pk_fma_f32 v[150:151], v[150:151], s[38:39], v[182:183] op_sel:[0,0,1] op_sel_hi:[1,0,0]
	s_waitcnt lgkmcnt(10)
	v_pk_add_f32 v[182:183], v[152:153], v[184:185]
	v_pk_add_f32 v[152:153], v[152:153], v[184:185] neg_lo:[0,1] neg_hi:[0,1]
	v_pk_mul_f32 v[8:9], v[6:7], v[4:5] op_sel:[1,0] op_sel_hi:[0,1]
	v_pk_mul_f32 v[184:185], v[152:153], s[42:43]
	v_pk_fma_f32 v[8:9], v[6:7], v[6:7], v[8:9] op_sel_hi:[1,0,1]
	v_pk_fma_f32 v[152:153], v[152:153], s[62:63], v[184:185] op_sel:[0,0,1] op_sel_hi:[1,0,0]
	s_waitcnt lgkmcnt(9)
	v_pk_add_f32 v[184:185], v[154:155], v[186:187]
	v_pk_add_f32 v[154:155], v[154:155], v[186:187] neg_lo:[0,1] neg_hi:[0,1]
	v_xor_b32_e32 v14, 0x80000000, v9
	v_pk_mul_f32 v[186:187], v[154:155], s[44:45]
	v_mov_b32_e32 v15, v9
	v_pk_fma_f32 v[154:155], v[154:155], s[50:51], v[186:187] op_sel:[0,0,1] op_sel_hi:[1,0,0]
	s_waitcnt lgkmcnt(8)
	v_pk_add_f32 v[186:187], v[156:157], v[188:189]
	v_pk_add_f32 v[156:157], v[156:157], v[188:189] neg_lo:[0,1] neg_hi:[0,1]
	v_pk_mul_f32 v[12:13], v[8:9], v[14:15] op_sel:[1,0] op_sel_hi:[0,1]
	v_pk_mul_f32 v[188:189], v[156:157], s[8:9]
	v_pk_fma_f32 v[12:13], v[8:9], v[8:9], v[12:13] op_sel_hi:[1,0,1]
	v_pk_fma_f32 v[156:157], v[156:157], s[16:17], v[188:189] op_sel:[0,0,1] op_sel_hi:[1,0,0]
	s_waitcnt lgkmcnt(7)
	v_pk_add_f32 v[188:189], v[158:159], v[190:191]
	v_pk_add_f32 v[190:191], v[158:159], v[190:191] neg_lo:[0,1] neg_hi:[0,1]
	v_xor_b32_e32 v16, 0x80000000, v13
	s_waitcnt lgkmcnt(6)
	v_pk_add_f32 v[158:159], v[160:161], v[192:193]
	v_pk_add_f32 v[160:161], v[160:161], v[192:193] neg_lo:[0,1] neg_hi:[0,1]
	v_mov_b32_e32 v17, v13
	v_pk_mul_f32 v[192:193], v[160:161], s[8:9]
	v_pk_mul_f32 v[28:29], v[12:13], v[16:17] op_sel:[1,0] op_sel_hi:[0,1]
	v_pk_fma_f32 v[160:161], v[160:161], s[16:17], v[192:193] op_sel:[0,0,1] op_sel_hi:[1,0,0] neg_lo:[1,0,0] neg_hi:[1,0,0]
	s_waitcnt lgkmcnt(5)
	v_pk_add_f32 v[192:193], v[162:163], v[194:195]
	v_pk_add_f32 v[162:163], v[162:163], v[194:195] neg_lo:[0,1] neg_hi:[0,1]
	v_pk_fma_f32 v[28:29], v[12:13], v[12:13], v[28:29] op_sel_hi:[1,0,1]
	v_pk_mul_f32 v[194:195], v[162:163], s[44:45]
	v_pk_mul_f32 v[44:45], v[16:17], v[28:29] op_sel:[0,1] op_sel_hi:[1,0]
	v_pk_fma_f32 v[162:163], v[162:163], s[50:51], v[194:195] op_sel:[0,0,1] op_sel_hi:[1,0,0] neg_lo:[1,0,0] neg_hi:[1,0,0]
	s_waitcnt lgkmcnt(4)
	v_pk_add_f32 v[194:195], v[164:165], v[196:197]
	v_pk_add_f32 v[164:165], v[164:165], v[196:197] neg_lo:[0,1] neg_hi:[0,1]
	v_pk_fma_f32 v[44:45], v[12:13], v[28:29], v[44:45] op_sel_hi:[0,1,1]
	v_pk_mul_f32 v[196:197], v[164:165], s[42:43]
	v_pk_mul_f32 v[60:61], v[16:17], v[44:45] op_sel:[0,1] op_sel_hi:[1,0]
	v_pk_fma_f32 v[164:165], v[164:165], s[62:63], v[196:197] op_sel:[0,0,1] op_sel_hi:[1,0,0] neg_lo:[1,0,0] neg_hi:[1,0,0]
	s_waitcnt lgkmcnt(3)
	v_pk_add_f32 v[196:197], v[166:167], v[198:199]
	v_pk_add_f32 v[166:167], v[166:167], v[198:199] neg_lo:[0,1] neg_hi:[0,1]
	v_pk_fma_f32 v[60:61], v[12:13], v[44:45], v[60:61] op_sel_hi:[0,1,1]
	v_pk_mul_f32 v[198:199], v[166:167], s[40:41]
	v_pk_mul_f32 v[76:77], v[16:17], v[60:61] op_sel:[0,1] op_sel_hi:[1,0]
	v_pk_fma_f32 v[166:167], v[166:167], s[38:39], v[198:199] op_sel:[0,0,1] op_sel_hi:[1,0,0] neg_lo:[1,0,0] neg_hi:[1,0,0]
	s_waitcnt lgkmcnt(2)
	v_pk_add_f32 v[198:199], v[168:169], v[204:205]
	v_pk_add_f32 v[168:169], v[168:169], v[204:205] neg_lo:[0,1] neg_hi:[0,1]
	v_pk_fma_f32 v[76:77], v[12:13], v[60:61], v[76:77] op_sel_hi:[0,1,1]
	v_pk_mul_f32 v[204:205], v[168:169], s[36:37]
	v_pk_mul_f32 v[92:93], v[16:17], v[76:77] op_sel:[0,1] op_sel_hi:[1,0]
	v_pk_fma_f32 v[168:169], v[168:169], s[26:27], v[204:205] op_sel:[0,0,1] op_sel_hi:[1,0,0] neg_lo:[1,0,0] neg_hi:[1,0,0]
	s_waitcnt lgkmcnt(1)
	v_pk_add_f32 v[204:205], v[170:171], v[206:207]
	v_pk_add_f32 v[170:171], v[170:171], v[206:207] neg_lo:[0,1] neg_hi:[0,1]
	v_pk_fma_f32 v[92:93], v[12:13], v[76:77], v[92:93] op_sel_hi:[0,1,1]
	v_pk_mul_f32 v[206:207], v[170:171], s[24:25]
	v_pk_mul_f32 v[108:109], v[16:17], v[92:93] op_sel:[0,1] op_sel_hi:[1,0]
	v_pk_fma_f32 v[170:171], v[170:171], s[22:23], v[206:207] op_sel:[0,0,1] op_sel_hi:[1,0,0] neg_lo:[1,0,0] neg_hi:[1,0,0]
	s_waitcnt lgkmcnt(0)
	v_pk_add_f32 v[206:207], v[172:173], v[208:209]
	v_pk_add_f32 v[172:173], v[172:173], v[208:209] neg_lo:[0,1] neg_hi:[0,1]
	v_pk_mul_f32 v[10:11], v[4:5], v[8:9] op_sel:[0,1] op_sel_hi:[1,0]
	v_pk_mul_f32 v[208:209], v[172:173], s[18:19]
	v_pk_fma_f32 v[108:109], v[12:13], v[92:93], v[108:109] op_sel_hi:[0,1,1]
	v_pk_fma_f32 v[172:173], v[172:173], s[0:1], v[208:209] op_sel:[0,0,1] op_sel_hi:[1,0,0] neg_lo:[1,0,0] neg_hi:[1,0,0]
	v_pk_add_f32 v[208:209], v[210:211], v[188:189]
	v_pk_add_f32 v[188:189], v[210:211], v[188:189] neg_lo:[0,1] neg_hi:[0,1]
	v_pk_add_f32 v[210:211], v[174:175], v[158:159]
	v_pk_add_f32 v[158:159], v[174:175], v[158:159] neg_lo:[0,1] neg_hi:[0,1]
	v_pk_fma_f32 v[10:11], v[6:7], v[8:9], v[10:11] op_sel_hi:[0,1,1]
	v_pk_mul_f32 v[174:175], v[158:159], s[24:25]
	v_pk_mul_f32 v[18:19], v[4:5], v[12:13] op_sel:[0,1] op_sel_hi:[1,0]
	v_pk_fma_f32 v[158:159], v[158:159], s[22:23], v[174:175] op_sel:[0,0,1] op_sel_hi:[1,0,0]
	v_pk_add_f32 v[174:175], v[176:177], v[192:193]
	v_pk_add_f32 v[176:177], v[176:177], v[192:193] neg_lo:[0,1] neg_hi:[0,1]
	v_pk_mul_f32 v[32:33], v[4:5], v[28:29] op_sel:[0,1] op_sel_hi:[1,0]
	v_pk_mul_f32 v[192:193], v[176:177], s[40:41]
	v_pk_mul_f32 v[48:49], v[4:5], v[44:45] op_sel:[0,1] op_sel_hi:[1,0]
	v_pk_fma_f32 v[176:177], v[176:177], s[38:39], v[192:193] op_sel:[0,0,1] op_sel_hi:[1,0,0]
	v_pk_add_f32 v[192:193], v[178:179], v[194:195]
	v_pk_add_f32 v[178:179], v[178:179], v[194:195] neg_lo:[0,1] neg_hi:[0,1]
	v_pk_mul_f32 v[64:65], v[4:5], v[60:61] op_sel:[0,1] op_sel_hi:[1,0]
	v_pk_mul_f32 v[194:195], v[178:179], s[44:45]
	v_pk_mul_f32 v[80:81], v[4:5], v[76:77] op_sel:[0,1] op_sel_hi:[1,0]
	v_pk_fma_f32 v[178:179], v[178:179], s[50:51], v[194:195] op_sel:[0,0,1] op_sel_hi:[1,0,0]
	v_pk_add_f32 v[194:195], v[180:181], v[196:197]
	v_pk_add_f32 v[196:197], v[180:181], v[196:197] neg_lo:[0,1] neg_hi:[0,1]
	v_pk_mul_f32 v[96:97], v[4:5], v[92:93] op_sel:[0,1] op_sel_hi:[1,0]
	v_pk_add_f32 v[180:181], v[182:183], v[198:199]
	v_pk_add_f32 v[182:183], v[182:183], v[198:199] neg_lo:[0,1] neg_hi:[0,1]
	v_pk_mul_f32 v[112:113], v[4:5], v[108:109] op_sel:[0,1] op_sel_hi:[1,0]
	v_pk_mul_f32 v[198:199], v[182:183], s[44:45]
	v_xor_b32_e32 v22, 0x80000000, v11
	v_pk_fma_f32 v[182:183], v[182:183], s[50:51], v[198:199] op_sel:[0,0,1] op_sel_hi:[1,0,0] neg_lo:[1,0,0] neg_hi:[1,0,0]
	v_pk_add_f32 v[198:199], v[184:185], v[204:205]
	v_pk_add_f32 v[184:185], v[184:185], v[204:205] neg_lo:[0,1] neg_hi:[0,1]
	v_mov_b32_e32 v23, v11
	v_pk_mul_f32 v[204:205], v[184:185], s[40:41]
	v_pk_fma_f32 v[18:19], v[6:7], v[12:13], v[18:19] op_sel_hi:[0,1,1]
	v_pk_fma_f32 v[184:185], v[184:185], s[38:39], v[204:205] op_sel:[0,0,1] op_sel_hi:[1,0,0] neg_lo:[1,0,0] neg_hi:[1,0,0]
	v_pk_add_f32 v[204:205], v[186:187], v[206:207]
	v_pk_add_f32 v[186:187], v[186:187], v[206:207] neg_lo:[0,1] neg_hi:[0,1]
	v_pk_mul_f32 v[20:21], v[14:15], v[12:13] op_sel:[0,1] op_sel_hi:[1,0]
	v_pk_mul_f32 v[206:207], v[186:187], s[24:25]
	v_pk_fma_f32 v[32:33], v[6:7], v[28:29], v[32:33] op_sel_hi:[0,1,1]
	v_pk_fma_f32 v[186:187], v[186:187], s[22:23], v[206:207] op_sel:[0,0,1] op_sel_hi:[1,0,0] neg_lo:[1,0,0] neg_hi:[1,0,0]
	v_pk_add_f32 v[206:207], v[128:129], v[190:191] op_sel:[0,1] op_sel_hi:[1,0] neg_hi:[0,1]
	v_pk_add_f32 v[128:129], v[128:129], v[190:191] op_sel:[0,1] op_sel_hi:[1,0] neg_lo:[0,1]
	v_pk_add_f32 v[190:191], v[130:131], v[160:161]
	v_pk_add_f32 v[130:131], v[130:131], v[160:161] neg_lo:[0,1] neg_hi:[0,1]
	v_pk_mul_f32 v[36:37], v[14:15], v[28:29] op_sel:[0,1] op_sel_hi:[1,0]
	v_pk_mul_f32 v[160:161], v[130:131], s[24:25]
	v_pk_fma_f32 v[48:49], v[6:7], v[44:45], v[48:49] op_sel_hi:[0,1,1]
	v_pk_fma_f32 v[130:131], v[130:131], s[22:23], v[160:161] op_sel:[0,0,1] op_sel_hi:[1,0,0]
	v_pk_add_f32 v[160:161], v[144:145], v[162:163]
	v_pk_add_f32 v[144:145], v[144:145], v[162:163] neg_lo:[0,1] neg_hi:[0,1]
	v_pk_mul_f32 v[52:53], v[14:15], v[44:45] op_sel:[0,1] op_sel_hi:[1,0]
	v_pk_mul_f32 v[162:163], v[144:145], s[40:41]
	v_pk_fma_f32 v[64:65], v[6:7], v[60:61], v[64:65] op_sel_hi:[0,1,1]
	v_pk_fma_f32 v[144:145], v[144:145], s[38:39], v[162:163] op_sel:[0,0,1] op_sel_hi:[1,0,0]
	v_pk_add_f32 v[162:163], v[148:149], v[164:165]
	v_pk_add_f32 v[148:149], v[148:149], v[164:165] neg_lo:[0,1] neg_hi:[0,1]
	v_pk_mul_f32 v[68:69], v[14:15], v[60:61] op_sel:[0,1] op_sel_hi:[1,0]
	v_pk_mul_f32 v[164:165], v[148:149], s[44:45]
	v_pk_fma_f32 v[80:81], v[6:7], v[76:77], v[80:81] op_sel_hi:[0,1,1]
	v_pk_fma_f32 v[148:149], v[148:149], s[50:51], v[164:165] op_sel:[0,0,1] op_sel_hi:[1,0,0]
	v_pk_add_f32 v[164:165], v[150:151], v[166:167]
	v_pk_add_f32 v[166:167], v[150:151], v[166:167] neg_lo:[0,1] neg_hi:[0,1]
	v_pk_mul_f32 v[84:85], v[14:15], v[76:77] op_sel:[0,1] op_sel_hi:[1,0]
	v_pk_add_f32 v[150:151], v[152:153], v[168:169]
	v_pk_add_f32 v[152:153], v[152:153], v[168:169] neg_lo:[0,1] neg_hi:[0,1]
	v_pk_fma_f32 v[96:97], v[6:7], v[92:93], v[96:97] op_sel_hi:[0,1,1]
	v_pk_mul_f32 v[168:169], v[152:153], s[44:45]
	v_pk_mul_f32 v[100:101], v[14:15], v[92:93] op_sel:[0,1] op_sel_hi:[1,0]
	v_pk_fma_f32 v[152:153], v[152:153], s[50:51], v[168:169] op_sel:[0,0,1] op_sel_hi:[1,0,0] neg_lo:[1,0,0] neg_hi:[1,0,0]
	v_pk_add_f32 v[168:169], v[154:155], v[170:171]
	v_pk_add_f32 v[154:155], v[154:155], v[170:171] neg_lo:[0,1] neg_hi:[0,1]
	v_pk_fma_f32 v[112:113], v[6:7], v[108:109], v[112:113] op_sel_hi:[0,1,1]
	v_pk_mul_f32 v[170:171], v[154:155], s[40:41]
	v_pk_mul_f32 v[116:117], v[14:15], v[108:109] op_sel:[0,1] op_sel_hi:[1,0]
	v_pk_fma_f32 v[154:155], v[154:155], s[38:39], v[170:171] op_sel:[0,0,1] op_sel_hi:[1,0,0] neg_lo:[1,0,0] neg_hi:[1,0,0]
	v_pk_add_f32 v[170:171], v[156:157], v[172:173]
	v_pk_add_f32 v[156:157], v[156:157], v[172:173] neg_lo:[0,1] neg_hi:[0,1]
	v_pk_fma_f32 v[20:21], v[8:9], v[12:13], v[20:21] op_sel_hi:[0,1,1]
	v_pk_mul_f32 v[172:173], v[156:157], s[24:25]
	v_pk_mul_f32 v[24:25], v[12:13], v[22:23] op_sel:[1,0] op_sel_hi:[0,1]
	v_pk_fma_f32 v[156:157], v[156:157], s[22:23], v[172:173] op_sel:[0,0,1] op_sel_hi:[1,0,0] neg_lo:[1,0,0] neg_hi:[1,0,0]
	v_pk_add_f32 v[172:173], v[208:209], v[194:195]
	v_pk_add_f32 v[194:195], v[208:209], v[194:195] neg_lo:[0,1] neg_hi:[0,1]
	v_pk_add_f32 v[208:209], v[210:211], v[180:181]
	v_pk_add_f32 v[180:181], v[210:211], v[180:181] neg_lo:[0,1] neg_hi:[0,1]
	v_pk_fma_f32 v[36:37], v[8:9], v[28:29], v[36:37] op_sel_hi:[0,1,1]
	v_pk_mul_f32 v[210:211], v[180:181], s[40:41]
	v_pk_mul_f32 v[40:41], v[22:23], v[28:29] op_sel:[0,1] op_sel_hi:[1,0]
	v_pk_fma_f32 v[180:181], v[180:181], s[38:39], v[210:211] op_sel:[0,0,1] op_sel_hi:[1,0,0]
	v_pk_add_f32 v[210:211], v[174:175], v[198:199]
	v_pk_add_f32 v[198:199], v[174:175], v[198:199] neg_lo:[0,1] neg_hi:[0,1]
	v_pk_fma_f32 v[52:53], v[8:9], v[44:45], v[52:53] op_sel_hi:[0,1,1]
	v_pk_add_f32 v[174:175], v[192:193], v[204:205]
	v_pk_add_f32 v[192:193], v[192:193], v[204:205] neg_lo:[0,1] neg_hi:[0,1]
	v_pk_mul_f32 v[56:57], v[22:23], v[44:45] op_sel:[0,1] op_sel_hi:[1,0]
	v_pk_mul_f32 v[204:205], v[192:193], s[40:41]
	v_pk_fma_f32 v[68:69], v[8:9], v[60:61], v[68:69] op_sel_hi:[0,1,1]
	v_pk_fma_f32 v[192:193], v[192:193], s[38:39], v[204:205] op_sel:[0,0,1] op_sel_hi:[1,0,0] neg_lo:[1,0,0] neg_hi:[1,0,0]
	v_pk_add_f32 v[204:205], v[188:189], v[196:197] op_sel:[0,1] op_sel_hi:[1,0] neg_hi:[0,1]
	v_pk_add_f32 v[188:189], v[188:189], v[196:197] op_sel:[0,1] op_sel_hi:[1,0] neg_lo:[0,1]
	v_pk_add_f32 v[196:197], v[158:159], v[182:183]
	v_pk_add_f32 v[158:159], v[158:159], v[182:183] neg_lo:[0,1] neg_hi:[0,1]
	v_pk_mul_f32 v[72:73], v[22:23], v[60:61] op_sel:[0,1] op_sel_hi:[1,0]
	v_pk_mul_f32 v[182:183], v[158:159], s[40:41]
	v_pk_fma_f32 v[84:85], v[8:9], v[76:77], v[84:85] op_sel_hi:[0,1,1]
	v_pk_fma_f32 v[158:159], v[158:159], s[38:39], v[182:183] op_sel:[0,0,1] op_sel_hi:[1,0,0]
	v_pk_add_f32 v[182:183], v[176:177], v[184:185]
	v_pk_add_f32 v[184:185], v[176:177], v[184:185] neg_lo:[0,1] neg_hi:[0,1]
	v_pk_mul_f32 v[88:89], v[22:23], v[76:77] op_sel:[0,1] op_sel_hi:[1,0]
	v_pk_add_f32 v[176:177], v[178:179], v[186:187]
	v_pk_add_f32 v[178:179], v[178:179], v[186:187] neg_lo:[0,1] neg_hi:[0,1]
	v_pk_fma_f32 v[100:101], v[8:9], v[92:93], v[100:101] op_sel_hi:[0,1,1]
	v_pk_mul_f32 v[186:187], v[178:179], s[40:41]
	v_pk_mul_f32 v[104:105], v[22:23], v[92:93] op_sel:[0,1] op_sel_hi:[1,0]
	v_pk_fma_f32 v[178:179], v[178:179], s[38:39], v[186:187] op_sel:[0,0,1] op_sel_hi:[1,0,0] neg_lo:[1,0,0] neg_hi:[1,0,0]
	v_pk_add_f32 v[186:187], v[206:207], v[164:165]
	v_pk_add_f32 v[164:165], v[206:207], v[164:165] neg_lo:[0,1] neg_hi:[0,1]
	v_pk_add_f32 v[206:207], v[190:191], v[150:151]
	v_pk_add_f32 v[150:151], v[190:191], v[150:151] neg_lo:[0,1] neg_hi:[0,1]
	v_pk_fma_f32 v[116:117], v[8:9], v[108:109], v[116:117] op_sel_hi:[0,1,1]
	v_pk_mul_f32 v[190:191], v[150:151], s[40:41]
	v_pk_mul_f32 v[120:121], v[22:23], v[108:109] op_sel:[0,1] op_sel_hi:[1,0]
	v_pk_fma_f32 v[150:151], v[150:151], s[38:39], v[190:191] op_sel:[0,0,1] op_sel_hi:[1,0,0]
	v_pk_add_f32 v[190:191], v[160:161], v[168:169]
	v_pk_add_f32 v[168:169], v[160:161], v[168:169] neg_lo:[0,1] neg_hi:[0,1]
	v_xor_b32_e32 v26, 0x80000000, v19
	v_pk_add_f32 v[160:161], v[162:163], v[170:171]
	v_pk_add_f32 v[162:163], v[162:163], v[170:171] neg_lo:[0,1] neg_hi:[0,1]
	v_xor_b32_e32 v30, 0x80000000, v21
	v_pk_mul_f32 v[170:171], v[162:163], s[40:41]
	v_pk_fma_f32 v[24:25], v[12:13], v[10:11], v[24:25] op_sel_hi:[1,0,1]
	v_pk_fma_f32 v[162:163], v[162:163], s[38:39], v[170:171] op_sel:[0,0,1] op_sel_hi:[1,0,0] neg_lo:[1,0,0] neg_hi:[1,0,0]
	v_pk_add_f32 v[170:171], v[128:129], v[166:167] op_sel:[0,1] op_sel_hi:[1,0] neg_hi:[0,1]
	v_pk_add_f32 v[128:129], v[128:129], v[166:167] op_sel:[0,1] op_sel_hi:[1,0] neg_lo:[0,1]
	v_pk_add_f32 v[166:167], v[130:131], v[152:153]
	v_pk_add_f32 v[130:131], v[130:131], v[152:153] neg_lo:[0,1] neg_hi:[0,1]
	v_pk_fma_f32 v[40:41], v[10:11], v[28:29], v[40:41] op_sel_hi:[0,1,1]
	v_pk_mul_f32 v[152:153], v[130:131], s[40:41]
	v_pk_fma_f32 v[56:57], v[10:11], v[44:45], v[56:57] op_sel_hi:[0,1,1]
	v_pk_fma_f32 v[130:131], v[130:131], s[38:39], v[152:153] op_sel:[0,0,1] op_sel_hi:[1,0,0]
	v_pk_add_f32 v[152:153], v[144:145], v[154:155]
	v_pk_add_f32 v[154:155], v[144:145], v[154:155] neg_lo:[0,1] neg_hi:[0,1]
	v_pk_fma_f32 v[72:73], v[10:11], v[60:61], v[72:73] op_sel_hi:[0,1,1]
	v_pk_add_f32 v[144:145], v[148:149], v[156:157]
	v_pk_add_f32 v[148:149], v[148:149], v[156:157] neg_lo:[0,1] neg_hi:[0,1]
	v_pk_fma_f32 v[88:89], v[10:11], v[76:77], v[88:89] op_sel_hi:[0,1,1]
	v_pk_mul_f32 v[156:157], v[148:149], s[40:41]
	v_pk_fma_f32 v[104:105], v[10:11], v[92:93], v[104:105] op_sel_hi:[0,1,1]
	v_pk_fma_f32 v[148:149], v[148:149], s[38:39], v[156:157] op_sel:[0,0,1] op_sel_hi:[1,0,0] neg_lo:[1,0,0] neg_hi:[1,0,0]
	v_pk_add_f32 v[156:157], v[172:173], v[210:211]
	v_pk_add_f32 v[172:173], v[172:173], v[210:211] neg_lo:[0,1] neg_hi:[0,1]
	v_pk_add_f32 v[210:211], v[208:209], v[174:175]
	v_pk_add_f32 v[208:209], v[208:209], v[174:175] neg_lo:[0,1] neg_hi:[0,1]
	v_pk_fma_f32 v[120:121], v[10:11], v[108:109], v[120:121] op_sel_hi:[0,1,1]
	v_pk_add_f32 v[174:175], v[194:195], v[198:199] op_sel:[0,1] op_sel_hi:[1,0] neg_hi:[0,1]
	v_pk_add_f32 v[194:195], v[194:195], v[198:199] op_sel:[0,1] op_sel_hi:[1,0] neg_lo:[0,1]
	v_pk_add_f32 v[198:199], v[180:181], v[192:193]
	v_pk_add_f32 v[192:193], v[180:181], v[192:193] neg_lo:[0,1] neg_hi:[0,1]
	v_mov_b32_e32 v27, v19
	v_pk_add_f32 v[180:181], v[204:205], v[182:183]
	v_pk_add_f32 v[182:183], v[204:205], v[182:183] neg_lo:[0,1] neg_hi:[0,1]
	v_pk_add_f32 v[204:205], v[196:197], v[176:177]
	v_pk_add_f32 v[196:197], v[196:197], v[176:177] neg_lo:[0,1] neg_hi:[0,1]
	v_mov_b32_e32 v31, v21
	v_pk_add_f32 v[176:177], v[188:189], v[184:185] op_sel:[0,1] op_sel_hi:[1,0] neg_hi:[0,1]
	v_pk_add_f32 v[184:185], v[188:189], v[184:185] op_sel:[0,1] op_sel_hi:[1,0] neg_lo:[0,1]
	v_pk_add_f32 v[188:189], v[158:159], v[178:179]
	v_pk_add_f32 v[178:179], v[158:159], v[178:179] neg_lo:[0,1] neg_hi:[0,1]
	v_xor_b32_e32 v34, 0x80000000, v25
	v_pk_add_f32 v[158:159], v[186:187], v[190:191]
	v_pk_add_f32 v[186:187], v[186:187], v[190:191] neg_lo:[0,1] neg_hi:[0,1]
	v_pk_add_f32 v[190:191], v[206:207], v[160:161]
	v_pk_add_f32 v[206:207], v[206:207], v[160:161] neg_lo:[0,1] neg_hi:[0,1]
	v_xor_b32_e32 v38, 0x80000000, v29
	v_pk_add_f32 v[160:161], v[164:165], v[168:169] op_sel:[0,1] op_sel_hi:[1,0] neg_hi:[0,1]
	v_pk_add_f32 v[164:165], v[164:165], v[168:169] op_sel:[0,1] op_sel_hi:[1,0] neg_lo:[0,1]
	v_pk_add_f32 v[168:169], v[150:151], v[162:163]
	v_pk_add_f32 v[162:163], v[150:151], v[162:163] neg_lo:[0,1] neg_hi:[0,1]
	v_xor_b32_e32 v42, 0x80000000, v33
	v_pk_add_f32 v[150:151], v[170:171], v[152:153]
	v_pk_add_f32 v[152:153], v[170:171], v[152:153] neg_lo:[0,1] neg_hi:[0,1]
	v_pk_add_f32 v[170:171], v[166:167], v[144:145]
	v_pk_add_f32 v[166:167], v[166:167], v[144:145] neg_lo:[0,1] neg_hi:[0,1]
	v_xor_b32_e32 v46, 0x80000000, v37
	v_pk_add_f32 v[144:145], v[128:129], v[154:155] op_sel:[0,1] op_sel_hi:[1,0] neg_hi:[0,1]
	v_pk_add_f32 v[128:129], v[128:129], v[154:155] op_sel:[0,1] op_sel_hi:[1,0] neg_lo:[0,1]
	v_pk_add_f32 v[154:155], v[130:131], v[148:149]
	v_pk_add_f32 v[130:131], v[130:131], v[148:149] neg_lo:[0,1] neg_hi:[0,1]
	v_mov_b32_e32 v35, v25
	v_xor_b32_e32 v149, 0x80000000, v130
	v_mov_b32_e32 v148, v131
	v_pk_add_f32 v[130:131], v[156:157], v[210:211]
	v_pk_add_f32 v[156:157], v[156:157], v[210:211] neg_lo:[0,1] neg_hi:[0,1]
	v_pk_add_f32 v[210:211], v[172:173], v[208:209] op_sel:[0,1] op_sel_hi:[1,0] neg_hi:[0,1]
	v_pk_add_f32 v[172:173], v[172:173], v[208:209] op_sel:[0,1] op_sel_hi:[1,0] neg_lo:[0,1]
	v_pk_add_f32 v[208:209], v[174:175], v[198:199]
	v_pk_add_f32 v[174:175], v[174:175], v[198:199] neg_lo:[0,1] neg_hi:[0,1]
	v_pk_add_f32 v[198:199], v[194:195], v[192:193] op_sel:[0,1] op_sel_hi:[1,0] neg_hi:[0,1]
	v_pk_add_f32 v[192:193], v[194:195], v[192:193] op_sel:[0,1] op_sel_hi:[1,0] neg_lo:[0,1]
	v_pk_add_f32 v[194:195], v[180:181], v[204:205]
	v_pk_add_f32 v[180:181], v[180:181], v[204:205] neg_lo:[0,1] neg_hi:[0,1]
	v_pk_add_f32 v[204:205], v[182:183], v[196:197] op_sel:[0,1] op_sel_hi:[1,0] neg_hi:[0,1]
	v_pk_add_f32 v[182:183], v[182:183], v[196:197] op_sel:[0,1] op_sel_hi:[1,0] neg_lo:[0,1]
	v_pk_add_f32 v[196:197], v[176:177], v[188:189]
	v_pk_add_f32 v[176:177], v[176:177], v[188:189] neg_lo:[0,1] neg_hi:[0,1]
	v_pk_add_f32 v[188:189], v[184:185], v[178:179] op_sel:[0,1] op_sel_hi:[1,0] neg_hi:[0,1]
	v_pk_add_f32 v[178:179], v[184:185], v[178:179] op_sel:[0,1] op_sel_hi:[1,0] neg_lo:[0,1]
	v_pk_add_f32 v[184:185], v[158:159], v[190:191]
	v_pk_add_f32 v[158:159], v[158:159], v[190:191] neg_lo:[0,1] neg_hi:[0,1]
	v_pk_mul_f32 v[4:5], v[4:5], v[184:185] op_sel:[0,1] op_sel_hi:[1,0]
	v_pk_add_f32 v[190:191], v[186:187], v[206:207] op_sel:[0,1] op_sel_hi:[1,0] neg_hi:[0,1]
	v_pk_add_f32 v[186:187], v[186:187], v[206:207] op_sel:[0,1] op_sel_hi:[1,0] neg_lo:[0,1]
	v_pk_add_f32 v[206:207], v[160:161], v[168:169]
	v_pk_add_f32 v[160:161], v[160:161], v[168:169] neg_lo:[0,1] neg_hi:[0,1]
	v_pk_add_f32 v[168:169], v[164:165], v[162:163] op_sel:[0,1] op_sel_hi:[1,0] neg_hi:[0,1]
	v_pk_add_f32 v[162:163], v[164:165], v[162:163] op_sel:[0,1] op_sel_hi:[1,0] neg_lo:[0,1]
	v_pk_add_f32 v[164:165], v[150:151], v[170:171]
	v_pk_fma_f32 v[4:5], v[6:7], v[184:185], v[4:5] op_sel_hi:[0,1,1]
	v_pk_mul_f32 v[6:7], v[14:15], v[194:195] op_sel:[0,1] op_sel_hi:[1,0]
	v_mov_b32_e32 v39, v29
	v_pk_fma_f32 v[6:7], v[8:9], v[194:195], v[6:7] op_sel_hi:[0,1,1]
	v_pk_mul_f32 v[8:9], v[22:23], v[164:165] op_sel:[0,1] op_sel_hi:[1,0]
	v_mov_b32_e32 v43, v33
	v_pk_fma_f32 v[8:9], v[10:11], v[164:165], v[8:9] op_sel_hi:[0,1,1]
	v_pk_mul_f32 v[10:11], v[16:17], v[208:209] op_sel:[0,1] op_sel_hi:[1,0]
	v_mov_b32_e32 v47, v37
	v_pk_add_f32 v[150:151], v[150:151], v[170:171] neg_lo:[0,1] neg_hi:[0,1]
	v_pk_add_f32 v[170:171], v[152:153], v[166:167] op_sel:[0,1] op_sel_hi:[1,0] neg_hi:[0,1]
	v_pk_add_f32 v[152:153], v[152:153], v[166:167] op_sel:[0,1] op_sel_hi:[1,0] neg_lo:[0,1]
	v_pk_add_f32 v[166:167], v[144:145], v[154:155]
	v_pk_fma_f32 v[10:11], v[12:13], v[208:209], v[10:11] op_sel_hi:[0,1,1]
	v_pk_mul_f32 v[12:13], v[26:27], v[206:207] op_sel:[0,1] op_sel_hi:[1,0]
	v_pk_mul_f32 v[14:15], v[30:31], v[196:197] op_sel:[0,1] op_sel_hi:[1,0]
	v_xor_b32_e32 v50, 0x80000000, v41
	v_xor_b32_e32 v54, 0x80000000, v45
	v_xor_b32_e32 v58, 0x80000000, v49
	v_xor_b32_e32 v62, 0x80000000, v53
	v_xor_b32_e32 v66, 0x80000000, v57
	v_xor_b32_e32 v70, 0x80000000, v61
	v_xor_b32_e32 v74, 0x80000000, v65
	v_mov_b32_e32 v51, v41
	v_mov_b32_e32 v55, v45
	v_mov_b32_e32 v59, v49
	v_mov_b32_e32 v63, v53
	v_mov_b32_e32 v67, v57
	v_mov_b32_e32 v71, v61
	v_mov_b32_e32 v75, v65
	v_pk_add_f32 v[144:145], v[144:145], v[154:155] neg_lo:[0,1] neg_hi:[0,1]
	v_pk_add_f32 v[154:155], v[128:129], v[148:149]
	v_pk_fma_f32 v[12:13], v[18:19], v[206:207], v[12:13] op_sel_hi:[0,1,1]
	v_pk_fma_f32 v[14:15], v[20:21], v[196:197], v[14:15] op_sel_hi:[0,1,1]
	v_pk_mul_f32 v[16:17], v[34:35], v[166:167] op_sel:[0,1] op_sel_hi:[1,0]
	v_pk_mul_f32 v[18:19], v[38:39], v[210:211] op_sel:[0,1] op_sel_hi:[1,0]
	v_pk_mul_f32 v[20:21], v[42:43], v[190:191] op_sel:[0,1] op_sel_hi:[1,0]
	v_pk_mul_f32 v[22:23], v[46:47], v[204:205] op_sel:[0,1] op_sel_hi:[1,0]
	v_xor_b32_e32 v78, 0x80000000, v69
	v_xor_b32_e32 v82, 0x80000000, v73
	v_xor_b32_e32 v86, 0x80000000, v77
	v_xor_b32_e32 v90, 0x80000000, v81
	v_xor_b32_e32 v94, 0x80000000, v85
	v_xor_b32_e32 v98, 0x80000000, v89
	v_xor_b32_e32 v102, 0x80000000, v93
	v_xor_b32_e32 v106, 0x80000000, v97
	v_xor_b32_e32 v110, 0x80000000, v101
	v_xor_b32_e32 v114, 0x80000000, v105
	v_xor_b32_e32 v118, 0x80000000, v109
	v_xor_b32_e32 v122, 0x80000000, v113
	v_xor_b32_e32 v124, 0x80000000, v117
	v_xor_b32_e32 v126, 0x80000000, v121
	v_mov_b32_e32 v79, v69
	v_mov_b32_e32 v83, v73
	v_mov_b32_e32 v87, v77
	v_mov_b32_e32 v91, v81
	v_mov_b32_e32 v95, v85
	v_mov_b32_e32 v99, v89
	v_mov_b32_e32 v103, v93
	v_mov_b32_e32 v107, v97
	v_mov_b32_e32 v111, v101
	v_mov_b32_e32 v115, v105
	v_mov_b32_e32 v119, v109
	v_mov_b32_e32 v123, v113
	v_mov_b32_e32 v125, v117
	v_mov_b32_e32 v127, v121
	v_pk_add_f32 v[128:129], v[128:129], v[148:149] neg_lo:[0,1] neg_hi:[0,1]
	v_pk_fma_f32 v[16:17], v[24:25], v[166:167], v[16:17] op_sel_hi:[0,1,1]
	v_pk_fma_f32 v[18:19], v[28:29], v[210:211], v[18:19] op_sel_hi:[0,1,1]
	v_pk_fma_f32 v[20:21], v[32:33], v[190:191], v[20:21] op_sel_hi:[0,1,1]
	v_pk_fma_f32 v[22:23], v[36:37], v[204:205], v[22:23] op_sel_hi:[0,1,1]
	v_pk_mul_f32 v[24:25], v[50:51], v[170:171] op_sel:[0,1] op_sel_hi:[1,0]
	v_pk_mul_f32 v[26:27], v[54:55], v[198:199] op_sel:[0,1] op_sel_hi:[1,0]
	v_pk_mul_f32 v[28:29], v[58:59], v[168:169] op_sel:[0,1] op_sel_hi:[1,0]
	v_pk_mul_f32 v[30:31], v[62:63], v[188:189] op_sel:[0,1] op_sel_hi:[1,0]
	v_pk_mul_f32 v[32:33], v[66:67], v[154:155] op_sel:[0,1] op_sel_hi:[1,0]
	v_pk_mul_f32 v[34:35], v[70:71], v[156:157] op_sel:[0,1] op_sel_hi:[1,0]
	v_pk_mul_f32 v[36:37], v[74:75], v[158:159] op_sel:[0,1] op_sel_hi:[1,0]
	v_pk_fma_f32 v[24:25], v[40:41], v[170:171], v[24:25] op_sel_hi:[0,1,1]
	v_pk_fma_f32 v[26:27], v[44:45], v[198:199], v[26:27] op_sel_hi:[0,1,1]
	v_pk_fma_f32 v[28:29], v[48:49], v[168:169], v[28:29] op_sel_hi:[0,1,1]
	v_pk_fma_f32 v[30:31], v[52:53], v[188:189], v[30:31] op_sel_hi:[0,1,1]
	v_pk_fma_f32 v[32:33], v[56:57], v[154:155], v[32:33] op_sel_hi:[0,1,1]
	v_pk_fma_f32 v[34:35], v[60:61], v[156:157], v[34:35] op_sel_hi:[0,1,1]
	v_pk_fma_f32 v[36:37], v[64:65], v[158:159], v[36:37] op_sel_hi:[0,1,1]
	v_pk_mul_f32 v[38:39], v[78:79], v[180:181] op_sel:[0,1] op_sel_hi:[1,0]
	v_pk_mul_f32 v[40:41], v[82:83], v[150:151] op_sel:[0,1] op_sel_hi:[1,0]
	v_pk_mul_f32 v[42:43], v[86:87], v[174:175] op_sel:[0,1] op_sel_hi:[1,0]
	v_pk_mul_f32 v[44:45], v[90:91], v[160:161] op_sel:[0,1] op_sel_hi:[1,0]
	v_pk_mul_f32 v[46:47], v[94:95], v[176:177] op_sel:[0,1] op_sel_hi:[1,0]
	v_pk_mul_f32 v[48:49], v[98:99], v[144:145] op_sel:[0,1] op_sel_hi:[1,0]
	v_pk_mul_f32 v[50:51], v[102:103], v[172:173] op_sel:[0,1] op_sel_hi:[1,0]
	v_pk_mul_f32 v[52:53], v[106:107], v[186:187] op_sel:[0,1] op_sel_hi:[1,0]
	v_pk_mul_f32 v[54:55], v[110:111], v[182:183] op_sel:[0,1] op_sel_hi:[1,0]
	v_pk_mul_f32 v[56:57], v[114:115], v[152:153] op_sel:[0,1] op_sel_hi:[1,0]
	v_pk_mul_f32 v[58:59], v[118:119], v[192:193] op_sel:[0,1] op_sel_hi:[1,0]
	v_pk_mul_f32 v[60:61], v[122:123], v[162:163] op_sel:[0,1] op_sel_hi:[1,0]
	v_pk_mul_f32 v[62:63], v[124:125], v[178:179] op_sel:[0,1] op_sel_hi:[1,0]
	v_pk_mul_f32 v[64:65], v[126:127], v[128:129] op_sel:[0,1] op_sel_hi:[1,0]
	v_pk_fma_f32 v[38:39], v[68:69], v[180:181], v[38:39] op_sel_hi:[0,1,1]
	v_pk_fma_f32 v[40:41], v[72:73], v[150:151], v[40:41] op_sel_hi:[0,1,1]
	v_pk_fma_f32 v[42:43], v[76:77], v[174:175], v[42:43] op_sel_hi:[0,1,1]
	v_pk_fma_f32 v[44:45], v[80:81], v[160:161], v[44:45] op_sel_hi:[0,1,1]
	v_pk_fma_f32 v[46:47], v[84:85], v[176:177], v[46:47] op_sel_hi:[0,1,1]
	v_pk_fma_f32 v[48:49], v[88:89], v[144:145], v[48:49] op_sel_hi:[0,1,1]
	v_pk_fma_f32 v[50:51], v[92:93], v[172:173], v[50:51] op_sel_hi:[0,1,1]
	v_pk_fma_f32 v[52:53], v[96:97], v[186:187], v[52:53] op_sel_hi:[0,1,1]
	v_pk_fma_f32 v[54:55], v[100:101], v[182:183], v[54:55] op_sel_hi:[0,1,1]
	v_pk_fma_f32 v[56:57], v[104:105], v[152:153], v[56:57] op_sel_hi:[0,1,1]
	v_pk_fma_f32 v[58:59], v[108:109], v[192:193], v[58:59] op_sel_hi:[0,1,1]
	v_pk_fma_f32 v[60:61], v[112:113], v[162:163], v[60:61] op_sel_hi:[0,1,1]
	v_pk_fma_f32 v[62:63], v[116:117], v[178:179], v[62:63] op_sel_hi:[0,1,1]
	v_pk_fma_f32 v[64:65], v[120:121], v[128:129], v[64:65] op_sel_hi:[0,1,1]
	ds_write_b64 v2, v[130:131]
	ds_write_b64 v2, v[34:35] offset:2112
	ds_write_b64 v2, v[18:19] offset:4224
	ds_write_b64 v2, v[50:51] offset:6336
	ds_write_b64 v2, v[10:11] offset:8448
	ds_write_b64 v2, v[42:43] offset:10560
	ds_write_b64 v2, v[26:27] offset:12672
	ds_write_b64 v2, v[58:59] offset:14784
	ds_write_b64 v2, v[6:7] offset:16896
	ds_write_b64 v2, v[38:39] offset:19008
	ds_write_b64 v2, v[22:23] offset:21120
	ds_write_b64 v2, v[54:55] offset:23232
	ds_write_b64 v2, v[14:15] offset:25344
	ds_write_b64 v2, v[46:47] offset:27456
	ds_write_b64 v2, v[30:31] offset:29568
	ds_write_b64 v2, v[62:63] offset:31680
	ds_write_b64 v2, v[4:5] offset:33792
	ds_write_b64 v2, v[36:37] offset:35904
	ds_write_b64 v2, v[20:21] offset:38016
	ds_write_b64 v2, v[52:53] offset:40128
	ds_write_b64 v2, v[12:13] offset:42240
	ds_write_b64 v2, v[44:45] offset:44352
	ds_write_b64 v2, v[28:29] offset:46464
	ds_write_b64 v2, v[60:61] offset:48576
	ds_write_b64 v2, v[8:9] offset:50688
	ds_write_b64 v2, v[40:41] offset:52800
	ds_write_b64 v2, v[24:25] offset:54912
	ds_write_b64 v2, v[56:57] offset:57024
	ds_write_b64 v2, v[16:17] offset:59136
	ds_write_b64 v2, v[48:49] offset:61248
	ds_write_b64 v2, v[32:33] offset:63360
	ds_write_b64 v2, v[64:65] offset:65472
	v_mov_b32_e32 v2, v142
	s_waitcnt lgkmcnt(0)
	s_barrier
	s_nop 0
	v_and_b32_e32 v5, 15, v2
	v_cvt_f32_ubyte0_e32 v4, v5
	v_mul_f32_e32 v6, 0x3b800000, v4
	v_sin_f32_e32 v4, v6
	v_cos_f32_e32 v6, v6
	v_lshlrev_b32_e32 v64, 3, v5
	v_lshlrev_b32_e32 v2, 4, v2
	v_xor_b32_e32 v7, 0x80000000, v4
	v_mov_b32_e32 v5, v7
	v_pk_mul_f32 v[8:9], v[6:7], v[4:5] op_sel:[1,0] op_sel_hi:[0,1]
	v_pk_fma_f32 v[8:9], v[6:7], v[6:7], v[8:9] op_sel_hi:[1,0,1]
	v_and_b32_e32 v2, 0xffffff00, v2
	v_xor_b32_e32 v14, 0x80000000, v9
	v_mov_b32_e32 v15, v9
	v_pk_mul_f32 v[12:13], v[8:9], v[14:15] op_sel:[1,0] op_sel_hi:[0,1]
	v_pk_fma_f32 v[12:13], v[8:9], v[8:9], v[12:13] op_sel_hi:[1,0,1]
	v_pk_mul_f32 v[10:11], v[4:5], v[8:9] op_sel:[0,1] op_sel_hi:[1,0]
	v_xor_b32_e32 v16, 0x80000000, v13
	v_mov_b32_e32 v17, v13
	v_pk_mul_f32 v[32:33], v[12:13], v[16:17] op_sel:[1,0] op_sel_hi:[0,1]
	v_pk_fma_f32 v[32:33], v[12:13], v[12:13], v[32:33] op_sel_hi:[1,0,1]
	v_pk_mul_f32 v[18:19], v[4:5], v[12:13] op_sel:[0,1] op_sel_hi:[1,0]
	v_pk_mul_f32 v[48:49], v[16:17], v[32:33] op_sel:[0,1] op_sel_hi:[1,0]
	v_pk_mul_f32 v[36:37], v[4:5], v[32:33] op_sel:[0,1] op_sel_hi:[1,0]
	v_pk_fma_f32 v[48:49], v[12:13], v[32:33], v[48:49] op_sel_hi:[0,1,1]
	v_pk_mul_f32 v[52:53], v[4:5], v[48:49] op_sel:[0,1] op_sel_hi:[1,0]
	v_pk_fma_f32 v[10:11], v[6:7], v[8:9], v[10:11] op_sel_hi:[0,1,1]
	v_pk_fma_f32 v[18:19], v[6:7], v[12:13], v[18:19] op_sel_hi:[0,1,1]
	v_pk_fma_f32 v[36:37], v[6:7], v[32:33], v[36:37] op_sel_hi:[0,1,1]
	v_pk_fma_f32 v[52:53], v[6:7], v[48:49], v[52:53] op_sel_hi:[0,1,1]
	v_lshlrev_b32_e32 v7, 3, v2
	v_add3_u32 v7, 0, v64, v7
	v_ashrrev_i32_e32 v64, 2, v2
	v_add_u32_e32 v106, v7, v64
	ds_read2_b64 v[64:67], v106 offset1:16
	ds_read2_b64 v[68:71], v106 offset0:33 offset1:49
	ds_read2_b64 v[72:75], v106 offset0:66 offset1:82
	ds_read2_b64 v[76:79], v106 offset0:132 offset1:148
	ds_read2_b64 v[80:83], v106 offset0:99 offset1:115
	ds_read2_b64 v[84:87], v106 offset0:165 offset1:181
	ds_read2_b64 v[88:91], v106 offset0:198 offset1:214
	ds_read2_b64 v[92:95], v106 offset0:231 offset1:247
	s_waitcnt lgkmcnt(4)
	v_pk_add_f32 v[96:97], v[64:65], v[76:77]
	v_pk_add_f32 v[64:65], v[64:65], v[76:77] neg_lo:[0,1] neg_hi:[0,1]
	v_pk_add_f32 v[76:77], v[66:67], v[78:79]
	v_pk_add_f32 v[66:67], v[66:67], v[78:79] neg_lo:[0,1] neg_hi:[0,1]
	s_waitcnt lgkmcnt(1)
	v_pk_add_f32 v[98:99], v[74:75], v[90:91]
	v_pk_mul_f32 v[78:79], v[66:67], s[24:25]
	v_pk_add_f32 v[74:75], v[74:75], v[90:91] neg_lo:[0,1] neg_hi:[0,1]
	v_pk_fma_f32 v[66:67], v[66:67], s[22:23], v[78:79] op_sel:[0,0,1] op_sel_hi:[1,0,0]
	v_pk_add_f32 v[78:79], v[68:69], v[84:85]
	v_pk_add_f32 v[68:69], v[68:69], v[84:85] neg_lo:[0,1] neg_hi:[0,1]
	v_pk_mul_f32 v[90:91], v[74:75], s[44:45]
	v_pk_mul_f32 v[84:85], v[68:69], s[40:41]
	v_pk_fma_f32 v[74:75], v[74:75], s[50:51], v[90:91] op_sel:[0,0,1] op_sel_hi:[1,0,0] neg_lo:[1,0,0] neg_hi:[1,0,0]
	v_pk_fma_f32 v[68:69], v[68:69], s[38:39], v[84:85] op_sel:[0,0,1] op_sel_hi:[1,0,0]
	v_pk_add_f32 v[84:85], v[70:71], v[86:87]
	v_pk_add_f32 v[70:71], v[70:71], v[86:87] neg_lo:[0,1] neg_hi:[0,1]
	s_waitcnt lgkmcnt(0)
	v_pk_add_f32 v[90:91], v[80:81], v[92:93]
	v_pk_add_f32 v[80:81], v[80:81], v[92:93] neg_lo:[0,1] neg_hi:[0,1]
	v_pk_mul_f32 v[86:87], v[70:71], s[44:45]
	v_pk_mul_f32 v[92:93], v[80:81], s[40:41]
	v_pk_fma_f32 v[70:71], v[70:71], s[50:51], v[86:87] op_sel:[0,0,1] op_sel_hi:[1,0,0]
	v_pk_add_f32 v[86:87], v[72:73], v[88:89]
	v_pk_add_f32 v[88:89], v[72:73], v[88:89] neg_lo:[0,1] neg_hi:[0,1]
	v_pk_fma_f32 v[80:81], v[80:81], s[38:39], v[92:93] op_sel:[0,0,1] op_sel_hi:[1,0,0] neg_lo:[1,0,0] neg_hi:[1,0,0]
	v_pk_add_f32 v[92:93], v[82:83], v[94:95]
	v_pk_add_f32 v[82:83], v[82:83], v[94:95] neg_lo:[0,1] neg_hi:[0,1]
	v_pk_mul_f32 v[94:95], v[82:83], s[24:25]
	v_pk_fma_f32 v[82:83], v[82:83], s[22:23], v[94:95] op_sel:[0,0,1] op_sel_hi:[1,0,0] neg_lo:[1,0,0] neg_hi:[1,0,0]
	v_pk_add_f32 v[94:95], v[96:97], v[86:87]
	v_pk_add_f32 v[86:87], v[96:97], v[86:87] neg_lo:[0,1] neg_hi:[0,1]
	v_pk_add_f32 v[96:97], v[76:77], v[98:99]
	v_pk_add_f32 v[76:77], v[76:77], v[98:99] neg_lo:[0,1] neg_hi:[0,1]
	v_pk_add_f32 v[100:101], v[84:85], v[92:93]
	v_pk_add_f32 v[84:85], v[84:85], v[92:93] neg_lo:[0,1] neg_hi:[0,1]
	v_pk_add_f32 v[72:73], v[64:65], v[88:89] op_sel:[0,1] op_sel_hi:[1,0] neg_hi:[0,1]
	v_pk_add_f32 v[64:65], v[64:65], v[88:89] op_sel:[0,1] op_sel_hi:[1,0] neg_lo:[0,1]
	v_pk_add_f32 v[88:89], v[66:67], v[74:75]
	v_pk_add_f32 v[66:67], v[66:67], v[74:75] neg_lo:[0,1] neg_hi:[0,1]
	v_pk_mul_f32 v[98:99], v[76:77], s[40:41]
	v_pk_mul_f32 v[92:93], v[84:85], s[40:41]
	v_pk_mul_f32 v[74:75], v[66:67], s[40:41]
	v_pk_fma_f32 v[76:77], v[76:77], s[38:39], v[98:99] op_sel:[0,0,1] op_sel_hi:[1,0,0]
	v_pk_add_f32 v[98:99], v[78:79], v[90:91]
	v_pk_add_f32 v[90:91], v[78:79], v[90:91] neg_lo:[0,1] neg_hi:[0,1]
	v_pk_fma_f32 v[84:85], v[84:85], s[38:39], v[92:93] op_sel:[0,0,1] op_sel_hi:[1,0,0] neg_lo:[1,0,0] neg_hi:[1,0,0]
	v_pk_fma_f32 v[66:67], v[66:67], s[38:39], v[74:75] op_sel:[0,0,1] op_sel_hi:[1,0,0]
	v_pk_add_f32 v[74:75], v[68:69], v[80:81]
	v_pk_add_f32 v[92:93], v[70:71], v[82:83]
	v_pk_add_f32 v[70:71], v[70:71], v[82:83] neg_lo:[0,1] neg_hi:[0,1]
	v_pk_add_f32 v[68:69], v[68:69], v[80:81] neg_lo:[0,1] neg_hi:[0,1]
	v_pk_mul_f32 v[82:83], v[70:71], s[40:41]
	v_pk_add_f32 v[102:103], v[72:73], v[74:75]
	v_pk_add_f32 v[72:73], v[72:73], v[74:75] neg_lo:[0,1] neg_hi:[0,1]
	v_pk_add_f32 v[74:75], v[88:89], v[92:93]
	v_pk_add_f32 v[92:93], v[88:89], v[92:93] neg_lo:[0,1] neg_hi:[0,1]
	v_xor_b32_e32 v20, 0x80000000, v11
	v_mov_b32_e32 v21, v11
	v_pk_mul_f32 v[24:25], v[14:15], v[12:13] op_sel:[0,1] op_sel_hi:[1,0]
	v_xor_b32_e32 v81, 0x80000000, v68
	v_pk_fma_f32 v[70:71], v[70:71], s[38:39], v[82:83] op_sel:[0,0,1] op_sel_hi:[1,0,0] neg_lo:[1,0,0] neg_hi:[1,0,0]
	v_pk_add_f32 v[78:79], v[86:87], v[90:91] op_sel:[0,1] op_sel_hi:[1,0] neg_hi:[0,1]
	v_pk_add_f32 v[86:87], v[86:87], v[90:91] op_sel:[0,1] op_sel_hi:[1,0] neg_lo:[0,1]
	v_pk_add_f32 v[90:91], v[76:77], v[84:85]
	v_pk_add_f32 v[84:85], v[76:77], v[84:85] neg_lo:[0,1] neg_hi:[0,1]
	v_mov_b32_e32 v80, v69
	v_xor_b32_e32 v22, 0x80000000, v19
	v_mov_b32_e32 v23, v19
	v_pk_fma_f32 v[24:25], v[8:9], v[12:13], v[24:25] op_sel_hi:[0,1,1]
	v_pk_mul_f32 v[28:29], v[12:13], v[20:21] op_sel:[1,0] op_sel_hi:[0,1]
	v_pk_add_f32 v[68:69], v[64:65], v[80:81]
	v_pk_add_f32 v[64:65], v[64:65], v[80:81] neg_lo:[0,1] neg_hi:[0,1]
	v_pk_add_f32 v[80:81], v[66:67], v[70:71]
	v_pk_add_f32 v[70:71], v[66:67], v[70:71] neg_lo:[0,1] neg_hi:[0,1]
	v_pk_add_f32 v[88:89], v[72:73], v[92:93] op_sel:[0,1] op_sel_hi:[1,0] neg_hi:[0,1]
	v_xor_b32_e32 v26, 0x80000000, v25
	v_mov_b32_e32 v27, v25
	v_pk_fma_f32 v[28:29], v[12:13], v[10:11], v[28:29] op_sel_hi:[1,0,1]
	v_pk_add_f32 v[76:77], v[86:87], v[84:85] op_sel:[0,1] op_sel_hi:[1,0] neg_hi:[0,1]
	v_pk_add_f32 v[72:73], v[72:73], v[92:93] op_sel:[0,1] op_sel_hi:[1,0] neg_lo:[0,1]
	v_pk_mul_f32 v[92:93], v[22:23], v[88:89] op_sel:[0,1] op_sel_hi:[1,0]
	v_xor_b32_e32 v30, 0x80000000, v29
	v_mov_b32_e32 v31, v29
	v_pk_add_f32 v[82:83], v[94:95], v[98:99]
	v_pk_add_f32 v[94:95], v[94:95], v[98:99] neg_lo:[0,1] neg_hi:[0,1]
	v_pk_add_f32 v[98:99], v[96:97], v[100:101]
	v_pk_add_f32 v[66:67], v[64:65], v[70:71] op_sel:[0,1] op_sel_hi:[1,0] neg_hi:[0,1]
	v_pk_fma_f32 v[88:89], v[18:19], v[88:89], v[92:93] op_sel_hi:[0,1,1]
	v_pk_mul_f32 v[92:93], v[26:27], v[76:77] op_sel:[0,1] op_sel_hi:[1,0]
	v_xor_b32_e32 v34, 0x80000000, v33
	v_mov_b32_e32 v35, v33
	v_pk_mul_f32 v[40:41], v[14:15], v[32:33] op_sel:[0,1] op_sel_hi:[1,0]
	v_pk_add_f32 v[104:105], v[82:83], v[98:99]
	v_pk_add_f32 v[82:83], v[82:83], v[98:99] neg_lo:[0,1] neg_hi:[0,1]
	v_pk_fma_f32 v[76:77], v[24:25], v[76:77], v[92:93] op_sel_hi:[0,1,1]
	v_pk_mul_f32 v[92:93], v[30:31], v[66:67] op_sel:[0,1] op_sel_hi:[1,0]
	v_xor_b32_e32 v38, 0x80000000, v37
	v_mov_b32_e32 v39, v37
	v_pk_fma_f32 v[40:41], v[8:9], v[32:33], v[40:41] op_sel_hi:[0,1,1]
	v_pk_mul_f32 v[44:45], v[20:21], v[32:33] op_sel:[0,1] op_sel_hi:[1,0]
	v_pk_add_f32 v[84:85], v[86:87], v[84:85] op_sel:[0,1] op_sel_hi:[1,0] neg_lo:[0,1]
	v_pk_add_f32 v[86:87], v[102:103], v[74:75]
	v_pk_add_f32 v[74:75], v[102:103], v[74:75] neg_lo:[0,1] neg_hi:[0,1]
	v_pk_fma_f32 v[66:67], v[28:29], v[66:67], v[92:93] op_sel_hi:[0,1,1]
	v_pk_mul_f32 v[92:93], v[34:35], v[82:83] op_sel:[0,1] op_sel_hi:[1,0]
	v_xor_b32_e32 v42, 0x80000000, v41
	v_mov_b32_e32 v43, v41
	v_pk_fma_f32 v[44:45], v[10:11], v[32:33], v[44:45] op_sel_hi:[0,1,1]
	v_pk_add_f32 v[100:101], v[96:97], v[100:101] neg_lo:[0,1] neg_hi:[0,1]
	v_pk_add_f32 v[98:99], v[78:79], v[90:91]
	v_pk_add_f32 v[78:79], v[78:79], v[90:91] neg_lo:[0,1] neg_hi:[0,1]
	v_pk_fma_f32 v[82:83], v[32:33], v[82:83], v[92:93] op_sel_hi:[0,1,1]
	v_pk_mul_f32 v[92:93], v[38:39], v[74:75] op_sel:[0,1] op_sel_hi:[1,0]
	v_xor_b32_e32 v46, 0x80000000, v45
	v_mov_b32_e32 v47, v45
	v_pk_add_f32 v[90:91], v[68:69], v[80:81]
	v_pk_add_f32 v[68:69], v[68:69], v[80:81] neg_lo:[0,1] neg_hi:[0,1]
	v_pk_fma_f32 v[74:75], v[36:37], v[74:75], v[92:93] op_sel_hi:[0,1,1]
	v_pk_mul_f32 v[92:93], v[42:43], v[78:79] op_sel:[0,1] op_sel_hi:[1,0]
	v_xor_b32_e32 v50, 0x80000000, v49
	v_mov_b32_e32 v51, v49
	v_pk_mul_f32 v[56:57], v[14:15], v[48:49] op_sel:[0,1] op_sel_hi:[1,0]
	v_pk_add_f32 v[96:97], v[94:95], v[100:101] op_sel:[0,1] op_sel_hi:[1,0] neg_hi:[0,1]
	v_pk_add_f32 v[94:95], v[94:95], v[100:101] op_sel:[0,1] op_sel_hi:[1,0] neg_lo:[0,1]
	v_pk_fma_f32 v[78:79], v[40:41], v[78:79], v[92:93] op_sel_hi:[0,1,1]
	v_pk_mul_f32 v[92:93], v[46:47], v[68:69] op_sel:[0,1] op_sel_hi:[1,0]
	v_xor_b32_e32 v54, 0x80000000, v53
	v_mov_b32_e32 v55, v53
	v_pk_fma_f32 v[56:57], v[8:9], v[48:49], v[56:57] op_sel_hi:[0,1,1]
	v_pk_mul_f32 v[60:61], v[20:21], v[48:49] op_sel:[0,1] op_sel_hi:[1,0]
	v_pk_fma_f32 v[68:69], v[44:45], v[68:69], v[92:93] op_sel_hi:[0,1,1]
	v_pk_mul_f32 v[92:93], v[50:51], v[94:95] op_sel:[0,1] op_sel_hi:[1,0]
	v_xor_b32_e32 v58, 0x80000000, v57
	v_mov_b32_e32 v59, v57
	v_pk_fma_f32 v[60:61], v[10:11], v[48:49], v[60:61] op_sel_hi:[0,1,1]
	v_pk_add_f32 v[64:65], v[64:65], v[70:71] op_sel:[0,1] op_sel_hi:[1,0] neg_lo:[0,1]
	v_pk_mul_f32 v[70:71], v[4:5], v[86:87] op_sel:[0,1] op_sel_hi:[1,0]
	v_pk_fma_f32 v[92:93], v[48:49], v[94:95], v[92:93] op_sel_hi:[0,1,1]
	v_pk_mul_f32 v[94:95], v[54:55], v[72:73] op_sel:[0,1] op_sel_hi:[1,0]
	v_xor_b32_e32 v62, 0x80000000, v61
	v_mov_b32_e32 v63, v61
	v_pk_fma_f32 v[70:71], v[6:7], v[86:87], v[70:71] op_sel_hi:[0,1,1]
	v_pk_mul_f32 v[86:87], v[20:21], v[90:91] op_sel:[0,1] op_sel_hi:[1,0]
	v_pk_fma_f32 v[72:73], v[52:53], v[72:73], v[94:95] op_sel_hi:[0,1,1]
	v_pk_mul_f32 v[94:95], v[58:59], v[84:85] op_sel:[0,1] op_sel_hi:[1,0]
	v_add_u32_e32 v2, 0x2000, v2
	v_pk_mul_f32 v[80:81], v[14:15], v[98:99] op_sel:[0,1] op_sel_hi:[1,0]
	v_pk_fma_f32 v[86:87], v[10:11], v[90:91], v[86:87] op_sel_hi:[0,1,1]
	v_pk_mul_f32 v[90:91], v[16:17], v[96:97] op_sel:[0,1] op_sel_hi:[1,0]
	v_pk_fma_f32 v[84:85], v[56:57], v[84:85], v[94:95] op_sel_hi:[0,1,1]
	v_pk_mul_f32 v[94:95], v[62:63], v[64:65] op_sel:[0,1] op_sel_hi:[1,0]
	v_ashrrev_i32_e32 v2, 2, v2
	v_pk_fma_f32 v[80:81], v[8:9], v[98:99], v[80:81] op_sel_hi:[0,1,1]
	v_pk_fma_f32 v[90:91], v[12:13], v[96:97], v[90:91] op_sel_hi:[0,1,1]
	v_pk_fma_f32 v[64:65], v[60:61], v[64:65], v[94:95] op_sel_hi:[0,1,1]
	ds_write2_b64 v106, v[104:105], v[82:83] offset1:16
	ds_write2_b64 v106, v[90:91], v[92:93] offset0:33 offset1:49
	ds_write2_b64 v106, v[80:81], v[78:79] offset0:66 offset1:82
	ds_write2_b64 v106, v[76:77], v[84:85] offset0:99 offset1:115
	ds_write2_b64 v106, v[70:71], v[74:75] offset0:132 offset1:148
	ds_write2_b64 v106, v[88:89], v[72:73] offset0:165 offset1:181
	ds_write2_b64 v106, v[86:87], v[68:69] offset0:198 offset1:214
	ds_write2_b64 v106, v[66:67], v[64:65] offset0:231 offset1:247
	v_add3_u32 v2, v7, v2, s60
	ds_read2_b64 v[64:67], v2 offset1:16
	ds_read2_b64 v[68:71], v2 offset0:33 offset1:49
	ds_read2_b64 v[72:75], v2 offset0:66 offset1:82
	ds_read2_b64 v[76:79], v2 offset0:132 offset1:148
	ds_read2_b64 v[80:83], v2 offset0:99 offset1:115
	ds_read2_b64 v[84:87], v2 offset0:165 offset1:181
	ds_read2_b64 v[88:91], v2 offset0:198 offset1:214
	ds_read2_b64 v[92:95], v2 offset0:231 offset1:247
	s_waitcnt lgkmcnt(4)
	v_pk_add_f32 v[96:97], v[64:65], v[76:77]
	v_pk_add_f32 v[64:65], v[64:65], v[76:77] neg_lo:[0,1] neg_hi:[0,1]
	v_pk_add_f32 v[76:77], v[66:67], v[78:79]
	v_pk_add_f32 v[66:67], v[66:67], v[78:79] neg_lo:[0,1] neg_hi:[0,1]
	s_waitcnt lgkmcnt(1)
	v_pk_add_f32 v[98:99], v[74:75], v[90:91]
	v_pk_mul_f32 v[78:79], v[66:67], s[24:25]
	v_pk_add_f32 v[74:75], v[74:75], v[90:91] neg_lo:[0,1] neg_hi:[0,1]
	v_pk_fma_f32 v[66:67], v[66:67], s[22:23], v[78:79] op_sel:[0,0,1] op_sel_hi:[1,0,0]
	v_pk_add_f32 v[78:79], v[68:69], v[84:85]
	v_pk_add_f32 v[68:69], v[68:69], v[84:85] neg_lo:[0,1] neg_hi:[0,1]
	v_pk_mul_f32 v[90:91], v[74:75], s[44:45]
	v_pk_mul_f32 v[84:85], v[68:69], s[40:41]
	v_pk_fma_f32 v[74:75], v[74:75], s[50:51], v[90:91] op_sel:[0,0,1] op_sel_hi:[1,0,0] neg_lo:[1,0,0] neg_hi:[1,0,0]
	s_waitcnt lgkmcnt(0)
	v_pk_add_f32 v[90:91], v[80:81], v[92:93]
	v_pk_add_f32 v[80:81], v[80:81], v[92:93] neg_lo:[0,1] neg_hi:[0,1]
	v_pk_fma_f32 v[68:69], v[68:69], s[38:39], v[84:85] op_sel:[0,0,1] op_sel_hi:[1,0,0]
	v_pk_add_f32 v[84:85], v[70:71], v[86:87]
	v_pk_add_f32 v[70:71], v[70:71], v[86:87] neg_lo:[0,1] neg_hi:[0,1]
	v_pk_mul_f32 v[92:93], v[80:81], s[40:41]
	v_pk_mul_f32 v[86:87], v[70:71], s[44:45]
	v_pk_fma_f32 v[80:81], v[80:81], s[38:39], v[92:93] op_sel:[0,0,1] op_sel_hi:[1,0,0] neg_lo:[1,0,0] neg_hi:[1,0,0]
	v_pk_add_f32 v[92:93], v[82:83], v[94:95]
	v_pk_add_f32 v[82:83], v[82:83], v[94:95] neg_lo:[0,1] neg_hi:[0,1]
	v_pk_fma_f32 v[70:71], v[70:71], s[50:51], v[86:87] op_sel:[0,0,1] op_sel_hi:[1,0,0]
	v_pk_add_f32 v[86:87], v[72:73], v[88:89]
	v_pk_mul_f32 v[94:95], v[82:83], s[24:25]
	v_pk_add_f32 v[88:89], v[72:73], v[88:89] neg_lo:[0,1] neg_hi:[0,1]
	v_pk_fma_f32 v[82:83], v[82:83], s[22:23], v[94:95] op_sel:[0,0,1] op_sel_hi:[1,0,0] neg_lo:[1,0,0] neg_hi:[1,0,0]
	v_pk_add_f32 v[94:95], v[96:97], v[86:87]
	v_pk_add_f32 v[86:87], v[96:97], v[86:87] neg_lo:[0,1] neg_hi:[0,1]
	v_pk_add_f32 v[96:97], v[76:77], v[98:99]
	v_pk_add_f32 v[76:77], v[76:77], v[98:99] neg_lo:[0,1] neg_hi:[0,1]
	v_pk_mul_f32 v[98:99], v[76:77], s[40:41]
	v_pk_add_f32 v[100:101], v[84:85], v[92:93]
	v_pk_add_f32 v[84:85], v[84:85], v[92:93] neg_lo:[0,1] neg_hi:[0,1]
	v_pk_fma_f32 v[76:77], v[76:77], s[38:39], v[98:99] op_sel:[0,0,1] op_sel_hi:[1,0,0]
	v_pk_add_f32 v[98:99], v[78:79], v[90:91]
	v_pk_add_f32 v[90:91], v[78:79], v[90:91] neg_lo:[0,1] neg_hi:[0,1]
	v_pk_mul_f32 v[92:93], v[84:85], s[40:41]
	v_pk_add_f32 v[72:73], v[64:65], v[88:89] op_sel:[0,1] op_sel_hi:[1,0] neg_hi:[0,1]
	v_pk_add_f32 v[64:65], v[64:65], v[88:89] op_sel:[0,1] op_sel_hi:[1,0] neg_lo:[0,1]
	v_pk_add_f32 v[88:89], v[66:67], v[74:75]
	v_pk_add_f32 v[66:67], v[66:67], v[74:75] neg_lo:[0,1] neg_hi:[0,1]
	v_pk_fma_f32 v[84:85], v[84:85], s[38:39], v[92:93] op_sel:[0,0,1] op_sel_hi:[1,0,0] neg_lo:[1,0,0] neg_hi:[1,0,0]
	v_pk_mul_f32 v[74:75], v[66:67], s[40:41]
	v_pk_fma_f32 v[66:67], v[66:67], s[38:39], v[74:75] op_sel:[0,0,1] op_sel_hi:[1,0,0]
	v_pk_add_f32 v[74:75], v[68:69], v[80:81]
	v_pk_add_f32 v[92:93], v[70:71], v[82:83]
	v_pk_add_f32 v[70:71], v[70:71], v[82:83] neg_lo:[0,1] neg_hi:[0,1]
	v_pk_add_f32 v[78:79], v[86:87], v[90:91] op_sel:[0,1] op_sel_hi:[1,0] neg_hi:[0,1]
	v_pk_add_f32 v[86:87], v[86:87], v[90:91] op_sel:[0,1] op_sel_hi:[1,0] neg_lo:[0,1]
	v_pk_add_f32 v[90:91], v[76:77], v[84:85]
	v_pk_add_f32 v[84:85], v[76:77], v[84:85] neg_lo:[0,1] neg_hi:[0,1]
	v_pk_add_f32 v[80:81], v[68:69], v[80:81] neg_lo:[0,1] neg_hi:[0,1]
	v_pk_mul_f32 v[82:83], v[70:71], s[40:41]
	v_pk_add_f32 v[102:103], v[72:73], v[74:75]
	v_pk_add_f32 v[72:73], v[72:73], v[74:75] neg_lo:[0,1] neg_hi:[0,1]
	v_pk_add_f32 v[74:75], v[88:89], v[92:93]
	v_pk_fma_f32 v[70:71], v[70:71], s[38:39], v[82:83] op_sel:[0,0,1] op_sel_hi:[1,0,0] neg_lo:[1,0,0] neg_hi:[1,0,0]
	v_pk_add_f32 v[82:83], v[94:95], v[98:99]
	v_pk_add_f32 v[94:95], v[94:95], v[98:99] neg_lo:[0,1] neg_hi:[0,1]
	v_pk_add_f32 v[98:99], v[96:97], v[100:101]
	v_pk_add_f32 v[76:77], v[86:87], v[84:85] op_sel:[0,1] op_sel_hi:[1,0] neg_hi:[0,1]
	v_pk_add_f32 v[84:85], v[86:87], v[84:85] op_sel:[0,1] op_sel_hi:[1,0] neg_lo:[0,1]
	v_pk_add_f32 v[86:87], v[102:103], v[74:75]
	v_pk_add_f32 v[96:97], v[96:97], v[100:101] neg_lo:[0,1] neg_hi:[0,1]
	v_pk_add_f32 v[68:69], v[64:65], v[80:81] op_sel:[0,1] op_sel_hi:[1,0] neg_hi:[0,1]
	v_pk_add_f32 v[64:65], v[64:65], v[80:81] op_sel:[0,1] op_sel_hi:[1,0] neg_lo:[0,1]
	v_pk_add_f32 v[80:81], v[66:67], v[70:71]
	v_pk_add_f32 v[104:105], v[82:83], v[98:99]
	v_pk_add_f32 v[82:83], v[82:83], v[98:99] neg_lo:[0,1] neg_hi:[0,1]
	v_pk_add_f32 v[98:99], v[78:79], v[90:91]
	v_pk_mul_f32 v[4:5], v[4:5], v[86:87] op_sel:[0,1] op_sel_hi:[1,0]
	v_xor_b32_e32 v101, 0x80000000, v96
	v_pk_add_f32 v[88:89], v[88:89], v[92:93] neg_lo:[0,1] neg_hi:[0,1]
	v_mov_b32_e32 v100, v97
	v_pk_add_f32 v[78:79], v[78:79], v[90:91] neg_lo:[0,1] neg_hi:[0,1]
	v_pk_add_f32 v[90:91], v[68:69], v[80:81]
	v_pk_fma_f32 v[4:5], v[6:7], v[86:87], v[4:5] op_sel_hi:[0,1,1]
	v_pk_mul_f32 v[6:7], v[14:15], v[98:99] op_sel:[0,1] op_sel_hi:[1,0]
	v_xor_b32_e32 v93, 0x80000000, v88
	v_pk_add_f32 v[66:67], v[66:67], v[70:71] neg_lo:[0,1] neg_hi:[0,1]
	v_pk_add_f32 v[96:97], v[94:95], v[100:101]
	v_mov_b32_e32 v92, v89
	v_pk_fma_f32 v[6:7], v[8:9], v[98:99], v[6:7] op_sel_hi:[0,1,1]
	v_pk_mul_f32 v[8:9], v[20:21], v[90:91] op_sel:[0,1] op_sel_hi:[1,0]
	v_xor_b32_e32 v71, 0x80000000, v66
	v_pk_add_f32 v[88:89], v[72:73], v[92:93]
	v_mov_b32_e32 v70, v67
	v_pk_fma_f32 v[8:9], v[10:11], v[90:91], v[8:9] op_sel_hi:[0,1,1]
	v_pk_mul_f32 v[10:11], v[16:17], v[96:97] op_sel:[0,1] op_sel_hi:[1,0]
	v_pk_add_f32 v[66:67], v[64:65], v[70:71]
	v_pk_fma_f32 v[10:11], v[12:13], v[96:97], v[10:11] op_sel_hi:[0,1,1]
	v_pk_mul_f32 v[12:13], v[22:23], v[88:89] op_sel:[0,1] op_sel_hi:[1,0]
	v_pk_add_f32 v[94:95], v[94:95], v[100:101] neg_lo:[0,1] neg_hi:[0,1]
	v_pk_add_f32 v[74:75], v[102:103], v[74:75] neg_lo:[0,1] neg_hi:[0,1]
	v_pk_add_f32 v[72:73], v[72:73], v[92:93] neg_lo:[0,1] neg_hi:[0,1]
	v_pk_add_f32 v[68:69], v[68:69], v[80:81] neg_lo:[0,1] neg_hi:[0,1]
	v_pk_add_f32 v[64:65], v[64:65], v[70:71] neg_lo:[0,1] neg_hi:[0,1]
	v_pk_fma_f32 v[12:13], v[18:19], v[88:89], v[12:13] op_sel_hi:[0,1,1]
	v_pk_mul_f32 v[14:15], v[26:27], v[76:77] op_sel:[0,1] op_sel_hi:[1,0]
	v_pk_mul_f32 v[16:17], v[30:31], v[66:67] op_sel:[0,1] op_sel_hi:[1,0]
	v_pk_mul_f32 v[18:19], v[34:35], v[82:83] op_sel:[0,1] op_sel_hi:[1,0]
	v_pk_fma_f32 v[14:15], v[24:25], v[76:77], v[14:15] op_sel_hi:[0,1,1]
	v_pk_fma_f32 v[16:17], v[28:29], v[66:67], v[16:17] op_sel_hi:[0,1,1]
	v_pk_fma_f32 v[18:19], v[32:33], v[82:83], v[18:19] op_sel_hi:[0,1,1]
	v_pk_mul_f32 v[20:21], v[38:39], v[74:75] op_sel:[0,1] op_sel_hi:[1,0]
	v_pk_mul_f32 v[22:23], v[42:43], v[78:79] op_sel:[0,1] op_sel_hi:[1,0]
	v_pk_mul_f32 v[24:25], v[46:47], v[68:69] op_sel:[0,1] op_sel_hi:[1,0]
	v_pk_mul_f32 v[26:27], v[50:51], v[94:95] op_sel:[0,1] op_sel_hi:[1,0]
	v_pk_mul_f32 v[28:29], v[54:55], v[72:73] op_sel:[0,1] op_sel_hi:[1,0]
	v_pk_mul_f32 v[30:31], v[58:59], v[84:85] op_sel:[0,1] op_sel_hi:[1,0]
	v_pk_mul_f32 v[32:33], v[62:63], v[64:65] op_sel:[0,1] op_sel_hi:[1,0]
	v_pk_fma_f32 v[20:21], v[36:37], v[74:75], v[20:21] op_sel_hi:[0,1,1]
	v_pk_fma_f32 v[22:23], v[40:41], v[78:79], v[22:23] op_sel_hi:[0,1,1]
	v_pk_fma_f32 v[24:25], v[44:45], v[68:69], v[24:25] op_sel_hi:[0,1,1]
	v_pk_fma_f32 v[26:27], v[48:49], v[94:95], v[26:27] op_sel_hi:[0,1,1]
	v_pk_fma_f32 v[28:29], v[52:53], v[72:73], v[28:29] op_sel_hi:[0,1,1]
	v_pk_fma_f32 v[30:31], v[56:57], v[84:85], v[30:31] op_sel_hi:[0,1,1]
	v_pk_fma_f32 v[32:33], v[60:61], v[64:65], v[32:33] op_sel_hi:[0,1,1]
	ds_write2_b64 v2, v[104:105], v[18:19] offset1:16
	ds_write2_b64 v2, v[10:11], v[26:27] offset0:33 offset1:49
	ds_write2_b64 v2, v[6:7], v[22:23] offset0:66 offset1:82
	ds_write2_b64 v2, v[14:15], v[30:31] offset0:99 offset1:115
	ds_write2_b64 v2, v[4:5], v[20:21] offset0:132 offset1:148
	ds_write2_b64 v2, v[12:13], v[28:29] offset0:165 offset1:181
	ds_write2_b64 v2, v[8:9], v[24:25] offset0:198 offset1:214
	ds_write2_b64 v2, v[16:17], v[32:33] offset0:231 offset1:247
	s_waitcnt lgkmcnt(0)
	s_barrier
	s_nop 0
	v_ashrrev_i32_e32 v2, 31, v142
	v_add_u32_sdwa v2, v142, v2 dst_sel:DWORD dst_unused:UNUSED_PAD src0_sel:DWORD src1_sel:BYTE_3
	v_ashrrev_i32_e32 v145, 8, v2
	v_mul_i32_i24_e32 v2, 0x100, v145
	v_sub_u32_e32 v144, v142, v2
	v_lshlrev_b32_e32 v2, 1, v144
	v_bfrev_b32_e32 v2, v2
	v_lshrrev_b32_e32 v2, 23, v2
	v_sub_u32_e32 v2, 0x200, v2
	v_bfrev_b32_e32 v2, v2
	v_lshrrev_b32_e32 v2, 19, v2
	v_lshlrev_b32_e32 v143, 13, v145
	v_and_b32_e32 v2, 0x1ff0, v2
	v_cmp_eq_u32_e32 vcc, 0, v144
	v_lshl_add_u32 v4, v144, 5, v143
	v_lshlrev_b32_e32 v5, 3, v4
	v_cndmask_b32_e64 v2, v2, 16, vcc
	v_ashrrev_i32_e32 v4, 2, v4
	v_or_b32_e32 v2, v2, v143
	v_add3_u32 v56, 0, v5, v4
	v_ashrrev_i32_e32 v4, 5, v2
	v_lshlrev_b32_e32 v2, 3, v2
	v_lshlrev_b32_e32 v4, 3, v4
	v_add3_u32 v2, 0, v2, v4
	ds_read2_b64 v[4:7], v56 offset1:1
	ds_read2_b64 v[8:11], v56 offset0:2 offset1:3
	ds_read2_b64 v[12:15], v2 offset1:1
	ds_read2_b64 v[16:19], v2 offset0:2 offset1:3
	ds_read2_b64 v[20:23], v56 offset0:4 offset1:5
	ds_read2_b64 v[24:27], v56 offset0:6 offset1:7
	ds_read2_b64 v[28:31], v2 offset0:4 offset1:5
	ds_read2_b64 v[32:35], v2 offset0:6 offset1:7
	ds_read2_b64 v[36:39], v56 offset0:8 offset1:9
	ds_read2_b64 v[40:43], v56 offset0:10 offset1:11
	ds_read2_b64 v[44:47], v2 offset0:8 offset1:9
	ds_read2_b64 v[52:55], v2 offset0:10 offset1:11
	ds_read2_b64 v[48:51], v56 offset0:12 offset1:13
	ds_read2_b64 v[56:59], v56 offset0:14 offset1:15
	ds_read2_b64 v[62:65], v2 offset0:12 offset1:13
	ds_read2_b64 v[74:77], v2 offset0:14 offset1:15
	s_waitcnt lgkmcnt(7)
	v_pk_add_f32 v[60:61], v[4:5], v[36:37]
	v_pk_add_f32 v[4:5], v[4:5], v[36:37] neg_lo:[0,1] neg_hi:[0,1]
	v_pk_add_f32 v[36:37], v[6:7], v[38:39]
	v_pk_add_f32 v[6:7], v[6:7], v[38:39] neg_lo:[0,1] neg_hi:[0,1]
	s_waitcnt lgkmcnt(3)
	v_pk_add_f32 v[66:67], v[22:23], v[50:51]
	v_pk_mul_f32 v[38:39], v[6:7], s[24:25]
	v_pk_add_f32 v[22:23], v[22:23], v[50:51] neg_lo:[0,1] neg_hi:[0,1]
	v_pk_fma_f32 v[6:7], v[6:7], s[22:23], v[38:39] op_sel:[0,0,1] op_sel_hi:[1,0,0]
	v_pk_add_f32 v[38:39], v[8:9], v[40:41]
	v_pk_add_f32 v[8:9], v[8:9], v[40:41] neg_lo:[0,1] neg_hi:[0,1]
	v_pk_mul_f32 v[50:51], v[22:23], s[44:45]
	v_pk_mul_f32 v[40:41], v[8:9], s[40:41]
	v_pk_fma_f32 v[22:23], v[22:23], s[50:51], v[50:51] op_sel:[0,0,1] op_sel_hi:[1,0,0] neg_lo:[1,0,0] neg_hi:[1,0,0]
	v_pk_fma_f32 v[8:9], v[8:9], s[38:39], v[40:41] op_sel:[0,0,1] op_sel_hi:[1,0,0]
	v_pk_add_f32 v[40:41], v[10:11], v[42:43]
	v_pk_add_f32 v[10:11], v[10:11], v[42:43] neg_lo:[0,1] neg_hi:[0,1]
	s_waitcnt lgkmcnt(2)
	v_pk_add_f32 v[50:51], v[24:25], v[56:57]
	v_pk_add_f32 v[24:25], v[24:25], v[56:57] neg_lo:[0,1] neg_hi:[0,1]
	v_pk_mul_f32 v[42:43], v[10:11], s[44:45]
	v_pk_mul_f32 v[56:57], v[24:25], s[40:41]
	v_pk_fma_f32 v[10:11], v[10:11], s[50:51], v[42:43] op_sel:[0,0,1] op_sel_hi:[1,0,0]
	v_pk_add_f32 v[42:43], v[20:21], v[48:49]
	v_pk_add_f32 v[48:49], v[20:21], v[48:49] neg_lo:[0,1] neg_hi:[0,1]
	v_pk_fma_f32 v[24:25], v[24:25], s[38:39], v[56:57] op_sel:[0,0,1] op_sel_hi:[1,0,0] neg_lo:[1,0,0] neg_hi:[1,0,0]
	v_pk_add_f32 v[56:57], v[26:27], v[58:59]
	v_pk_add_f32 v[26:27], v[26:27], v[58:59] neg_lo:[0,1] neg_hi:[0,1]
	v_pk_mul_f32 v[58:59], v[26:27], s[24:25]
	v_pk_add_f32 v[68:69], v[40:41], v[56:57]
	v_pk_add_f32 v[40:41], v[40:41], v[56:57] neg_lo:[0,1] neg_hi:[0,1]
	v_pk_fma_f32 v[26:27], v[26:27], s[22:23], v[58:59] op_sel:[0,0,1] op_sel_hi:[1,0,0] neg_lo:[1,0,0] neg_hi:[1,0,0]
	v_pk_mul_f32 v[56:57], v[40:41], s[40:41]
	v_pk_add_f32 v[20:21], v[4:5], v[48:49] op_sel:[0,1] op_sel_hi:[1,0] neg_hi:[0,1]
	v_pk_add_f32 v[4:5], v[4:5], v[48:49] op_sel:[0,1] op_sel_hi:[1,0] neg_lo:[0,1]
	v_pk_add_f32 v[48:49], v[6:7], v[22:23]
	v_pk_add_f32 v[6:7], v[6:7], v[22:23] neg_lo:[0,1] neg_hi:[0,1]
	v_pk_fma_f32 v[40:41], v[40:41], s[38:39], v[56:57] op_sel:[0,0,1] op_sel_hi:[1,0,0] neg_lo:[1,0,0] neg_hi:[1,0,0]
	v_pk_mul_f32 v[22:23], v[6:7], s[40:41]
	v_pk_add_f32 v[56:57], v[10:11], v[26:27]
	v_pk_add_f32 v[10:11], v[10:11], v[26:27] neg_lo:[0,1] neg_hi:[0,1]
	v_pk_add_f32 v[58:59], v[60:61], v[42:43]
	v_pk_add_f32 v[42:43], v[60:61], v[42:43] neg_lo:[0,1] neg_hi:[0,1]
	v_pk_add_f32 v[60:61], v[36:37], v[66:67]
	v_pk_add_f32 v[36:37], v[36:37], v[66:67] neg_lo:[0,1] neg_hi:[0,1]
	v_pk_fma_f32 v[6:7], v[6:7], s[38:39], v[22:23] op_sel:[0,0,1] op_sel_hi:[1,0,0]
	v_pk_add_f32 v[22:23], v[8:9], v[24:25]
	v_pk_add_f32 v[24:25], v[8:9], v[24:25] neg_lo:[0,1] neg_hi:[0,1]
	v_pk_mul_f32 v[26:27], v[10:11], s[40:41]
	v_pk_mul_f32 v[66:67], v[36:37], s[40:41]
	v_pk_fma_f32 v[10:11], v[10:11], s[38:39], v[26:27] op_sel:[0,0,1] op_sel_hi:[1,0,0] neg_lo:[1,0,0] neg_hi:[1,0,0]
	v_pk_fma_f32 v[36:37], v[36:37], s[38:39], v[66:67] op_sel:[0,0,1] op_sel_hi:[1,0,0]
	v_pk_add_f32 v[66:67], v[38:39], v[50:51]
	v_pk_add_f32 v[8:9], v[4:5], v[24:25] op_sel:[0,1] op_sel_hi:[1,0] neg_hi:[0,1]
	v_pk_add_f32 v[4:5], v[4:5], v[24:25] op_sel:[0,1] op_sel_hi:[1,0] neg_lo:[0,1]
	v_pk_add_f32 v[24:25], v[6:7], v[10:11]
	v_pk_add_f32 v[10:11], v[6:7], v[10:11] neg_lo:[0,1] neg_hi:[0,1]
	v_pk_add_f32 v[26:27], v[58:59], v[66:67]
	v_pk_add_f32 v[58:59], v[58:59], v[66:67] neg_lo:[0,1] neg_hi:[0,1]
	v_pk_add_f32 v[66:67], v[60:61], v[68:69]
	v_pk_add_f32 v[68:69], v[60:61], v[68:69] neg_lo:[0,1] neg_hi:[0,1]
	v_pk_add_f32 v[60:61], v[4:5], v[10:11] op_sel:[0,1] op_sel_hi:[1,0] neg_hi:[0,1]
	v_pk_add_f32 v[90:91], v[4:5], v[10:11] op_sel:[0,1] op_sel_hi:[1,0] neg_lo:[0,1]
	v_pk_add_f32 v[10:11], v[14:15], v[46:47] neg_lo:[0,1] neg_hi:[0,1]
	v_pk_add_f32 v[50:51], v[38:39], v[50:51] neg_lo:[0,1] neg_hi:[0,1]
	v_pk_add_f32 v[84:85], v[58:59], v[68:69] op_sel:[0,1] op_sel_hi:[1,0] neg_hi:[0,1]
	v_pk_add_f32 v[86:87], v[58:59], v[68:69] op_sel:[0,1] op_sel_hi:[1,0] neg_lo:[0,1]
	v_pk_add_f32 v[82:83], v[8:9], v[24:25]
	v_pk_add_f32 v[68:69], v[8:9], v[24:25] neg_lo:[0,1] neg_hi:[0,1]
	v_pk_add_f32 v[4:5], v[12:13], v[44:45]
	v_pk_add_f32 v[6:7], v[12:13], v[44:45] neg_lo:[0,1] neg_hi:[0,1]
	v_pk_add_f32 v[8:9], v[14:15], v[46:47]
	v_pk_mul_f32 v[12:13], v[10:11], s[24:25]
	v_pk_add_f32 v[14:15], v[16:17], v[52:53] neg_lo:[0,1] neg_hi:[0,1]
	v_pk_add_f32 v[70:71], v[20:21], v[22:23]
	v_pk_add_f32 v[20:21], v[20:21], v[22:23] neg_lo:[0,1] neg_hi:[0,1]
	v_pk_add_f32 v[22:23], v[48:49], v[56:57]
	v_pk_add_f32 v[48:49], v[48:49], v[56:57] neg_lo:[0,1] neg_hi:[0,1]
	v_pk_fma_f32 v[10:11], v[10:11], s[22:23], v[12:13] op_sel:[0,0,1] op_sel_hi:[1,0,0]
	v_pk_add_f32 v[12:13], v[16:17], v[52:53]
	v_pk_mul_f32 v[16:17], v[14:15], s[40:41]
	v_pk_add_f32 v[38:39], v[42:43], v[50:51] op_sel:[0,1] op_sel_hi:[1,0] neg_hi:[0,1]
	v_pk_add_f32 v[42:43], v[42:43], v[50:51] op_sel:[0,1] op_sel_hi:[1,0] neg_lo:[0,1]
	v_pk_add_f32 v[50:51], v[36:37], v[40:41]
	v_xor_b32_e32 v57, 0x80000000, v48
	v_mov_b32_e32 v56, v49
	v_pk_fma_f32 v[14:15], v[14:15], s[38:39], v[16:17] op_sel:[0,0,1] op_sel_hi:[1,0,0]
	v_pk_add_f32 v[16:17], v[18:19], v[54:55]
	v_pk_add_f32 v[18:19], v[18:19], v[54:55] neg_lo:[0,1] neg_hi:[0,1]
	v_pk_add_f32 v[130:131], v[26:27], v[66:67]
	v_pk_add_f32 v[92:93], v[26:27], v[66:67] neg_lo:[0,1] neg_hi:[0,1]
	v_pk_add_f32 v[88:89], v[38:39], v[50:51]
	v_pk_add_f32 v[72:73], v[38:39], v[50:51] neg_lo:[0,1] neg_hi:[0,1]
	v_pk_add_f32 v[96:97], v[70:71], v[22:23]
	v_pk_add_f32 v[50:51], v[70:71], v[22:23] neg_lo:[0,1] neg_hi:[0,1]
	v_pk_add_f32 v[66:67], v[20:21], v[56:57]
	v_pk_add_f32 v[80:81], v[20:21], v[56:57] neg_lo:[0,1] neg_hi:[0,1]
	v_pk_mul_f32 v[20:21], v[18:19], s[44:45]
	s_waitcnt lgkmcnt(1)
	v_pk_add_f32 v[24:25], v[28:29], v[62:63] neg_lo:[0,1] neg_hi:[0,1]
	v_pk_add_f32 v[26:27], v[30:31], v[64:65] neg_lo:[0,1] neg_hi:[0,1]
	v_pk_fma_f32 v[18:19], v[18:19], s[50:51], v[20:21] op_sel:[0,0,1] op_sel_hi:[1,0,0]
	v_pk_add_f32 v[20:21], v[28:29], v[62:63]
	v_pk_add_f32 v[22:23], v[30:31], v[64:65]
	v_pk_mul_f32 v[28:29], v[26:27], s[44:45]
	s_waitcnt lgkmcnt(0)
	v_pk_add_f32 v[30:31], v[32:33], v[74:75] neg_lo:[0,1] neg_hi:[0,1]
	v_pk_fma_f32 v[26:27], v[26:27], s[50:51], v[28:29] op_sel:[0,0,1] op_sel_hi:[1,0,0] neg_lo:[1,0,0] neg_hi:[1,0,0]
	v_pk_add_f32 v[28:29], v[32:33], v[74:75]
	v_pk_mul_f32 v[32:33], v[30:31], s[40:41]
	v_pk_add_f32 v[36:37], v[36:37], v[40:41] neg_lo:[0,1] neg_hi:[0,1]
	v_pk_fma_f32 v[30:31], v[30:31], s[38:39], v[32:33] op_sel:[0,0,1] op_sel_hi:[1,0,0] neg_lo:[1,0,0] neg_hi:[1,0,0]
	v_pk_add_f32 v[32:33], v[34:35], v[76:77]
	v_pk_add_f32 v[34:35], v[34:35], v[76:77] neg_lo:[0,1] neg_hi:[0,1]
	v_xor_b32_e32 v41, 0x80000000, v36
	v_mov_b32_e32 v40, v37
	v_pk_mul_f32 v[36:37], v[34:35], s[24:25]
	v_mov_b32_e32 v2, v130
	v_pk_fma_f32 v[34:35], v[34:35], s[22:23], v[36:37] op_sel:[0,0,1] op_sel_hi:[1,0,0] neg_lo:[1,0,0] neg_hi:[1,0,0]
	v_pk_add_f32 v[36:37], v[4:5], v[20:21]
	v_pk_add_f32 v[4:5], v[4:5], v[20:21] neg_lo:[0,1] neg_hi:[0,1]
	v_pk_add_f32 v[20:21], v[8:9], v[22:23]
	v_pk_add_f32 v[8:9], v[8:9], v[22:23] neg_lo:[0,1] neg_hi:[0,1]
	v_cmp_ne_u32_e64 s[0:1], 0, v144
	v_pk_mul_f32 v[22:23], v[8:9], s[40:41]
	v_pk_add_f32 v[78:79], v[42:43], v[40:41]
	v_pk_fma_f32 v[8:9], v[8:9], s[38:39], v[22:23] op_sel:[0,0,1] op_sel_hi:[1,0,0]
	v_pk_add_f32 v[22:23], v[12:13], v[28:29]
	v_pk_add_f32 v[28:29], v[12:13], v[28:29] neg_lo:[0,1] neg_hi:[0,1]
	v_pk_add_f32 v[94:95], v[42:43], v[40:41] neg_lo:[0,1] neg_hi:[0,1]
	v_pk_add_f32 v[12:13], v[16:17], v[32:33]
	v_pk_add_f32 v[16:17], v[16:17], v[32:33] neg_lo:[0,1] neg_hi:[0,1]
	s_nop 0
	v_pk_mul_f32 v[32:33], v[16:17], s[40:41]
	s_nop 0
	v_pk_fma_f32 v[16:17], v[16:17], s[38:39], v[32:33] op_sel:[0,0,1] op_sel_hi:[1,0,0] neg_lo:[1,0,0] neg_hi:[1,0,0]
	v_pk_add_f32 v[32:33], v[6:7], v[24:25] op_sel:[0,1] op_sel_hi:[1,0] neg_hi:[0,1]
	v_pk_add_f32 v[6:7], v[6:7], v[24:25] op_sel:[0,1] op_sel_hi:[1,0] neg_lo:[0,1]
	v_pk_add_f32 v[24:25], v[10:11], v[26:27]
	v_pk_add_f32 v[10:11], v[10:11], v[26:27] neg_lo:[0,1] neg_hi:[0,1]
	s_nop 0
	v_pk_mul_f32 v[26:27], v[10:11], s[40:41]
	s_nop 0
	v_pk_fma_f32 v[10:11], v[10:11], s[38:39], v[26:27] op_sel:[0,0,1] op_sel_hi:[1,0,0]
	v_pk_add_f32 v[26:27], v[14:15], v[30:31]
	v_pk_add_f32 v[30:31], v[14:15], v[30:31] neg_lo:[0,1] neg_hi:[0,1]
	s_nop 0
	v_pk_add_f32 v[14:15], v[18:19], v[34:35]
	v_pk_add_f32 v[18:19], v[18:19], v[34:35] neg_lo:[0,1] neg_hi:[0,1]
	s_nop 0
	v_pk_mul_f32 v[34:35], v[18:19], s[40:41]
	s_nop 0
	v_pk_fma_f32 v[18:19], v[18:19], s[38:39], v[34:35] op_sel:[0,0,1] op_sel_hi:[1,0,0] neg_lo:[1,0,0] neg_hi:[1,0,0]
	v_pk_add_f32 v[34:35], v[36:37], v[22:23]
	v_pk_add_f32 v[22:23], v[36:37], v[22:23] neg_lo:[0,1] neg_hi:[0,1]
	v_pk_add_f32 v[36:37], v[20:21], v[12:13]
	v_pk_add_f32 v[12:13], v[20:21], v[12:13] neg_lo:[0,1] neg_hi:[0,1]
	v_pk_add_f32 v[98:99], v[34:35], v[36:37]
	v_xor_b32_e32 v21, 0x80000000, v12
	v_mov_b32_e32 v20, v13
	v_pk_add_f32 v[12:13], v[4:5], v[28:29] op_sel:[0,1] op_sel_hi:[1,0] neg_hi:[0,1]
	v_pk_add_f32 v[4:5], v[4:5], v[28:29] op_sel:[0,1] op_sel_hi:[1,0] neg_lo:[0,1]
	v_pk_add_f32 v[28:29], v[8:9], v[16:17]
	v_pk_add_f32 v[8:9], v[8:9], v[16:17] neg_lo:[0,1] neg_hi:[0,1]
	v_pk_add_f32 v[100:101], v[34:35], v[36:37] neg_lo:[0,1] neg_hi:[0,1]
	v_xor_b32_e32 v17, 0x80000000, v8
	v_mov_b32_e32 v16, v9
	v_pk_add_f32 v[8:9], v[32:33], v[26:27]
	v_pk_add_f32 v[26:27], v[32:33], v[26:27] neg_lo:[0,1] neg_hi:[0,1]
	v_pk_add_f32 v[32:33], v[24:25], v[14:15]
	v_pk_add_f32 v[14:15], v[24:25], v[14:15] neg_lo:[0,1] neg_hi:[0,1]
	v_pk_add_f32 v[102:103], v[22:23], v[20:21]
	v_xor_b32_e32 v25, 0x80000000, v14
	v_mov_b32_e32 v24, v15
	v_pk_add_f32 v[14:15], v[6:7], v[30:31] op_sel:[0,1] op_sel_hi:[1,0] neg_hi:[0,1]
	v_pk_add_f32 v[6:7], v[6:7], v[30:31] op_sel:[0,1] op_sel_hi:[1,0] neg_lo:[0,1]
	v_pk_add_f32 v[30:31], v[10:11], v[18:19]
	v_pk_add_f32 v[10:11], v[10:11], v[18:19] neg_lo:[0,1] neg_hi:[0,1]
	v_pk_add_f32 v[104:105], v[22:23], v[20:21] neg_lo:[0,1] neg_hi:[0,1]
	v_xor_b32_e32 v19, 0x80000000, v10
	v_mov_b32_e32 v18, v11
	v_pk_add_f32 v[106:107], v[12:13], v[28:29]
	v_pk_add_f32 v[108:109], v[12:13], v[28:29] neg_lo:[0,1] neg_hi:[0,1]
	v_pk_add_f32 v[110:111], v[4:5], v[16:17]
	v_pk_add_f32 v[112:113], v[4:5], v[16:17] neg_lo:[0,1] neg_hi:[0,1]
	v_pk_add_f32 v[114:115], v[8:9], v[32:33]
	v_pk_add_f32 v[116:117], v[8:9], v[32:33] neg_lo:[0,1] neg_hi:[0,1]
	v_pk_add_f32 v[118:119], v[26:27], v[24:25]
	v_pk_add_f32 v[120:121], v[26:27], v[24:25] neg_lo:[0,1] neg_hi:[0,1]
	v_pk_add_f32 v[122:123], v[14:15], v[30:31]
	v_pk_add_f32 v[124:125], v[14:15], v[30:31] neg_lo:[0,1] neg_hi:[0,1]
	v_pk_add_f32 v[126:127], v[6:7], v[18:19]
	v_pk_add_f32 v[128:129], v[6:7], v[18:19] neg_lo:[0,1] neg_hi:[0,1]
	v_mov_b32_e32 v4, v131
	v_mov_b32_e32 v5, v3
	v_mov_b64_e32 v[6:7], v[2:3]
	s_and_saveexec_b64 s[50:51], s[0:1]
	s_xor_b64 s[0:1], exec, s[50:51]
	s_cbranch_execz .LBB0_576
	v_pk_add_f32 v[4:5], v[96:97], v[112:113]
	v_pk_add_f32 v[24:25], v[96:97], v[112:113] neg_lo:[0,1] neg_hi:[0,1]
	v_pk_add_f32 v[148:149], v[130:131], v[128:129]
	v_pk_add_f32 v[8:9], v[130:131], v[128:129] neg_lo:[0,1] neg_hi:[0,1]
	v_pk_add_f32 v[128:129], v[126:127], v[92:93]
	v_pk_add_f32 v[10:11], v[126:127], v[92:93] neg_lo:[0,1] neg_hi:[0,1]
	v_pk_add_f32 v[92:93], v[84:85], v[124:125]
	v_pk_add_f32 v[12:13], v[84:85], v[124:125] neg_lo:[0,1] neg_hi:[0,1]
	v_pk_add_f32 v[84:85], v[122:123], v[86:87]
	v_pk_add_f32 v[14:15], v[122:123], v[86:87] neg_lo:[0,1] neg_hi:[0,1]
	v_pk_add_f32 v[86:87], v[88:89], v[120:121]
	v_pk_add_f32 v[16:17], v[88:89], v[120:121] neg_lo:[0,1] neg_hi:[0,1]
	v_pk_add_f32 v[88:89], v[118:119], v[72:73]
	v_pk_add_f32 v[18:19], v[118:119], v[72:73] neg_lo:[0,1] neg_hi:[0,1]
	v_pk_add_f32 v[72:73], v[78:79], v[116:117]
	v_pk_add_f32 v[20:21], v[78:79], v[116:117] neg_lo:[0,1] neg_hi:[0,1]
	v_pk_add_f32 v[78:79], v[114:115], v[94:95]
	v_pk_add_f32 v[22:23], v[114:115], v[94:95] neg_lo:[0,1] neg_hi:[0,1]
	v_mov_b32_e32 v6, v4
	v_mov_b32_e32 v7, v25
	v_pk_mov_b32 v[4:5], v[4:5], v[24:25] op_sel:[1,0]
	v_pk_add_f32 v[94:95], v[110:111], v[50:51]
	v_pk_add_f32 v[24:25], v[110:111], v[50:51] neg_lo:[0,1] neg_hi:[0,1]
	v_pk_add_f32 v[50:51], v[66:67], v[108:109]
	v_pk_add_f32 v[26:27], v[66:67], v[108:109] neg_lo:[0,1] neg_hi:[0,1]
	v_pk_add_f32 v[66:67], v[106:107], v[80:81]
	v_pk_add_f32 v[28:29], v[106:107], v[80:81] neg_lo:[0,1] neg_hi:[0,1]
	v_pk_add_f32 v[80:81], v[82:83], v[104:105]
	v_pk_add_f32 v[30:31], v[82:83], v[104:105] neg_lo:[0,1] neg_hi:[0,1]
	v_pk_add_f32 v[82:83], v[102:103], v[68:69]
	v_pk_add_f32 v[32:33], v[102:103], v[68:69] neg_lo:[0,1] neg_hi:[0,1]
	v_pk_add_f32 v[68:69], v[60:61], v[100:101]
	v_pk_add_f32 v[34:35], v[60:61], v[100:101] neg_lo:[0,1] neg_hi:[0,1]
	v_pk_add_f32 v[60:61], v[98:99], v[90:91]
	v_pk_add_f32 v[36:37], v[98:99], v[90:91] neg_lo:[0,1] neg_hi:[0,1]
	v_pk_mul_f32 v[6:7], v[6:7], 0.5 op_sel_hi:[1,0]
	v_pk_mul_f32 v[4:5], v[4:5], s[46:47]
	v_mov_b32_e32 v39, v8
	v_mov_b32_e32 v38, v149
	v_mov_b32_e32 v41, v10
	v_mov_b32_e32 v40, v129
	v_mov_b32_e32 v43, v12
	v_mov_b32_e32 v42, v93
	v_mov_b32_e32 v45, v14
	v_mov_b32_e32 v44, v85
	v_mov_b32_e32 v47, v16
	v_mov_b32_e32 v46, v87
	v_mov_b32_e32 v49, v18
	v_mov_b32_e32 v48, v89
	v_mov_b32_e32 v53, v20
	v_mov_b32_e32 v52, v73
	v_mov_b32_e32 v55, v22
	v_mov_b32_e32 v54, v79
	v_mov_b32_e32 v57, v24
	v_mov_b32_e32 v56, v95
	v_mov_b32_e32 v59, v26
	v_mov_b32_e32 v58, v51
	v_mov_b32_e32 v63, v28
	v_mov_b32_e32 v62, v67
	v_mov_b32_e32 v65, v30
	v_mov_b32_e32 v64, v81
	v_mov_b32_e32 v71, v32
	v_mov_b32_e32 v70, v83
	v_mov_b32_e32 v75, v34
	v_mov_b32_e32 v74, v69
	v_mov_b32_e32 v77, v36
	v_mov_b32_e32 v76, v61
	v_mov_b32_e32 v8, v148
	v_mov_b32_e32 v10, v128
	v_mov_b32_e32 v12, v92
	v_mov_b32_e32 v14, v84
	v_mov_b32_e32 v16, v86
	v_mov_b32_e32 v18, v88
	v_mov_b32_e32 v20, v72
	v_mov_b32_e32 v22, v78
	v_mov_b32_e32 v24, v94
	v_mov_b32_e32 v26, v50
	v_mov_b32_e32 v28, v66
	v_mov_b32_e32 v30, v80
	v_mov_b32_e32 v32, v82
	v_mov_b32_e32 v34, v68
	v_mov_b32_e32 v36, v60
